# P1 tail: forget-gate log-sigmoid epilogue with hardware exp2/log2 (f32) instead of unrolled software path; deep-prefetch tail GEMMs; flat->global
# speedup vs baseline: 1.0689x; 1.0265x over previous
; DI int tid8_op() { int t = threadIdx.x; asm volatile("" : "+v"(t)); return t; }
; DI void prologue(const Params& p, unsigned char* smem) {
;     unsigned char* ws = p.ws; asm volatile("" : "+s"(ws));
;     { const int t0 = tid8_op(); if (blockIdx.x == 0 && t0 < 64) ((unsigned*)(ws + O_CNT))[t0] = 0u; }
.LBB0_19:
	s_or_b64 exec, exec, s[4:5]
	s_mov_b64 s[8:9], s[76:77]
	v_mov_b32_e32 v0, v214
	s_cmp_eq_u32 s2, 0
	s_cselect_b64 s[4:5], -1, 0
	v_cmp_gt_i32_e32 vcc, 64, v0
	v_readfirstlane_b32 s0, v214
	s_mov_b32 s13, 0
	s_and_b64 s[6:7], s[4:5], vcc
	s_and_saveexec_b64 s[4:5], s[6:7]
	s_cbranch_execz .LBB0_21
	v_ashrrev_i32_e32 v1, 31, v0
	v_lshl_add_u64 v[0:1], v[0:1], 2, s[8:9]
	v_add_co_u32_e32 v0, vcc, 0x1a4c0000, v0
	v_mov_b32_e32 v2, 0
	s_nop 0
	v_addc_co_u32_e32 v1, vcc, 0, v1, vcc
	global_store_dword v[0:1], v2, off

; DI unsigned pk2(float a, float b) { f32x2 v = {a, b}; return __builtin_bit_cast(unsigned, __builtin_convertvector(v, bf2_t)); }
;     ...
; #pragma unroll
;         for (int i = 0; i < 16; ++i) tl[(ty + 4 * i) * 65 + tx] = tv[i];
;         __syncthreads();
;         const int rr = tid >> 2, c0 = (tid & 3) * 16;
;         u32x4 o0, o1;
;         o0.x = pk2(tl[(c0 + 0) * 65 + rr], tl[(c0 + 1) * 65 + rr]);   o0.y = pk2(tl[(c0 + 2) * 65 + rr], tl[(c0 + 3) * 65 + rr]);
;         o0.z = pk2(tl[(c0 + 4) * 65 + rr], tl[(c0 + 5) * 65 + rr]);   o0.w = pk2(tl[(c0 + 6) * 65 + rr], tl[(c0 + 7) * 65 + rr]);
;         o1.x = pk2(tl[(c0 + 8) * 65 + rr], tl[(c0 + 9) * 65 + rr]);   o1.y = pk2(tl[(c0 + 10) * 65 + rr], tl[(c0 + 11) * 65 + rr]);
;         o1.z = pk2(tl[(c0 + 12) * 65 + rr], tl[(c0 + 13) * 65 + rr]); o1.w = pk2(tl[(c0 + 14) * 65 + rr], tl[(c0 + 15) * 65 + rr]);
;         bf16_t* d = dst + (size_t)(n0 + rr) * K + k0 + c0;
;         *(u32x4*)d = o0; *(u32x4*)(d + 8) = o1;
;         __syncthreads();
.LBB0_25:
	s_or_b64 exec, exec, s[14:15]
	s_waitcnt vmcnt(0)
	ds_write_b32 v12, v17
	ds_write_b32 v13, v0 offset:1040
	ds_write_b32 v13, v20 offset:2080
	ds_write_b32 v13, v19 offset:3120
	ds_write_b32 v13, v22 offset:4160
	ds_write_b32 v13, v21 offset:5200
	ds_write_b32 v13, v24 offset:6240
	ds_write_b32 v13, v23 offset:7280
	ds_write_b32 v13, v26 offset:8320
	ds_write_b32 v13, v25 offset:9360
	ds_write_b32 v13, v28 offset:10400
	ds_write_b32 v13, v27 offset:11440
	ds_write_b32 v13, v30 offset:12480
	ds_write_b32 v13, v29 offset:13520
	ds_write_b32 v13, v32 offset:14560
	ds_write_b32 v13, v31 offset:15600
	s_waitcnt lgkmcnt(0)
	s_barrier
	ds_read2_b32 v[4:5], v9 offset1:65
	ds_read2_b32 v[20:21], v9 offset0:130 offset1:195
	ds_read2_b32 v[22:23], v14 offset0:4 offset1:69
	s_sub_i32 s14, 0, s16
	s_add_i32 s14, s20, s14
	s_waitcnt lgkmcnt(2)
	v_cvt_pk_bf16_f32 v18, v4, v5
	s_waitcnt lgkmcnt(1)
	v_cvt_pk_bf16_f32 v19, v20, v21
	s_waitcnt lgkmcnt(0)
	v_cvt_pk_bf16_f32 v20, v22, v23
	ds_read2_b32 v[4:5], v14 offset0:134 offset1:199
	ds_read2_b32 v[22:23], v15 offset0:8 offset1:73
	ds_read2_b32 v[24:25], v15 offset0:138 offset1:203
	ds_read2_b32 v[26:27], v16 offset0:12 offset1:77
	ds_read2_b32 v[28:29], v16 offset0:142 offset1:207
	s_waitcnt lgkmcnt(4)
	v_cvt_pk_bf16_f32 v21, v4, v5
	v_add_u32_e32 v4, s42, v8
	v_ashrrev_i32_e32 v5, 31, v4
	v_lshlrev_b64 v[4:5], 11, v[4:5]
	v_lshl_add_u64 v[4:5], s[6:7], 0, v[4:5]
	s_ashr_i32 s15, s14, 31
	v_lshl_add_u64 v[4:5], s[14:15], 1, v[4:5]
	s_add_i32 s18, s18, s19
	s_add_i32 s20, s20, s21
	v_lshl_add_u64 v[4:5], v[4:5], 0, v[2:3]
	s_cmpk_lt_i32 s18, 0x3c0
	s_waitcnt lgkmcnt(3)
	v_cvt_pk_bf16_f32 v22, v22, v23
	s_waitcnt lgkmcnt(2)
	v_cvt_pk_bf16_f32 v23, v24, v25
	s_waitcnt lgkmcnt(1)
	v_cvt_pk_bf16_f32 v24, v26, v27
	s_waitcnt lgkmcnt(0)
	v_cvt_pk_bf16_f32 v25, v28, v29
	global_store_dwordx4 v[4:5], v[18:21], off
	global_store_dwordx4 v[4:5], v[22:25], off offset:16
	s_waitcnt lgkmcnt(0)
	s_barrier
	s_cbranch_scc0 .LBB0_72

; DI unsigned pk2(float a, float b) { f32x2 v = {a, b}; return __builtin_bit_cast(unsigned, __builtin_convertvector(v, bf2_t)); }
;     ...
; #pragma unroll
;         for (int i = 0; i < 16; ++i) tl[(ty + 4 * i) * 65 + tx] = tv[i];
;         __syncthreads();
;         const int rr = tid >> 2, c0 = (tid & 3) * 16;
;         u32x4 o0, o1;
;         o0.x = pk2(tl[(c0 + 0) * 65 + rr], tl[(c0 + 1) * 65 + rr]);   o0.y = pk2(tl[(c0 + 2) * 65 + rr], tl[(c0 + 3) * 65 + rr]);
;         o0.z = pk2(tl[(c0 + 4) * 65 + rr], tl[(c0 + 5) * 65 + rr]);   o0.w = pk2(tl[(c0 + 6) * 65 + rr], tl[(c0 + 7) * 65 + rr]);
;         o1.x = pk2(tl[(c0 + 8) * 65 + rr], tl[(c0 + 9) * 65 + rr]);   o1.y = pk2(tl[(c0 + 10) * 65 + rr], tl[(c0 + 11) * 65 + rr]);
;         o1.z = pk2(tl[(c0 + 12) * 65 + rr], tl[(c0 + 13) * 65 + rr]); o1.w = pk2(tl[(c0 + 14) * 65 + rr], tl[(c0 + 15) * 65 + rr]);
;         bf16_t* d = dst + (size_t)(n0 + rr) * K + k0 + c0;
;         *(u32x4*)d = o0; *(u32x4*)(d + 8) = o1;
;         __syncthreads();
.LBB0_74:
	s_or_b64 exec, exec, s[20:21]
	s_waitcnt vmcnt(0)
	ds_write_b32 v16, v21
	ds_write_b32 v17, v0 offset:1040
	ds_write_b32 v17, v23 offset:2080
	ds_write_b32 v17, v22 offset:3120
	ds_write_b32 v17, v25 offset:4160
	ds_write_b32 v17, v24 offset:5200
	ds_write_b32 v17, v27 offset:6240
	ds_write_b32 v17, v26 offset:7280
	ds_write_b32 v17, v29 offset:8320
	ds_write_b32 v17, v28 offset:9360
	ds_write_b32 v17, v31 offset:10400
	ds_write_b32 v17, v30 offset:11440
	ds_write_b32 v17, v33 offset:12480
	ds_write_b32 v17, v32 offset:13520
	ds_write_b32 v17, v35 offset:14560
	ds_write_b32 v17, v34 offset:15600
	s_waitcnt lgkmcnt(0)
	s_barrier
	ds_read2_b32 v[6:7], v15 offset1:65
	ds_read2_b32 v[8:9], v15 offset0:130 offset1:195
	ds_read2_b32 v[22:23], v18 offset0:4 offset1:69
	v_add_u32_e32 v0, s19, v14
	s_ashr_i32 s19, s18, 31
	s_waitcnt lgkmcnt(2)
	v_cvt_pk_bf16_f32 v6, v6, v7
	s_waitcnt lgkmcnt(1)
	v_cvt_pk_bf16_f32 v7, v8, v9
	s_waitcnt lgkmcnt(0)
	v_cvt_pk_bf16_f32 v8, v22, v23
	ds_read2_b32 v[22:23], v18 offset0:134 offset1:199
	ds_read2_b32 v[24:25], v19 offset0:8 offset1:73
	ds_read2_b32 v[26:27], v19 offset0:138 offset1:203
	ds_read2_b32 v[28:29], v20 offset0:12 offset1:77
	ds_read2_b32 v[30:31], v20 offset0:142 offset1:207
	s_waitcnt lgkmcnt(4)
	v_cvt_pk_bf16_f32 v9, v22, v23
	s_add_i32 s42, s42, s43
	s_waitcnt lgkmcnt(2)
	v_cvt_pk_bf16_f32 v23, v26, v27
	v_mad_i64_i32 v[26:27], s[4:5], v0, s41, v[2:3]
	v_lshl_add_u64 v[26:27], s[18:19], 1, v[26:27]
	s_add_i32 s44, s44, s45
	v_lshl_add_u64 v[26:27], v[26:27], 0, v[4:5]
	s_cmp_lt_i32 s42, 48
	v_cvt_pk_bf16_f32 v22, v24, v25
	s_waitcnt lgkmcnt(1)
	v_cvt_pk_bf16_f32 v24, v28, v29
	s_waitcnt lgkmcnt(0)
	v_cvt_pk_bf16_f32 v25, v30, v31
	global_store_dwordx4 v[26:27], v[6:9], off
	global_store_dwordx4 v[26:27], v[22:25], off offset:16
	s_waitcnt lgkmcnt(0)
	s_barrier
	s_cbranch_scc0 .LBB0_123

; DI unsigned pk2(float a, float b) { f32x2 v = {a, b}; return __builtin_bit_cast(unsigned, __builtin_convertvector(v, bf2_t)); }
;     ...
; #pragma unroll
;         for (int i = 0; i < 16; ++i) tl[(ty + 4 * i) * 65 + tx] = tv[i];
;         __syncthreads();
;         const int rr = tid >> 2, c0 = (tid & 3) * 16;
;         u32x4 o0, o1;
;         o0.x = pk2(tl[(c0 + 0) * 65 + rr], tl[(c0 + 1) * 65 + rr]);   o0.y = pk2(tl[(c0 + 2) * 65 + rr], tl[(c0 + 3) * 65 + rr]);
;         o0.z = pk2(tl[(c0 + 4) * 65 + rr], tl[(c0 + 5) * 65 + rr]);   o0.w = pk2(tl[(c0 + 6) * 65 + rr], tl[(c0 + 7) * 65 + rr]);
;         o1.x = pk2(tl[(c0 + 8) * 65 + rr], tl[(c0 + 9) * 65 + rr]);   o1.y = pk2(tl[(c0 + 10) * 65 + rr], tl[(c0 + 11) * 65 + rr]);
;         o1.z = pk2(tl[(c0 + 12) * 65 + rr], tl[(c0 + 13) * 65 + rr]); o1.w = pk2(tl[(c0 + 14) * 65 + rr], tl[(c0 + 15) * 65 + rr]);
;         bf16_t* d = dst + (size_t)(n0 + rr) * K + k0 + c0;
;         *(u32x4*)d = o0; *(u32x4*)(d + 8) = o1;
;         __syncthreads();
.LBB0_125:
	s_or_b64 exec, exec, s[20:21]
	s_waitcnt vmcnt(0)
	ds_write_b32 v14, v3
	ds_write_b32 v15, v0 offset:1040
	ds_write_b32 v15, v17 offset:2080
	ds_write_b32 v15, v16 offset:3120
	ds_write_b32 v15, v19 offset:4160
	ds_write_b32 v15, v18 offset:5200
	ds_write_b32 v15, v21 offset:6240
	ds_write_b32 v15, v20 offset:7280
	ds_write_b32 v15, v23 offset:8320
	ds_write_b32 v15, v22 offset:9360
	ds_write_b32 v15, v25 offset:10400
	ds_write_b32 v15, v24 offset:11440
	ds_write_b32 v15, v27 offset:12480
	ds_write_b32 v15, v26 offset:13520
	ds_write_b32 v15, v29 offset:14560
	ds_write_b32 v15, v28 offset:15600
	v_add_u32_e32 v0, 0x400, v13
	s_waitcnt lgkmcnt(0)
	s_barrier
	ds_read2_b32 v[4:5], v13 offset1:65
	ds_read2_b32 v[6:7], v13 offset0:130 offset1:195
	ds_read2_b32 v[16:17], v0 offset0:4 offset1:69
	s_sub_i32 s4, 0, s47
	s_add_i32 s4, s44, s4
	s_waitcnt lgkmcnt(2)
	v_cvt_pk_bf16_f32 v4, v4, v5
	s_waitcnt lgkmcnt(1)
	v_cvt_pk_bf16_f32 v5, v6, v7
	s_waitcnt lgkmcnt(0)
	v_cvt_pk_bf16_f32 v6, v16, v17
	ds_read2_b32 v[16:17], v0 offset0:134 offset1:199
	v_add_u32_e32 v0, 0x800, v13
	ds_read2_b32 v[18:19], v0 offset0:8 offset1:73
	ds_read2_b32 v[20:21], v0 offset0:138 offset1:203
	v_add_u32_e32 v0, 0xc00, v13
	ds_read2_b32 v[22:23], v0 offset0:12 offset1:77
	ds_read2_b32 v[24:25], v0 offset0:142 offset1:207
	s_waitcnt lgkmcnt(4)
	v_cvt_pk_bf16_f32 v7, v16, v17
	s_ashr_i32 s5, s4, 31
	s_waitcnt lgkmcnt(2)
	v_cvt_pk_bf16_f32 v17, v20, v21
	v_add_u32_e32 v20, s46, v12
	v_ashrrev_i32_e32 v21, 31, v20
	v_lshlrev_b64 v[20:21], 9, v[20:21]
	v_lshl_add_u64 v[20:21], s[16:17], 0, v[20:21]
	v_lshl_add_u64 v[20:21], s[4:5], 1, v[20:21]
	v_mov_b32_e32 v3, v1
	s_add_i32 s42, s42, s43
	s_add_i32 s44, s44, s45
	v_lshl_add_u64 v[20:21], v[20:21], 0, v[2:3]
	s_cmp_lt_i32 s42, 32
	v_cvt_pk_bf16_f32 v16, v18, v19
	s_waitcnt lgkmcnt(1)
	v_cvt_pk_bf16_f32 v18, v22, v23
	s_waitcnt lgkmcnt(0)
	v_cvt_pk_bf16_f32 v19, v24, v25
	global_store_dwordx4 v[20:21], v[4:7], off
	global_store_dwordx4 v[20:21], v[16:19], off offset:16
	s_waitcnt lgkmcnt(0)
	s_barrier
	s_cbranch_scc0 .LBB0_174

; DI unsigned pk2(float a, float b) { f32x2 v = {a, b}; return __builtin_bit_cast(unsigned, __builtin_convertvector(v, bf2_t)); }
;     ...
; #pragma unroll
;         for (int i = 0; i < 16; ++i) tl[(ty + 4 * i) * 65 + tx] = tv[i];
;         __syncthreads();
;         const int rr = tid >> 2, c0 = (tid & 3) * 16;
;         u32x4 o0, o1;
;         o0.x = pk2(tl[(c0 + 0) * 65 + rr], tl[(c0 + 1) * 65 + rr]);   o0.y = pk2(tl[(c0 + 2) * 65 + rr], tl[(c0 + 3) * 65 + rr]);
;         o0.z = pk2(tl[(c0 + 4) * 65 + rr], tl[(c0 + 5) * 65 + rr]);   o0.w = pk2(tl[(c0 + 6) * 65 + rr], tl[(c0 + 7) * 65 + rr]);
;         o1.x = pk2(tl[(c0 + 8) * 65 + rr], tl[(c0 + 9) * 65 + rr]);   o1.y = pk2(tl[(c0 + 10) * 65 + rr], tl[(c0 + 11) * 65 + rr]);
;         o1.z = pk2(tl[(c0 + 12) * 65 + rr], tl[(c0 + 13) * 65 + rr]); o1.w = pk2(tl[(c0 + 14) * 65 + rr], tl[(c0 + 15) * 65 + rr]);
;         bf16_t* d = dst + (size_t)(n0 + rr) * K + k0 + c0;
;         *(u32x4*)d = o0; *(u32x4*)(d + 8) = o1;
;         __syncthreads();
.LBB0_176:
	s_or_b64 exec, exec, s[18:19]
	s_waitcnt vmcnt(0)
	ds_write_b32 v14, v3
	ds_write_b32 v15, v0 offset:1040
	ds_write_b32 v15, v16 offset:2080
	ds_write_b32 v15, v7 offset:3120
	ds_write_b32 v15, v18 offset:4160
	ds_write_b32 v15, v17 offset:5200
	ds_write_b32 v15, v20 offset:6240
	ds_write_b32 v15, v19 offset:7280
	ds_write_b32 v15, v22 offset:8320
	ds_write_b32 v15, v21 offset:9360
	ds_write_b32 v15, v24 offset:10400
	ds_write_b32 v15, v23 offset:11440
	ds_write_b32 v15, v26 offset:12480
	ds_write_b32 v15, v25 offset:13520
	ds_write_b32 v15, v28 offset:14560
	ds_write_b32 v15, v27 offset:15600
	v_add_u32_e32 v0, 0x400, v13
	s_waitcnt lgkmcnt(0)
	s_barrier
	ds_read2_b32 v[4:5], v13 offset1:65
	ds_read2_b32 v[6:7], v13 offset0:130 offset1:195
	ds_read2_b32 v[16:17], v0 offset0:4 offset1:69
	s_sub_i32 s18, 0, s45
	s_add_i32 s18, s42, s18
	s_waitcnt lgkmcnt(2)
	v_cvt_pk_bf16_f32 v4, v4, v5
	s_waitcnt lgkmcnt(1)
	v_cvt_pk_bf16_f32 v5, v6, v7
	s_waitcnt lgkmcnt(0)
	v_cvt_pk_bf16_f32 v6, v16, v17
	ds_read2_b32 v[16:17], v0 offset0:134 offset1:199
	v_add_u32_e32 v0, 0x800, v13
	ds_read2_b32 v[18:19], v0 offset0:8 offset1:73
	ds_read2_b32 v[20:21], v0 offset0:138 offset1:203
	v_add_u32_e32 v0, 0xc00, v13
	ds_read2_b32 v[22:23], v0 offset0:12 offset1:77
	ds_read2_b32 v[24:25], v0 offset0:142 offset1:207
	s_waitcnt lgkmcnt(4)
	v_cvt_pk_bf16_f32 v7, v16, v17
	s_ashr_i32 s19, s18, 31
	s_waitcnt lgkmcnt(2)
	v_cvt_pk_bf16_f32 v17, v20, v21
	v_add_u32_e32 v20, s44, v12
	v_ashrrev_i32_e32 v21, 31, v20
	v_lshlrev_b64 v[20:21], 11, v[20:21]
	v_lshl_add_u64 v[20:21], s[16:17], 0, v[20:21]
	v_lshl_add_u64 v[20:21], s[18:19], 1, v[20:21]
	v_mov_b32_e32 v3, v1
	s_add_i32 s20, s20, s21
	s_add_i32 s42, s42, s43
	v_lshl_add_u64 v[20:21], v[20:21], 0, v[2:3]
	s_cmpk_lt_i32 s20, 0x80
	v_cvt_pk_bf16_f32 v16, v18, v19
	s_waitcnt lgkmcnt(1)
	v_cvt_pk_bf16_f32 v18, v22, v23
	s_waitcnt lgkmcnt(0)
	v_cvt_pk_bf16_f32 v19, v24, v25
	global_store_dwordx4 v[20:21], v[4:7], off
	global_store_dwordx4 v[20:21], v[16:19], off offset:16
	s_waitcnt lgkmcnt(0)
	s_barrier
	s_cbranch_scc0 .LBB0_209

; DI unsigned pk2(float a, float b) { f32x2 v = {a, b}; return __builtin_bit_cast(unsigned, __builtin_convertvector(v, bf2_t)); }
;     ...
; #pragma unroll
;         for (int i = 0; i < 16; ++i) tl[(ty + 4 * i) * 65 + tx] = tv[i];
;         __syncthreads();
;         const int rr = tid >> 2, c0 = (tid & 3) * 16;
;         u32x4 o0, o1;
;         o0.x = pk2(tl[(c0 + 0) * 65 + rr], tl[(c0 + 1) * 65 + rr]);   o0.y = pk2(tl[(c0 + 2) * 65 + rr], tl[(c0 + 3) * 65 + rr]);
;         o0.z = pk2(tl[(c0 + 4) * 65 + rr], tl[(c0 + 5) * 65 + rr]);   o0.w = pk2(tl[(c0 + 6) * 65 + rr], tl[(c0 + 7) * 65 + rr]);
;         o1.x = pk2(tl[(c0 + 8) * 65 + rr], tl[(c0 + 9) * 65 + rr]);   o1.y = pk2(tl[(c0 + 10) * 65 + rr], tl[(c0 + 11) * 65 + rr]);
;         o1.z = pk2(tl[(c0 + 12) * 65 + rr], tl[(c0 + 13) * 65 + rr]); o1.w = pk2(tl[(c0 + 14) * 65 + rr], tl[(c0 + 15) * 65 + rr]);
;         bf16_t* d = dst + (size_t)(n0 + rr) * K + k0 + c0;
;         *(u32x4*)d = o0; *(u32x4*)(d + 8) = o1;
;         __syncthreads();
.LBB0_211:
	s_or_b64 exec, exec, s[18:19]
	s_waitcnt vmcnt(0)
	ds_write_b32 v14, v3
	ds_write_b32 v15, v0 offset:1040
	ds_write_b32 v15, v16 offset:2080
	ds_write_b32 v15, v7 offset:3120
	ds_write_b32 v15, v18 offset:4160
	ds_write_b32 v15, v17 offset:5200
	ds_write_b32 v15, v20 offset:6240
	ds_write_b32 v15, v19 offset:7280
	ds_write_b32 v15, v22 offset:8320
	ds_write_b32 v15, v21 offset:9360
	ds_write_b32 v15, v24 offset:10400
	ds_write_b32 v15, v23 offset:11440
	ds_write_b32 v15, v26 offset:12480
	ds_write_b32 v15, v25 offset:13520
	ds_write_b32 v15, v28 offset:14560
	ds_write_b32 v15, v27 offset:15600
	v_add_u32_e32 v0, 0x400, v13
	s_waitcnt lgkmcnt(0)
	s_barrier
	ds_read2_b32 v[4:5], v13 offset1:65
	ds_read2_b32 v[6:7], v13 offset0:130 offset1:195
	ds_read2_b32 v[16:17], v0 offset0:4 offset1:69
	s_sub_i32 s18, 0, s45
	s_add_i32 s18, s42, s18
	s_waitcnt lgkmcnt(2)
	v_cvt_pk_bf16_f32 v4, v4, v5
	s_waitcnt lgkmcnt(1)
	v_cvt_pk_bf16_f32 v5, v6, v7
	s_waitcnt lgkmcnt(0)
	v_cvt_pk_bf16_f32 v6, v16, v17
	ds_read2_b32 v[16:17], v0 offset0:134 offset1:199
	v_add_u32_e32 v0, 0x800, v13
	ds_read2_b32 v[18:19], v0 offset0:8 offset1:73
	ds_read2_b32 v[20:21], v0 offset0:138 offset1:203
	v_add_u32_e32 v0, 0xc00, v13
	ds_read2_b32 v[22:23], v0 offset0:12 offset1:77
	ds_read2_b32 v[24:25], v0 offset0:142 offset1:207
	s_waitcnt lgkmcnt(4)
	v_cvt_pk_bf16_f32 v7, v16, v17
	s_ashr_i32 s19, s18, 31
	s_waitcnt lgkmcnt(2)
	v_cvt_pk_bf16_f32 v17, v20, v21
	v_add_u32_e32 v20, s44, v12
	v_ashrrev_i32_e32 v21, 31, v20
	v_lshlrev_b64 v[20:21], 8, v[20:21]
	v_lshl_add_u64 v[20:21], s[16:17], 0, v[20:21]
	v_lshl_add_u64 v[20:21], s[18:19], 1, v[20:21]
	v_mov_b32_e32 v3, v1
	s_add_i32 s20, s20, s21
	s_add_i32 s42, s42, s43
	v_lshl_add_u64 v[20:21], v[20:21], 0, v[2:3]
	s_cmpk_lt_i32 s20, 0x80
	v_cvt_pk_bf16_f32 v16, v18, v19
	s_waitcnt lgkmcnt(1)
	v_cvt_pk_bf16_f32 v18, v22, v23
	s_waitcnt lgkmcnt(0)
	v_cvt_pk_bf16_f32 v19, v24, v25
	global_store_dwordx4 v[20:21], v[4:7], off
	global_store_dwordx4 v[20:21], v[16:19], off offset:16
	s_waitcnt lgkmcnt(0)
	s_barrier
	s_cbranch_scc0 .LBB0_244

; DI unsigned pk2(float a, float b) { f32x2 v = {a, b}; return __builtin_bit_cast(unsigned, __builtin_convertvector(v, bf2_t)); }
;     ...
; #pragma unroll
;         for (int i = 0; i < 16; ++i) tl[(ty + 4 * i) * 65 + tx] = tv[i];
;         __syncthreads();
;         const int rr = tid >> 2, c0 = (tid & 3) * 16;
;         u32x4 o0, o1;
;         o0.x = pk2(tl[(c0 + 0) * 65 + rr], tl[(c0 + 1) * 65 + rr]);   o0.y = pk2(tl[(c0 + 2) * 65 + rr], tl[(c0 + 3) * 65 + rr]);
;         o0.z = pk2(tl[(c0 + 4) * 65 + rr], tl[(c0 + 5) * 65 + rr]);   o0.w = pk2(tl[(c0 + 6) * 65 + rr], tl[(c0 + 7) * 65 + rr]);
;         o1.x = pk2(tl[(c0 + 8) * 65 + rr], tl[(c0 + 9) * 65 + rr]);   o1.y = pk2(tl[(c0 + 10) * 65 + rr], tl[(c0 + 11) * 65 + rr]);
;         o1.z = pk2(tl[(c0 + 12) * 65 + rr], tl[(c0 + 13) * 65 + rr]); o1.w = pk2(tl[(c0 + 14) * 65 + rr], tl[(c0 + 15) * 65 + rr]);
;         bf16_t* d = dst + (size_t)(n0 + rr) * K + k0 + c0;
;         *(u32x4*)d = o0; *(u32x4*)(d + 8) = o1;
;         __syncthreads();
.LBB0_246:
	s_or_b64 exec, exec, s[18:19]
	s_waitcnt vmcnt(0)
	ds_write_b32 v14, v3
	ds_write_b32 v15, v0 offset:1040
	ds_write_b32 v15, v16 offset:2080
	ds_write_b32 v15, v7 offset:3120
	ds_write_b32 v15, v18 offset:4160
	ds_write_b32 v15, v17 offset:5200
	ds_write_b32 v15, v20 offset:6240
	ds_write_b32 v15, v19 offset:7280
	ds_write_b32 v15, v22 offset:8320
	ds_write_b32 v15, v21 offset:9360
	ds_write_b32 v15, v24 offset:10400
	ds_write_b32 v15, v23 offset:11440
	ds_write_b32 v15, v26 offset:12480
	ds_write_b32 v15, v25 offset:13520
	ds_write_b32 v15, v28 offset:14560
	ds_write_b32 v15, v27 offset:15600
	v_add_u32_e32 v0, 0x400, v13
	s_waitcnt lgkmcnt(0)
	s_barrier
	ds_read2_b32 v[4:5], v13 offset1:65
	ds_read2_b32 v[6:7], v13 offset0:130 offset1:195
	ds_read2_b32 v[16:17], v0 offset0:4 offset1:69
	s_sub_i32 s18, 0, s45
	s_add_i32 s18, s42, s18
	s_waitcnt lgkmcnt(2)
	v_cvt_pk_bf16_f32 v4, v4, v5
	s_waitcnt lgkmcnt(1)
	v_cvt_pk_bf16_f32 v5, v6, v7
	s_waitcnt lgkmcnt(0)
	v_cvt_pk_bf16_f32 v6, v16, v17
	ds_read2_b32 v[16:17], v0 offset0:134 offset1:199
	v_add_u32_e32 v0, 0x800, v13
	ds_read2_b32 v[18:19], v0 offset0:8 offset1:73
	ds_read2_b32 v[20:21], v0 offset0:138 offset1:203
	v_add_u32_e32 v0, 0xc00, v13
	ds_read2_b32 v[22:23], v0 offset0:12 offset1:77
	ds_read2_b32 v[24:25], v0 offset0:142 offset1:207
	s_waitcnt lgkmcnt(4)
	v_cvt_pk_bf16_f32 v7, v16, v17
	s_ashr_i32 s19, s18, 31
	s_waitcnt lgkmcnt(2)
	v_cvt_pk_bf16_f32 v17, v20, v21
	v_add_u32_e32 v20, s44, v12
	v_ashrrev_i32_e32 v21, 31, v20
	v_lshlrev_b64 v[20:21], 11, v[20:21]
	v_lshl_add_u64 v[20:21], s[16:17], 0, v[20:21]
	v_lshl_add_u64 v[20:21], s[18:19], 1, v[20:21]
	v_mov_b32_e32 v3, v1
	s_add_i32 s20, s20, s21
	s_add_i32 s42, s42, s43
	v_lshl_add_u64 v[20:21], v[20:21], 0, v[2:3]
	s_cmpk_lt_i32 s20, 0x100
	v_cvt_pk_bf16_f32 v16, v18, v19
	s_waitcnt lgkmcnt(1)
	v_cvt_pk_bf16_f32 v18, v22, v23
	s_waitcnt lgkmcnt(0)
	v_cvt_pk_bf16_f32 v19, v24, v25
	global_store_dwordx4 v[20:21], v[4:7], off
	global_store_dwordx4 v[20:21], v[16:19], off offset:16
	s_waitcnt lgkmcnt(0)
	s_barrier
	s_cbranch_scc0 .LBB0_279

; DI unsigned pk2(float a, float b) { f32x2 v = {a, b}; return __builtin_bit_cast(unsigned, __builtin_convertvector(v, bf2_t)); }
;     ...
; #pragma unroll
;         for (int i = 0; i < 16; ++i) tl[(ty + 4 * i) * 65 + tx] = tv[i];
;         __syncthreads();
;         const int rr = tid >> 2, c0 = (tid & 3) * 16;
;         u32x4 o0, o1;
;         o0.x = pk2(tl[(c0 + 0) * 65 + rr], tl[(c0 + 1) * 65 + rr]);   o0.y = pk2(tl[(c0 + 2) * 65 + rr], tl[(c0 + 3) * 65 + rr]);
;         o0.z = pk2(tl[(c0 + 4) * 65 + rr], tl[(c0 + 5) * 65 + rr]);   o0.w = pk2(tl[(c0 + 6) * 65 + rr], tl[(c0 + 7) * 65 + rr]);
;         o1.x = pk2(tl[(c0 + 8) * 65 + rr], tl[(c0 + 9) * 65 + rr]);   o1.y = pk2(tl[(c0 + 10) * 65 + rr], tl[(c0 + 11) * 65 + rr]);
;         o1.z = pk2(tl[(c0 + 12) * 65 + rr], tl[(c0 + 13) * 65 + rr]); o1.w = pk2(tl[(c0 + 14) * 65 + rr], tl[(c0 + 15) * 65 + rr]);
;         bf16_t* d = dst + (size_t)(n0 + rr) * K + k0 + c0;
;         *(u32x4*)d = o0; *(u32x4*)(d + 8) = o1;
;         __syncthreads();
.LBB0_281:
	s_or_b64 exec, exec, s[14:15]
	s_waitcnt vmcnt(0)
	ds_write_b32 v14, v3
	ds_write_b32 v15, v0 offset:1040
	ds_write_b32 v15, v16 offset:2080
	ds_write_b32 v15, v7 offset:3120
	ds_write_b32 v15, v18 offset:4160
	ds_write_b32 v15, v17 offset:5200
	ds_write_b32 v15, v20 offset:6240
	ds_write_b32 v15, v19 offset:7280
	ds_write_b32 v15, v22 offset:8320
	ds_write_b32 v15, v21 offset:9360
	ds_write_b32 v15, v24 offset:10400
	ds_write_b32 v15, v23 offset:11440
	ds_write_b32 v15, v26 offset:12480
	ds_write_b32 v15, v25 offset:13520
	ds_write_b32 v15, v28 offset:14560
	ds_write_b32 v15, v27 offset:15600
	v_add_u32_e32 v0, 0x400, v13
	s_waitcnt lgkmcnt(0)
	s_barrier
	ds_read2_b32 v[4:5], v13 offset1:65
	ds_read2_b32 v[6:7], v13 offset0:130 offset1:195
	ds_read2_b32 v[16:17], v0 offset0:4 offset1:69
	s_sub_i32 s14, 0, s21
	s_add_i32 s14, s18, s14
	s_waitcnt lgkmcnt(2)
	v_cvt_pk_bf16_f32 v4, v4, v5
	s_waitcnt lgkmcnt(1)
	v_cvt_pk_bf16_f32 v5, v6, v7
	s_waitcnt lgkmcnt(0)
	v_cvt_pk_bf16_f32 v6, v16, v17
	ds_read2_b32 v[16:17], v0 offset0:134 offset1:199
	v_add_u32_e32 v0, 0x800, v13
	ds_read2_b32 v[18:19], v0 offset0:8 offset1:73
	ds_read2_b32 v[20:21], v0 offset0:138 offset1:203
	v_add_u32_e32 v0, 0xc00, v13
	ds_read2_b32 v[22:23], v0 offset0:12 offset1:77
	ds_read2_b32 v[24:25], v0 offset0:142 offset1:207
	s_waitcnt lgkmcnt(4)
	v_cvt_pk_bf16_f32 v7, v16, v17
	s_ashr_i32 s15, s14, 31
	s_waitcnt lgkmcnt(2)
	v_cvt_pk_bf16_f32 v17, v20, v21
	v_add_u32_e32 v20, s20, v12
	v_ashrrev_i32_e32 v21, 31, v20
	v_lshlrev_b64 v[20:21], 11, v[20:21]
	v_lshl_add_u64 v[20:21], s[4:5], 0, v[20:21]
	v_lshl_add_u64 v[20:21], s[14:15], 1, v[20:21]
	v_mov_b32_e32 v3, v1
	s_add_i32 s16, s16, s17
	s_add_i32 s18, s18, s19
	v_lshl_add_u64 v[20:21], v[20:21], 0, v[2:3]
	s_cmpk_lt_i32 s16, 0x100
	v_cvt_pk_bf16_f32 v16, v18, v19
	s_waitcnt lgkmcnt(1)
	v_cvt_pk_bf16_f32 v18, v22, v23
	s_waitcnt lgkmcnt(0)
	v_cvt_pk_bf16_f32 v19, v24, v25
	global_store_dwordx4 v[20:21], v[4:7], off
	global_store_dwordx4 v[20:21], v[16:19], off offset:16
	s_waitcnt lgkmcnt(0)
	s_barrier
	s_cbranch_scc0 .LBB0_22

; DI unsigned pk2(float a, float b) { f32x2 v = {a, b}; return __builtin_bit_cast(unsigned, __builtin_convertvector(v, bf2_t)); }
; DI int tid8_op() { int t = threadIdx.x; asm volatile("" : "+v"(t)); return t; }
; DI void cvt_job(const float* __restrict__ src, bf16_t* __restrict__ dst, size_t n8) {
;     const size_t stride = (size_t)gridDim.x * 512;
;     for (size_t i0 = (size_t)blockIdx.x * 512 + tid8_op(); i0 < n8; i0 += 4 * stride) {
;         f32x4 a[4], b[4];
; #pragma unroll
;         for (int u = 0; u < 4; ++u) { const size_t i = i0 + u * stride; if (i < n8) { a[u] = *(const f32x4*)(src + i * 8); b[u] = *(const f32x4*)(src + i * 8 + 4); } }
; #pragma unroll
;         for (int u = 0; u < 4; ++u) { const size_t i = i0 + u * stride; if (i < n8) {
;             u32x4 o; o.x = pk2(a[u].x, a[u].y); o.y = pk2(a[u].z, a[u].w); o.z = pk2(b[u].x, b[u].y); o.w = pk2(b[u].z, b[u].w);
;             *(u32x4*)(dst + i * 8) = o; } }
;     }
; }
.LBB0_323:
	s_or_b64 exec, exec, s[38:39]
	s_waitcnt vmcnt(0)
	v_cvt_pk_bf16_f32 v28, v28, v29
	v_cvt_pk_bf16_f32 v29, v30, v31
	v_cvt_pk_bf16_f32 v30, v24, v25
	v_cvt_pk_bf16_f32 v31, v26, v27
	v_lshl_add_u64 v[24:25], s[36:37], 0, v[32:33]
	global_store_dwordx4 v[24:25], v[28:31], off
	s_and_saveexec_b64 s[38:39], vcc
	s_cbranch_execnz .LBB0_326
	s_or_b64 exec, exec, s[38:39]
	s_and_saveexec_b64 s[38:39], s[4:5]
	s_cbranch_execnz .LBB0_327

; DI unsigned pk2(float a, float b) { f32x2 v = {a, b}; return __builtin_bit_cast(unsigned, __builtin_convertvector(v, bf2_t)); }
; DI int tid8_op() { int t = threadIdx.x; asm volatile("" : "+v"(t)); return t; }
; DI void cvt_job(const float* __restrict__ src, bf16_t* __restrict__ dst, size_t n8) {
;     const size_t stride = (size_t)gridDim.x * 512;
;     for (size_t i0 = (size_t)blockIdx.x * 512 + tid8_op(); i0 < n8; i0 += 4 * stride) {
;         f32x4 a[4], b[4];
; #pragma unroll
;         for (int u = 0; u < 4; ++u) { const size_t i = i0 + u * stride; if (i < n8) { a[u] = *(const f32x4*)(src + i * 8); b[u] = *(const f32x4*)(src + i * 8 + 4); } }
; #pragma unroll
;         for (int u = 0; u < 4; ++u) { const size_t i = i0 + u * stride; if (i < n8) {
;             u32x4 o; o.x = pk2(a[u].x, a[u].y); o.y = pk2(a[u].z, a[u].w); o.z = pk2(b[u].x, b[u].y); o.w = pk2(b[u].z, b[u].w);
;             *(u32x4*)(dst + i * 8) = o; } }
;     }
; }
.LBB0_326:
	v_cvt_pk_bf16_f32 v24, v0, v1
	v_cvt_pk_bf16_f32 v25, v2, v3
	v_cvt_pk_bf16_f32 v26, v8, v9
	v_cvt_pk_bf16_f32 v27, v10, v11
	v_lshl_add_u64 v[28:29], s[36:37], 0, v[44:45]
	global_store_dwordx4 v[28:29], v[24:27], off
	s_or_b64 exec, exec, s[38:39]
	s_and_saveexec_b64 s[38:39], s[4:5]
	s_cbranch_execz .LBB0_325
.LBB0_327:
	v_cvt_pk_bf16_f32 v24, v4, v5
	v_cvt_pk_bf16_f32 v25, v6, v7
	v_cvt_pk_bf16_f32 v26, v16, v17
	v_cvt_pk_bf16_f32 v27, v18, v19
	v_lshl_add_u64 v[28:29], s[36:37], 0, v[38:39]
	global_store_dwordx4 v[28:29], v[24:27], off
	s_or_b64 exec, exec, s[38:39]
	s_and_saveexec_b64 s[4:5], s[6:7]
	s_cbranch_execz .LBB0_316
.LBB0_328:
	v_cvt_pk_bf16_f32 v24, v12, v13
	v_cvt_pk_bf16_f32 v25, v14, v15
	v_cvt_pk_bf16_f32 v26, v20, v21
	v_cvt_pk_bf16_f32 v27, v22, v23
	v_lshl_add_u64 v[28:29], s[36:37], 0, v[42:43]
	global_store_dwordx4 v[28:29], v[24:27], off
	s_branch .LBB0_316

; DI unsigned pk2(float a, float b) { f32x2 v = {a, b}; return __builtin_bit_cast(unsigned, __builtin_convertvector(v, bf2_t)); }
; DI int tid8_op() { int t = threadIdx.x; asm volatile("" : "+v"(t)); return t; }
; DI void cvt_job(const float* __restrict__ src, bf16_t* __restrict__ dst, size_t n8) {
;     const size_t stride = (size_t)gridDim.x * 512;
;     for (size_t i0 = (size_t)blockIdx.x * 512 + tid8_op(); i0 < n8; i0 += 4 * stride) {
;         f32x4 a[4], b[4];
; #pragma unroll
;         for (int u = 0; u < 4; ++u) { const size_t i = i0 + u * stride; if (i < n8) { a[u] = *(const f32x4*)(src + i * 8); b[u] = *(const f32x4*)(src + i * 8 + 4); } }
; #pragma unroll
;         for (int u = 0; u < 4; ++u) { const size_t i = i0 + u * stride; if (i < n8) {
;             u32x4 o; o.x = pk2(a[u].x, a[u].y); o.y = pk2(a[u].z, a[u].w); o.z = pk2(b[u].x, b[u].y); o.w = pk2(b[u].z, b[u].w);
;             *(u32x4*)(dst + i * 8) = o; } }
;     }
; }
.LBB0_338:
	s_or_b64 exec, exec, s[34:35]
	s_waitcnt vmcnt(0)
	v_cvt_pk_bf16_f32 v28, v28, v29
	v_cvt_pk_bf16_f32 v29, v30, v31
	v_cvt_pk_bf16_f32 v30, v24, v25
	v_cvt_pk_bf16_f32 v31, v26, v27
	v_lshl_add_u64 v[24:25], s[30:31], 0, v[32:33]
	global_store_dwordx4 v[24:25], v[28:31], off
	s_and_saveexec_b64 s[34:35], vcc
	s_cbranch_execnz .LBB0_341
	s_or_b64 exec, exec, s[34:35]
	s_and_saveexec_b64 s[34:35], s[4:5]
	s_cbranch_execnz .LBB0_342

; DI unsigned pk2(float a, float b) { f32x2 v = {a, b}; return __builtin_bit_cast(unsigned, __builtin_convertvector(v, bf2_t)); }
; DI int tid8_op() { int t = threadIdx.x; asm volatile("" : "+v"(t)); return t; }
; DI void cvt_job(const float* __restrict__ src, bf16_t* __restrict__ dst, size_t n8) {
;     const size_t stride = (size_t)gridDim.x * 512;
;     for (size_t i0 = (size_t)blockIdx.x * 512 + tid8_op(); i0 < n8; i0 += 4 * stride) {
;         f32x4 a[4], b[4];
; #pragma unroll
;         for (int u = 0; u < 4; ++u) { const size_t i = i0 + u * stride; if (i < n8) { a[u] = *(const f32x4*)(src + i * 8); b[u] = *(const f32x4*)(src + i * 8 + 4); } }
; #pragma unroll
;         for (int u = 0; u < 4; ++u) { const size_t i = i0 + u * stride; if (i < n8) {
;             u32x4 o; o.x = pk2(a[u].x, a[u].y); o.y = pk2(a[u].z, a[u].w); o.z = pk2(b[u].x, b[u].y); o.w = pk2(b[u].z, b[u].w);
;             *(u32x4*)(dst + i * 8) = o; } }
;     }
; }
.LBB0_341:
	v_cvt_pk_bf16_f32 v24, v0, v1
	v_cvt_pk_bf16_f32 v25, v2, v3
	v_cvt_pk_bf16_f32 v26, v8, v9
	v_cvt_pk_bf16_f32 v27, v10, v11
	v_lshl_add_u64 v[28:29], s[30:31], 0, v[44:45]
	global_store_dwordx4 v[28:29], v[24:27], off
	s_or_b64 exec, exec, s[34:35]
	s_and_saveexec_b64 s[34:35], s[4:5]
	s_cbranch_execz .LBB0_340
.LBB0_342:
	v_cvt_pk_bf16_f32 v24, v4, v5
	v_cvt_pk_bf16_f32 v25, v6, v7
	v_cvt_pk_bf16_f32 v26, v16, v17
	v_cvt_pk_bf16_f32 v27, v18, v19
	v_lshl_add_u64 v[28:29], s[30:31], 0, v[38:39]
	global_store_dwordx4 v[28:29], v[24:27], off
	s_or_b64 exec, exec, s[34:35]
	s_and_saveexec_b64 s[4:5], s[6:7]
	s_cbranch_execz .LBB0_331
.LBB0_343:
	v_cvt_pk_bf16_f32 v24, v12, v13
	v_cvt_pk_bf16_f32 v25, v14, v15
	v_cvt_pk_bf16_f32 v26, v20, v21
	v_cvt_pk_bf16_f32 v27, v22, v23
	v_lshl_add_u64 v[28:29], s[30:31], 0, v[42:43]
	global_store_dwordx4 v[28:29], v[24:27], off
	s_branch .LBB0_331

; DI int tid8_op() { int t = threadIdx.x; asm volatile("" : "+v"(t)); return t; }
; DI void prologue(const Params& p, unsigned char* smem) {
;     ...
;     float* cs = (float*)(ws + O_COS); float* sn = (float*)(ws + O_SIN);
;     for (int idx = blockIdx.x * 512 + tid8_op(); idx < T_ * 16; idx += gridDim.x * 512) {
;         const int t = idx >> 4, i = idx & 15;
;         const float inv = (float)exp2(-(double)i * (2.0 / 32.0) * 13.287712379549449);
;         const float ang = (float)p.pos[t] * inv;
;         const double rr = (double)ang - 6.283185307179586476925 * rint((double)ang * 0.15915494309189533577);
;         const float rf = (float)rr;
;         cs[idx] = cosf(rf); sn[idx] = sinf(rf);
;     }
.LBB0_346:
	s_or_b64 exec, exec, s[4:5]
	v_mul_f32_e32 v2, v15, v15
	v_fmamk_f32 v12, v2, 0xb94c1982, v5
	v_fmaak_f32 v12, v2, v12, 0xbe2aaa9d
	v_mul_f32_e32 v12, v2, v12
	v_fmac_f32_e32 v15, v15, v12
	v_fmamk_f32 v12, v2, 0x37d75334, v6
	v_fmaak_f32 v12, v2, v12, 0x3d2aabf7
	v_fmaak_f32 v12, v2, v12, 0xbf000004
	v_fma_f32 v2, v2, v12, 1.0
	v_and_b32_e32 v12, 1, v14
	v_cmp_eq_u32_e64 s[4:5], 0, v12
	v_lshlrev_b32_e32 v12, 30, v14
	v_and_b32_e32 v12, 0x80000000, v12
	v_xor_b32_e32 v10, v11, v10
	v_cndmask_b32_e64 v2, v2, v15, s[4:5]
	v_xor_b32_e32 v10, v10, v12
	v_xor_b32_e32 v2, v10, v2
	v_lshl_add_u64 v[10:11], v[0:1], 2, s[16:17]
	v_add_u32_e32 v0, s0, v0
	v_cndmask_b32_e32 v2, v7, v2, vcc
	v_cmp_lt_i32_e32 vcc, s39, v0
	s_or_b64 s[18:19], vcc, s[18:19]
	global_store_dword v[10:11], v2, off
	s_andn2_b64 exec, exec, s[18:19]
	s_cbranch_execz .LBB0_355

; DI int tid8_op() { int t = threadIdx.x; asm volatile("" : "+v"(t)); return t; }
; DI void prologue(const Params& p, unsigned char* smem) {
;     ...
;     float* cs = (float*)(ws + O_COS); float* sn = (float*)(ws + O_SIN);
;     for (int idx = blockIdx.x * 512 + tid8_op(); idx < T_ * 16; idx += gridDim.x * 512) {
;         const int t = idx >> 4, i = idx & 15;
;         const float inv = (float)exp2(-(double)i * (2.0 / 32.0) * 13.287712379549449);
;         const float ang = (float)p.pos[t] * inv;
;         const double rr = (double)ang - 6.283185307179586476925 * rint((double)ang * 0.15915494309189533577);
;         const float rf = (float)rr;
;         cs[idx] = cosf(rf); sn[idx] = sinf(rf);
;     }
.LBB0_349:
	s_or_saveexec_b64 s[4:5], s[24:25]
	v_mul_f32_e64 v2, |v10|, s35
	v_rndne_f32_e32 v2, v2
	s_xor_b64 exec, exec, s[4:5]
	v_cvt_i32_f32_e32 v1, v2
	v_fma_f32 v14, v2, s36, |v10|
	v_fmac_f32_e32 v14, 0xb3a22168, v2
	v_fmac_f32_e32 v14, 0xa7c234c4, v2
	s_or_b64 exec, exec, s[4:5]
	v_mul_f32_e32 v15, v14, v14
	v_fmamk_f32 v16, v15, 0xb94c1982, v5
	v_fmaak_f32 v16, v15, v16, 0xbe2aaa9d
	v_mul_f32_e32 v16, v15, v16
	v_fmac_f32_e32 v14, v14, v16
	v_fmamk_f32 v16, v15, 0x37d75334, v6
	v_fmaak_f32 v16, v15, v16, 0x3d2aabf7
	v_fmaak_f32 v16, v15, v16, 0xbf000004
	v_fma_f32 v15, v15, v16, 1.0
	v_and_b32_e32 v16, 1, v1
	v_cmp_eq_u32_e32 vcc, 0, v16
	v_lshlrev_b32_e32 v1, 30, v1
	s_nop 0
	v_cndmask_b32_e64 v14, -v14, v15, vcc
	v_bitop3_b32 v1, v1, v14, s37 bitop3:0x6c
	v_cmp_class_f32_e64 vcc, v10, s38
	s_nop 1
	v_cndmask_b32_e32 v16, v7, v1, vcc
	v_ashrrev_i32_e32 v1, 31, v0
	v_lshl_add_u64 v[14:15], v[0:1], 2, s[14:15]
	global_store_dword v[14:15], v16, off
	s_and_saveexec_b64 s[4:5], s[10:11]
	s_xor_b64 s[24:25], exec, s[4:5]
	s_cbranch_execz .LBB0_353
	v_cmp_lt_u32_e64 s[4:5], 63, v13
	v_mad_u64_u32 v[14:15], s[10:11], v12, s3, 0
	s_nop 0
	v_cndmask_b32_e64 v2, 0, v8, s[4:5]
	v_add_u32_e32 v2, v2, v13
	v_cmp_lt_u32_e64 s[6:7], 31, v2
	s_nop 1
	v_cndmask_b32_e64 v13, 0, v9, s[6:7]
	v_add_u32_e32 v2, v13, v2
	v_cmp_lt_u32_e64 s[8:9], 31, v2
	s_nop 1
	v_cndmask_b32_e64 v13, 0, v9, s[8:9]
	v_add_u32_e32 v26, v13, v2
	v_mov_b32_e32 v2, v15
	v_mad_u64_u32 v[16:17], s[10:11], v12, s26, v[2:3]
	v_mov_b32_e32 v2, v17
	v_mad_u64_u32 v[18:19], s[10:11], v12, s27, v[2:3]
	v_mov_b32_e32 v2, v19
	v_mad_u64_u32 v[20:21], s[10:11], v12, s28, v[2:3]
	v_mov_b32_e32 v2, v21
	v_mad_u64_u32 v[22:23], s[10:11], v12, s29, v[2:3]
	v_mov_b32_e32 v2, v23
	v_mad_u64_u32 v[24:25], s[10:11], v12, s30, v[2:3]
	v_mov_b32_e32 v2, v25
	v_mad_u64_u32 v[12:13], s[10:11], v12, s31, v[2:3]
	v_cndmask_b32_e64 v15, v24, v20, s[4:5]
	v_cndmask_b32_e64 v2, v12, v22, s[4:5]
	v_cndmask_b32_e64 v13, v13, v24, s[4:5]
	v_cndmask_b32_e64 v12, v2, v15, s[6:7]
	v_cndmask_b32_e64 v2, v13, v2, s[6:7]
	v_cndmask_b32_e64 v13, v22, v18, s[4:5]
	v_cndmask_b32_e64 v15, v15, v13, s[6:7]
	v_cndmask_b32_e64 v16, v20, v16, s[4:5]
	v_cndmask_b32_e64 v2, v2, v12, s[8:9]
	v_cndmask_b32_e64 v12, v12, v15, s[8:9]
	v_sub_u32_e32 v17, 32, v26
	v_cndmask_b32_e64 v13, v13, v16, s[6:7]
	v_alignbit_b32 v19, v2, v12, v17
	v_cmp_eq_u32_e64 s[10:11], 0, v26
	v_cndmask_b32_e64 v15, v15, v13, s[8:9]
	v_cndmask_b32_e64 v14, v18, v14, s[4:5]
	v_cndmask_b32_e64 v2, v19, v2, s[10:11]
	v_alignbit_b32 v19, v12, v15, v17
	v_cndmask_b32_e64 v12, v19, v12, s[10:11]
	v_bfe_u32 v21, v2, 29, 1
	v_cndmask_b32_e64 v14, v16, v14, s[6:7]
	v_alignbit_b32 v19, v2, v12, 30
	v_sub_u32_e32 v22, 0, v21
	v_cndmask_b32_e64 v13, v13, v14, s[8:9]
	v_xor_b32_e32 v19, v19, v22
	v_alignbit_b32 v14, v15, v13, v17
	v_cndmask_b32_e64 v14, v14, v15, s[10:11]
	v_ffbh_u32_e32 v15, v19
	v_alignbit_b32 v12, v12, v14, 30
	v_min_u32_e32 v15, 32, v15
	v_alignbit_b32 v13, v14, v13, 30
	v_xor_b32_e32 v12, v12, v22
	v_sub_u32_e32 v16, 31, v15
	v_xor_b32_e32 v13, v13, v22
	v_alignbit_b32 v17, v19, v12, v16
	v_alignbit_b32 v12, v12, v13, v16
	v_alignbit_b32 v13, v17, v12, 9
	v_ffbh_u32_e32 v14, v13
	v_min_u32_e32 v14, 32, v14
	v_lshrrev_b32_e32 v20, 29, v2
	v_not_b32_e32 v16, v14
	v_alignbit_b32 v12, v13, v12, v16
	v_lshlrev_b32_e32 v13, 31, v20
	v_or_b32_e32 v16, 0x33000000, v13
	v_add_lshl_u32 v14, v14, v15, 23
	v_lshrrev_b32_e32 v12, 9, v12
	v_sub_u32_e32 v14, v16, v14
	v_or_b32_e32 v13, 0.5, v13
	v_lshlrev_b32_e32 v15, 23, v15
	v_or_b32_e32 v12, v14, v12
	v_lshrrev_b32_e32 v14, 9, v17
	v_sub_u32_e32 v13, v13, v15
	v_or_b32_e32 v13, v14, v13
	v_mul_f32_e32 v14, 0x3fc90fda, v13
	v_fma_f32 v15, v13, s34, -v14
	v_fmac_f32_e32 v15, 0x33a22168, v13
	v_fmac_f32_e32 v15, 0x3fc90fda, v12
	v_lshrrev_b32_e32 v2, 30, v2
	v_add_f32_e32 v15, v14, v15
	v_add_u32_e32 v14, v21, v2

; DI unsigned xb_ld(unsigned* p)              { return __hip_atomic_load(p, __ATOMIC_RELAXED, __HIP_MEMORY_SCOPE_AGENT); }
; DI void xcd_barrier_complete(unsigned* bar, unsigned x, unsigned& nloc, unsigned& nx) {
;     const unsigned G = gridDim.x * gridDim.y * gridDim.z;
;     unsigned sum, cnt, mine, sp = 0u;
;     for (;;) {
;         sum = 0u; cnt = 0u; mine = 0u;
; #pragma unroll
;         for (unsigned j = 0; j < 16; ++j) { const unsigned c = xb_ld(&bar[XB_XCNT(j)]); sum += c; cnt += (c > 0u) ? 1u : 0u; mine = (j == x) ? c : mine; }
;         if (sum == G) break;
;         __builtin_amdgcn_s_sleep(1);
;         if ((++sp & 255u) == 0u) { if (xb_ld(&bar[XB_TMO])) break; if (sp > XB_SPIN_CAP) { atomicAdd(&bar[XB_TMO], 1u); break; } }
;     }
;     nloc = mine > 0u ? mine : 1u; nx = cnt > 0u ? cnt : 1u;
; }
.LBB0_360:
	global_load_dword v25, v[0:1], off offset:1024 sc1
	global_load_dword v10, v[0:1], off offset:1280 sc1
	global_load_dword v11, v[0:1], off offset:1536 sc1
	global_load_dword v12, v[0:1], off offset:1792 sc1
	global_load_dword v13, v[0:1], off offset:2048 sc1
	global_load_dword v14, v[0:1], off offset:2304 sc1
	global_load_dword v15, v[0:1], off offset:2560 sc1
	global_load_dword v16, v[0:1], off offset:2816 sc1
	global_load_dword v17, v[0:1], off offset:3072 sc1
	global_load_dword v18, v[0:1], off offset:3328 sc1
	global_load_dword v19, v[0:1], off offset:3584 sc1
	global_load_dword v20, v[0:1], off offset:3840 sc1
	global_load_dword v21, v[2:3], off sc1
	global_load_dword v22, v[4:5], off sc1
	global_load_dword v23, v[6:7], off sc1
	global_load_dword v24, v[8:9], off sc1
	s_or_b64 s[10:11], s[10:11], exec
	s_or_b64 s[8:9], s[8:9], exec
	s_waitcnt vmcnt(0) lgkmcnt(0)
	v_add_u32_e32 v26, v10, v25
	v_add_u32_e32 v26, v26, v11
	v_add_u32_e32 v26, v26, v12
	v_add_u32_e32 v26, v26, v13
	v_add_u32_e32 v26, v26, v14
	v_add_u32_e32 v26, v26, v15
	v_add_u32_e32 v26, v26, v16
	v_add_u32_e32 v26, v26, v17
	v_add_u32_e32 v26, v26, v18
	v_add_u32_e32 v26, v26, v19
	v_add_u32_e32 v26, v26, v20
	v_add_u32_e32 v26, v26, v21
	v_add_u32_e32 v26, v26, v22
	v_add_u32_e32 v26, v26, v23
	v_add_u32_e32 v26, v26, v24
	v_cmp_ne_u32_e32 vcc, s1, v26
	s_and_saveexec_b64 s[12:13], vcc
	s_cbranch_execz .LBB0_359
	s_and_b32 s16, s3, 0xff
	s_mov_b64 s[14:15], -1
	s_cmp_eq_u32 s16, 0
	s_mov_b64 s[18:19], -1
	s_mov_b64 s[16:17], -1
	s_sleep 1
	s_cbranch_scc1 .LBB0_363
	s_and_saveexec_b64 s[20:21], s[18:19]
	s_cbranch_execz .LBB0_358
	s_branch .LBB0_366
.LBB0_363:
	global_load_dword v26, v[0:1], off offset:512 sc1
	s_mov_b64 s[18:19], 0
	s_waitcnt vmcnt(0) lgkmcnt(0)
	v_cmp_eq_u32_e32 vcc, 0, v26
	s_and_saveexec_b64 s[20:21], vcc
	s_cmp_lt_u32 s3, 0x40001
	s_cselect_b64 s[18:19], -1, 0
	s_xor_b64 s[16:17], exec, -1
	s_and_b64 s[18:19], s[18:19], exec
	s_or_b64 exec, exec, s[20:21]
	s_and_saveexec_b64 s[20:21], s[18:19]
	s_cbranch_execz .LBB0_358

; DI unsigned xb_xcc_id() { return (unsigned)__builtin_amdgcn_readfirstlane((int)(__builtin_amdgcn_s_getreg((3 << 11) | 20) & 0xFu)); }
; DI unsigned xb_ld(unsigned* p)              { return __hip_atomic_load(p, __ATOMIC_RELAXED, __HIP_MEMORY_SCOPE_AGENT); }
; DI unsigned xb_add(unsigned* p, unsigned v) { return __hip_atomic_fetch_add(p, v, __ATOMIC_RELAXED, __HIP_MEMORY_SCOPE_AGENT); }
; #define XB_SPIN(cond, bar) do { unsigned _sp = 0; while (cond) { __builtin_amdgcn_s_sleep(1); \
;     if ((++_sp & 255u) == 0u) { if (xb_ld(&(bar)[XB_TMO])) break; if (_sp > XB_SPIN_CAP) { atomicAdd(&(bar)[XB_TMO], 1u); break; } } } } while (0)
; DI void xcd_barrier(const XcdBarrier& b) {
;     ...
;         const unsigned bx = xb_xcc_id();
;         __builtin_amdgcn_s_waitcnt(0);
;         unsigned nloc = b.st[0], nx = b.st[1];
;         if (nloc == 0u) { xcd_barrier_complete(bar, bx, nloc, nx); b.st[0] = nloc; b.st[1] = nx; }
;         const unsigned old = xb_add(&bar[XB_XSUB(bx)], 1u);
;         const unsigned gen = old / nloc;
;         if (old + 1u == (gen + 1u) * nloc) {
;             __builtin_amdgcn_fence(__ATOMIC_RELEASE, "agent");
;             asm volatile("s_waitcnt vmcnt(0)" ::: "memory");
;             const unsigned og = xb_add(&bar[XB_TOP], 1u);
;             const unsigned tg = og / nx;
;             if (og + 1u == (tg + 1u) * nx) xb_add(&bar[XB_TOPGEN], 1u);
;             else XB_SPIN(xb_ld(&bar[XB_TOPGEN]) == tg, bar);
;             __builtin_amdgcn_fence(__ATOMIC_ACQUIRE, "agent");
;             xb_add(&bar[XB_XGEN(bx)], 1u);
;             asm volatile("s_waitcnt vmcnt(0)" ::: "memory");
;         } else {
;             XB_SPIN(xb_ld(&bar[XB_XGEN(bx)]) == gen, bar);
.LBB0_370:
	s_lshl_b32 s0, s0, 8
	s_add_u32 s1, s38, s0
	s_addc_u32 s0, s39, 0
	v_mov_b32_e32 v1, s1
	v_add_co_u32_e32 v4, vcc, 0x1000, v1
	v_mov_b32_e32 v1, s0
	s_nop 0
	v_addc_co_u32_e32 v5, vcc, 0, v1, vcc
	v_mov_b32_e32 v1, 1
	flat_atomic_add v1, v[4:5], v1 offset:1024 sc0
	v_cvt_f32_u32_e32 v3, v2
	v_sub_u32_e32 v4, 0, v2
	v_rcp_iflag_f32_e32 v3, v3
	s_nop 0
	v_mul_f32_e32 v3, 0x4f7ffffe, v3
	v_cvt_u32_f32_e32 v3, v3
	v_mul_lo_u32 v4, v4, v3
	v_mul_hi_u32 v4, v3, v4
	v_add_u32_e32 v3, v3, v4
	s_waitcnt vmcnt(0) lgkmcnt(0)
	v_mul_hi_u32 v3, v1, v3
	v_mul_lo_u32 v5, v3, v2
	v_add_u32_e32 v4, 1, v1
	v_sub_u32_e32 v1, v1, v5
	v_add_u32_e32 v6, 1, v3
	v_cmp_ge_u32_e32 vcc, v1, v2
	v_sub_u32_e32 v5, v1, v2
	s_nop 0
	v_cndmask_b32_e32 v3, v3, v6, vcc
	v_cndmask_b32_e32 v1, v1, v5, vcc
	v_add_u32_e32 v5, 1, v3
	v_cmp_ge_u32_e32 vcc, v1, v2
	s_nop 1
	v_cndmask_b32_e32 v1, v3, v5, vcc
	v_mad_u64_u32 v[2:3], s[4:5], v2, v1, v[2:3]
	v_cmp_ne_u32_e32 vcc, v4, v2
	s_and_saveexec_b64 s[4:5], vcc
	s_xor_b64 s[4:5], exec, s[4:5]
	s_cbranch_execz .LBB0_383
	v_mov_b32_e32 v0, s1
	v_add_co_u32_e32 v2, vcc, 0x2000, v0
	v_mov_b32_e32 v0, s0
	s_nop 0
	v_addc_co_u32_e32 v3, vcc, 0, v0, vcc
	global_load_dword v0, v[2:3], off offset:1024 sc1
	s_add_u32 s8, s1, 0x2400
	s_addc_u32 s9, s0, 0
	s_waitcnt vmcnt(0) lgkmcnt(0)
	v_cmp_eq_u32_e32 vcc, v0, v1
	s_and_saveexec_b64 s[6:7], vcc
	s_cbranch_execz .LBB0_382
	s_mov_b32 s3, 1
	s_mov_b64 s[10:11], 0
	s_branch .LBB0_374

; DI unsigned xb_ld(unsigned* p)              { return __hip_atomic_load(p, __ATOMIC_RELAXED, __HIP_MEMORY_SCOPE_AGENT); }
; #define XB_SPIN(cond, bar) do { unsigned _sp = 0; while (cond) { __builtin_amdgcn_s_sleep(1); \
;     if ((++_sp & 255u) == 0u) { if (xb_ld(&(bar)[XB_TMO])) break; if (_sp > XB_SPIN_CAP) { atomicAdd(&(bar)[XB_TMO], 1u); break; } } } } while (0)
; DI void xcd_barrier(const XcdBarrier& b) {
;     ...
;         } else {
;             XB_SPIN(xb_ld(&bar[XB_XGEN(bx)]) == gen, bar);
;             __builtin_amdgcn_fence(__ATOMIC_ACQUIRE, "agent");
.LBB0_374:
	s_and_b32 s18, s3, 0xff
	s_mov_b64 s[16:17], -1
	s_cmp_lg_u32 s18, 0
	s_mov_b64 s[18:19], -1
	s_sleep 1
	s_cbranch_scc1 .LBB0_378
	v_mov_b64_e32 v[2:3], s[38:39]
	global_load_dword v0, v[2:3], off offset:512 sc1
	s_mov_b64 s[18:19], 0
	s_mov_b64 s[20:21], -1
	s_waitcnt vmcnt(0) lgkmcnt(0)
	v_cmp_eq_u32_e32 vcc, 0, v0
	s_and_saveexec_b64 s[22:23], vcc
	s_cmp_lt_u32 s3, 0x40001
	s_cselect_b64 s[18:19], -1, 0
	s_xor_b64 s[20:21], exec, -1
	s_and_b64 s[18:19], s[18:19], exec
	s_or_b64 exec, exec, s[22:23]
.LBB0_378:
	s_andn2_b64 s[14:15], s[14:15], exec
	s_and_b64 s[20:21], s[20:21], exec
	s_or_b64 s[14:15], s[14:15], s[20:21]
	s_and_saveexec_b64 s[20:21], s[18:19]
	s_cbranch_execz .LBB0_373
	v_mov_b64_e32 v[2:3], s[8:9]
	global_load_dword v0, v[2:3], off sc1
	s_add_i32 s3, s3, 1
	s_or_b64 s[14:15], s[14:15], exec
	s_waitcnt vmcnt(0) lgkmcnt(0)
	v_cmp_ne_u32_e32 vcc, v0, v1
	s_orn2_b64 s[16:17], vcc, exec
	s_branch .LBB0_373

; DI unsigned xb_ld(unsigned* p)              { return __hip_atomic_load(p, __ATOMIC_RELAXED, __HIP_MEMORY_SCOPE_AGENT); }
; DI unsigned xb_add(unsigned* p, unsigned v) { return __hip_atomic_fetch_add(p, v, __ATOMIC_RELAXED, __HIP_MEMORY_SCOPE_AGENT); }
; #define XB_SPIN(cond, bar) do { unsigned _sp = 0; while (cond) { __builtin_amdgcn_s_sleep(1); \
;     if ((++_sp & 255u) == 0u) { if (xb_ld(&(bar)[XB_TMO])) break; if (_sp > XB_SPIN_CAP) { atomicAdd(&(bar)[XB_TMO], 1u); break; } } } } while (0)
; DI void xcd_barrier(const XcdBarrier& b) {
;     ...
;         if (old + 1u == (gen + 1u) * nloc) {
;             __builtin_amdgcn_fence(__ATOMIC_RELEASE, "agent");
;             asm volatile("s_waitcnt vmcnt(0)" ::: "memory");
;             const unsigned og = xb_add(&bar[XB_TOP], 1u);
;             const unsigned tg = og / nx;
;             if (og + 1u == (tg + 1u) * nx) xb_add(&bar[XB_TOPGEN], 1u);
;             else XB_SPIN(xb_ld(&bar[XB_TOPGEN]) == tg, bar);
.LBB0_383:
	s_andn2_saveexec_b64 s[4:5], s[4:5]
	s_cbranch_execz .LBB0_399
	v_mov_b32_e32 v1, s38
	v_add_co_u32_e32 v2, vcc, 0x3000, v1
	v_mov_b32_e32 v1, s39
	buffer_wbl2 sc1
	s_waitcnt vmcnt(0)
	v_addc_co_u32_e32 v3, vcc, 0, v1, vcc
	v_mov_b32_e32 v1, 1
	flat_atomic_add v1, v[2:3], v1 offset:1024 sc0
	v_cvt_f32_u32_e32 v2, v0
	v_sub_u32_e32 v3, 0, v0
	s_add_u32 s4, s38, 0x3500
	s_addc_u32 s5, s39, 0
	v_rcp_iflag_f32_e32 v2, v2
	s_mov_b64 s[8:9], -1
	v_mul_f32_e32 v2, 0x4f7ffffe, v2
	v_cvt_u32_f32_e32 v2, v2
	v_mul_lo_u32 v3, v3, v2
	v_mul_hi_u32 v3, v2, v3
	v_add_u32_e32 v2, v2, v3
	s_waitcnt vmcnt(0) lgkmcnt(0)
	v_mul_hi_u32 v2, v1, v2
	v_mul_lo_u32 v4, v2, v0
	v_add_u32_e32 v3, 1, v1
	v_sub_u32_e32 v1, v1, v4
	v_add_u32_e32 v5, 1, v2
	v_cmp_ge_u32_e32 vcc, v1, v0
	v_sub_u32_e32 v4, v1, v0
	s_nop 0
	v_cndmask_b32_e32 v2, v2, v5, vcc
	v_cndmask_b32_e32 v1, v1, v4, vcc
	v_add_u32_e32 v4, 1, v2
	v_cmp_ge_u32_e32 vcc, v1, v0
	s_nop 1
	v_cndmask_b32_e32 v2, v2, v4, vcc
	v_mad_u64_u32 v[0:1], s[6:7], v0, v2, v[0:1]
	v_cmp_ne_u32_e32 vcc, v3, v0
	v_mov_b64_e32 v[0:1], s[4:5]
	s_and_saveexec_b64 s[6:7], vcc
	s_cbranch_execz .LBB0_396
	v_mov_b64_e32 v[0:1], s[4:5]
	global_load_dword v0, v[0:1], off sc1
	s_mov_b64 s[12:13], 0
	s_waitcnt vmcnt(0) lgkmcnt(0)
	v_cmp_eq_u32_e32 vcc, v0, v2
	s_and_saveexec_b64 s[10:11], vcc
	s_cbranch_execz .LBB0_395
	s_add_u32 s8, s38, 0x200
	s_addc_u32 s9, s39, 0
	s_mov_b32 s3, 1
	s_branch .LBB0_388

; DI unsigned xb_ld(unsigned* p)              { return __hip_atomic_load(p, __ATOMIC_RELAXED, __HIP_MEMORY_SCOPE_AGENT); }
; #define XB_SPIN(cond, bar) do { unsigned _sp = 0; while (cond) { __builtin_amdgcn_s_sleep(1); \
;     if ((++_sp & 255u) == 0u) { if (xb_ld(&(bar)[XB_TMO])) break; if (_sp > XB_SPIN_CAP) { atomicAdd(&(bar)[XB_TMO], 1u); break; } } } } while (0)
; DI void xcd_barrier(const XcdBarrier& b) {
;     ...
;             else XB_SPIN(xb_ld(&bar[XB_TOPGEN]) == tg, bar);
.LBB0_390:
	v_mov_b64_e32 v[0:1], s[8:9]
	global_load_dword v0, v[0:1], off sc1
	s_mov_b64 s[18:19], 0
	s_mov_b64 s[16:17], -1
	s_waitcnt vmcnt(0) lgkmcnt(0)
	v_cmp_eq_u32_e32 vcc, 0, v0
	s_and_saveexec_b64 s[20:21], vcc
	s_cmp_lt_u32 s3, 0x40001
	s_cselect_b64 s[18:19], -1, 0
	s_xor_b64 s[16:17], exec, -1
	s_and_b64 s[18:19], s[18:19], exec
	s_or_b64 exec, exec, s[20:21]
	s_mov_b64 s[20:21], -1
	s_and_saveexec_b64 s[22:23], s[18:19]
	s_cbranch_execz .LBB0_387
.LBB0_393:
	v_mov_b64_e32 v[0:1], s[4:5]
	global_load_dword v0, v[0:1], off sc1
	s_add_i32 s3, s3, 1
	s_or_b64 s[16:17], s[16:17], exec
	s_waitcnt vmcnt(0) lgkmcnt(0)
	v_cmp_ne_u32_e32 vcc, v0, v2
	s_orn2_b64 s[20:21], vcc, exec
	s_branch .LBB0_387

; DI bf16_t tobf(float a) { return (bf16_t)(pk2(a, 0.f) & 0xffffu); }
; template <typename T> DI T* opaque(T* p) { asm volatile("" : "+v"(p) : : "memory"); return p; }
;     DI void operator()(const pg8::f32x4 (&acc)[2][2][4][2], const pg8::Unit& u, int wr, int wc, int fr, int fq) const {
;     ...
;                 } else {
;                     bf16_t* pb = (bf16_t*)(ws + o_vt) + ((size_t)bh * 64 + d0) * S_ + s0;
; #pragma unroll
;                     for (int ai = 0; ai < 2; ++ai)
; #pragma unroll
;                         for (int m = 0; m < 4; ++m) {
;                             bf16_t* q = opaque(pb + ai * 128 + m * 16);
;                             const f32x4 v0 = acc[ai][bj][m][0], v1 = acc[ai][bj][m][1];
;                             q[0] = tobf(v0.x); q[(size_t)S_] = tobf(v0.y); q[(size_t)2 * S_] = tobf(v0.z); q[(size_t)3 * S_] = tobf(v0.w);
;                             q[(size_t)4 * S_] = tobf(v1.x); q[(size_t)5 * S_] = tobf(v1.y); q[(size_t)6 * S_] = tobf(v1.z); q[(size_t)7 * S_] = tobf(v1.w);
;                         }
.LBB0_419:
	s_add_i32 s31, s24, s48
	s_bfe_u32 s24, s31, 0x20006
	s_or_b32 s24, s24, s17
	s_cmpk_gt_u32 s31, 0x1ff
	s_mov_b64 s[28:29], -1
	s_cbranch_scc0 .LBB0_421
	s_add_u32 s28, s8, s26
	s_addc_u32 s29, s9, s27
	s_ashr_i32 s25, s24, 31
	s_lshl_b64 s[26:27], s[24:25], 20
	s_add_u32 s26, s28, s26
	s_addc_u32 s27, s29, s27
	v_lshlrev_b32_e32 v0, 1, v142
	v_lshl_add_u64 v[148:149], s[26:27], 0, v[0:1]
	v_lshlrev_b32_e32 v0, 1, v170
	v_lshl_add_u64 v[148:149], v[148:149], 0, v[0:1]
	v_mov_b64_e32 v[150:151], v[148:149]
	v_cvt_pk_bf16_f32 v0, v126, s0
	v_add_co_u32_e32 v172, vcc, s86, v150
	s_waitcnt vmcnt(0)
	global_store_short v[150:151], v0, off
	v_cvt_pk_bf16_f32 v0, v127, s0
	v_addc_co_u32_e32 v173, vcc, 0, v151, vcc
	global_store_short v[172:173], v0, off
	v_add_co_u32_e32 v172, vcc, s67, v150
	v_cvt_pk_bf16_f32 v0, v128, s0
	s_nop 0
	v_addc_co_u32_e32 v173, vcc, 0, v151, vcc
	global_store_short v[172:173], v0, off
	v_add_co_u32_e32 v172, vcc, s89, v150
	v_cvt_pk_bf16_f32 v0, v129, s0
	s_nop 0
	v_addc_co_u32_e32 v173, vcc, 0, v151, vcc
	global_store_short v[172:173], v0, off
	v_add_co_u32_e32 v172, vcc, s63, v150
	v_cvt_pk_bf16_f32 v0, v122, s0
	s_nop 0
	v_addc_co_u32_e32 v173, vcc, 0, v151, vcc
	global_store_short v[172:173], v0, off
	v_add_co_u32_e32 v172, vcc, s85, v150
	v_cvt_pk_bf16_f32 v0, v123, s0
	s_nop 0
	v_addc_co_u32_e32 v173, vcc, 0, v151, vcc
	global_store_short v[172:173], v0, off
	v_add_co_u32_e32 v172, vcc, s87, v150
	v_cvt_pk_bf16_f32 v0, v124, s0
	s_nop 0
	v_addc_co_u32_e32 v173, vcc, 0, v151, vcc
	v_add_co_u32_e32 v150, vcc, s88, v150
	global_store_short v[172:173], v0, off
	v_cvt_pk_bf16_f32 v0, v125, s0
	v_addc_co_u32_e32 v151, vcc, 0, v151, vcc
	global_store_short v[150:151], v0, off
	v_lshl_add_u64 v[150:151], v[148:149], 0, 32
	v_cvt_pk_bf16_f32 v0, v118, s0
	v_add_co_u32_e32 v172, vcc, s86, v150
	global_store_short v[150:151], v0, off
	v_cvt_pk_bf16_f32 v0, v119, s0
	v_addc_co_u32_e32 v173, vcc, 0, v151, vcc
	global_store_short v[172:173], v0, off
	v_add_co_u32_e32 v172, vcc, s67, v150
	v_cvt_pk_bf16_f32 v0, v120, s0
	s_nop 0
	v_addc_co_u32_e32 v173, vcc, 0, v151, vcc
	global_store_short v[172:173], v0, off
	v_add_co_u32_e32 v172, vcc, s89, v150
	v_cvt_pk_bf16_f32 v0, v121, s0
	s_nop 0
	v_addc_co_u32_e32 v173, vcc, 0, v151, vcc
	global_store_short v[172:173], v0, off
	v_add_co_u32_e32 v172, vcc, s63, v150
	v_cvt_pk_bf16_f32 v0, v114, s0
	s_nop 0
	v_addc_co_u32_e32 v173, vcc, 0, v151, vcc
	global_store_short v[172:173], v0, off
	v_add_co_u32_e32 v172, vcc, s85, v150
	v_cvt_pk_bf16_f32 v0, v115, s0
	s_nop 0
	v_addc_co_u32_e32 v173, vcc, 0, v151, vcc
	global_store_short v[172:173], v0, off
	v_add_co_u32_e32 v172, vcc, s87, v150
	v_cvt_pk_bf16_f32 v0, v116, s0
	s_nop 0
	v_addc_co_u32_e32 v173, vcc, 0, v151, vcc
	v_add_co_u32_e32 v150, vcc, s88, v150
	global_store_short v[172:173], v0, off
	v_cvt_pk_bf16_f32 v0, v117, s0
	v_addc_co_u32_e32 v151, vcc, 0, v151, vcc
	global_store_short v[150:151], v0, off
	v_lshl_add_u64 v[150:151], v[148:149], 0, 64
	v_cvt_pk_bf16_f32 v0, v110, s0
	v_add_co_u32_e32 v172, vcc, s86, v150
	global_store_short v[150:151], v0, off
	v_cvt_pk_bf16_f32 v0, v111, s0
	v_addc_co_u32_e32 v173, vcc, 0, v151, vcc
	global_store_short v[172:173], v0, off
	v_add_co_u32_e32 v172, vcc, s67, v150
	v_cvt_pk_bf16_f32 v0, v112, s0
	s_nop 0
	v_addc_co_u32_e32 v173, vcc, 0, v151, vcc
	global_store_short v[172:173], v0, off
	v_add_co_u32_e32 v172, vcc, s89, v150
	v_cvt_pk_bf16_f32 v0, v113, s0
	s_nop 0
	v_addc_co_u32_e32 v173, vcc, 0, v151, vcc
	global_store_short v[172:173], v0, off
	v_add_co_u32_e32 v172, vcc, s63, v150
	v_cvt_pk_bf16_f32 v0, v106, s0
	s_nop 0
	v_addc_co_u32_e32 v173, vcc, 0, v151, vcc
	global_store_short v[172:173], v0, off
	v_add_co_u32_e32 v172, vcc, s85, v150
	v_cvt_pk_bf16_f32 v0, v107, s0
	s_nop 0
	v_addc_co_u32_e32 v173, vcc, 0, v151, vcc
	global_store_short v[172:173], v0, off
	v_add_co_u32_e32 v172, vcc, s87, v150
	v_cvt_pk_bf16_f32 v0, v108, s0
	s_nop 0
	v_addc_co_u32_e32 v173, vcc, 0, v151, vcc
	v_add_co_u32_e32 v150, vcc, s88, v150
	global_store_short v[172:173], v0, off
	v_cvt_pk_bf16_f32 v0, v109, s0
	v_addc_co_u32_e32 v151, vcc, 0, v151, vcc
	s_mov_b64 s[0:1], 0x60
	global_store_short v[150:151], v0, off
	v_lshl_add_u64 v[150:151], v[148:149], 0, s[0:1]
	v_cvt_pk_bf16_f32 v0, v102, s0
	v_add_co_u32_e32 v172, vcc, s86, v150
	global_store_short v[150:151], v0, off
	v_cvt_pk_bf16_f32 v0, v103, s0
	v_addc_co_u32_e32 v173, vcc, 0, v151, vcc
	global_store_short v[172:173], v0, off
	v_add_co_u32_e32 v172, vcc, s67, v150
	v_cvt_pk_bf16_f32 v0, v104, s0
	s_nop 0
	v_addc_co_u32_e32 v173, vcc, 0, v151, vcc
	global_store_short v[172:173], v0, off
	v_add_co_u32_e32 v172, vcc, s89, v150
	v_cvt_pk_bf16_f32 v0, v105, s0
	s_nop 0
	v_addc_co_u32_e32 v173, vcc, 0, v151, vcc
	global_store_short v[172:173], v0, off
	v_add_co_u32_e32 v172, vcc, s63, v150
	v_cvt_pk_bf16_f32 v0, v98, s0
	s_nop 0
	v_addc_co_u32_e32 v173, vcc, 0, v151, vcc
	global_store_short v[172:173], v0, off
	v_add_co_u32_e32 v172, vcc, s85, v150
	v_cvt_pk_bf16_f32 v0, v99, s0
	s_nop 0
	v_addc_co_u32_e32 v173, vcc, 0, v151, vcc
	global_store_short v[172:173], v0, off
	v_add_co_u32_e32 v172, vcc, s87, v150
	v_cvt_pk_bf16_f32 v0, v100, s0
	s_nop 0
	v_addc_co_u32_e32 v173, vcc, 0, v151, vcc
	v_add_co_u32_e32 v150, vcc, s88, v150
	global_store_short v[172:173], v0, off
	v_cvt_pk_bf16_f32 v0, v101, s0
	v_addc_co_u32_e32 v151, vcc, 0, v151, vcc
	s_mov_b64 s[0:1], 0x100
	global_store_short v[150:151], v0, off
	v_lshl_add_u64 v[150:151], v[148:149], 0, s[0:1]
	v_cvt_pk_bf16_f32 v0, v94, s0
	v_add_co_u32_e32 v172, vcc, s86, v150
; DI bf16_t tobf(float a) { return (bf16_t)(pk2(a, 0.f) & 0xffffu); }
; template <typename T> DI T* opaque(T* p) { asm volatile("" : "+v"(p) : : "memory"); return p; }
;     DI void operator()(const pg8::f32x4 (&acc)[2][2][4][2], const pg8::Unit& u, int wr, int wc, int fr, int fq) const {
;     ...
;                 } else {
;                     bf16_t* pb = (bf16_t*)(ws + o_vt) + ((size_t)bh * 64 + d0) * S_ + s0;
; #pragma unroll
;                     for (int ai = 0; ai < 2; ++ai)
; #pragma unroll
;                         for (int m = 0; m < 4; ++m) {
;                             bf16_t* q = opaque(pb + ai * 128 + m * 16);
;                             const f32x4 v0 = acc[ai][bj][m][0], v1 = acc[ai][bj][m][1];
;                             q[0] = tobf(v0.x); q[(size_t)S_] = tobf(v0.y); q[(size_t)2 * S_] = tobf(v0.z); q[(size_t)3 * S_] = tobf(v0.w);
;                             q[(size_t)4 * S_] = tobf(v1.x); q[(size_t)5 * S_] = tobf(v1.y); q[(size_t)6 * S_] = tobf(v1.z); q[(size_t)7 * S_] = tobf(v1.w);
;                         }
	global_store_short v[150:151], v0, off
	v_cvt_pk_bf16_f32 v0, v95, s0
	v_addc_co_u32_e32 v173, vcc, 0, v151, vcc
	global_store_short v[172:173], v0, off
	v_add_co_u32_e32 v172, vcc, s67, v150
	v_cvt_pk_bf16_f32 v0, v96, s0
	s_nop 0
	v_addc_co_u32_e32 v173, vcc, 0, v151, vcc
	global_store_short v[172:173], v0, off
	v_add_co_u32_e32 v172, vcc, s89, v150
	v_cvt_pk_bf16_f32 v0, v97, s0
	s_nop 0
	v_addc_co_u32_e32 v173, vcc, 0, v151, vcc
	global_store_short v[172:173], v0, off
	v_add_co_u32_e32 v172, vcc, s63, v150
	v_cvt_pk_bf16_f32 v0, v90, s0
	s_nop 0
	v_addc_co_u32_e32 v173, vcc, 0, v151, vcc
	global_store_short v[172:173], v0, off
	v_add_co_u32_e32 v172, vcc, s85, v150
	v_cvt_pk_bf16_f32 v0, v91, s0
	s_nop 0
	v_addc_co_u32_e32 v173, vcc, 0, v151, vcc
	global_store_short v[172:173], v0, off
	v_add_co_u32_e32 v172, vcc, s87, v150
	v_cvt_pk_bf16_f32 v0, v92, s0
	s_nop 0
	v_addc_co_u32_e32 v173, vcc, 0, v151, vcc
	v_add_co_u32_e32 v150, vcc, s88, v150
	global_store_short v[172:173], v0, off
	v_cvt_pk_bf16_f32 v0, v93, s0
	v_addc_co_u32_e32 v151, vcc, 0, v151, vcc
	s_mov_b64 s[0:1], 0x120
	global_store_short v[150:151], v0, off
	v_lshl_add_u64 v[150:151], v[148:149], 0, s[0:1]
	v_cvt_pk_bf16_f32 v0, v86, s0
	v_add_co_u32_e32 v172, vcc, s86, v150
	global_store_short v[150:151], v0, off
	v_cvt_pk_bf16_f32 v0, v87, s0
	v_addc_co_u32_e32 v173, vcc, 0, v151, vcc
	global_store_short v[172:173], v0, off
	v_add_co_u32_e32 v172, vcc, s67, v150
	v_cvt_pk_bf16_f32 v0, v88, s0
	s_nop 0
	v_addc_co_u32_e32 v173, vcc, 0, v151, vcc
	global_store_short v[172:173], v0, off
	v_add_co_u32_e32 v172, vcc, s89, v150
	v_cvt_pk_bf16_f32 v0, v89, s0
	s_nop 0
	v_addc_co_u32_e32 v173, vcc, 0, v151, vcc
	global_store_short v[172:173], v0, off
	v_add_co_u32_e32 v172, vcc, s63, v150
	v_cvt_pk_bf16_f32 v0, v82, s0
	s_nop 0
	v_addc_co_u32_e32 v173, vcc, 0, v151, vcc
	global_store_short v[172:173], v0, off
	v_add_co_u32_e32 v172, vcc, s85, v150
	v_cvt_pk_bf16_f32 v0, v83, s0
	s_nop 0
	v_addc_co_u32_e32 v173, vcc, 0, v151, vcc
	global_store_short v[172:173], v0, off
	v_add_co_u32_e32 v172, vcc, s87, v150
	v_cvt_pk_bf16_f32 v0, v84, s0
	s_nop 0
	v_addc_co_u32_e32 v173, vcc, 0, v151, vcc
	v_add_co_u32_e32 v150, vcc, s88, v150
	global_store_short v[172:173], v0, off
	v_cvt_pk_bf16_f32 v0, v85, s0
	v_addc_co_u32_e32 v151, vcc, 0, v151, vcc
	s_mov_b64 s[0:1], 0x140
	global_store_short v[150:151], v0, off
	v_lshl_add_u64 v[150:151], v[148:149], 0, s[0:1]
	v_cvt_pk_bf16_f32 v0, v78, s0
	v_add_co_u32_e32 v172, vcc, s86, v150
	global_store_short v[150:151], v0, off
	v_cvt_pk_bf16_f32 v0, v79, s0
	v_addc_co_u32_e32 v173, vcc, 0, v151, vcc
	global_store_short v[172:173], v0, off
	v_add_co_u32_e32 v172, vcc, s67, v150
	v_cvt_pk_bf16_f32 v0, v80, s0
	s_nop 0
	v_addc_co_u32_e32 v173, vcc, 0, v151, vcc
	global_store_short v[172:173], v0, off
	v_add_co_u32_e32 v172, vcc, s89, v150
	v_cvt_pk_bf16_f32 v0, v81, s0
	s_nop 0
	v_addc_co_u32_e32 v173, vcc, 0, v151, vcc
	global_store_short v[172:173], v0, off
	v_add_co_u32_e32 v172, vcc, s63, v150
	v_cvt_pk_bf16_f32 v0, v74, s0
	s_nop 0
	v_addc_co_u32_e32 v173, vcc, 0, v151, vcc
	global_store_short v[172:173], v0, off
	v_add_co_u32_e32 v172, vcc, s85, v150
	v_cvt_pk_bf16_f32 v0, v75, s0
	s_nop 0
	v_addc_co_u32_e32 v173, vcc, 0, v151, vcc
	global_store_short v[172:173], v0, off
	v_add_co_u32_e32 v172, vcc, s87, v150
	v_cvt_pk_bf16_f32 v0, v76, s0
	s_nop 0
	v_addc_co_u32_e32 v173, vcc, 0, v151, vcc
	v_add_co_u32_e32 v150, vcc, s88, v150
	global_store_short v[172:173], v0, off
	v_cvt_pk_bf16_f32 v0, v77, s0
	v_addc_co_u32_e32 v151, vcc, 0, v151, vcc
	s_mov_b64 s[0:1], 0x160
	global_store_short v[150:151], v0, off
	v_lshl_add_u64 v[148:149], v[148:149], 0, s[0:1]
	v_cvt_pk_bf16_f32 v0, v70, s0
	v_add_co_u32_e32 v150, vcc, s86, v148
	global_store_short v[148:149], v0, off
	v_cvt_pk_bf16_f32 v0, v71, s0
	v_addc_co_u32_e32 v151, vcc, 0, v149, vcc
	global_store_short v[150:151], v0, off
	v_add_co_u32_e32 v150, vcc, 0x8000, v148
	v_cvt_pk_bf16_f32 v0, v72, s0
	s_nop 0
	v_addc_co_u32_e32 v151, vcc, 0, v149, vcc
	global_store_short v[150:151], v0, off
	v_add_co_u32_e32 v150, vcc, 0xc000, v148
	v_cvt_pk_bf16_f32 v0, v73, s0
	s_nop 0
	v_addc_co_u32_e32 v151, vcc, 0, v149, vcc
	global_store_short v[150:151], v0, off
	v_add_co_u32_e32 v150, vcc, s63, v148
	v_cvt_pk_bf16_f32 v0, v66, s0
	s_nop 0
	v_addc_co_u32_e32 v151, vcc, 0, v149, vcc
	global_store_short v[150:151], v0, off
	v_add_co_u32_e32 v150, vcc, 0x14000, v148
	v_cvt_pk_bf16_f32 v0, v67, s0
	s_nop 0
	v_addc_co_u32_e32 v151, vcc, 0, v149, vcc
	global_store_short v[150:151], v0, off
	v_add_co_u32_e32 v150, vcc, 0x18000, v148
	v_cvt_pk_bf16_f32 v0, v68, s0
	s_nop 0
	v_addc_co_u32_e32 v151, vcc, 0, v149, vcc
	v_add_co_u32_e32 v148, vcc, 0x1c000, v148
	global_store_short v[150:151], v0, off
	v_cvt_pk_bf16_f32 v0, v69, s0
	v_addc_co_u32_e32 v149, vcc, 0, v149, vcc
	global_store_short v[148:149], v0, off
	s_mov_b64 s[28:29], 0
; DI unsigned pk2(float a, float b) { f32x2 v = {a, b}; return __builtin_bit_cast(unsigned, __builtin_convertvector(v, bf2_t)); }
; template <typename T> DI T* opaque(T* p) { asm volatile("" : "+v"(p) : : "memory"); return p; }
;     DI void operator()(const pg8::f32x4 (&acc)[2][2][4][2], const pg8::Unit& u, int wr, int wc, int fr, int fq) const {
;     ...
;                 if (part < 2) {
;                     const float sc = part == 0 ? 0.125f * LOG2E : 1.f;
;                     bf16_t* pb = (bf16_t*)(ws + (part == 0 ? o_q : o_k)) + ((size_t)bh * S_ + s0) * 64 + d0;
; #pragma unroll
;                     for (int ai = 0; ai < 2; ++ai) {
;                         bf16_t* q = opaque(pb + (size_t)(ai * 128) * 64);
; #pragma unroll
;                         for (int m = 0; m < 4; ++m) {
;                             const f32x4 v0 = acc[ai][bj][m][0] * sc, v1 = acc[ai][bj][m][1] * sc;
;                             u32x4 wv; wv.x = pk2(v0.x, v0.y); wv.y = pk2(v0.z, v0.w); wv.z = pk2(v1.x, v1.y); wv.w = pk2(v1.z, v1.w);
;                             *(u32x4*)(q + (m * 16) * 64) = wv;
;                         }
;                     }
.LBB0_421:
	s_andn2_b64 vcc, exec, s[28:29]
	s_cbranch_vccnz .LBB0_423
	s_cmpk_lt_u32 s31, 0x100
	s_cselect_b64 vcc, -1, 0
	s_and_b64 s[26:27], vcc, exec
	s_cselect_b32 s6, s6, s22
	s_cselect_b32 s7, s7, s23
	s_add_u32 s22, s8, s6
	s_addc_u32 s23, s9, s7
	s_ashr_i32 s25, s24, 31
	s_lshl_b64 s[6:7], s[24:25], 20
	s_add_u32 s6, s22, s6
	s_addc_u32 s7, s23, s7
	v_lshlrev_b32_e32 v0, 1, v168
	v_cndmask_b32_e32 v172, 1.0, v222, vcc
	v_lshl_add_u64 v[148:149], s[6:7], 0, v[0:1]
	v_lshlrev_b32_e32 v0, 1, v140
	v_lshl_add_u64 v[174:175], v[148:149], 0, v[0:1]
	v_pk_mul_f32 v[150:151], v[128:129], v[172:173] op_sel_hi:[1,0]
	v_pk_mul_f32 v[148:149], v[126:127], v[172:173] op_sel_hi:[1,0]
	v_pk_mul_f32 v[178:179], v[124:125], v[172:173] op_sel_hi:[1,0]
	v_pk_mul_f32 v[180:181], v[122:123], v[172:173] op_sel_hi:[1,0]
	v_mov_b64_e32 v[176:177], v[174:175]
	v_cvt_pk_bf16_f32 v148, v148, v149
	v_cvt_pk_bf16_f32 v149, v150, v151
	v_cvt_pk_bf16_f32 v150, v180, v181
	v_cvt_pk_bf16_f32 v151, v178, v179
	s_waitcnt vmcnt(0)
	global_store_dwordx4 v[176:177], v[148:151], off
	v_pk_mul_f32 v[178:179], v[116:117], v[172:173] op_sel_hi:[1,0]
	v_pk_mul_f32 v[180:181], v[114:115], v[172:173] op_sel_hi:[1,0]
	v_pk_mul_f32 v[150:151], v[120:121], v[172:173] op_sel_hi:[1,0]
	v_pk_mul_f32 v[148:149], v[118:119], v[172:173] op_sel_hi:[1,0]
	s_mov_b64 s[0:1], 0x4000
	v_cvt_pk_bf16_f32 v148, v148, v149
	v_cvt_pk_bf16_f32 v149, v150, v151
	v_cvt_pk_bf16_f32 v150, v180, v181
	v_cvt_pk_bf16_f32 v151, v178, v179
	global_store_dwordx4 v[176:177], v[148:151], off offset:2048
	v_pk_mul_f32 v[178:179], v[108:109], v[172:173] op_sel_hi:[1,0]
	v_pk_mul_f32 v[180:181], v[106:107], v[172:173] op_sel_hi:[1,0]
	v_pk_mul_f32 v[150:151], v[112:113], v[172:173] op_sel_hi:[1,0]
	v_pk_mul_f32 v[148:149], v[110:111], v[172:173] op_sel_hi:[1,0]
	v_add_co_u32_e32 v176, vcc, s90, v176
	v_cvt_pk_bf16_f32 v148, v148, v149
	v_cvt_pk_bf16_f32 v149, v150, v151
	v_cvt_pk_bf16_f32 v150, v180, v181
	v_cvt_pk_bf16_f32 v151, v178, v179
	v_addc_co_u32_e32 v177, vcc, 0, v177, vcc
	global_store_dwordx4 v[176:177], v[148:151], off
	v_pk_mul_f32 v[178:179], v[100:101], v[172:173] op_sel_hi:[1,0]
	v_pk_mul_f32 v[180:181], v[98:99], v[172:173] op_sel_hi:[1,0]
	v_pk_mul_f32 v[150:151], v[104:105], v[172:173] op_sel_hi:[1,0]
	v_pk_mul_f32 v[148:149], v[102:103], v[172:173] op_sel_hi:[1,0]
	v_lshl_add_u64 v[174:175], v[174:175], 0, s[0:1]
	v_cvt_pk_bf16_f32 v148, v148, v149
	v_cvt_pk_bf16_f32 v149, v150, v151
	v_cvt_pk_bf16_f32 v150, v180, v181
	v_cvt_pk_bf16_f32 v151, v178, v179
	global_store_dwordx4 v[176:177], v[148:151], off offset:2048
	v_pk_mul_f32 v[176:177], v[92:93], v[172:173] op_sel_hi:[1,0]
	v_pk_mul_f32 v[178:179], v[90:91], v[172:173] op_sel_hi:[1,0]
	v_pk_mul_f32 v[150:151], v[96:97], v[172:173] op_sel_hi:[1,0]
	v_pk_mul_f32 v[148:149], v[94:95], v[172:173] op_sel_hi:[1,0]
	s_nop 0
	v_cvt_pk_bf16_f32 v148, v148, v149
	v_cvt_pk_bf16_f32 v149, v150, v151
	v_cvt_pk_bf16_f32 v150, v178, v179
	v_cvt_pk_bf16_f32 v151, v176, v177
	global_store_dwordx4 v[174:175], v[148:151], off
	v_pk_mul_f32 v[176:177], v[84:85], v[172:173] op_sel_hi:[1,0]
	v_pk_mul_f32 v[178:179], v[82:83], v[172:173] op_sel_hi:[1,0]
	v_pk_mul_f32 v[150:151], v[88:89], v[172:173] op_sel_hi:[1,0]
	v_pk_mul_f32 v[148:149], v[86:87], v[172:173] op_sel_hi:[1,0]
	s_nop 0
	v_cvt_pk_bf16_f32 v148, v148, v149
	v_cvt_pk_bf16_f32 v149, v150, v151
	v_cvt_pk_bf16_f32 v150, v178, v179
	v_cvt_pk_bf16_f32 v151, v176, v177
	global_store_dwordx4 v[174:175], v[148:151], off offset:2048
	v_pk_mul_f32 v[176:177], v[76:77], v[172:173] op_sel_hi:[1,0]
	v_pk_mul_f32 v[178:179], v[74:75], v[172:173] op_sel_hi:[1,0]
	v_pk_mul_f32 v[150:151], v[80:81], v[172:173] op_sel_hi:[1,0]
	v_pk_mul_f32 v[148:149], v[78:79], v[172:173] op_sel_hi:[1,0]
	v_add_co_u32_e32 v174, vcc, s90, v174
	v_cvt_pk_bf16_f32 v148, v148, v149
	v_cvt_pk_bf16_f32 v149, v150, v151
	v_cvt_pk_bf16_f32 v150, v178, v179
	v_cvt_pk_bf16_f32 v151, v176, v177
	v_addc_co_u32_e32 v175, vcc, 0, v175, vcc
	global_store_dwordx4 v[174:175], v[148:151], off
	v_pk_mul_f32 v[176:177], v[68:69], v[172:173] op_sel_hi:[1,0]
	s_nop 0
	v_pk_mul_f32 v[150:151], v[72:73], v[172:173] op_sel_hi:[1,0]
	v_pk_mul_f32 v[148:149], v[70:71], v[172:173] op_sel_hi:[1,0]
	v_pk_mul_f32 v[172:173], v[66:67], v[172:173] op_sel_hi:[1,0]
	v_cvt_pk_bf16_f32 v148, v148, v149
	v_cvt_pk_bf16_f32 v149, v150, v151
	v_cvt_pk_bf16_f32 v150, v172, v173
	v_cvt_pk_bf16_f32 v151, v176, v177
	global_store_dwordx4 v[174:175], v[148:151], off offset:2048

; DI unsigned pk2(float a, float b) { f32x2 v = {a, b}; return __builtin_bit_cast(unsigned, __builtin_convertvector(v, bf2_t)); }
; DI float fexp2(float x) { return __builtin_amdgcn_exp2f(x); }
; template <typename T> DI T* opaque(T* p) { asm volatile("" : "+v"(p) : : "memory"); return p; }
;     DI void operator()(const pg8::f32x4 (&acc)[2][2][4][2], const pg8::Unit& u, int wr, int wc, int fr, int fq) const {
;     ...
;                 bf16_t* pb = base + (size_t)rowb * ld + c8;
; #pragma unroll
;                 for (int ai = 0; ai < 2; ++ai) {
;                     bf16_t* q = opaque(pb + (size_t)(ai * 128) * ld);
; #pragma unroll
;                     for (int m = 0; m < 4; ++m) {
;                         f32x4 v0 = acc[ai][bj][m][0], v1 = acc[ai][bj][m][1];
;                         if (silu) {
; #pragma unroll
;                             for (int e = 0; e < 4; ++e) { v0[e] = v0[e] * __builtin_amdgcn_rcpf(1.f + fexp2(-v0[e] * LOG2E)); v1[e] = v1[e] * __builtin_amdgcn_rcpf(1.f + fexp2(-v1[e] * LOG2E)); }
;                         }
;                         u32x4 wv; wv.x = pk2(v0.x, v0.y); wv.y = pk2(v0.z, v0.w); wv.z = pk2(v1.x, v1.y); wv.w = pk2(v1.z, v1.w);
;                         *(u32x4*)(q + (size_t)(m * 16) * ld) = wv;
.LBB0_439:
	v_cndmask_b32_e64 v0, 0, 1, s[24:25]
	v_cvt_pk_bf16_f32 v126, v126, v127
	v_cvt_pk_bf16_f32 v127, v128, v129
	v_cvt_pk_bf16_f32 v128, v122, v123
	v_cvt_pk_bf16_f32 v129, v124, v125
	v_cmp_ne_u32_e64 s[6:7], 1, v0
	s_andn2_b64 vcc, exec, s[24:25]
	s_waitcnt vmcnt(0)
	global_store_dwordx4 v[150:151], v[126:129], off
	s_cbranch_vccnz .LBB0_441
	v_mul_f32_e32 v0, 0xbfb8aa3b, v118
	v_exp_f32_e32 v0, v0
	s_nop 0
	v_add_f32_e32 v0, 1.0, v0
	v_rcp_f32_e32 v122, v0
	v_mul_f32_e32 v0, 0xbfb8aa3b, v114
	v_exp_f32_e32 v0, v0
	s_nop 0
	v_add_f32_e32 v0, 1.0, v0
	v_rcp_f32_e32 v124, v0
	v_mul_f32_e32 v0, 0xbfb8aa3b, v119
	v_exp_f32_e32 v0, v0
	s_nop 0
	v_add_f32_e32 v0, 1.0, v0
	v_rcp_f32_e32 v123, v0
	v_mul_f32_e32 v0, 0xbfb8aa3b, v115
	v_exp_f32_e32 v0, v0
	v_pk_mul_f32 v[118:119], v[118:119], v[122:123]
	v_add_f32_e32 v0, 1.0, v0
	v_rcp_f32_e32 v125, v0
	v_mul_f32_e32 v0, 0xbfb8aa3b, v120
	v_exp_f32_e32 v0, v0
	v_pk_mul_f32 v[114:115], v[114:115], v[124:125]
	v_add_f32_e32 v0, 1.0, v0
	v_rcp_f32_e32 v126, v0
	v_mul_f32_e32 v0, 0xbfb8aa3b, v116
	v_exp_f32_e32 v0, v0
	s_nop 0
	v_add_f32_e32 v0, 1.0, v0
	v_rcp_f32_e32 v128, v0
	v_mul_f32_e32 v0, 0xbfb8aa3b, v121
	v_exp_f32_e32 v0, v0
	s_nop 0
	v_add_f32_e32 v0, 1.0, v0
	v_rcp_f32_e32 v127, v0
	v_mul_f32_e32 v0, 0xbfb8aa3b, v117
	v_exp_f32_e32 v0, v0
	v_pk_mul_f32 v[120:121], v[120:121], v[126:127]
	v_add_f32_e32 v0, 1.0, v0
	v_rcp_f32_e32 v129, v0
	s_nop 0
	v_pk_mul_f32 v[116:117], v[116:117], v[128:129]
.LBB0_441:
	s_lshl_b64 s[24:25], s[22:23], 5
	v_cvt_pk_bf16_f32 v118, v118, v119
	v_cvt_pk_bf16_f32 v119, v120, v121
	v_cvt_pk_bf16_f32 v120, v114, v115
	v_cvt_pk_bf16_f32 v121, v116, v117
	v_lshl_add_u64 v[114:115], v[150:151], 0, s[24:25]
	s_and_b64 vcc, exec, s[6:7]
	global_store_dwordx4 v[114:115], v[118:121], off
	s_cbranch_vccnz .LBB0_443
	v_mul_f32_e32 v0, 0xbfb8aa3b, v110
	v_exp_f32_e32 v0, v0
	s_nop 0
	v_add_f32_e32 v0, 1.0, v0
	v_rcp_f32_e32 v116, v0
	v_mul_f32_e32 v0, 0xbfb8aa3b, v106
	v_exp_f32_e32 v0, v0
	s_nop 0
	v_add_f32_e32 v0, 1.0, v0
	v_rcp_f32_e32 v118, v0
	v_mul_f32_e32 v0, 0xbfb8aa3b, v111
	v_exp_f32_e32 v0, v0
	s_nop 0
	v_add_f32_e32 v0, 1.0, v0
	v_rcp_f32_e32 v117, v0
	v_mul_f32_e32 v0, 0xbfb8aa3b, v107
	v_exp_f32_e32 v0, v0
	v_pk_mul_f32 v[110:111], v[110:111], v[116:117]
	v_add_f32_e32 v0, 1.0, v0
	v_rcp_f32_e32 v119, v0
	v_mul_f32_e32 v0, 0xbfb8aa3b, v112
	v_exp_f32_e32 v0, v0
	v_pk_mul_f32 v[106:107], v[106:107], v[118:119]
	v_add_f32_e32 v0, 1.0, v0
	v_rcp_f32_e32 v120, v0
	v_mul_f32_e32 v0, 0xbfb8aa3b, v108
	v_exp_f32_e32 v0, v0
	s_nop 0
	v_add_f32_e32 v0, 1.0, v0
	v_rcp_f32_e32 v122, v0
	v_mul_f32_e32 v0, 0xbfb8aa3b, v113
	v_exp_f32_e32 v0, v0
	s_nop 0
	v_add_f32_e32 v0, 1.0, v0
	v_rcp_f32_e32 v121, v0
	v_mul_f32_e32 v0, 0xbfb8aa3b, v109
	v_exp_f32_e32 v0, v0
	v_pk_mul_f32 v[112:113], v[112:113], v[120:121]
	v_add_f32_e32 v0, 1.0, v0
	v_rcp_f32_e32 v123, v0
	s_nop 0
	v_pk_mul_f32 v[108:109], v[108:109], v[122:123]
.LBB0_443:
	v_cvt_pk_bf16_f32 v110, v110, v111
	v_cvt_pk_bf16_f32 v111, v112, v113
	v_cvt_pk_bf16_f32 v112, v106, v107
	v_cvt_pk_bf16_f32 v113, v108, v109
	v_lshl_add_u64 v[106:107], v[114:115], 0, s[24:25]
	s_and_b64 vcc, exec, s[6:7]
	global_store_dwordx4 v[106:107], v[110:113], off
	s_cbranch_vccnz .LBB0_445
	v_mul_f32_e32 v0, 0xbfb8aa3b, v102
	v_exp_f32_e32 v0, v0
	s_nop 0
	v_add_f32_e32 v0, 1.0, v0
	v_rcp_f32_e32 v108, v0
	v_mul_f32_e32 v0, 0xbfb8aa3b, v98
	v_exp_f32_e32 v0, v0
	s_nop 0
	v_add_f32_e32 v0, 1.0, v0
	v_rcp_f32_e32 v110, v0
	v_mul_f32_e32 v0, 0xbfb8aa3b, v103
	v_exp_f32_e32 v0, v0
	s_nop 0
	v_add_f32_e32 v0, 1.0, v0
	v_rcp_f32_e32 v109, v0
	v_mul_f32_e32 v0, 0xbfb8aa3b, v99
	v_exp_f32_e32 v0, v0
	v_pk_mul_f32 v[102:103], v[102:103], v[108:109]
	v_add_f32_e32 v0, 1.0, v0
	v_rcp_f32_e32 v111, v0
	v_mul_f32_e32 v0, 0xbfb8aa3b, v104
	v_exp_f32_e32 v0, v0
	v_pk_mul_f32 v[98:99], v[98:99], v[110:111]
	v_add_f32_e32 v0, 1.0, v0
	v_rcp_f32_e32 v112, v0
	v_mul_f32_e32 v0, 0xbfb8aa3b, v100
	v_exp_f32_e32 v0, v0
	s_nop 0
	v_add_f32_e32 v0, 1.0, v0
	v_rcp_f32_e32 v114, v0
	v_mul_f32_e32 v0, 0xbfb8aa3b, v105
	v_exp_f32_e32 v0, v0
	s_nop 0
	v_add_f32_e32 v0, 1.0, v0
	v_rcp_f32_e32 v113, v0
	v_mul_f32_e32 v0, 0xbfb8aa3b, v101
	v_exp_f32_e32 v0, v0
	v_pk_mul_f32 v[104:105], v[104:105], v[112:113]
	v_add_f32_e32 v0, 1.0, v0
	v_rcp_f32_e32 v115, v0
	s_nop 0
	v_pk_mul_f32 v[100:101], v[100:101], v[114:115]
; DI unsigned pk2(float a, float b) { f32x2 v = {a, b}; return __builtin_bit_cast(unsigned, __builtin_convertvector(v, bf2_t)); }
; DI float fexp2(float x) { return __builtin_amdgcn_exp2f(x); }
; template <typename T> DI T* opaque(T* p) { asm volatile("" : "+v"(p) : : "memory"); return p; }
;     DI void operator()(const pg8::f32x4 (&acc)[2][2][4][2], const pg8::Unit& u, int wr, int wc, int fr, int fq) const {
;     ...
;                 bf16_t* pb = base + (size_t)rowb * ld + c8;
; #pragma unroll
;                 for (int ai = 0; ai < 2; ++ai) {
;                     bf16_t* q = opaque(pb + (size_t)(ai * 128) * ld);
; #pragma unroll
;                     for (int m = 0; m < 4; ++m) {
;                         f32x4 v0 = acc[ai][bj][m][0], v1 = acc[ai][bj][m][1];
;                         if (silu) {
; #pragma unroll
;                             for (int e = 0; e < 4; ++e) { v0[e] = v0[e] * __builtin_amdgcn_rcpf(1.f + fexp2(-v0[e] * LOG2E)); v1[e] = v1[e] * __builtin_amdgcn_rcpf(1.f + fexp2(-v1[e] * LOG2E)); }
;                         }
;                         u32x4 wv; wv.x = pk2(v0.x, v0.y); wv.y = pk2(v0.z, v0.w); wv.z = pk2(v1.x, v1.y); wv.w = pk2(v1.z, v1.w);
;                         *(u32x4*)(q + (size_t)(m * 16) * ld) = wv;
.LBB0_445:
	v_cvt_pk_bf16_f32 v102, v102, v103
	v_cvt_pk_bf16_f32 v103, v104, v105
	v_cvt_pk_bf16_f32 v104, v98, v99
	v_cvt_pk_bf16_f32 v105, v100, v101
	v_lshl_add_u64 v[98:99], v[106:107], 0, s[24:25]
	s_lshl_b64 s[26:27], s[22:23], 8
	global_store_dwordx4 v[98:99], v[102:105], off
	v_lshl_add_u64 v[98:99], v[148:149], 0, s[26:27]
	s_and_b64 vcc, exec, s[6:7]
	s_cbranch_vccnz .LBB0_447
	v_mul_f32_e32 v0, 0xbfb8aa3b, v94
	v_exp_f32_e32 v0, v0
	s_nop 0
	v_add_f32_e32 v0, 1.0, v0
	v_rcp_f32_e32 v100, v0
	v_mul_f32_e32 v0, 0xbfb8aa3b, v90
	v_exp_f32_e32 v0, v0
	s_nop 0
	v_add_f32_e32 v0, 1.0, v0
	v_rcp_f32_e32 v102, v0
	v_mul_f32_e32 v0, 0xbfb8aa3b, v95
	v_exp_f32_e32 v0, v0
	s_nop 0
	v_add_f32_e32 v0, 1.0, v0
	v_rcp_f32_e32 v101, v0
	v_mul_f32_e32 v0, 0xbfb8aa3b, v91
	v_exp_f32_e32 v0, v0
	v_pk_mul_f32 v[94:95], v[94:95], v[100:101]
	v_add_f32_e32 v0, 1.0, v0
	v_rcp_f32_e32 v103, v0
	v_mul_f32_e32 v0, 0xbfb8aa3b, v96
	v_exp_f32_e32 v0, v0
	v_pk_mul_f32 v[90:91], v[90:91], v[102:103]
	v_add_f32_e32 v0, 1.0, v0
	v_rcp_f32_e32 v104, v0
	v_mul_f32_e32 v0, 0xbfb8aa3b, v92
	v_exp_f32_e32 v0, v0
	s_nop 0
	v_add_f32_e32 v0, 1.0, v0
	v_rcp_f32_e32 v106, v0
	v_mul_f32_e32 v0, 0xbfb8aa3b, v97
	v_exp_f32_e32 v0, v0
	s_nop 0
	v_add_f32_e32 v0, 1.0, v0
	v_rcp_f32_e32 v105, v0
	v_mul_f32_e32 v0, 0xbfb8aa3b, v93
	v_exp_f32_e32 v0, v0
	v_pk_mul_f32 v[96:97], v[96:97], v[104:105]
	v_add_f32_e32 v0, 1.0, v0
	v_rcp_f32_e32 v107, v0
	s_nop 0
	v_pk_mul_f32 v[92:93], v[92:93], v[106:107]
.LBB0_447:
	v_cvt_pk_bf16_f32 v94, v94, v95
	v_cvt_pk_bf16_f32 v95, v96, v97
	v_cvt_pk_bf16_f32 v96, v90, v91
	v_cvt_pk_bf16_f32 v97, v92, v93
	s_and_b64 vcc, exec, s[6:7]
	global_store_dwordx4 v[98:99], v[94:97], off
	s_cbranch_vccnz .LBB0_449
	v_mul_f32_e32 v0, 0xbfb8aa3b, v86
	v_exp_f32_e32 v0, v0
	s_nop 0
	v_add_f32_e32 v0, 1.0, v0
	v_rcp_f32_e32 v90, v0
	v_mul_f32_e32 v0, 0xbfb8aa3b, v82
	v_exp_f32_e32 v0, v0
	s_nop 0
	v_add_f32_e32 v0, 1.0, v0
	v_rcp_f32_e32 v92, v0
	v_mul_f32_e32 v0, 0xbfb8aa3b, v87
	v_exp_f32_e32 v0, v0
	s_nop 0
	v_add_f32_e32 v0, 1.0, v0
	v_rcp_f32_e32 v91, v0
	v_mul_f32_e32 v0, 0xbfb8aa3b, v83
	v_exp_f32_e32 v0, v0
	v_pk_mul_f32 v[86:87], v[86:87], v[90:91]
	v_add_f32_e32 v0, 1.0, v0
	v_rcp_f32_e32 v93, v0
	v_mul_f32_e32 v0, 0xbfb8aa3b, v88
	v_exp_f32_e32 v0, v0
	v_pk_mul_f32 v[82:83], v[82:83], v[92:93]
	v_add_f32_e32 v0, 1.0, v0
	v_rcp_f32_e32 v94, v0
	v_mul_f32_e32 v0, 0xbfb8aa3b, v84
	v_exp_f32_e32 v0, v0
	s_nop 0
	v_add_f32_e32 v0, 1.0, v0
	v_rcp_f32_e32 v96, v0
	v_mul_f32_e32 v0, 0xbfb8aa3b, v89
	v_exp_f32_e32 v0, v0
	s_nop 0
	v_add_f32_e32 v0, 1.0, v0
	v_rcp_f32_e32 v95, v0
	v_mul_f32_e32 v0, 0xbfb8aa3b, v85
	v_exp_f32_e32 v0, v0
	v_pk_mul_f32 v[88:89], v[88:89], v[94:95]
	v_add_f32_e32 v0, 1.0, v0
	v_rcp_f32_e32 v97, v0
	s_nop 0
	v_pk_mul_f32 v[84:85], v[84:85], v[96:97]
.LBB0_449:
	s_lshl_b64 s[22:23], s[22:23], 4
	v_cvt_pk_bf16_f32 v86, v86, v87
	v_cvt_pk_bf16_f32 v87, v88, v89
	v_cvt_pk_bf16_f32 v88, v82, v83
	v_cvt_pk_bf16_f32 v89, v84, v85
	v_lshl_add_u64 v[82:83], s[22:23], 1, v[98:99]
	s_and_b64 vcc, exec, s[6:7]
	global_store_dwordx4 v[82:83], v[86:89], off
	s_cbranch_vccnz .LBB0_451
	v_mul_f32_e32 v0, 0xbfb8aa3b, v78
	v_exp_f32_e32 v0, v0
	s_nop 0
	v_add_f32_e32 v0, 1.0, v0
	v_rcp_f32_e32 v84, v0
	v_mul_f32_e32 v0, 0xbfb8aa3b, v74
	v_exp_f32_e32 v0, v0
	s_nop 0
	v_add_f32_e32 v0, 1.0, v0
	v_rcp_f32_e32 v86, v0
	v_mul_f32_e32 v0, 0xbfb8aa3b, v79
	v_exp_f32_e32 v0, v0
	s_nop 0
	v_add_f32_e32 v0, 1.0, v0
	v_rcp_f32_e32 v85, v0
	v_mul_f32_e32 v0, 0xbfb8aa3b, v75
	v_exp_f32_e32 v0, v0
	v_pk_mul_f32 v[78:79], v[78:79], v[84:85]
	v_add_f32_e32 v0, 1.0, v0
	v_rcp_f32_e32 v87, v0
	v_mul_f32_e32 v0, 0xbfb8aa3b, v80
	v_exp_f32_e32 v0, v0
	v_pk_mul_f32 v[74:75], v[74:75], v[86:87]
	v_add_f32_e32 v0, 1.0, v0
	v_rcp_f32_e32 v88, v0
	v_mul_f32_e32 v0, 0xbfb8aa3b, v76
	v_exp_f32_e32 v0, v0
	s_nop 0
	v_add_f32_e32 v0, 1.0, v0
	v_rcp_f32_e32 v90, v0
	v_mul_f32_e32 v0, 0xbfb8aa3b, v81
	v_exp_f32_e32 v0, v0
	s_nop 0
	v_add_f32_e32 v0, 1.0, v0
	v_rcp_f32_e32 v89, v0
	v_mul_f32_e32 v0, 0xbfb8aa3b, v77
	v_exp_f32_e32 v0, v0
	v_pk_mul_f32 v[80:81], v[80:81], v[88:89]
	v_add_f32_e32 v0, 1.0, v0
	v_rcp_f32_e32 v91, v0
	s_nop 0
	v_pk_mul_f32 v[76:77], v[76:77], v[90:91]
.LBB0_451:
	v_cvt_pk_bf16_f32 v78, v78, v79
	v_cvt_pk_bf16_f32 v79, v80, v81
	v_cvt_pk_bf16_f32 v80, v74, v75
	v_cvt_pk_bf16_f32 v81, v76, v77
	v_lshl_add_u64 v[74:75], v[82:83], 0, s[24:25]
	s_and_b64 vcc, exec, s[6:7]
	global_store_dwordx4 v[74:75], v[78:81], off
	s_cbranch_vccnz .LBB0_453
	v_mul_f32_e32 v0, 0xbfb8aa3b, v70
	v_exp_f32_e32 v0, v0
	s_nop 0
	v_add_f32_e32 v0, 1.0, v0
	v_rcp_f32_e32 v76, v0
	v_mul_f32_e32 v0, 0xbfb8aa3b, v66
	v_exp_f32_e32 v0, v0
	s_nop 0
	v_add_f32_e32 v0, 1.0, v0
	v_rcp_f32_e32 v78, v0
	v_mul_f32_e32 v0, 0xbfb8aa3b, v71
	v_exp_f32_e32 v0, v0
	s_nop 0
	v_add_f32_e32 v0, 1.0, v0
	v_rcp_f32_e32 v77, v0
	v_mul_f32_e32 v0, 0xbfb8aa3b, v67
	v_exp_f32_e32 v0, v0
	v_pk_mul_f32 v[70:71], v[70:71], v[76:77]
	v_add_f32_e32 v0, 1.0, v0
	v_rcp_f32_e32 v79, v0
	v_mul_f32_e32 v0, 0xbfb8aa3b, v72
	v_exp_f32_e32 v0, v0
	v_pk_mul_f32 v[66:67], v[66:67], v[78:79]
	v_add_f32_e32 v0, 1.0, v0
	v_rcp_f32_e32 v80, v0
	v_mul_f32_e32 v0, 0xbfb8aa3b, v68
	v_exp_f32_e32 v0, v0
	s_nop 0
	v_add_f32_e32 v0, 1.0, v0
	v_rcp_f32_e32 v82, v0
	v_mul_f32_e32 v0, 0xbfb8aa3b, v73
	v_exp_f32_e32 v0, v0
	s_nop 0
	v_add_f32_e32 v0, 1.0, v0
	v_rcp_f32_e32 v81, v0
	v_mul_f32_e32 v0, 0xbfb8aa3b, v69
	v_exp_f32_e32 v0, v0
	v_pk_mul_f32 v[72:73], v[72:73], v[80:81]
	v_add_f32_e32 v0, 1.0, v0
	v_rcp_f32_e32 v83, v0
	s_nop 0
	v_pk_mul_f32 v[68:69], v[68:69], v[82:83]
.LBB0_453:
	v_cvt_pk_bf16_f32 v70, v70, v71
	v_cvt_pk_bf16_f32 v71, v72, v73
	v_cvt_pk_bf16_f32 v72, v66, v67
	v_cvt_pk_bf16_f32 v73, v68, v69
	v_lshl_add_u64 v[66:67], v[74:75], 0, s[24:25]
	global_store_dwordx4 v[66:67], v[70:73], off

; DI bf16_t tobf(float a) { return (bf16_t)(pk2(a, 0.f) & 0xffffu); }
; template <typename T> DI T* opaque(T* p) { asm volatile("" : "+v"(p) : : "memory"); return p; }
;     DI void operator()(const pg8::f32x4 (&acc)[2][2][4][2], const pg8::Unit& u, int wr, int wc, int fr, int fq) const {
;     ...
;                 } else {
;                     bf16_t* pb = (bf16_t*)(ws + o_vt) + ((size_t)bh * 64 + d0) * S_ + s0;
; #pragma unroll
;                     for (int ai = 0; ai < 2; ++ai)
; #pragma unroll
;                         for (int m = 0; m < 4; ++m) {
;                             bf16_t* q = opaque(pb + ai * 128 + m * 16);
;                             const f32x4 v0 = acc[ai][bj][m][0], v1 = acc[ai][bj][m][1];
;                             q[0] = tobf(v0.x); q[(size_t)S_] = tobf(v0.y); q[(size_t)2 * S_] = tobf(v0.z); q[(size_t)3 * S_] = tobf(v0.w);
;                             q[(size_t)4 * S_] = tobf(v1.x); q[(size_t)5 * S_] = tobf(v1.y); q[(size_t)6 * S_] = tobf(v1.z); q[(size_t)7 * S_] = tobf(v1.w);
;                         }
.LBB0_460:
	s_add_i32 s7, s7, s6
	s_or_b32 s26, s17, s60
	s_cmpk_lt_u32 s7, 0x200
	s_mov_b64 s[30:31], -1
	s_cbranch_scc1 .LBB0_462
	s_add_u32 s17, s8, s28
	s_addc_u32 s30, s9, s29
	s_ashr_i32 s27, s26, 31
	s_lshl_b64 s[28:29], s[26:27], 20
	s_add_u32 s28, s17, s28
	s_addc_u32 s29, s30, s29
	v_lshlrev_b32_e32 v0, 1, v142
	v_lshl_add_u64 v[66:67], s[28:29], 0, v[0:1]
	v_lshlrev_b32_e32 v0, 1, v170
	v_lshl_add_u64 v[66:67], v[66:67], 0, v[0:1]
	v_mov_b64_e32 v[68:69], v[66:67]
	v_cvt_pk_bf16_f32 v0, v62, s0
	v_add_co_u32_e32 v70, vcc, s86, v68
	s_waitcnt vmcnt(0)
	global_store_short v[68:69], v0, off
	v_cvt_pk_bf16_f32 v0, v63, s0
	v_addc_co_u32_e32 v71, vcc, 0, v69, vcc
	global_store_short v[70:71], v0, off
	v_add_co_u32_e32 v70, vcc, s67, v68
	v_cvt_pk_bf16_f32 v0, v64, s0
	s_nop 0
	v_addc_co_u32_e32 v71, vcc, 0, v69, vcc
	global_store_short v[70:71], v0, off
	v_add_co_u32_e32 v70, vcc, s89, v68
	v_cvt_pk_bf16_f32 v0, v65, s0
	s_nop 0
	v_addc_co_u32_e32 v71, vcc, 0, v69, vcc
	global_store_short v[70:71], v0, off
	v_add_co_u32_e32 v70, vcc, s63, v68
	v_cvt_pk_bf16_f32 v0, v58, s0
	s_nop 0
	v_addc_co_u32_e32 v71, vcc, 0, v69, vcc
	global_store_short v[70:71], v0, off
	v_add_co_u32_e32 v70, vcc, s85, v68
	v_cvt_pk_bf16_f32 v0, v59, s0
	s_nop 0
	v_addc_co_u32_e32 v71, vcc, 0, v69, vcc
	global_store_short v[70:71], v0, off
	v_add_co_u32_e32 v70, vcc, s87, v68
	v_cvt_pk_bf16_f32 v0, v60, s0
	s_nop 0
	v_addc_co_u32_e32 v71, vcc, 0, v69, vcc
	v_add_co_u32_e32 v68, vcc, s88, v68
	global_store_short v[70:71], v0, off
	v_cvt_pk_bf16_f32 v0, v61, s0
	v_addc_co_u32_e32 v69, vcc, 0, v69, vcc
	global_store_short v[68:69], v0, off
	v_lshl_add_u64 v[68:69], v[66:67], 0, 32
	v_cvt_pk_bf16_f32 v0, v54, s0
	v_add_co_u32_e32 v70, vcc, s86, v68
	global_store_short v[68:69], v0, off
	v_cvt_pk_bf16_f32 v0, v55, s0
	v_addc_co_u32_e32 v71, vcc, 0, v69, vcc
	global_store_short v[70:71], v0, off
	v_add_co_u32_e32 v70, vcc, s67, v68
	v_cvt_pk_bf16_f32 v0, v56, s0
	s_nop 0
	v_addc_co_u32_e32 v71, vcc, 0, v69, vcc
	global_store_short v[70:71], v0, off
	v_add_co_u32_e32 v70, vcc, s89, v68
	v_cvt_pk_bf16_f32 v0, v57, s0
	s_nop 0
	v_addc_co_u32_e32 v71, vcc, 0, v69, vcc
	global_store_short v[70:71], v0, off
	v_add_co_u32_e32 v70, vcc, s63, v68
	v_cvt_pk_bf16_f32 v0, v50, s0
	s_nop 0
	v_addc_co_u32_e32 v71, vcc, 0, v69, vcc
	global_store_short v[70:71], v0, off
	v_add_co_u32_e32 v70, vcc, s85, v68
	v_cvt_pk_bf16_f32 v0, v51, s0
	s_nop 0
	v_addc_co_u32_e32 v71, vcc, 0, v69, vcc
	global_store_short v[70:71], v0, off
	v_add_co_u32_e32 v70, vcc, s87, v68
	v_cvt_pk_bf16_f32 v0, v52, s0
	s_nop 0
	v_addc_co_u32_e32 v71, vcc, 0, v69, vcc
	v_add_co_u32_e32 v68, vcc, s88, v68
	global_store_short v[70:71], v0, off
	v_cvt_pk_bf16_f32 v0, v53, s0
	v_addc_co_u32_e32 v69, vcc, 0, v69, vcc
	global_store_short v[68:69], v0, off
	v_lshl_add_u64 v[68:69], v[66:67], 0, 64
	v_cvt_pk_bf16_f32 v0, v46, s0
	v_add_co_u32_e32 v70, vcc, s86, v68
	global_store_short v[68:69], v0, off
	v_cvt_pk_bf16_f32 v0, v47, s0
	v_addc_co_u32_e32 v71, vcc, 0, v69, vcc
	global_store_short v[70:71], v0, off
	v_add_co_u32_e32 v70, vcc, s67, v68
	v_cvt_pk_bf16_f32 v0, v48, s0
	s_nop 0
	v_addc_co_u32_e32 v71, vcc, 0, v69, vcc
	global_store_short v[70:71], v0, off
	v_add_co_u32_e32 v70, vcc, s89, v68
	v_cvt_pk_bf16_f32 v0, v49, s0
	s_nop 0
	v_addc_co_u32_e32 v71, vcc, 0, v69, vcc
	global_store_short v[70:71], v0, off
	v_add_co_u32_e32 v70, vcc, s63, v68
	v_cvt_pk_bf16_f32 v0, v42, s0
	s_nop 0
	v_addc_co_u32_e32 v71, vcc, 0, v69, vcc
	global_store_short v[70:71], v0, off
	v_add_co_u32_e32 v70, vcc, s85, v68
	v_cvt_pk_bf16_f32 v0, v43, s0
	s_nop 0
	v_addc_co_u32_e32 v71, vcc, 0, v69, vcc
	global_store_short v[70:71], v0, off
	v_add_co_u32_e32 v70, vcc, s87, v68
	v_cvt_pk_bf16_f32 v0, v44, s0
	s_nop 0
	v_addc_co_u32_e32 v71, vcc, 0, v69, vcc
	v_add_co_u32_e32 v68, vcc, s88, v68
	global_store_short v[70:71], v0, off
	v_cvt_pk_bf16_f32 v0, v45, s0
	v_addc_co_u32_e32 v69, vcc, 0, v69, vcc
	s_mov_b64 s[0:1], 0x60
	global_store_short v[68:69], v0, off
	v_lshl_add_u64 v[68:69], v[66:67], 0, s[0:1]
	v_cvt_pk_bf16_f32 v0, v38, s0
	v_add_co_u32_e32 v70, vcc, s86, v68
	global_store_short v[68:69], v0, off
	v_cvt_pk_bf16_f32 v0, v39, s0
	v_addc_co_u32_e32 v71, vcc, 0, v69, vcc
	global_store_short v[70:71], v0, off
	v_add_co_u32_e32 v70, vcc, s67, v68
	v_cvt_pk_bf16_f32 v0, v40, s0
	s_nop 0
	v_addc_co_u32_e32 v71, vcc, 0, v69, vcc
	global_store_short v[70:71], v0, off
	v_add_co_u32_e32 v70, vcc, s89, v68
	v_cvt_pk_bf16_f32 v0, v41, s0
	s_nop 0
	v_addc_co_u32_e32 v71, vcc, 0, v69, vcc
	global_store_short v[70:71], v0, off
	v_add_co_u32_e32 v70, vcc, s63, v68
	v_cvt_pk_bf16_f32 v0, v34, s0
	s_nop 0
	v_addc_co_u32_e32 v71, vcc, 0, v69, vcc
	global_store_short v[70:71], v0, off
	v_add_co_u32_e32 v70, vcc, s85, v68
	v_cvt_pk_bf16_f32 v0, v35, s0
	s_nop 0
	v_addc_co_u32_e32 v71, vcc, 0, v69, vcc
	global_store_short v[70:71], v0, off
	v_add_co_u32_e32 v70, vcc, s87, v68
	v_cvt_pk_bf16_f32 v0, v36, s0
	s_nop 0
	v_addc_co_u32_e32 v71, vcc, 0, v69, vcc
	v_add_co_u32_e32 v68, vcc, s88, v68
	global_store_short v[70:71], v0, off
	v_cvt_pk_bf16_f32 v0, v37, s0
	v_addc_co_u32_e32 v69, vcc, 0, v69, vcc
	s_mov_b64 s[0:1], 0x100
	global_store_short v[68:69], v0, off
	v_lshl_add_u64 v[68:69], v[66:67], 0, s[0:1]
	v_cvt_pk_bf16_f32 v0, v30, s0
	v_add_co_u32_e32 v70, vcc, s86, v68
	global_store_short v[68:69], v0, off
	v_cvt_pk_bf16_f32 v0, v31, s0
	v_addc_co_u32_e32 v71, vcc, 0, v69, vcc
	global_store_short v[70:71], v0, off
	v_add_co_u32_e32 v70, vcc, s67, v68
	v_cvt_pk_bf16_f32 v0, v32, s0
	s_nop 0
	v_addc_co_u32_e32 v71, vcc, 0, v69, vcc
; DI bf16_t tobf(float a) { return (bf16_t)(pk2(a, 0.f) & 0xffffu); }
; template <typename T> DI T* opaque(T* p) { asm volatile("" : "+v"(p) : : "memory"); return p; }
;     DI void operator()(const pg8::f32x4 (&acc)[2][2][4][2], const pg8::Unit& u, int wr, int wc, int fr, int fq) const {
;     ...
;                 } else {
;                     bf16_t* pb = (bf16_t*)(ws + o_vt) + ((size_t)bh * 64 + d0) * S_ + s0;
; #pragma unroll
;                     for (int ai = 0; ai < 2; ++ai)
; #pragma unroll
;                         for (int m = 0; m < 4; ++m) {
;                             bf16_t* q = opaque(pb + ai * 128 + m * 16);
;                             const f32x4 v0 = acc[ai][bj][m][0], v1 = acc[ai][bj][m][1];
;                             q[0] = tobf(v0.x); q[(size_t)S_] = tobf(v0.y); q[(size_t)2 * S_] = tobf(v0.z); q[(size_t)3 * S_] = tobf(v0.w);
;                             q[(size_t)4 * S_] = tobf(v1.x); q[(size_t)5 * S_] = tobf(v1.y); q[(size_t)6 * S_] = tobf(v1.z); q[(size_t)7 * S_] = tobf(v1.w);
;                         }
	global_store_short v[70:71], v0, off
	v_add_co_u32_e32 v70, vcc, s89, v68
	v_cvt_pk_bf16_f32 v0, v33, s0
	s_nop 0
	v_addc_co_u32_e32 v71, vcc, 0, v69, vcc
	global_store_short v[70:71], v0, off
	v_add_co_u32_e32 v70, vcc, s63, v68
	v_cvt_pk_bf16_f32 v0, v26, s0
	s_nop 0
	v_addc_co_u32_e32 v71, vcc, 0, v69, vcc
	global_store_short v[70:71], v0, off
	v_add_co_u32_e32 v70, vcc, s85, v68
	v_cvt_pk_bf16_f32 v0, v27, s0
	s_nop 0
	v_addc_co_u32_e32 v71, vcc, 0, v69, vcc
	global_store_short v[70:71], v0, off
	v_add_co_u32_e32 v70, vcc, s87, v68
	v_cvt_pk_bf16_f32 v0, v28, s0
	s_nop 0
	v_addc_co_u32_e32 v71, vcc, 0, v69, vcc
	v_add_co_u32_e32 v68, vcc, s88, v68
	global_store_short v[70:71], v0, off
	v_cvt_pk_bf16_f32 v0, v29, s0
	v_addc_co_u32_e32 v69, vcc, 0, v69, vcc
	s_mov_b64 s[0:1], 0x120
	global_store_short v[68:69], v0, off
	v_lshl_add_u64 v[68:69], v[66:67], 0, s[0:1]
	v_cvt_pk_bf16_f32 v0, v22, s0
	v_add_co_u32_e32 v70, vcc, s86, v68
	global_store_short v[68:69], v0, off
	v_cvt_pk_bf16_f32 v0, v23, s0
	v_addc_co_u32_e32 v71, vcc, 0, v69, vcc
	global_store_short v[70:71], v0, off
	v_add_co_u32_e32 v70, vcc, s67, v68
	v_cvt_pk_bf16_f32 v0, v24, s0
	s_nop 0
	v_addc_co_u32_e32 v71, vcc, 0, v69, vcc
	global_store_short v[70:71], v0, off
	v_add_co_u32_e32 v70, vcc, s89, v68
	v_cvt_pk_bf16_f32 v0, v25, s0
	s_nop 0
	v_addc_co_u32_e32 v71, vcc, 0, v69, vcc
	global_store_short v[70:71], v0, off
	v_add_co_u32_e32 v70, vcc, s63, v68
	v_cvt_pk_bf16_f32 v0, v18, s0
	s_nop 0
	v_addc_co_u32_e32 v71, vcc, 0, v69, vcc
	global_store_short v[70:71], v0, off
	v_add_co_u32_e32 v70, vcc, s85, v68
	v_cvt_pk_bf16_f32 v0, v19, s0
	s_nop 0
	v_addc_co_u32_e32 v71, vcc, 0, v69, vcc
	global_store_short v[70:71], v0, off
	v_add_co_u32_e32 v70, vcc, s87, v68
	v_cvt_pk_bf16_f32 v0, v20, s0
	s_nop 0
	v_addc_co_u32_e32 v71, vcc, 0, v69, vcc
	v_add_co_u32_e32 v68, vcc, s88, v68
	global_store_short v[70:71], v0, off
	v_cvt_pk_bf16_f32 v0, v21, s0
	v_addc_co_u32_e32 v69, vcc, 0, v69, vcc
	s_mov_b64 s[0:1], 0x140
	global_store_short v[68:69], v0, off
	v_lshl_add_u64 v[68:69], v[66:67], 0, s[0:1]
	v_cvt_pk_bf16_f32 v0, v14, s0
	v_add_co_u32_e32 v70, vcc, s86, v68
	global_store_short v[68:69], v0, off
	v_cvt_pk_bf16_f32 v0, v15, s0
	v_addc_co_u32_e32 v71, vcc, 0, v69, vcc
	global_store_short v[70:71], v0, off
	v_add_co_u32_e32 v70, vcc, s67, v68
	v_cvt_pk_bf16_f32 v0, v16, s0
	s_nop 0
	v_addc_co_u32_e32 v71, vcc, 0, v69, vcc
	global_store_short v[70:71], v0, off
	v_add_co_u32_e32 v70, vcc, s89, v68
	v_cvt_pk_bf16_f32 v0, v17, s0
	s_nop 0
	v_addc_co_u32_e32 v71, vcc, 0, v69, vcc
	global_store_short v[70:71], v0, off
	v_add_co_u32_e32 v70, vcc, s63, v68
	v_cvt_pk_bf16_f32 v0, v10, s0
	s_nop 0
	v_addc_co_u32_e32 v71, vcc, 0, v69, vcc
	global_store_short v[70:71], v0, off
	v_add_co_u32_e32 v70, vcc, s85, v68
	v_cvt_pk_bf16_f32 v0, v11, s0
	s_nop 0
	v_addc_co_u32_e32 v71, vcc, 0, v69, vcc
	global_store_short v[70:71], v0, off
	v_add_co_u32_e32 v70, vcc, s87, v68
	v_cvt_pk_bf16_f32 v0, v12, s0
	s_nop 0
	v_addc_co_u32_e32 v71, vcc, 0, v69, vcc
	v_add_co_u32_e32 v68, vcc, s88, v68
	global_store_short v[70:71], v0, off
	v_cvt_pk_bf16_f32 v0, v13, s0
	v_addc_co_u32_e32 v69, vcc, 0, v69, vcc
	s_mov_b64 s[0:1], 0x160
	global_store_short v[68:69], v0, off
	v_lshl_add_u64 v[66:67], v[66:67], 0, s[0:1]
	v_cvt_pk_bf16_f32 v0, v6, s0
	v_add_co_u32_e32 v68, vcc, s86, v66
	global_store_short v[66:67], v0, off
	v_cvt_pk_bf16_f32 v0, v7, s0
	v_addc_co_u32_e32 v69, vcc, 0, v67, vcc
	global_store_short v[68:69], v0, off
	v_add_co_u32_e32 v68, vcc, 0x8000, v66
	v_cvt_pk_bf16_f32 v0, v8, s0
	s_nop 0
	v_addc_co_u32_e32 v69, vcc, 0, v67, vcc
	global_store_short v[68:69], v0, off
	v_add_co_u32_e32 v68, vcc, 0xc000, v66
	v_cvt_pk_bf16_f32 v0, v9, s0
	s_nop 0
	v_addc_co_u32_e32 v69, vcc, 0, v67, vcc
	global_store_short v[68:69], v0, off
	v_add_co_u32_e32 v68, vcc, s63, v66
	v_cvt_pk_bf16_f32 v0, v2, s0
	s_nop 0
	v_addc_co_u32_e32 v69, vcc, 0, v67, vcc
	global_store_short v[68:69], v0, off
	v_add_co_u32_e32 v68, vcc, 0x14000, v66
	v_cvt_pk_bf16_f32 v0, v3, s0
	s_nop 0
	v_addc_co_u32_e32 v69, vcc, 0, v67, vcc
	global_store_short v[68:69], v0, off
	v_add_co_u32_e32 v68, vcc, 0x18000, v66
	v_cvt_pk_bf16_f32 v0, v4, s0
	s_nop 0
	v_addc_co_u32_e32 v69, vcc, 0, v67, vcc
	v_add_co_u32_e32 v66, vcc, 0x1c000, v66
	global_store_short v[68:69], v0, off
	v_cvt_pk_bf16_f32 v0, v5, s0
	v_addc_co_u32_e32 v67, vcc, 0, v67, vcc
	s_mov_b64 s[30:31], 0
	global_store_short v[66:67], v0, off
; DI unsigned pk2(float a, float b) { f32x2 v = {a, b}; return __builtin_bit_cast(unsigned, __builtin_convertvector(v, bf2_t)); }
; template <typename T> DI T* opaque(T* p) { asm volatile("" : "+v"(p) : : "memory"); return p; }
;     DI void operator()(const pg8::f32x4 (&acc)[2][2][4][2], const pg8::Unit& u, int wr, int wc, int fr, int fq) const {
;     ...
;                 if (part < 2) {
;                     const float sc = part == 0 ? 0.125f * LOG2E : 1.f;
;                     bf16_t* pb = (bf16_t*)(ws + (part == 0 ? o_q : o_k)) + ((size_t)bh * S_ + s0) * 64 + d0;
; #pragma unroll
;                     for (int ai = 0; ai < 2; ++ai) {
;                         bf16_t* q = opaque(pb + (size_t)(ai * 128) * 64);
; #pragma unroll
;                         for (int m = 0; m < 4; ++m) {
;                             const f32x4 v0 = acc[ai][bj][m][0] * sc, v1 = acc[ai][bj][m][1] * sc;
;                             u32x4 wv; wv.x = pk2(v0.x, v0.y); wv.y = pk2(v0.z, v0.w); wv.z = pk2(v1.x, v1.y); wv.w = pk2(v1.z, v1.w);
;                             *(u32x4*)(q + (m * 16) * 64) = wv;
;                         }
;                     }
.LBB0_462:
	s_andn2_b64 vcc, exec, s[30:31]
	s_cbranch_vccnz .LBB0_464
	s_cmpk_lt_u32 s7, 0x100
	s_cselect_b64 vcc, -1, 0
	s_and_b64 s[28:29], vcc, exec
	s_cselect_b32 s17, s24, s22
	s_cselect_b32 s7, s25, s23
	s_add_u32 s17, s8, s17
	s_addc_u32 s7, s9, s7
	s_ashr_i32 s27, s26, 31
	s_lshl_b64 s[22:23], s[26:27], 20
	s_add_u32 s22, s17, s22
	s_addc_u32 s23, s7, s23
	v_lshlrev_b32_e32 v0, 1, v168
	v_cndmask_b32_e32 v70, 1.0, v222, vcc
	v_lshl_add_u64 v[66:67], s[22:23], 0, v[0:1]
	v_lshlrev_b32_e32 v0, 1, v140
	v_lshl_add_u64 v[72:73], v[66:67], 0, v[0:1]
	v_pk_mul_f32 v[68:69], v[64:65], v[70:71] op_sel_hi:[1,0]
	v_pk_mul_f32 v[66:67], v[62:63], v[70:71] op_sel_hi:[1,0]
	v_pk_mul_f32 v[76:77], v[60:61], v[70:71] op_sel_hi:[1,0]
	v_pk_mul_f32 v[78:79], v[58:59], v[70:71] op_sel_hi:[1,0]
	v_mov_b64_e32 v[74:75], v[72:73]
	v_cvt_pk_bf16_f32 v66, v66, v67
	v_cvt_pk_bf16_f32 v67, v68, v69
	v_cvt_pk_bf16_f32 v68, v78, v79
	v_cvt_pk_bf16_f32 v69, v76, v77
	s_waitcnt vmcnt(0)
	global_store_dwordx4 v[74:75], v[66:69], off
	v_pk_mul_f32 v[76:77], v[52:53], v[70:71] op_sel_hi:[1,0]
	v_pk_mul_f32 v[78:79], v[50:51], v[70:71] op_sel_hi:[1,0]
	v_pk_mul_f32 v[68:69], v[56:57], v[70:71] op_sel_hi:[1,0]
	v_pk_mul_f32 v[66:67], v[54:55], v[70:71] op_sel_hi:[1,0]
	s_mov_b64 s[0:1], 0x4000
	v_cvt_pk_bf16_f32 v66, v66, v67
	v_cvt_pk_bf16_f32 v67, v68, v69
	v_cvt_pk_bf16_f32 v68, v78, v79
	v_cvt_pk_bf16_f32 v69, v76, v77
	global_store_dwordx4 v[74:75], v[66:69], off offset:2048
	v_pk_mul_f32 v[76:77], v[44:45], v[70:71] op_sel_hi:[1,0]
	v_pk_mul_f32 v[78:79], v[42:43], v[70:71] op_sel_hi:[1,0]
	v_pk_mul_f32 v[68:69], v[48:49], v[70:71] op_sel_hi:[1,0]
	v_pk_mul_f32 v[66:67], v[46:47], v[70:71] op_sel_hi:[1,0]
	v_add_co_u32_e32 v74, vcc, s90, v74
	v_cvt_pk_bf16_f32 v66, v66, v67
	v_cvt_pk_bf16_f32 v67, v68, v69
	v_cvt_pk_bf16_f32 v68, v78, v79
	v_cvt_pk_bf16_f32 v69, v76, v77
	v_addc_co_u32_e32 v75, vcc, 0, v75, vcc
	global_store_dwordx4 v[74:75], v[66:69], off
	v_pk_mul_f32 v[76:77], v[36:37], v[70:71] op_sel_hi:[1,0]
	v_pk_mul_f32 v[78:79], v[34:35], v[70:71] op_sel_hi:[1,0]
	v_pk_mul_f32 v[68:69], v[40:41], v[70:71] op_sel_hi:[1,0]
	v_pk_mul_f32 v[66:67], v[38:39], v[70:71] op_sel_hi:[1,0]
	v_lshl_add_u64 v[72:73], v[72:73], 0, s[0:1]
	v_cvt_pk_bf16_f32 v66, v66, v67
	v_cvt_pk_bf16_f32 v67, v68, v69
	v_cvt_pk_bf16_f32 v68, v78, v79
	v_cvt_pk_bf16_f32 v69, v76, v77
	global_store_dwordx4 v[74:75], v[66:69], off offset:2048
	v_pk_mul_f32 v[74:75], v[28:29], v[70:71] op_sel_hi:[1,0]
	v_pk_mul_f32 v[76:77], v[26:27], v[70:71] op_sel_hi:[1,0]
	v_pk_mul_f32 v[68:69], v[32:33], v[70:71] op_sel_hi:[1,0]
	v_pk_mul_f32 v[66:67], v[30:31], v[70:71] op_sel_hi:[1,0]
	s_nop 0
	v_cvt_pk_bf16_f32 v66, v66, v67
	v_cvt_pk_bf16_f32 v67, v68, v69
	v_cvt_pk_bf16_f32 v68, v76, v77
	v_cvt_pk_bf16_f32 v69, v74, v75
	global_store_dwordx4 v[72:73], v[66:69], off
	v_pk_mul_f32 v[74:75], v[20:21], v[70:71] op_sel_hi:[1,0]
	v_pk_mul_f32 v[76:77], v[18:19], v[70:71] op_sel_hi:[1,0]
	v_pk_mul_f32 v[68:69], v[24:25], v[70:71] op_sel_hi:[1,0]
	v_pk_mul_f32 v[66:67], v[22:23], v[70:71] op_sel_hi:[1,0]
	s_nop 0
	v_cvt_pk_bf16_f32 v66, v66, v67
	v_cvt_pk_bf16_f32 v67, v68, v69
	v_cvt_pk_bf16_f32 v68, v76, v77
	v_cvt_pk_bf16_f32 v69, v74, v75
	global_store_dwordx4 v[72:73], v[66:69], off offset:2048
	v_pk_mul_f32 v[74:75], v[12:13], v[70:71] op_sel_hi:[1,0]
	v_pk_mul_f32 v[76:77], v[10:11], v[70:71] op_sel_hi:[1,0]
	v_pk_mul_f32 v[68:69], v[16:17], v[70:71] op_sel_hi:[1,0]
	v_pk_mul_f32 v[66:67], v[14:15], v[70:71] op_sel_hi:[1,0]
	v_add_co_u32_e32 v72, vcc, s90, v72
	v_cvt_pk_bf16_f32 v66, v66, v67
	v_cvt_pk_bf16_f32 v67, v68, v69
	v_cvt_pk_bf16_f32 v68, v76, v77
	v_cvt_pk_bf16_f32 v69, v74, v75
	v_addc_co_u32_e32 v73, vcc, 0, v73, vcc
	global_store_dwordx4 v[72:73], v[66:69], off
	v_pk_mul_f32 v[74:75], v[4:5], v[70:71] op_sel_hi:[1,0]
	s_nop 0
	v_pk_mul_f32 v[68:69], v[8:9], v[70:71] op_sel_hi:[1,0]
	v_pk_mul_f32 v[66:67], v[6:7], v[70:71] op_sel_hi:[1,0]
	v_pk_mul_f32 v[70:71], v[2:3], v[70:71] op_sel_hi:[1,0]
	v_cvt_pk_bf16_f32 v66, v66, v67
	v_cvt_pk_bf16_f32 v67, v68, v69
	v_cvt_pk_bf16_f32 v68, v70, v71
	v_cvt_pk_bf16_f32 v69, v74, v75
	global_store_dwordx4 v[72:73], v[66:69], off offset:2048

; DI unsigned pk2(float a, float b) { f32x2 v = {a, b}; return __builtin_bit_cast(unsigned, __builtin_convertvector(v, bf2_t)); }
; DI float fexp2(float x) { return __builtin_amdgcn_exp2f(x); }
; template <typename T> DI T* opaque(T* p) { asm volatile("" : "+v"(p) : : "memory"); return p; }
;     DI void operator()(const pg8::f32x4 (&acc)[2][2][4][2], const pg8::Unit& u, int wr, int wc, int fr, int fq) const {
;     ...
;                 bf16_t* pb = base + (size_t)rowb * ld + c8;
; #pragma unroll
;                 for (int ai = 0; ai < 2; ++ai) {
;                     bf16_t* q = opaque(pb + (size_t)(ai * 128) * ld);
; #pragma unroll
;                     for (int m = 0; m < 4; ++m) {
;                         f32x4 v0 = acc[ai][bj][m][0], v1 = acc[ai][bj][m][1];
;                         if (silu) {
; #pragma unroll
;                             for (int e = 0; e < 4; ++e) { v0[e] = v0[e] * __builtin_amdgcn_rcpf(1.f + fexp2(-v0[e] * LOG2E)); v1[e] = v1[e] * __builtin_amdgcn_rcpf(1.f + fexp2(-v1[e] * LOG2E)); }
;                         }
;                         u32x4 wv; wv.x = pk2(v0.x, v0.y); wv.y = pk2(v0.z, v0.w); wv.z = pk2(v1.x, v1.y); wv.w = pk2(v1.z, v1.w);
;                         *(u32x4*)(q + (size_t)(m * 16) * ld) = wv;
.LBB0_479:
	v_cndmask_b32_e64 v0, 0, 1, s[24:25]
	v_cvt_pk_bf16_f32 v62, v62, v63
	v_cvt_pk_bf16_f32 v63, v64, v65
	v_cvt_pk_bf16_f32 v64, v58, v59
	v_cvt_pk_bf16_f32 v65, v60, v61
	v_cmp_ne_u32_e64 s[6:7], 1, v0
	s_andn2_b64 vcc, exec, s[24:25]
	s_waitcnt vmcnt(0)
	global_store_dwordx4 v[68:69], v[62:65], off
	s_cbranch_vccnz .LBB0_481
	v_mul_f32_e32 v0, 0xbfb8aa3b, v54
	v_exp_f32_e32 v0, v0
	s_nop 0
	v_add_f32_e32 v0, 1.0, v0
	v_rcp_f32_e32 v58, v0
	v_mul_f32_e32 v0, 0xbfb8aa3b, v50
	v_exp_f32_e32 v0, v0
	s_nop 0
	v_add_f32_e32 v0, 1.0, v0
	v_rcp_f32_e32 v60, v0
	v_mul_f32_e32 v0, 0xbfb8aa3b, v55
	v_exp_f32_e32 v0, v0
	s_nop 0
	v_add_f32_e32 v0, 1.0, v0
	v_rcp_f32_e32 v59, v0
	v_mul_f32_e32 v0, 0xbfb8aa3b, v51
	v_exp_f32_e32 v0, v0
	v_pk_mul_f32 v[54:55], v[54:55], v[58:59]
	v_add_f32_e32 v0, 1.0, v0
	v_rcp_f32_e32 v61, v0
	v_mul_f32_e32 v0, 0xbfb8aa3b, v56
	v_exp_f32_e32 v0, v0
	v_pk_mul_f32 v[50:51], v[50:51], v[60:61]
	v_add_f32_e32 v0, 1.0, v0
	v_rcp_f32_e32 v62, v0
	v_mul_f32_e32 v0, 0xbfb8aa3b, v52
	v_exp_f32_e32 v0, v0
	s_nop 0
	v_add_f32_e32 v0, 1.0, v0
	v_rcp_f32_e32 v64, v0
	v_mul_f32_e32 v0, 0xbfb8aa3b, v57
	v_exp_f32_e32 v0, v0
	s_nop 0
	v_add_f32_e32 v0, 1.0, v0
	v_rcp_f32_e32 v63, v0
	v_mul_f32_e32 v0, 0xbfb8aa3b, v53
	v_exp_f32_e32 v0, v0
	v_pk_mul_f32 v[56:57], v[56:57], v[62:63]
	v_add_f32_e32 v0, 1.0, v0
	v_rcp_f32_e32 v65, v0
	s_nop 0
	v_pk_mul_f32 v[52:53], v[52:53], v[64:65]
.LBB0_481:
	s_lshl_b64 s[24:25], s[22:23], 5
	v_cvt_pk_bf16_f32 v54, v54, v55
	v_cvt_pk_bf16_f32 v55, v56, v57
	v_cvt_pk_bf16_f32 v56, v50, v51
	v_cvt_pk_bf16_f32 v57, v52, v53
	v_lshl_add_u64 v[50:51], v[68:69], 0, s[24:25]
	s_and_b64 vcc, exec, s[6:7]
	global_store_dwordx4 v[50:51], v[54:57], off
	s_cbranch_vccnz .LBB0_483
	v_mul_f32_e32 v0, 0xbfb8aa3b, v46
	v_exp_f32_e32 v0, v0
	s_nop 0
	v_add_f32_e32 v0, 1.0, v0
	v_rcp_f32_e32 v52, v0
	v_mul_f32_e32 v0, 0xbfb8aa3b, v42
	v_exp_f32_e32 v0, v0
	s_nop 0
	v_add_f32_e32 v0, 1.0, v0
	v_rcp_f32_e32 v54, v0
	v_mul_f32_e32 v0, 0xbfb8aa3b, v47
	v_exp_f32_e32 v0, v0
	s_nop 0
	v_add_f32_e32 v0, 1.0, v0
	v_rcp_f32_e32 v53, v0
	v_mul_f32_e32 v0, 0xbfb8aa3b, v43
	v_exp_f32_e32 v0, v0
	v_pk_mul_f32 v[46:47], v[46:47], v[52:53]
	v_add_f32_e32 v0, 1.0, v0
	v_rcp_f32_e32 v55, v0
	v_mul_f32_e32 v0, 0xbfb8aa3b, v48
	v_exp_f32_e32 v0, v0
	v_pk_mul_f32 v[42:43], v[42:43], v[54:55]
	v_add_f32_e32 v0, 1.0, v0
	v_rcp_f32_e32 v56, v0
	v_mul_f32_e32 v0, 0xbfb8aa3b, v44
	v_exp_f32_e32 v0, v0
	s_nop 0
	v_add_f32_e32 v0, 1.0, v0
	v_rcp_f32_e32 v58, v0
	v_mul_f32_e32 v0, 0xbfb8aa3b, v49
	v_exp_f32_e32 v0, v0
	s_nop 0
	v_add_f32_e32 v0, 1.0, v0
	v_rcp_f32_e32 v57, v0
	v_mul_f32_e32 v0, 0xbfb8aa3b, v45
	v_exp_f32_e32 v0, v0
	v_pk_mul_f32 v[48:49], v[48:49], v[56:57]
	v_add_f32_e32 v0, 1.0, v0
	v_rcp_f32_e32 v59, v0
	s_nop 0
	v_pk_mul_f32 v[44:45], v[44:45], v[58:59]
.LBB0_483:
	v_cvt_pk_bf16_f32 v46, v46, v47
	v_cvt_pk_bf16_f32 v47, v48, v49
	v_cvt_pk_bf16_f32 v48, v42, v43
	v_cvt_pk_bf16_f32 v49, v44, v45
	v_lshl_add_u64 v[42:43], v[50:51], 0, s[24:25]
	s_and_b64 vcc, exec, s[6:7]
	global_store_dwordx4 v[42:43], v[46:49], off
	s_cbranch_vccnz .LBB0_485
	v_mul_f32_e32 v0, 0xbfb8aa3b, v38
	v_exp_f32_e32 v0, v0
	s_nop 0
	v_add_f32_e32 v0, 1.0, v0
	v_rcp_f32_e32 v44, v0
	v_mul_f32_e32 v0, 0xbfb8aa3b, v34
	v_exp_f32_e32 v0, v0
	s_nop 0
	v_add_f32_e32 v0, 1.0, v0
	v_rcp_f32_e32 v46, v0
	v_mul_f32_e32 v0, 0xbfb8aa3b, v39
	v_exp_f32_e32 v0, v0
	s_nop 0
	v_add_f32_e32 v0, 1.0, v0
	v_rcp_f32_e32 v45, v0
	v_mul_f32_e32 v0, 0xbfb8aa3b, v35
	v_exp_f32_e32 v0, v0
	v_pk_mul_f32 v[38:39], v[38:39], v[44:45]
	v_add_f32_e32 v0, 1.0, v0
	v_rcp_f32_e32 v47, v0
	v_mul_f32_e32 v0, 0xbfb8aa3b, v40
	v_exp_f32_e32 v0, v0
	v_pk_mul_f32 v[34:35], v[34:35], v[46:47]
	v_add_f32_e32 v0, 1.0, v0
	v_rcp_f32_e32 v48, v0
	v_mul_f32_e32 v0, 0xbfb8aa3b, v36
	v_exp_f32_e32 v0, v0
	s_nop 0
	v_add_f32_e32 v0, 1.0, v0
	v_rcp_f32_e32 v50, v0
	v_mul_f32_e32 v0, 0xbfb8aa3b, v41
	v_exp_f32_e32 v0, v0
	s_nop 0
	v_add_f32_e32 v0, 1.0, v0
	v_rcp_f32_e32 v49, v0
	v_mul_f32_e32 v0, 0xbfb8aa3b, v37
	v_exp_f32_e32 v0, v0
	v_pk_mul_f32 v[40:41], v[40:41], v[48:49]
	v_add_f32_e32 v0, 1.0, v0
	v_rcp_f32_e32 v51, v0
	s_nop 0
	v_pk_mul_f32 v[36:37], v[36:37], v[50:51]
.LBB0_485:
	v_cvt_pk_bf16_f32 v38, v38, v39
	v_cvt_pk_bf16_f32 v39, v40, v41
	v_cvt_pk_bf16_f32 v40, v34, v35
	v_cvt_pk_bf16_f32 v41, v36, v37
	v_lshl_add_u64 v[34:35], v[42:43], 0, s[24:25]
	s_lshl_b64 s[26:27], s[22:23], 8
	global_store_dwordx4 v[34:35], v[38:41], off
	v_lshl_add_u64 v[34:35], v[66:67], 0, s[26:27]
	s_and_b64 vcc, exec, s[6:7]
	s_cbranch_vccnz .LBB0_487
	v_mul_f32_e32 v0, 0xbfb8aa3b, v30
	v_exp_f32_e32 v0, v0
	s_nop 0
	v_add_f32_e32 v0, 1.0, v0
	v_rcp_f32_e32 v36, v0
	v_mul_f32_e32 v0, 0xbfb8aa3b, v26
	v_exp_f32_e32 v0, v0
	s_nop 0
	v_add_f32_e32 v0, 1.0, v0
	v_rcp_f32_e32 v38, v0
	v_mul_f32_e32 v0, 0xbfb8aa3b, v31
	v_exp_f32_e32 v0, v0
	s_nop 0
	v_add_f32_e32 v0, 1.0, v0
	v_rcp_f32_e32 v37, v0
	v_mul_f32_e32 v0, 0xbfb8aa3b, v27
	v_exp_f32_e32 v0, v0
	v_pk_mul_f32 v[30:31], v[30:31], v[36:37]
	v_add_f32_e32 v0, 1.0, v0
	v_rcp_f32_e32 v39, v0
	v_mul_f32_e32 v0, 0xbfb8aa3b, v32
	v_exp_f32_e32 v0, v0
	v_pk_mul_f32 v[26:27], v[26:27], v[38:39]
	v_add_f32_e32 v0, 1.0, v0
	v_rcp_f32_e32 v40, v0
	v_mul_f32_e32 v0, 0xbfb8aa3b, v28
	v_exp_f32_e32 v0, v0
	s_nop 0
	v_add_f32_e32 v0, 1.0, v0
	v_rcp_f32_e32 v42, v0
	v_mul_f32_e32 v0, 0xbfb8aa3b, v33
	v_exp_f32_e32 v0, v0
	s_nop 0
	v_add_f32_e32 v0, 1.0, v0
	v_rcp_f32_e32 v41, v0
	v_mul_f32_e32 v0, 0xbfb8aa3b, v29
	v_exp_f32_e32 v0, v0
	v_pk_mul_f32 v[32:33], v[32:33], v[40:41]
	v_add_f32_e32 v0, 1.0, v0
	v_rcp_f32_e32 v43, v0
	s_nop 0
	v_pk_mul_f32 v[28:29], v[28:29], v[42:43]
; DI unsigned pk2(float a, float b) { f32x2 v = {a, b}; return __builtin_bit_cast(unsigned, __builtin_convertvector(v, bf2_t)); }
; DI float fexp2(float x) { return __builtin_amdgcn_exp2f(x); }
; template <typename T> DI T* opaque(T* p) { asm volatile("" : "+v"(p) : : "memory"); return p; }
;     DI void operator()(const pg8::f32x4 (&acc)[2][2][4][2], const pg8::Unit& u, int wr, int wc, int fr, int fq) const {
;     ...
;                 bf16_t* pb = base + (size_t)rowb * ld + c8;
; #pragma unroll
;                 for (int ai = 0; ai < 2; ++ai) {
;                     bf16_t* q = opaque(pb + (size_t)(ai * 128) * ld);
; #pragma unroll
;                     for (int m = 0; m < 4; ++m) {
;                         f32x4 v0 = acc[ai][bj][m][0], v1 = acc[ai][bj][m][1];
;                         if (silu) {
; #pragma unroll
;                             for (int e = 0; e < 4; ++e) { v0[e] = v0[e] * __builtin_amdgcn_rcpf(1.f + fexp2(-v0[e] * LOG2E)); v1[e] = v1[e] * __builtin_amdgcn_rcpf(1.f + fexp2(-v1[e] * LOG2E)); }
;                         }
;                         u32x4 wv; wv.x = pk2(v0.x, v0.y); wv.y = pk2(v0.z, v0.w); wv.z = pk2(v1.x, v1.y); wv.w = pk2(v1.z, v1.w);
;                         *(u32x4*)(q + (size_t)(m * 16) * ld) = wv;
.LBB0_487:
	v_cvt_pk_bf16_f32 v30, v30, v31
	v_cvt_pk_bf16_f32 v31, v32, v33
	v_cvt_pk_bf16_f32 v32, v26, v27
	v_cvt_pk_bf16_f32 v33, v28, v29
	s_and_b64 vcc, exec, s[6:7]
	global_store_dwordx4 v[34:35], v[30:33], off
	s_cbranch_vccnz .LBB0_489
	v_mul_f32_e32 v0, 0xbfb8aa3b, v22
	v_exp_f32_e32 v0, v0
	s_nop 0
	v_add_f32_e32 v0, 1.0, v0
	v_rcp_f32_e32 v26, v0
	v_mul_f32_e32 v0, 0xbfb8aa3b, v18
	v_exp_f32_e32 v0, v0
	s_nop 0
	v_add_f32_e32 v0, 1.0, v0
	v_rcp_f32_e32 v28, v0
	v_mul_f32_e32 v0, 0xbfb8aa3b, v23
	v_exp_f32_e32 v0, v0
	s_nop 0
	v_add_f32_e32 v0, 1.0, v0
	v_rcp_f32_e32 v27, v0
	v_mul_f32_e32 v0, 0xbfb8aa3b, v19
	v_exp_f32_e32 v0, v0
	v_pk_mul_f32 v[22:23], v[22:23], v[26:27]
	v_add_f32_e32 v0, 1.0, v0
	v_rcp_f32_e32 v29, v0
	v_mul_f32_e32 v0, 0xbfb8aa3b, v24
	v_exp_f32_e32 v0, v0
	v_pk_mul_f32 v[18:19], v[18:19], v[28:29]
	v_add_f32_e32 v0, 1.0, v0
	v_rcp_f32_e32 v30, v0
	v_mul_f32_e32 v0, 0xbfb8aa3b, v20
	v_exp_f32_e32 v0, v0
	s_nop 0
	v_add_f32_e32 v0, 1.0, v0
	v_rcp_f32_e32 v32, v0
	v_mul_f32_e32 v0, 0xbfb8aa3b, v25
	v_exp_f32_e32 v0, v0
	s_nop 0
	v_add_f32_e32 v0, 1.0, v0
	v_rcp_f32_e32 v31, v0
	v_mul_f32_e32 v0, 0xbfb8aa3b, v21
	v_exp_f32_e32 v0, v0
	v_pk_mul_f32 v[24:25], v[24:25], v[30:31]
	v_add_f32_e32 v0, 1.0, v0
	v_rcp_f32_e32 v33, v0
	s_nop 0
	v_pk_mul_f32 v[20:21], v[20:21], v[32:33]
.LBB0_489:
	s_lshl_b64 s[22:23], s[22:23], 4
	v_cvt_pk_bf16_f32 v22, v22, v23
	v_cvt_pk_bf16_f32 v23, v24, v25
	v_cvt_pk_bf16_f32 v24, v18, v19
	v_cvt_pk_bf16_f32 v25, v20, v21
	v_lshl_add_u64 v[18:19], s[22:23], 1, v[34:35]
	s_and_b64 vcc, exec, s[6:7]
	global_store_dwordx4 v[18:19], v[22:25], off
	s_cbranch_vccnz .LBB0_491
	v_mul_f32_e32 v0, 0xbfb8aa3b, v14
	v_exp_f32_e32 v0, v0
	s_nop 0
	v_add_f32_e32 v0, 1.0, v0
	v_rcp_f32_e32 v20, v0
	v_mul_f32_e32 v0, 0xbfb8aa3b, v10
	v_exp_f32_e32 v0, v0
	s_nop 0
	v_add_f32_e32 v0, 1.0, v0
	v_rcp_f32_e32 v22, v0
	v_mul_f32_e32 v0, 0xbfb8aa3b, v15
	v_exp_f32_e32 v0, v0
	s_nop 0
	v_add_f32_e32 v0, 1.0, v0
	v_rcp_f32_e32 v21, v0
	v_mul_f32_e32 v0, 0xbfb8aa3b, v11
	v_exp_f32_e32 v0, v0
	v_pk_mul_f32 v[14:15], v[14:15], v[20:21]
	v_add_f32_e32 v0, 1.0, v0
	v_rcp_f32_e32 v23, v0
	v_mul_f32_e32 v0, 0xbfb8aa3b, v16
	v_exp_f32_e32 v0, v0
	v_pk_mul_f32 v[10:11], v[10:11], v[22:23]
	v_add_f32_e32 v0, 1.0, v0
	v_rcp_f32_e32 v24, v0
	v_mul_f32_e32 v0, 0xbfb8aa3b, v12
	v_exp_f32_e32 v0, v0
	s_nop 0
	v_add_f32_e32 v0, 1.0, v0
	v_rcp_f32_e32 v26, v0
	v_mul_f32_e32 v0, 0xbfb8aa3b, v17
	v_exp_f32_e32 v0, v0
	s_nop 0
	v_add_f32_e32 v0, 1.0, v0
	v_rcp_f32_e32 v25, v0
	v_mul_f32_e32 v0, 0xbfb8aa3b, v13
	v_exp_f32_e32 v0, v0
	v_pk_mul_f32 v[16:17], v[16:17], v[24:25]
	v_add_f32_e32 v0, 1.0, v0
	v_rcp_f32_e32 v27, v0
	s_nop 0
	v_pk_mul_f32 v[12:13], v[12:13], v[26:27]
.LBB0_491:
	v_cvt_pk_bf16_f32 v14, v14, v15
	v_cvt_pk_bf16_f32 v15, v16, v17
	v_cvt_pk_bf16_f32 v16, v10, v11
	v_cvt_pk_bf16_f32 v17, v12, v13
	v_lshl_add_u64 v[10:11], v[18:19], 0, s[24:25]
	s_and_b64 vcc, exec, s[6:7]
	global_store_dwordx4 v[10:11], v[14:17], off
	s_cbranch_vccnz .LBB0_493
	v_mul_f32_e32 v0, 0xbfb8aa3b, v6
	v_exp_f32_e32 v0, v0
	s_nop 0
	v_add_f32_e32 v0, 1.0, v0
	v_rcp_f32_e32 v12, v0
	v_mul_f32_e32 v0, 0xbfb8aa3b, v2
	v_exp_f32_e32 v0, v0
	s_nop 0
	v_add_f32_e32 v0, 1.0, v0
	v_rcp_f32_e32 v14, v0
	v_mul_f32_e32 v0, 0xbfb8aa3b, v7
	v_exp_f32_e32 v0, v0
	s_nop 0
	v_add_f32_e32 v0, 1.0, v0
	v_rcp_f32_e32 v13, v0
	v_mul_f32_e32 v0, 0xbfb8aa3b, v3
	v_exp_f32_e32 v0, v0
	v_pk_mul_f32 v[6:7], v[6:7], v[12:13]
	v_add_f32_e32 v0, 1.0, v0
	v_rcp_f32_e32 v15, v0
	v_mul_f32_e32 v0, 0xbfb8aa3b, v8
	v_exp_f32_e32 v0, v0
	v_pk_mul_f32 v[2:3], v[2:3], v[14:15]
	v_add_f32_e32 v0, 1.0, v0
	v_rcp_f32_e32 v16, v0
	v_mul_f32_e32 v0, 0xbfb8aa3b, v4
	v_exp_f32_e32 v0, v0
	s_nop 0
	v_add_f32_e32 v0, 1.0, v0
	v_rcp_f32_e32 v18, v0
	v_mul_f32_e32 v0, 0xbfb8aa3b, v9
	v_exp_f32_e32 v0, v0
	s_nop 0
	v_add_f32_e32 v0, 1.0, v0
	v_rcp_f32_e32 v17, v0
	v_mul_f32_e32 v0, 0xbfb8aa3b, v5
	v_exp_f32_e32 v0, v0
	v_pk_mul_f32 v[8:9], v[8:9], v[16:17]
	v_add_f32_e32 v0, 1.0, v0
	v_rcp_f32_e32 v19, v0
	s_nop 0
	v_pk_mul_f32 v[4:5], v[4:5], v[18:19]
.LBB0_493:
	v_cvt_pk_bf16_f32 v6, v6, v7
	v_cvt_pk_bf16_f32 v7, v8, v9
	v_cvt_pk_bf16_f32 v8, v2, v3
	v_cvt_pk_bf16_f32 v9, v4, v5
	v_lshl_add_u64 v[2:3], v[10:11], 0, s[24:25]
	global_store_dwordx4 v[2:3], v[6:9], off
	s_andn2_b64 vcc, exec, s[4:5]
	s_mov_b64 s[4:5], -1
	s_cbranch_vccnz .LBB0_408

; DI void gemm_accum_n1(f32x16 (&acc)[2], const bf16_t* A, int lda, const bf16_t* Bt, int ldb, int nk, unsigned char* smem) {
;     const int tid = tid_op(), lane = tid & 63, w = tid >> 6, wr = w >> 1, wc = w & 1, r = lane & 31, h = lane >> 5;
;     bf16_t* sA = (bf16_t*)smem;
;     bf16_t* sB = sA + 2 * TILE_E;
;     u32x4 ra[4], rb[2];
;     const unsigned oa = (unsigned)(((tid >> 3) * lda + (tid & 7) * 8) * 2), ob = (unsigned)(((tid >> 3) * ldb + (tid & 7) * 8) * 2);
;     const unsigned sa = (unsigned)(lda * 64), sb = (unsigned)(ldb * 64);
;     const int srow = tid >> 3, skc = (tid & 7) * 8;
; #pragma unroll
;     for (int j = 0; j < 4; ++j) ra[j] = *(const u32x4*)((const unsigned char*)A + (oa + j * sa));
; #pragma unroll
;     for (int j = 0; j < 2; ++j) rb[j] = *(const u32x4*)((const unsigned char*)Bt + (ob + j * sb));
;     __syncthreads();
; #pragma unroll
;     for (int j = 0; j < 4; ++j) *(u32x4*)(sA + (srow + 32 * j) * LS + skc) = ra[j];
; #pragma unroll
;     for (int j = 0; j < 2; ++j) *(u32x4*)(sB + (srow + 32 * j) * LS + skc) = rb[j];
; #pragma unroll 1
;     for (int kt = 0; kt < nk; ++kt) {
;         const int buf = kt & 1;
;         if (kt + 1 < nk) {
; #pragma unroll
;             for (int j = 0; j < 4; ++j) ra[j] = *(const u32x4*)((const unsigned char*)(A + (kt + 1) * 64) + (oa + j * sa));
; #pragma unroll
;             for (int j = 0; j < 2; ++j) rb[j] = *(const u32x4*)((const unsigned char*)(Bt + (kt + 1) * 64) + (ob + j * sb));
;         }
;         __syncthreads();
;         const bf16_t* a = sA + buf * TILE_E + (wr * 64 + r) * LS + h * 8;
;         const bf16_t* b = sB + buf * TILE_E + (wc * 32 + r) * LS + h * 8;
; #pragma unroll
;         for (int s = 0; s < 4; ++s) {
;             const bf16x8 a0 = *(const bf16x8*)(a + s * 16), a1 = *(const bf16x8*)(a + 32 * LS + s * 16);
;             const bf16x8 b0 = *(const bf16x8*)(b + s * 16);
;             acc[0] = MFMA32(a0, b0, acc[0]);
;             acc[1] = MFMA32(a1, b0, acc[1]);
;         }
;         if (kt + 1 < nk) {
; #pragma unroll
;             for (int j = 0; j < 4; ++j) *(u32x4*)(sA + (buf ^ 1) * TILE_E + (srow + 32 * j) * LS + skc) = ra[j];
; #pragma unroll
;             for (int j = 0; j < 2; ++j) *(u32x4*)(sB + (buf ^ 1) * TILE_E + (srow + 32 * j) * LS + skc) = rb[j];
;         }
;     }
; }
.LBB0_500:
	s_lshl_b32 s18, s24, 7
	s_ashr_i32 s17, s16, 31
	s_ashr_i32 s19, s18, 31
	v_mov_b32_e32 v10, v215
	s_lshl_b64 s[20:21], s[16:17], 11
	s_lshl_b64 s[22:23], s[18:19], 11
	s_add_u32 s22, s34, s22
	v_lshlrev_b32_e32 v0, 4, v10
	v_ashrrev_i32_e32 v12, 3, v10
	v_and_b32_e32 v13, 0x70, v0
	s_addc_u32 s23, s35, s23
	v_lshl_or_b32 v0, v12, 11, v13
	v_lshl_add_u64 v[2:3], s[22:23], 0, v[0:1]
	s_waitcnt vmcnt(0)
	global_load_dwordx4 v[34:37], v[2:3], off
	v_add_u32_e32 v2, 0x10000, v0
	v_mov_b32_e32 v3, v1
	v_lshl_add_u64 v[4:5], s[22:23], 0, v[2:3]
	global_load_dwordx4 v[38:41], v[4:5], off
	v_add_u32_e32 v4, 0x20000, v0
	v_mov_b32_e32 v5, v1
	v_lshl_add_u64 v[6:7], s[22:23], 0, v[4:5]
	global_load_dwordx4 v[42:45], v[6:7], off
	v_add_u32_e32 v6, 0x30000, v0
	v_mov_b32_e32 v7, v1
	v_lshl_add_u64 v[8:9], s[22:23], 0, v[6:7]
	global_load_dwordx4 v[46:49], v[8:9], off
	v_lshl_add_u64 v[8:9], s[10:11], 0, v[0:1]
	global_load_dwordx4 v[50:53], v[8:9], off
	v_lshl_add_u64 v[8:9], s[10:11], 0, v[2:3]
	global_load_dwordx4 v[54:57], v[8:9], off
	v_mul_lo_u32 v8, v12, s92
	v_and_b32_e32 v11, 31, v10
	v_add3_u32 v78, s3, v13, v8
	v_lshrrev_b32_e32 v8, 1, v10
	s_add_u32 s20, s25, s20
	v_and_or_b32 v9, v8, s93, v11
	v_and_b32_e32 v10, 16, v8
	v_and_or_b32 v8, v8, 32, v11
	s_addc_u32 s21, s26, s21
	v_mul_lo_u32 v9, v9, s92
	v_mul_u32_u24_e32 v8, 0x90, v8
	v_lshl_add_u64 v[66:67], s[14:15], 0, v[2:3]
	v_lshl_add_u64 v[74:75], s[20:21], 0, v[2:3]
	v_mov_b32_e32 v2, 0
	v_add3_u32 v79, s3, v9, v10
	v_add3_u32 v80, s3, v8, v10
	v_lshl_add_u64 v[68:69], s[14:15], 0, v[0:1]
	v_lshl_add_u64 v[70:71], s[20:21], 0, v[6:7]
	v_lshl_add_u64 v[72:73], s[20:21], 0, v[4:5]
	v_lshl_add_u64 v[76:77], s[20:21], 0, v[0:1]
	global_load_dwordx4 v[140:143], v[76:77], off offset:0
	global_load_dwordx4 v[144:147], v[74:75], off offset:0
	global_load_dwordx4 v[148:151], v[72:73], off offset:0
	global_load_dwordx4 v[152:155], v[70:71], off offset:0
	global_load_dwordx4 v[156:159], v[68:69], off offset:0
	global_load_dwordx4 v[160:163], v[66:67], off offset:0
	global_load_dwordx4 v[164:167], v[76:77], off offset:128
	global_load_dwordx4 v[168:171], v[74:75], off offset:128
	global_load_dwordx4 v[172:175], v[72:73], off offset:128
	global_load_dwordx4 v[176:179], v[70:71], off offset:128
	global_load_dwordx4 v[180:183], v[68:69], off offset:128
	global_load_dwordx4 v[184:187], v[66:67], off offset:128
	s_mov_b32 s17, 0
	s_mov_b64 s[20:21], 0
	v_mov_b32_e32 v3, v2
	v_mov_b32_e32 v4, v2
	v_mov_b32_e32 v5, v2
	v_mov_b32_e32 v6, v2
	v_mov_b32_e32 v7, v2
	v_mov_b32_e32 v8, v2
	v_mov_b32_e32 v9, v2
	v_mov_b32_e32 v10, v2
	v_mov_b32_e32 v11, v2
	v_mov_b32_e32 v12, v2
	v_mov_b32_e32 v13, v2
	v_mov_b32_e32 v14, v2
	v_mov_b32_e32 v15, v2
	v_mov_b32_e32 v16, v2
	v_mov_b32_e32 v17, v2
	v_mov_b32_e32 v18, v2
	v_mov_b32_e32 v19, v2
	v_mov_b32_e32 v20, v2
	v_mov_b32_e32 v21, v2
	v_mov_b32_e32 v22, v2
	v_mov_b32_e32 v23, v2
	v_mov_b32_e32 v24, v2
	v_mov_b32_e32 v25, v2
	v_mov_b32_e32 v26, v2
	v_mov_b32_e32 v27, v2
	v_mov_b32_e32 v28, v2
	v_mov_b32_e32 v29, v2
	v_mov_b32_e32 v30, v2
	v_mov_b32_e32 v31, v2
	v_mov_b32_e32 v32, v2
	v_mov_b32_e32 v33, v2
	s_waitcnt vmcnt(12) lgkmcnt(0)
	s_barrier
	ds_write_b128 v78, v[34:37]
	ds_write_b128 v78, v[38:41] offset:4608
	ds_write_b128 v78, v[42:45] offset:9216
	ds_write_b128 v78, v[46:49] offset:13824
	ds_write_b128 v78, v[50:53] offset:36864
	ds_write_b128 v78, v[54:57] offset:41472
	s_branch .LBB0_502
.LBB0_502:
	s_waitcnt lgkmcnt(0)
	global_load_dwordx4 v[34:37], v[76:77], off offset:256
	global_load_dwordx4 v[38:41], v[74:75], off offset:256
	global_load_dwordx4 v[42:45], v[72:73], off offset:256
	global_load_dwordx4 v[46:49], v[70:71], off offset:256
	global_load_dwordx4 v[50:53], v[68:69], off offset:256
	global_load_dwordx4 v[54:57], v[66:67], off offset:256
	s_barrier
	ds_read_b128 v[82:85], v79 offset:0
	ds_read_b128 v[188:191], v80 offset:36864
	ds_read_b128 v[86:89], v79 offset:4608
	ds_read_b128 v[192:195], v79 offset:32
	ds_read_b128 v[200:203], v80 offset:36896
	ds_read_b128 v[196:199], v79 offset:4640
	ds_read_b128 v[204:207], v79 offset:64
	ds_read_b128 v[230:233], v80 offset:36928
	ds_read_b128 v[208:211], v79 offset:4672
	ds_read_b128 v[234:237], v79 offset:96
	ds_read_b128 v[242:245], v80 offset:36960
	ds_read_b128 v[238:241], v79 offset:4704
	s_waitcnt lgkmcnt(10)
	v_mfma_f32_32x32x16_bf16 v[18:33], v[82:85], v[188:191], v[18:33]
	s_waitcnt lgkmcnt(9)
	v_mfma_f32_32x32x16_bf16 v[2:17], v[86:89], v[188:191], v[2:17]
	s_waitcnt lgkmcnt(7)
	v_mfma_f32_32x32x16_bf16 v[18:33], v[192:195], v[200:203], v[18:33]
	s_waitcnt lgkmcnt(6)
	v_mfma_f32_32x32x16_bf16 v[2:17], v[196:199], v[200:203], v[2:17]
	s_waitcnt lgkmcnt(4)
	v_mfma_f32_32x32x16_bf16 v[18:33], v[204:207], v[230:233], v[18:33]
	s_waitcnt lgkmcnt(3)
	v_mfma_f32_32x32x16_bf16 v[2:17], v[208:211], v[230:233], v[2:17]
	s_waitcnt lgkmcnt(1)
	v_mfma_f32_32x32x16_bf16 v[18:33], v[234:237], v[242:245], v[18:33]
	s_waitcnt lgkmcnt(0)
	v_mfma_f32_32x32x16_bf16 v[2:17], v[238:241], v[242:245], v[2:17]
	s_waitcnt vmcnt(12)
	ds_write_b128 v78, v[140:143] offset:18432
	ds_write_b128 v78, v[144:147] offset:23040
	ds_write_b128 v78, v[148:151] offset:27648
	ds_write_b128 v78, v[152:155] offset:32256
	ds_write_b128 v78, v[156:159] offset:55296
	ds_write_b128 v78, v[160:163] offset:59904
	s_waitcnt lgkmcnt(0)
	global_load_dwordx4 v[140:143], v[76:77], off offset:384
	global_load_dwordx4 v[144:147], v[74:75], off offset:384
	global_load_dwordx4 v[148:151], v[72:73], off offset:384
	global_load_dwordx4 v[152:155], v[70:71], off offset:384
	global_load_dwordx4 v[156:159], v[68:69], off offset:384
	global_load_dwordx4 v[160:163], v[66:67], off offset:384
	s_barrier
; #define MFMA32(a, b, c) __builtin_amdgcn_mfma_f32_32x32x16_bf16((a), (b), (c), 0, 0, 0)
; DI void gemm_accum_n1(f32x16 (&acc)[2], const bf16_t* A, int lda, const bf16_t* Bt, int ldb, int nk, unsigned char* smem) {
;     ...
;     for (int kt = 0; kt < nk; ++kt) {
;         const int buf = kt & 1;
;         if (kt + 1 < nk) {
; #pragma unroll
;             for (int j = 0; j < 4; ++j) ra[j] = *(const u32x4*)((const unsigned char*)(A + (kt + 1) * 64) + (oa + j * sa));
; #pragma unroll
;             for (int j = 0; j < 2; ++j) rb[j] = *(const u32x4*)((const unsigned char*)(Bt + (kt + 1) * 64) + (ob + j * sb));
;         }
;         __syncthreads();
;         const bf16_t* a = sA + buf * TILE_E + (wr * 64 + r) * LS + h * 8;
;         const bf16_t* b = sB + buf * TILE_E + (wc * 32 + r) * LS + h * 8;
; #pragma unroll
;         for (int s = 0; s < 4; ++s) {
;             const bf16x8 a0 = *(const bf16x8*)(a + s * 16), a1 = *(const bf16x8*)(a + 32 * LS + s * 16);
;             const bf16x8 b0 = *(const bf16x8*)(b + s * 16);
;             acc[0] = MFMA32(a0, b0, acc[0]);
;             acc[1] = MFMA32(a1, b0, acc[1]);
;         }
;         if (kt + 1 < nk) {
; #pragma unroll
;             for (int j = 0; j < 4; ++j) *(u32x4*)(sA + (buf ^ 1) * TILE_E + (srow + 32 * j) * LS + skc) = ra[j];
; #pragma unroll
;             for (int j = 0; j < 2; ++j) *(u32x4*)(sB + (buf ^ 1) * TILE_E + (srow + 32 * j) * LS + skc) = rb[j];
;         }
;     }
	ds_read_b128 v[82:85], v79 offset:18432
	ds_read_b128 v[188:191], v80 offset:55296
	ds_read_b128 v[86:89], v79 offset:23040
	ds_read_b128 v[192:195], v79 offset:18464
	ds_read_b128 v[200:203], v80 offset:55328
	ds_read_b128 v[196:199], v79 offset:23072
	ds_read_b128 v[204:207], v79 offset:18496
	ds_read_b128 v[230:233], v80 offset:55360
	ds_read_b128 v[208:211], v79 offset:23104
	ds_read_b128 v[234:237], v79 offset:18528
	ds_read_b128 v[242:245], v80 offset:55392
	ds_read_b128 v[238:241], v79 offset:23136
	s_waitcnt lgkmcnt(10)
	v_mfma_f32_32x32x16_bf16 v[18:33], v[82:85], v[188:191], v[18:33]
	s_waitcnt lgkmcnt(9)
	v_mfma_f32_32x32x16_bf16 v[2:17], v[86:89], v[188:191], v[2:17]
	s_waitcnt lgkmcnt(7)
	v_mfma_f32_32x32x16_bf16 v[18:33], v[192:195], v[200:203], v[18:33]
	s_waitcnt lgkmcnt(6)
	v_mfma_f32_32x32x16_bf16 v[2:17], v[196:199], v[200:203], v[2:17]
	s_waitcnt lgkmcnt(4)
	v_mfma_f32_32x32x16_bf16 v[18:33], v[204:207], v[230:233], v[18:33]
	s_waitcnt lgkmcnt(3)
	v_mfma_f32_32x32x16_bf16 v[2:17], v[208:211], v[230:233], v[2:17]
	s_waitcnt lgkmcnt(1)
	v_mfma_f32_32x32x16_bf16 v[18:33], v[234:237], v[242:245], v[18:33]
	s_waitcnt lgkmcnt(0)
	v_mfma_f32_32x32x16_bf16 v[2:17], v[238:241], v[242:245], v[2:17]
	s_waitcnt vmcnt(12)
	ds_write_b128 v78, v[164:167] offset:0
	ds_write_b128 v78, v[168:171] offset:4608
	ds_write_b128 v78, v[172:175] offset:9216
	ds_write_b128 v78, v[176:179] offset:13824
	ds_write_b128 v78, v[180:183] offset:36864
	ds_write_b128 v78, v[184:187] offset:41472
	s_waitcnt lgkmcnt(0)
	global_load_dwordx4 v[164:167], v[76:77], off offset:512
	global_load_dwordx4 v[168:171], v[74:75], off offset:512
	global_load_dwordx4 v[172:175], v[72:73], off offset:512
	global_load_dwordx4 v[176:179], v[70:71], off offset:512
	global_load_dwordx4 v[180:183], v[68:69], off offset:512
	global_load_dwordx4 v[184:187], v[66:67], off offset:512
	s_barrier
	ds_read_b128 v[82:85], v79 offset:0
	ds_read_b128 v[188:191], v80 offset:36864
	ds_read_b128 v[86:89], v79 offset:4608
	ds_read_b128 v[192:195], v79 offset:32
	ds_read_b128 v[200:203], v80 offset:36896
	ds_read_b128 v[196:199], v79 offset:4640
	ds_read_b128 v[204:207], v79 offset:64
	ds_read_b128 v[230:233], v80 offset:36928
	ds_read_b128 v[208:211], v79 offset:4672
	ds_read_b128 v[234:237], v79 offset:96
	ds_read_b128 v[242:245], v80 offset:36960
	ds_read_b128 v[238:241], v79 offset:4704
	s_waitcnt lgkmcnt(10)
	v_mfma_f32_32x32x16_bf16 v[18:33], v[82:85], v[188:191], v[18:33]
	s_waitcnt lgkmcnt(9)
	v_mfma_f32_32x32x16_bf16 v[2:17], v[86:89], v[188:191], v[2:17]
	s_waitcnt lgkmcnt(7)
	v_mfma_f32_32x32x16_bf16 v[18:33], v[192:195], v[200:203], v[18:33]
	s_waitcnt lgkmcnt(6)
	v_mfma_f32_32x32x16_bf16 v[2:17], v[196:199], v[200:203], v[2:17]
	s_waitcnt lgkmcnt(4)
	v_mfma_f32_32x32x16_bf16 v[18:33], v[204:207], v[230:233], v[18:33]
	s_waitcnt lgkmcnt(3)
	v_mfma_f32_32x32x16_bf16 v[2:17], v[208:211], v[230:233], v[2:17]
	s_waitcnt lgkmcnt(1)
	v_mfma_f32_32x32x16_bf16 v[18:33], v[234:237], v[242:245], v[18:33]
	s_waitcnt lgkmcnt(0)
	v_mfma_f32_32x32x16_bf16 v[2:17], v[238:241], v[242:245], v[2:17]
	s_waitcnt vmcnt(12)
	ds_write_b128 v78, v[34:37] offset:18432
	ds_write_b128 v78, v[38:41] offset:23040
	ds_write_b128 v78, v[42:45] offset:27648
	ds_write_b128 v78, v[46:49] offset:32256
	ds_write_b128 v78, v[50:53] offset:55296
	ds_write_b128 v78, v[54:57] offset:59904
	s_waitcnt lgkmcnt(0)
	global_load_dwordx4 v[34:37], v[76:77], off offset:640
	global_load_dwordx4 v[38:41], v[74:75], off offset:640
	global_load_dwordx4 v[42:45], v[72:73], off offset:640
	global_load_dwordx4 v[46:49], v[70:71], off offset:640
	global_load_dwordx4 v[50:53], v[68:69], off offset:640
	global_load_dwordx4 v[54:57], v[66:67], off offset:640
	s_barrier
	ds_read_b128 v[82:85], v79 offset:18432
	ds_read_b128 v[188:191], v80 offset:55296
	ds_read_b128 v[86:89], v79 offset:23040
	ds_read_b128 v[192:195], v79 offset:18464
	ds_read_b128 v[200:203], v80 offset:55328
	ds_read_b128 v[196:199], v79 offset:23072
	ds_read_b128 v[204:207], v79 offset:18496
	ds_read_b128 v[230:233], v80 offset:55360
	ds_read_b128 v[208:211], v79 offset:23104
	ds_read_b128 v[234:237], v79 offset:18528
	ds_read_b128 v[242:245], v80 offset:55392
	ds_read_b128 v[238:241], v79 offset:23136
	s_waitcnt lgkmcnt(10)
	v_mfma_f32_32x32x16_bf16 v[18:33], v[82:85], v[188:191], v[18:33]
	s_waitcnt lgkmcnt(9)
	v_mfma_f32_32x32x16_bf16 v[2:17], v[86:89], v[188:191], v[2:17]
	s_waitcnt lgkmcnt(7)
	v_mfma_f32_32x32x16_bf16 v[18:33], v[192:195], v[200:203], v[18:33]
	s_waitcnt lgkmcnt(6)
	v_mfma_f32_32x32x16_bf16 v[2:17], v[196:199], v[200:203], v[2:17]
	s_waitcnt lgkmcnt(4)
	v_mfma_f32_32x32x16_bf16 v[18:33], v[204:207], v[230:233], v[18:33]
	s_waitcnt lgkmcnt(3)
	v_mfma_f32_32x32x16_bf16 v[2:17], v[208:211], v[230:233], v[2:17]
	s_waitcnt lgkmcnt(1)
	v_mfma_f32_32x32x16_bf16 v[18:33], v[234:237], v[242:245], v[18:33]
	s_waitcnt lgkmcnt(0)
	v_mfma_f32_32x32x16_bf16 v[2:17], v[238:241], v[242:245], v[2:17]
	s_waitcnt vmcnt(12)
	ds_write_b128 v78, v[140:143] offset:0
	ds_write_b128 v78, v[144:147] offset:4608
	ds_write_b128 v78, v[148:151] offset:9216
	ds_write_b128 v78, v[152:155] offset:13824
	ds_write_b128 v78, v[156:159] offset:36864
	ds_write_b128 v78, v[160:163] offset:41472
	s_waitcnt lgkmcnt(0)
	global_load_dwordx4 v[140:143], v[76:77], off offset:768
	global_load_dwordx4 v[144:147], v[74:75], off offset:768
	global_load_dwordx4 v[148:151], v[72:73], off offset:768
	global_load_dwordx4 v[152:155], v[70:71], off offset:768
	global_load_dwordx4 v[156:159], v[68:69], off offset:768
	global_load_dwordx4 v[160:163], v[66:67], off offset:768
	s_barrier
; #define MFMA32(a, b, c) __builtin_amdgcn_mfma_f32_32x32x16_bf16((a), (b), (c), 0, 0, 0)
; DI void gemm_accum_n1(f32x16 (&acc)[2], const bf16_t* A, int lda, const bf16_t* Bt, int ldb, int nk, unsigned char* smem) {
;     ...
;     for (int kt = 0; kt < nk; ++kt) {
;         const int buf = kt & 1;
;         if (kt + 1 < nk) {
; #pragma unroll
;             for (int j = 0; j < 4; ++j) ra[j] = *(const u32x4*)((const unsigned char*)(A + (kt + 1) * 64) + (oa + j * sa));
; #pragma unroll
;             for (int j = 0; j < 2; ++j) rb[j] = *(const u32x4*)((const unsigned char*)(Bt + (kt + 1) * 64) + (ob + j * sb));
;         }
;         __syncthreads();
;         const bf16_t* a = sA + buf * TILE_E + (wr * 64 + r) * LS + h * 8;
;         const bf16_t* b = sB + buf * TILE_E + (wc * 32 + r) * LS + h * 8;
; #pragma unroll
;         for (int s = 0; s < 4; ++s) {
;             const bf16x8 a0 = *(const bf16x8*)(a + s * 16), a1 = *(const bf16x8*)(a + 32 * LS + s * 16);
;             const bf16x8 b0 = *(const bf16x8*)(b + s * 16);
;             acc[0] = MFMA32(a0, b0, acc[0]);
;             acc[1] = MFMA32(a1, b0, acc[1]);
;         }
;         if (kt + 1 < nk) {
; #pragma unroll
;             for (int j = 0; j < 4; ++j) *(u32x4*)(sA + (buf ^ 1) * TILE_E + (srow + 32 * j) * LS + skc) = ra[j];
; #pragma unroll
;             for (int j = 0; j < 2; ++j) *(u32x4*)(sB + (buf ^ 1) * TILE_E + (srow + 32 * j) * LS + skc) = rb[j];
;         }
;     }
	ds_read_b128 v[82:85], v79 offset:0
	ds_read_b128 v[188:191], v80 offset:36864
	ds_read_b128 v[86:89], v79 offset:4608
	ds_read_b128 v[192:195], v79 offset:32
	ds_read_b128 v[200:203], v80 offset:36896
	ds_read_b128 v[196:199], v79 offset:4640
	ds_read_b128 v[204:207], v79 offset:64
	ds_read_b128 v[230:233], v80 offset:36928
	ds_read_b128 v[208:211], v79 offset:4672
	ds_read_b128 v[234:237], v79 offset:96
	ds_read_b128 v[242:245], v80 offset:36960
	ds_read_b128 v[238:241], v79 offset:4704
	s_waitcnt lgkmcnt(10)
	v_mfma_f32_32x32x16_bf16 v[18:33], v[82:85], v[188:191], v[18:33]
	s_waitcnt lgkmcnt(9)
	v_mfma_f32_32x32x16_bf16 v[2:17], v[86:89], v[188:191], v[2:17]
	s_waitcnt lgkmcnt(7)
	v_mfma_f32_32x32x16_bf16 v[18:33], v[192:195], v[200:203], v[18:33]
	s_waitcnt lgkmcnt(6)
	v_mfma_f32_32x32x16_bf16 v[2:17], v[196:199], v[200:203], v[2:17]
	s_waitcnt lgkmcnt(4)
	v_mfma_f32_32x32x16_bf16 v[18:33], v[204:207], v[230:233], v[18:33]
	s_waitcnt lgkmcnt(3)
	v_mfma_f32_32x32x16_bf16 v[2:17], v[208:211], v[230:233], v[2:17]
	s_waitcnt lgkmcnt(1)
	v_mfma_f32_32x32x16_bf16 v[18:33], v[234:237], v[242:245], v[18:33]
	s_waitcnt lgkmcnt(0)
	v_mfma_f32_32x32x16_bf16 v[2:17], v[238:241], v[242:245], v[2:17]
	s_waitcnt vmcnt(12)
	ds_write_b128 v78, v[164:167] offset:18432
	ds_write_b128 v78, v[168:171] offset:23040
	ds_write_b128 v78, v[172:175] offset:27648
	ds_write_b128 v78, v[176:179] offset:32256
	ds_write_b128 v78, v[180:183] offset:55296
	ds_write_b128 v78, v[184:187] offset:59904
	s_waitcnt lgkmcnt(0)
	global_load_dwordx4 v[164:167], v[76:77], off offset:896
	global_load_dwordx4 v[168:171], v[74:75], off offset:896
	global_load_dwordx4 v[172:175], v[72:73], off offset:896
	global_load_dwordx4 v[176:179], v[70:71], off offset:896
	global_load_dwordx4 v[180:183], v[68:69], off offset:896
	global_load_dwordx4 v[184:187], v[66:67], off offset:896
	s_barrier
	ds_read_b128 v[82:85], v79 offset:18432
	ds_read_b128 v[188:191], v80 offset:55296
	ds_read_b128 v[86:89], v79 offset:23040
	ds_read_b128 v[192:195], v79 offset:18464
	ds_read_b128 v[200:203], v80 offset:55328
	ds_read_b128 v[196:199], v79 offset:23072
	ds_read_b128 v[204:207], v79 offset:18496
	ds_read_b128 v[230:233], v80 offset:55360
	ds_read_b128 v[208:211], v79 offset:23104
	ds_read_b128 v[234:237], v79 offset:18528
	ds_read_b128 v[242:245], v80 offset:55392
	ds_read_b128 v[238:241], v79 offset:23136
	s_waitcnt lgkmcnt(10)
	v_mfma_f32_32x32x16_bf16 v[18:33], v[82:85], v[188:191], v[18:33]
	s_waitcnt lgkmcnt(9)
	v_mfma_f32_32x32x16_bf16 v[2:17], v[86:89], v[188:191], v[2:17]
	s_waitcnt lgkmcnt(7)
	v_mfma_f32_32x32x16_bf16 v[18:33], v[192:195], v[200:203], v[18:33]
	s_waitcnt lgkmcnt(6)
	v_mfma_f32_32x32x16_bf16 v[2:17], v[196:199], v[200:203], v[2:17]
	s_waitcnt lgkmcnt(4)
	v_mfma_f32_32x32x16_bf16 v[18:33], v[204:207], v[230:233], v[18:33]
	s_waitcnt lgkmcnt(3)
	v_mfma_f32_32x32x16_bf16 v[2:17], v[208:211], v[230:233], v[2:17]
	s_waitcnt lgkmcnt(1)
	v_mfma_f32_32x32x16_bf16 v[18:33], v[234:237], v[242:245], v[18:33]
	s_waitcnt lgkmcnt(0)
	v_mfma_f32_32x32x16_bf16 v[2:17], v[238:241], v[242:245], v[2:17]
	s_waitcnt vmcnt(12)
	ds_write_b128 v78, v[34:37] offset:0
	ds_write_b128 v78, v[38:41] offset:4608
	ds_write_b128 v78, v[42:45] offset:9216
	ds_write_b128 v78, v[46:49] offset:13824
	ds_write_b128 v78, v[50:53] offset:36864
	ds_write_b128 v78, v[54:57] offset:41472
	s_waitcnt lgkmcnt(0)
	global_load_dwordx4 v[34:37], v[76:77], off offset:1024
	global_load_dwordx4 v[38:41], v[74:75], off offset:1024
	global_load_dwordx4 v[42:45], v[72:73], off offset:1024
	global_load_dwordx4 v[46:49], v[70:71], off offset:1024
	global_load_dwordx4 v[50:53], v[68:69], off offset:1024
	global_load_dwordx4 v[54:57], v[66:67], off offset:1024
	s_barrier
	ds_read_b128 v[82:85], v79 offset:0
	ds_read_b128 v[188:191], v80 offset:36864
	ds_read_b128 v[86:89], v79 offset:4608
	ds_read_b128 v[192:195], v79 offset:32
	ds_read_b128 v[200:203], v80 offset:36896
	ds_read_b128 v[196:199], v79 offset:4640
	ds_read_b128 v[204:207], v79 offset:64
	ds_read_b128 v[230:233], v80 offset:36928
	ds_read_b128 v[208:211], v79 offset:4672
	ds_read_b128 v[234:237], v79 offset:96
	ds_read_b128 v[242:245], v80 offset:36960
	ds_read_b128 v[238:241], v79 offset:4704
	s_waitcnt lgkmcnt(10)
	v_mfma_f32_32x32x16_bf16 v[18:33], v[82:85], v[188:191], v[18:33]
	s_waitcnt lgkmcnt(9)
	v_mfma_f32_32x32x16_bf16 v[2:17], v[86:89], v[188:191], v[2:17]
	s_waitcnt lgkmcnt(7)
	v_mfma_f32_32x32x16_bf16 v[18:33], v[192:195], v[200:203], v[18:33]
	s_waitcnt lgkmcnt(6)
	v_mfma_f32_32x32x16_bf16 v[2:17], v[196:199], v[200:203], v[2:17]
	s_waitcnt lgkmcnt(4)
	v_mfma_f32_32x32x16_bf16 v[18:33], v[204:207], v[230:233], v[18:33]
	s_waitcnt lgkmcnt(3)
	v_mfma_f32_32x32x16_bf16 v[2:17], v[208:211], v[230:233], v[2:17]
	s_waitcnt lgkmcnt(1)
	v_mfma_f32_32x32x16_bf16 v[18:33], v[234:237], v[242:245], v[18:33]
	s_waitcnt lgkmcnt(0)
	v_mfma_f32_32x32x16_bf16 v[2:17], v[238:241], v[242:245], v[2:17]
	s_waitcnt vmcnt(12)
	ds_write_b128 v78, v[140:143] offset:18432
	ds_write_b128 v78, v[144:147] offset:23040
	ds_write_b128 v78, v[148:151] offset:27648
	ds_write_b128 v78, v[152:155] offset:32256
	ds_write_b128 v78, v[156:159] offset:55296
	ds_write_b128 v78, v[160:163] offset:59904
	s_waitcnt lgkmcnt(0)
	global_load_dwordx4 v[140:143], v[76:77], off offset:1152
	global_load_dwordx4 v[144:147], v[74:75], off offset:1152
	global_load_dwordx4 v[148:151], v[72:73], off offset:1152
	global_load_dwordx4 v[152:155], v[70:71], off offset:1152
	global_load_dwordx4 v[156:159], v[68:69], off offset:1152
	global_load_dwordx4 v[160:163], v[66:67], off offset:1152
	s_barrier
; #define MFMA32(a, b, c) __builtin_amdgcn_mfma_f32_32x32x16_bf16((a), (b), (c), 0, 0, 0)
; DI void gemm_accum_n1(f32x16 (&acc)[2], const bf16_t* A, int lda, const bf16_t* Bt, int ldb, int nk, unsigned char* smem) {
;     ...
;     for (int kt = 0; kt < nk; ++kt) {
;         const int buf = kt & 1;
;         if (kt + 1 < nk) {
; #pragma unroll
;             for (int j = 0; j < 4; ++j) ra[j] = *(const u32x4*)((const unsigned char*)(A + (kt + 1) * 64) + (oa + j * sa));
; #pragma unroll
;             for (int j = 0; j < 2; ++j) rb[j] = *(const u32x4*)((const unsigned char*)(Bt + (kt + 1) * 64) + (ob + j * sb));
;         }
;         __syncthreads();
;         const bf16_t* a = sA + buf * TILE_E + (wr * 64 + r) * LS + h * 8;
;         const bf16_t* b = sB + buf * TILE_E + (wc * 32 + r) * LS + h * 8;
; #pragma unroll
;         for (int s = 0; s < 4; ++s) {
;             const bf16x8 a0 = *(const bf16x8*)(a + s * 16), a1 = *(const bf16x8*)(a + 32 * LS + s * 16);
;             const bf16x8 b0 = *(const bf16x8*)(b + s * 16);
;             acc[0] = MFMA32(a0, b0, acc[0]);
;             acc[1] = MFMA32(a1, b0, acc[1]);
;         }
;         if (kt + 1 < nk) {
; #pragma unroll
;             for (int j = 0; j < 4; ++j) *(u32x4*)(sA + (buf ^ 1) * TILE_E + (srow + 32 * j) * LS + skc) = ra[j];
; #pragma unroll
;             for (int j = 0; j < 2; ++j) *(u32x4*)(sB + (buf ^ 1) * TILE_E + (srow + 32 * j) * LS + skc) = rb[j];
;         }
;     }
	ds_read_b128 v[82:85], v79 offset:18432
	ds_read_b128 v[188:191], v80 offset:55296
	ds_read_b128 v[86:89], v79 offset:23040
	ds_read_b128 v[192:195], v79 offset:18464
	ds_read_b128 v[200:203], v80 offset:55328
	ds_read_b128 v[196:199], v79 offset:23072
	ds_read_b128 v[204:207], v79 offset:18496
	ds_read_b128 v[230:233], v80 offset:55360
	ds_read_b128 v[208:211], v79 offset:23104
	ds_read_b128 v[234:237], v79 offset:18528
	ds_read_b128 v[242:245], v80 offset:55392
	ds_read_b128 v[238:241], v79 offset:23136
	s_waitcnt lgkmcnt(10)
	v_mfma_f32_32x32x16_bf16 v[18:33], v[82:85], v[188:191], v[18:33]
	s_waitcnt lgkmcnt(9)
	v_mfma_f32_32x32x16_bf16 v[2:17], v[86:89], v[188:191], v[2:17]
	s_waitcnt lgkmcnt(7)
	v_mfma_f32_32x32x16_bf16 v[18:33], v[192:195], v[200:203], v[18:33]
	s_waitcnt lgkmcnt(6)
	v_mfma_f32_32x32x16_bf16 v[2:17], v[196:199], v[200:203], v[2:17]
	s_waitcnt lgkmcnt(4)
	v_mfma_f32_32x32x16_bf16 v[18:33], v[204:207], v[230:233], v[18:33]
	s_waitcnt lgkmcnt(3)
	v_mfma_f32_32x32x16_bf16 v[2:17], v[208:211], v[230:233], v[2:17]
	s_waitcnt lgkmcnt(1)
	v_mfma_f32_32x32x16_bf16 v[18:33], v[234:237], v[242:245], v[18:33]
	s_waitcnt lgkmcnt(0)
	v_mfma_f32_32x32x16_bf16 v[2:17], v[238:241], v[242:245], v[2:17]
	s_waitcnt vmcnt(12)
	ds_write_b128 v78, v[164:167] offset:0
	ds_write_b128 v78, v[168:171] offset:4608
	ds_write_b128 v78, v[172:175] offset:9216
	ds_write_b128 v78, v[176:179] offset:13824
	ds_write_b128 v78, v[180:183] offset:36864
	ds_write_b128 v78, v[184:187] offset:41472
	s_waitcnt lgkmcnt(0)
	global_load_dwordx4 v[164:167], v[76:77], off offset:1280
	global_load_dwordx4 v[168:171], v[74:75], off offset:1280
	global_load_dwordx4 v[172:175], v[72:73], off offset:1280
	global_load_dwordx4 v[176:179], v[70:71], off offset:1280
	global_load_dwordx4 v[180:183], v[68:69], off offset:1280
	global_load_dwordx4 v[184:187], v[66:67], off offset:1280
	s_barrier
	ds_read_b128 v[82:85], v79 offset:0
	ds_read_b128 v[188:191], v80 offset:36864
	ds_read_b128 v[86:89], v79 offset:4608
	ds_read_b128 v[192:195], v79 offset:32
	ds_read_b128 v[200:203], v80 offset:36896
	ds_read_b128 v[196:199], v79 offset:4640
	ds_read_b128 v[204:207], v79 offset:64
	ds_read_b128 v[230:233], v80 offset:36928
	ds_read_b128 v[208:211], v79 offset:4672
	ds_read_b128 v[234:237], v79 offset:96
	ds_read_b128 v[242:245], v80 offset:36960
	ds_read_b128 v[238:241], v79 offset:4704
	s_waitcnt lgkmcnt(10)
	v_mfma_f32_32x32x16_bf16 v[18:33], v[82:85], v[188:191], v[18:33]
	s_waitcnt lgkmcnt(9)
	v_mfma_f32_32x32x16_bf16 v[2:17], v[86:89], v[188:191], v[2:17]
	s_waitcnt lgkmcnt(7)
	v_mfma_f32_32x32x16_bf16 v[18:33], v[192:195], v[200:203], v[18:33]
	s_waitcnt lgkmcnt(6)
	v_mfma_f32_32x32x16_bf16 v[2:17], v[196:199], v[200:203], v[2:17]
	s_waitcnt lgkmcnt(4)
	v_mfma_f32_32x32x16_bf16 v[18:33], v[204:207], v[230:233], v[18:33]
	s_waitcnt lgkmcnt(3)
	v_mfma_f32_32x32x16_bf16 v[2:17], v[208:211], v[230:233], v[2:17]
	s_waitcnt lgkmcnt(1)
	v_mfma_f32_32x32x16_bf16 v[18:33], v[234:237], v[242:245], v[18:33]
	s_waitcnt lgkmcnt(0)
	v_mfma_f32_32x32x16_bf16 v[2:17], v[238:241], v[242:245], v[2:17]
	s_waitcnt vmcnt(12)
	ds_write_b128 v78, v[34:37] offset:18432
	ds_write_b128 v78, v[38:41] offset:23040
	ds_write_b128 v78, v[42:45] offset:27648
	ds_write_b128 v78, v[46:49] offset:32256
	ds_write_b128 v78, v[50:53] offset:55296
	ds_write_b128 v78, v[54:57] offset:59904
	s_waitcnt lgkmcnt(0)
	global_load_dwordx4 v[34:37], v[76:77], off offset:1408
	global_load_dwordx4 v[38:41], v[74:75], off offset:1408
	global_load_dwordx4 v[42:45], v[72:73], off offset:1408
	global_load_dwordx4 v[46:49], v[70:71], off offset:1408
	global_load_dwordx4 v[50:53], v[68:69], off offset:1408
	global_load_dwordx4 v[54:57], v[66:67], off offset:1408
	s_barrier
	ds_read_b128 v[82:85], v79 offset:18432
	ds_read_b128 v[188:191], v80 offset:55296
	ds_read_b128 v[86:89], v79 offset:23040
	ds_read_b128 v[192:195], v79 offset:18464
	ds_read_b128 v[200:203], v80 offset:55328
	ds_read_b128 v[196:199], v79 offset:23072
	ds_read_b128 v[204:207], v79 offset:18496
	ds_read_b128 v[230:233], v80 offset:55360
	ds_read_b128 v[208:211], v79 offset:23104
	ds_read_b128 v[234:237], v79 offset:18528
	ds_read_b128 v[242:245], v80 offset:55392
	ds_read_b128 v[238:241], v79 offset:23136
	s_waitcnt lgkmcnt(10)
	v_mfma_f32_32x32x16_bf16 v[18:33], v[82:85], v[188:191], v[18:33]
	s_waitcnt lgkmcnt(9)
	v_mfma_f32_32x32x16_bf16 v[2:17], v[86:89], v[188:191], v[2:17]
	s_waitcnt lgkmcnt(7)
	v_mfma_f32_32x32x16_bf16 v[18:33], v[192:195], v[200:203], v[18:33]
	s_waitcnt lgkmcnt(6)
	v_mfma_f32_32x32x16_bf16 v[2:17], v[196:199], v[200:203], v[2:17]
	s_waitcnt lgkmcnt(4)
	v_mfma_f32_32x32x16_bf16 v[18:33], v[204:207], v[230:233], v[18:33]
	s_waitcnt lgkmcnt(3)
	v_mfma_f32_32x32x16_bf16 v[2:17], v[208:211], v[230:233], v[2:17]
	s_waitcnt lgkmcnt(1)
	v_mfma_f32_32x32x16_bf16 v[18:33], v[234:237], v[242:245], v[18:33]
	s_waitcnt lgkmcnt(0)
	v_mfma_f32_32x32x16_bf16 v[2:17], v[238:241], v[242:245], v[2:17]
	s_waitcnt vmcnt(12)
	ds_write_b128 v78, v[140:143] offset:0
	ds_write_b128 v78, v[144:147] offset:4608
	ds_write_b128 v78, v[148:151] offset:9216
	ds_write_b128 v78, v[152:155] offset:13824
	ds_write_b128 v78, v[156:159] offset:36864
	ds_write_b128 v78, v[160:163] offset:41472
	s_waitcnt lgkmcnt(0)
	global_load_dwordx4 v[140:143], v[76:77], off offset:1536
	global_load_dwordx4 v[144:147], v[74:75], off offset:1536
	global_load_dwordx4 v[148:151], v[72:73], off offset:1536
	global_load_dwordx4 v[152:155], v[70:71], off offset:1536
	global_load_dwordx4 v[156:159], v[68:69], off offset:1536
	global_load_dwordx4 v[160:163], v[66:67], off offset:1536
	s_barrier
; #define MFMA32(a, b, c) __builtin_amdgcn_mfma_f32_32x32x16_bf16((a), (b), (c), 0, 0, 0)
; DI void gemm_accum_n1(f32x16 (&acc)[2], const bf16_t* A, int lda, const bf16_t* Bt, int ldb, int nk, unsigned char* smem) {
;     ...
;     for (int kt = 0; kt < nk; ++kt) {
;         const int buf = kt & 1;
;         if (kt + 1 < nk) {
; #pragma unroll
;             for (int j = 0; j < 4; ++j) ra[j] = *(const u32x4*)((const unsigned char*)(A + (kt + 1) * 64) + (oa + j * sa));
; #pragma unroll
;             for (int j = 0; j < 2; ++j) rb[j] = *(const u32x4*)((const unsigned char*)(Bt + (kt + 1) * 64) + (ob + j * sb));
;         }
;         __syncthreads();
;         const bf16_t* a = sA + buf * TILE_E + (wr * 64 + r) * LS + h * 8;
;         const bf16_t* b = sB + buf * TILE_E + (wc * 32 + r) * LS + h * 8;
; #pragma unroll
;         for (int s = 0; s < 4; ++s) {
;             const bf16x8 a0 = *(const bf16x8*)(a + s * 16), a1 = *(const bf16x8*)(a + 32 * LS + s * 16);
;             const bf16x8 b0 = *(const bf16x8*)(b + s * 16);
;             acc[0] = MFMA32(a0, b0, acc[0]);
;             acc[1] = MFMA32(a1, b0, acc[1]);
;         }
;         if (kt + 1 < nk) {
; #pragma unroll
;             for (int j = 0; j < 4; ++j) *(u32x4*)(sA + (buf ^ 1) * TILE_E + (srow + 32 * j) * LS + skc) = ra[j];
; #pragma unroll
;             for (int j = 0; j < 2; ++j) *(u32x4*)(sB + (buf ^ 1) * TILE_E + (srow + 32 * j) * LS + skc) = rb[j];
;         }
;     }
	ds_read_b128 v[82:85], v79 offset:0
	ds_read_b128 v[188:191], v80 offset:36864
	ds_read_b128 v[86:89], v79 offset:4608
	ds_read_b128 v[192:195], v79 offset:32
	ds_read_b128 v[200:203], v80 offset:36896
	ds_read_b128 v[196:199], v79 offset:4640
	ds_read_b128 v[204:207], v79 offset:64
	ds_read_b128 v[230:233], v80 offset:36928
	ds_read_b128 v[208:211], v79 offset:4672
	ds_read_b128 v[234:237], v79 offset:96
	ds_read_b128 v[242:245], v80 offset:36960
	ds_read_b128 v[238:241], v79 offset:4704
	s_waitcnt lgkmcnt(10)
	v_mfma_f32_32x32x16_bf16 v[18:33], v[82:85], v[188:191], v[18:33]
	s_waitcnt lgkmcnt(9)
	v_mfma_f32_32x32x16_bf16 v[2:17], v[86:89], v[188:191], v[2:17]
	s_waitcnt lgkmcnt(7)
	v_mfma_f32_32x32x16_bf16 v[18:33], v[192:195], v[200:203], v[18:33]
	s_waitcnt lgkmcnt(6)
	v_mfma_f32_32x32x16_bf16 v[2:17], v[196:199], v[200:203], v[2:17]
	s_waitcnt lgkmcnt(4)
	v_mfma_f32_32x32x16_bf16 v[18:33], v[204:207], v[230:233], v[18:33]
	s_waitcnt lgkmcnt(3)
	v_mfma_f32_32x32x16_bf16 v[2:17], v[208:211], v[230:233], v[2:17]
	s_waitcnt lgkmcnt(1)
	v_mfma_f32_32x32x16_bf16 v[18:33], v[234:237], v[242:245], v[18:33]
	s_waitcnt lgkmcnt(0)
	v_mfma_f32_32x32x16_bf16 v[2:17], v[238:241], v[242:245], v[2:17]
	s_waitcnt vmcnt(12)
	ds_write_b128 v78, v[164:167] offset:18432
	ds_write_b128 v78, v[168:171] offset:23040
	ds_write_b128 v78, v[172:175] offset:27648
	ds_write_b128 v78, v[176:179] offset:32256
	ds_write_b128 v78, v[180:183] offset:55296
	ds_write_b128 v78, v[184:187] offset:59904
	s_waitcnt lgkmcnt(0)
	global_load_dwordx4 v[164:167], v[76:77], off offset:1664
	global_load_dwordx4 v[168:171], v[74:75], off offset:1664
	global_load_dwordx4 v[172:175], v[72:73], off offset:1664
	global_load_dwordx4 v[176:179], v[70:71], off offset:1664
	global_load_dwordx4 v[180:183], v[68:69], off offset:1664
	global_load_dwordx4 v[184:187], v[66:67], off offset:1664
	s_barrier
	ds_read_b128 v[82:85], v79 offset:18432
	ds_read_b128 v[188:191], v80 offset:55296
	ds_read_b128 v[86:89], v79 offset:23040
	ds_read_b128 v[192:195], v79 offset:18464
	ds_read_b128 v[200:203], v80 offset:55328
	ds_read_b128 v[196:199], v79 offset:23072
	ds_read_b128 v[204:207], v79 offset:18496
	ds_read_b128 v[230:233], v80 offset:55360
	ds_read_b128 v[208:211], v79 offset:23104
	ds_read_b128 v[234:237], v79 offset:18528
	ds_read_b128 v[242:245], v80 offset:55392
	ds_read_b128 v[238:241], v79 offset:23136
	s_waitcnt lgkmcnt(10)
	v_mfma_f32_32x32x16_bf16 v[18:33], v[82:85], v[188:191], v[18:33]
	s_waitcnt lgkmcnt(9)
	v_mfma_f32_32x32x16_bf16 v[2:17], v[86:89], v[188:191], v[2:17]
	s_waitcnt lgkmcnt(7)
	v_mfma_f32_32x32x16_bf16 v[18:33], v[192:195], v[200:203], v[18:33]
	s_waitcnt lgkmcnt(6)
	v_mfma_f32_32x32x16_bf16 v[2:17], v[196:199], v[200:203], v[2:17]
	s_waitcnt lgkmcnt(4)
	v_mfma_f32_32x32x16_bf16 v[18:33], v[204:207], v[230:233], v[18:33]
	s_waitcnt lgkmcnt(3)
	v_mfma_f32_32x32x16_bf16 v[2:17], v[208:211], v[230:233], v[2:17]
	s_waitcnt lgkmcnt(1)
	v_mfma_f32_32x32x16_bf16 v[18:33], v[234:237], v[242:245], v[18:33]
	s_waitcnt lgkmcnt(0)
	v_mfma_f32_32x32x16_bf16 v[2:17], v[238:241], v[242:245], v[2:17]
	s_waitcnt vmcnt(12)
	ds_write_b128 v78, v[34:37] offset:0
	ds_write_b128 v78, v[38:41] offset:4608
	ds_write_b128 v78, v[42:45] offset:9216
	ds_write_b128 v78, v[46:49] offset:13824
	ds_write_b128 v78, v[50:53] offset:36864
	ds_write_b128 v78, v[54:57] offset:41472
	s_waitcnt lgkmcnt(0)
	global_load_dwordx4 v[34:37], v[76:77], off offset:1792
	global_load_dwordx4 v[38:41], v[74:75], off offset:1792
	global_load_dwordx4 v[42:45], v[72:73], off offset:1792
	global_load_dwordx4 v[46:49], v[70:71], off offset:1792
	global_load_dwordx4 v[50:53], v[68:69], off offset:1792
	global_load_dwordx4 v[54:57], v[66:67], off offset:1792
	s_barrier
	ds_read_b128 v[82:85], v79 offset:0
	ds_read_b128 v[188:191], v80 offset:36864
	ds_read_b128 v[86:89], v79 offset:4608
	ds_read_b128 v[192:195], v79 offset:32
	ds_read_b128 v[200:203], v80 offset:36896
	ds_read_b128 v[196:199], v79 offset:4640
	ds_read_b128 v[204:207], v79 offset:64
	ds_read_b128 v[230:233], v80 offset:36928
	ds_read_b128 v[208:211], v79 offset:4672
	ds_read_b128 v[234:237], v79 offset:96
	ds_read_b128 v[242:245], v80 offset:36960
	ds_read_b128 v[238:241], v79 offset:4704
	s_waitcnt lgkmcnt(10)
	v_mfma_f32_32x32x16_bf16 v[18:33], v[82:85], v[188:191], v[18:33]
	s_waitcnt lgkmcnt(9)
	v_mfma_f32_32x32x16_bf16 v[2:17], v[86:89], v[188:191], v[2:17]
	s_waitcnt lgkmcnt(7)
	v_mfma_f32_32x32x16_bf16 v[18:33], v[192:195], v[200:203], v[18:33]
	s_waitcnt lgkmcnt(6)
	v_mfma_f32_32x32x16_bf16 v[2:17], v[196:199], v[200:203], v[2:17]
	s_waitcnt lgkmcnt(4)
	v_mfma_f32_32x32x16_bf16 v[18:33], v[204:207], v[230:233], v[18:33]
	s_waitcnt lgkmcnt(3)
	v_mfma_f32_32x32x16_bf16 v[2:17], v[208:211], v[230:233], v[2:17]
	s_waitcnt lgkmcnt(1)
	v_mfma_f32_32x32x16_bf16 v[18:33], v[234:237], v[242:245], v[18:33]
	s_waitcnt lgkmcnt(0)
	v_mfma_f32_32x32x16_bf16 v[2:17], v[238:241], v[242:245], v[2:17]
	s_waitcnt vmcnt(12)
	ds_write_b128 v78, v[140:143] offset:18432
	ds_write_b128 v78, v[144:147] offset:23040
	ds_write_b128 v78, v[148:151] offset:27648
	ds_write_b128 v78, v[152:155] offset:32256
	ds_write_b128 v78, v[156:159] offset:55296
	ds_write_b128 v78, v[160:163] offset:59904
	s_waitcnt lgkmcnt(0)
	s_barrier
; #define MFMA32(a, b, c) __builtin_amdgcn_mfma_f32_32x32x16_bf16((a), (b), (c), 0, 0, 0)
; DI void gemm_accum_n1(f32x16 (&acc)[2], const bf16_t* A, int lda, const bf16_t* Bt, int ldb, int nk, unsigned char* smem) {
;     ...
;     for (int kt = 0; kt < nk; ++kt) {
;         const int buf = kt & 1;
;         if (kt + 1 < nk) {
; #pragma unroll
;             for (int j = 0; j < 4; ++j) ra[j] = *(const u32x4*)((const unsigned char*)(A + (kt + 1) * 64) + (oa + j * sa));
; #pragma unroll
;             for (int j = 0; j < 2; ++j) rb[j] = *(const u32x4*)((const unsigned char*)(Bt + (kt + 1) * 64) + (ob + j * sb));
;         }
;         __syncthreads();
;         const bf16_t* a = sA + buf * TILE_E + (wr * 64 + r) * LS + h * 8;
;         const bf16_t* b = sB + buf * TILE_E + (wc * 32 + r) * LS + h * 8;
; #pragma unroll
;         for (int s = 0; s < 4; ++s) {
;             const bf16x8 a0 = *(const bf16x8*)(a + s * 16), a1 = *(const bf16x8*)(a + 32 * LS + s * 16);
;             const bf16x8 b0 = *(const bf16x8*)(b + s * 16);
;             acc[0] = MFMA32(a0, b0, acc[0]);
;             acc[1] = MFMA32(a1, b0, acc[1]);
;         }
;         if (kt + 1 < nk) {
; #pragma unroll
;             for (int j = 0; j < 4; ++j) *(u32x4*)(sA + (buf ^ 1) * TILE_E + (srow + 32 * j) * LS + skc) = ra[j];
; #pragma unroll
;             for (int j = 0; j < 2; ++j) *(u32x4*)(sB + (buf ^ 1) * TILE_E + (srow + 32 * j) * LS + skc) = rb[j];
;         }
;     }
	ds_read_b128 v[82:85], v79 offset:18432
	ds_read_b128 v[188:191], v80 offset:55296
	ds_read_b128 v[86:89], v79 offset:23040
	ds_read_b128 v[192:195], v79 offset:18464
	ds_read_b128 v[200:203], v80 offset:55328
	ds_read_b128 v[196:199], v79 offset:23072
	ds_read_b128 v[204:207], v79 offset:18496
	ds_read_b128 v[230:233], v80 offset:55360
	ds_read_b128 v[208:211], v79 offset:23104
	ds_read_b128 v[234:237], v79 offset:18528
	ds_read_b128 v[242:245], v80 offset:55392
	ds_read_b128 v[238:241], v79 offset:23136
	s_waitcnt lgkmcnt(10)
	v_mfma_f32_32x32x16_bf16 v[18:33], v[82:85], v[188:191], v[18:33]
	s_waitcnt lgkmcnt(9)
	v_mfma_f32_32x32x16_bf16 v[2:17], v[86:89], v[188:191], v[2:17]
	s_waitcnt lgkmcnt(7)
	v_mfma_f32_32x32x16_bf16 v[18:33], v[192:195], v[200:203], v[18:33]
	s_waitcnt lgkmcnt(6)
	v_mfma_f32_32x32x16_bf16 v[2:17], v[196:199], v[200:203], v[2:17]
	s_waitcnt lgkmcnt(4)
	v_mfma_f32_32x32x16_bf16 v[18:33], v[204:207], v[230:233], v[18:33]
	s_waitcnt lgkmcnt(3)
	v_mfma_f32_32x32x16_bf16 v[2:17], v[208:211], v[230:233], v[2:17]
	s_waitcnt lgkmcnt(1)
	v_mfma_f32_32x32x16_bf16 v[18:33], v[234:237], v[242:245], v[18:33]
	s_waitcnt lgkmcnt(0)
	v_mfma_f32_32x32x16_bf16 v[2:17], v[238:241], v[242:245], v[2:17]
	s_waitcnt vmcnt(6)
	ds_write_b128 v78, v[164:167] offset:0
	ds_write_b128 v78, v[168:171] offset:4608
	ds_write_b128 v78, v[172:175] offset:9216
	ds_write_b128 v78, v[176:179] offset:13824
	ds_write_b128 v78, v[180:183] offset:36864
	ds_write_b128 v78, v[184:187] offset:41472
	s_waitcnt lgkmcnt(0)
	s_barrier
	ds_read_b128 v[82:85], v79 offset:0
	ds_read_b128 v[188:191], v80 offset:36864
	ds_read_b128 v[86:89], v79 offset:4608
	ds_read_b128 v[192:195], v79 offset:32
	ds_read_b128 v[200:203], v80 offset:36896
	ds_read_b128 v[196:199], v79 offset:4640
	ds_read_b128 v[204:207], v79 offset:64
	ds_read_b128 v[230:233], v80 offset:36928
	ds_read_b128 v[208:211], v79 offset:4672
	ds_read_b128 v[234:237], v79 offset:96
	ds_read_b128 v[242:245], v80 offset:36960
	ds_read_b128 v[238:241], v79 offset:4704
	s_waitcnt lgkmcnt(10)
	v_mfma_f32_32x32x16_bf16 v[18:33], v[82:85], v[188:191], v[18:33]
	s_waitcnt lgkmcnt(9)
	v_mfma_f32_32x32x16_bf16 v[2:17], v[86:89], v[188:191], v[2:17]
	s_waitcnt lgkmcnt(7)
	v_mfma_f32_32x32x16_bf16 v[18:33], v[192:195], v[200:203], v[18:33]
	s_waitcnt lgkmcnt(6)
	v_mfma_f32_32x32x16_bf16 v[2:17], v[196:199], v[200:203], v[2:17]
	s_waitcnt lgkmcnt(4)
	v_mfma_f32_32x32x16_bf16 v[18:33], v[204:207], v[230:233], v[18:33]
	s_waitcnt lgkmcnt(3)
	v_mfma_f32_32x32x16_bf16 v[2:17], v[208:211], v[230:233], v[2:17]
	s_waitcnt lgkmcnt(1)
	v_mfma_f32_32x32x16_bf16 v[18:33], v[234:237], v[242:245], v[18:33]
	s_waitcnt lgkmcnt(0)
	v_mfma_f32_32x32x16_bf16 v[2:17], v[238:241], v[242:245], v[2:17]
	s_waitcnt vmcnt(0)
	ds_write_b128 v78, v[34:37] offset:18432
	ds_write_b128 v78, v[38:41] offset:23040
	ds_write_b128 v78, v[42:45] offset:27648
	ds_write_b128 v78, v[46:49] offset:32256
	ds_write_b128 v78, v[50:53] offset:55296
	ds_write_b128 v78, v[54:57] offset:59904
	s_waitcnt lgkmcnt(0)
	s_barrier
	ds_read_b128 v[82:85], v79 offset:18432
	ds_read_b128 v[188:191], v80 offset:55296
	ds_read_b128 v[86:89], v79 offset:23040
	ds_read_b128 v[192:195], v79 offset:18464
	ds_read_b128 v[200:203], v80 offset:55328
	ds_read_b128 v[196:199], v79 offset:23072
	ds_read_b128 v[204:207], v79 offset:18496
	ds_read_b128 v[230:233], v80 offset:55360
	ds_read_b128 v[208:211], v79 offset:23104
	ds_read_b128 v[234:237], v79 offset:18528
	ds_read_b128 v[242:245], v80 offset:55392
	ds_read_b128 v[238:241], v79 offset:23136
	s_waitcnt lgkmcnt(10)
	v_mfma_f32_32x32x16_bf16 v[18:33], v[82:85], v[188:191], v[18:33]
	s_waitcnt lgkmcnt(9)
	v_mfma_f32_32x32x16_bf16 v[2:17], v[86:89], v[188:191], v[2:17]
	s_waitcnt lgkmcnt(7)
	v_mfma_f32_32x32x16_bf16 v[18:33], v[192:195], v[200:203], v[18:33]
	s_waitcnt lgkmcnt(6)
	v_mfma_f32_32x32x16_bf16 v[2:17], v[196:199], v[200:203], v[2:17]
	s_waitcnt lgkmcnt(4)
	v_mfma_f32_32x32x16_bf16 v[18:33], v[204:207], v[230:233], v[18:33]
	s_waitcnt lgkmcnt(3)
	v_mfma_f32_32x32x16_bf16 v[2:17], v[208:211], v[230:233], v[2:17]
	s_waitcnt lgkmcnt(1)
	v_mfma_f32_32x32x16_bf16 v[18:33], v[234:237], v[242:245], v[18:33]
	s_waitcnt lgkmcnt(0)
	v_mfma_f32_32x32x16_bf16 v[2:17], v[238:241], v[242:245], v[2:17]
	s_nop 7
; DI void phase1(const Params& p, int l, unsigned char* smem) {
;     ...
;             } else if (r4 < 4) {
;                 float* pf = (float*)(ws + O_FL) + (size_t)(b * 4 + r4) * S_ + s0 + 4 * h4;
;                 const float fb = p.fox_bias[l * 4 + r4];
; #pragma unroll
;                 for (int mi = 0; mi < 2; ++mi)
; #pragma unroll
;                     for (int qd = 0; qd < 4; ++qd) {
;                         f32x4 o;
; #pragma unroll
;                         for (int e = 0; e < 4; ++e) { const float xv = acc[mi][4 * qd + e] + fb; o[e] = (fminf(xv, 0.f) - log1pf(expf(-fabsf(xv)))) * LOG2E; }
;                         *(f32x4*)(pf + 32 * mi + 8 * qd) = o;
;                     }
.LBB0_506:
	v_add_u32_e32 v0, s18, v122
	s_and_saveexec_b64 s[18:19], s[4:5]
	s_xor_b64 s[18:19], exec, s[18:19]
	s_cbranch_execz .LBB0_510
	s_and_saveexec_b64 s[20:21], s[6:7]
	s_cbranch_execz .LBB0_509
	global_load_dword v40, v[64:65], off
	s_waitcnt vmcnt(0)
	v_and_b32_e32 v35, 0x1fc0, v0
	v_ashrrev_i32_e32 v0, 11, v0
	v_and_or_b32 v34, v0, -4, v58
	v_lshlrev_b32_e32 v0, 2, v35
	v_ashrrev_i32_e32 v35, 31, v34
	v_lshlrev_b64 v[34:35], 15, v[34:35]
	v_lshl_add_u64 v[34:35], s[12:13], 0, v[34:35]
	v_lshl_add_u64 v[34:35], v[34:35], 0, v[0:1]
	v_lshlrev_b32_e32 v0, 2, v60
	v_lshl_add_u64 v[34:35], v[34:35], 0, v[0:1]
	s_mov_b32 s0, 0x3fb8aa3b
	v_add_f32_e32 v42, v18, v40
	v_add_f32_e32 v43, v19, v40
	v_add_f32_e32 v44, v20, v40
	v_add_f32_e32 v45, v21, v40
	v_mul_f32_e64 v46, |v42|, s64
	v_mul_f32_e64 v47, |v43|, s64
	v_mul_f32_e64 v48, |v44|, s64
	v_mul_f32_e64 v49, |v45|, s64
	v_exp_f32_e32 v46, v46
	v_exp_f32_e32 v47, v47
	v_exp_f32_e32 v48, v48
	v_exp_f32_e32 v49, v49
	v_min_f32_e32 v50, 0, v42
	v_min_f32_e32 v51, 0, v43
	v_min_f32_e32 v52, 0, v44
	v_min_f32_e32 v53, 0, v45
	v_add_f32_e32 v46, 1.0, v46
	v_add_f32_e32 v47, 1.0, v47
	v_add_f32_e32 v48, 1.0, v48
	v_add_f32_e32 v49, 1.0, v49
	v_log_f32_e32 v46, v46
	v_log_f32_e32 v47, v47
	v_log_f32_e32 v48, v48
	v_log_f32_e32 v49, v49
	v_mul_f32_e32 v50, s0, v50
	v_mul_f32_e32 v51, s0, v51
	v_mul_f32_e32 v52, s0, v52
	v_mul_f32_e32 v53, s0, v53
	v_sub_f32_e32 v42, v50, v46
	v_sub_f32_e32 v43, v51, v47
	v_sub_f32_e32 v44, v52, v48
	v_sub_f32_e32 v45, v53, v49
	global_store_dwordx4 v[34:35], v[42:45], off
	s_nop 1
	v_add_f32_e32 v42, v22, v40
	v_add_f32_e32 v43, v23, v40
	v_add_f32_e32 v44, v24, v40
	v_add_f32_e32 v45, v25, v40
	v_mul_f32_e64 v46, |v42|, s64
	v_mul_f32_e64 v47, |v43|, s64
	v_mul_f32_e64 v48, |v44|, s64
	v_mul_f32_e64 v49, |v45|, s64
	v_exp_f32_e32 v46, v46
	v_exp_f32_e32 v47, v47
	v_exp_f32_e32 v48, v48
	v_exp_f32_e32 v49, v49
	v_min_f32_e32 v50, 0, v42
	v_min_f32_e32 v51, 0, v43
	v_min_f32_e32 v52, 0, v44
	v_min_f32_e32 v53, 0, v45
	v_add_f32_e32 v46, 1.0, v46
	v_add_f32_e32 v47, 1.0, v47
	v_add_f32_e32 v48, 1.0, v48
	v_add_f32_e32 v49, 1.0, v49
	v_log_f32_e32 v46, v46
	v_log_f32_e32 v47, v47
	v_log_f32_e32 v48, v48
	v_log_f32_e32 v49, v49
	v_mul_f32_e32 v50, s0, v50
	v_mul_f32_e32 v51, s0, v51
	v_mul_f32_e32 v52, s0, v52
	v_mul_f32_e32 v53, s0, v53
	v_sub_f32_e32 v42, v50, v46
	v_sub_f32_e32 v43, v51, v47
	v_sub_f32_e32 v44, v52, v48
	v_sub_f32_e32 v45, v53, v49
	global_store_dwordx4 v[34:35], v[42:45], off offset:32
	s_nop 1
	v_add_f32_e32 v42, v26, v40
	v_add_f32_e32 v43, v27, v40
	v_add_f32_e32 v44, v28, v40
	v_add_f32_e32 v45, v29, v40
	v_mul_f32_e64 v46, |v42|, s64
	v_mul_f32_e64 v47, |v43|, s64
	v_mul_f32_e64 v48, |v44|, s64
	v_mul_f32_e64 v49, |v45|, s64
	v_exp_f32_e32 v46, v46
	v_exp_f32_e32 v47, v47
	v_exp_f32_e32 v48, v48
	v_exp_f32_e32 v49, v49
	v_min_f32_e32 v50, 0, v42
	v_min_f32_e32 v51, 0, v43
	v_min_f32_e32 v52, 0, v44
	v_min_f32_e32 v53, 0, v45
	v_add_f32_e32 v46, 1.0, v46
	v_add_f32_e32 v47, 1.0, v47
	v_add_f32_e32 v48, 1.0, v48
	v_add_f32_e32 v49, 1.0, v49
	v_log_f32_e32 v46, v46
	v_log_f32_e32 v47, v47
	v_log_f32_e32 v48, v48
	v_log_f32_e32 v49, v49
	v_mul_f32_e32 v50, s0, v50
	v_mul_f32_e32 v51, s0, v51
	v_mul_f32_e32 v52, s0, v52
	v_mul_f32_e32 v53, s0, v53
	v_sub_f32_e32 v42, v50, v46
	v_sub_f32_e32 v43, v51, v47
	v_sub_f32_e32 v44, v52, v48
	v_sub_f32_e32 v45, v53, v49
	global_store_dwordx4 v[34:35], v[42:45], off offset:64
	s_nop 1
	v_add_f32_e32 v42, v30, v40
	v_add_f32_e32 v43, v31, v40
	v_add_f32_e32 v44, v32, v40
	v_add_f32_e32 v45, v33, v40
	v_mul_f32_e64 v46, |v42|, s64
	v_mul_f32_e64 v47, |v43|, s64
	v_mul_f32_e64 v48, |v44|, s64
	v_mul_f32_e64 v49, |v45|, s64
	v_exp_f32_e32 v46, v46
	v_exp_f32_e32 v47, v47
	v_exp_f32_e32 v48, v48
	v_exp_f32_e32 v49, v49
	v_min_f32_e32 v50, 0, v42
	v_min_f32_e32 v51, 0, v43
	v_min_f32_e32 v52, 0, v44
	v_min_f32_e32 v53, 0, v45
	v_add_f32_e32 v46, 1.0, v46
	v_add_f32_e32 v47, 1.0, v47
	v_add_f32_e32 v48, 1.0, v48
	v_add_f32_e32 v49, 1.0, v49
	v_log_f32_e32 v46, v46
	v_log_f32_e32 v47, v47
	v_log_f32_e32 v48, v48
; DI void phase1(const Params& p, int l, unsigned char* smem) {
;     ...
;             } else if (r4 < 4) {
;                 float* pf = (float*)(ws + O_FL) + (size_t)(b * 4 + r4) * S_ + s0 + 4 * h4;
;                 const float fb = p.fox_bias[l * 4 + r4];
; #pragma unroll
;                 for (int mi = 0; mi < 2; ++mi)
; #pragma unroll
;                     for (int qd = 0; qd < 4; ++qd) {
;                         f32x4 o;
; #pragma unroll
;                         for (int e = 0; e < 4; ++e) { const float xv = acc[mi][4 * qd + e] + fb; o[e] = (fminf(xv, 0.f) - log1pf(expf(-fabsf(xv)))) * LOG2E; }
;                         *(f32x4*)(pf + 32 * mi + 8 * qd) = o;
;                     }
	v_log_f32_e32 v49, v49
	v_mul_f32_e32 v50, s0, v50
	v_mul_f32_e32 v51, s0, v51
	v_mul_f32_e32 v52, s0, v52
	v_mul_f32_e32 v53, s0, v53
	v_sub_f32_e32 v42, v50, v46
	v_sub_f32_e32 v43, v51, v47
	v_sub_f32_e32 v44, v52, v48
	v_sub_f32_e32 v45, v53, v49
	global_store_dwordx4 v[34:35], v[42:45], off offset:96
	s_nop 1
	v_add_f32_e32 v42, v2, v40
	v_add_f32_e32 v43, v3, v40
	v_add_f32_e32 v44, v4, v40
	v_add_f32_e32 v45, v5, v40
	v_mul_f32_e64 v46, |v42|, s64
	v_mul_f32_e64 v47, |v43|, s64
	v_mul_f32_e64 v48, |v44|, s64
	v_mul_f32_e64 v49, |v45|, s64
	v_exp_f32_e32 v46, v46
	v_exp_f32_e32 v47, v47
	v_exp_f32_e32 v48, v48
	v_exp_f32_e32 v49, v49
	v_min_f32_e32 v50, 0, v42
	v_min_f32_e32 v51, 0, v43
	v_min_f32_e32 v52, 0, v44
	v_min_f32_e32 v53, 0, v45
	v_add_f32_e32 v46, 1.0, v46
	v_add_f32_e32 v47, 1.0, v47
	v_add_f32_e32 v48, 1.0, v48
	v_add_f32_e32 v49, 1.0, v49
	v_log_f32_e32 v46, v46
	v_log_f32_e32 v47, v47
	v_log_f32_e32 v48, v48
	v_log_f32_e32 v49, v49
	v_mul_f32_e32 v50, s0, v50
	v_mul_f32_e32 v51, s0, v51
	v_mul_f32_e32 v52, s0, v52
	v_mul_f32_e32 v53, s0, v53
	v_sub_f32_e32 v42, v50, v46
	v_sub_f32_e32 v43, v51, v47
	v_sub_f32_e32 v44, v52, v48
	v_sub_f32_e32 v45, v53, v49
	global_store_dwordx4 v[34:35], v[42:45], off offset:128
	s_nop 1
	v_add_f32_e32 v42, v6, v40
	v_add_f32_e32 v43, v7, v40
	v_add_f32_e32 v44, v8, v40
	v_add_f32_e32 v45, v9, v40
	v_mul_f32_e64 v46, |v42|, s64
	v_mul_f32_e64 v47, |v43|, s64
	v_mul_f32_e64 v48, |v44|, s64
	v_mul_f32_e64 v49, |v45|, s64
	v_exp_f32_e32 v46, v46
	v_exp_f32_e32 v47, v47
	v_exp_f32_e32 v48, v48
	v_exp_f32_e32 v49, v49
	v_min_f32_e32 v50, 0, v42
	v_min_f32_e32 v51, 0, v43
	v_min_f32_e32 v52, 0, v44
	v_min_f32_e32 v53, 0, v45
	v_add_f32_e32 v46, 1.0, v46
	v_add_f32_e32 v47, 1.0, v47
	v_add_f32_e32 v48, 1.0, v48
	v_add_f32_e32 v49, 1.0, v49
	v_log_f32_e32 v46, v46
	v_log_f32_e32 v47, v47
	v_log_f32_e32 v48, v48
	v_log_f32_e32 v49, v49
	v_mul_f32_e32 v50, s0, v50
	v_mul_f32_e32 v51, s0, v51
	v_mul_f32_e32 v52, s0, v52
	v_mul_f32_e32 v53, s0, v53
	v_sub_f32_e32 v42, v50, v46
	v_sub_f32_e32 v43, v51, v47
	v_sub_f32_e32 v44, v52, v48
	v_sub_f32_e32 v45, v53, v49
	global_store_dwordx4 v[34:35], v[42:45], off offset:160
	s_nop 1
	v_add_f32_e32 v42, v10, v40
	v_add_f32_e32 v43, v11, v40
	v_add_f32_e32 v44, v12, v40
	v_add_f32_e32 v45, v13, v40
	v_mul_f32_e64 v46, |v42|, s64
	v_mul_f32_e64 v47, |v43|, s64
	v_mul_f32_e64 v48, |v44|, s64
	v_mul_f32_e64 v49, |v45|, s64
	v_exp_f32_e32 v46, v46
	v_exp_f32_e32 v47, v47
	v_exp_f32_e32 v48, v48
	v_exp_f32_e32 v49, v49
	v_min_f32_e32 v50, 0, v42
	v_min_f32_e32 v51, 0, v43
	v_min_f32_e32 v52, 0, v44
	v_min_f32_e32 v53, 0, v45
	v_add_f32_e32 v46, 1.0, v46
	v_add_f32_e32 v47, 1.0, v47
	v_add_f32_e32 v48, 1.0, v48
	v_add_f32_e32 v49, 1.0, v49
	v_log_f32_e32 v46, v46
	v_log_f32_e32 v47, v47
	v_log_f32_e32 v48, v48
	v_log_f32_e32 v49, v49
	v_mul_f32_e32 v50, s0, v50
	v_mul_f32_e32 v51, s0, v51
	v_mul_f32_e32 v52, s0, v52
	v_mul_f32_e32 v53, s0, v53
	v_sub_f32_e32 v42, v50, v46
	v_sub_f32_e32 v43, v51, v47
	v_sub_f32_e32 v44, v52, v48
	v_sub_f32_e32 v45, v53, v49
	global_store_dwordx4 v[34:35], v[42:45], off offset:192
	s_nop 1
	v_add_f32_e32 v42, v14, v40
	v_add_f32_e32 v43, v15, v40
	v_add_f32_e32 v44, v16, v40
	v_add_f32_e32 v45, v17, v40
	v_mul_f32_e64 v46, |v42|, s64
	v_mul_f32_e64 v47, |v43|, s64
	v_mul_f32_e64 v48, |v44|, s64
	v_mul_f32_e64 v49, |v45|, s64
	v_exp_f32_e32 v46, v46
	v_exp_f32_e32 v47, v47
	v_exp_f32_e32 v48, v48
	v_exp_f32_e32 v49, v49
	v_min_f32_e32 v50, 0, v42
	v_min_f32_e32 v51, 0, v43
	v_min_f32_e32 v52, 0, v44
	v_min_f32_e32 v53, 0, v45
	v_add_f32_e32 v46, 1.0, v46
	v_add_f32_e32 v47, 1.0, v47
	v_add_f32_e32 v48, 1.0, v48
	v_add_f32_e32 v49, 1.0, v49
	v_log_f32_e32 v46, v46
	v_log_f32_e32 v47, v47
	v_log_f32_e32 v48, v48
	v_log_f32_e32 v49, v49
	v_mul_f32_e32 v50, s0, v50
	v_mul_f32_e32 v51, s0, v51
	v_mul_f32_e32 v52, s0, v52
	v_mul_f32_e32 v53, s0, v53
	v_sub_f32_e32 v42, v50, v46
	v_sub_f32_e32 v43, v51, v47
	v_sub_f32_e32 v44, v52, v48
	v_sub_f32_e32 v45, v53, v49
	global_store_dwordx4 v[34:35], v[42:45], off offset:224
	s_nop 1

; template <typename T> DI T* opaque(T* p) { asm volatile("" : "+v"(p) : : "memory"); return p; }
; DI void phase1(const Params& p, int l, unsigned char* smem) {
;     ...
;             if (wc4 == 0) {
;                 float* pb = (float*)(ws + O_TAIL) + (size_t)(row0 + 4 * h4) * 32 + r4;
; #pragma unroll
;                 for (int mi = 0; mi < 2; ++mi)
; #pragma unroll
;                     for (int qd = 0; qd < 4; ++qd) {
;                         float* q = opaque(pb + (size_t)(32 * mi + 8 * qd) * 32);
; #pragma unroll
;                         for (int e = 0; e < 4; ++e) q[e * 32] = acc[mi][4 * qd + e];
;                     }
.LBB0_510:
	s_andn2_saveexec_b64 s[18:19], s[18:19]
	s_cbranch_execz .LBB0_499
	s_waitcnt vmcnt(0)
	v_or_b32_e32 v34, v0, v60
	v_ashrrev_i32_e32 v35, 31, v34
	v_lshlrev_b64 v[34:35], 7, v[34:35]
	v_lshl_add_u64 v[34:35], v[62:63], 0, v[34:35]
	v_mov_b64_e32 v[36:37], v[34:35]
	s_mov_b64 s[0:1], 0x400
	global_store_dword v[36:37], v18, off
	global_store_dword v[36:37], v19, off offset:128
	global_store_dword v[36:37], v20, off offset:256
	global_store_dword v[36:37], v21, off offset:384
	v_lshl_add_u64 v[18:19], v[34:35], 0, s[0:1]
	s_mov_b64 s[0:1], 0x800
	global_store_dword v[18:19], v22, off
	global_store_dword v[18:19], v23, off offset:128
	global_store_dword v[18:19], v24, off offset:256
	global_store_dword v[18:19], v25, off offset:384
	v_lshl_add_u64 v[18:19], v[34:35], 0, s[0:1]
	s_mov_b64 s[0:1], 0xc00
	global_store_dword v[18:19], v26, off
	global_store_dword v[18:19], v27, off offset:128
	global_store_dword v[18:19], v28, off offset:256
	global_store_dword v[18:19], v29, off offset:384
	v_lshl_add_u64 v[18:19], v[34:35], 0, s[0:1]
	s_mov_b64 s[0:1], 0x1000
	global_store_dword v[18:19], v30, off
	global_store_dword v[18:19], v31, off offset:128
	global_store_dword v[18:19], v32, off offset:256
	global_store_dword v[18:19], v33, off offset:384
	v_lshl_add_u64 v[18:19], v[34:35], 0, s[0:1]
	s_mov_b64 s[0:1], 0x1400
	global_store_dword v[18:19], v2, off
	global_store_dword v[18:19], v3, off offset:128
	global_store_dword v[18:19], v4, off offset:256
	global_store_dword v[18:19], v5, off offset:384
	v_lshl_add_u64 v[2:3], v[34:35], 0, s[0:1]
	s_mov_b64 s[0:1], 0x1800
	global_store_dword v[2:3], v6, off
	global_store_dword v[2:3], v7, off offset:128
	global_store_dword v[2:3], v8, off offset:256
	global_store_dword v[2:3], v9, off offset:384
	v_lshl_add_u64 v[2:3], v[34:35], 0, s[0:1]
	s_mov_b64 s[0:1], 0x1c00
	global_store_dword v[2:3], v10, off
	global_store_dword v[2:3], v11, off offset:128
	global_store_dword v[2:3], v12, off offset:256
	global_store_dword v[2:3], v13, off offset:384
	v_lshl_add_u64 v[2:3], v[34:35], 0, s[0:1]
	global_store_dword v[2:3], v14, off
	global_store_dword v[2:3], v15, off offset:128
	global_store_dword v[2:3], v16, off offset:256
	global_store_dword v[2:3], v17, off offset:384
	s_branch .LBB0_499

; DI void gemm_accum(f32x16 (&acc)[2][2], const bf16_t* A, int lda, const bf16_t* Bt, int ldb, int nk, unsigned char* smem) {
;     const int tid = tid_op(), lane = tid & 63, w = tid >> 6, wr = w >> 1, wc = w & 1, r = lane & 31, h = lane >> 5;
;     bf16_t* sA = (bf16_t*)smem;
;     bf16_t* sB = sA + 2 * TILE_E;
;     u32x4 ra[4], rb[4];
;     const unsigned oa = (unsigned)(((tid >> 3) * lda + (tid & 7) * 8) * 2), ob = (unsigned)(((tid >> 3) * ldb + (tid & 7) * 8) * 2);
;     const unsigned sa = (unsigned)(lda * 64), sb = (unsigned)(ldb * 64);
;     g_load(ra, rb, A, oa, sa, Bt, ob, sb);
;     __syncthreads();
;     g_store(ra, rb, sA, sB, tid);
; #pragma unroll 1
;     for (int kt = 0; kt < nk; ++kt) {
;         const int buf = kt & 1;
;         if (kt + 1 < nk) g_load(ra, rb, A + (kt + 1) * 64, oa, sa, Bt + (kt + 1) * 64, ob, sb);
;         __syncthreads();
;         const bf16_t* a = sA + buf * TILE_E + (wr * 64 + r) * LS + h * 8;
;         const bf16_t* b = sB + buf * TILE_E + (wc * 64 + r) * LS + h * 8;
; #pragma unroll
;         for (int s = 0; s < 4; ++s) {
;             const bf16x8 a0 = *(const bf16x8*)(a + s * 16), a1 = *(const bf16x8*)(a + 32 * LS + s * 16);
;             const bf16x8 b0 = *(const bf16x8*)(b + s * 16), b1 = *(const bf16x8*)(b + 32 * LS + s * 16);
;             acc[0][0] = MFMA32(a0, b0, acc[0][0]);
;             acc[0][1] = MFMA32(a0, b1, acc[0][1]);
;             acc[1][0] = MFMA32(a1, b0, acc[1][0]);
;             acc[1][1] = MFMA32(a1, b1, acc[1][1]);
;         }
;         if (kt + 1 < nk) g_store(ra, rb, sA + (buf ^ 1) * TILE_E, sB + (buf ^ 1) * TILE_E, tid);
;     }
; }
; DI void phase1(const Params& p, int l, unsigned char* smem) {
;     ...
;         for (int t = VB - 256; t >= 0 && t < 32; t += VG) {
;             const int m0 = (t >> 2) * 128, n0 = (t & 3) * 128;
;             f32x16 acc[2][2]; zero4(acc);
;             gemm_accum(acc, (const bf16_t*)(ws + O_MEMB) + (size_t)m0 * 1024, 1024, (const bf16_t*)(ws + O_WMEM + l * SZ_WMEM) + (size_t)n0 * 1024, 1024, 16, hs);
;             const int row0 = m0 + 64 * wr4, b = row0 >> 8, j0 = row0 & 255, gc = n0 + 64 * wc4;
;             if (gc < 256) st_rm(acc, (bf16_t*)(ws + O_MEMK) + ((size_t)(b * 4 + (gc >> 6)) * 256 + j0) * 64, 64, 1.f, r4, h4);
;             else st_tr(acc, (bf16_t*)(ws + O_MEMVT) + (size_t)(b * 4 + ((gc - 256) >> 6)) * 64 * 256 + j0, 256, 1.f, r4, h4);
.LBB0_515:
	s_lshl_b32 s8, s19, 11
	s_and_b32 s25, s8, 0xc0000
	s_lshl_b32 s8, s22, 11
	s_and_b32 s26, s8, 0x1c0000
	s_lshl_b32 s8, s12, 5
	s_and_b32 s24, s8, 0x380
	s_lshl_b32 s8, s12, 7
	s_and_b32 s23, s8, 0x180
	s_lshl_b32 s8, s24, 11
	v_mov_b32_e32 v12, v215
	s_add_u32 s8, s13, s8
	s_addc_u32 s9, s14, 0
	v_lshlrev_b32_e32 v0, 4, v12
	s_lshl_b32 s10, s23, 11
	v_ashrrev_i32_e32 v13, 3, v12
	v_and_b32_e32 v14, 0x70, v0
	s_add_u32 s10, s15, s10
	v_lshl_or_b32 v0, v13, 11, v14
	s_addc_u32 s11, s16, 0
	v_lshl_add_u64 v[2:3], s[8:9], 0, v[0:1]
	v_lshl_add_u64 v[4:5], s[10:11], 0, v[0:1]
	global_load_dwordx4 v[66:69], v[2:3], off
	global_load_dwordx4 v[70:73], v[4:5], off
	v_add_u32_e32 v2, 0x10000, v0
	v_mov_b32_e32 v3, v1
	v_lshl_add_u64 v[4:5], s[8:9], 0, v[2:3]
	v_lshl_add_u64 v[6:7], s[10:11], 0, v[2:3]
	global_load_dwordx4 v[74:77], v[4:5], off
	global_load_dwordx4 v[78:81], v[6:7], off
	v_add_u32_e32 v4, 0x20000, v0
	v_mov_b32_e32 v5, v1
	v_lshl_add_u64 v[6:7], s[8:9], 0, v[4:5]
	v_lshl_add_u64 v[8:9], s[10:11], 0, v[4:5]
	global_load_dwordx4 v[82:85], v[6:7], off
	global_load_dwordx4 v[86:89], v[8:9], off
	v_add_u32_e32 v6, 0x30000, v0
	v_mov_b32_e32 v7, v1
	v_lshl_add_u64 v[8:9], s[8:9], 0, v[6:7]
	v_lshl_add_u64 v[10:11], s[10:11], 0, v[6:7]
	global_load_dwordx4 v[90:93], v[8:9], off
	global_load_dwordx4 v[94:97], v[10:11], off
	s_add_u32 s8, s17, s25
	v_add_u32_e32 v9, 0x100, v12
	v_add_u32_e32 v10, 0x200, v12
	v_add_u32_e32 v11, 0x300, v12
	s_addc_u32 s9, s18, 0
	v_and_b32_e32 v8, 31, v12
	v_lshrrev_b32_e32 v15, 1, v12
	v_and_b32_e32 v12, 0x5f, v12
	s_movk_i32 s1, 0x48
	v_lshrrev_b32_e32 v9, 3, v9
	v_lshrrev_b32_e32 v10, 3, v10
	v_lshrrev_b32_e32 v11, 3, v11
	v_lshl_add_u64 v[106:107], s[8:9], 0, v[6:7]
	v_lshl_add_u64 v[108:109], s[8:9], 0, v[4:5]
	v_lshl_add_u64 v[110:111], s[8:9], 0, v[2:3]
	v_lshl_add_u64 v[112:113], s[8:9], 0, v[0:1]
	s_add_u32 s8, s20, s26
	v_mul_lo_u32 v99, v13, s1
	v_and_or_b32 v8, v15, s93, v8
	v_and_b32_e32 v13, 16, v15
	v_mul_u32_u24_e32 v12, 0x90, v12
	v_add_u32_e32 v101, s3, v14
	v_mul_lo_u32 v103, v9, s1
	v_mul_lo_u32 v105, v10, s1
	v_mul_lo_u32 v124, v11, s1
	s_addc_u32 s9, s21, 0
	v_mul_lo_u32 v8, v8, s92
	v_add3_u32 v125, s3, v12, v13
	v_lshl_add_u32 v9, v99, 1, v101
	v_lshl_add_u32 v10, v103, 1, v101
	v_lshl_add_u32 v11, v105, 1, v101
	v_lshl_add_u32 v12, v124, 1, v101
	v_lshl_add_u64 v[118:119], s[8:9], 0, v[2:3]
	v_mov_b32_e32 v2, 0
	v_add3_u32 v126, s3, v8, v13
	s_waitcnt vmcnt(0) lgkmcnt(0)
	s_barrier
	v_lshl_add_u64 v[114:115], s[8:9], 0, v[6:7]
	v_lshl_add_u64 v[116:117], s[8:9], 0, v[4:5]
	v_lshl_add_u64 v[120:121], s[8:9], 0, v[0:1]
	global_load_dwordx4 v[140:143], v[120:121], off offset:0
	global_load_dwordx4 v[144:147], v[112:113], off offset:0
	global_load_dwordx4 v[148:151], v[118:119], off offset:0
	global_load_dwordx4 v[152:155], v[110:111], off offset:0
	global_load_dwordx4 v[156:159], v[116:117], off offset:0
	global_load_dwordx4 v[160:163], v[108:109], off offset:0
	global_load_dwordx4 v[164:167], v[114:115], off offset:0
	global_load_dwordx4 v[168:171], v[106:107], off offset:0
	global_load_dwordx4 v[172:175], v[120:121], off offset:128
	global_load_dwordx4 v[176:179], v[112:113], off offset:128
	global_load_dwordx4 v[180:183], v[118:119], off offset:128
	global_load_dwordx4 v[184:187], v[110:111], off offset:128
	global_load_dwordx4 v[188:191], v[116:117], off offset:128
	global_load_dwordx4 v[192:195], v[108:109], off offset:128
	global_load_dwordx4 v[196:199], v[114:115], off offset:128
	global_load_dwordx4 v[200:203], v[106:107], off offset:128
	s_mov_b32 s25, 0
	s_mov_b64 s[8:9], 0
	v_mov_b32_e32 v3, v2
	v_mov_b32_e32 v4, v2
	v_mov_b32_e32 v5, v2
	v_mov_b32_e32 v6, v2
	v_mov_b32_e32 v7, v2
	v_mov_b32_e32 v8, v2
	v_mov_b32_e32 v13, v2
	v_mov_b32_e32 v14, v2
	v_mov_b32_e32 v15, v2
	v_mov_b32_e32 v16, v2
	v_mov_b32_e32 v17, v2
	v_mov_b32_e32 v18, v2
	v_mov_b32_e32 v19, v2
	v_mov_b32_e32 v20, v2
	ds_write_b128 v9, v[66:69]
	ds_write_b128 v9, v[70:73] offset:36864
	ds_write_b128 v10, v[74:77]
	ds_write_b128 v10, v[78:81] offset:36864
	ds_write_b128 v11, v[82:85]
	ds_write_b128 v11, v[86:89] offset:36864
	ds_write_b128 v12, v[90:93]
	ds_write_b128 v12, v[94:97] offset:36864
	v_mov_b32_e32 v9, v2
	v_mov_b32_e32 v10, v2
	v_mov_b32_e32 v11, v2
	v_mov_b32_e32 v12, v2
	v_mov_b32_e32 v21, v2
	v_mov_b32_e32 v22, v2
	v_mov_b32_e32 v23, v2
	v_mov_b32_e32 v24, v2
	v_mov_b32_e32 v25, v2
	v_mov_b32_e32 v26, v2
	v_mov_b32_e32 v27, v2
	v_mov_b32_e32 v28, v2
	v_mov_b32_e32 v29, v2
	v_mov_b32_e32 v30, v2
	v_mov_b32_e32 v31, v2
	v_mov_b32_e32 v32, v2
	v_mov_b32_e32 v33, v2
	v_mov_b32_e32 v34, v2
	v_mov_b32_e32 v35, v2
	v_mov_b32_e32 v36, v2
	v_mov_b32_e32 v37, v2
	v_mov_b32_e32 v38, v2
	v_mov_b32_e32 v39, v2
	v_mov_b32_e32 v40, v2
	v_mov_b32_e32 v41, v2
	v_mov_b32_e32 v42, v2
	v_mov_b32_e32 v43, v2
	v_mov_b32_e32 v44, v2
	v_mov_b32_e32 v45, v2
	v_mov_b32_e32 v46, v2
	v_mov_b32_e32 v47, v2
	v_mov_b32_e32 v48, v2
	v_mov_b32_e32 v49, v2
	v_mov_b32_e32 v50, v2
	v_mov_b32_e32 v51, v2
	v_mov_b32_e32 v52, v2
	v_mov_b32_e32 v53, v2
	v_mov_b32_e32 v54, v2
	v_mov_b32_e32 v55, v2
	v_mov_b32_e32 v56, v2
	v_mov_b32_e32 v57, v2
	v_mov_b32_e32 v58, v2
	v_mov_b32_e32 v59, v2
	v_mov_b32_e32 v60, v2
	v_mov_b32_e32 v61, v2
	v_mov_b32_e32 v62, v2
	v_mov_b32_e32 v63, v2
	v_mov_b32_e32 v64, v2
	v_mov_b32_e32 v65, v2
	v_lshl_add_u32 v208, v99, 1, v101
	v_lshl_add_u32 v209, v103, 1, v101
	v_lshl_add_u32 v210, v105, 1, v101
	v_lshl_add_u32 v211, v124, 1, v101
	s_branch .LBB0_517
; DI int tid_op() { int t = threadIdx.x & 255; asm volatile("" : "+v"(t)); return t; }
; DI void g_load(u32x4 (&ra)[4], u32x4 (&rb)[4], const bf16_t* A, unsigned oa, unsigned sa, const bf16_t* Bt, unsigned ob, unsigned sb) {
; #pragma unroll
;     for (int j = 0; j < 4; ++j) {
;         ra[j] = *(const u32x4*)((const unsigned char*)A + (oa + j * sa));
;         rb[j] = *(const u32x4*)((const unsigned char*)Bt + (ob + j * sb));
;     }
; }
; DI void g_store(const u32x4 (&ra)[4], const u32x4 (&rb)[4], bf16_t* sa, bf16_t* sb, int tid) {
; #pragma unroll
;     for (int j = 0; j < 4; ++j) {
;         const int c = tid + 256 * j, row = c >> 3, kc = (c & 7) * 8;
;         *(u32x4*)(sa + row * LS + kc) = ra[j];
;         *(u32x4*)(sb + row * LS + kc) = rb[j];
;     }
; }
; DI void gemm_accum(f32x16 (&acc)[2][2], const bf16_t* A, int lda, const bf16_t* Bt, int ldb, int nk, unsigned char* smem) {
;     const int tid = tid_op(), lane = tid & 63, w = tid >> 6, wr = w >> 1, wc = w & 1, r = lane & 31, h = lane >> 5;
;     bf16_t* sA = (bf16_t*)smem;
;     bf16_t* sB = sA + 2 * TILE_E;
;     u32x4 ra[4], rb[4];
;     const unsigned oa = (unsigned)(((tid >> 3) * lda + (tid & 7) * 8) * 2), ob = (unsigned)(((tid >> 3) * ldb + (tid & 7) * 8) * 2);
;     const unsigned sa = (unsigned)(lda * 64), sb = (unsigned)(ldb * 64);
;     g_load(ra, rb, A, oa, sa, Bt, ob, sb);
;     __syncthreads();
;     g_store(ra, rb, sA, sB, tid);
; #pragma unroll 1
;     for (int kt = 0; kt < nk; ++kt) {
;         const int buf = kt & 1;
;         if (kt + 1 < nk) g_load(ra, rb, A + (kt + 1) * 64, oa, sa, Bt + (kt + 1) * 64, ob, sb);
;         __syncthreads();
;         const bf16_t* a = sA + buf * TILE_E + (wr * 64 + r) * LS + h * 8;
;         const bf16_t* b = sB + buf * TILE_E + (wc * 64 + r) * LS + h * 8;
; #pragma unroll
;         for (int s = 0; s < 4; ++s) {
;             const bf16x8 a0 = *(const bf16x8*)(a + s * 16), a1 = *(const bf16x8*)(a + 32 * LS + s * 16);
;             const bf16x8 b0 = *(const bf16x8*)(b + s * 16), b1 = *(const bf16x8*)(b + 32 * LS + s * 16);
;             acc[0][0] = MFMA32(a0, b0, acc[0][0]);
;             acc[0][1] = MFMA32(a0, b1, acc[0][1]);
;             acc[1][0] = MFMA32(a1, b0, acc[1][0]);
;             acc[1][1] = MFMA32(a1, b1, acc[1][1]);
;         }
;         if (kt + 1 < nk) g_store(ra, rb, sA + (buf ^ 1) * TILE_E, sB + (buf ^ 1) * TILE_E, tid);
;     }
.LBB0_517:
	s_waitcnt lgkmcnt(0)
	global_load_dwordx4 v[66:69], v[120:121], off offset:256
	global_load_dwordx4 v[70:73], v[112:113], off offset:256
	global_load_dwordx4 v[74:77], v[118:119], off offset:256
	global_load_dwordx4 v[78:81], v[110:111], off offset:256
	global_load_dwordx4 v[82:85], v[116:117], off offset:256
	global_load_dwordx4 v[86:89], v[108:109], off offset:256
	global_load_dwordx4 v[90:93], v[114:115], off offset:256
	global_load_dwordx4 v[94:97], v[106:107], off offset:256
	s_barrier
	ds_read_b128 v[128:131], v126 offset:0
	ds_read_b128 v[136:139], v125 offset:36864
	ds_read_b128 v[230:233], v125 offset:41472
	ds_read_b128 v[132:135], v126 offset:4608
	ds_read_b128 v[234:237], v126 offset:32
	ds_read_b128 v[242:245], v125 offset:36896
	ds_read_b128 v[246:249], v125 offset:41504
	ds_read_b128 v[238:241], v126 offset:4640
	s_waitcnt lgkmcnt(6)
	v_mfma_f32_32x32x16_bf16 v[50:65], v[128:131], v[136:139], v[50:65]
	s_waitcnt lgkmcnt(5)
	v_mfma_f32_32x32x16_bf16 v[34:49], v[128:131], v[230:233], v[34:49]
	s_waitcnt lgkmcnt(4)
	v_mfma_f32_32x32x16_bf16 v[18:33], v[132:135], v[136:139], v[18:33]
	v_mfma_f32_32x32x16_bf16 v[2:17], v[132:135], v[230:233], v[2:17]
	ds_read_b128 v[128:131], v126 offset:64
	ds_read_b128 v[136:139], v125 offset:36928
	ds_read_b128 v[230:233], v125 offset:41536
	ds_read_b128 v[132:135], v126 offset:4672
	s_waitcnt lgkmcnt(6)
	v_mfma_f32_32x32x16_bf16 v[50:65], v[234:237], v[242:245], v[50:65]
	s_waitcnt lgkmcnt(5)
	v_mfma_f32_32x32x16_bf16 v[34:49], v[234:237], v[246:249], v[34:49]
	s_waitcnt lgkmcnt(4)
	v_mfma_f32_32x32x16_bf16 v[18:33], v[238:241], v[242:245], v[18:33]
	v_mfma_f32_32x32x16_bf16 v[2:17], v[238:241], v[246:249], v[2:17]
	ds_read_b128 v[234:237], v126 offset:96
	ds_read_b128 v[242:245], v125 offset:36960
	ds_read_b128 v[246:249], v125 offset:41568
	ds_read_b128 v[238:241], v126 offset:4704
	s_waitcnt lgkmcnt(6)
	v_mfma_f32_32x32x16_bf16 v[50:65], v[128:131], v[136:139], v[50:65]
	s_waitcnt lgkmcnt(5)
	v_mfma_f32_32x32x16_bf16 v[34:49], v[128:131], v[230:233], v[34:49]
	s_waitcnt lgkmcnt(4)
	v_mfma_f32_32x32x16_bf16 v[18:33], v[132:135], v[136:139], v[18:33]
	v_mfma_f32_32x32x16_bf16 v[2:17], v[132:135], v[230:233], v[2:17]
	s_waitcnt lgkmcnt(2)
	v_mfma_f32_32x32x16_bf16 v[50:65], v[234:237], v[242:245], v[50:65]
	s_waitcnt lgkmcnt(1)
	v_mfma_f32_32x32x16_bf16 v[34:49], v[234:237], v[246:249], v[34:49]
	s_waitcnt lgkmcnt(0)
	v_mfma_f32_32x32x16_bf16 v[18:33], v[238:241], v[242:245], v[18:33]
	v_mfma_f32_32x32x16_bf16 v[2:17], v[238:241], v[246:249], v[2:17]
	s_waitcnt vmcnt(16)
	ds_write_b128 v208, v[140:143] offset:18432
	ds_write_b128 v208, v[144:147] offset:55296
	ds_write_b128 v209, v[148:151] offset:18432
	ds_write_b128 v209, v[152:155] offset:55296
	ds_write_b128 v210, v[156:159] offset:18432
	ds_write_b128 v210, v[160:163] offset:55296
	ds_write_b128 v211, v[164:167] offset:18432
	ds_write_b128 v211, v[168:171] offset:55296
	s_waitcnt lgkmcnt(0)
	global_load_dwordx4 v[140:143], v[120:121], off offset:384
	global_load_dwordx4 v[144:147], v[112:113], off offset:384
	global_load_dwordx4 v[148:151], v[118:119], off offset:384
	global_load_dwordx4 v[152:155], v[110:111], off offset:384
	global_load_dwordx4 v[156:159], v[116:117], off offset:384
	global_load_dwordx4 v[160:163], v[108:109], off offset:384
	global_load_dwordx4 v[164:167], v[114:115], off offset:384
	global_load_dwordx4 v[168:171], v[106:107], off offset:384
	s_barrier
	ds_read_b128 v[128:131], v126 offset:18432
	ds_read_b128 v[136:139], v125 offset:55296
	ds_read_b128 v[230:233], v125 offset:59904
	ds_read_b128 v[132:135], v126 offset:23040
	ds_read_b128 v[234:237], v126 offset:18464
	ds_read_b128 v[242:245], v125 offset:55328
	ds_read_b128 v[246:249], v125 offset:59936
	ds_read_b128 v[238:241], v126 offset:23072
	s_waitcnt lgkmcnt(6)
	v_mfma_f32_32x32x16_bf16 v[50:65], v[128:131], v[136:139], v[50:65]
	s_waitcnt lgkmcnt(5)
	v_mfma_f32_32x32x16_bf16 v[34:49], v[128:131], v[230:233], v[34:49]
	s_waitcnt lgkmcnt(4)
	v_mfma_f32_32x32x16_bf16 v[18:33], v[132:135], v[136:139], v[18:33]
	v_mfma_f32_32x32x16_bf16 v[2:17], v[132:135], v[230:233], v[2:17]
	ds_read_b128 v[128:131], v126 offset:18496
	ds_read_b128 v[136:139], v125 offset:55360
	ds_read_b128 v[230:233], v125 offset:59968
	ds_read_b128 v[132:135], v126 offset:23104
	s_waitcnt lgkmcnt(6)
	v_mfma_f32_32x32x16_bf16 v[50:65], v[234:237], v[242:245], v[50:65]
	s_waitcnt lgkmcnt(5)
	v_mfma_f32_32x32x16_bf16 v[34:49], v[234:237], v[246:249], v[34:49]
	s_waitcnt lgkmcnt(4)
	v_mfma_f32_32x32x16_bf16 v[18:33], v[238:241], v[242:245], v[18:33]
	v_mfma_f32_32x32x16_bf16 v[2:17], v[238:241], v[246:249], v[2:17]
	ds_read_b128 v[234:237], v126 offset:18528
	ds_read_b128 v[242:245], v125 offset:55392
	ds_read_b128 v[246:249], v125 offset:60000
	ds_read_b128 v[238:241], v126 offset:23136
	s_waitcnt lgkmcnt(6)
	v_mfma_f32_32x32x16_bf16 v[50:65], v[128:131], v[136:139], v[50:65]
	s_waitcnt lgkmcnt(5)
	v_mfma_f32_32x32x16_bf16 v[34:49], v[128:131], v[230:233], v[34:49]
	s_waitcnt lgkmcnt(4)
	v_mfma_f32_32x32x16_bf16 v[18:33], v[132:135], v[136:139], v[18:33]
	v_mfma_f32_32x32x16_bf16 v[2:17], v[132:135], v[230:233], v[2:17]
	s_waitcnt lgkmcnt(2)
	v_mfma_f32_32x32x16_bf16 v[50:65], v[234:237], v[242:245], v[50:65]
	s_waitcnt lgkmcnt(1)
	v_mfma_f32_32x32x16_bf16 v[34:49], v[234:237], v[246:249], v[34:49]
	s_waitcnt lgkmcnt(0)
	v_mfma_f32_32x32x16_bf16 v[18:33], v[238:241], v[242:245], v[18:33]
	v_mfma_f32_32x32x16_bf16 v[2:17], v[238:241], v[246:249], v[2:17]
	s_waitcnt vmcnt(16)
	ds_write_b128 v208, v[172:175] offset:0
	ds_write_b128 v208, v[176:179] offset:36864
	ds_write_b128 v209, v[180:183] offset:0
	ds_write_b128 v209, v[184:187] offset:36864
	ds_write_b128 v210, v[188:191] offset:0
	ds_write_b128 v210, v[192:195] offset:36864
	ds_write_b128 v211, v[196:199] offset:0
	ds_write_b128 v211, v[200:203] offset:36864
	s_waitcnt lgkmcnt(0)
	global_load_dwordx4 v[172:175], v[120:121], off offset:512
	global_load_dwordx4 v[176:179], v[112:113], off offset:512
	global_load_dwordx4 v[180:183], v[118:119], off offset:512
	global_load_dwordx4 v[184:187], v[110:111], off offset:512
	global_load_dwordx4 v[188:191], v[116:117], off offset:512
	global_load_dwordx4 v[192:195], v[108:109], off offset:512
	global_load_dwordx4 v[196:199], v[114:115], off offset:512
	global_load_dwordx4 v[200:203], v[106:107], off offset:512
	s_barrier
; #define MFMA32(a, b, c) __builtin_amdgcn_mfma_f32_32x32x16_bf16((a), (b), (c), 0, 0, 0)
; DI void gemm_accum(f32x16 (&acc)[2][2], const bf16_t* A, int lda, const bf16_t* Bt, int ldb, int nk, unsigned char* smem) {
;     ...
; #pragma unroll 1
;     for (int kt = 0; kt < nk; ++kt) {
;         const int buf = kt & 1;
;         if (kt + 1 < nk) g_load(ra, rb, A + (kt + 1) * 64, oa, sa, Bt + (kt + 1) * 64, ob, sb);
;         __syncthreads();
;         const bf16_t* a = sA + buf * TILE_E + (wr * 64 + r) * LS + h * 8;
;         const bf16_t* b = sB + buf * TILE_E + (wc * 64 + r) * LS + h * 8;
; #pragma unroll
;         for (int s = 0; s < 4; ++s) {
;             const bf16x8 a0 = *(const bf16x8*)(a + s * 16), a1 = *(const bf16x8*)(a + 32 * LS + s * 16);
;             const bf16x8 b0 = *(const bf16x8*)(b + s * 16), b1 = *(const bf16x8*)(b + 32 * LS + s * 16);
;             acc[0][0] = MFMA32(a0, b0, acc[0][0]);
;             acc[0][1] = MFMA32(a0, b1, acc[0][1]);
;             acc[1][0] = MFMA32(a1, b0, acc[1][0]);
;             acc[1][1] = MFMA32(a1, b1, acc[1][1]);
;         }
;         if (kt + 1 < nk) g_store(ra, rb, sA + (buf ^ 1) * TILE_E, sB + (buf ^ 1) * TILE_E, tid);
;     }
	ds_read_b128 v[128:131], v126 offset:0
	ds_read_b128 v[136:139], v125 offset:36864
	ds_read_b128 v[230:233], v125 offset:41472
	ds_read_b128 v[132:135], v126 offset:4608
	ds_read_b128 v[234:237], v126 offset:32
	ds_read_b128 v[242:245], v125 offset:36896
	ds_read_b128 v[246:249], v125 offset:41504
	ds_read_b128 v[238:241], v126 offset:4640
	s_waitcnt lgkmcnt(6)
	v_mfma_f32_32x32x16_bf16 v[50:65], v[128:131], v[136:139], v[50:65]
	s_waitcnt lgkmcnt(5)
	v_mfma_f32_32x32x16_bf16 v[34:49], v[128:131], v[230:233], v[34:49]
	s_waitcnt lgkmcnt(4)
	v_mfma_f32_32x32x16_bf16 v[18:33], v[132:135], v[136:139], v[18:33]
	v_mfma_f32_32x32x16_bf16 v[2:17], v[132:135], v[230:233], v[2:17]
	ds_read_b128 v[128:131], v126 offset:64
	ds_read_b128 v[136:139], v125 offset:36928
	ds_read_b128 v[230:233], v125 offset:41536
	ds_read_b128 v[132:135], v126 offset:4672
	s_waitcnt lgkmcnt(6)
	v_mfma_f32_32x32x16_bf16 v[50:65], v[234:237], v[242:245], v[50:65]
	s_waitcnt lgkmcnt(5)
	v_mfma_f32_32x32x16_bf16 v[34:49], v[234:237], v[246:249], v[34:49]
	s_waitcnt lgkmcnt(4)
	v_mfma_f32_32x32x16_bf16 v[18:33], v[238:241], v[242:245], v[18:33]
	v_mfma_f32_32x32x16_bf16 v[2:17], v[238:241], v[246:249], v[2:17]
	ds_read_b128 v[234:237], v126 offset:96
	ds_read_b128 v[242:245], v125 offset:36960
	ds_read_b128 v[246:249], v125 offset:41568
	ds_read_b128 v[238:241], v126 offset:4704
	s_waitcnt lgkmcnt(6)
	v_mfma_f32_32x32x16_bf16 v[50:65], v[128:131], v[136:139], v[50:65]
	s_waitcnt lgkmcnt(5)
	v_mfma_f32_32x32x16_bf16 v[34:49], v[128:131], v[230:233], v[34:49]
	s_waitcnt lgkmcnt(4)
	v_mfma_f32_32x32x16_bf16 v[18:33], v[132:135], v[136:139], v[18:33]
	v_mfma_f32_32x32x16_bf16 v[2:17], v[132:135], v[230:233], v[2:17]
	s_waitcnt lgkmcnt(2)
	v_mfma_f32_32x32x16_bf16 v[50:65], v[234:237], v[242:245], v[50:65]
	s_waitcnt lgkmcnt(1)
	v_mfma_f32_32x32x16_bf16 v[34:49], v[234:237], v[246:249], v[34:49]
	s_waitcnt lgkmcnt(0)
	v_mfma_f32_32x32x16_bf16 v[18:33], v[238:241], v[242:245], v[18:33]
	v_mfma_f32_32x32x16_bf16 v[2:17], v[238:241], v[246:249], v[2:17]
	s_waitcnt vmcnt(16)
	ds_write_b128 v208, v[66:69] offset:18432
	ds_write_b128 v208, v[70:73] offset:55296
	ds_write_b128 v209, v[74:77] offset:18432
	ds_write_b128 v209, v[78:81] offset:55296
	ds_write_b128 v210, v[82:85] offset:18432
	ds_write_b128 v210, v[86:89] offset:55296
	ds_write_b128 v211, v[90:93] offset:18432
	ds_write_b128 v211, v[94:97] offset:55296
	s_waitcnt lgkmcnt(0)
	global_load_dwordx4 v[66:69], v[120:121], off offset:640
	global_load_dwordx4 v[70:73], v[112:113], off offset:640
	global_load_dwordx4 v[74:77], v[118:119], off offset:640
	global_load_dwordx4 v[78:81], v[110:111], off offset:640
	global_load_dwordx4 v[82:85], v[116:117], off offset:640
	global_load_dwordx4 v[86:89], v[108:109], off offset:640
	global_load_dwordx4 v[90:93], v[114:115], off offset:640
	global_load_dwordx4 v[94:97], v[106:107], off offset:640
	s_barrier
	ds_read_b128 v[128:131], v126 offset:18432
	ds_read_b128 v[136:139], v125 offset:55296
	ds_read_b128 v[230:233], v125 offset:59904
	ds_read_b128 v[132:135], v126 offset:23040
	ds_read_b128 v[234:237], v126 offset:18464
	ds_read_b128 v[242:245], v125 offset:55328
	ds_read_b128 v[246:249], v125 offset:59936
	ds_read_b128 v[238:241], v126 offset:23072
	s_waitcnt lgkmcnt(6)
	v_mfma_f32_32x32x16_bf16 v[50:65], v[128:131], v[136:139], v[50:65]
	s_waitcnt lgkmcnt(5)
	v_mfma_f32_32x32x16_bf16 v[34:49], v[128:131], v[230:233], v[34:49]
	s_waitcnt lgkmcnt(4)
	v_mfma_f32_32x32x16_bf16 v[18:33], v[132:135], v[136:139], v[18:33]
	v_mfma_f32_32x32x16_bf16 v[2:17], v[132:135], v[230:233], v[2:17]
	ds_read_b128 v[128:131], v126 offset:18496
	ds_read_b128 v[136:139], v125 offset:55360
	ds_read_b128 v[230:233], v125 offset:59968
	ds_read_b128 v[132:135], v126 offset:23104
	s_waitcnt lgkmcnt(6)
	v_mfma_f32_32x32x16_bf16 v[50:65], v[234:237], v[242:245], v[50:65]
	s_waitcnt lgkmcnt(5)
	v_mfma_f32_32x32x16_bf16 v[34:49], v[234:237], v[246:249], v[34:49]
	s_waitcnt lgkmcnt(4)
	v_mfma_f32_32x32x16_bf16 v[18:33], v[238:241], v[242:245], v[18:33]
	v_mfma_f32_32x32x16_bf16 v[2:17], v[238:241], v[246:249], v[2:17]
	ds_read_b128 v[234:237], v126 offset:18528
	ds_read_b128 v[242:245], v125 offset:55392
	ds_read_b128 v[246:249], v125 offset:60000
	ds_read_b128 v[238:241], v126 offset:23136
	s_waitcnt lgkmcnt(6)
	v_mfma_f32_32x32x16_bf16 v[50:65], v[128:131], v[136:139], v[50:65]
	s_waitcnt lgkmcnt(5)
	v_mfma_f32_32x32x16_bf16 v[34:49], v[128:131], v[230:233], v[34:49]
	s_waitcnt lgkmcnt(4)
	v_mfma_f32_32x32x16_bf16 v[18:33], v[132:135], v[136:139], v[18:33]
	v_mfma_f32_32x32x16_bf16 v[2:17], v[132:135], v[230:233], v[2:17]
	s_waitcnt lgkmcnt(2)
	v_mfma_f32_32x32x16_bf16 v[50:65], v[234:237], v[242:245], v[50:65]
	s_waitcnt lgkmcnt(1)
	v_mfma_f32_32x32x16_bf16 v[34:49], v[234:237], v[246:249], v[34:49]
	s_waitcnt lgkmcnt(0)
	v_mfma_f32_32x32x16_bf16 v[18:33], v[238:241], v[242:245], v[18:33]
	v_mfma_f32_32x32x16_bf16 v[2:17], v[238:241], v[246:249], v[2:17]
	s_waitcnt vmcnt(16)
	ds_write_b128 v208, v[140:143] offset:0
	ds_write_b128 v208, v[144:147] offset:36864
	ds_write_b128 v209, v[148:151] offset:0
	ds_write_b128 v209, v[152:155] offset:36864
	ds_write_b128 v210, v[156:159] offset:0
	ds_write_b128 v210, v[160:163] offset:36864
	ds_write_b128 v211, v[164:167] offset:0
	ds_write_b128 v211, v[168:171] offset:36864
	s_waitcnt lgkmcnt(0)
	global_load_dwordx4 v[140:143], v[120:121], off offset:768
	global_load_dwordx4 v[144:147], v[112:113], off offset:768
	global_load_dwordx4 v[148:151], v[118:119], off offset:768
	global_load_dwordx4 v[152:155], v[110:111], off offset:768
	global_load_dwordx4 v[156:159], v[116:117], off offset:768
	global_load_dwordx4 v[160:163], v[108:109], off offset:768
	global_load_dwordx4 v[164:167], v[114:115], off offset:768
	global_load_dwordx4 v[168:171], v[106:107], off offset:768
	s_barrier
; #define MFMA32(a, b, c) __builtin_amdgcn_mfma_f32_32x32x16_bf16((a), (b), (c), 0, 0, 0)
; DI void gemm_accum(f32x16 (&acc)[2][2], const bf16_t* A, int lda, const bf16_t* Bt, int ldb, int nk, unsigned char* smem) {
;     ...
; #pragma unroll 1
;     for (int kt = 0; kt < nk; ++kt) {
;         const int buf = kt & 1;
;         if (kt + 1 < nk) g_load(ra, rb, A + (kt + 1) * 64, oa, sa, Bt + (kt + 1) * 64, ob, sb);
;         __syncthreads();
;         const bf16_t* a = sA + buf * TILE_E + (wr * 64 + r) * LS + h * 8;
;         const bf16_t* b = sB + buf * TILE_E + (wc * 64 + r) * LS + h * 8;
; #pragma unroll
;         for (int s = 0; s < 4; ++s) {
;             const bf16x8 a0 = *(const bf16x8*)(a + s * 16), a1 = *(const bf16x8*)(a + 32 * LS + s * 16);
;             const bf16x8 b0 = *(const bf16x8*)(b + s * 16), b1 = *(const bf16x8*)(b + 32 * LS + s * 16);
;             acc[0][0] = MFMA32(a0, b0, acc[0][0]);
;             acc[0][1] = MFMA32(a0, b1, acc[0][1]);
;             acc[1][0] = MFMA32(a1, b0, acc[1][0]);
;             acc[1][1] = MFMA32(a1, b1, acc[1][1]);
;         }
;         if (kt + 1 < nk) g_store(ra, rb, sA + (buf ^ 1) * TILE_E, sB + (buf ^ 1) * TILE_E, tid);
;     }
	ds_read_b128 v[128:131], v126 offset:0
	ds_read_b128 v[136:139], v125 offset:36864
	ds_read_b128 v[230:233], v125 offset:41472
	ds_read_b128 v[132:135], v126 offset:4608
	ds_read_b128 v[234:237], v126 offset:32
	ds_read_b128 v[242:245], v125 offset:36896
	ds_read_b128 v[246:249], v125 offset:41504
	ds_read_b128 v[238:241], v126 offset:4640
	s_waitcnt lgkmcnt(6)
	v_mfma_f32_32x32x16_bf16 v[50:65], v[128:131], v[136:139], v[50:65]
	s_waitcnt lgkmcnt(5)
	v_mfma_f32_32x32x16_bf16 v[34:49], v[128:131], v[230:233], v[34:49]
	s_waitcnt lgkmcnt(4)
	v_mfma_f32_32x32x16_bf16 v[18:33], v[132:135], v[136:139], v[18:33]
	v_mfma_f32_32x32x16_bf16 v[2:17], v[132:135], v[230:233], v[2:17]
	ds_read_b128 v[128:131], v126 offset:64
	ds_read_b128 v[136:139], v125 offset:36928
	ds_read_b128 v[230:233], v125 offset:41536
	ds_read_b128 v[132:135], v126 offset:4672
	s_waitcnt lgkmcnt(6)
	v_mfma_f32_32x32x16_bf16 v[50:65], v[234:237], v[242:245], v[50:65]
	s_waitcnt lgkmcnt(5)
	v_mfma_f32_32x32x16_bf16 v[34:49], v[234:237], v[246:249], v[34:49]
	s_waitcnt lgkmcnt(4)
	v_mfma_f32_32x32x16_bf16 v[18:33], v[238:241], v[242:245], v[18:33]
	v_mfma_f32_32x32x16_bf16 v[2:17], v[238:241], v[246:249], v[2:17]
	ds_read_b128 v[234:237], v126 offset:96
	ds_read_b128 v[242:245], v125 offset:36960
	ds_read_b128 v[246:249], v125 offset:41568
	ds_read_b128 v[238:241], v126 offset:4704
	s_waitcnt lgkmcnt(6)
	v_mfma_f32_32x32x16_bf16 v[50:65], v[128:131], v[136:139], v[50:65]
	s_waitcnt lgkmcnt(5)
	v_mfma_f32_32x32x16_bf16 v[34:49], v[128:131], v[230:233], v[34:49]
	s_waitcnt lgkmcnt(4)
	v_mfma_f32_32x32x16_bf16 v[18:33], v[132:135], v[136:139], v[18:33]
	v_mfma_f32_32x32x16_bf16 v[2:17], v[132:135], v[230:233], v[2:17]
	s_waitcnt lgkmcnt(2)
	v_mfma_f32_32x32x16_bf16 v[50:65], v[234:237], v[242:245], v[50:65]
	s_waitcnt lgkmcnt(1)
	v_mfma_f32_32x32x16_bf16 v[34:49], v[234:237], v[246:249], v[34:49]
	s_waitcnt lgkmcnt(0)
	v_mfma_f32_32x32x16_bf16 v[18:33], v[238:241], v[242:245], v[18:33]
	v_mfma_f32_32x32x16_bf16 v[2:17], v[238:241], v[246:249], v[2:17]
	s_waitcnt vmcnt(16)
	ds_write_b128 v208, v[172:175] offset:18432
	ds_write_b128 v208, v[176:179] offset:55296
	ds_write_b128 v209, v[180:183] offset:18432
	ds_write_b128 v209, v[184:187] offset:55296
	ds_write_b128 v210, v[188:191] offset:18432
	ds_write_b128 v210, v[192:195] offset:55296
	ds_write_b128 v211, v[196:199] offset:18432
	ds_write_b128 v211, v[200:203] offset:55296
	s_waitcnt lgkmcnt(0)
	global_load_dwordx4 v[172:175], v[120:121], off offset:896
	global_load_dwordx4 v[176:179], v[112:113], off offset:896
	global_load_dwordx4 v[180:183], v[118:119], off offset:896
	global_load_dwordx4 v[184:187], v[110:111], off offset:896
	global_load_dwordx4 v[188:191], v[116:117], off offset:896
	global_load_dwordx4 v[192:195], v[108:109], off offset:896
	global_load_dwordx4 v[196:199], v[114:115], off offset:896
	global_load_dwordx4 v[200:203], v[106:107], off offset:896
	s_barrier
	ds_read_b128 v[128:131], v126 offset:18432
	ds_read_b128 v[136:139], v125 offset:55296
	ds_read_b128 v[230:233], v125 offset:59904
	ds_read_b128 v[132:135], v126 offset:23040
	ds_read_b128 v[234:237], v126 offset:18464
	ds_read_b128 v[242:245], v125 offset:55328
	ds_read_b128 v[246:249], v125 offset:59936
	ds_read_b128 v[238:241], v126 offset:23072
	s_waitcnt lgkmcnt(6)
	v_mfma_f32_32x32x16_bf16 v[50:65], v[128:131], v[136:139], v[50:65]
	s_waitcnt lgkmcnt(5)
	v_mfma_f32_32x32x16_bf16 v[34:49], v[128:131], v[230:233], v[34:49]
	s_waitcnt lgkmcnt(4)
	v_mfma_f32_32x32x16_bf16 v[18:33], v[132:135], v[136:139], v[18:33]
	v_mfma_f32_32x32x16_bf16 v[2:17], v[132:135], v[230:233], v[2:17]
	ds_read_b128 v[128:131], v126 offset:18496
	ds_read_b128 v[136:139], v125 offset:55360
	ds_read_b128 v[230:233], v125 offset:59968
	ds_read_b128 v[132:135], v126 offset:23104
	s_waitcnt lgkmcnt(6)
	v_mfma_f32_32x32x16_bf16 v[50:65], v[234:237], v[242:245], v[50:65]
	s_waitcnt lgkmcnt(5)
	v_mfma_f32_32x32x16_bf16 v[34:49], v[234:237], v[246:249], v[34:49]
	s_waitcnt lgkmcnt(4)
	v_mfma_f32_32x32x16_bf16 v[18:33], v[238:241], v[242:245], v[18:33]
	v_mfma_f32_32x32x16_bf16 v[2:17], v[238:241], v[246:249], v[2:17]
	ds_read_b128 v[234:237], v126 offset:18528
	ds_read_b128 v[242:245], v125 offset:55392
	ds_read_b128 v[246:249], v125 offset:60000
	ds_read_b128 v[238:241], v126 offset:23136
	s_waitcnt lgkmcnt(6)
	v_mfma_f32_32x32x16_bf16 v[50:65], v[128:131], v[136:139], v[50:65]
	s_waitcnt lgkmcnt(5)
	v_mfma_f32_32x32x16_bf16 v[34:49], v[128:131], v[230:233], v[34:49]
	s_waitcnt lgkmcnt(4)
	v_mfma_f32_32x32x16_bf16 v[18:33], v[132:135], v[136:139], v[18:33]
	v_mfma_f32_32x32x16_bf16 v[2:17], v[132:135], v[230:233], v[2:17]
	s_waitcnt lgkmcnt(2)
	v_mfma_f32_32x32x16_bf16 v[50:65], v[234:237], v[242:245], v[50:65]
	s_waitcnt lgkmcnt(1)
	v_mfma_f32_32x32x16_bf16 v[34:49], v[234:237], v[246:249], v[34:49]
	s_waitcnt lgkmcnt(0)
	v_mfma_f32_32x32x16_bf16 v[18:33], v[238:241], v[242:245], v[18:33]
	v_mfma_f32_32x32x16_bf16 v[2:17], v[238:241], v[246:249], v[2:17]
	s_waitcnt vmcnt(16)
	ds_write_b128 v208, v[66:69] offset:0
	ds_write_b128 v208, v[70:73] offset:36864
	ds_write_b128 v209, v[74:77] offset:0
	ds_write_b128 v209, v[78:81] offset:36864
	ds_write_b128 v210, v[82:85] offset:0
	ds_write_b128 v210, v[86:89] offset:36864
	ds_write_b128 v211, v[90:93] offset:0
	ds_write_b128 v211, v[94:97] offset:36864
	s_waitcnt lgkmcnt(0)
	global_load_dwordx4 v[66:69], v[120:121], off offset:1024
	global_load_dwordx4 v[70:73], v[112:113], off offset:1024
	global_load_dwordx4 v[74:77], v[118:119], off offset:1024
	global_load_dwordx4 v[78:81], v[110:111], off offset:1024
	global_load_dwordx4 v[82:85], v[116:117], off offset:1024
	global_load_dwordx4 v[86:89], v[108:109], off offset:1024
	global_load_dwordx4 v[90:93], v[114:115], off offset:1024
	global_load_dwordx4 v[94:97], v[106:107], off offset:1024
	s_barrier
; #define MFMA32(a, b, c) __builtin_amdgcn_mfma_f32_32x32x16_bf16((a), (b), (c), 0, 0, 0)
; DI void gemm_accum(f32x16 (&acc)[2][2], const bf16_t* A, int lda, const bf16_t* Bt, int ldb, int nk, unsigned char* smem) {
;     ...
;         const bf16_t* a = sA + buf * TILE_E + (wr * 64 + r) * LS + h * 8;
;         const bf16_t* b = sB + buf * TILE_E + (wc * 64 + r) * LS + h * 8;
; #pragma unroll
;         for (int s = 0; s < 4; ++s) {
;             const bf16x8 a0 = *(const bf16x8*)(a + s * 16), a1 = *(const bf16x8*)(a + 32 * LS + s * 16);
;             const bf16x8 b0 = *(const bf16x8*)(b + s * 16), b1 = *(const bf16x8*)(b + 32 * LS + s * 16);
;             acc[0][0] = MFMA32(a0, b0, acc[0][0]);
;             acc[0][1] = MFMA32(a0, b1, acc[0][1]);
;             acc[1][0] = MFMA32(a1, b0, acc[1][0]);
;             acc[1][1] = MFMA32(a1, b1, acc[1][1]);
;         }
	ds_read_b128 v[128:131], v126 offset:0
	ds_read_b128 v[136:139], v125 offset:36864
	ds_read_b128 v[230:233], v125 offset:41472
	ds_read_b128 v[132:135], v126 offset:4608
	ds_read_b128 v[234:237], v126 offset:32
	ds_read_b128 v[242:245], v125 offset:36896
	ds_read_b128 v[246:249], v125 offset:41504
	ds_read_b128 v[238:241], v126 offset:4640
	s_waitcnt lgkmcnt(6)
	v_mfma_f32_32x32x16_bf16 v[50:65], v[128:131], v[136:139], v[50:65]
	s_waitcnt lgkmcnt(5)
	v_mfma_f32_32x32x16_bf16 v[34:49], v[128:131], v[230:233], v[34:49]
	s_waitcnt lgkmcnt(4)
	v_mfma_f32_32x32x16_bf16 v[18:33], v[132:135], v[136:139], v[18:33]
	v_mfma_f32_32x32x16_bf16 v[2:17], v[132:135], v[230:233], v[2:17]
	ds_read_b128 v[128:131], v126 offset:64
	ds_read_b128 v[136:139], v125 offset:36928
	ds_read_b128 v[230:233], v125 offset:41536
	ds_read_b128 v[132:135], v126 offset:4672
	s_waitcnt lgkmcnt(6)
	v_mfma_f32_32x32x16_bf16 v[50:65], v[234:237], v[242:245], v[50:65]
	s_waitcnt lgkmcnt(5)
	v_mfma_f32_32x32x16_bf16 v[34:49], v[234:237], v[246:249], v[34:49]
	s_waitcnt lgkmcnt(4)
	v_mfma_f32_32x32x16_bf16 v[18:33], v[238:241], v[242:245], v[18:33]
	v_mfma_f32_32x32x16_bf16 v[2:17], v[238:241], v[246:249], v[2:17]
	ds_read_b128 v[234:237], v126 offset:96
	ds_read_b128 v[242:245], v125 offset:36960
	ds_read_b128 v[246:249], v125 offset:41568
	ds_read_b128 v[238:241], v126 offset:4704
	s_waitcnt lgkmcnt(6)
	v_mfma_f32_32x32x16_bf16 v[50:65], v[128:131], v[136:139], v[50:65]
	s_waitcnt lgkmcnt(5)
	v_mfma_f32_32x32x16_bf16 v[34:49], v[128:131], v[230:233], v[34:49]
	s_waitcnt lgkmcnt(4)
	v_mfma_f32_32x32x16_bf16 v[18:33], v[132:135], v[136:139], v[18:33]
	v_mfma_f32_32x32x16_bf16 v[2:17], v[132:135], v[230:233], v[2:17]
	s_waitcnt lgkmcnt(2)
	v_mfma_f32_32x32x16_bf16 v[50:65], v[234:237], v[242:245], v[50:65]
	s_waitcnt lgkmcnt(1)
	v_mfma_f32_32x32x16_bf16 v[34:49], v[234:237], v[246:249], v[34:49]
	s_waitcnt lgkmcnt(0)
	v_mfma_f32_32x32x16_bf16 v[18:33], v[238:241], v[242:245], v[18:33]
	v_mfma_f32_32x32x16_bf16 v[2:17], v[238:241], v[246:249], v[2:17]
	s_waitcnt vmcnt(16)
	ds_write_b128 v208, v[140:143] offset:18432
	ds_write_b128 v208, v[144:147] offset:55296
	ds_write_b128 v209, v[148:151] offset:18432
	ds_write_b128 v209, v[152:155] offset:55296
	ds_write_b128 v210, v[156:159] offset:18432
	ds_write_b128 v210, v[160:163] offset:55296
	ds_write_b128 v211, v[164:167] offset:18432
	ds_write_b128 v211, v[168:171] offset:55296
	s_waitcnt lgkmcnt(0)
	global_load_dwordx4 v[140:143], v[120:121], off offset:1152
	global_load_dwordx4 v[144:147], v[112:113], off offset:1152
	global_load_dwordx4 v[148:151], v[118:119], off offset:1152
	global_load_dwordx4 v[152:155], v[110:111], off offset:1152
	global_load_dwordx4 v[156:159], v[116:117], off offset:1152
	global_load_dwordx4 v[160:163], v[108:109], off offset:1152
	global_load_dwordx4 v[164:167], v[114:115], off offset:1152
	global_load_dwordx4 v[168:171], v[106:107], off offset:1152
	s_barrier
	ds_read_b128 v[128:131], v126 offset:18432
	ds_read_b128 v[136:139], v125 offset:55296
	ds_read_b128 v[230:233], v125 offset:59904
	ds_read_b128 v[132:135], v126 offset:23040
	ds_read_b128 v[234:237], v126 offset:18464
	ds_read_b128 v[242:245], v125 offset:55328
	ds_read_b128 v[246:249], v125 offset:59936
	ds_read_b128 v[238:241], v126 offset:23072
	s_waitcnt lgkmcnt(6)
	v_mfma_f32_32x32x16_bf16 v[50:65], v[128:131], v[136:139], v[50:65]
	s_waitcnt lgkmcnt(5)
	v_mfma_f32_32x32x16_bf16 v[34:49], v[128:131], v[230:233], v[34:49]
	s_waitcnt lgkmcnt(4)
	v_mfma_f32_32x32x16_bf16 v[18:33], v[132:135], v[136:139], v[18:33]
	v_mfma_f32_32x32x16_bf16 v[2:17], v[132:135], v[230:233], v[2:17]
	ds_read_b128 v[128:131], v126 offset:18496
	ds_read_b128 v[136:139], v125 offset:55360
	ds_read_b128 v[230:233], v125 offset:59968
	ds_read_b128 v[132:135], v126 offset:23104
	s_waitcnt lgkmcnt(6)
	v_mfma_f32_32x32x16_bf16 v[50:65], v[234:237], v[242:245], v[50:65]
	s_waitcnt lgkmcnt(5)
	v_mfma_f32_32x32x16_bf16 v[34:49], v[234:237], v[246:249], v[34:49]
	s_waitcnt lgkmcnt(4)
	v_mfma_f32_32x32x16_bf16 v[18:33], v[238:241], v[242:245], v[18:33]
	v_mfma_f32_32x32x16_bf16 v[2:17], v[238:241], v[246:249], v[2:17]
	ds_read_b128 v[234:237], v126 offset:18528
	ds_read_b128 v[242:245], v125 offset:55392
	ds_read_b128 v[246:249], v125 offset:60000
	ds_read_b128 v[238:241], v126 offset:23136
	s_waitcnt lgkmcnt(6)
	v_mfma_f32_32x32x16_bf16 v[50:65], v[128:131], v[136:139], v[50:65]
	s_waitcnt lgkmcnt(5)
	v_mfma_f32_32x32x16_bf16 v[34:49], v[128:131], v[230:233], v[34:49]
	s_waitcnt lgkmcnt(4)
	v_mfma_f32_32x32x16_bf16 v[18:33], v[132:135], v[136:139], v[18:33]
	v_mfma_f32_32x32x16_bf16 v[2:17], v[132:135], v[230:233], v[2:17]
	s_waitcnt lgkmcnt(2)
	v_mfma_f32_32x32x16_bf16 v[50:65], v[234:237], v[242:245], v[50:65]
	s_waitcnt lgkmcnt(1)
	v_mfma_f32_32x32x16_bf16 v[34:49], v[234:237], v[246:249], v[34:49]
	s_waitcnt lgkmcnt(0)
	v_mfma_f32_32x32x16_bf16 v[18:33], v[238:241], v[242:245], v[18:33]
	v_mfma_f32_32x32x16_bf16 v[2:17], v[238:241], v[246:249], v[2:17]
	s_waitcnt vmcnt(16)
	ds_write_b128 v208, v[172:175] offset:0
	ds_write_b128 v208, v[176:179] offset:36864
	ds_write_b128 v209, v[180:183] offset:0
	ds_write_b128 v209, v[184:187] offset:36864
	ds_write_b128 v210, v[188:191] offset:0
	ds_write_b128 v210, v[192:195] offset:36864
	ds_write_b128 v211, v[196:199] offset:0
	ds_write_b128 v211, v[200:203] offset:36864
	s_waitcnt lgkmcnt(0)
	global_load_dwordx4 v[172:175], v[120:121], off offset:1280
	global_load_dwordx4 v[176:179], v[112:113], off offset:1280
	global_load_dwordx4 v[180:183], v[118:119], off offset:1280
	global_load_dwordx4 v[184:187], v[110:111], off offset:1280
	global_load_dwordx4 v[188:191], v[116:117], off offset:1280
	global_load_dwordx4 v[192:195], v[108:109], off offset:1280
	global_load_dwordx4 v[196:199], v[114:115], off offset:1280
	global_load_dwordx4 v[200:203], v[106:107], off offset:1280
	s_barrier
; #define MFMA32(a, b, c) __builtin_amdgcn_mfma_f32_32x32x16_bf16((a), (b), (c), 0, 0, 0)
; DI void gemm_accum(f32x16 (&acc)[2][2], const bf16_t* A, int lda, const bf16_t* Bt, int ldb, int nk, unsigned char* smem) {
;     ...
; #pragma unroll 1
;     for (int kt = 0; kt < nk; ++kt) {
;         const int buf = kt & 1;
;         if (kt + 1 < nk) g_load(ra, rb, A + (kt + 1) * 64, oa, sa, Bt + (kt + 1) * 64, ob, sb);
;         __syncthreads();
;         const bf16_t* a = sA + buf * TILE_E + (wr * 64 + r) * LS + h * 8;
;         const bf16_t* b = sB + buf * TILE_E + (wc * 64 + r) * LS + h * 8;
; #pragma unroll
;         for (int s = 0; s < 4; ++s) {
;             const bf16x8 a0 = *(const bf16x8*)(a + s * 16), a1 = *(const bf16x8*)(a + 32 * LS + s * 16);
;             const bf16x8 b0 = *(const bf16x8*)(b + s * 16), b1 = *(const bf16x8*)(b + 32 * LS + s * 16);
;             acc[0][0] = MFMA32(a0, b0, acc[0][0]);
;             acc[0][1] = MFMA32(a0, b1, acc[0][1]);
;             acc[1][0] = MFMA32(a1, b0, acc[1][0]);
;             acc[1][1] = MFMA32(a1, b1, acc[1][1]);
;         }
;         if (kt + 1 < nk) g_store(ra, rb, sA + (buf ^ 1) * TILE_E, sB + (buf ^ 1) * TILE_E, tid);
;     }
	ds_read_b128 v[128:131], v126 offset:0
	ds_read_b128 v[136:139], v125 offset:36864
	ds_read_b128 v[230:233], v125 offset:41472
	ds_read_b128 v[132:135], v126 offset:4608
	ds_read_b128 v[234:237], v126 offset:32
	ds_read_b128 v[242:245], v125 offset:36896
	ds_read_b128 v[246:249], v125 offset:41504
	ds_read_b128 v[238:241], v126 offset:4640
	s_waitcnt lgkmcnt(6)
	v_mfma_f32_32x32x16_bf16 v[50:65], v[128:131], v[136:139], v[50:65]
	s_waitcnt lgkmcnt(5)
	v_mfma_f32_32x32x16_bf16 v[34:49], v[128:131], v[230:233], v[34:49]
	s_waitcnt lgkmcnt(4)
	v_mfma_f32_32x32x16_bf16 v[18:33], v[132:135], v[136:139], v[18:33]
	v_mfma_f32_32x32x16_bf16 v[2:17], v[132:135], v[230:233], v[2:17]
	ds_read_b128 v[128:131], v126 offset:64
	ds_read_b128 v[136:139], v125 offset:36928
	ds_read_b128 v[230:233], v125 offset:41536
	ds_read_b128 v[132:135], v126 offset:4672
	s_waitcnt lgkmcnt(6)
	v_mfma_f32_32x32x16_bf16 v[50:65], v[234:237], v[242:245], v[50:65]
	s_waitcnt lgkmcnt(5)
	v_mfma_f32_32x32x16_bf16 v[34:49], v[234:237], v[246:249], v[34:49]
	s_waitcnt lgkmcnt(4)
	v_mfma_f32_32x32x16_bf16 v[18:33], v[238:241], v[242:245], v[18:33]
	v_mfma_f32_32x32x16_bf16 v[2:17], v[238:241], v[246:249], v[2:17]
	ds_read_b128 v[234:237], v126 offset:96
	ds_read_b128 v[242:245], v125 offset:36960
	ds_read_b128 v[246:249], v125 offset:41568
	ds_read_b128 v[238:241], v126 offset:4704
	s_waitcnt lgkmcnt(6)
	v_mfma_f32_32x32x16_bf16 v[50:65], v[128:131], v[136:139], v[50:65]
	s_waitcnt lgkmcnt(5)
	v_mfma_f32_32x32x16_bf16 v[34:49], v[128:131], v[230:233], v[34:49]
	s_waitcnt lgkmcnt(4)
	v_mfma_f32_32x32x16_bf16 v[18:33], v[132:135], v[136:139], v[18:33]
	v_mfma_f32_32x32x16_bf16 v[2:17], v[132:135], v[230:233], v[2:17]
	s_waitcnt lgkmcnt(2)
	v_mfma_f32_32x32x16_bf16 v[50:65], v[234:237], v[242:245], v[50:65]
	s_waitcnt lgkmcnt(1)
	v_mfma_f32_32x32x16_bf16 v[34:49], v[234:237], v[246:249], v[34:49]
	s_waitcnt lgkmcnt(0)
	v_mfma_f32_32x32x16_bf16 v[18:33], v[238:241], v[242:245], v[18:33]
	v_mfma_f32_32x32x16_bf16 v[2:17], v[238:241], v[246:249], v[2:17]
	s_waitcnt vmcnt(16)
	ds_write_b128 v208, v[66:69] offset:18432
	ds_write_b128 v208, v[70:73] offset:55296
	ds_write_b128 v209, v[74:77] offset:18432
	ds_write_b128 v209, v[78:81] offset:55296
	ds_write_b128 v210, v[82:85] offset:18432
	ds_write_b128 v210, v[86:89] offset:55296
	ds_write_b128 v211, v[90:93] offset:18432
	ds_write_b128 v211, v[94:97] offset:55296
	s_waitcnt lgkmcnt(0)
	global_load_dwordx4 v[66:69], v[120:121], off offset:1408
	global_load_dwordx4 v[70:73], v[112:113], off offset:1408
	global_load_dwordx4 v[74:77], v[118:119], off offset:1408
	global_load_dwordx4 v[78:81], v[110:111], off offset:1408
	global_load_dwordx4 v[82:85], v[116:117], off offset:1408
	global_load_dwordx4 v[86:89], v[108:109], off offset:1408
	global_load_dwordx4 v[90:93], v[114:115], off offset:1408
	global_load_dwordx4 v[94:97], v[106:107], off offset:1408
	s_barrier
	ds_read_b128 v[128:131], v126 offset:18432
	ds_read_b128 v[136:139], v125 offset:55296
	ds_read_b128 v[230:233], v125 offset:59904
	ds_read_b128 v[132:135], v126 offset:23040
	ds_read_b128 v[234:237], v126 offset:18464
	ds_read_b128 v[242:245], v125 offset:55328
	ds_read_b128 v[246:249], v125 offset:59936
	ds_read_b128 v[238:241], v126 offset:23072
	s_waitcnt lgkmcnt(6)
	v_mfma_f32_32x32x16_bf16 v[50:65], v[128:131], v[136:139], v[50:65]
	s_waitcnt lgkmcnt(5)
	v_mfma_f32_32x32x16_bf16 v[34:49], v[128:131], v[230:233], v[34:49]
	s_waitcnt lgkmcnt(4)
	v_mfma_f32_32x32x16_bf16 v[18:33], v[132:135], v[136:139], v[18:33]
	v_mfma_f32_32x32x16_bf16 v[2:17], v[132:135], v[230:233], v[2:17]
	ds_read_b128 v[128:131], v126 offset:18496
	ds_read_b128 v[136:139], v125 offset:55360
	ds_read_b128 v[230:233], v125 offset:59968
	ds_read_b128 v[132:135], v126 offset:23104
	s_waitcnt lgkmcnt(6)
	v_mfma_f32_32x32x16_bf16 v[50:65], v[234:237], v[242:245], v[50:65]
	s_waitcnt lgkmcnt(5)
	v_mfma_f32_32x32x16_bf16 v[34:49], v[234:237], v[246:249], v[34:49]
	s_waitcnt lgkmcnt(4)
	v_mfma_f32_32x32x16_bf16 v[18:33], v[238:241], v[242:245], v[18:33]
	v_mfma_f32_32x32x16_bf16 v[2:17], v[238:241], v[246:249], v[2:17]
	ds_read_b128 v[234:237], v126 offset:18528
	ds_read_b128 v[242:245], v125 offset:55392
	ds_read_b128 v[246:249], v125 offset:60000
	ds_read_b128 v[238:241], v126 offset:23136
	s_waitcnt lgkmcnt(6)
	v_mfma_f32_32x32x16_bf16 v[50:65], v[128:131], v[136:139], v[50:65]
	s_waitcnt lgkmcnt(5)
	v_mfma_f32_32x32x16_bf16 v[34:49], v[128:131], v[230:233], v[34:49]
	s_waitcnt lgkmcnt(4)
	v_mfma_f32_32x32x16_bf16 v[18:33], v[132:135], v[136:139], v[18:33]
	v_mfma_f32_32x32x16_bf16 v[2:17], v[132:135], v[230:233], v[2:17]
	s_waitcnt lgkmcnt(2)
	v_mfma_f32_32x32x16_bf16 v[50:65], v[234:237], v[242:245], v[50:65]
	s_waitcnt lgkmcnt(1)
	v_mfma_f32_32x32x16_bf16 v[34:49], v[234:237], v[246:249], v[34:49]
	s_waitcnt lgkmcnt(0)
	v_mfma_f32_32x32x16_bf16 v[18:33], v[238:241], v[242:245], v[18:33]
	v_mfma_f32_32x32x16_bf16 v[2:17], v[238:241], v[246:249], v[2:17]
	s_waitcnt vmcnt(16)
	ds_write_b128 v208, v[140:143] offset:0
	ds_write_b128 v208, v[144:147] offset:36864
	ds_write_b128 v209, v[148:151] offset:0
	ds_write_b128 v209, v[152:155] offset:36864
	ds_write_b128 v210, v[156:159] offset:0
	ds_write_b128 v210, v[160:163] offset:36864
	ds_write_b128 v211, v[164:167] offset:0
	ds_write_b128 v211, v[168:171] offset:36864
	s_waitcnt lgkmcnt(0)
	global_load_dwordx4 v[140:143], v[120:121], off offset:1536
	global_load_dwordx4 v[144:147], v[112:113], off offset:1536
	global_load_dwordx4 v[148:151], v[118:119], off offset:1536
	global_load_dwordx4 v[152:155], v[110:111], off offset:1536
	global_load_dwordx4 v[156:159], v[116:117], off offset:1536
	global_load_dwordx4 v[160:163], v[108:109], off offset:1536
	global_load_dwordx4 v[164:167], v[114:115], off offset:1536
	global_load_dwordx4 v[168:171], v[106:107], off offset:1536
	s_barrier
; #define MFMA32(a, b, c) __builtin_amdgcn_mfma_f32_32x32x16_bf16((a), (b), (c), 0, 0, 0)
; DI void gemm_accum(f32x16 (&acc)[2][2], const bf16_t* A, int lda, const bf16_t* Bt, int ldb, int nk, unsigned char* smem) {
;     ...
; #pragma unroll 1
;     for (int kt = 0; kt < nk; ++kt) {
;         const int buf = kt & 1;
;         if (kt + 1 < nk) g_load(ra, rb, A + (kt + 1) * 64, oa, sa, Bt + (kt + 1) * 64, ob, sb);
;         __syncthreads();
;         const bf16_t* a = sA + buf * TILE_E + (wr * 64 + r) * LS + h * 8;
;         const bf16_t* b = sB + buf * TILE_E + (wc * 64 + r) * LS + h * 8;
; #pragma unroll
;         for (int s = 0; s < 4; ++s) {
;             const bf16x8 a0 = *(const bf16x8*)(a + s * 16), a1 = *(const bf16x8*)(a + 32 * LS + s * 16);
;             const bf16x8 b0 = *(const bf16x8*)(b + s * 16), b1 = *(const bf16x8*)(b + 32 * LS + s * 16);
;             acc[0][0] = MFMA32(a0, b0, acc[0][0]);
;             acc[0][1] = MFMA32(a0, b1, acc[0][1]);
;             acc[1][0] = MFMA32(a1, b0, acc[1][0]);
;             acc[1][1] = MFMA32(a1, b1, acc[1][1]);
;         }
;         if (kt + 1 < nk) g_store(ra, rb, sA + (buf ^ 1) * TILE_E, sB + (buf ^ 1) * TILE_E, tid);
;     }
	ds_read_b128 v[128:131], v126 offset:0
	ds_read_b128 v[136:139], v125 offset:36864
	ds_read_b128 v[230:233], v125 offset:41472
	ds_read_b128 v[132:135], v126 offset:4608
	ds_read_b128 v[234:237], v126 offset:32
	ds_read_b128 v[242:245], v125 offset:36896
	ds_read_b128 v[246:249], v125 offset:41504
	ds_read_b128 v[238:241], v126 offset:4640
	s_waitcnt lgkmcnt(6)
	v_mfma_f32_32x32x16_bf16 v[50:65], v[128:131], v[136:139], v[50:65]
	s_waitcnt lgkmcnt(5)
	v_mfma_f32_32x32x16_bf16 v[34:49], v[128:131], v[230:233], v[34:49]
	s_waitcnt lgkmcnt(4)
	v_mfma_f32_32x32x16_bf16 v[18:33], v[132:135], v[136:139], v[18:33]
	v_mfma_f32_32x32x16_bf16 v[2:17], v[132:135], v[230:233], v[2:17]
	ds_read_b128 v[128:131], v126 offset:64
	ds_read_b128 v[136:139], v125 offset:36928
	ds_read_b128 v[230:233], v125 offset:41536
	ds_read_b128 v[132:135], v126 offset:4672
	s_waitcnt lgkmcnt(6)
	v_mfma_f32_32x32x16_bf16 v[50:65], v[234:237], v[242:245], v[50:65]
	s_waitcnt lgkmcnt(5)
	v_mfma_f32_32x32x16_bf16 v[34:49], v[234:237], v[246:249], v[34:49]
	s_waitcnt lgkmcnt(4)
	v_mfma_f32_32x32x16_bf16 v[18:33], v[238:241], v[242:245], v[18:33]
	v_mfma_f32_32x32x16_bf16 v[2:17], v[238:241], v[246:249], v[2:17]
	ds_read_b128 v[234:237], v126 offset:96
	ds_read_b128 v[242:245], v125 offset:36960
	ds_read_b128 v[246:249], v125 offset:41568
	ds_read_b128 v[238:241], v126 offset:4704
	s_waitcnt lgkmcnt(6)
	v_mfma_f32_32x32x16_bf16 v[50:65], v[128:131], v[136:139], v[50:65]
	s_waitcnt lgkmcnt(5)
	v_mfma_f32_32x32x16_bf16 v[34:49], v[128:131], v[230:233], v[34:49]
	s_waitcnt lgkmcnt(4)
	v_mfma_f32_32x32x16_bf16 v[18:33], v[132:135], v[136:139], v[18:33]
	v_mfma_f32_32x32x16_bf16 v[2:17], v[132:135], v[230:233], v[2:17]
	s_waitcnt lgkmcnt(2)
	v_mfma_f32_32x32x16_bf16 v[50:65], v[234:237], v[242:245], v[50:65]
	s_waitcnt lgkmcnt(1)
	v_mfma_f32_32x32x16_bf16 v[34:49], v[234:237], v[246:249], v[34:49]
	s_waitcnt lgkmcnt(0)
	v_mfma_f32_32x32x16_bf16 v[18:33], v[238:241], v[242:245], v[18:33]
	v_mfma_f32_32x32x16_bf16 v[2:17], v[238:241], v[246:249], v[2:17]
	s_waitcnt vmcnt(16)
	ds_write_b128 v208, v[172:175] offset:18432
	ds_write_b128 v208, v[176:179] offset:55296
	ds_write_b128 v209, v[180:183] offset:18432
	ds_write_b128 v209, v[184:187] offset:55296
	ds_write_b128 v210, v[188:191] offset:18432
	ds_write_b128 v210, v[192:195] offset:55296
	ds_write_b128 v211, v[196:199] offset:18432
	ds_write_b128 v211, v[200:203] offset:55296
	s_waitcnt lgkmcnt(0)
	global_load_dwordx4 v[172:175], v[120:121], off offset:1664
	global_load_dwordx4 v[176:179], v[112:113], off offset:1664
	global_load_dwordx4 v[180:183], v[118:119], off offset:1664
	global_load_dwordx4 v[184:187], v[110:111], off offset:1664
	global_load_dwordx4 v[188:191], v[116:117], off offset:1664
	global_load_dwordx4 v[192:195], v[108:109], off offset:1664
	global_load_dwordx4 v[196:199], v[114:115], off offset:1664
	global_load_dwordx4 v[200:203], v[106:107], off offset:1664
	s_barrier
	ds_read_b128 v[128:131], v126 offset:18432
	ds_read_b128 v[136:139], v125 offset:55296
	ds_read_b128 v[230:233], v125 offset:59904
	ds_read_b128 v[132:135], v126 offset:23040
	ds_read_b128 v[234:237], v126 offset:18464
	ds_read_b128 v[242:245], v125 offset:55328
	ds_read_b128 v[246:249], v125 offset:59936
	ds_read_b128 v[238:241], v126 offset:23072
	s_waitcnt lgkmcnt(6)
	v_mfma_f32_32x32x16_bf16 v[50:65], v[128:131], v[136:139], v[50:65]
	s_waitcnt lgkmcnt(5)
	v_mfma_f32_32x32x16_bf16 v[34:49], v[128:131], v[230:233], v[34:49]
	s_waitcnt lgkmcnt(4)
	v_mfma_f32_32x32x16_bf16 v[18:33], v[132:135], v[136:139], v[18:33]
	v_mfma_f32_32x32x16_bf16 v[2:17], v[132:135], v[230:233], v[2:17]
	ds_read_b128 v[128:131], v126 offset:18496
	ds_read_b128 v[136:139], v125 offset:55360
	ds_read_b128 v[230:233], v125 offset:59968
	ds_read_b128 v[132:135], v126 offset:23104
	s_waitcnt lgkmcnt(6)
	v_mfma_f32_32x32x16_bf16 v[50:65], v[234:237], v[242:245], v[50:65]
	s_waitcnt lgkmcnt(5)
	v_mfma_f32_32x32x16_bf16 v[34:49], v[234:237], v[246:249], v[34:49]
	s_waitcnt lgkmcnt(4)
	v_mfma_f32_32x32x16_bf16 v[18:33], v[238:241], v[242:245], v[18:33]
	v_mfma_f32_32x32x16_bf16 v[2:17], v[238:241], v[246:249], v[2:17]
	ds_read_b128 v[234:237], v126 offset:18528
	ds_read_b128 v[242:245], v125 offset:55392
	ds_read_b128 v[246:249], v125 offset:60000
	ds_read_b128 v[238:241], v126 offset:23136
	s_waitcnt lgkmcnt(6)
	v_mfma_f32_32x32x16_bf16 v[50:65], v[128:131], v[136:139], v[50:65]
	s_waitcnt lgkmcnt(5)
	v_mfma_f32_32x32x16_bf16 v[34:49], v[128:131], v[230:233], v[34:49]
	s_waitcnt lgkmcnt(4)
	v_mfma_f32_32x32x16_bf16 v[18:33], v[132:135], v[136:139], v[18:33]
	v_mfma_f32_32x32x16_bf16 v[2:17], v[132:135], v[230:233], v[2:17]
	s_waitcnt lgkmcnt(2)
	v_mfma_f32_32x32x16_bf16 v[50:65], v[234:237], v[242:245], v[50:65]
	s_waitcnt lgkmcnt(1)
	v_mfma_f32_32x32x16_bf16 v[34:49], v[234:237], v[246:249], v[34:49]
	s_waitcnt lgkmcnt(0)
	v_mfma_f32_32x32x16_bf16 v[18:33], v[238:241], v[242:245], v[18:33]
	v_mfma_f32_32x32x16_bf16 v[2:17], v[238:241], v[246:249], v[2:17]
	s_waitcnt vmcnt(16)
	ds_write_b128 v208, v[66:69] offset:0
	ds_write_b128 v208, v[70:73] offset:36864
	ds_write_b128 v209, v[74:77] offset:0
	ds_write_b128 v209, v[78:81] offset:36864
	ds_write_b128 v210, v[82:85] offset:0
	ds_write_b128 v210, v[86:89] offset:36864
	ds_write_b128 v211, v[90:93] offset:0
	ds_write_b128 v211, v[94:97] offset:36864
	s_waitcnt lgkmcnt(0)
	global_load_dwordx4 v[66:69], v[120:121], off offset:1792
	global_load_dwordx4 v[70:73], v[112:113], off offset:1792
	global_load_dwordx4 v[74:77], v[118:119], off offset:1792
	global_load_dwordx4 v[78:81], v[110:111], off offset:1792
	global_load_dwordx4 v[82:85], v[116:117], off offset:1792
	global_load_dwordx4 v[86:89], v[108:109], off offset:1792
	global_load_dwordx4 v[90:93], v[114:115], off offset:1792
	global_load_dwordx4 v[94:97], v[106:107], off offset:1792
	s_barrier
; #define MFMA32(a, b, c) __builtin_amdgcn_mfma_f32_32x32x16_bf16((a), (b), (c), 0, 0, 0)
; DI void gemm_accum(f32x16 (&acc)[2][2], const bf16_t* A, int lda, const bf16_t* Bt, int ldb, int nk, unsigned char* smem) {
;     ...
; #pragma unroll 1
;     for (int kt = 0; kt < nk; ++kt) {
;         const int buf = kt & 1;
;         if (kt + 1 < nk) g_load(ra, rb, A + (kt + 1) * 64, oa, sa, Bt + (kt + 1) * 64, ob, sb);
;         __syncthreads();
;         const bf16_t* a = sA + buf * TILE_E + (wr * 64 + r) * LS + h * 8;
;         const bf16_t* b = sB + buf * TILE_E + (wc * 64 + r) * LS + h * 8;
; #pragma unroll
;         for (int s = 0; s < 4; ++s) {
;             const bf16x8 a0 = *(const bf16x8*)(a + s * 16), a1 = *(const bf16x8*)(a + 32 * LS + s * 16);
;             const bf16x8 b0 = *(const bf16x8*)(b + s * 16), b1 = *(const bf16x8*)(b + 32 * LS + s * 16);
;             acc[0][0] = MFMA32(a0, b0, acc[0][0]);
;             acc[0][1] = MFMA32(a0, b1, acc[0][1]);
;             acc[1][0] = MFMA32(a1, b0, acc[1][0]);
;             acc[1][1] = MFMA32(a1, b1, acc[1][1]);
;         }
;         if (kt + 1 < nk) g_store(ra, rb, sA + (buf ^ 1) * TILE_E, sB + (buf ^ 1) * TILE_E, tid);
;     }
	ds_read_b128 v[128:131], v126 offset:0
	ds_read_b128 v[136:139], v125 offset:36864
	ds_read_b128 v[230:233], v125 offset:41472
	ds_read_b128 v[132:135], v126 offset:4608
	ds_read_b128 v[234:237], v126 offset:32
	ds_read_b128 v[242:245], v125 offset:36896
	ds_read_b128 v[246:249], v125 offset:41504
	ds_read_b128 v[238:241], v126 offset:4640
	s_waitcnt lgkmcnt(6)
	v_mfma_f32_32x32x16_bf16 v[50:65], v[128:131], v[136:139], v[50:65]
	s_waitcnt lgkmcnt(5)
	v_mfma_f32_32x32x16_bf16 v[34:49], v[128:131], v[230:233], v[34:49]
	s_waitcnt lgkmcnt(4)
	v_mfma_f32_32x32x16_bf16 v[18:33], v[132:135], v[136:139], v[18:33]
	v_mfma_f32_32x32x16_bf16 v[2:17], v[132:135], v[230:233], v[2:17]
	ds_read_b128 v[128:131], v126 offset:64
	ds_read_b128 v[136:139], v125 offset:36928
	ds_read_b128 v[230:233], v125 offset:41536
	ds_read_b128 v[132:135], v126 offset:4672
	s_waitcnt lgkmcnt(6)
	v_mfma_f32_32x32x16_bf16 v[50:65], v[234:237], v[242:245], v[50:65]
	s_waitcnt lgkmcnt(5)
	v_mfma_f32_32x32x16_bf16 v[34:49], v[234:237], v[246:249], v[34:49]
	s_waitcnt lgkmcnt(4)
	v_mfma_f32_32x32x16_bf16 v[18:33], v[238:241], v[242:245], v[18:33]
	v_mfma_f32_32x32x16_bf16 v[2:17], v[238:241], v[246:249], v[2:17]
	ds_read_b128 v[234:237], v126 offset:96
	ds_read_b128 v[242:245], v125 offset:36960
	ds_read_b128 v[246:249], v125 offset:41568
	ds_read_b128 v[238:241], v126 offset:4704
	s_waitcnt lgkmcnt(6)
	v_mfma_f32_32x32x16_bf16 v[50:65], v[128:131], v[136:139], v[50:65]
	s_waitcnt lgkmcnt(5)
	v_mfma_f32_32x32x16_bf16 v[34:49], v[128:131], v[230:233], v[34:49]
	s_waitcnt lgkmcnt(4)
	v_mfma_f32_32x32x16_bf16 v[18:33], v[132:135], v[136:139], v[18:33]
	v_mfma_f32_32x32x16_bf16 v[2:17], v[132:135], v[230:233], v[2:17]
	s_waitcnt lgkmcnt(2)
	v_mfma_f32_32x32x16_bf16 v[50:65], v[234:237], v[242:245], v[50:65]
	s_waitcnt lgkmcnt(1)
	v_mfma_f32_32x32x16_bf16 v[34:49], v[234:237], v[246:249], v[34:49]
	s_waitcnt lgkmcnt(0)
	v_mfma_f32_32x32x16_bf16 v[18:33], v[238:241], v[242:245], v[18:33]
	v_mfma_f32_32x32x16_bf16 v[2:17], v[238:241], v[246:249], v[2:17]
	s_waitcnt vmcnt(16)
	ds_write_b128 v208, v[140:143] offset:18432
	ds_write_b128 v208, v[144:147] offset:55296
	ds_write_b128 v209, v[148:151] offset:18432
	ds_write_b128 v209, v[152:155] offset:55296
	ds_write_b128 v210, v[156:159] offset:18432
	ds_write_b128 v210, v[160:163] offset:55296
	ds_write_b128 v211, v[164:167] offset:18432
	ds_write_b128 v211, v[168:171] offset:55296
	s_waitcnt lgkmcnt(0)
	s_barrier
	ds_read_b128 v[128:131], v126 offset:18432
	ds_read_b128 v[136:139], v125 offset:55296
	ds_read_b128 v[230:233], v125 offset:59904
	ds_read_b128 v[132:135], v126 offset:23040
	ds_read_b128 v[234:237], v126 offset:18464
	ds_read_b128 v[242:245], v125 offset:55328
	ds_read_b128 v[246:249], v125 offset:59936
	ds_read_b128 v[238:241], v126 offset:23072
	s_waitcnt lgkmcnt(6)
	v_mfma_f32_32x32x16_bf16 v[50:65], v[128:131], v[136:139], v[50:65]
	s_waitcnt lgkmcnt(5)
	v_mfma_f32_32x32x16_bf16 v[34:49], v[128:131], v[230:233], v[34:49]
	s_waitcnt lgkmcnt(4)
	v_mfma_f32_32x32x16_bf16 v[18:33], v[132:135], v[136:139], v[18:33]
	v_mfma_f32_32x32x16_bf16 v[2:17], v[132:135], v[230:233], v[2:17]
	ds_read_b128 v[128:131], v126 offset:18496
	ds_read_b128 v[136:139], v125 offset:55360
	ds_read_b128 v[230:233], v125 offset:59968
	ds_read_b128 v[132:135], v126 offset:23104
	s_waitcnt lgkmcnt(6)
	v_mfma_f32_32x32x16_bf16 v[50:65], v[234:237], v[242:245], v[50:65]
	s_waitcnt lgkmcnt(5)
	v_mfma_f32_32x32x16_bf16 v[34:49], v[234:237], v[246:249], v[34:49]
	s_waitcnt lgkmcnt(4)
	v_mfma_f32_32x32x16_bf16 v[18:33], v[238:241], v[242:245], v[18:33]
	v_mfma_f32_32x32x16_bf16 v[2:17], v[238:241], v[246:249], v[2:17]
	ds_read_b128 v[234:237], v126 offset:18528
	ds_read_b128 v[242:245], v125 offset:55392
	ds_read_b128 v[246:249], v125 offset:60000
	ds_read_b128 v[238:241], v126 offset:23136
	s_waitcnt lgkmcnt(6)
	v_mfma_f32_32x32x16_bf16 v[50:65], v[128:131], v[136:139], v[50:65]
	s_waitcnt lgkmcnt(5)
	v_mfma_f32_32x32x16_bf16 v[34:49], v[128:131], v[230:233], v[34:49]
	s_waitcnt lgkmcnt(4)
	v_mfma_f32_32x32x16_bf16 v[18:33], v[132:135], v[136:139], v[18:33]
	v_mfma_f32_32x32x16_bf16 v[2:17], v[132:135], v[230:233], v[2:17]
	s_waitcnt lgkmcnt(2)
	v_mfma_f32_32x32x16_bf16 v[50:65], v[234:237], v[242:245], v[50:65]
	s_waitcnt lgkmcnt(1)
	v_mfma_f32_32x32x16_bf16 v[34:49], v[234:237], v[246:249], v[34:49]
	s_waitcnt lgkmcnt(0)
	v_mfma_f32_32x32x16_bf16 v[18:33], v[238:241], v[242:245], v[18:33]
	v_mfma_f32_32x32x16_bf16 v[2:17], v[238:241], v[246:249], v[2:17]
	s_waitcnt vmcnt(8)
	ds_write_b128 v208, v[172:175] offset:0
	ds_write_b128 v208, v[176:179] offset:36864
	ds_write_b128 v209, v[180:183] offset:0
	ds_write_b128 v209, v[184:187] offset:36864
	ds_write_b128 v210, v[188:191] offset:0
	ds_write_b128 v210, v[192:195] offset:36864
	ds_write_b128 v211, v[196:199] offset:0
	ds_write_b128 v211, v[200:203] offset:36864
	s_waitcnt lgkmcnt(0)
	s_barrier
; #define MFMA32(a, b, c) __builtin_amdgcn_mfma_f32_32x32x16_bf16((a), (b), (c), 0, 0, 0)
; DI void gemm_accum(f32x16 (&acc)[2][2], const bf16_t* A, int lda, const bf16_t* Bt, int ldb, int nk, unsigned char* smem) {
;     ...
; #pragma unroll 1
;     for (int kt = 0; kt < nk; ++kt) {
;         const int buf = kt & 1;
;         if (kt + 1 < nk) g_load(ra, rb, A + (kt + 1) * 64, oa, sa, Bt + (kt + 1) * 64, ob, sb);
;         __syncthreads();
;         const bf16_t* a = sA + buf * TILE_E + (wr * 64 + r) * LS + h * 8;
;         const bf16_t* b = sB + buf * TILE_E + (wc * 64 + r) * LS + h * 8;
; #pragma unroll
;         for (int s = 0; s < 4; ++s) {
;             const bf16x8 a0 = *(const bf16x8*)(a + s * 16), a1 = *(const bf16x8*)(a + 32 * LS + s * 16);
;             const bf16x8 b0 = *(const bf16x8*)(b + s * 16), b1 = *(const bf16x8*)(b + 32 * LS + s * 16);
;             acc[0][0] = MFMA32(a0, b0, acc[0][0]);
;             acc[0][1] = MFMA32(a0, b1, acc[0][1]);
;             acc[1][0] = MFMA32(a1, b0, acc[1][0]);
;             acc[1][1] = MFMA32(a1, b1, acc[1][1]);
;         }
;         if (kt + 1 < nk) g_store(ra, rb, sA + (buf ^ 1) * TILE_E, sB + (buf ^ 1) * TILE_E, tid);
;     }
	ds_read_b128 v[128:131], v126 offset:0
	ds_read_b128 v[136:139], v125 offset:36864
	ds_read_b128 v[230:233], v125 offset:41472
	ds_read_b128 v[132:135], v126 offset:4608
	ds_read_b128 v[234:237], v126 offset:32
	ds_read_b128 v[242:245], v125 offset:36896
	ds_read_b128 v[246:249], v125 offset:41504
	ds_read_b128 v[238:241], v126 offset:4640
	s_waitcnt lgkmcnt(6)
	v_mfma_f32_32x32x16_bf16 v[50:65], v[128:131], v[136:139], v[50:65]
	s_waitcnt lgkmcnt(5)
	v_mfma_f32_32x32x16_bf16 v[34:49], v[128:131], v[230:233], v[34:49]
	s_waitcnt lgkmcnt(4)
	v_mfma_f32_32x32x16_bf16 v[18:33], v[132:135], v[136:139], v[18:33]
	v_mfma_f32_32x32x16_bf16 v[2:17], v[132:135], v[230:233], v[2:17]
	ds_read_b128 v[128:131], v126 offset:64
	ds_read_b128 v[136:139], v125 offset:36928
	ds_read_b128 v[230:233], v125 offset:41536
	ds_read_b128 v[132:135], v126 offset:4672
	s_waitcnt lgkmcnt(6)
	v_mfma_f32_32x32x16_bf16 v[50:65], v[234:237], v[242:245], v[50:65]
	s_waitcnt lgkmcnt(5)
	v_mfma_f32_32x32x16_bf16 v[34:49], v[234:237], v[246:249], v[34:49]
	s_waitcnt lgkmcnt(4)
	v_mfma_f32_32x32x16_bf16 v[18:33], v[238:241], v[242:245], v[18:33]
	v_mfma_f32_32x32x16_bf16 v[2:17], v[238:241], v[246:249], v[2:17]
	ds_read_b128 v[234:237], v126 offset:96
	ds_read_b128 v[242:245], v125 offset:36960
	ds_read_b128 v[246:249], v125 offset:41568
	ds_read_b128 v[238:241], v126 offset:4704
	s_waitcnt lgkmcnt(6)
	v_mfma_f32_32x32x16_bf16 v[50:65], v[128:131], v[136:139], v[50:65]
	s_waitcnt lgkmcnt(5)
	v_mfma_f32_32x32x16_bf16 v[34:49], v[128:131], v[230:233], v[34:49]
	s_waitcnt lgkmcnt(4)
	v_mfma_f32_32x32x16_bf16 v[18:33], v[132:135], v[136:139], v[18:33]
	v_mfma_f32_32x32x16_bf16 v[2:17], v[132:135], v[230:233], v[2:17]
	s_waitcnt lgkmcnt(2)
	v_mfma_f32_32x32x16_bf16 v[50:65], v[234:237], v[242:245], v[50:65]
	s_waitcnt lgkmcnt(1)
	v_mfma_f32_32x32x16_bf16 v[34:49], v[234:237], v[246:249], v[34:49]
	s_waitcnt lgkmcnt(0)
	v_mfma_f32_32x32x16_bf16 v[18:33], v[238:241], v[242:245], v[18:33]
	v_mfma_f32_32x32x16_bf16 v[2:17], v[238:241], v[246:249], v[2:17]
	s_waitcnt vmcnt(0)
	ds_write_b128 v208, v[66:69] offset:18432
	ds_write_b128 v208, v[70:73] offset:55296
	ds_write_b128 v209, v[74:77] offset:18432
	ds_write_b128 v209, v[78:81] offset:55296
	ds_write_b128 v210, v[82:85] offset:18432
	ds_write_b128 v210, v[86:89] offset:55296
	ds_write_b128 v211, v[90:93] offset:18432
	ds_write_b128 v211, v[94:97] offset:55296
	s_waitcnt lgkmcnt(0)
	s_barrier
	ds_read_b128 v[128:131], v126 offset:18432
	ds_read_b128 v[136:139], v125 offset:55296
	ds_read_b128 v[230:233], v125 offset:59904
	ds_read_b128 v[132:135], v126 offset:23040
	ds_read_b128 v[234:237], v126 offset:18464
	ds_read_b128 v[242:245], v125 offset:55328
	ds_read_b128 v[246:249], v125 offset:59936
	ds_read_b128 v[238:241], v126 offset:23072
	s_waitcnt lgkmcnt(6)
	v_mfma_f32_32x32x16_bf16 v[50:65], v[128:131], v[136:139], v[50:65]
	s_waitcnt lgkmcnt(5)
	v_mfma_f32_32x32x16_bf16 v[34:49], v[128:131], v[230:233], v[34:49]
	s_waitcnt lgkmcnt(4)
	v_mfma_f32_32x32x16_bf16 v[18:33], v[132:135], v[136:139], v[18:33]
	v_mfma_f32_32x32x16_bf16 v[2:17], v[132:135], v[230:233], v[2:17]
	ds_read_b128 v[128:131], v126 offset:18496
	ds_read_b128 v[136:139], v125 offset:55360
	ds_read_b128 v[230:233], v125 offset:59968
	ds_read_b128 v[132:135], v126 offset:23104
	s_waitcnt lgkmcnt(6)
	v_mfma_f32_32x32x16_bf16 v[50:65], v[234:237], v[242:245], v[50:65]
	s_waitcnt lgkmcnt(5)
	v_mfma_f32_32x32x16_bf16 v[34:49], v[234:237], v[246:249], v[34:49]
	s_waitcnt lgkmcnt(4)
	v_mfma_f32_32x32x16_bf16 v[18:33], v[238:241], v[242:245], v[18:33]
	v_mfma_f32_32x32x16_bf16 v[2:17], v[238:241], v[246:249], v[2:17]
	ds_read_b128 v[234:237], v126 offset:18528
	ds_read_b128 v[242:245], v125 offset:55392
	ds_read_b128 v[246:249], v125 offset:60000
	ds_read_b128 v[238:241], v126 offset:23136
	s_waitcnt lgkmcnt(6)
	v_mfma_f32_32x32x16_bf16 v[50:65], v[128:131], v[136:139], v[50:65]
	s_waitcnt lgkmcnt(5)
	v_mfma_f32_32x32x16_bf16 v[34:49], v[128:131], v[230:233], v[34:49]
	s_waitcnt lgkmcnt(4)
	v_mfma_f32_32x32x16_bf16 v[18:33], v[132:135], v[136:139], v[18:33]
	v_mfma_f32_32x32x16_bf16 v[2:17], v[132:135], v[230:233], v[2:17]
	s_waitcnt lgkmcnt(2)
	v_mfma_f32_32x32x16_bf16 v[50:65], v[234:237], v[242:245], v[50:65]
	s_waitcnt lgkmcnt(1)
	v_mfma_f32_32x32x16_bf16 v[34:49], v[234:237], v[246:249], v[34:49]
	s_waitcnt lgkmcnt(0)
	v_mfma_f32_32x32x16_bf16 v[18:33], v[238:241], v[242:245], v[18:33]
	v_mfma_f32_32x32x16_bf16 v[2:17], v[238:241], v[246:249], v[2:17]
	s_nop 7
; DI unsigned pk2(float a, float b) { f32x2 v = {a, b}; return __builtin_bit_cast(unsigned, __builtin_convertvector(v, bf2_t)); }
; template <typename T> DI T* opaque(T* p) { asm volatile("" : "+v"(p) : : "memory"); return p; }
; DI void st_tr(const f32x16 (&acc)[2][2], bf16_t* base, int ld, float scale, int r, int h) {
;     bf16_t* pb = base + (size_t)r * ld + 4 * h;
; #pragma unroll
;     for (int ni = 0; ni < 2; ++ni) {
;         bf16_t* q = opaque(pb + (size_t)(32 * ni) * ld);
; #pragma unroll
;         for (int mi = 0; mi < 2; ++mi)
; #pragma unroll
;             for (int qd = 0; qd < 4; ++qd) {
;                 u32x2 v;
;                 v.x = pk2(acc[mi][ni][4 * qd] * scale, acc[mi][ni][4 * qd + 1] * scale);
;                 v.y = pk2(acc[mi][ni][4 * qd + 2] * scale, acc[mi][ni][4 * qd + 3] * scale);
;                 *(u32x2*)(q + 32 * mi + 8 * qd) = v;
;             }
;     }
; }
; DI void phase1(const Params& p, int l, unsigned char* smem) {
;     ...
;             const int row0 = m0 + 64 * wr4, b = row0 >> 8, j0 = row0 & 255, gc = n0 + 64 * wc4;
;             if (gc < 256) st_rm(acc, (bf16_t*)(ws + O_MEMK) + ((size_t)(b * 4 + (gc >> 6)) * 256 + j0) * 64, 64, 1.f, r4, h4);
;             else st_tr(acc, (bf16_t*)(ws + O_MEMVT) + (size_t)(b * 4 + ((gc - 256) >> 6)) * 64 * 256 + j0, 256, 1.f, r4, h4);
.LBB0_521:
	v_add_u32_e32 v0, s24, v122
	s_waitcnt vmcnt(0)
	v_and_b32_e32 v66, 0xc0, v0
	v_ashrrev_i32_e32 v0, 6, v0
	v_or_b32_e32 v67, s23, v123
	s_cmpk_gt_u32 s23, 0xff
	v_and_b32_e32 v68, -4, v0
	s_mov_b64 s[8:9], -1
	s_cbranch_scc0 .LBB0_523
	v_add_u32_e32 v0, 0xffffff00, v67
	v_lshrrev_b32_e32 v0, 6, v0
	v_add_u32_e32 v70, v68, v0
	v_ashrrev_i32_e32 v71, 31, v70
	v_lshlrev_b64 v[70:71], 15, v[70:71]
	v_lshl_add_u64 v[70:71], s[4:5], 0, v[70:71]
	v_lshlrev_b32_e32 v0, 1, v66
	v_lshl_add_u64 v[70:71], v[70:71], 0, v[0:1]
	v_mov_b32_e32 v99, v1
	v_lshl_add_u64 v[70:71], v[70:71], 0, v[98:99]
	v_mov_b32_e32 v101, v1
	v_lshl_add_u64 v[70:71], v[70:71], 0, v[100:101]
	v_mov_b64_e32 v[72:73], v[70:71]
	v_cvt_pk_bf16_f32 v74, v50, v51
	v_cvt_pk_bf16_f32 v75, v52, v53
	global_store_dwordx2 v[72:73], v[74:75], off
	v_cvt_pk_bf16_f32 v74, v54, v55
	v_cvt_pk_bf16_f32 v75, v56, v57
	global_store_dwordx2 v[72:73], v[74:75], off offset:16
	v_cvt_pk_bf16_f32 v74, v58, v59
	v_cvt_pk_bf16_f32 v75, v60, v61
	global_store_dwordx2 v[72:73], v[74:75], off offset:32
	v_cvt_pk_bf16_f32 v74, v62, v63
	v_cvt_pk_bf16_f32 v75, v64, v65
	global_store_dwordx2 v[72:73], v[74:75], off offset:48
	v_cvt_pk_bf16_f32 v74, v18, v19
	v_cvt_pk_bf16_f32 v75, v20, v21
	global_store_dwordx2 v[72:73], v[74:75], off offset:64
	v_cvt_pk_bf16_f32 v74, v22, v23
	v_cvt_pk_bf16_f32 v75, v24, v25
	global_store_dwordx2 v[72:73], v[74:75], off offset:80
	v_cvt_pk_bf16_f32 v74, v26, v27
	v_cvt_pk_bf16_f32 v75, v28, v29
	global_store_dwordx2 v[72:73], v[74:75], off offset:96
	v_cvt_pk_bf16_f32 v74, v30, v31
	v_cvt_pk_bf16_f32 v75, v32, v33
	s_mov_b64 s[8:9], 0x4000
	global_store_dwordx2 v[72:73], v[74:75], off offset:112
	v_lshl_add_u64 v[70:71], v[70:71], 0, s[8:9]
	v_cvt_pk_bf16_f32 v72, v34, v35
	v_cvt_pk_bf16_f32 v73, v36, v37
	global_store_dwordx2 v[70:71], v[72:73], off
	v_cvt_pk_bf16_f32 v72, v38, v39
	v_cvt_pk_bf16_f32 v73, v40, v41
	global_store_dwordx2 v[70:71], v[72:73], off offset:16
	v_cvt_pk_bf16_f32 v72, v42, v43
	v_cvt_pk_bf16_f32 v73, v44, v45
	global_store_dwordx2 v[70:71], v[72:73], off offset:32
	v_cvt_pk_bf16_f32 v72, v46, v47
	v_cvt_pk_bf16_f32 v73, v48, v49
	global_store_dwordx2 v[70:71], v[72:73], off offset:48
	v_cvt_pk_bf16_f32 v72, v2, v3
	v_cvt_pk_bf16_f32 v73, v4, v5
	global_store_dwordx2 v[70:71], v[72:73], off offset:64
	v_cvt_pk_bf16_f32 v72, v6, v7
	v_cvt_pk_bf16_f32 v73, v8, v9
	global_store_dwordx2 v[70:71], v[72:73], off offset:80
	v_cvt_pk_bf16_f32 v72, v10, v11
	v_cvt_pk_bf16_f32 v73, v12, v13
	global_store_dwordx2 v[70:71], v[72:73], off offset:96
	v_cvt_pk_bf16_f32 v72, v14, v15
	v_cvt_pk_bf16_f32 v73, v16, v17
	global_store_dwordx2 v[70:71], v[72:73], off offset:112
	s_mov_b64 s[8:9], 0
; DI bf16_t tobf(float a) { return (bf16_t)(pk2(a, 0.f) & 0xffffu); }
; template <typename T> DI T* opaque(T* p) { asm volatile("" : "+v"(p) : : "memory"); return p; }
; DI void st_rm(const f32x16 (&acc)[2][2], bf16_t* base, int ld, float scale, int r, int h) {
;     bf16_t* pb = base + (size_t)(4 * h) * ld + r;
; #pragma unroll
;     for (int mi = 0; mi < 2; ++mi)
; #pragma unroll
;         for (int qd = 0; qd < 4; ++qd) {
;             bf16_t* q = opaque(pb + (size_t)(32 * mi + 8 * qd) * ld);
; #pragma unroll
;             for (int e = 0; e < 4; ++e)
; #pragma unroll
;                 for (int ni = 0; ni < 2; ++ni) q[(size_t)e * ld + 32 * ni] = tobf(acc[mi][ni][4 * qd + e] * scale);
;         }
; }
; DI void phase1(const Params& p, int l, unsigned char* smem) {
;     ...
;             if (gc < 256) st_rm(acc, (bf16_t*)(ws + O_MEMK) + ((size_t)(b * 4 + (gc >> 6)) * 256 + j0) * 64, 64, 1.f, r4, h4);
.LBB0_523:
	s_andn2_b64 vcc, exec, s[8:9]
	s_cbranch_vccnz .LBB0_514
	v_lshrrev_b32_e32 v0, 6, v67
	v_or_b32_e32 v68, v68, v0
	v_ashrrev_i32_e32 v69, 31, v68
	v_lshlrev_b64 v[68:69], 15, v[68:69]
	v_lshl_add_u64 v[68:69], s[6:7], 0, v[68:69]
	v_lshlrev_b32_e32 v0, 7, v66
	v_lshl_add_u64 v[66:67], v[68:69], 0, v[0:1]
	v_mov_b32_e32 v103, v1
	v_lshl_add_u64 v[66:67], v[66:67], 0, v[102:103]
	v_mov_b32_e32 v105, v1
	v_lshl_add_u64 v[66:67], v[66:67], 0, v[104:105]
	v_mov_b64_e32 v[68:69], v[66:67]
	v_cvt_pk_bf16_f32 v0, v50, s0
	global_store_short v[68:69], v0, off
	v_cvt_pk_bf16_f32 v0, v34, s0
	global_store_short v[68:69], v0, off offset:64
	v_cvt_pk_bf16_f32 v0, v51, s0
	global_store_short v[68:69], v0, off offset:128
	v_cvt_pk_bf16_f32 v0, v35, s0
	global_store_short v[68:69], v0, off offset:192
	v_cvt_pk_bf16_f32 v0, v52, s0
	global_store_short v[68:69], v0, off offset:256
	v_cvt_pk_bf16_f32 v0, v36, s0
	global_store_short v[68:69], v0, off offset:320
	v_cvt_pk_bf16_f32 v0, v53, s0
	global_store_short v[68:69], v0, off offset:384
	v_cvt_pk_bf16_f32 v0, v37, s0
	s_mov_b64 s[8:9], 0x400
	global_store_short v[68:69], v0, off offset:448
	v_lshl_add_u64 v[34:35], v[66:67], 0, s[8:9]
	v_cvt_pk_bf16_f32 v0, v54, s0
	global_store_short v[34:35], v0, off
	v_cvt_pk_bf16_f32 v0, v38, s0
	global_store_short v[34:35], v0, off offset:64
	v_cvt_pk_bf16_f32 v0, v55, s0
	global_store_short v[34:35], v0, off offset:128
	v_cvt_pk_bf16_f32 v0, v39, s0
	global_store_short v[34:35], v0, off offset:192
	v_cvt_pk_bf16_f32 v0, v56, s0
	global_store_short v[34:35], v0, off offset:256
	v_cvt_pk_bf16_f32 v0, v40, s0
	global_store_short v[34:35], v0, off offset:320
	v_cvt_pk_bf16_f32 v0, v57, s0
	global_store_short v[34:35], v0, off offset:384
	v_cvt_pk_bf16_f32 v0, v41, s0
	s_mov_b64 s[8:9], 0x800
	global_store_short v[34:35], v0, off offset:448
	v_lshl_add_u64 v[34:35], v[66:67], 0, s[8:9]
	v_cvt_pk_bf16_f32 v0, v58, s0
	global_store_short v[34:35], v0, off
	v_cvt_pk_bf16_f32 v0, v42, s0
	global_store_short v[34:35], v0, off offset:64
	v_cvt_pk_bf16_f32 v0, v59, s0
	global_store_short v[34:35], v0, off offset:128
	v_cvt_pk_bf16_f32 v0, v43, s0
	global_store_short v[34:35], v0, off offset:192
	v_cvt_pk_bf16_f32 v0, v60, s0
	global_store_short v[34:35], v0, off offset:256
	v_cvt_pk_bf16_f32 v0, v44, s0
	global_store_short v[34:35], v0, off offset:320
	v_cvt_pk_bf16_f32 v0, v61, s0
	global_store_short v[34:35], v0, off offset:384
	v_cvt_pk_bf16_f32 v0, v45, s0
	s_mov_b64 s[8:9], 0xc00
	global_store_short v[34:35], v0, off offset:448
	v_lshl_add_u64 v[34:35], v[66:67], 0, s[8:9]
	v_cvt_pk_bf16_f32 v0, v62, s0
	global_store_short v[34:35], v0, off
	v_cvt_pk_bf16_f32 v0, v46, s0
	global_store_short v[34:35], v0, off offset:64
	v_cvt_pk_bf16_f32 v0, v63, s0
	global_store_short v[34:35], v0, off offset:128
	v_cvt_pk_bf16_f32 v0, v47, s0
	global_store_short v[34:35], v0, off offset:192
	v_cvt_pk_bf16_f32 v0, v64, s0
	global_store_short v[34:35], v0, off offset:256
	v_cvt_pk_bf16_f32 v0, v48, s0
	global_store_short v[34:35], v0, off offset:320
	v_cvt_pk_bf16_f32 v0, v65, s0
	global_store_short v[34:35], v0, off offset:384
	v_cvt_pk_bf16_f32 v0, v49, s0
	s_mov_b64 s[8:9], 0x1000
	global_store_short v[34:35], v0, off offset:448
	v_lshl_add_u64 v[34:35], v[66:67], 0, s[8:9]
	v_cvt_pk_bf16_f32 v0, v18, s0
	global_store_short v[34:35], v0, off
	v_cvt_pk_bf16_f32 v0, v2, s0
	global_store_short v[34:35], v0, off offset:64
	v_cvt_pk_bf16_f32 v0, v19, s0
	global_store_short v[34:35], v0, off offset:128
	v_cvt_pk_bf16_f32 v0, v3, s0
	global_store_short v[34:35], v0, off offset:192
	v_cvt_pk_bf16_f32 v0, v20, s0
	global_store_short v[34:35], v0, off offset:256
	v_cvt_pk_bf16_f32 v0, v4, s0
	global_store_short v[34:35], v0, off offset:320
	v_cvt_pk_bf16_f32 v0, v21, s0
	global_store_short v[34:35], v0, off offset:384
	v_cvt_pk_bf16_f32 v0, v5, s0
	s_mov_b64 s[8:9], 0x1400
	global_store_short v[34:35], v0, off offset:448
	v_lshl_add_u64 v[2:3], v[66:67], 0, s[8:9]
	v_cvt_pk_bf16_f32 v0, v22, s0
	global_store_short v[2:3], v0, off
	v_cvt_pk_bf16_f32 v0, v6, s0
	global_store_short v[2:3], v0, off offset:64
	v_cvt_pk_bf16_f32 v0, v23, s0
	global_store_short v[2:3], v0, off offset:128
	v_cvt_pk_bf16_f32 v0, v7, s0
	global_store_short v[2:3], v0, off offset:192
	v_cvt_pk_bf16_f32 v0, v24, s0
	global_store_short v[2:3], v0, off offset:256
	v_cvt_pk_bf16_f32 v0, v8, s0
	global_store_short v[2:3], v0, off offset:320
	v_cvt_pk_bf16_f32 v0, v25, s0
	global_store_short v[2:3], v0, off offset:384
	v_cvt_pk_bf16_f32 v0, v9, s0
	s_mov_b64 s[8:9], 0x1800
	global_store_short v[2:3], v0, off offset:448
	v_lshl_add_u64 v[2:3], v[66:67], 0, s[8:9]
	v_cvt_pk_bf16_f32 v0, v26, s0
	global_store_short v[2:3], v0, off
	v_cvt_pk_bf16_f32 v0, v10, s0
	global_store_short v[2:3], v0, off offset:64
	v_cvt_pk_bf16_f32 v0, v27, s0
	global_store_short v[2:3], v0, off offset:128
	v_cvt_pk_bf16_f32 v0, v11, s0
	global_store_short v[2:3], v0, off offset:192
	v_cvt_pk_bf16_f32 v0, v28, s0
	global_store_short v[2:3], v0, off offset:256
	v_cvt_pk_bf16_f32 v0, v12, s0
	global_store_short v[2:3], v0, off offset:320
	v_cvt_pk_bf16_f32 v0, v29, s0
	global_store_short v[2:3], v0, off offset:384
	v_cvt_pk_bf16_f32 v0, v13, s0
	s_mov_b64 s[8:9], 0x1c00
	global_store_short v[2:3], v0, off offset:448
	v_lshl_add_u64 v[2:3], v[66:67], 0, s[8:9]
	v_cvt_pk_bf16_f32 v0, v30, s0
	global_store_short v[2:3], v0, off
	v_cvt_pk_bf16_f32 v0, v14, s0
	global_store_short v[2:3], v0, off offset:64
	v_cvt_pk_bf16_f32 v0, v31, s0
	global_store_short v[2:3], v0, off offset:128
	v_cvt_pk_bf16_f32 v0, v15, s0
	global_store_short v[2:3], v0, off offset:192
	v_cvt_pk_bf16_f32 v0, v32, s0
	global_store_short v[2:3], v0, off offset:256
	v_cvt_pk_bf16_f32 v0, v16, s0
	global_store_short v[2:3], v0, off offset:320
	v_cvt_pk_bf16_f32 v0, v33, s0
	global_store_short v[2:3], v0, off offset:384
	v_cvt_pk_bf16_f32 v0, v17, s0
	global_store_short v[2:3], v0, off offset:448
	s_branch .LBB0_514

; DI unsigned xb_ld(unsigned* p)              { return __hip_atomic_load(p, __ATOMIC_RELAXED, __HIP_MEMORY_SCOPE_AGENT); }
; DI void xcd_barrier_complete(unsigned* bar, unsigned x, unsigned& nloc, unsigned& nx) {
;     const unsigned G = gridDim.x * gridDim.y * gridDim.z;
;     unsigned sum, cnt, mine, sp = 0u;
;     for (;;) {
;         sum = 0u; cnt = 0u; mine = 0u;
; #pragma unroll
;         for (unsigned j = 0; j < 16; ++j) { const unsigned c = xb_ld(&bar[XB_XCNT(j)]); sum += c; cnt += (c > 0u) ? 1u : 0u; mine = (j == x) ? c : mine; }
;         if (sum == G) break;
;         __builtin_amdgcn_s_sleep(1);
;         if ((++sp & 255u) == 0u) { if (xb_ld(&bar[XB_TMO])) break; if (sp > XB_SPIN_CAP) { atomicAdd(&bar[XB_TMO], 1u); break; } }
;     }
;     nloc = mine > 0u ? mine : 1u; nx = cnt > 0u ? cnt : 1u;
; }
.LBB0_530:
	v_mov_b64_e32 v[12:13], s[38:39]
	global_load_dword v2, v[12:13], off offset:1024 sc1
	s_waitcnt lgkmcnt(0)
	global_load_dword v0, v[12:13], off offset:1280 sc1
	global_load_dword v3, v[12:13], off offset:1536 sc1
	s_or_b64 s[18:19], s[18:19], exec
	s_or_b64 s[16:17], s[16:17], exec
	s_waitcnt vmcnt(0) lgkmcnt(0)
	v_add_u32_e32 v4, v0, v2
	v_add_u32_e32 v5, v4, v3
	global_load_dword v4, v[12:13], off offset:1792 sc1
	s_waitcnt vmcnt(0) lgkmcnt(0)
	v_add_u32_e32 v6, v5, v4
	global_load_dword v5, v[12:13], off offset:2048 sc1
	s_waitcnt vmcnt(0) lgkmcnt(0)
	v_add_u32_e32 v7, v6, v5
	global_load_dword v6, v[12:13], off offset:2304 sc1
	s_waitcnt vmcnt(0) lgkmcnt(0)
	v_add_u32_e32 v8, v7, v6
	global_load_dword v7, v[12:13], off offset:2560 sc1
	s_waitcnt vmcnt(0) lgkmcnt(0)
	v_add_u32_e32 v9, v8, v7
	global_load_dword v8, v[12:13], off offset:2816 sc1
	s_waitcnt vmcnt(0) lgkmcnt(0)
	v_add_u32_e32 v10, v9, v8
	global_load_dword v9, v[12:13], off offset:3072 sc1
	s_waitcnt vmcnt(0) lgkmcnt(0)
	v_add_u32_e32 v11, v10, v9
	global_load_dword v10, v[12:13], off offset:3328 sc1
	s_waitcnt vmcnt(0) lgkmcnt(0)
	v_add_u32_e32 v14, v11, v10
	global_load_dword v11, v[12:13], off offset:3584 sc1
	s_waitcnt vmcnt(0) lgkmcnt(0)
	v_add_u32_e32 v14, v14, v11
	global_load_dword v12, v[12:13], off offset:3840 sc1
	s_waitcnt vmcnt(0) lgkmcnt(0)
	v_add_u32_e32 v16, v14, v12
	v_mov_b64_e32 v[14:15], s[4:5]
	global_load_dword v13, v[14:15], off sc1
	v_mov_b64_e32 v[14:15], s[6:7]
	global_load_dword v14, v[14:15], off sc1
	s_waitcnt vmcnt(0) lgkmcnt(0)
	v_add_u32_e32 v16, v16, v13
	v_add_u32_e32 v18, v16, v14
	v_mov_b64_e32 v[16:17], s[8:9]
	global_load_dword v15, v[16:17], off sc1
	v_mov_b64_e32 v[16:17], s[10:11]
	global_load_dword v16, v[16:17], off sc1
	s_waitcnt vmcnt(0) lgkmcnt(0)
	v_add_u32_e32 v18, v18, v15
	v_add_u32_e32 v17, v18, v16
	v_cmp_ne_u32_e32 vcc, s84, v17
	s_and_saveexec_b64 s[20:21], vcc
	s_cbranch_execz .LBB0_529
	s_and_b32 s24, s30, 0xff
	s_mov_b64 s[22:23], -1
	s_cmp_eq_u32 s24, 0
	s_mov_b64 s[26:27], -1
	s_mov_b64 s[24:25], -1
	s_sleep 1
	s_cbranch_scc1 .LBB0_533
	s_and_saveexec_b64 s[28:29], s[26:27]
	s_cbranch_execz .LBB0_528
	s_branch .LBB0_536
.LBB0_533:
	v_mov_b64_e32 v[18:19], s[38:39]
	global_load_dword v17, v[18:19], off offset:512 sc1
	s_mov_b64 s[26:27], 0
	s_waitcnt vmcnt(0) lgkmcnt(0)
	v_cmp_eq_u32_e32 vcc, 0, v17
	s_and_saveexec_b64 s[28:29], vcc
	s_cmp_lt_u32 s30, 0x40001
	s_cselect_b64 s[26:27], -1, 0
	s_xor_b64 s[24:25], exec, -1
	s_and_b64 s[26:27], s[26:27], exec
	s_or_b64 exec, exec, s[28:29]
	s_and_saveexec_b64 s[28:29], s[26:27]
	s_cbranch_execz .LBB0_528

; DI unsigned xb_ld(unsigned* p)              { return __hip_atomic_load(p, __ATOMIC_RELAXED, __HIP_MEMORY_SCOPE_AGENT); }
; DI unsigned xb_add(unsigned* p, unsigned v) { return __hip_atomic_fetch_add(p, v, __ATOMIC_RELAXED, __HIP_MEMORY_SCOPE_AGENT); }
; #define XB_SPIN(cond, bar) do { unsigned _sp = 0; while (cond) { __builtin_amdgcn_s_sleep(1); \
;     if ((++_sp & 255u) == 0u) { if (xb_ld(&(bar)[XB_TMO])) break; if (_sp > XB_SPIN_CAP) { atomicAdd(&(bar)[XB_TMO], 1u); break; } } } } while (0)
; DI void xcd_barrier(const XcdBarrier& b) {
;     ...
;         const unsigned old = xb_add(&bar[XB_XSUB(bx)], 1u);
;         const unsigned gen = old / nloc;
;         if (old + 1u == (gen + 1u) * nloc) {
;             __builtin_amdgcn_fence(__ATOMIC_RELEASE, "agent");
;             asm volatile("s_waitcnt vmcnt(0)" ::: "memory");
;             const unsigned og = xb_add(&bar[XB_TOP], 1u);
;             const unsigned tg = og / nx;
;             if (og + 1u == (tg + 1u) * nx) xb_add(&bar[XB_TOPGEN], 1u);
;             else XB_SPIN(xb_ld(&bar[XB_TOPGEN]) == tg, bar);
;             __builtin_amdgcn_fence(__ATOMIC_ACQUIRE, "agent");
;             xb_add(&bar[XB_XGEN(bx)], 1u);
;             asm volatile("s_waitcnt vmcnt(0)" ::: "memory");
;         } else {
;             XB_SPIN(xb_ld(&bar[XB_XGEN(bx)]) == gen, bar);
.LBB0_540:
	s_lshl_b32 s3, s3, 8
	s_add_u32 s24, s38, s3
	s_addc_u32 s3, s39, 0
	v_mov_b32_e32 v3, s24
	v_add_co_u32_e32 v4, vcc, 0x1000, v3
	v_mov_b32_e32 v3, s3
	s_nop 0
	v_addc_co_u32_e32 v5, vcc, 0, v3, vcc
	flat_atomic_add v4, v[4:5], v218 offset:1024 sc0
	v_cvt_f32_u32_e32 v3, v2
	v_sub_u32_e32 v5, 0, v2
	v_rcp_iflag_f32_e32 v3, v3
	s_nop 0
	v_mul_f32_e32 v3, 0x4f7ffffe, v3
	v_cvt_u32_f32_e32 v3, v3
	v_mul_lo_u32 v5, v5, v3
	v_mul_hi_u32 v5, v3, v5
	v_add_u32_e32 v3, v3, v5
	s_waitcnt vmcnt(0) lgkmcnt(0)
	v_mul_hi_u32 v3, v4, v3
	v_mul_lo_u32 v5, v3, v2
	v_sub_u32_e32 v5, v4, v5
	v_cmp_ge_u32_e32 vcc, v5, v2
	v_add_u32_e32 v6, 1, v3
	s_nop 0
	v_cndmask_b32_e32 v3, v3, v6, vcc
	v_sub_u32_e32 v6, v5, v2
	v_cndmask_b32_e32 v5, v5, v6, vcc
	v_cmp_ge_u32_e32 vcc, v5, v2
	v_add_u32_e32 v5, 1, v3
	v_add_u32_e32 v6, 1, v4
	v_cndmask_b32_e32 v3, v3, v5, vcc
	v_mad_u64_u32 v[4:5], s[4:5], v2, v3, v[2:3]
	v_cmp_ne_u32_e32 vcc, v6, v4
	s_and_saveexec_b64 s[4:5], vcc
	s_xor_b64 s[4:5], exec, s[4:5]
	s_cbranch_execz .LBB0_553
	v_mov_b32_e32 v0, s24
	v_add_co_u32_e32 v4, vcc, 0x2000, v0
	v_mov_b32_e32 v0, s3
	s_nop 0
	v_addc_co_u32_e32 v5, vcc, 0, v0, vcc
	global_load_dword v0, v[4:5], off offset:1024 sc1
	s_add_u32 s8, s24, 0x2400
	s_addc_u32 s9, s3, 0
	s_waitcnt vmcnt(0) lgkmcnt(0)
	v_cmp_eq_u32_e32 vcc, v0, v3
	s_and_saveexec_b64 s[6:7], vcc
	s_cbranch_execz .LBB0_552
	s_mov_b32 s25, 1
	s_mov_b64 s[10:11], 0
	s_branch .LBB0_544

; DI unsigned xb_ld(unsigned* p)              { return __hip_atomic_load(p, __ATOMIC_RELAXED, __HIP_MEMORY_SCOPE_AGENT); }
; #define XB_SPIN(cond, bar) do { unsigned _sp = 0; while (cond) { __builtin_amdgcn_s_sleep(1); \
;     if ((++_sp & 255u) == 0u) { if (xb_ld(&(bar)[XB_TMO])) break; if (_sp > XB_SPIN_CAP) { atomicAdd(&(bar)[XB_TMO], 1u); break; } } } } while (0)
; DI void xcd_barrier(const XcdBarrier& b) {
;     ...
;             XB_SPIN(xb_ld(&bar[XB_XGEN(bx)]) == gen, bar);
.LBB0_544:
	s_and_b32 s18, s25, 0xff
	s_mov_b64 s[16:17], -1
	s_cmp_lg_u32 s18, 0
	s_mov_b64 s[18:19], -1
	s_sleep 1
	s_cbranch_scc1 .LBB0_548
	v_mov_b64_e32 v[4:5], s[38:39]
	global_load_dword v0, v[4:5], off offset:512 sc1
	s_mov_b64 s[18:19], 0
	s_mov_b64 s[20:21], -1
	s_waitcnt vmcnt(0) lgkmcnt(0)
	v_cmp_eq_u32_e32 vcc, 0, v0
	s_and_saveexec_b64 s[22:23], vcc
	s_cmp_lt_u32 s25, 0x40001
	s_cselect_b64 s[18:19], -1, 0
	s_xor_b64 s[20:21], exec, -1
	s_and_b64 s[18:19], s[18:19], exec
	s_or_b64 exec, exec, s[22:23]
.LBB0_548:
	s_andn2_b64 s[14:15], s[14:15], exec
	s_and_b64 s[20:21], s[20:21], exec
	s_or_b64 s[14:15], s[14:15], s[20:21]
	s_and_saveexec_b64 s[20:21], s[18:19]
	s_cbranch_execz .LBB0_543
	v_mov_b64_e32 v[4:5], s[8:9]
	global_load_dword v0, v[4:5], off sc1
	s_add_i32 s25, s25, 1
	s_or_b64 s[14:15], s[14:15], exec
	s_waitcnt vmcnt(0) lgkmcnt(0)
	v_cmp_ne_u32_e32 vcc, v0, v3
	s_orn2_b64 s[16:17], vcc, exec
	s_branch .LBB0_543

; DI unsigned xb_ld(unsigned* p)              { return __hip_atomic_load(p, __ATOMIC_RELAXED, __HIP_MEMORY_SCOPE_AGENT); }
; DI unsigned xb_add(unsigned* p, unsigned v) { return __hip_atomic_fetch_add(p, v, __ATOMIC_RELAXED, __HIP_MEMORY_SCOPE_AGENT); }
; #define XB_SPIN(cond, bar) do { unsigned _sp = 0; while (cond) { __builtin_amdgcn_s_sleep(1); \
;     if ((++_sp & 255u) == 0u) { if (xb_ld(&(bar)[XB_TMO])) break; if (_sp > XB_SPIN_CAP) { atomicAdd(&(bar)[XB_TMO], 1u); break; } } } } while (0)
; DI void xcd_barrier(const XcdBarrier& b) {
;     ...
;         if (old + 1u == (gen + 1u) * nloc) {
;             __builtin_amdgcn_fence(__ATOMIC_RELEASE, "agent");
;             asm volatile("s_waitcnt vmcnt(0)" ::: "memory");
;             const unsigned og = xb_add(&bar[XB_TOP], 1u);
;             const unsigned tg = og / nx;
;             if (og + 1u == (tg + 1u) * nx) xb_add(&bar[XB_TOPGEN], 1u);
;             else XB_SPIN(xb_ld(&bar[XB_TOPGEN]) == tg, bar);
.LBB0_553:
	s_andn2_saveexec_b64 s[4:5], s[4:5]
	s_cbranch_execz .LBB0_569
	v_mov_b32_e32 v2, s38
	v_add_co_u32_e32 v2, vcc, 0x3000, v2
	v_mov_b32_e32 v3, s39
	buffer_wbl2 sc1
	s_waitcnt vmcnt(0)
	v_addc_co_u32_e32 v3, vcc, 0, v3, vcc
	flat_atomic_add v2, v[2:3], v218 offset:1024 sc0
	v_cvt_f32_u32_e32 v3, v0
	v_sub_u32_e32 v4, 0, v0
	s_mov_b64 s[8:9], -1
	v_rcp_iflag_f32_e32 v3, v3
	s_nop 0
	v_mul_f32_e32 v3, 0x4f7ffffe, v3
	v_cvt_u32_f32_e32 v3, v3
	v_mul_lo_u32 v4, v4, v3
	v_mul_hi_u32 v4, v3, v4
	v_add_u32_e32 v3, v3, v4
	s_waitcnt vmcnt(0) lgkmcnt(0)
	v_mul_hi_u32 v3, v2, v3
	v_mul_lo_u32 v4, v3, v0
	v_sub_u32_e32 v4, v2, v4
	v_cmp_ge_u32_e32 vcc, v4, v0
	v_add_u32_e32 v5, 1, v3
	s_nop 0
	v_cndmask_b32_e32 v3, v3, v5, vcc
	v_sub_u32_e32 v5, v4, v0
	v_cndmask_b32_e32 v4, v4, v5, vcc
	v_cmp_ge_u32_e32 vcc, v4, v0
	v_add_u32_e32 v4, 1, v3
	v_add_u32_e32 v5, 1, v2
	v_cndmask_b32_e32 v4, v3, v4, vcc
	v_mad_u64_u32 v[2:3], s[4:5], v0, v4, v[0:1]
	s_add_u32 s4, s38, 0x3500
	s_addc_u32 s5, s39, 0
	v_cmp_ne_u32_e32 vcc, v5, v2
	v_mov_b64_e32 v[2:3], s[4:5]
	s_and_saveexec_b64 s[6:7], vcc
	s_cbranch_execz .LBB0_566
	v_mov_b64_e32 v[2:3], s[4:5]
	global_load_dword v0, v[2:3], off sc1
	s_mov_b64 s[12:13], 0
	s_waitcnt vmcnt(0) lgkmcnt(0)
	v_cmp_eq_u32_e32 vcc, v0, v4
	s_and_saveexec_b64 s[10:11], vcc
	s_cbranch_execz .LBB0_565
	s_add_u32 s8, s38, 0x200
	s_addc_u32 s9, s39, 0
	s_mov_b32 s25, 1
	s_branch .LBB0_558

; DI unsigned xb_ld(unsigned* p)              { return __hip_atomic_load(p, __ATOMIC_RELAXED, __HIP_MEMORY_SCOPE_AGENT); }
; #define XB_SPIN(cond, bar) do { unsigned _sp = 0; while (cond) { __builtin_amdgcn_s_sleep(1); \
;     if ((++_sp & 255u) == 0u) { if (xb_ld(&(bar)[XB_TMO])) break; if (_sp > XB_SPIN_CAP) { atomicAdd(&(bar)[XB_TMO], 1u); break; } } } } while (0)
; DI void xcd_barrier(const XcdBarrier& b) {
;     ...
;             else XB_SPIN(xb_ld(&bar[XB_TOPGEN]) == tg, bar);
.LBB0_560:
	v_mov_b64_e32 v[2:3], s[8:9]
	global_load_dword v0, v[2:3], off sc1
	s_mov_b64 s[20:21], 0
	s_mov_b64 s[18:19], -1
	s_waitcnt vmcnt(0) lgkmcnt(0)
	v_cmp_eq_u32_e32 vcc, 0, v0
	s_and_saveexec_b64 s[22:23], vcc
	s_cmp_lt_u32 s25, 0x40001
	s_cselect_b64 s[20:21], -1, 0
	s_xor_b64 s[18:19], exec, -1
	s_and_b64 s[20:21], s[20:21], exec
	s_or_b64 exec, exec, s[22:23]
	s_and_saveexec_b64 s[22:23], s[20:21]
	s_cbranch_execz .LBB0_557
.LBB0_563:
	v_mov_b64_e32 v[2:3], s[4:5]
	global_load_dword v0, v[2:3], off sc1
	s_add_i32 s25, s25, 1
	s_or_b64 s[18:19], s[18:19], exec
	s_waitcnt vmcnt(0) lgkmcnt(0)
	v_cmp_ne_u32_e32 vcc, v0, v4
	s_orn2_b64 s[16:17], vcc, exec
	s_branch .LBB0_557

; DI float bflo(unsigned u) { return __uint_as_float(u << 16); }
; DI float bfhi(unsigned u) { return __uint_as_float(u & 0xffff0000u); }
; DI int tid8_op() { int t = threadIdx.x; asm volatile("" : "+v"(t)); return t; }
; template <int K> DI void row_rstd8(const bf16_t* A, float* rs) {
;     const int tid = tid8_op(), row = tid >> 1, half = tid & 1;
;     constexpr int n = K / 2;
;     const bf16_t* pr = A + (size_t)row * K + half * n;
;     float s = 0.f;
; #pragma unroll 1
;     for (int c = 0; c < n / 64; ++c) {
;         u32x4 v[8];
; #pragma unroll
;         for (int j = 0; j < 8; ++j) v[j] = *(const u32x4*)(pr + 64 * c + 8 * j);
; #pragma unroll
;         for (int j = 0; j < 8; ++j) {
;             float a;
;             a = bflo(v[j].x); s += a * a; a = bfhi(v[j].x); s += a * a; a = bflo(v[j].y); s += a * a; a = bfhi(v[j].y); s += a * a;
;             a = bflo(v[j].z); s += a * a; a = bfhi(v[j].z); s += a * a; a = bflo(v[j].w); s += a * a; a = bfhi(v[j].w); s += a * a;
;         }
;     }
;     s += __shfl_xor(s, 1);
;     if (half == 0) rs[row] = rsqrtf(s / (float)K + 1e-6f);
; }
.LBB0_580:
	v_lshl_add_u64 v[6:7], v[2:3], 0, s[4:5]
	v_add_co_u32_e32 v34, vcc, 0x7880000, v6
	s_add_u32 s4, s4, 0x80
	s_nop 0
	v_addc_co_u32_e32 v35, vcc, 0, v7, vcc
	global_load_dwordx4 v[6:9], v[34:35], off
	global_load_dwordx4 v[10:13], v[34:35], off offset:16
	global_load_dwordx4 v[14:17], v[34:35], off offset:32
	global_load_dwordx4 v[18:21], v[34:35], off offset:48
	global_load_dwordx4 v[22:25], v[34:35], off offset:64
	global_load_dwordx4 v[26:29], v[34:35], off offset:80
	global_load_dwordx4 v[30:33], v[34:35], off offset:96
	s_nop 0
	global_load_dwordx4 v[34:37], v[34:35], off offset:112
	s_addc_u32 s5, s5, 0
	s_cmpk_lg_i32 s4, 0x180
	s_waitcnt vmcnt(0) lgkmcnt(0)
	v_lshlrev_b32_e32 v38, 16, v6
	v_fmac_f32_e32 v0, v38, v38
	v_and_b32_e32 v6, 0xffff0000, v6
	v_fmac_f32_e32 v0, v6, v6
	v_lshlrev_b32_e32 v6, 16, v7
	v_fmac_f32_e32 v0, v6, v6
	v_and_b32_e32 v6, 0xffff0000, v7
	v_fmac_f32_e32 v0, v6, v6
	v_lshlrev_b32_e32 v6, 16, v8
	v_fmac_f32_e32 v0, v6, v6
	v_and_b32_e32 v6, 0xffff0000, v8
	v_fmac_f32_e32 v0, v6, v6
	v_lshlrev_b32_e32 v6, 16, v9
	v_fmac_f32_e32 v0, v6, v6
	v_and_b32_e32 v6, 0xffff0000, v9
	v_fmac_f32_e32 v0, v6, v6
	v_lshlrev_b32_e32 v6, 16, v10
	v_fmac_f32_e32 v0, v6, v6
	v_and_b32_e32 v6, 0xffff0000, v10
	v_fmac_f32_e32 v0, v6, v6
	v_lshlrev_b32_e32 v6, 16, v11
	v_fmac_f32_e32 v0, v6, v6
	v_and_b32_e32 v6, 0xffff0000, v11
	v_fmac_f32_e32 v0, v6, v6
	v_lshlrev_b32_e32 v6, 16, v12
	v_fmac_f32_e32 v0, v6, v6
	v_and_b32_e32 v6, 0xffff0000, v12
	v_fmac_f32_e32 v0, v6, v6
	v_lshlrev_b32_e32 v6, 16, v13
	v_fmac_f32_e32 v0, v6, v6
	v_and_b32_e32 v6, 0xffff0000, v13
	v_fmac_f32_e32 v0, v6, v6
	v_lshlrev_b32_e32 v6, 16, v14
	v_fmac_f32_e32 v0, v6, v6
	v_and_b32_e32 v6, 0xffff0000, v14
	v_fmac_f32_e32 v0, v6, v6
	v_lshlrev_b32_e32 v6, 16, v15
	v_fmac_f32_e32 v0, v6, v6
	v_and_b32_e32 v6, 0xffff0000, v15
	v_fmac_f32_e32 v0, v6, v6
	v_lshlrev_b32_e32 v6, 16, v16
	v_fmac_f32_e32 v0, v6, v6
	v_and_b32_e32 v6, 0xffff0000, v16
	v_fmac_f32_e32 v0, v6, v6
	v_lshlrev_b32_e32 v6, 16, v17
	v_fmac_f32_e32 v0, v6, v6
	v_and_b32_e32 v6, 0xffff0000, v17
	v_fmac_f32_e32 v0, v6, v6
	v_lshlrev_b32_e32 v6, 16, v18
	v_fmac_f32_e32 v0, v6, v6
	v_and_b32_e32 v6, 0xffff0000, v18
	v_fmac_f32_e32 v0, v6, v6
	v_lshlrev_b32_e32 v6, 16, v19
	v_fmac_f32_e32 v0, v6, v6
	v_and_b32_e32 v6, 0xffff0000, v19
	v_fmac_f32_e32 v0, v6, v6
	v_lshlrev_b32_e32 v6, 16, v20
	v_fmac_f32_e32 v0, v6, v6
	v_and_b32_e32 v6, 0xffff0000, v20
	v_fmac_f32_e32 v0, v6, v6
	v_lshlrev_b32_e32 v6, 16, v21
	v_fmac_f32_e32 v0, v6, v6
	v_and_b32_e32 v6, 0xffff0000, v21
	v_fmac_f32_e32 v0, v6, v6
	v_lshlrev_b32_e32 v6, 16, v22
	v_fmac_f32_e32 v0, v6, v6
	v_and_b32_e32 v6, 0xffff0000, v22
	v_fmac_f32_e32 v0, v6, v6
	v_lshlrev_b32_e32 v6, 16, v23
	v_fmac_f32_e32 v0, v6, v6
	v_and_b32_e32 v6, 0xffff0000, v23
	v_fmac_f32_e32 v0, v6, v6
	v_lshlrev_b32_e32 v6, 16, v24
	v_fmac_f32_e32 v0, v6, v6
	v_and_b32_e32 v6, 0xffff0000, v24
	v_fmac_f32_e32 v0, v6, v6
	v_lshlrev_b32_e32 v6, 16, v25
	v_fmac_f32_e32 v0, v6, v6
	v_and_b32_e32 v6, 0xffff0000, v25
	v_fmac_f32_e32 v0, v6, v6
	v_lshlrev_b32_e32 v6, 16, v26
	v_fmac_f32_e32 v0, v6, v6
	v_and_b32_e32 v6, 0xffff0000, v26
	v_fmac_f32_e32 v0, v6, v6
	v_lshlrev_b32_e32 v6, 16, v27
	v_fmac_f32_e32 v0, v6, v6
	v_and_b32_e32 v6, 0xffff0000, v27
	v_fmac_f32_e32 v0, v6, v6
	v_lshlrev_b32_e32 v6, 16, v28
	v_fmac_f32_e32 v0, v6, v6
	v_and_b32_e32 v6, 0xffff0000, v28
	v_fmac_f32_e32 v0, v6, v6
	v_lshlrev_b32_e32 v6, 16, v29
	v_fmac_f32_e32 v0, v6, v6
	v_and_b32_e32 v6, 0xffff0000, v29
	v_fmac_f32_e32 v0, v6, v6
	v_lshlrev_b32_e32 v6, 16, v30
	v_fmac_f32_e32 v0, v6, v6
	v_and_b32_e32 v6, 0xffff0000, v30
	v_fmac_f32_e32 v0, v6, v6
	v_lshlrev_b32_e32 v6, 16, v31
	v_fmac_f32_e32 v0, v6, v6
	v_lshlrev_b32_e32 v7, 16, v32
	v_and_b32_e32 v6, 0xffff0000, v31
	v_pk_mul_f32 v[6:7], v[6:7], v[6:7]
	s_nop 0
	v_add_f32_e32 v0, v6, v0
	v_add_f32_e32 v0, v7, v0
	v_lshlrev_b32_e32 v7, 16, v33
	v_and_b32_e32 v6, 0xffff0000, v32
	v_pk_mul_f32 v[6:7], v[6:7], v[6:7]
	s_nop 0
	v_add_f32_e32 v0, v6, v0
	v_add_f32_e32 v0, v7, v0
	v_lshlrev_b32_e32 v6, 16, v34
	v_and_b32_e32 v7, 0xffff0000, v33
	v_pk_mul_f32 v[6:7], v[6:7], v[6:7]
	s_nop 0
	v_add_f32_e32 v0, v7, v0
	v_add_f32_e32 v0, v6, v0
	v_lshlrev_b32_e32 v7, 16, v35
	v_and_b32_e32 v6, 0xffff0000, v34
	v_pk_mul_f32 v[6:7], v[6:7], v[6:7]
	s_nop 0
	v_add_f32_e32 v0, v6, v0
	v_add_f32_e32 v0, v7, v0
	v_lshlrev_b32_e32 v7, 16, v36
	v_and_b32_e32 v6, 0xffff0000, v35
	v_pk_mul_f32 v[6:7], v[6:7], v[6:7]
	s_nop 0
	v_add_f32_e32 v0, v6, v0
	v_add_f32_e32 v0, v7, v0
	v_lshlrev_b32_e32 v7, 16, v37
	v_and_b32_e32 v6, 0xffff0000, v36
	v_pk_mul_f32 v[6:7], v[6:7], v[6:7]
	s_nop 0
	v_add_f32_e32 v0, v6, v0
	v_add_f32_e32 v0, v7, v0
	v_and_b32_e32 v6, 0xffff0000, v37
	v_fmac_f32_e32 v0, v6, v6
	s_cbranch_scc1 .LBB0_580
	v_and_b32_e32 v3, 64, v224
	v_xor_b32_e32 v2, 1, v224
	v_add_u32_e32 v3, 64, v3
	v_cmp_lt_i32_e32 vcc, v2, v3
	s_nop 1
	v_cndmask_b32_e32 v2, v224, v2, vcc
	v_lshlrev_b32_e32 v6, 2, v2
	ds_bpermute_b32 v2, v6, v0
	v_cmp_eq_u32_e32 vcc, 0, v5
	s_and_saveexec_b64 s[4:5], vcc
	s_cbranch_execz .LBB0_583
	s_waitcnt lgkmcnt(0)
	v_add_f32_e32 v0, v0, v2
	s_mov_b32 s3, 0x43c00000
	v_div_scale_f32 v2, s[6:7], s3, s3, v0
	v_rcp_f32_e32 v3, v2
	v_div_scale_f32 v5, vcc, v0, s3, v0
	v_fma_f32 v7, -v2, v3, 1.0
	v_fmac_f32_e32 v3, v7, v3
	v_mul_f32_e32 v7, v5, v3
	v_fma_f32 v8, -v2, v7, v5
	v_fmac_f32_e32 v7, v8, v3
	v_fma_f32 v2, -v2, v7, v5
	v_div_fmas_f32 v2, v2, v3, v7
	v_div_fixup_f32 v0, v2, s3, v0
	v_add_f32_e32 v0, 0x358637bd, v0
	v_mul_f32_e32 v2, 0x4b800000, v0
	v_cmp_gt_f32_e32 vcc, s94, v0
	s_nop 1
	v_cndmask_b32_e32 v0, v0, v2, vcc
	v_rsq_f32_e32 v0, v0
	s_nop 0
	v_mul_f32_e32 v2, 0x45800000, v0
	v_cndmask_b32_e32 v0, v0, v2, vcc
	v_lshl_add_u32 v2, v4, 2, v225
	ds_write_b32 v2, v0

; DI float bflo(unsigned u) { return __uint_as_float(u << 16); }
; DI float bfhi(unsigned u) { return __uint_as_float(u & 0xffff0000u); }
; DI int tid8_op() { int t = threadIdx.x; asm volatile("" : "+v"(t)); return t; }
; template <int K> DI void row_rstd8(const bf16_t* A, float* rs) {
;     const int tid = tid8_op(), row = tid >> 1, half = tid & 1;
;     constexpr int n = K / 2;
;     const bf16_t* pr = A + (size_t)row * K + half * n;
;     float s = 0.f;
; #pragma unroll 1
;     for (int c = 0; c < n / 64; ++c) {
;         u32x4 v[8];
; #pragma unroll
;         for (int j = 0; j < 8; ++j) v[j] = *(const u32x4*)(pr + 64 * c + 8 * j);
; #pragma unroll
;         for (int j = 0; j < 8; ++j) {
;             float a;
;             a = bflo(v[j].x); s += a * a; a = bfhi(v[j].x); s += a * a; a = bflo(v[j].y); s += a * a; a = bfhi(v[j].y); s += a * a;
;             a = bflo(v[j].z); s += a * a; a = bfhi(v[j].z); s += a * a; a = bflo(v[j].w); s += a * a; a = bfhi(v[j].w); s += a * a;
;         }
;     }
;     s += __shfl_xor(s, 1);
;     if (half == 0) rs[row] = rsqrtf(s / (float)K + 1e-6f);
; }
.LBB0_584:
	v_lshl_add_u64 v[36:37], s[6:7], 1, v[4:5]
	global_load_dwordx4 v[8:11], v[36:37], off
	global_load_dwordx4 v[12:15], v[36:37], off offset:16
	global_load_dwordx4 v[16:19], v[36:37], off offset:32
	global_load_dwordx4 v[20:23], v[36:37], off offset:48
	global_load_dwordx4 v[24:27], v[36:37], off offset:64
	global_load_dwordx4 v[28:31], v[36:37], off offset:80
	global_load_dwordx4 v[32:35], v[36:37], off offset:96
	s_nop 0
	global_load_dwordx4 v[36:39], v[36:37], off offset:112
	s_mov_b64 s[6:7], 64
	s_and_b64 vcc, exec, s[4:5]
	s_mov_b64 s[4:5], 0
	s_waitcnt vmcnt(0) lgkmcnt(0)
	v_lshlrev_b32_e32 v3, 16, v8
	v_fmac_f32_e32 v0, v3, v3
	v_and_b32_e32 v3, 0xffff0000, v8
	v_fmac_f32_e32 v0, v3, v3
	v_lshlrev_b32_e32 v3, 16, v9
	v_fmac_f32_e32 v0, v3, v3
	v_and_b32_e32 v3, 0xffff0000, v9
	v_fmac_f32_e32 v0, v3, v3
	v_lshlrev_b32_e32 v3, 16, v10
	v_fmac_f32_e32 v0, v3, v3
	v_and_b32_e32 v3, 0xffff0000, v10
	v_fmac_f32_e32 v0, v3, v3
	v_lshlrev_b32_e32 v3, 16, v11
	v_fmac_f32_e32 v0, v3, v3
	v_and_b32_e32 v3, 0xffff0000, v11
	v_fmac_f32_e32 v0, v3, v3
	v_lshlrev_b32_e32 v3, 16, v12
	v_fmac_f32_e32 v0, v3, v3
	v_and_b32_e32 v3, 0xffff0000, v12
	v_fmac_f32_e32 v0, v3, v3
	v_lshlrev_b32_e32 v3, 16, v13
	v_fmac_f32_e32 v0, v3, v3
	v_and_b32_e32 v3, 0xffff0000, v13
	v_fmac_f32_e32 v0, v3, v3
	v_lshlrev_b32_e32 v3, 16, v14
	v_fmac_f32_e32 v0, v3, v3
	v_and_b32_e32 v3, 0xffff0000, v14
	v_fmac_f32_e32 v0, v3, v3
	v_lshlrev_b32_e32 v3, 16, v15
	v_fmac_f32_e32 v0, v3, v3
	v_and_b32_e32 v3, 0xffff0000, v15
	v_fmac_f32_e32 v0, v3, v3
	v_lshlrev_b32_e32 v3, 16, v16
	v_fmac_f32_e32 v0, v3, v3
	v_and_b32_e32 v3, 0xffff0000, v16
	v_fmac_f32_e32 v0, v3, v3
	v_lshlrev_b32_e32 v3, 16, v17
	v_fmac_f32_e32 v0, v3, v3
	v_and_b32_e32 v3, 0xffff0000, v17
	v_fmac_f32_e32 v0, v3, v3
	v_lshlrev_b32_e32 v3, 16, v18
	v_fmac_f32_e32 v0, v3, v3
	v_and_b32_e32 v3, 0xffff0000, v18
	v_fmac_f32_e32 v0, v3, v3
	v_lshlrev_b32_e32 v3, 16, v19
	v_fmac_f32_e32 v0, v3, v3
	v_and_b32_e32 v3, 0xffff0000, v19
	v_fmac_f32_e32 v0, v3, v3
	v_lshlrev_b32_e32 v3, 16, v20
	v_fmac_f32_e32 v0, v3, v3
	v_and_b32_e32 v3, 0xffff0000, v20
	v_fmac_f32_e32 v0, v3, v3
	v_lshlrev_b32_e32 v3, 16, v21
	v_fmac_f32_e32 v0, v3, v3
	v_and_b32_e32 v3, 0xffff0000, v21
	v_fmac_f32_e32 v0, v3, v3
	v_lshlrev_b32_e32 v3, 16, v22
	v_fmac_f32_e32 v0, v3, v3
	v_and_b32_e32 v3, 0xffff0000, v22
	v_fmac_f32_e32 v0, v3, v3
	v_lshlrev_b32_e32 v3, 16, v23
	v_fmac_f32_e32 v0, v3, v3
	v_and_b32_e32 v3, 0xffff0000, v23
	v_fmac_f32_e32 v0, v3, v3
	v_lshlrev_b32_e32 v3, 16, v24
	v_fmac_f32_e32 v0, v3, v3
	v_and_b32_e32 v3, 0xffff0000, v24
	v_fmac_f32_e32 v0, v3, v3
	v_lshlrev_b32_e32 v3, 16, v25
	v_fmac_f32_e32 v0, v3, v3
	v_and_b32_e32 v3, 0xffff0000, v25
	v_fmac_f32_e32 v0, v3, v3
	v_lshlrev_b32_e32 v3, 16, v26
	v_fmac_f32_e32 v0, v3, v3
	v_and_b32_e32 v3, 0xffff0000, v26
	v_fmac_f32_e32 v0, v3, v3
	v_lshlrev_b32_e32 v3, 16, v27
	v_fmac_f32_e32 v0, v3, v3
	v_and_b32_e32 v3, 0xffff0000, v27
	v_fmac_f32_e32 v0, v3, v3
	v_lshlrev_b32_e32 v3, 16, v28
	v_fmac_f32_e32 v0, v3, v3
	v_and_b32_e32 v3, 0xffff0000, v28
	v_fmac_f32_e32 v0, v3, v3
	v_lshlrev_b32_e32 v3, 16, v29
	v_fmac_f32_e32 v0, v3, v3
	v_and_b32_e32 v3, 0xffff0000, v29
	v_fmac_f32_e32 v0, v3, v3
	v_lshlrev_b32_e32 v3, 16, v30
	v_fmac_f32_e32 v0, v3, v3
	v_and_b32_e32 v3, 0xffff0000, v30
	v_fmac_f32_e32 v0, v3, v3
	v_lshlrev_b32_e32 v3, 16, v31
	v_fmac_f32_e32 v0, v3, v3
	v_and_b32_e32 v3, 0xffff0000, v31
	v_fmac_f32_e32 v0, v3, v3
	v_lshlrev_b32_e32 v3, 16, v32
	v_fmac_f32_e32 v0, v3, v3
	v_and_b32_e32 v3, 0xffff0000, v32
	v_fmac_f32_e32 v0, v3, v3
	v_lshlrev_b32_e32 v3, 16, v33
	v_lshlrev_b32_e32 v9, 16, v34
	v_and_b32_e32 v8, 0xffff0000, v33
	v_fmac_f32_e32 v0, v3, v3
	v_pk_mul_f32 v[8:9], v[8:9], v[8:9]
	v_and_b32_e32 v3, 0xffff0000, v39
	v_add_f32_e32 v0, v8, v0
	v_add_f32_e32 v0, v9, v0
	v_lshlrev_b32_e32 v9, 16, v35
	v_and_b32_e32 v8, 0xffff0000, v34
	v_pk_mul_f32 v[8:9], v[8:9], v[8:9]
	s_nop 0
	v_add_f32_e32 v0, v8, v0
	v_add_f32_e32 v0, v9, v0
	v_lshlrev_b32_e32 v8, 16, v36
	v_and_b32_e32 v9, 0xffff0000, v35
	v_pk_mul_f32 v[8:9], v[8:9], v[8:9]
	s_nop 0
	v_add_f32_e32 v0, v9, v0
	v_add_f32_e32 v0, v8, v0
	v_lshlrev_b32_e32 v9, 16, v37
	v_and_b32_e32 v8, 0xffff0000, v36
	v_pk_mul_f32 v[8:9], v[8:9], v[8:9]
	s_nop 0
	v_add_f32_e32 v0, v8, v0
	v_add_f32_e32 v0, v9, v0
	v_lshlrev_b32_e32 v9, 16, v38
	v_and_b32_e32 v8, 0xffff0000, v37
	v_pk_mul_f32 v[8:9], v[8:9], v[8:9]
	s_nop 0
	v_add_f32_e32 v0, v8, v0
	v_add_f32_e32 v0, v9, v0
	v_lshlrev_b32_e32 v9, 16, v39
	v_and_b32_e32 v8, 0xffff0000, v38
	v_pk_mul_f32 v[8:9], v[8:9], v[8:9]
	s_nop 0
	v_add_f32_e32 v0, v8, v0
	v_add_f32_e32 v0, v9, v0
	v_fmac_f32_e32 v0, v3, v3
	s_cbranch_vccnz .LBB0_584
	ds_bpermute_b32 v3, v6, v0
	v_cmp_eq_u32_e32 vcc, 0, v7
	s_and_saveexec_b64 s[4:5], vcc
	s_cbranch_execz .LBB0_587
	s_waitcnt lgkmcnt(0)
	v_add_f32_e32 v0, v0, v3
	v_mov_b32_e32 v3, 0x358637bd
	v_fmamk_f32 v0, v0, 0x3b800000, v3
	v_mul_f32_e32 v3, 0x4b800000, v0
	v_cmp_gt_f32_e32 vcc, s94, v0
	v_lshl_add_u32 v2, v2, 2, v226
	s_nop 0
	v_cndmask_b32_e32 v0, v0, v3, vcc
	v_rsq_f32_e32 v0, v0
	s_nop 0
	v_mul_f32_e32 v3, 0x45800000, v0
	v_cndmask_b32_e32 v0, v0, v3, vcc
	ds_write_b32 v2, v0

;     DI void operator()(const pg8::f32x4 (&acc)[2][2][4][2], const pg8::Unit& u, int wr, int wc, int fr, int fq) const {
;         asm volatile("" : "+v"(fr), "+v"(fq));
;         const int rowb = u.pm * 256 + wr * 64 + fr, b = (u.pm * 256) >> 13, s0 = rowb & (S_ - 1), hh = fq >> 1;
;         const float qs = 0.10206207261596575f * LOG2E;
;         const float* COS = (const float*)(ws + O_COS); const float* SIN = (const float*)(ws + O_SIN);
; #pragma unroll
;         for (int bj = 0; bj < 2; ++bj) {
;             const int c0 = u.pn * 256 + bj * 128 + wc * 32;
;             if (c0 < 384) {
;                 const int head = c0 / 96, d0 = c0 - head * 96;
;                 bf16_t* pb = (bf16_t*)(ws + O_MQ) + ((size_t)(b * 4 + head) * S_ + s0) * 96 + d0 + 8 * fq;
; #pragma unroll
;                 for (int ai = 0; ai < 2; ++ai)
; #pragma unroll
;                     for (int m = 0; m < 4; ++m) {
;                         const int rl = ai * 128 + wr * 64 + m * 16 + fr;
;                         const float sc = rs[rl] * qs;
;                         f32x4 v0 = acc[ai][bj][m][0] * sc, v1 = acc[ai][bj][m][1] * sc;
;                         if (d0 == 64) {
;                             const float* pc = opaque(COS + (size_t)(rowb + ai * 128 + m * 16) * 16 + 8 * (fq & 1));
;                             const float* ps = SIN + (pc - COS);
;                             {   const f32x4 cv = *(const f32x4*)pc, sv = *(const f32x4*)ps; f32x4 pp;
; #pragma unroll
;                                 for (int e = 0; e < 4; ++e) pp[e] = xhalf_other(v0[e], hh);
;                                 v0 = hh ? (v0 * cv + pp * sv) : (v0 * cv - pp * sv); }
;                             {   const f32x4 cv = *(const f32x4*)(pc + 4), sv = *(const f32x4*)(ps + 4); f32x4 pp;
; #pragma unroll
;                                 for (int e = 0; e < 4; ++e) pp[e] = xhalf_other(v1[e], hh);
;                                 v1 = hh ? (v1 * cv + pp * sv) : (v1 * cv - pp * sv); }
;                         }
;                         u32x4 wv; wv.x = pk2(v0.x, v0.y); wv.y = pk2(v0.z, v0.w); wv.z = pk2(v1.x, v1.y); wv.w = pk2(v1.z, v1.w);
;                         *(u32x4*)(opaque(pb) + (size_t)(ai * 128 + m * 16) * 96) = wv;
;                         asm volatile("" ::: "memory");
;                     }
;             }
;         }
;     }
.LBB0_592:
	s_lshl_b32 s41, s16, 8
	v_add_u32_e32 v131, s40, v141
	s_ashr_i32 s4, s16, 3
	v_lshlrev_b32_e32 v0, 5, v140
	s_lshl_b32 s6, s39, 8
	v_add_u32_e32 v130, s41, v131
	s_and_b32 s40, s4, -4
	v_lshlrev_b32_e32 v134, 3, v140
	v_and_b32_e32 v0, 32, v0
	s_or_b32 s3, s3, s6
	v_and_b32_e32 v148, 0x1fff, v130
	v_ashrrev_i32_e32 v135, 31, v134
	v_lshl_add_u64 v[132:133], s[10:11], 0, v[0:1]
	v_cmp_gt_u32_e64 s[4:5], 2, v140
	s_cmpk_gt_i32 s3, 0x17f
	v_lshl_add_u32 v0, v131, 2, v225
	s_cbranch_scc1 .LBB0_610
	s_mul_hi_i32 s6, s3, 0x2aaaaaab
	s_waitcnt vmcnt(0)
	ds_read_b32 v131, v0
	s_lshr_b32 s7, s6, 31
	s_ashr_i32 s6, s6, 4
	s_add_i32 s7, s6, s7
	s_mul_i32 s6, s7, 0xffffffa0
	s_add_i32 s6, s6, s3
	s_cmp_eq_u32 s6, 64
	s_waitcnt lgkmcnt(0)
	v_mul_f32_e32 v142, 0x3e16c740, v131
	s_cselect_b64 s[18:19], -1, 0
	s_cmp_lg_u32 s6, 64
	v_pk_mul_f32 v[136:137], v[128:129], v[142:143] op_sel_hi:[1,0]
	v_pk_mul_f32 v[138:139], v[126:127], v[142:143] op_sel_hi:[1,0]
	v_pk_mul_f32 v[140:141], v[124:125], v[142:143] op_sel_hi:[1,0]
	v_pk_mul_f32 v[142:143], v[122:123], v[142:143] op_sel_hi:[1,0]
	s_cbranch_scc1 .LBB0_595
	v_ashrrev_i32_e32 v131, 31, v130
	v_lshlrev_b64 v[122:123], 6, v[130:131]
	v_lshl_add_u64 v[150:151], v[132:133], 0, v[122:123]
	v_mov_b32_e32 v123, s11
	v_subrev_co_u32_e32 v122, vcc, s10, v150
	v_mov_b32_e32 v131, v138
	s_nop 0
	v_subb_co_u32_e32 v123, vcc, v151, v123, vcc
	v_lshl_add_u64 v[152:153], s[12:13], 0, v[122:123]
	global_load_dwordx4 v[126:129], v[150:151], off
	global_load_dwordx4 v[122:125], v[152:153], off
	v_mov_b32_e32 v144, v138
	s_nop 1
	v_permlane32_swap_b32_e32 v131, v144
	v_cndmask_b32_e64 v144, v131, v144, s[4:5]
	v_mov_b32_e32 v131, v139
	v_mov_b32_e32 v145, v139
	s_nop 1
	v_permlane32_swap_b32_e32 v131, v145
	v_cndmask_b32_e64 v145, v131, v145, s[4:5]
	v_mov_b32_e32 v131, v136
	v_mov_b32_e32 v146, v136
	s_nop 1
	v_permlane32_swap_b32_e32 v131, v146
	v_cndmask_b32_e64 v146, v131, v146, s[4:5]
	v_mov_b32_e32 v131, v137
	v_mov_b32_e32 v147, v137
	s_nop 1
	v_permlane32_swap_b32_e32 v131, v147
	v_cndmask_b32_e64 v147, v131, v147, s[4:5]
	v_mov_b32_e32 v149, v142
	s_waitcnt vmcnt(0) lgkmcnt(0)
	v_pk_mul_f32 v[124:125], v[124:125], v[146:147]
	v_pk_mul_f32 v[122:123], v[122:123], v[144:145]
	v_xor_b32_e32 v131, 0x80000000, v124
	v_xor_b32_e32 v144, 0x80000000, v125
	v_xor_b32_e32 v146, 0x80000000, v122
	v_xor_b32_e32 v147, 0x80000000, v123
	v_cndmask_b32_e64 v145, v125, v144, s[4:5]
	v_cndmask_b32_e64 v144, v124, v131, s[4:5]
	v_cndmask_b32_e64 v147, v123, v147, s[4:5]
	v_cndmask_b32_e64 v146, v122, v146, s[4:5]
	global_load_dwordx4 v[122:125], v[150:151], off offset:16
	s_nop 0
	global_load_dwordx4 v[150:153], v[152:153], off offset:16
	v_mov_b32_e32 v131, v142
	s_nop 1
	v_permlane32_swap_b32_e32 v131, v149
	v_cndmask_b32_e64 v154, v131, v149, s[4:5]
	v_mov_b32_e32 v131, v143
	v_mov_b32_e32 v149, v143
	s_nop 1
	v_permlane32_swap_b32_e32 v131, v149
	v_cndmask_b32_e64 v155, v131, v149, s[4:5]
	v_mov_b32_e32 v131, v140
	v_mov_b32_e32 v149, v140
	s_nop 1
	v_permlane32_swap_b32_e32 v131, v149
	v_cndmask_b32_e64 v156, v131, v149, s[4:5]
	v_mov_b32_e32 v131, v141
	v_mov_b32_e32 v149, v141
	s_nop 1
	v_permlane32_swap_b32_e32 v131, v149
	v_cndmask_b32_e64 v157, v131, v149, s[4:5]
	v_pk_fma_f32 v[136:137], v[136:137], v[128:129], v[144:145]
	v_pk_fma_f32 v[138:139], v[138:139], v[126:127], v[146:147]
	s_waitcnt vmcnt(0) lgkmcnt(0)
	v_pk_mul_f32 v[126:127], v[152:153], v[156:157]
	v_pk_mul_f32 v[128:129], v[150:151], v[154:155]
	v_xor_b32_e32 v131, 0x80000000, v126
	v_xor_b32_e32 v144, 0x80000000, v127
	v_xor_b32_e32 v145, 0x80000000, v128
	v_xor_b32_e32 v146, 0x80000000, v129
	v_cndmask_b32_e64 v127, v127, v144, s[4:5]
	v_cndmask_b32_e64 v126, v126, v131, s[4:5]
	v_cndmask_b32_e64 v129, v129, v146, s[4:5]
	v_cndmask_b32_e64 v128, v128, v145, s[4:5]
	v_pk_fma_f32 v[140:141], v[140:141], v[124:125], v[126:127]
	v_pk_fma_f32 v[142:143], v[142:143], v[122:123], v[128:129]
.LBB0_595:
	s_add_i32 s20, s7, s40
	s_ashr_i32 s21, s20, 31
	s_lshl_b64 s[20:21], s[20:21], 13
	v_or_b32_e32 v124, s20, v148
	v_mov_b64_e32 v[122:123], s[14:15]
	v_mad_u64_u32 v[122:123], s[22:23], v124, s79, v[122:123]
	v_mad_i32_i24 v123, s21, v227, v123
	s_ashr_i32 s7, s6, 31
	v_lshl_add_u64 v[122:123], s[6:7], 1, v[122:123]
	v_lshl_add_u64 v[122:123], v[134:135], 1, v[122:123]
	v_cvt_pk_bf16_f32 v124, v138, v139
	v_cvt_pk_bf16_f32 v125, v136, v137
	v_cvt_pk_bf16_f32 v126, v142, v143
	v_cvt_pk_bf16_f32 v127, v140, v141
	v_mov_b64_e32 v[128:129], v[122:123]
	global_store_dwordx4 v[128:129], v[124:127], off
	ds_read_b32 v124, v0 offset:64
	s_andn2_b64 vcc, exec, s[18:19]
	s_waitcnt lgkmcnt(0)
	v_mul_f32_e32 v136, 0x3e16c740, v124
	v_pk_mul_f32 v[128:129], v[116:117], v[136:137] op_sel_hi:[1,0]
	v_cndmask_b32_e64 v116, 0, 1, s[18:19]
	v_pk_mul_f32 v[124:125], v[120:121], v[136:137] op_sel_hi:[1,0]
	v_pk_mul_f32 v[126:127], v[118:119], v[136:137] op_sel_hi:[1,0]
	v_cmp_ne_u32_e64 s[6:7], 1, v116
	v_pk_mul_f32 v[136:137], v[114:115], v[136:137] op_sel_hi:[1,0]
	s_cbranch_vccnz .LBB0_597
; DI unsigned pk2(float a, float b) { f32x2 v = {a, b}; return __builtin_bit_cast(unsigned, __builtin_convertvector(v, bf2_t)); }
; DI float xhalf_other(float x, int h) { auto r = __builtin_amdgcn_permlane32_swap(__float_as_uint(x), __float_as_uint(x), false, false); return h ? __uint_as_float(r[0]) : __uint_as_float(r[1]); }
; template <typename T> DI T* opaque(T* p) { asm volatile("" : "+v"(p) : : "memory"); return p; }
;     DI void operator()(const pg8::f32x4 (&acc)[2][2][4][2], const pg8::Unit& u, int wr, int wc, int fr, int fq) const {
;     ...
;                 for (int ai = 0; ai < 2; ++ai)
; #pragma unroll
;                     for (int m = 0; m < 4; ++m) {
;                         const int rl = ai * 128 + wr * 64 + m * 16 + fr;
;                         const float sc = rs[rl] * qs;
;                         f32x4 v0 = acc[ai][bj][m][0] * sc, v1 = acc[ai][bj][m][1] * sc;
;                         if (d0 == 64) {
;                             const float* pc = opaque(COS + (size_t)(rowb + ai * 128 + m * 16) * 16 + 8 * (fq & 1));
;                             const float* ps = SIN + (pc - COS);
;                             {   const f32x4 cv = *(const f32x4*)pc, sv = *(const f32x4*)ps; f32x4 pp;
; #pragma unroll
;                                 for (int e = 0; e < 4; ++e) pp[e] = xhalf_other(v0[e], hh);
;                                 v0 = hh ? (v0 * cv + pp * sv) : (v0 * cv - pp * sv); }
;                             {   const f32x4 cv = *(const f32x4*)(pc + 4), sv = *(const f32x4*)(ps + 4); f32x4 pp;
; #pragma unroll
;                                 for (int e = 0; e < 4; ++e) pp[e] = xhalf_other(v1[e], hh);
;                                 v1 = hh ? (v1 * cv + pp * sv) : (v1 * cv - pp * sv); }
;                         }
;                         u32x4 wv; wv.x = pk2(v0.x, v0.y); wv.y = pk2(v0.z, v0.w); wv.z = pk2(v1.x, v1.y); wv.w = pk2(v1.z, v1.w);
;                         *(u32x4*)(opaque(pb) + (size_t)(ai * 128 + m * 16) * 96) = wv;
;                         asm volatile("" ::: "memory");
;                     }
	v_ashrrev_i32_e32 v131, 31, v130
	v_lshlrev_b64 v[114:115], 6, v[130:131]
	v_lshl_add_u64 v[114:115], v[132:133], 0, v[114:115]
	s_mov_b64 s[18:19], 0x400
	v_lshl_add_u64 v[142:143], v[114:115], 0, s[18:19]
	v_mov_b32_e32 v115, s11
	v_subrev_co_u32_e32 v114, vcc, s10, v142
	v_mov_b32_e32 v131, v126
	s_nop 0
	v_subb_co_u32_e32 v115, vcc, v143, v115, vcc
	v_lshl_add_u64 v[144:145], s[12:13], 0, v[114:115]
	global_load_dwordx4 v[118:121], v[142:143], off
	global_load_dwordx4 v[114:117], v[144:145], off
	v_mov_b32_e32 v138, v126
	s_nop 1
	v_permlane32_swap_b32_e32 v131, v138
	v_cndmask_b32_e64 v138, v131, v138, s[4:5]
	v_mov_b32_e32 v131, v127
	v_mov_b32_e32 v139, v127
	s_nop 1
	v_permlane32_swap_b32_e32 v131, v139
	v_cndmask_b32_e64 v139, v131, v139, s[4:5]
	v_mov_b32_e32 v131, v124
	v_mov_b32_e32 v140, v124
	s_nop 1
	v_permlane32_swap_b32_e32 v131, v140
	v_cndmask_b32_e64 v140, v131, v140, s[4:5]
	v_mov_b32_e32 v131, v125
	v_mov_b32_e32 v141, v125
	s_nop 1
	v_permlane32_swap_b32_e32 v131, v141
	v_cndmask_b32_e64 v141, v131, v141, s[4:5]
	v_mov_b32_e32 v146, v136
	v_mov_b32_e32 v147, v137
	v_mov_b32_e32 v149, v128
	s_waitcnt vmcnt(0) lgkmcnt(0)
	v_pk_mul_f32 v[116:117], v[116:117], v[140:141]
	v_pk_mul_f32 v[114:115], v[114:115], v[138:139]
	v_xor_b32_e32 v131, 0x80000000, v116
	v_xor_b32_e32 v138, 0x80000000, v117
	v_xor_b32_e32 v140, 0x80000000, v114
	v_xor_b32_e32 v141, 0x80000000, v115
	v_cndmask_b32_e64 v139, v117, v138, s[4:5]
	v_cndmask_b32_e64 v138, v116, v131, s[4:5]
	v_cndmask_b32_e64 v141, v115, v141, s[4:5]
	v_cndmask_b32_e64 v140, v114, v140, s[4:5]
	global_load_dwordx4 v[114:117], v[142:143], off offset:16
	s_nop 0
	global_load_dwordx4 v[142:145], v[144:145], off offset:16
	v_mov_b32_e32 v131, v136
	s_nop 1
	v_permlane32_swap_b32_e32 v131, v146
	v_cndmask_b32_e64 v146, v131, v146, s[4:5]
	v_mov_b32_e32 v131, v137
	s_nop 1
	v_permlane32_swap_b32_e32 v131, v147
	v_cndmask_b32_e64 v147, v131, v147, s[4:5]
	v_mov_b32_e32 v131, v128
	s_nop 1
	v_permlane32_swap_b32_e32 v131, v149
	v_cndmask_b32_e64 v150, v131, v149, s[4:5]
	v_mov_b32_e32 v131, v129
	v_mov_b32_e32 v149, v129
	s_nop 1
	v_permlane32_swap_b32_e32 v131, v149
	v_cndmask_b32_e64 v151, v131, v149, s[4:5]
	v_pk_fma_f32 v[124:125], v[124:125], v[120:121], v[138:139]
	v_pk_fma_f32 v[126:127], v[126:127], v[118:119], v[140:141]
	s_waitcnt vmcnt(0) lgkmcnt(0)
	v_pk_mul_f32 v[118:119], v[144:145], v[150:151]
	v_pk_mul_f32 v[120:121], v[142:143], v[146:147]
	v_xor_b32_e32 v131, 0x80000000, v118
	v_xor_b32_e32 v138, 0x80000000, v119
	v_xor_b32_e32 v139, 0x80000000, v120
	v_xor_b32_e32 v140, 0x80000000, v121
	v_cndmask_b32_e64 v119, v119, v138, s[4:5]
	v_cndmask_b32_e64 v118, v118, v131, s[4:5]
	v_cndmask_b32_e64 v121, v121, v140, s[4:5]
	v_cndmask_b32_e64 v120, v120, v139, s[4:5]
	v_pk_fma_f32 v[128:129], v[128:129], v[116:117], v[118:119]
	v_pk_fma_f32 v[136:137], v[136:137], v[114:115], v[120:121]
.LBB0_597:
	v_cvt_pk_bf16_f32 v114, v126, v127
	v_cvt_pk_bf16_f32 v115, v124, v125
	v_cvt_pk_bf16_f32 v116, v136, v137
	v_cvt_pk_bf16_f32 v117, v128, v129
	v_mov_b64_e32 v[118:119], v[122:123]
	global_store_dwordx4 v[118:119], v[114:117], off offset:3072
	ds_read_b32 v114, v0 offset:128
	s_and_b64 vcc, exec, s[6:7]
	s_waitcnt lgkmcnt(0)
	v_mul_f32_e32 v118, 0x3e16c740, v114
	v_pk_mul_f32 v[116:117], v[112:113], v[118:119] op_sel_hi:[1,0]
	v_pk_mul_f32 v[120:121], v[110:111], v[118:119] op_sel_hi:[1,0]
	v_pk_mul_f32 v[114:115], v[108:109], v[118:119] op_sel_hi:[1,0]
	v_pk_mul_f32 v[118:119], v[106:107], v[118:119] op_sel_hi:[1,0]
	s_cbranch_vccnz .LBB0_599
	v_ashrrev_i32_e32 v131, 31, v130
	v_lshlrev_b64 v[106:107], 6, v[130:131]
	v_lshl_add_u64 v[106:107], v[132:133], 0, v[106:107]
	s_mov_b64 s[18:19], 0x800
	v_lshl_add_u64 v[128:129], v[106:107], 0, s[18:19]
	v_mov_b32_e32 v107, s11
	v_subrev_co_u32_e32 v106, vcc, s10, v128
	v_mov_b32_e32 v124, v120
	s_nop 0
	v_subb_co_u32_e32 v107, vcc, v129, v107, vcc
	v_lshl_add_u64 v[136:137], s[12:13], 0, v[106:107]
	global_load_dwordx4 v[110:113], v[128:129], off
	global_load_dwordx4 v[106:109], v[136:137], off
	v_mov_b32_e32 v125, v120
	s_nop 1
	v_permlane32_swap_b32_e32 v124, v125
	v_cndmask_b32_e64 v124, v124, v125, s[4:5]
	v_mov_b32_e32 v125, v121
	v_mov_b32_e32 v126, v121
	s_nop 1
	v_permlane32_swap_b32_e32 v125, v126
	v_cndmask_b32_e64 v125, v125, v126, s[4:5]
	v_mov_b32_e32 v126, v116
	v_mov_b32_e32 v127, v116
	s_nop 1
	v_permlane32_swap_b32_e32 v126, v127
	v_cndmask_b32_e64 v126, v126, v127, s[4:5]
	v_mov_b32_e32 v127, v117
	v_mov_b32_e32 v131, v117
	s_nop 1
	v_permlane32_swap_b32_e32 v127, v131
	v_cndmask_b32_e64 v127, v127, v131, s[4:5]
	v_mov_b32_e32 v131, v119
	v_mov_b32_e32 v140, v114
	v_mov_b32_e32 v141, v115
	s_waitcnt vmcnt(0) lgkmcnt(0)
	v_pk_mul_f32 v[108:109], v[108:109], v[126:127]
	v_pk_mul_f32 v[106:107], v[106:107], v[124:125]
	v_xor_b32_e32 v124, 0x80000000, v108
	v_xor_b32_e32 v125, 0x80000000, v109
	v_xor_b32_e32 v126, 0x80000000, v106
	v_xor_b32_e32 v127, 0x80000000, v107
	v_cndmask_b32_e64 v125, v109, v125, s[4:5]
	v_cndmask_b32_e64 v124, v108, v124, s[4:5]
	v_cndmask_b32_e64 v127, v107, v127, s[4:5]
	v_cndmask_b32_e64 v126, v106, v126, s[4:5]
	global_load_dwordx4 v[106:109], v[128:129], off offset:16
	s_nop 0
	global_load_dwordx4 v[136:139], v[136:137], off offset:16
	v_mov_b32_e32 v128, v118
	v_mov_b32_e32 v129, v118
	s_nop 1
	v_permlane32_swap_b32_e32 v128, v129
	v_cndmask_b32_e64 v128, v128, v129, s[4:5]
	v_mov_b32_e32 v129, v119
	s_nop 1
	v_permlane32_swap_b32_e32 v129, v131
	v_cndmask_b32_e64 v129, v129, v131, s[4:5]
	v_mov_b32_e32 v131, v114
	s_nop 1
	v_permlane32_swap_b32_e32 v131, v140
	v_cndmask_b32_e64 v140, v131, v140, s[4:5]
	v_mov_b32_e32 v131, v115
	s_nop 1
	v_permlane32_swap_b32_e32 v131, v141
	v_cndmask_b32_e64 v141, v131, v141, s[4:5]
	v_pk_fma_f32 v[116:117], v[116:117], v[112:113], v[124:125]
	v_pk_fma_f32 v[120:121], v[120:121], v[110:111], v[126:127]
	s_waitcnt vmcnt(0) lgkmcnt(0)
	v_pk_mul_f32 v[110:111], v[138:139], v[140:141]
	v_pk_mul_f32 v[112:113], v[136:137], v[128:129]
	v_xor_b32_e32 v124, 0x80000000, v110
	v_xor_b32_e32 v125, 0x80000000, v111
	v_xor_b32_e32 v126, 0x80000000, v112
	v_xor_b32_e32 v127, 0x80000000, v113
	v_cndmask_b32_e64 v111, v111, v125, s[4:5]
	v_cndmask_b32_e64 v110, v110, v124, s[4:5]
	v_cndmask_b32_e64 v113, v113, v127, s[4:5]
	v_cndmask_b32_e64 v112, v112, v126, s[4:5]
	v_pk_fma_f32 v[114:115], v[114:115], v[108:109], v[110:111]
	v_pk_fma_f32 v[118:119], v[118:119], v[106:107], v[112:113]
; DI unsigned pk2(float a, float b) { f32x2 v = {a, b}; return __builtin_bit_cast(unsigned, __builtin_convertvector(v, bf2_t)); }
; DI float xhalf_other(float x, int h) { auto r = __builtin_amdgcn_permlane32_swap(__float_as_uint(x), __float_as_uint(x), false, false); return h ? __uint_as_float(r[0]) : __uint_as_float(r[1]); }
; template <typename T> DI T* opaque(T* p) { asm volatile("" : "+v"(p) : : "memory"); return p; }
;     DI void operator()(const pg8::f32x4 (&acc)[2][2][4][2], const pg8::Unit& u, int wr, int wc, int fr, int fq) const {
;     ...
;                 for (int ai = 0; ai < 2; ++ai)
; #pragma unroll
;                     for (int m = 0; m < 4; ++m) {
;                         const int rl = ai * 128 + wr * 64 + m * 16 + fr;
;                         const float sc = rs[rl] * qs;
;                         f32x4 v0 = acc[ai][bj][m][0] * sc, v1 = acc[ai][bj][m][1] * sc;
;                         if (d0 == 64) {
;                             const float* pc = opaque(COS + (size_t)(rowb + ai * 128 + m * 16) * 16 + 8 * (fq & 1));
;                             const float* ps = SIN + (pc - COS);
;                             {   const f32x4 cv = *(const f32x4*)pc, sv = *(const f32x4*)ps; f32x4 pp;
; #pragma unroll
;                                 for (int e = 0; e < 4; ++e) pp[e] = xhalf_other(v0[e], hh);
;                                 v0 = hh ? (v0 * cv + pp * sv) : (v0 * cv - pp * sv); }
;                             {   const f32x4 cv = *(const f32x4*)(pc + 4), sv = *(const f32x4*)(ps + 4); f32x4 pp;
; #pragma unroll
;                                 for (int e = 0; e < 4; ++e) pp[e] = xhalf_other(v1[e], hh);
;                                 v1 = hh ? (v1 * cv + pp * sv) : (v1 * cv - pp * sv); }
;                         }
;                         u32x4 wv; wv.x = pk2(v0.x, v0.y); wv.y = pk2(v0.z, v0.w); wv.z = pk2(v1.x, v1.y); wv.w = pk2(v1.z, v1.w);
;                         *(u32x4*)(opaque(pb) + (size_t)(ai * 128 + m * 16) * 96) = wv;
;                         asm volatile("" ::: "memory");
;                     }
.LBB0_599:
	v_mov_b64_e32 v[110:111], v[122:123]
	v_cvt_pk_bf16_f32 v106, v120, v121
	v_add_co_u32_e32 v110, vcc, s90, v110
	v_cvt_pk_bf16_f32 v107, v116, v117
	v_cvt_pk_bf16_f32 v108, v118, v119
	v_cvt_pk_bf16_f32 v109, v114, v115
	v_addc_co_u32_e32 v111, vcc, 0, v111, vcc
	global_store_dwordx4 v[110:111], v[106:109], off offset:2048
	ds_read_b32 v106, v0 offset:192
	s_and_b64 vcc, exec, s[6:7]
	s_waitcnt lgkmcnt(0)
	v_mul_f32_e32 v112, 0x3e16c740, v106
	v_pk_mul_f32 v[106:107], v[104:105], v[112:113] op_sel_hi:[1,0]
	v_pk_mul_f32 v[108:109], v[102:103], v[112:113] op_sel_hi:[1,0]
	v_pk_mul_f32 v[110:111], v[100:101], v[112:113] op_sel_hi:[1,0]
	v_pk_mul_f32 v[112:113], v[98:99], v[112:113] op_sel_hi:[1,0]
	s_cbranch_vccnz .LBB0_601
	v_ashrrev_i32_e32 v131, 31, v130
	v_lshlrev_b64 v[98:99], 6, v[130:131]
	v_lshl_add_u64 v[98:99], v[132:133], 0, v[98:99]
	s_mov_b64 s[18:19], 0xc00
	v_lshl_add_u64 v[118:119], v[98:99], 0, s[18:19]
	v_mov_b32_e32 v99, s11
	v_subrev_co_u32_e32 v98, vcc, s10, v118
	v_mov_b32_e32 v114, v108
	s_nop 0
	v_subb_co_u32_e32 v99, vcc, v119, v99, vcc
	v_lshl_add_u64 v[120:121], s[12:13], 0, v[98:99]
	global_load_dwordx4 v[102:105], v[118:119], off
	global_load_dwordx4 v[98:101], v[120:121], off
	v_mov_b32_e32 v115, v108
	s_nop 1
	v_permlane32_swap_b32_e32 v114, v115
	v_cndmask_b32_e64 v114, v114, v115, s[4:5]
	v_mov_b32_e32 v115, v109
	v_mov_b32_e32 v116, v109
	s_nop 1
	v_permlane32_swap_b32_e32 v115, v116
	v_cndmask_b32_e64 v115, v115, v116, s[4:5]
	v_mov_b32_e32 v116, v106
	v_mov_b32_e32 v117, v106
	s_nop 1
	v_permlane32_swap_b32_e32 v116, v117
	v_cndmask_b32_e64 v116, v116, v117, s[4:5]
	v_mov_b32_e32 v117, v107
	v_mov_b32_e32 v124, v107
	s_nop 1
	v_permlane32_swap_b32_e32 v117, v124
	v_cndmask_b32_e64 v117, v117, v124, s[4:5]
	v_mov_b32_e32 v124, v112
	v_mov_b32_e32 v125, v112
	s_nop 1
	v_permlane32_swap_b32_e32 v124, v125
	v_cndmask_b32_e64 v124, v124, v125, s[4:5]
	v_mov_b32_e32 v125, v113
	v_mov_b32_e32 v126, v113
	s_nop 1
	v_permlane32_swap_b32_e32 v125, v126
	v_cndmask_b32_e64 v125, v125, v126, s[4:5]
	v_mov_b32_e32 v126, v110
	v_mov_b32_e32 v127, v110
	s_nop 1
	v_permlane32_swap_b32_e32 v126, v127
	v_cndmask_b32_e64 v126, v126, v127, s[4:5]
	v_mov_b32_e32 v127, v111
	v_mov_b32_e32 v128, v111
	s_nop 1
	v_permlane32_swap_b32_e32 v127, v128
	v_cndmask_b32_e64 v127, v127, v128, s[4:5]
	s_waitcnt vmcnt(0) lgkmcnt(0)
	v_pk_mul_f32 v[100:101], v[100:101], v[116:117]
	v_pk_mul_f32 v[98:99], v[98:99], v[114:115]
	v_xor_b32_e32 v114, 0x80000000, v100
	v_xor_b32_e32 v115, 0x80000000, v101
	v_xor_b32_e32 v116, 0x80000000, v98
	v_xor_b32_e32 v117, 0x80000000, v99
	v_cndmask_b32_e64 v115, v101, v115, s[4:5]
	v_cndmask_b32_e64 v114, v100, v114, s[4:5]
	v_cndmask_b32_e64 v117, v99, v117, s[4:5]
	v_cndmask_b32_e64 v116, v98, v116, s[4:5]
	global_load_dwordx4 v[98:101], v[118:119], off offset:16
	s_nop 0
	global_load_dwordx4 v[118:121], v[120:121], off offset:16
	v_pk_fma_f32 v[106:107], v[106:107], v[104:105], v[114:115]
	v_pk_fma_f32 v[108:109], v[108:109], v[102:103], v[116:117]
	s_waitcnt vmcnt(0) lgkmcnt(0)
	v_pk_mul_f32 v[102:103], v[120:121], v[126:127]
	v_pk_mul_f32 v[104:105], v[118:119], v[124:125]
	v_xor_b32_e32 v114, 0x80000000, v102
	v_xor_b32_e32 v115, 0x80000000, v103
	v_xor_b32_e32 v116, 0x80000000, v104
	v_xor_b32_e32 v117, 0x80000000, v105
	v_cndmask_b32_e64 v103, v103, v115, s[4:5]
	v_cndmask_b32_e64 v102, v102, v114, s[4:5]
	v_cndmask_b32_e64 v105, v105, v117, s[4:5]
	v_cndmask_b32_e64 v104, v104, v116, s[4:5]
	v_pk_fma_f32 v[110:111], v[110:111], v[100:101], v[102:103]
	v_pk_fma_f32 v[112:113], v[112:113], v[98:99], v[104:105]
.LBB0_601:
	v_mov_b64_e32 v[102:103], v[122:123]
	v_cvt_pk_bf16_f32 v98, v108, v109
	v_add_co_u32_e32 v102, vcc, s0, v102
	v_cvt_pk_bf16_f32 v99, v106, v107
	v_cvt_pk_bf16_f32 v100, v112, v113
	v_cvt_pk_bf16_f32 v101, v110, v111
	v_addc_co_u32_e32 v103, vcc, 0, v103, vcc
	global_store_dwordx4 v[102:103], v[98:101], off offset:1024
	ds_read_b32 v98, v0 offset:512
	s_and_b64 vcc, exec, s[6:7]
	s_waitcnt lgkmcnt(0)
	v_mul_f32_e32 v104, 0x3e16c740, v98
	v_pk_mul_f32 v[98:99], v[96:97], v[104:105] op_sel_hi:[1,0]
	v_pk_mul_f32 v[100:101], v[94:95], v[104:105] op_sel_hi:[1,0]
	v_pk_mul_f32 v[102:103], v[92:93], v[104:105] op_sel_hi:[1,0]
	v_pk_mul_f32 v[104:105], v[90:91], v[104:105] op_sel_hi:[1,0]
	s_cbranch_vccnz .LBB0_603
; DI unsigned pk2(float a, float b) { f32x2 v = {a, b}; return __builtin_bit_cast(unsigned, __builtin_convertvector(v, bf2_t)); }
; DI float xhalf_other(float x, int h) { auto r = __builtin_amdgcn_permlane32_swap(__float_as_uint(x), __float_as_uint(x), false, false); return h ? __uint_as_float(r[0]) : __uint_as_float(r[1]); }
; template <typename T> DI T* opaque(T* p) { asm volatile("" : "+v"(p) : : "memory"); return p; }
;     DI void operator()(const pg8::f32x4 (&acc)[2][2][4][2], const pg8::Unit& u, int wr, int wc, int fr, int fq) const {
;     ...
;                 for (int ai = 0; ai < 2; ++ai)
; #pragma unroll
;                     for (int m = 0; m < 4; ++m) {
;                         const int rl = ai * 128 + wr * 64 + m * 16 + fr;
;                         const float sc = rs[rl] * qs;
;                         f32x4 v0 = acc[ai][bj][m][0] * sc, v1 = acc[ai][bj][m][1] * sc;
;                         if (d0 == 64) {
;                             const float* pc = opaque(COS + (size_t)(rowb + ai * 128 + m * 16) * 16 + 8 * (fq & 1));
;                             const float* ps = SIN + (pc - COS);
;                             {   const f32x4 cv = *(const f32x4*)pc, sv = *(const f32x4*)ps; f32x4 pp;
; #pragma unroll
;                                 for (int e = 0; e < 4; ++e) pp[e] = xhalf_other(v0[e], hh);
;                                 v0 = hh ? (v0 * cv + pp * sv) : (v0 * cv - pp * sv); }
;                             {   const f32x4 cv = *(const f32x4*)(pc + 4), sv = *(const f32x4*)(ps + 4); f32x4 pp;
; #pragma unroll
;                                 for (int e = 0; e < 4; ++e) pp[e] = xhalf_other(v1[e], hh);
;                                 v1 = hh ? (v1 * cv + pp * sv) : (v1 * cv - pp * sv); }
;                         }
;                         u32x4 wv; wv.x = pk2(v0.x, v0.y); wv.y = pk2(v0.z, v0.w); wv.z = pk2(v1.x, v1.y); wv.w = pk2(v1.z, v1.w);
;                         *(u32x4*)(opaque(pb) + (size_t)(ai * 128 + m * 16) * 96) = wv;
;                         asm volatile("" ::: "memory");
;                     }
	v_ashrrev_i32_e32 v131, 31, v130
	v_lshlrev_b64 v[90:91], 6, v[130:131]
	v_lshl_add_u64 v[90:91], v[132:133], 0, v[90:91]
	v_lshl_add_u64 v[110:111], v[90:91], 0, s[42:43]
	v_mov_b32_e32 v91, s11
	v_subrev_co_u32_e32 v90, vcc, s10, v110
	v_mov_b32_e32 v106, v100
	s_nop 0
	v_subb_co_u32_e32 v91, vcc, v111, v91, vcc
	v_lshl_add_u64 v[112:113], s[12:13], 0, v[90:91]
	global_load_dwordx4 v[94:97], v[110:111], off
	global_load_dwordx4 v[90:93], v[112:113], off
	v_mov_b32_e32 v107, v100
	s_nop 1
	v_permlane32_swap_b32_e32 v106, v107
	v_cndmask_b32_e64 v106, v106, v107, s[4:5]
	v_mov_b32_e32 v107, v101
	v_mov_b32_e32 v108, v101
	s_nop 1
	v_permlane32_swap_b32_e32 v107, v108
	v_cndmask_b32_e64 v107, v107, v108, s[4:5]
	v_mov_b32_e32 v108, v98
	v_mov_b32_e32 v109, v98
	s_nop 1
	v_permlane32_swap_b32_e32 v108, v109
	v_cndmask_b32_e64 v108, v108, v109, s[4:5]
	v_mov_b32_e32 v109, v99
	v_mov_b32_e32 v114, v99
	s_nop 1
	v_permlane32_swap_b32_e32 v109, v114
	v_cndmask_b32_e64 v109, v109, v114, s[4:5]
	v_mov_b32_e32 v114, v104
	v_mov_b32_e32 v115, v104
	s_nop 1
	v_permlane32_swap_b32_e32 v114, v115
	v_cndmask_b32_e64 v114, v114, v115, s[4:5]
	v_mov_b32_e32 v115, v105
	v_mov_b32_e32 v116, v105
	s_nop 1
	v_permlane32_swap_b32_e32 v115, v116
	v_cndmask_b32_e64 v115, v115, v116, s[4:5]
	v_mov_b32_e32 v116, v102
	v_mov_b32_e32 v117, v102
	s_nop 1
	v_permlane32_swap_b32_e32 v116, v117
	v_cndmask_b32_e64 v116, v116, v117, s[4:5]
	v_mov_b32_e32 v117, v103
	v_mov_b32_e32 v118, v103
	s_nop 1
	v_permlane32_swap_b32_e32 v117, v118
	v_cndmask_b32_e64 v117, v117, v118, s[4:5]
	s_waitcnt vmcnt(0) lgkmcnt(0)
	v_pk_mul_f32 v[92:93], v[92:93], v[108:109]
	v_pk_mul_f32 v[90:91], v[90:91], v[106:107]
	v_xor_b32_e32 v106, 0x80000000, v92
	v_xor_b32_e32 v107, 0x80000000, v93
	v_xor_b32_e32 v108, 0x80000000, v90
	v_xor_b32_e32 v109, 0x80000000, v91
	v_cndmask_b32_e64 v107, v93, v107, s[4:5]
	v_cndmask_b32_e64 v106, v92, v106, s[4:5]
	v_cndmask_b32_e64 v109, v91, v109, s[4:5]
	v_cndmask_b32_e64 v108, v90, v108, s[4:5]
	global_load_dwordx4 v[90:93], v[110:111], off offset:16
	s_nop 0
	global_load_dwordx4 v[110:113], v[112:113], off offset:16
	v_pk_fma_f32 v[98:99], v[98:99], v[96:97], v[106:107]
	v_pk_fma_f32 v[100:101], v[100:101], v[94:95], v[108:109]
	s_waitcnt vmcnt(0) lgkmcnt(0)
	v_pk_mul_f32 v[94:95], v[112:113], v[116:117]
	v_pk_mul_f32 v[96:97], v[110:111], v[114:115]
	v_xor_b32_e32 v106, 0x80000000, v94
	v_xor_b32_e32 v107, 0x80000000, v95
	v_xor_b32_e32 v108, 0x80000000, v96
	v_xor_b32_e32 v109, 0x80000000, v97
	v_cndmask_b32_e64 v95, v95, v107, s[4:5]
	v_cndmask_b32_e64 v94, v94, v106, s[4:5]
	v_cndmask_b32_e64 v97, v97, v109, s[4:5]
	v_cndmask_b32_e64 v96, v96, v108, s[4:5]
	v_pk_fma_f32 v[102:103], v[102:103], v[92:93], v[94:95]
	v_pk_fma_f32 v[104:105], v[104:105], v[90:91], v[96:97]
.LBB0_603:
	v_mov_b64_e32 v[94:95], v[122:123]
	v_cvt_pk_bf16_f32 v90, v100, v101
	v_add_co_u32_e32 v94, vcc, s1, v94
	v_cvt_pk_bf16_f32 v91, v98, v99
	v_cvt_pk_bf16_f32 v92, v104, v105
	v_cvt_pk_bf16_f32 v93, v102, v103
	v_addc_co_u32_e32 v95, vcc, 0, v95, vcc
	global_store_dwordx4 v[94:95], v[90:93], off
	ds_read_b32 v90, v0 offset:576
	s_and_b64 vcc, exec, s[6:7]
	s_waitcnt lgkmcnt(0)
	v_mul_f32_e32 v96, 0x3e16c740, v90
	v_pk_mul_f32 v[90:91], v[88:89], v[96:97] op_sel_hi:[1,0]
	v_pk_mul_f32 v[92:93], v[86:87], v[96:97] op_sel_hi:[1,0]
	v_pk_mul_f32 v[94:95], v[84:85], v[96:97] op_sel_hi:[1,0]
	v_pk_mul_f32 v[96:97], v[82:83], v[96:97] op_sel_hi:[1,0]
	s_cbranch_vccnz .LBB0_605
	v_ashrrev_i32_e32 v131, 31, v130
	v_lshlrev_b64 v[82:83], 6, v[130:131]
	v_lshl_add_u64 v[82:83], v[132:133], 0, v[82:83]
	s_mov_b64 s[18:19], 0x2400
	v_lshl_add_u64 v[102:103], v[82:83], 0, s[18:19]
	v_mov_b32_e32 v83, s11
	v_subrev_co_u32_e32 v82, vcc, s10, v102
	v_mov_b32_e32 v98, v92
	s_nop 0
	v_subb_co_u32_e32 v83, vcc, v103, v83, vcc
	v_lshl_add_u64 v[104:105], s[12:13], 0, v[82:83]
	global_load_dwordx4 v[86:89], v[102:103], off
	global_load_dwordx4 v[82:85], v[104:105], off
	v_mov_b32_e32 v99, v92
	s_nop 1
	v_permlane32_swap_b32_e32 v98, v99
	v_cndmask_b32_e64 v98, v98, v99, s[4:5]
	v_mov_b32_e32 v99, v93
	v_mov_b32_e32 v100, v93
	s_nop 1
	v_permlane32_swap_b32_e32 v99, v100
	v_cndmask_b32_e64 v99, v99, v100, s[4:5]
	v_mov_b32_e32 v100, v90
	v_mov_b32_e32 v101, v90
	s_nop 1
	v_permlane32_swap_b32_e32 v100, v101
	v_cndmask_b32_e64 v100, v100, v101, s[4:5]
	v_mov_b32_e32 v101, v91
	v_mov_b32_e32 v106, v91
	s_nop 1
	v_permlane32_swap_b32_e32 v101, v106
	v_cndmask_b32_e64 v101, v101, v106, s[4:5]
	v_mov_b32_e32 v106, v96
	v_mov_b32_e32 v107, v96
	s_nop 1
	v_permlane32_swap_b32_e32 v106, v107
	v_cndmask_b32_e64 v106, v106, v107, s[4:5]
	v_mov_b32_e32 v107, v97
	v_mov_b32_e32 v108, v97
	s_nop 1
	v_permlane32_swap_b32_e32 v107, v108
	v_cndmask_b32_e64 v107, v107, v108, s[4:5]
	v_mov_b32_e32 v108, v94
	v_mov_b32_e32 v109, v94
	s_nop 1
	v_permlane32_swap_b32_e32 v108, v109
	v_cndmask_b32_e64 v108, v108, v109, s[4:5]
	v_mov_b32_e32 v109, v95
	v_mov_b32_e32 v110, v95
	s_nop 1
	v_permlane32_swap_b32_e32 v109, v110
	v_cndmask_b32_e64 v109, v109, v110, s[4:5]
	s_waitcnt vmcnt(0) lgkmcnt(0)
	v_pk_mul_f32 v[84:85], v[84:85], v[100:101]
	v_pk_mul_f32 v[82:83], v[82:83], v[98:99]
	v_xor_b32_e32 v98, 0x80000000, v84
	v_xor_b32_e32 v99, 0x80000000, v85
	v_xor_b32_e32 v100, 0x80000000, v82
	v_xor_b32_e32 v101, 0x80000000, v83
	v_cndmask_b32_e64 v99, v85, v99, s[4:5]
	v_cndmask_b32_e64 v98, v84, v98, s[4:5]
	v_cndmask_b32_e64 v101, v83, v101, s[4:5]
	v_cndmask_b32_e64 v100, v82, v100, s[4:5]
	global_load_dwordx4 v[82:85], v[102:103], off offset:16
	s_nop 0
	global_load_dwordx4 v[102:105], v[104:105], off offset:16
	v_pk_fma_f32 v[90:91], v[90:91], v[88:89], v[98:99]
	v_pk_fma_f32 v[92:93], v[92:93], v[86:87], v[100:101]
	s_waitcnt vmcnt(0) lgkmcnt(0)
	v_pk_mul_f32 v[86:87], v[104:105], v[108:109]
	v_pk_mul_f32 v[88:89], v[102:103], v[106:107]
	v_xor_b32_e32 v98, 0x80000000, v86
	v_xor_b32_e32 v99, 0x80000000, v87
	v_xor_b32_e32 v100, 0x80000000, v88
	v_xor_b32_e32 v101, 0x80000000, v89
	v_cndmask_b32_e64 v87, v87, v99, s[4:5]
	v_cndmask_b32_e64 v86, v86, v98, s[4:5]
	v_cndmask_b32_e64 v89, v89, v101, s[4:5]
	v_cndmask_b32_e64 v88, v88, v100, s[4:5]
	v_pk_fma_f32 v[94:95], v[94:95], v[84:85], v[86:87]
	v_pk_fma_f32 v[96:97], v[96:97], v[82:83], v[88:89]
; DI unsigned pk2(float a, float b) { f32x2 v = {a, b}; return __builtin_bit_cast(unsigned, __builtin_convertvector(v, bf2_t)); }
; DI float xhalf_other(float x, int h) { auto r = __builtin_amdgcn_permlane32_swap(__float_as_uint(x), __float_as_uint(x), false, false); return h ? __uint_as_float(r[0]) : __uint_as_float(r[1]); }
; template <typename T> DI T* opaque(T* p) { asm volatile("" : "+v"(p) : : "memory"); return p; }
;     DI void operator()(const pg8::f32x4 (&acc)[2][2][4][2], const pg8::Unit& u, int wr, int wc, int fr, int fq) const {
;     ...
;                 for (int ai = 0; ai < 2; ++ai)
; #pragma unroll
;                     for (int m = 0; m < 4; ++m) {
;                         const int rl = ai * 128 + wr * 64 + m * 16 + fr;
;                         const float sc = rs[rl] * qs;
;                         f32x4 v0 = acc[ai][bj][m][0] * sc, v1 = acc[ai][bj][m][1] * sc;
;                         if (d0 == 64) {
;                             const float* pc = opaque(COS + (size_t)(rowb + ai * 128 + m * 16) * 16 + 8 * (fq & 1));
;                             const float* ps = SIN + (pc - COS);
;                             {   const f32x4 cv = *(const f32x4*)pc, sv = *(const f32x4*)ps; f32x4 pp;
; #pragma unroll
;                                 for (int e = 0; e < 4; ++e) pp[e] = xhalf_other(v0[e], hh);
;                                 v0 = hh ? (v0 * cv + pp * sv) : (v0 * cv - pp * sv); }
;                             {   const f32x4 cv = *(const f32x4*)(pc + 4), sv = *(const f32x4*)(ps + 4); f32x4 pp;
; #pragma unroll
;                                 for (int e = 0; e < 4; ++e) pp[e] = xhalf_other(v1[e], hh);
;                                 v1 = hh ? (v1 * cv + pp * sv) : (v1 * cv - pp * sv); }
;                         }
;                         u32x4 wv; wv.x = pk2(v0.x, v0.y); wv.y = pk2(v0.z, v0.w); wv.z = pk2(v1.x, v1.y); wv.w = pk2(v1.z, v1.w);
;                         *(u32x4*)(opaque(pb) + (size_t)(ai * 128 + m * 16) * 96) = wv;
;                         asm volatile("" ::: "memory");
;                     }
.LBB0_605:
	v_mov_b64_e32 v[86:87], v[122:123]
	v_cvt_pk_bf16_f32 v82, v92, v93
	v_add_co_u32_e32 v86, vcc, s1, v86
	v_cvt_pk_bf16_f32 v83, v90, v91
	v_cvt_pk_bf16_f32 v84, v96, v97
	v_cvt_pk_bf16_f32 v85, v94, v95
	v_addc_co_u32_e32 v87, vcc, 0, v87, vcc
	global_store_dwordx4 v[86:87], v[82:85], off offset:3072
	ds_read_b32 v82, v0 offset:640
	s_and_b64 vcc, exec, s[6:7]
	s_waitcnt lgkmcnt(0)
	v_mul_f32_e32 v88, 0x3e16c740, v82
	v_pk_mul_f32 v[82:83], v[80:81], v[88:89] op_sel_hi:[1,0]
	v_pk_mul_f32 v[84:85], v[78:79], v[88:89] op_sel_hi:[1,0]
	v_pk_mul_f32 v[86:87], v[76:77], v[88:89] op_sel_hi:[1,0]
	v_pk_mul_f32 v[88:89], v[74:75], v[88:89] op_sel_hi:[1,0]
	s_cbranch_vccnz .LBB0_607
	v_ashrrev_i32_e32 v131, 31, v130
	v_lshlrev_b64 v[74:75], 6, v[130:131]
	v_lshl_add_u64 v[74:75], v[132:133], 0, v[74:75]
	s_mov_b64 s[18:19], 0x2800
	v_lshl_add_u64 v[94:95], v[74:75], 0, s[18:19]
	v_mov_b32_e32 v75, s11
	v_subrev_co_u32_e32 v74, vcc, s10, v94
	v_mov_b32_e32 v90, v84
	s_nop 0
	v_subb_co_u32_e32 v75, vcc, v95, v75, vcc
	v_lshl_add_u64 v[96:97], s[12:13], 0, v[74:75]
	global_load_dwordx4 v[78:81], v[94:95], off
	global_load_dwordx4 v[74:77], v[96:97], off
	v_mov_b32_e32 v91, v84
	s_nop 1
	v_permlane32_swap_b32_e32 v90, v91
	v_cndmask_b32_e64 v90, v90, v91, s[4:5]
	v_mov_b32_e32 v91, v85
	v_mov_b32_e32 v92, v85
	s_nop 1
	v_permlane32_swap_b32_e32 v91, v92
	v_cndmask_b32_e64 v91, v91, v92, s[4:5]
	v_mov_b32_e32 v92, v82
	v_mov_b32_e32 v93, v82
	s_nop 1
	v_permlane32_swap_b32_e32 v92, v93
	v_cndmask_b32_e64 v92, v92, v93, s[4:5]
	v_mov_b32_e32 v93, v83
	v_mov_b32_e32 v98, v83
	s_nop 1
	v_permlane32_swap_b32_e32 v93, v98
	v_cndmask_b32_e64 v93, v93, v98, s[4:5]
	v_mov_b32_e32 v98, v88
	v_mov_b32_e32 v99, v88
	s_nop 1
	v_permlane32_swap_b32_e32 v98, v99
	v_cndmask_b32_e64 v98, v98, v99, s[4:5]
	v_mov_b32_e32 v99, v89
	v_mov_b32_e32 v100, v89
	s_nop 1
	v_permlane32_swap_b32_e32 v99, v100
	v_cndmask_b32_e64 v99, v99, v100, s[4:5]
	v_mov_b32_e32 v100, v86
	v_mov_b32_e32 v101, v86
	s_nop 1
	v_permlane32_swap_b32_e32 v100, v101
	v_cndmask_b32_e64 v100, v100, v101, s[4:5]
	v_mov_b32_e32 v101, v87
	v_mov_b32_e32 v102, v87
	s_nop 1
	v_permlane32_swap_b32_e32 v101, v102
	v_cndmask_b32_e64 v101, v101, v102, s[4:5]
	s_waitcnt vmcnt(0) lgkmcnt(0)
	v_pk_mul_f32 v[76:77], v[76:77], v[92:93]
	v_pk_mul_f32 v[74:75], v[74:75], v[90:91]
	v_xor_b32_e32 v90, 0x80000000, v76
	v_xor_b32_e32 v91, 0x80000000, v77
	v_xor_b32_e32 v92, 0x80000000, v74
	v_xor_b32_e32 v93, 0x80000000, v75
	v_cndmask_b32_e64 v91, v77, v91, s[4:5]
	v_cndmask_b32_e64 v90, v76, v90, s[4:5]
	v_cndmask_b32_e64 v93, v75, v93, s[4:5]
	v_cndmask_b32_e64 v92, v74, v92, s[4:5]
	global_load_dwordx4 v[74:77], v[94:95], off offset:16
	s_nop 0
	global_load_dwordx4 v[94:97], v[96:97], off offset:16
	v_pk_fma_f32 v[82:83], v[82:83], v[80:81], v[90:91]
	v_pk_fma_f32 v[84:85], v[84:85], v[78:79], v[92:93]
	s_waitcnt vmcnt(0) lgkmcnt(0)
	v_pk_mul_f32 v[78:79], v[96:97], v[100:101]
	v_pk_mul_f32 v[80:81], v[94:95], v[98:99]
	v_xor_b32_e32 v90, 0x80000000, v78
	v_xor_b32_e32 v91, 0x80000000, v79
	v_xor_b32_e32 v92, 0x80000000, v80
	v_xor_b32_e32 v93, 0x80000000, v81
	v_cndmask_b32_e64 v79, v79, v91, s[4:5]
	v_cndmask_b32_e64 v78, v78, v90, s[4:5]
	v_cndmask_b32_e64 v81, v81, v93, s[4:5]
	v_cndmask_b32_e64 v80, v80, v92, s[4:5]
	v_pk_fma_f32 v[86:87], v[86:87], v[76:77], v[78:79]
	v_pk_fma_f32 v[88:89], v[88:89], v[74:75], v[80:81]
.LBB0_607:
	v_mov_b64_e32 v[78:79], v[122:123]
	s_movk_i32 s18, 0x7000
	v_add_co_u32_e32 v78, vcc, s18, v78
	v_cvt_pk_bf16_f32 v74, v84, v85
	v_cvt_pk_bf16_f32 v75, v82, v83
	v_cvt_pk_bf16_f32 v76, v88, v89
	v_cvt_pk_bf16_f32 v77, v86, v87
	v_addc_co_u32_e32 v79, vcc, 0, v79, vcc
	global_store_dwordx4 v[78:79], v[74:77], off offset:2048
	ds_read_b32 v74, v0 offset:704
	s_and_b64 vcc, exec, s[6:7]
	s_waitcnt lgkmcnt(0)
	v_mul_f32_e32 v80, 0x3e16c740, v74
	v_pk_mul_f32 v[74:75], v[72:73], v[80:81] op_sel_hi:[1,0]
	v_pk_mul_f32 v[76:77], v[70:71], v[80:81] op_sel_hi:[1,0]
	v_pk_mul_f32 v[78:79], v[68:69], v[80:81] op_sel_hi:[1,0]
	v_pk_mul_f32 v[80:81], v[66:67], v[80:81] op_sel_hi:[1,0]
	s_cbranch_vccnz .LBB0_609
	v_ashrrev_i32_e32 v131, 31, v130
	v_lshlrev_b64 v[66:67], 6, v[130:131]
	v_lshl_add_u64 v[66:67], v[132:133], 0, v[66:67]
	s_mov_b64 s[6:7], 0x2c00
	v_lshl_add_u64 v[86:87], v[66:67], 0, s[6:7]
	v_mov_b32_e32 v67, s11
	v_subrev_co_u32_e32 v66, vcc, s10, v86
	v_mov_b32_e32 v82, v76
	s_nop 0
	v_subb_co_u32_e32 v67, vcc, v87, v67, vcc
	v_lshl_add_u64 v[88:89], s[12:13], 0, v[66:67]
	global_load_dwordx4 v[70:73], v[86:87], off
	global_load_dwordx4 v[66:69], v[88:89], off
	v_mov_b32_e32 v83, v76
	s_nop 1
	v_permlane32_swap_b32_e32 v82, v83
	v_cndmask_b32_e64 v82, v82, v83, s[4:5]
	v_mov_b32_e32 v83, v77
	v_mov_b32_e32 v84, v77
	s_nop 1
	v_permlane32_swap_b32_e32 v83, v84
	v_cndmask_b32_e64 v83, v83, v84, s[4:5]
	v_mov_b32_e32 v84, v74
	v_mov_b32_e32 v85, v74
	s_nop 1
	v_permlane32_swap_b32_e32 v84, v85
	v_cndmask_b32_e64 v84, v84, v85, s[4:5]
	v_mov_b32_e32 v85, v75
	v_mov_b32_e32 v90, v75
	s_nop 1
	v_permlane32_swap_b32_e32 v85, v90
	v_cndmask_b32_e64 v85, v85, v90, s[4:5]
	v_mov_b32_e32 v90, v80
	v_mov_b32_e32 v91, v80
	s_nop 1
	v_permlane32_swap_b32_e32 v90, v91
	v_cndmask_b32_e64 v90, v90, v91, s[4:5]
	v_mov_b32_e32 v91, v81
	v_mov_b32_e32 v92, v81
	s_nop 1
	v_permlane32_swap_b32_e32 v91, v92
	v_cndmask_b32_e64 v91, v91, v92, s[4:5]
	v_mov_b32_e32 v92, v78
	v_mov_b32_e32 v93, v78
	s_nop 1
	v_permlane32_swap_b32_e32 v92, v93
	v_cndmask_b32_e64 v92, v92, v93, s[4:5]
	v_mov_b32_e32 v93, v79
	v_mov_b32_e32 v94, v79
	s_nop 1
	v_permlane32_swap_b32_e32 v93, v94
	v_cndmask_b32_e64 v93, v93, v94, s[4:5]
	s_waitcnt vmcnt(0) lgkmcnt(0)
	v_pk_mul_f32 v[68:69], v[68:69], v[84:85]
	v_pk_mul_f32 v[66:67], v[66:67], v[82:83]
	v_xor_b32_e32 v82, 0x80000000, v68
	v_xor_b32_e32 v83, 0x80000000, v69
	v_xor_b32_e32 v84, 0x80000000, v66
	v_xor_b32_e32 v85, 0x80000000, v67
	v_cndmask_b32_e64 v83, v69, v83, s[4:5]
	v_cndmask_b32_e64 v82, v68, v82, s[4:5]
	v_cndmask_b32_e64 v85, v67, v85, s[4:5]
	v_cndmask_b32_e64 v84, v66, v84, s[4:5]
	global_load_dwordx4 v[66:69], v[86:87], off offset:16
	s_nop 0
	global_load_dwordx4 v[86:89], v[88:89], off offset:16
	v_pk_fma_f32 v[74:75], v[74:75], v[72:73], v[82:83]
	v_pk_fma_f32 v[76:77], v[76:77], v[70:71], v[84:85]
	s_waitcnt vmcnt(0) lgkmcnt(0)
	v_pk_mul_f32 v[70:71], v[88:89], v[92:93]
	v_pk_mul_f32 v[72:73], v[86:87], v[90:91]
	v_xor_b32_e32 v82, 0x80000000, v70
	v_xor_b32_e32 v83, 0x80000000, v71
	v_xor_b32_e32 v84, 0x80000000, v72
	v_xor_b32_e32 v85, 0x80000000, v73
	v_cndmask_b32_e64 v71, v71, v83, s[4:5]
	v_cndmask_b32_e64 v70, v70, v82, s[4:5]
	v_cndmask_b32_e64 v73, v73, v85, s[4:5]
	v_cndmask_b32_e64 v72, v72, v84, s[4:5]
	v_pk_fma_f32 v[78:79], v[78:79], v[68:69], v[70:71]
	v_pk_fma_f32 v[80:81], v[80:81], v[66:67], v[72:73]
; DI unsigned pk2(float a, float b) { f32x2 v = {a, b}; return __builtin_bit_cast(unsigned, __builtin_convertvector(v, bf2_t)); }
; DI float xhalf_other(float x, int h) { auto r = __builtin_amdgcn_permlane32_swap(__float_as_uint(x), __float_as_uint(x), false, false); return h ? __uint_as_float(r[0]) : __uint_as_float(r[1]); }
; template <typename T> DI T* opaque(T* p) { asm volatile("" : "+v"(p) : : "memory"); return p; }
;     DI void operator()(const pg8::f32x4 (&acc)[2][2][4][2], const pg8::Unit& u, int wr, int wc, int fr, int fq) const {
;     ...
;         for (int bj = 0; bj < 2; ++bj) {
;             const int c0 = u.pn * 256 + bj * 128 + wc * 32;
;             if (c0 < 384) {
;                 const int head = c0 / 96, d0 = c0 - head * 96;
;                 bf16_t* pb = (bf16_t*)(ws + O_MQ) + ((size_t)(b * 4 + head) * S_ + s0) * 96 + d0 + 8 * fq;
;     ...
;                 for (int ai = 0; ai < 2; ++ai)
; #pragma unroll
;                     for (int m = 0; m < 4; ++m) {
;                         const int rl = ai * 128 + wr * 64 + m * 16 + fr;
;                         const float sc = rs[rl] * qs;
;                         f32x4 v0 = acc[ai][bj][m][0] * sc, v1 = acc[ai][bj][m][1] * sc;
;                         if (d0 == 64) {
;                             const float* pc = opaque(COS + (size_t)(rowb + ai * 128 + m * 16) * 16 + 8 * (fq & 1));
;                             const float* ps = SIN + (pc - COS);
;                             {   const f32x4 cv = *(const f32x4*)pc, sv = *(const f32x4*)ps; f32x4 pp;
; #pragma unroll
;                                 for (int e = 0; e < 4; ++e) pp[e] = xhalf_other(v0[e], hh);
;                                 v0 = hh ? (v0 * cv + pp * sv) : (v0 * cv - pp * sv); }
;                             {   const f32x4 cv = *(const f32x4*)(pc + 4), sv = *(const f32x4*)(ps + 4); f32x4 pp;
; #pragma unroll
;                                 for (int e = 0; e < 4; ++e) pp[e] = xhalf_other(v1[e], hh);
;                                 v1 = hh ? (v1 * cv + pp * sv) : (v1 * cv - pp * sv); }
;                         }
;                         u32x4 wv; wv.x = pk2(v0.x, v0.y); wv.y = pk2(v0.z, v0.w); wv.z = pk2(v1.x, v1.y); wv.w = pk2(v1.z, v1.w);
;                         *(u32x4*)(opaque(pb) + (size_t)(ai * 128 + m * 16) * 96) = wv;
;                         asm volatile("" ::: "memory");
;                     }
.LBB0_609:
	v_cvt_pk_bf16_f32 v66, v76, v77
	v_add_co_u32_e32 v70, vcc, 0x8000, v122
	v_cvt_pk_bf16_f32 v67, v74, v75
	v_cvt_pk_bf16_f32 v68, v80, v81
	v_cvt_pk_bf16_f32 v69, v78, v79
	v_addc_co_u32_e32 v71, vcc, 0, v123, vcc
	global_store_dwordx4 v[70:71], v[66:69], off offset:1024
.LBB0_610:
	s_or_b32 s6, s3, 0x80
	s_cmpk_gt_i32 s6, 0x17f
	s_cbranch_scc1 .LBB0_628
	s_mul_hi_i32 s3, s6, 0x2aaaaaab
	s_waitcnt vmcnt(0)
	ds_read_b32 v66, v0
	s_lshr_b32 s7, s3, 31
	s_ashr_i32 s3, s3, 4
	s_add_i32 s3, s3, s7
	s_mul_i32 s7, s3, 0xffffffa0
	s_add_i32 s6, s7, s6
	s_cmp_eq_u32 s6, 64
	s_waitcnt lgkmcnt(0)
	v_mul_f32_e32 v72, 0x3e16c740, v66
	s_cselect_b64 s[18:19], -1, 0
	s_cmp_lg_u32 s6, 64
	v_pk_mul_f32 v[66:67], v[64:65], v[72:73] op_sel_hi:[1,0]
	v_pk_mul_f32 v[68:69], v[62:63], v[72:73] op_sel_hi:[1,0]
	v_pk_mul_f32 v[70:71], v[60:61], v[72:73] op_sel_hi:[1,0]
	v_pk_mul_f32 v[72:73], v[58:59], v[72:73] op_sel_hi:[1,0]
	v_ashrrev_i32_e32 v131, 31, v130
	s_cbranch_scc1 .LBB0_613
	v_lshlrev_b64 v[58:59], 6, v[130:131]
	v_lshl_add_u64 v[78:79], v[132:133], 0, v[58:59]
	v_mov_b32_e32 v59, s11
	v_subrev_co_u32_e32 v58, vcc, s10, v78
	v_mov_b32_e32 v74, v68
	s_nop 0
	v_subb_co_u32_e32 v59, vcc, v79, v59, vcc
	v_lshl_add_u64 v[80:81], s[12:13], 0, v[58:59]
	global_load_dwordx4 v[62:65], v[78:79], off
	global_load_dwordx4 v[58:61], v[80:81], off
	v_mov_b32_e32 v75, v68
	s_nop 1
	v_permlane32_swap_b32_e32 v74, v75
	v_cndmask_b32_e64 v74, v74, v75, s[4:5]
	v_mov_b32_e32 v75, v69
	v_mov_b32_e32 v76, v69
	s_nop 1
	v_permlane32_swap_b32_e32 v75, v76
	v_cndmask_b32_e64 v75, v75, v76, s[4:5]
	v_mov_b32_e32 v76, v66
	v_mov_b32_e32 v77, v66
	s_nop 1
	v_permlane32_swap_b32_e32 v76, v77
	v_cndmask_b32_e64 v76, v76, v77, s[4:5]
	v_mov_b32_e32 v77, v67
	v_mov_b32_e32 v82, v67
	s_nop 1
	v_permlane32_swap_b32_e32 v77, v82
	v_cndmask_b32_e64 v77, v77, v82, s[4:5]
	v_mov_b32_e32 v82, v72
	v_mov_b32_e32 v83, v72
	s_nop 1
	v_permlane32_swap_b32_e32 v82, v83
	v_cndmask_b32_e64 v82, v82, v83, s[4:5]
	v_mov_b32_e32 v83, v73
	v_mov_b32_e32 v84, v73
	s_nop 1
	v_permlane32_swap_b32_e32 v83, v84
	v_cndmask_b32_e64 v83, v83, v84, s[4:5]
	v_mov_b32_e32 v84, v70
	v_mov_b32_e32 v85, v70
	s_nop 1
	v_permlane32_swap_b32_e32 v84, v85
	v_cndmask_b32_e64 v84, v84, v85, s[4:5]
	v_mov_b32_e32 v85, v71
	v_mov_b32_e32 v86, v71
	s_nop 1
	v_permlane32_swap_b32_e32 v85, v86
	v_cndmask_b32_e64 v85, v85, v86, s[4:5]
	s_waitcnt vmcnt(0) lgkmcnt(0)
	v_pk_mul_f32 v[60:61], v[60:61], v[76:77]
	v_pk_mul_f32 v[58:59], v[58:59], v[74:75]
	v_xor_b32_e32 v74, 0x80000000, v60
	v_xor_b32_e32 v75, 0x80000000, v61
	v_xor_b32_e32 v76, 0x80000000, v58
	v_xor_b32_e32 v77, 0x80000000, v59
	v_cndmask_b32_e64 v75, v61, v75, s[4:5]
	v_cndmask_b32_e64 v74, v60, v74, s[4:5]
	v_cndmask_b32_e64 v77, v59, v77, s[4:5]
	v_cndmask_b32_e64 v76, v58, v76, s[4:5]
	global_load_dwordx4 v[58:61], v[78:79], off offset:16
	s_nop 0
	global_load_dwordx4 v[78:81], v[80:81], off offset:16
	v_pk_fma_f32 v[66:67], v[66:67], v[64:65], v[74:75]
	v_pk_fma_f32 v[68:69], v[68:69], v[62:63], v[76:77]
	s_waitcnt vmcnt(0) lgkmcnt(0)
	v_pk_mul_f32 v[62:63], v[80:81], v[84:85]
	v_pk_mul_f32 v[64:65], v[78:79], v[82:83]
	v_xor_b32_e32 v74, 0x80000000, v62
	v_xor_b32_e32 v75, 0x80000000, v63
	v_xor_b32_e32 v76, 0x80000000, v64
	v_xor_b32_e32 v77, 0x80000000, v65
	v_cndmask_b32_e64 v63, v63, v75, s[4:5]
	v_cndmask_b32_e64 v62, v62, v74, s[4:5]
	v_cndmask_b32_e64 v65, v65, v77, s[4:5]
	v_cndmask_b32_e64 v64, v64, v76, s[4:5]
	v_pk_fma_f32 v[70:71], v[70:71], v[60:61], v[62:63]
	v_pk_fma_f32 v[72:73], v[72:73], v[58:59], v[64:65]
.LBB0_613:
	s_add_i32 s20, s3, s40
	s_ashr_i32 s21, s20, 31
	s_lshl_b64 s[20:21], s[20:21], 13
	v_or_b32_e32 v60, s20, v148
	v_mov_b64_e32 v[58:59], s[14:15]
	v_mad_u64_u32 v[58:59], s[22:23], v60, s79, v[58:59]
	v_mad_i32_i24 v59, s21, v227, v59
	s_ashr_i32 s7, s6, 31
	v_lshl_add_u64 v[58:59], s[6:7], 1, v[58:59]
	v_lshl_add_u64 v[58:59], v[134:135], 1, v[58:59]
	v_cvt_pk_bf16_f32 v60, v68, v69
	v_cvt_pk_bf16_f32 v61, v66, v67
	v_cvt_pk_bf16_f32 v62, v72, v73
	v_cvt_pk_bf16_f32 v63, v70, v71
	v_mov_b64_e32 v[64:65], v[58:59]
	global_store_dwordx4 v[64:65], v[60:63], off
	ds_read_b32 v60, v0 offset:64
	s_andn2_b64 vcc, exec, s[18:19]
	s_waitcnt lgkmcnt(0)
	v_mul_f32_e32 v66, 0x3e16c740, v60
	v_pk_mul_f32 v[64:65], v[52:53], v[66:67] op_sel_hi:[1,0]
	v_cndmask_b32_e64 v52, 0, 1, s[18:19]
	v_pk_mul_f32 v[60:61], v[56:57], v[66:67] op_sel_hi:[1,0]
	v_pk_mul_f32 v[62:63], v[54:55], v[66:67] op_sel_hi:[1,0]
	v_cmp_ne_u32_e64 s[6:7], 1, v52
	v_pk_mul_f32 v[66:67], v[50:51], v[66:67] op_sel_hi:[1,0]
	s_cbranch_vccnz .LBB0_615
; DI unsigned pk2(float a, float b) { f32x2 v = {a, b}; return __builtin_bit_cast(unsigned, __builtin_convertvector(v, bf2_t)); }
; DI float xhalf_other(float x, int h) { auto r = __builtin_amdgcn_permlane32_swap(__float_as_uint(x), __float_as_uint(x), false, false); return h ? __uint_as_float(r[0]) : __uint_as_float(r[1]); }
; template <typename T> DI T* opaque(T* p) { asm volatile("" : "+v"(p) : : "memory"); return p; }
;     DI void operator()(const pg8::f32x4 (&acc)[2][2][4][2], const pg8::Unit& u, int wr, int wc, int fr, int fq) const {
;     ...
;                 for (int ai = 0; ai < 2; ++ai)
; #pragma unroll
;                     for (int m = 0; m < 4; ++m) {
;                         const int rl = ai * 128 + wr * 64 + m * 16 + fr;
;                         const float sc = rs[rl] * qs;
;                         f32x4 v0 = acc[ai][bj][m][0] * sc, v1 = acc[ai][bj][m][1] * sc;
;                         if (d0 == 64) {
;                             const float* pc = opaque(COS + (size_t)(rowb + ai * 128 + m * 16) * 16 + 8 * (fq & 1));
;                             const float* ps = SIN + (pc - COS);
;                             {   const f32x4 cv = *(const f32x4*)pc, sv = *(const f32x4*)ps; f32x4 pp;
; #pragma unroll
;                                 for (int e = 0; e < 4; ++e) pp[e] = xhalf_other(v0[e], hh);
;                                 v0 = hh ? (v0 * cv + pp * sv) : (v0 * cv - pp * sv); }
;                             {   const f32x4 cv = *(const f32x4*)(pc + 4), sv = *(const f32x4*)(ps + 4); f32x4 pp;
; #pragma unroll
;                                 for (int e = 0; e < 4; ++e) pp[e] = xhalf_other(v1[e], hh);
;                                 v1 = hh ? (v1 * cv + pp * sv) : (v1 * cv - pp * sv); }
;                         }
;                         u32x4 wv; wv.x = pk2(v0.x, v0.y); wv.y = pk2(v0.z, v0.w); wv.z = pk2(v1.x, v1.y); wv.w = pk2(v1.z, v1.w);
;                         *(u32x4*)(opaque(pb) + (size_t)(ai * 128 + m * 16) * 96) = wv;
;                         asm volatile("" ::: "memory");
;                     }
	v_lshlrev_b64 v[50:51], 6, v[130:131]
	v_lshl_add_u64 v[50:51], v[132:133], 0, v[50:51]
	s_mov_b64 s[18:19], 0x400
	v_lshl_add_u64 v[72:73], v[50:51], 0, s[18:19]
	v_mov_b32_e32 v51, s11
	v_subrev_co_u32_e32 v50, vcc, s10, v72
	v_mov_b32_e32 v68, v62
	s_nop 0
	v_subb_co_u32_e32 v51, vcc, v73, v51, vcc
	v_lshl_add_u64 v[74:75], s[12:13], 0, v[50:51]
	global_load_dwordx4 v[54:57], v[72:73], off
	global_load_dwordx4 v[50:53], v[74:75], off
	v_mov_b32_e32 v69, v62
	s_nop 1
	v_permlane32_swap_b32_e32 v68, v69
	v_cndmask_b32_e64 v68, v68, v69, s[4:5]
	v_mov_b32_e32 v69, v63
	v_mov_b32_e32 v70, v63
	s_nop 1
	v_permlane32_swap_b32_e32 v69, v70
	v_cndmask_b32_e64 v69, v69, v70, s[4:5]
	v_mov_b32_e32 v70, v60
	v_mov_b32_e32 v71, v60
	s_nop 1
	v_permlane32_swap_b32_e32 v70, v71
	v_cndmask_b32_e64 v70, v70, v71, s[4:5]
	v_mov_b32_e32 v71, v61
	v_mov_b32_e32 v76, v61
	s_nop 1
	v_permlane32_swap_b32_e32 v71, v76
	v_cndmask_b32_e64 v71, v71, v76, s[4:5]
	v_mov_b32_e32 v76, v66
	v_mov_b32_e32 v77, v66
	s_nop 1
	v_permlane32_swap_b32_e32 v76, v77
	v_cndmask_b32_e64 v76, v76, v77, s[4:5]
	v_mov_b32_e32 v77, v67
	v_mov_b32_e32 v78, v67
	s_nop 1
	v_permlane32_swap_b32_e32 v77, v78
	v_cndmask_b32_e64 v77, v77, v78, s[4:5]
	v_mov_b32_e32 v78, v64
	v_mov_b32_e32 v79, v64
	s_nop 1
	v_permlane32_swap_b32_e32 v78, v79
	v_cndmask_b32_e64 v78, v78, v79, s[4:5]
	v_mov_b32_e32 v79, v65
	v_mov_b32_e32 v80, v65
	s_nop 1
	v_permlane32_swap_b32_e32 v79, v80
	v_cndmask_b32_e64 v79, v79, v80, s[4:5]
	s_waitcnt vmcnt(0) lgkmcnt(0)
	v_pk_mul_f32 v[52:53], v[52:53], v[70:71]
	v_pk_mul_f32 v[50:51], v[50:51], v[68:69]
	v_xor_b32_e32 v68, 0x80000000, v52
	v_xor_b32_e32 v69, 0x80000000, v53
	v_xor_b32_e32 v70, 0x80000000, v50
	v_xor_b32_e32 v71, 0x80000000, v51
	v_cndmask_b32_e64 v69, v53, v69, s[4:5]
	v_cndmask_b32_e64 v68, v52, v68, s[4:5]
	v_cndmask_b32_e64 v71, v51, v71, s[4:5]
	v_cndmask_b32_e64 v70, v50, v70, s[4:5]
	global_load_dwordx4 v[50:53], v[72:73], off offset:16
	s_nop 0
	global_load_dwordx4 v[72:75], v[74:75], off offset:16
	v_pk_fma_f32 v[60:61], v[60:61], v[56:57], v[68:69]
	v_pk_fma_f32 v[62:63], v[62:63], v[54:55], v[70:71]
	s_waitcnt vmcnt(0) lgkmcnt(0)
	v_pk_mul_f32 v[54:55], v[74:75], v[78:79]
	v_pk_mul_f32 v[56:57], v[72:73], v[76:77]
	v_xor_b32_e32 v68, 0x80000000, v54
	v_xor_b32_e32 v69, 0x80000000, v55
	v_xor_b32_e32 v70, 0x80000000, v56
	v_xor_b32_e32 v71, 0x80000000, v57
	v_cndmask_b32_e64 v55, v55, v69, s[4:5]
	v_cndmask_b32_e64 v54, v54, v68, s[4:5]
	v_cndmask_b32_e64 v57, v57, v71, s[4:5]
	v_cndmask_b32_e64 v56, v56, v70, s[4:5]
	v_pk_fma_f32 v[64:65], v[64:65], v[52:53], v[54:55]
	v_pk_fma_f32 v[66:67], v[66:67], v[50:51], v[56:57]
.LBB0_615:
	v_cvt_pk_bf16_f32 v50, v62, v63
	v_cvt_pk_bf16_f32 v51, v60, v61
	v_cvt_pk_bf16_f32 v52, v66, v67
	v_cvt_pk_bf16_f32 v53, v64, v65
	v_mov_b64_e32 v[54:55], v[58:59]
	global_store_dwordx4 v[54:55], v[50:53], off offset:3072
	ds_read_b32 v50, v0 offset:128
	s_and_b64 vcc, exec, s[6:7]
	s_waitcnt lgkmcnt(0)
	v_mul_f32_e32 v54, 0x3e16c740, v50
	v_pk_mul_f32 v[52:53], v[48:49], v[54:55] op_sel_hi:[1,0]
	v_pk_mul_f32 v[56:57], v[46:47], v[54:55] op_sel_hi:[1,0]
	v_pk_mul_f32 v[50:51], v[44:45], v[54:55] op_sel_hi:[1,0]
	v_pk_mul_f32 v[54:55], v[42:43], v[54:55] op_sel_hi:[1,0]
	s_cbranch_vccnz .LBB0_617
	v_lshlrev_b64 v[42:43], 6, v[130:131]
	v_lshl_add_u64 v[42:43], v[132:133], 0, v[42:43]
	s_mov_b64 s[18:19], 0x800
	v_lshl_add_u64 v[64:65], v[42:43], 0, s[18:19]
	v_mov_b32_e32 v43, s11
	v_subrev_co_u32_e32 v42, vcc, s10, v64
	v_mov_b32_e32 v60, v56
	s_nop 0
	v_subb_co_u32_e32 v43, vcc, v65, v43, vcc
	v_lshl_add_u64 v[66:67], s[12:13], 0, v[42:43]
	global_load_dwordx4 v[46:49], v[64:65], off
	global_load_dwordx4 v[42:45], v[66:67], off
	v_mov_b32_e32 v61, v56
	s_nop 1
	v_permlane32_swap_b32_e32 v60, v61
	v_cndmask_b32_e64 v60, v60, v61, s[4:5]
	v_mov_b32_e32 v61, v57
	v_mov_b32_e32 v62, v57
	s_nop 1
	v_permlane32_swap_b32_e32 v61, v62
	v_cndmask_b32_e64 v61, v61, v62, s[4:5]
	v_mov_b32_e32 v62, v52
	v_mov_b32_e32 v63, v52
	s_nop 1
	v_permlane32_swap_b32_e32 v62, v63
	v_cndmask_b32_e64 v62, v62, v63, s[4:5]
	v_mov_b32_e32 v63, v53
	v_mov_b32_e32 v68, v53
	s_nop 1
	v_permlane32_swap_b32_e32 v63, v68
	v_cndmask_b32_e64 v63, v63, v68, s[4:5]
	v_mov_b32_e32 v68, v54
	v_mov_b32_e32 v69, v54
	s_nop 1
	v_permlane32_swap_b32_e32 v68, v69
	v_cndmask_b32_e64 v68, v68, v69, s[4:5]
	v_mov_b32_e32 v69, v55
	v_mov_b32_e32 v70, v55
	s_nop 1
	v_permlane32_swap_b32_e32 v69, v70
	v_cndmask_b32_e64 v69, v69, v70, s[4:5]
	v_mov_b32_e32 v70, v50
	v_mov_b32_e32 v71, v50
	s_nop 1
	v_permlane32_swap_b32_e32 v70, v71
	v_cndmask_b32_e64 v70, v70, v71, s[4:5]
	v_mov_b32_e32 v71, v51
	v_mov_b32_e32 v72, v51
	s_nop 1
	v_permlane32_swap_b32_e32 v71, v72
	v_cndmask_b32_e64 v71, v71, v72, s[4:5]
	s_waitcnt vmcnt(0) lgkmcnt(0)
	v_pk_mul_f32 v[44:45], v[44:45], v[62:63]
	v_pk_mul_f32 v[42:43], v[42:43], v[60:61]
	v_xor_b32_e32 v60, 0x80000000, v44
	v_xor_b32_e32 v61, 0x80000000, v45
	v_xor_b32_e32 v62, 0x80000000, v42
	v_xor_b32_e32 v63, 0x80000000, v43
	v_cndmask_b32_e64 v61, v45, v61, s[4:5]
	v_cndmask_b32_e64 v60, v44, v60, s[4:5]
	v_cndmask_b32_e64 v63, v43, v63, s[4:5]
	v_cndmask_b32_e64 v62, v42, v62, s[4:5]
	global_load_dwordx4 v[42:45], v[64:65], off offset:16
	s_nop 0
	global_load_dwordx4 v[64:67], v[66:67], off offset:16
	v_pk_fma_f32 v[52:53], v[52:53], v[48:49], v[60:61]
	v_pk_fma_f32 v[56:57], v[56:57], v[46:47], v[62:63]
	s_waitcnt vmcnt(0) lgkmcnt(0)
	v_pk_mul_f32 v[46:47], v[66:67], v[70:71]
	v_pk_mul_f32 v[48:49], v[64:65], v[68:69]
	v_xor_b32_e32 v60, 0x80000000, v46
	v_xor_b32_e32 v61, 0x80000000, v47
	v_xor_b32_e32 v62, 0x80000000, v48
	v_xor_b32_e32 v63, 0x80000000, v49
	v_cndmask_b32_e64 v47, v47, v61, s[4:5]
	v_cndmask_b32_e64 v46, v46, v60, s[4:5]
	v_cndmask_b32_e64 v49, v49, v63, s[4:5]
	v_cndmask_b32_e64 v48, v48, v62, s[4:5]
	v_pk_fma_f32 v[50:51], v[50:51], v[44:45], v[46:47]
	v_pk_fma_f32 v[54:55], v[54:55], v[42:43], v[48:49]
; DI unsigned pk2(float a, float b) { f32x2 v = {a, b}; return __builtin_bit_cast(unsigned, __builtin_convertvector(v, bf2_t)); }
; DI float xhalf_other(float x, int h) { auto r = __builtin_amdgcn_permlane32_swap(__float_as_uint(x), __float_as_uint(x), false, false); return h ? __uint_as_float(r[0]) : __uint_as_float(r[1]); }
; template <typename T> DI T* opaque(T* p) { asm volatile("" : "+v"(p) : : "memory"); return p; }
;     DI void operator()(const pg8::f32x4 (&acc)[2][2][4][2], const pg8::Unit& u, int wr, int wc, int fr, int fq) const {
;     ...
;                     for (int m = 0; m < 4; ++m) {
;                         const int rl = ai * 128 + wr * 64 + m * 16 + fr;
;                         const float sc = rs[rl] * qs;
;                         f32x4 v0 = acc[ai][bj][m][0] * sc, v1 = acc[ai][bj][m][1] * sc;
;                         if (d0 == 64) {
;                             const float* pc = opaque(COS + (size_t)(rowb + ai * 128 + m * 16) * 16 + 8 * (fq & 1));
;                             const float* ps = SIN + (pc - COS);
;                             {   const f32x4 cv = *(const f32x4*)pc, sv = *(const f32x4*)ps; f32x4 pp;
; #pragma unroll
;                                 for (int e = 0; e < 4; ++e) pp[e] = xhalf_other(v0[e], hh);
;                                 v0 = hh ? (v0 * cv + pp * sv) : (v0 * cv - pp * sv); }
;                             {   const f32x4 cv = *(const f32x4*)(pc + 4), sv = *(const f32x4*)(ps + 4); f32x4 pp;
; #pragma unroll
;                                 for (int e = 0; e < 4; ++e) pp[e] = xhalf_other(v1[e], hh);
;                                 v1 = hh ? (v1 * cv + pp * sv) : (v1 * cv - pp * sv); }
;                         }
;                         u32x4 wv; wv.x = pk2(v0.x, v0.y); wv.y = pk2(v0.z, v0.w); wv.z = pk2(v1.x, v1.y); wv.w = pk2(v1.z, v1.w);
;                         *(u32x4*)(opaque(pb) + (size_t)(ai * 128 + m * 16) * 96) = wv;
.LBB0_617:
	v_mov_b64_e32 v[46:47], v[58:59]
	v_cvt_pk_bf16_f32 v42, v56, v57
	v_add_co_u32_e32 v46, vcc, s90, v46
	v_cvt_pk_bf16_f32 v43, v52, v53
	v_cvt_pk_bf16_f32 v44, v54, v55
	v_cvt_pk_bf16_f32 v45, v50, v51
	v_addc_co_u32_e32 v47, vcc, 0, v47, vcc
	global_store_dwordx4 v[46:47], v[42:45], off offset:2048
	ds_read_b32 v42, v0 offset:192
	s_and_b64 vcc, exec, s[6:7]
	s_waitcnt lgkmcnt(0)
	v_mul_f32_e32 v48, 0x3e16c740, v42
	v_pk_mul_f32 v[42:43], v[40:41], v[48:49] op_sel_hi:[1,0]
	v_pk_mul_f32 v[44:45], v[38:39], v[48:49] op_sel_hi:[1,0]
	v_pk_mul_f32 v[46:47], v[36:37], v[48:49] op_sel_hi:[1,0]
	v_pk_mul_f32 v[48:49], v[34:35], v[48:49] op_sel_hi:[1,0]
	s_cbranch_vccnz .LBB0_619
	v_lshlrev_b64 v[34:35], 6, v[130:131]
	v_lshl_add_u64 v[34:35], v[132:133], 0, v[34:35]
	s_mov_b64 s[18:19], 0xc00
	v_lshl_add_u64 v[54:55], v[34:35], 0, s[18:19]
	v_mov_b32_e32 v35, s11
	v_subrev_co_u32_e32 v34, vcc, s10, v54
	v_mov_b32_e32 v50, v44
	s_nop 0
	v_subb_co_u32_e32 v35, vcc, v55, v35, vcc
	v_lshl_add_u64 v[56:57], s[12:13], 0, v[34:35]
	global_load_dwordx4 v[38:41], v[54:55], off
	global_load_dwordx4 v[34:37], v[56:57], off
	v_mov_b32_e32 v51, v44
	s_nop 1
	v_permlane32_swap_b32_e32 v50, v51
	v_cndmask_b32_e64 v50, v50, v51, s[4:5]
	v_mov_b32_e32 v51, v45
	v_mov_b32_e32 v52, v45
	s_nop 1
	v_permlane32_swap_b32_e32 v51, v52
	v_cndmask_b32_e64 v51, v51, v52, s[4:5]
	v_mov_b32_e32 v52, v42
	v_mov_b32_e32 v53, v42
	s_nop 1
	v_permlane32_swap_b32_e32 v52, v53
	v_cndmask_b32_e64 v52, v52, v53, s[4:5]
	v_mov_b32_e32 v53, v43
	v_mov_b32_e32 v60, v43
	s_nop 1
	v_permlane32_swap_b32_e32 v53, v60
	v_cndmask_b32_e64 v53, v53, v60, s[4:5]
	v_mov_b32_e32 v60, v48
	v_mov_b32_e32 v61, v48
	s_nop 1
	v_permlane32_swap_b32_e32 v60, v61
	v_cndmask_b32_e64 v60, v60, v61, s[4:5]
	v_mov_b32_e32 v61, v49
	v_mov_b32_e32 v62, v49
	s_nop 1
	v_permlane32_swap_b32_e32 v61, v62
	v_cndmask_b32_e64 v61, v61, v62, s[4:5]
	v_mov_b32_e32 v62, v46
	v_mov_b32_e32 v63, v46
	s_nop 1
	v_permlane32_swap_b32_e32 v62, v63
	v_cndmask_b32_e64 v62, v62, v63, s[4:5]
	v_mov_b32_e32 v63, v47
	v_mov_b32_e32 v64, v47
	s_nop 1
	v_permlane32_swap_b32_e32 v63, v64
	v_cndmask_b32_e64 v63, v63, v64, s[4:5]
	s_waitcnt vmcnt(0) lgkmcnt(0)
	v_pk_mul_f32 v[36:37], v[36:37], v[52:53]
	v_pk_mul_f32 v[34:35], v[34:35], v[50:51]
	v_xor_b32_e32 v50, 0x80000000, v36
	v_xor_b32_e32 v51, 0x80000000, v37
	v_xor_b32_e32 v52, 0x80000000, v34
	v_xor_b32_e32 v53, 0x80000000, v35
	v_cndmask_b32_e64 v51, v37, v51, s[4:5]
	v_cndmask_b32_e64 v50, v36, v50, s[4:5]
	v_cndmask_b32_e64 v53, v35, v53, s[4:5]
	v_cndmask_b32_e64 v52, v34, v52, s[4:5]
	global_load_dwordx4 v[34:37], v[54:55], off offset:16
	s_nop 0
	global_load_dwordx4 v[54:57], v[56:57], off offset:16
	v_pk_fma_f32 v[42:43], v[42:43], v[40:41], v[50:51]
	v_pk_fma_f32 v[44:45], v[44:45], v[38:39], v[52:53]
	s_waitcnt vmcnt(0) lgkmcnt(0)
	v_pk_mul_f32 v[38:39], v[56:57], v[62:63]
	v_pk_mul_f32 v[40:41], v[54:55], v[60:61]
	v_xor_b32_e32 v50, 0x80000000, v38
	v_xor_b32_e32 v51, 0x80000000, v39
	v_xor_b32_e32 v52, 0x80000000, v40
	v_xor_b32_e32 v53, 0x80000000, v41
	v_cndmask_b32_e64 v39, v39, v51, s[4:5]
	v_cndmask_b32_e64 v38, v38, v50, s[4:5]
	v_cndmask_b32_e64 v41, v41, v53, s[4:5]
	v_cndmask_b32_e64 v40, v40, v52, s[4:5]
	v_pk_fma_f32 v[46:47], v[46:47], v[36:37], v[38:39]
	v_pk_fma_f32 v[48:49], v[48:49], v[34:35], v[40:41]
.LBB0_619:
	v_mov_b64_e32 v[38:39], v[58:59]
	v_cvt_pk_bf16_f32 v34, v44, v45
	v_add_co_u32_e32 v38, vcc, s0, v38
	v_cvt_pk_bf16_f32 v35, v42, v43
	v_cvt_pk_bf16_f32 v36, v48, v49
	v_cvt_pk_bf16_f32 v37, v46, v47
	v_addc_co_u32_e32 v39, vcc, 0, v39, vcc
	global_store_dwordx4 v[38:39], v[34:37], off offset:1024
	ds_read_b32 v34, v0 offset:512
	s_and_b64 vcc, exec, s[6:7]
	s_waitcnt lgkmcnt(0)
	v_mul_f32_e32 v40, 0x3e16c740, v34
	v_pk_mul_f32 v[34:35], v[32:33], v[40:41] op_sel_hi:[1,0]
	v_pk_mul_f32 v[36:37], v[30:31], v[40:41] op_sel_hi:[1,0]
	v_pk_mul_f32 v[38:39], v[28:29], v[40:41] op_sel_hi:[1,0]
	v_pk_mul_f32 v[40:41], v[26:27], v[40:41] op_sel_hi:[1,0]
	s_cbranch_vccnz .LBB0_621
	v_lshlrev_b64 v[26:27], 6, v[130:131]
	v_lshl_add_u64 v[26:27], v[132:133], 0, v[26:27]
	v_lshl_add_u64 v[46:47], v[26:27], 0, s[42:43]
	v_mov_b32_e32 v27, s11
	v_subrev_co_u32_e32 v26, vcc, s10, v46
	v_mov_b32_e32 v42, v36
	s_nop 0
	v_subb_co_u32_e32 v27, vcc, v47, v27, vcc
	v_lshl_add_u64 v[48:49], s[12:13], 0, v[26:27]
	global_load_dwordx4 v[30:33], v[46:47], off
	global_load_dwordx4 v[26:29], v[48:49], off
	v_mov_b32_e32 v43, v36
	s_nop 1
	v_permlane32_swap_b32_e32 v42, v43
	v_cndmask_b32_e64 v42, v42, v43, s[4:5]
	v_mov_b32_e32 v43, v37
	v_mov_b32_e32 v44, v37
	s_nop 1
	v_permlane32_swap_b32_e32 v43, v44
	v_cndmask_b32_e64 v43, v43, v44, s[4:5]
	v_mov_b32_e32 v44, v34
	v_mov_b32_e32 v45, v34
	s_nop 1
	v_permlane32_swap_b32_e32 v44, v45
	v_cndmask_b32_e64 v44, v44, v45, s[4:5]
	v_mov_b32_e32 v45, v35
	v_mov_b32_e32 v50, v35
	s_nop 1
	v_permlane32_swap_b32_e32 v45, v50
	v_cndmask_b32_e64 v45, v45, v50, s[4:5]
	v_mov_b32_e32 v50, v40
	v_mov_b32_e32 v51, v40
	s_nop 1
	v_permlane32_swap_b32_e32 v50, v51
	v_cndmask_b32_e64 v50, v50, v51, s[4:5]
	v_mov_b32_e32 v51, v41
	v_mov_b32_e32 v52, v41
	s_nop 1
	v_permlane32_swap_b32_e32 v51, v52
	v_cndmask_b32_e64 v51, v51, v52, s[4:5]
	v_mov_b32_e32 v52, v38
	v_mov_b32_e32 v53, v38
	s_nop 1
	v_permlane32_swap_b32_e32 v52, v53
	v_cndmask_b32_e64 v52, v52, v53, s[4:5]
	v_mov_b32_e32 v53, v39
	v_mov_b32_e32 v54, v39
	s_nop 1
	v_permlane32_swap_b32_e32 v53, v54
	v_cndmask_b32_e64 v53, v53, v54, s[4:5]
	s_waitcnt vmcnt(0) lgkmcnt(0)
	v_pk_mul_f32 v[28:29], v[28:29], v[44:45]
	v_pk_mul_f32 v[26:27], v[26:27], v[42:43]
	v_xor_b32_e32 v42, 0x80000000, v28
	v_xor_b32_e32 v43, 0x80000000, v29
	v_xor_b32_e32 v44, 0x80000000, v26
	v_xor_b32_e32 v45, 0x80000000, v27
	v_cndmask_b32_e64 v43, v29, v43, s[4:5]
	v_cndmask_b32_e64 v42, v28, v42, s[4:5]
	v_cndmask_b32_e64 v45, v27, v45, s[4:5]
	v_cndmask_b32_e64 v44, v26, v44, s[4:5]
	global_load_dwordx4 v[26:29], v[46:47], off offset:16
	s_nop 0
	global_load_dwordx4 v[46:49], v[48:49], off offset:16
	v_pk_fma_f32 v[34:35], v[34:35], v[32:33], v[42:43]
	v_pk_fma_f32 v[36:37], v[36:37], v[30:31], v[44:45]
	s_waitcnt vmcnt(0) lgkmcnt(0)
	v_pk_mul_f32 v[30:31], v[48:49], v[52:53]
	v_pk_mul_f32 v[32:33], v[46:47], v[50:51]
	v_xor_b32_e32 v42, 0x80000000, v30
	v_xor_b32_e32 v43, 0x80000000, v31
	v_xor_b32_e32 v44, 0x80000000, v32
	v_xor_b32_e32 v45, 0x80000000, v33
	v_cndmask_b32_e64 v31, v31, v43, s[4:5]
	v_cndmask_b32_e64 v30, v30, v42, s[4:5]
	v_cndmask_b32_e64 v33, v33, v45, s[4:5]
	v_cndmask_b32_e64 v32, v32, v44, s[4:5]
	v_pk_fma_f32 v[38:39], v[38:39], v[28:29], v[30:31]
	v_pk_fma_f32 v[40:41], v[40:41], v[26:27], v[32:33]
; DI unsigned pk2(float a, float b) { f32x2 v = {a, b}; return __builtin_bit_cast(unsigned, __builtin_convertvector(v, bf2_t)); }
; DI float xhalf_other(float x, int h) { auto r = __builtin_amdgcn_permlane32_swap(__float_as_uint(x), __float_as_uint(x), false, false); return h ? __uint_as_float(r[0]) : __uint_as_float(r[1]); }
; template <typename T> DI T* opaque(T* p) { asm volatile("" : "+v"(p) : : "memory"); return p; }
;     DI void operator()(const pg8::f32x4 (&acc)[2][2][4][2], const pg8::Unit& u, int wr, int wc, int fr, int fq) const {
;     ...
;                     for (int m = 0; m < 4; ++m) {
;                         const int rl = ai * 128 + wr * 64 + m * 16 + fr;
;                         const float sc = rs[rl] * qs;
;                         f32x4 v0 = acc[ai][bj][m][0] * sc, v1 = acc[ai][bj][m][1] * sc;
;                         if (d0 == 64) {
;                             const float* pc = opaque(COS + (size_t)(rowb + ai * 128 + m * 16) * 16 + 8 * (fq & 1));
;                             const float* ps = SIN + (pc - COS);
;                             {   const f32x4 cv = *(const f32x4*)pc, sv = *(const f32x4*)ps; f32x4 pp;
; #pragma unroll
;                                 for (int e = 0; e < 4; ++e) pp[e] = xhalf_other(v0[e], hh);
;                                 v0 = hh ? (v0 * cv + pp * sv) : (v0 * cv - pp * sv); }
;                             {   const f32x4 cv = *(const f32x4*)(pc + 4), sv = *(const f32x4*)(ps + 4); f32x4 pp;
; #pragma unroll
;                                 for (int e = 0; e < 4; ++e) pp[e] = xhalf_other(v1[e], hh);
;                                 v1 = hh ? (v1 * cv + pp * sv) : (v1 * cv - pp * sv); }
;                         }
;                         u32x4 wv; wv.x = pk2(v0.x, v0.y); wv.y = pk2(v0.z, v0.w); wv.z = pk2(v1.x, v1.y); wv.w = pk2(v1.z, v1.w);
;                         *(u32x4*)(opaque(pb) + (size_t)(ai * 128 + m * 16) * 96) = wv;
.LBB0_621:
	v_mov_b64_e32 v[30:31], v[58:59]
	v_cvt_pk_bf16_f32 v26, v36, v37
	v_add_co_u32_e32 v30, vcc, s1, v30
	v_cvt_pk_bf16_f32 v27, v34, v35
	v_cvt_pk_bf16_f32 v28, v40, v41
	v_cvt_pk_bf16_f32 v29, v38, v39
	v_addc_co_u32_e32 v31, vcc, 0, v31, vcc
	global_store_dwordx4 v[30:31], v[26:29], off
	ds_read_b32 v26, v0 offset:576
	s_and_b64 vcc, exec, s[6:7]
	s_waitcnt lgkmcnt(0)
	v_mul_f32_e32 v32, 0x3e16c740, v26
	v_pk_mul_f32 v[26:27], v[24:25], v[32:33] op_sel_hi:[1,0]
	v_pk_mul_f32 v[28:29], v[22:23], v[32:33] op_sel_hi:[1,0]
	v_pk_mul_f32 v[30:31], v[20:21], v[32:33] op_sel_hi:[1,0]
	v_pk_mul_f32 v[32:33], v[18:19], v[32:33] op_sel_hi:[1,0]
	s_cbranch_vccnz .LBB0_623
	v_lshlrev_b64 v[18:19], 6, v[130:131]
	v_lshl_add_u64 v[18:19], v[132:133], 0, v[18:19]
	s_mov_b64 s[18:19], 0x2400
	v_lshl_add_u64 v[38:39], v[18:19], 0, s[18:19]
	v_mov_b32_e32 v19, s11
	v_subrev_co_u32_e32 v18, vcc, s10, v38
	v_mov_b32_e32 v34, v28
	s_nop 0
	v_subb_co_u32_e32 v19, vcc, v39, v19, vcc
	v_lshl_add_u64 v[40:41], s[12:13], 0, v[18:19]
	global_load_dwordx4 v[22:25], v[38:39], off
	global_load_dwordx4 v[18:21], v[40:41], off
	v_mov_b32_e32 v35, v28
	s_nop 1
	v_permlane32_swap_b32_e32 v34, v35
	v_cndmask_b32_e64 v34, v34, v35, s[4:5]
	v_mov_b32_e32 v35, v29
	v_mov_b32_e32 v36, v29
	s_nop 1
	v_permlane32_swap_b32_e32 v35, v36
	v_cndmask_b32_e64 v35, v35, v36, s[4:5]
	v_mov_b32_e32 v36, v26
	v_mov_b32_e32 v37, v26
	s_nop 1
	v_permlane32_swap_b32_e32 v36, v37
	v_cndmask_b32_e64 v36, v36, v37, s[4:5]
	v_mov_b32_e32 v37, v27
	v_mov_b32_e32 v42, v27
	s_nop 1
	v_permlane32_swap_b32_e32 v37, v42
	v_cndmask_b32_e64 v37, v37, v42, s[4:5]
	v_mov_b32_e32 v42, v32
	v_mov_b32_e32 v43, v32
	s_nop 1
	v_permlane32_swap_b32_e32 v42, v43
	v_cndmask_b32_e64 v42, v42, v43, s[4:5]
	v_mov_b32_e32 v43, v33
	v_mov_b32_e32 v44, v33
	s_nop 1
	v_permlane32_swap_b32_e32 v43, v44
	v_cndmask_b32_e64 v43, v43, v44, s[4:5]
	v_mov_b32_e32 v44, v30
	v_mov_b32_e32 v45, v30
	s_nop 1
	v_permlane32_swap_b32_e32 v44, v45
	v_cndmask_b32_e64 v44, v44, v45, s[4:5]
	v_mov_b32_e32 v45, v31
	v_mov_b32_e32 v46, v31
	s_nop 1
	v_permlane32_swap_b32_e32 v45, v46
	v_cndmask_b32_e64 v45, v45, v46, s[4:5]
	s_waitcnt vmcnt(0) lgkmcnt(0)
	v_pk_mul_f32 v[20:21], v[20:21], v[36:37]
	v_pk_mul_f32 v[18:19], v[18:19], v[34:35]
	v_xor_b32_e32 v34, 0x80000000, v20
	v_xor_b32_e32 v35, 0x80000000, v21
	v_xor_b32_e32 v36, 0x80000000, v18
	v_xor_b32_e32 v37, 0x80000000, v19
	v_cndmask_b32_e64 v35, v21, v35, s[4:5]
	v_cndmask_b32_e64 v34, v20, v34, s[4:5]
	v_cndmask_b32_e64 v37, v19, v37, s[4:5]
	v_cndmask_b32_e64 v36, v18, v36, s[4:5]
	global_load_dwordx4 v[18:21], v[38:39], off offset:16
	s_nop 0
	global_load_dwordx4 v[38:41], v[40:41], off offset:16
	v_pk_fma_f32 v[26:27], v[26:27], v[24:25], v[34:35]
	v_pk_fma_f32 v[28:29], v[28:29], v[22:23], v[36:37]
	s_waitcnt vmcnt(0) lgkmcnt(0)
	v_pk_mul_f32 v[22:23], v[40:41], v[44:45]
	v_pk_mul_f32 v[24:25], v[38:39], v[42:43]
	v_xor_b32_e32 v34, 0x80000000, v22
	v_xor_b32_e32 v35, 0x80000000, v23
	v_xor_b32_e32 v36, 0x80000000, v24
	v_xor_b32_e32 v37, 0x80000000, v25
	v_cndmask_b32_e64 v23, v23, v35, s[4:5]
	v_cndmask_b32_e64 v22, v22, v34, s[4:5]
	v_cndmask_b32_e64 v25, v25, v37, s[4:5]
	v_cndmask_b32_e64 v24, v24, v36, s[4:5]
	v_pk_fma_f32 v[30:31], v[30:31], v[20:21], v[22:23]
	v_pk_fma_f32 v[32:33], v[32:33], v[18:19], v[24:25]
.LBB0_623:
	v_mov_b64_e32 v[22:23], v[58:59]
	v_cvt_pk_bf16_f32 v18, v28, v29
	v_add_co_u32_e32 v22, vcc, s1, v22
	v_cvt_pk_bf16_f32 v19, v26, v27
	v_cvt_pk_bf16_f32 v20, v32, v33
	v_cvt_pk_bf16_f32 v21, v30, v31
	v_addc_co_u32_e32 v23, vcc, 0, v23, vcc
	global_store_dwordx4 v[22:23], v[18:21], off offset:3072
	ds_read_b32 v18, v0 offset:640
	s_and_b64 vcc, exec, s[6:7]
	s_waitcnt lgkmcnt(0)
	v_mul_f32_e32 v24, 0x3e16c740, v18
	v_pk_mul_f32 v[18:19], v[16:17], v[24:25] op_sel_hi:[1,0]
	v_pk_mul_f32 v[20:21], v[14:15], v[24:25] op_sel_hi:[1,0]
	v_pk_mul_f32 v[22:23], v[12:13], v[24:25] op_sel_hi:[1,0]
	v_pk_mul_f32 v[24:25], v[10:11], v[24:25] op_sel_hi:[1,0]
	s_cbranch_vccnz .LBB0_625
	v_lshlrev_b64 v[10:11], 6, v[130:131]
	v_lshl_add_u64 v[10:11], v[132:133], 0, v[10:11]
	s_mov_b64 s[18:19], 0x2800
	v_lshl_add_u64 v[30:31], v[10:11], 0, s[18:19]
	v_mov_b32_e32 v11, s11
	v_subrev_co_u32_e32 v10, vcc, s10, v30
	v_mov_b32_e32 v26, v20
	s_nop 0
	v_subb_co_u32_e32 v11, vcc, v31, v11, vcc
	v_lshl_add_u64 v[32:33], s[12:13], 0, v[10:11]
	global_load_dwordx4 v[14:17], v[30:31], off
	global_load_dwordx4 v[10:13], v[32:33], off
	v_mov_b32_e32 v27, v20
	s_nop 1
	v_permlane32_swap_b32_e32 v26, v27
	v_cndmask_b32_e64 v26, v26, v27, s[4:5]
	v_mov_b32_e32 v27, v21
	v_mov_b32_e32 v28, v21
	s_nop 1
	v_permlane32_swap_b32_e32 v27, v28
	v_cndmask_b32_e64 v27, v27, v28, s[4:5]
	v_mov_b32_e32 v28, v18
	v_mov_b32_e32 v29, v18
	s_nop 1
	v_permlane32_swap_b32_e32 v28, v29
	v_cndmask_b32_e64 v28, v28, v29, s[4:5]
	v_mov_b32_e32 v29, v19
	v_mov_b32_e32 v34, v19
	s_nop 1
	v_permlane32_swap_b32_e32 v29, v34
	v_cndmask_b32_e64 v29, v29, v34, s[4:5]
	v_mov_b32_e32 v34, v24
	v_mov_b32_e32 v35, v24
	s_nop 1
	v_permlane32_swap_b32_e32 v34, v35
	v_cndmask_b32_e64 v34, v34, v35, s[4:5]
	v_mov_b32_e32 v35, v25
	v_mov_b32_e32 v36, v25
	s_nop 1
	v_permlane32_swap_b32_e32 v35, v36
	v_cndmask_b32_e64 v35, v35, v36, s[4:5]
	v_mov_b32_e32 v36, v22
	v_mov_b32_e32 v37, v22
	s_nop 1
	v_permlane32_swap_b32_e32 v36, v37
	v_cndmask_b32_e64 v36, v36, v37, s[4:5]
	v_mov_b32_e32 v37, v23
	v_mov_b32_e32 v38, v23
	s_nop 1
	v_permlane32_swap_b32_e32 v37, v38
	v_cndmask_b32_e64 v37, v37, v38, s[4:5]
	s_waitcnt vmcnt(0) lgkmcnt(0)
	v_pk_mul_f32 v[12:13], v[12:13], v[28:29]
	v_pk_mul_f32 v[10:11], v[10:11], v[26:27]
	v_xor_b32_e32 v26, 0x80000000, v12
	v_xor_b32_e32 v27, 0x80000000, v13
	v_xor_b32_e32 v28, 0x80000000, v10
	v_xor_b32_e32 v29, 0x80000000, v11
	v_cndmask_b32_e64 v27, v13, v27, s[4:5]
	v_cndmask_b32_e64 v26, v12, v26, s[4:5]
	v_cndmask_b32_e64 v29, v11, v29, s[4:5]
	v_cndmask_b32_e64 v28, v10, v28, s[4:5]
	global_load_dwordx4 v[10:13], v[30:31], off offset:16
	s_nop 0
	global_load_dwordx4 v[30:33], v[32:33], off offset:16
	v_pk_fma_f32 v[18:19], v[18:19], v[16:17], v[26:27]
	v_pk_fma_f32 v[20:21], v[20:21], v[14:15], v[28:29]
	s_waitcnt vmcnt(0) lgkmcnt(0)
	v_pk_mul_f32 v[14:15], v[32:33], v[36:37]
	v_pk_mul_f32 v[16:17], v[30:31], v[34:35]
	v_xor_b32_e32 v26, 0x80000000, v14
	v_xor_b32_e32 v27, 0x80000000, v15
	v_xor_b32_e32 v28, 0x80000000, v16
	v_xor_b32_e32 v29, 0x80000000, v17
	v_cndmask_b32_e64 v15, v15, v27, s[4:5]
	v_cndmask_b32_e64 v14, v14, v26, s[4:5]
	v_cndmask_b32_e64 v17, v17, v29, s[4:5]
	v_cndmask_b32_e64 v16, v16, v28, s[4:5]
	v_pk_fma_f32 v[22:23], v[22:23], v[12:13], v[14:15]
	v_pk_fma_f32 v[24:25], v[24:25], v[10:11], v[16:17]
; DI unsigned pk2(float a, float b) { f32x2 v = {a, b}; return __builtin_bit_cast(unsigned, __builtin_convertvector(v, bf2_t)); }
; DI float xhalf_other(float x, int h) { auto r = __builtin_amdgcn_permlane32_swap(__float_as_uint(x), __float_as_uint(x), false, false); return h ? __uint_as_float(r[0]) : __uint_as_float(r[1]); }
; template <typename T> DI T* opaque(T* p) { asm volatile("" : "+v"(p) : : "memory"); return p; }
;     DI void operator()(const pg8::f32x4 (&acc)[2][2][4][2], const pg8::Unit& u, int wr, int wc, int fr, int fq) const {
;     ...
;                     for (int m = 0; m < 4; ++m) {
;                         const int rl = ai * 128 + wr * 64 + m * 16 + fr;
;                         const float sc = rs[rl] * qs;
;                         f32x4 v0 = acc[ai][bj][m][0] * sc, v1 = acc[ai][bj][m][1] * sc;
;                         if (d0 == 64) {
;                             const float* pc = opaque(COS + (size_t)(rowb + ai * 128 + m * 16) * 16 + 8 * (fq & 1));
;                             const float* ps = SIN + (pc - COS);
;                             {   const f32x4 cv = *(const f32x4*)pc, sv = *(const f32x4*)ps; f32x4 pp;
; #pragma unroll
;                                 for (int e = 0; e < 4; ++e) pp[e] = xhalf_other(v0[e], hh);
;                                 v0 = hh ? (v0 * cv + pp * sv) : (v0 * cv - pp * sv); }
;                             {   const f32x4 cv = *(const f32x4*)(pc + 4), sv = *(const f32x4*)(ps + 4); f32x4 pp;
; #pragma unroll
;                                 for (int e = 0; e < 4; ++e) pp[e] = xhalf_other(v1[e], hh);
;                                 v1 = hh ? (v1 * cv + pp * sv) : (v1 * cv - pp * sv); }
;                         }
;                         u32x4 wv; wv.x = pk2(v0.x, v0.y); wv.y = pk2(v0.z, v0.w); wv.z = pk2(v1.x, v1.y); wv.w = pk2(v1.z, v1.w);
;                         *(u32x4*)(opaque(pb) + (size_t)(ai * 128 + m * 16) * 96) = wv;
.LBB0_625:
	v_mov_b64_e32 v[14:15], v[58:59]
	s_movk_i32 s3, 0x7000
	v_add_co_u32_e32 v14, vcc, s3, v14
	v_cvt_pk_bf16_f32 v10, v20, v21
	v_cvt_pk_bf16_f32 v11, v18, v19
	v_cvt_pk_bf16_f32 v12, v24, v25
	v_cvt_pk_bf16_f32 v13, v22, v23
	v_addc_co_u32_e32 v15, vcc, 0, v15, vcc
	global_store_dwordx4 v[14:15], v[10:13], off offset:2048
	ds_read_b32 v0, v0 offset:704
	s_and_b64 vcc, exec, s[6:7]
	s_waitcnt lgkmcnt(0)
	v_mul_f32_e32 v0, 0x3e16c740, v0
	v_pk_mul_f32 v[10:11], v[8:9], v[0:1] op_sel_hi:[1,0]
	v_pk_mul_f32 v[12:13], v[6:7], v[0:1] op_sel_hi:[1,0]
	v_pk_mul_f32 v[14:15], v[4:5], v[0:1] op_sel_hi:[1,0]
	v_pk_mul_f32 v[16:17], v[2:3], v[0:1] op_sel_hi:[1,0]
	s_cbranch_vccnz .LBB0_627
	v_lshlrev_b64 v[2:3], 6, v[130:131]
	v_lshl_add_u64 v[2:3], v[132:133], 0, v[2:3]
	s_mov_b64 s[6:7], 0x2c00
	v_lshl_add_u64 v[22:23], v[2:3], 0, s[6:7]
	v_mov_b32_e32 v0, s11
	v_subrev_co_u32_e32 v2, vcc, s10, v22
	v_mov_b32_e32 v18, v12
	s_nop 0
	v_subb_co_u32_e32 v3, vcc, v23, v0, vcc
	v_lshl_add_u64 v[24:25], s[12:13], 0, v[2:3]
	global_load_dwordx4 v[6:9], v[22:23], off
	global_load_dwordx4 v[2:5], v[24:25], off
	v_mov_b32_e32 v0, v12
	s_nop 1
	v_permlane32_swap_b32_e32 v0, v18
	v_cndmask_b32_e64 v18, v0, v18, s[4:5]
	v_mov_b32_e32 v0, v13
	v_mov_b32_e32 v19, v13
	s_nop 1
	v_permlane32_swap_b32_e32 v0, v19
	v_cndmask_b32_e64 v19, v0, v19, s[4:5]
	v_mov_b32_e32 v0, v10
	v_mov_b32_e32 v20, v10
	s_nop 1
	v_permlane32_swap_b32_e32 v0, v20
	v_cndmask_b32_e64 v20, v0, v20, s[4:5]
	v_mov_b32_e32 v0, v11
	v_mov_b32_e32 v21, v11
	s_nop 1
	v_permlane32_swap_b32_e32 v0, v21
	v_cndmask_b32_e64 v21, v0, v21, s[4:5]
	v_mov_b32_e32 v26, v16
	v_mov_b32_e32 v27, v17
	v_mov_b32_e32 v28, v14
	v_mov_b32_e32 v29, v15
	s_waitcnt vmcnt(0) lgkmcnt(0)
	v_pk_mul_f32 v[4:5], v[4:5], v[20:21]
	v_pk_mul_f32 v[2:3], v[2:3], v[18:19]
	v_xor_b32_e32 v0, 0x80000000, v4
	v_xor_b32_e32 v18, 0x80000000, v5
	v_xor_b32_e32 v20, 0x80000000, v2
	v_xor_b32_e32 v21, 0x80000000, v3
	v_cndmask_b32_e64 v19, v5, v18, s[4:5]
	v_cndmask_b32_e64 v18, v4, v0, s[4:5]
	v_cndmask_b32_e64 v21, v3, v21, s[4:5]
	v_cndmask_b32_e64 v20, v2, v20, s[4:5]
	global_load_dwordx4 v[2:5], v[22:23], off offset:16
	s_nop 0
	global_load_dwordx4 v[22:25], v[24:25], off offset:16
	v_mov_b32_e32 v0, v16
	s_nop 1
	v_permlane32_swap_b32_e32 v0, v26
	v_cndmask_b32_e64 v26, v0, v26, s[4:5]
	v_mov_b32_e32 v0, v17
	s_nop 1
	v_permlane32_swap_b32_e32 v0, v27
	v_cndmask_b32_e64 v27, v0, v27, s[4:5]
	v_mov_b32_e32 v0, v14
	s_nop 1
	v_permlane32_swap_b32_e32 v0, v28
	v_cndmask_b32_e64 v28, v0, v28, s[4:5]
	v_mov_b32_e32 v0, v15
	s_nop 1
	v_permlane32_swap_b32_e32 v0, v29
	v_cndmask_b32_e64 v29, v0, v29, s[4:5]
	v_pk_fma_f32 v[10:11], v[10:11], v[8:9], v[18:19]
	v_pk_fma_f32 v[12:13], v[12:13], v[6:7], v[20:21]
	s_waitcnt vmcnt(0) lgkmcnt(0)
	v_pk_mul_f32 v[6:7], v[24:25], v[28:29]
	v_pk_mul_f32 v[8:9], v[22:23], v[26:27]
	v_xor_b32_e32 v0, 0x80000000, v6
	v_xor_b32_e32 v18, 0x80000000, v7
	v_xor_b32_e32 v19, 0x80000000, v8
	v_xor_b32_e32 v20, 0x80000000, v9
	v_cndmask_b32_e64 v7, v7, v18, s[4:5]
	v_cndmask_b32_e64 v6, v6, v0, s[4:5]
	v_cndmask_b32_e64 v9, v9, v20, s[4:5]
	v_cndmask_b32_e64 v8, v8, v19, s[4:5]
	v_pk_fma_f32 v[14:15], v[14:15], v[4:5], v[6:7]
	v_pk_fma_f32 v[16:17], v[16:17], v[2:3], v[8:9]
.LBB0_627:
	v_cvt_pk_bf16_f32 v2, v12, v13
	v_add_co_u32_e32 v6, vcc, 0x8000, v58
	v_cvt_pk_bf16_f32 v3, v10, v11
	v_cvt_pk_bf16_f32 v4, v16, v17
	v_cvt_pk_bf16_f32 v5, v14, v15
	v_addc_co_u32_e32 v7, vcc, 0, v59, vcc
	global_store_dwordx4 v[6:7], v[2:5], off offset:1024

; DI bf16_t tobf(float a) { return (bf16_t)(pk2(a, 0.f) & 0xffffu); }
; template <typename T> DI T* opaque(T* p) { asm volatile("" : "+v"(p) : : "memory"); return p; }
;     DI void operator()(const pg8::f32x4 (&acc)[2][2][4][2], const pg8::Unit& u, int wr, int wc, int fr, int fq) const {
;     ...
;             } else {
;                 bf16_t* pb = (bf16_t*)(ws + O_MVT) + ((size_t)bh * 64 + (within - 64) + 8 * fq) * S_ + s0;
; #pragma unroll
;                 for (int ai = 0; ai < 2; ++ai)
; #pragma unroll
;                     for (int m = 0; m < 4; ++m) {
;                         const float sc = rs[ai * 128 + wr * 64 + m * 16 + fr];
;                         const f32x4 v0 = acc[ai][bj][m][0] * sc, v1 = acc[ai][bj][m][1] * sc;
;                         bf16_t* q = opaque(pb + ai * 128 + m * 16);
;                         q[0] = tobf(v0.x); q[(size_t)S_] = tobf(v0.y); q[(size_t)2 * S_] = tobf(v0.z); q[(size_t)3 * S_] = tobf(v0.w);
;                         q[(size_t)4 * S_] = tobf(v1.x); q[(size_t)5 * S_] = tobf(v1.y); q[(size_t)6 * S_] = tobf(v1.z); q[(size_t)7 * S_] = tobf(v1.w);
;                     }
.LBB0_635:
	s_lshl_b32 s4, s45, 5
	v_add_u32_e32 v0, s44, v141
	v_lshl_add_u32 v136, v0, 2, v226
	s_cmp_gt_u32 s45, 1
	v_add_u32_e32 v130, s41, v0
	s_waitcnt vmcnt(0)
	ds_read_b32 v0, v136
	s_cselect_b64 s[6:7], -1, 0
	s_sub_i32 s48, s4, 64
	s_lshl_b32 s4, s45, 6
	s_add_u32 s4, s36, s4
	v_and_b32_e32 v137, 0x1fff, v130
	v_lshlrev_b32_e32 v130, 3, v140
	s_addc_u32 s5, s37, 0
	s_lshl_b32 s17, s39, 1
	v_ashrrev_i32_e32 v131, 31, v130
	v_lshl_add_u64 v[134:135], v[130:131], 0, s[48:49]
	s_add_i32 s18, s17, s40
	s_ashr_i32 s19, s18, 31
	s_waitcnt lgkmcnt(0)
	v_pk_mul_f32 v[128:129], v[128:129], v[0:1] op_sel_hi:[1,0]
	v_pk_mul_f32 v[126:127], v[126:127], v[0:1] op_sel_hi:[1,0]
	v_pk_mul_f32 v[124:125], v[124:125], v[0:1] op_sel_hi:[1,0]
	v_pk_mul_f32 v[132:133], v[122:123], v[0:1] op_sel_hi:[1,0]
	s_mov_b64 s[20:21], -1
	s_and_b64 vcc, exec, s[6:7]
	v_lshlrev_b64 v[122:123], 14, v[134:135]
	v_lshlrev_b32_e32 v0, 1, v137
	s_cbranch_vccz .LBB0_637
	s_lshl_b64 s[20:21], s[18:19], 20
	s_add_u32 s20, s34, s20
	s_addc_u32 s21, s35, s21
	v_lshl_add_u64 v[134:135], s[20:21], 0, v[122:123]
	v_lshl_add_u64 v[134:135], v[134:135], 0, v[0:1]
	v_mov_b64_e32 v[138:139], v[134:135]
	v_cvt_pk_bf16_f32 v140, v126, s0
	global_store_short v[138:139], v140, off
	v_add_co_u32_e32 v140, vcc, s86, v138
	v_cvt_pk_bf16_f32 v142, v127, s0
	s_nop 0
	v_addc_co_u32_e32 v141, vcc, 0, v139, vcc
	global_store_short v[140:141], v142, off
	v_add_co_u32_e32 v140, vcc, s67, v138
	v_cvt_pk_bf16_f32 v142, v128, s0
	s_nop 0
	v_addc_co_u32_e32 v141, vcc, 0, v139, vcc
	global_store_short v[140:141], v142, off
	v_add_co_u32_e32 v140, vcc, s89, v138
	v_cvt_pk_bf16_f32 v142, v129, s0
	s_nop 0
	v_addc_co_u32_e32 v141, vcc, 0, v139, vcc
	global_store_short v[140:141], v142, off
	v_add_co_u32_e32 v140, vcc, s63, v138
	v_cvt_pk_bf16_f32 v142, v132, s0
	s_nop 0
	v_addc_co_u32_e32 v141, vcc, 0, v139, vcc
	global_store_short v[140:141], v142, off
	v_add_co_u32_e32 v140, vcc, s85, v138
	v_cvt_pk_bf16_f32 v142, v133, s0
	s_nop 0
	v_addc_co_u32_e32 v141, vcc, 0, v139, vcc
	global_store_short v[140:141], v142, off
	v_add_co_u32_e32 v140, vcc, s87, v138
	v_cvt_pk_bf16_f32 v142, v124, s0
	s_nop 0
	v_addc_co_u32_e32 v141, vcc, 0, v139, vcc
	global_store_short v[140:141], v142, off
	ds_read_b32 v140, v136 offset:64
	v_cvt_pk_bf16_f32 v141, v125, s0
	v_add_co_u32_e32 v138, vcc, s88, v138
	v_lshl_add_u64 v[146:147], v[134:135], 0, 32
	s_nop 0
	v_addc_co_u32_e32 v139, vcc, 0, v139, vcc
	s_waitcnt lgkmcnt(0)
	v_pk_mul_f32 v[142:143], v[118:119], v[140:141] op_sel_hi:[1,0]
	global_store_short v[138:139], v141, off
	v_cvt_pk_bf16_f32 v142, v142, s0
	global_store_short v[146:147], v142, off
	v_add_co_u32_e32 v142, vcc, s86, v146
	v_cvt_pk_bf16_f32 v148, v143, s0
	s_nop 0
	v_addc_co_u32_e32 v143, vcc, 0, v147, vcc
	v_pk_mul_f32 v[138:139], v[120:121], v[140:141] op_sel_hi:[1,0]
	global_store_short v[142:143], v148, off
	v_add_co_u32_e32 v142, vcc, s67, v146
	v_cvt_pk_bf16_f32 v138, v138, s0
	s_nop 0
	v_addc_co_u32_e32 v143, vcc, 0, v147, vcc
	global_store_short v[142:143], v138, off
	v_add_co_u32_e32 v138, vcc, s89, v146
	v_cvt_pk_bf16_f32 v142, v139, s0
	s_nop 0
	v_addc_co_u32_e32 v139, vcc, 0, v147, vcc
	v_pk_mul_f32 v[144:145], v[116:117], v[140:141] op_sel_hi:[1,0]
	v_pk_mul_f32 v[140:141], v[114:115], v[140:141] op_sel_hi:[1,0]
	global_store_short v[138:139], v142, off
	v_add_co_u32_e32 v138, vcc, s63, v146
	v_cvt_pk_bf16_f32 v140, v140, s0
	s_nop 0
	v_addc_co_u32_e32 v139, vcc, 0, v147, vcc
	global_store_short v[138:139], v140, off
	v_add_co_u32_e32 v138, vcc, s85, v146
	v_cvt_pk_bf16_f32 v140, v141, s0
	s_nop 0
	v_addc_co_u32_e32 v139, vcc, 0, v147, vcc
	global_store_short v[138:139], v140, off
	v_add_co_u32_e32 v138, vcc, s87, v146
	v_cvt_pk_bf16_f32 v140, v144, s0
	s_nop 0
	v_addc_co_u32_e32 v139, vcc, 0, v147, vcc
	global_store_short v[138:139], v140, off
	ds_read_b32 v138, v136 offset:128
	v_cvt_pk_bf16_f32 v139, v145, s0
	v_add_co_u32_e32 v140, vcc, s88, v146
	s_mov_b64 s[20:21], 0x60
	s_nop 0
	v_addc_co_u32_e32 v141, vcc, 0, v147, vcc
	s_waitcnt lgkmcnt(0)
	v_pk_mul_f32 v[142:143], v[110:111], v[138:139] op_sel_hi:[1,0]
	global_store_short v[140:141], v139, off
	v_lshl_add_u64 v[146:147], v[134:135], 0, 64
	v_cvt_pk_bf16_f32 v142, v142, s0
	global_store_short v[146:147], v142, off
	v_add_co_u32_e32 v142, vcc, s86, v146
	v_cvt_pk_bf16_f32 v148, v143, s0
	s_nop 0
	v_addc_co_u32_e32 v143, vcc, 0, v147, vcc
	v_pk_mul_f32 v[140:141], v[112:113], v[138:139] op_sel_hi:[1,0]
	global_store_short v[142:143], v148, off
	v_add_co_u32_e32 v142, vcc, s67, v146
	v_cvt_pk_bf16_f32 v140, v140, s0
	s_nop 0
	v_addc_co_u32_e32 v143, vcc, 0, v147, vcc
	global_store_short v[142:143], v140, off
	v_add_co_u32_e32 v140, vcc, s89, v146
	v_cvt_pk_bf16_f32 v142, v141, s0
	s_nop 0
	v_addc_co_u32_e32 v141, vcc, 0, v147, vcc
	v_pk_mul_f32 v[144:145], v[108:109], v[138:139] op_sel_hi:[1,0]
	v_pk_mul_f32 v[138:139], v[106:107], v[138:139] op_sel_hi:[1,0]
	global_store_short v[140:141], v142, off
	v_add_co_u32_e32 v140, vcc, s63, v146
	v_cvt_pk_bf16_f32 v138, v138, s0
	s_nop 0
	v_addc_co_u32_e32 v141, vcc, 0, v147, vcc
	global_store_short v[140:141], v138, off
	v_add_co_u32_e32 v138, vcc, s85, v146
	v_cvt_pk_bf16_f32 v140, v139, s0
	s_nop 0
	v_addc_co_u32_e32 v139, vcc, 0, v147, vcc
	global_store_short v[138:139], v140, off
	v_add_co_u32_e32 v138, vcc, s87, v146
	v_cvt_pk_bf16_f32 v140, v144, s0
	s_nop 0
	v_addc_co_u32_e32 v139, vcc, 0, v147, vcc
	global_store_short v[138:139], v140, off
	ds_read_b32 v138, v136 offset:192
	v_cvt_pk_bf16_f32 v139, v145, s0
	v_add_co_u32_e32 v140, vcc, s88, v146
	s_waitcnt lgkmcnt(0)
; DI bf16_t tobf(float a) { return (bf16_t)(pk2(a, 0.f) & 0xffffu); }
; template <typename T> DI T* opaque(T* p) { asm volatile("" : "+v"(p) : : "memory"); return p; }
;     DI void operator()(const pg8::f32x4 (&acc)[2][2][4][2], const pg8::Unit& u, int wr, int wc, int fr, int fq) const {
;     ...
;             } else {
;                 bf16_t* pb = (bf16_t*)(ws + O_MVT) + ((size_t)bh * 64 + (within - 64) + 8 * fq) * S_ + s0;
; #pragma unroll
;                 for (int ai = 0; ai < 2; ++ai)
; #pragma unroll
;                     for (int m = 0; m < 4; ++m) {
;                         const float sc = rs[ai * 128 + wr * 64 + m * 16 + fr];
;                         const f32x4 v0 = acc[ai][bj][m][0] * sc, v1 = acc[ai][bj][m][1] * sc;
;                         bf16_t* q = opaque(pb + ai * 128 + m * 16);
;                         q[0] = tobf(v0.x); q[(size_t)S_] = tobf(v0.y); q[(size_t)2 * S_] = tobf(v0.z); q[(size_t)3 * S_] = tobf(v0.w);
;                         q[(size_t)4 * S_] = tobf(v1.x); q[(size_t)5 * S_] = tobf(v1.y); q[(size_t)6 * S_] = tobf(v1.z); q[(size_t)7 * S_] = tobf(v1.w);
;                     }
	v_pk_mul_f32 v[142:143], v[102:103], v[138:139] op_sel_hi:[1,0]
	v_addc_co_u32_e32 v141, vcc, 0, v147, vcc
	global_store_short v[140:141], v139, off
	v_lshl_add_u64 v[146:147], v[134:135], 0, s[20:21]
	v_cvt_pk_bf16_f32 v142, v142, s0
	global_store_short v[146:147], v142, off
	v_add_co_u32_e32 v142, vcc, s86, v146
	v_cvt_pk_bf16_f32 v148, v143, s0
	s_nop 0
	v_addc_co_u32_e32 v143, vcc, 0, v147, vcc
	v_pk_mul_f32 v[140:141], v[104:105], v[138:139] op_sel_hi:[1,0]
	global_store_short v[142:143], v148, off
	v_add_co_u32_e32 v142, vcc, s67, v146
	v_cvt_pk_bf16_f32 v140, v140, s0
	s_nop 0
	v_addc_co_u32_e32 v143, vcc, 0, v147, vcc
	global_store_short v[142:143], v140, off
	v_add_co_u32_e32 v140, vcc, s89, v146
	v_cvt_pk_bf16_f32 v142, v141, s0
	s_nop 0
	v_addc_co_u32_e32 v141, vcc, 0, v147, vcc
	v_pk_mul_f32 v[144:145], v[100:101], v[138:139] op_sel_hi:[1,0]
	v_pk_mul_f32 v[138:139], v[98:99], v[138:139] op_sel_hi:[1,0]
	global_store_short v[140:141], v142, off
	v_add_co_u32_e32 v140, vcc, s63, v146
	v_cvt_pk_bf16_f32 v138, v138, s0
	s_nop 0
	v_addc_co_u32_e32 v141, vcc, 0, v147, vcc
	global_store_short v[140:141], v138, off
	v_add_co_u32_e32 v138, vcc, s85, v146
	v_cvt_pk_bf16_f32 v140, v139, s0
	s_nop 0
	v_addc_co_u32_e32 v139, vcc, 0, v147, vcc
	global_store_short v[138:139], v140, off
	v_add_co_u32_e32 v138, vcc, s87, v146
	v_cvt_pk_bf16_f32 v140, v144, s0
	s_nop 0
	v_addc_co_u32_e32 v139, vcc, 0, v147, vcc
	global_store_short v[138:139], v140, off
	ds_read_b32 v138, v136 offset:512
	v_cvt_pk_bf16_f32 v139, v145, s0
	v_add_co_u32_e32 v140, vcc, s88, v146
	s_mov_b64 s[20:21], 0x100
	s_nop 0
	v_addc_co_u32_e32 v141, vcc, 0, v147, vcc
	s_waitcnt lgkmcnt(0)
	v_pk_mul_f32 v[144:145], v[94:95], v[138:139] op_sel_hi:[1,0]
	global_store_short v[140:141], v139, off
	v_lshl_add_u64 v[140:141], v[134:135], 0, s[20:21]
	v_cvt_pk_bf16_f32 v144, v144, s0
	global_store_short v[140:141], v144, off
	v_add_co_u32_e32 v144, vcc, s86, v140
	v_cvt_pk_bf16_f32 v148, v145, s0
	s_nop 0
	v_addc_co_u32_e32 v145, vcc, 0, v141, vcc
	v_pk_mul_f32 v[142:143], v[96:97], v[138:139] op_sel_hi:[1,0]
	global_store_short v[144:145], v148, off
	v_add_co_u32_e32 v144, vcc, s67, v140
	v_cvt_pk_bf16_f32 v142, v142, s0
	s_nop 0
	v_addc_co_u32_e32 v145, vcc, 0, v141, vcc
	global_store_short v[144:145], v142, off
	v_add_co_u32_e32 v142, vcc, s89, v140
	v_cvt_pk_bf16_f32 v144, v143, s0
	s_nop 0
	v_addc_co_u32_e32 v143, vcc, 0, v141, vcc
	v_pk_mul_f32 v[146:147], v[92:93], v[138:139] op_sel_hi:[1,0]
	v_pk_mul_f32 v[138:139], v[90:91], v[138:139] op_sel_hi:[1,0]
	global_store_short v[142:143], v144, off
	v_add_co_u32_e32 v142, vcc, s63, v140
	v_cvt_pk_bf16_f32 v138, v138, s0
	s_nop 0
	v_addc_co_u32_e32 v143, vcc, 0, v141, vcc
	global_store_short v[142:143], v138, off
	v_add_co_u32_e32 v138, vcc, s85, v140
	v_cvt_pk_bf16_f32 v142, v139, s0
	s_nop 0
	v_addc_co_u32_e32 v139, vcc, 0, v141, vcc
	global_store_short v[138:139], v142, off
	v_add_co_u32_e32 v138, vcc, s87, v140
	v_cvt_pk_bf16_f32 v142, v146, s0
	s_nop 0
	v_addc_co_u32_e32 v139, vcc, 0, v141, vcc
	global_store_short v[138:139], v142, off
	ds_read_b32 v138, v136 offset:576
	v_cvt_pk_bf16_f32 v139, v147, s0
	v_add_co_u32_e32 v140, vcc, s88, v140
	s_mov_b64 s[20:21], 0x120
	s_nop 0
	v_addc_co_u32_e32 v141, vcc, 0, v141, vcc
	s_waitcnt lgkmcnt(0)
	v_pk_mul_f32 v[142:143], v[86:87], v[138:139] op_sel_hi:[1,0]
	global_store_short v[140:141], v139, off
	v_lshl_add_u64 v[146:147], v[134:135], 0, s[20:21]
	v_cvt_pk_bf16_f32 v142, v142, s0
	global_store_short v[146:147], v142, off
	v_add_co_u32_e32 v142, vcc, s86, v146
	v_cvt_pk_bf16_f32 v148, v143, s0
	s_nop 0
	v_addc_co_u32_e32 v143, vcc, 0, v147, vcc
	v_pk_mul_f32 v[140:141], v[88:89], v[138:139] op_sel_hi:[1,0]
	global_store_short v[142:143], v148, off
	v_add_co_u32_e32 v142, vcc, s67, v146
	v_cvt_pk_bf16_f32 v140, v140, s0
	s_nop 0
	v_addc_co_u32_e32 v143, vcc, 0, v147, vcc
	global_store_short v[142:143], v140, off
	v_add_co_u32_e32 v140, vcc, s89, v146
	v_cvt_pk_bf16_f32 v142, v141, s0
	s_nop 0
	v_addc_co_u32_e32 v141, vcc, 0, v147, vcc
	v_pk_mul_f32 v[144:145], v[84:85], v[138:139] op_sel_hi:[1,0]
	v_pk_mul_f32 v[138:139], v[82:83], v[138:139] op_sel_hi:[1,0]
	global_store_short v[140:141], v142, off
	v_add_co_u32_e32 v140, vcc, s63, v146
	v_cvt_pk_bf16_f32 v138, v138, s0
	s_nop 0
	v_addc_co_u32_e32 v141, vcc, 0, v147, vcc
	global_store_short v[140:141], v138, off
	v_add_co_u32_e32 v138, vcc, s85, v146
	v_cvt_pk_bf16_f32 v140, v139, s0
	s_nop 0
	v_addc_co_u32_e32 v139, vcc, 0, v147, vcc
	global_store_short v[138:139], v140, off
	v_add_co_u32_e32 v138, vcc, s87, v146
	v_cvt_pk_bf16_f32 v140, v144, s0
	s_nop 0
	v_addc_co_u32_e32 v139, vcc, 0, v147, vcc
	global_store_short v[138:139], v140, off
	ds_read_b32 v138, v136 offset:640
	v_cvt_pk_bf16_f32 v139, v145, s0
	v_add_co_u32_e32 v140, vcc, s88, v146
	s_mov_b64 s[20:21], 0x140
	s_nop 0
	v_addc_co_u32_e32 v141, vcc, 0, v147, vcc
	s_waitcnt lgkmcnt(0)
; DI unsigned pk2(float a, float b) { f32x2 v = {a, b}; return __builtin_bit_cast(unsigned, __builtin_convertvector(v, bf2_t)); }
; DI bf16_t tobf(float a) { return (bf16_t)(pk2(a, 0.f) & 0xffffu); }
; template <typename T> DI T* opaque(T* p) { asm volatile("" : "+v"(p) : : "memory"); return p; }
;     DI void operator()(const pg8::f32x4 (&acc)[2][2][4][2], const pg8::Unit& u, int wr, int wc, int fr, int fq) const {
;     ...
;             if (within < 64) {
;                 bf16_t* pb = (bf16_t*)(ws + O_MK) + ((size_t)bh * S_ + s0) * 96 + within + 8 * fq;
; #pragma unroll
;                 for (int ai = 0; ai < 2; ++ai)
; #pragma unroll
;                     for (int m = 0; m < 4; ++m) {
;                         const float sc = rs[ai * 128 + wr * 64 + m * 16 + fr];
;                         const f32x4 v0 = acc[ai][bj][m][0] * sc, v1 = acc[ai][bj][m][1] * sc;
;                         u32x4 wv; wv.x = pk2(v0.x, v0.y); wv.y = pk2(v0.z, v0.w); wv.z = pk2(v1.x, v1.y); wv.w = pk2(v1.z, v1.w);
;                         *(u32x4*)(opaque(pb) + (size_t)(ai * 128 + m * 16) * 96) = wv;
;                         asm volatile("" ::: "memory");
;                     }
;             } else {
;                 bf16_t* pb = (bf16_t*)(ws + O_MVT) + ((size_t)bh * 64 + (within - 64) + 8 * fq) * S_ + s0;
; #pragma unroll
;                 for (int ai = 0; ai < 2; ++ai)
; #pragma unroll
;                     for (int m = 0; m < 4; ++m) {
;                         const float sc = rs[ai * 128 + wr * 64 + m * 16 + fr];
;                         const f32x4 v0 = acc[ai][bj][m][0] * sc, v1 = acc[ai][bj][m][1] * sc;
;                         bf16_t* q = opaque(pb + ai * 128 + m * 16);
;                         q[0] = tobf(v0.x); q[(size_t)S_] = tobf(v0.y); q[(size_t)2 * S_] = tobf(v0.z); q[(size_t)3 * S_] = tobf(v0.w);
;                         q[(size_t)4 * S_] = tobf(v1.x); q[(size_t)5 * S_] = tobf(v1.y); q[(size_t)6 * S_] = tobf(v1.z); q[(size_t)7 * S_] = tobf(v1.w);
;                     }
	v_pk_mul_f32 v[142:143], v[78:79], v[138:139] op_sel_hi:[1,0]
	global_store_short v[140:141], v139, off
	v_lshl_add_u64 v[146:147], v[134:135], 0, s[20:21]
	v_cvt_pk_bf16_f32 v142, v142, s0
	global_store_short v[146:147], v142, off
	v_add_co_u32_e32 v142, vcc, s86, v146
	v_cvt_pk_bf16_f32 v148, v143, s0
	s_nop 0
	v_addc_co_u32_e32 v143, vcc, 0, v147, vcc
	v_pk_mul_f32 v[140:141], v[80:81], v[138:139] op_sel_hi:[1,0]
	global_store_short v[142:143], v148, off
	v_add_co_u32_e32 v142, vcc, s67, v146
	v_cvt_pk_bf16_f32 v140, v140, s0
	s_nop 0
	v_addc_co_u32_e32 v143, vcc, 0, v147, vcc
	global_store_short v[142:143], v140, off
	v_add_co_u32_e32 v140, vcc, s89, v146
	v_cvt_pk_bf16_f32 v142, v141, s0
	s_nop 0
	v_addc_co_u32_e32 v141, vcc, 0, v147, vcc
	v_pk_mul_f32 v[144:145], v[76:77], v[138:139] op_sel_hi:[1,0]
	v_pk_mul_f32 v[138:139], v[74:75], v[138:139] op_sel_hi:[1,0]
	global_store_short v[140:141], v142, off
	v_add_co_u32_e32 v140, vcc, s63, v146
	v_cvt_pk_bf16_f32 v138, v138, s0
	s_nop 0
	v_addc_co_u32_e32 v141, vcc, 0, v147, vcc
	global_store_short v[140:141], v138, off
	v_add_co_u32_e32 v138, vcc, s85, v146
	v_cvt_pk_bf16_f32 v140, v139, s0
	s_nop 0
	v_addc_co_u32_e32 v139, vcc, 0, v147, vcc
	global_store_short v[138:139], v140, off
	v_add_co_u32_e32 v138, vcc, s87, v146
	v_cvt_pk_bf16_f32 v140, v144, s0
	s_nop 0
	v_addc_co_u32_e32 v139, vcc, 0, v147, vcc
	global_store_short v[138:139], v140, off
	ds_read_b32 v138, v136 offset:704
	v_cvt_pk_bf16_f32 v139, v145, s0
	v_add_co_u32_e32 v140, vcc, s88, v146
	s_mov_b64 s[20:21], 0x160
	s_nop 0
	v_addc_co_u32_e32 v141, vcc, 0, v147, vcc
	s_waitcnt lgkmcnt(0)
	v_pk_mul_f32 v[142:143], v[70:71], v[138:139] op_sel_hi:[1,0]
	global_store_short v[140:141], v139, off
	v_lshl_add_u64 v[134:135], v[134:135], 0, s[20:21]
	v_cvt_pk_bf16_f32 v142, v142, s0
	global_store_short v[134:135], v142, off
	v_add_co_u32_e32 v142, vcc, s86, v134
	v_cvt_pk_bf16_f32 v146, v143, s0
	s_nop 0
	v_addc_co_u32_e32 v143, vcc, 0, v135, vcc
	v_pk_mul_f32 v[140:141], v[72:73], v[138:139] op_sel_hi:[1,0]
	global_store_short v[142:143], v146, off
	v_add_co_u32_e32 v142, vcc, s67, v134
	v_cvt_pk_bf16_f32 v140, v140, s0
	s_nop 0
	v_addc_co_u32_e32 v143, vcc, 0, v135, vcc
	global_store_short v[142:143], v140, off
	v_add_co_u32_e32 v140, vcc, s89, v134
	v_cvt_pk_bf16_f32 v142, v141, s0
	s_nop 0
	v_addc_co_u32_e32 v141, vcc, 0, v135, vcc
	v_pk_mul_f32 v[144:145], v[68:69], v[138:139] op_sel_hi:[1,0]
	v_pk_mul_f32 v[138:139], v[66:67], v[138:139] op_sel_hi:[1,0]
	global_store_short v[140:141], v142, off
	v_add_co_u32_e32 v140, vcc, s63, v134
	v_cvt_pk_bf16_f32 v138, v138, s0
	s_nop 0
	v_addc_co_u32_e32 v141, vcc, 0, v135, vcc
	global_store_short v[140:141], v138, off
	v_add_co_u32_e32 v138, vcc, s85, v134
	v_cvt_pk_bf16_f32 v140, v139, s0
	s_nop 0
	v_addc_co_u32_e32 v139, vcc, 0, v135, vcc
	global_store_short v[138:139], v140, off
	v_add_co_u32_e32 v138, vcc, 0x18000, v134
	v_cvt_pk_bf16_f32 v140, v144, s0
	s_nop 0
	v_addc_co_u32_e32 v139, vcc, 0, v135, vcc
	v_add_co_u32_e32 v134, vcc, 0x1c000, v134
	global_store_short v[138:139], v140, off
	v_cvt_pk_bf16_f32 v138, v145, s0
	v_addc_co_u32_e32 v135, vcc, 0, v135, vcc
	global_store_short v[134:135], v138, off
	s_mov_b64 s[20:21], 0
.LBB0_637:
	s_andn2_b64 vcc, exec, s[20:21]
	s_cbranch_vccnz .LBB0_639
	s_lshl_b64 s[20:21], s[18:19], 13
	v_or_b32_e32 v138, s20, v137
	v_mov_b64_e32 v[134:135], s[4:5]
	v_mad_u64_u32 v[134:135], s[22:23], v138, s79, v[134:135]
	v_mad_i32_i24 v135, s21, v227, v135
	v_lshl_add_u64 v[134:135], v[130:131], 1, v[134:135]
	v_cvt_pk_bf16_f32 v126, v126, v127
	v_cvt_pk_bf16_f32 v127, v128, v129
	v_cvt_pk_bf16_f32 v128, v132, v133
	v_cvt_pk_bf16_f32 v129, v124, v125
	v_mov_b64_e32 v[124:125], v[134:135]
	global_store_dwordx4 v[124:125], v[126:129], off
	ds_read_b32 v124, v136 offset:64
	s_movk_i32 s17, 0x7000
	s_waitcnt lgkmcnt(0)
	v_pk_mul_f32 v[120:121], v[120:121], v[124:125] op_sel_hi:[1,0]
	v_pk_mul_f32 v[118:119], v[118:119], v[124:125] op_sel_hi:[1,0]
	v_pk_mul_f32 v[126:127], v[116:117], v[124:125] op_sel_hi:[1,0]
	v_pk_mul_f32 v[116:117], v[114:115], v[124:125] op_sel_hi:[1,0]
	v_cvt_pk_bf16_f32 v114, v118, v119
	v_cvt_pk_bf16_f32 v115, v120, v121
	v_cvt_pk_bf16_f32 v116, v116, v117
	v_cvt_pk_bf16_f32 v117, v126, v127
	v_mov_b64_e32 v[118:119], v[134:135]
	global_store_dwordx4 v[118:119], v[114:117], off offset:3072
	ds_read_b32 v114, v136 offset:128
	s_waitcnt lgkmcnt(0)
	v_pk_mul_f32 v[110:111], v[110:111], v[114:115] op_sel_hi:[1,0]
	v_pk_mul_f32 v[116:117], v[108:109], v[114:115] op_sel_hi:[1,0]
	v_pk_mul_f32 v[108:109], v[106:107], v[114:115] op_sel_hi:[1,0]
	v_cvt_pk_bf16_f32 v106, v110, v111
	v_mov_b64_e32 v[110:111], v[134:135]
	v_pk_mul_f32 v[112:113], v[112:113], v[114:115] op_sel_hi:[1,0]
	v_add_co_u32_e32 v110, vcc, s90, v110
	v_cvt_pk_bf16_f32 v107, v112, v113
	v_cvt_pk_bf16_f32 v108, v108, v109
	v_cvt_pk_bf16_f32 v109, v116, v117
	v_addc_co_u32_e32 v111, vcc, 0, v111, vcc
	global_store_dwordx4 v[110:111], v[106:109], off offset:2048
	ds_read_b32 v106, v136 offset:192
	s_waitcnt lgkmcnt(0)
	v_pk_mul_f32 v[102:103], v[102:103], v[106:107] op_sel_hi:[1,0]
	v_pk_mul_f32 v[108:109], v[100:101], v[106:107] op_sel_hi:[1,0]
	v_pk_mul_f32 v[100:101], v[98:99], v[106:107] op_sel_hi:[1,0]
	v_cvt_pk_bf16_f32 v98, v102, v103
	v_mov_b64_e32 v[102:103], v[134:135]
	v_pk_mul_f32 v[104:105], v[104:105], v[106:107] op_sel_hi:[1,0]
	v_add_co_u32_e32 v102, vcc, s0, v102
	v_cvt_pk_bf16_f32 v99, v104, v105
	v_cvt_pk_bf16_f32 v100, v100, v101
	v_cvt_pk_bf16_f32 v101, v108, v109
	v_addc_co_u32_e32 v103, vcc, 0, v103, vcc
	global_store_dwordx4 v[102:103], v[98:101], off offset:1024
	ds_read_b32 v98, v136 offset:512
	s_waitcnt lgkmcnt(0)
; DI unsigned pk2(float a, float b) { f32x2 v = {a, b}; return __builtin_bit_cast(unsigned, __builtin_convertvector(v, bf2_t)); }
; DI bf16_t tobf(float a) { return (bf16_t)(pk2(a, 0.f) & 0xffffu); }
; template <typename T> DI T* opaque(T* p) { asm volatile("" : "+v"(p) : : "memory"); return p; }
;     DI void operator()(const pg8::f32x4 (&acc)[2][2][4][2], const pg8::Unit& u, int wr, int wc, int fr, int fq) const {
;     ...
;             if (within < 64) {
;                 bf16_t* pb = (bf16_t*)(ws + O_MK) + ((size_t)bh * S_ + s0) * 96 + within + 8 * fq;
; #pragma unroll
;                 for (int ai = 0; ai < 2; ++ai)
; #pragma unroll
;                     for (int m = 0; m < 4; ++m) {
;                         const float sc = rs[ai * 128 + wr * 64 + m * 16 + fr];
;                         const f32x4 v0 = acc[ai][bj][m][0] * sc, v1 = acc[ai][bj][m][1] * sc;
;                         u32x4 wv; wv.x = pk2(v0.x, v0.y); wv.y = pk2(v0.z, v0.w); wv.z = pk2(v1.x, v1.y); wv.w = pk2(v1.z, v1.w);
;                         *(u32x4*)(opaque(pb) + (size_t)(ai * 128 + m * 16) * 96) = wv;
;                         asm volatile("" ::: "memory");
;                     }
;             } else {
;                 bf16_t* pb = (bf16_t*)(ws + O_MVT) + ((size_t)bh * 64 + (within - 64) + 8 * fq) * S_ + s0;
; #pragma unroll
;                 for (int ai = 0; ai < 2; ++ai)
; #pragma unroll
;                     for (int m = 0; m < 4; ++m) {
;                         const float sc = rs[ai * 128 + wr * 64 + m * 16 + fr];
;                         const f32x4 v0 = acc[ai][bj][m][0] * sc, v1 = acc[ai][bj][m][1] * sc;
;                         bf16_t* q = opaque(pb + ai * 128 + m * 16);
;                         q[0] = tobf(v0.x); q[(size_t)S_] = tobf(v0.y); q[(size_t)2 * S_] = tobf(v0.z); q[(size_t)3 * S_] = tobf(v0.w);
;                         q[(size_t)4 * S_] = tobf(v1.x); q[(size_t)5 * S_] = tobf(v1.y); q[(size_t)6 * S_] = tobf(v1.z); q[(size_t)7 * S_] = tobf(v1.w);
;                     }
	v_pk_mul_f32 v[94:95], v[94:95], v[98:99] op_sel_hi:[1,0]
	v_pk_mul_f32 v[100:101], v[92:93], v[98:99] op_sel_hi:[1,0]
	v_pk_mul_f32 v[92:93], v[90:91], v[98:99] op_sel_hi:[1,0]
	v_cvt_pk_bf16_f32 v90, v94, v95
	v_mov_b64_e32 v[94:95], v[134:135]
	v_pk_mul_f32 v[96:97], v[96:97], v[98:99] op_sel_hi:[1,0]
	v_add_co_u32_e32 v94, vcc, s1, v94
	v_cvt_pk_bf16_f32 v91, v96, v97
	v_cvt_pk_bf16_f32 v92, v92, v93
	v_cvt_pk_bf16_f32 v93, v100, v101
	v_addc_co_u32_e32 v95, vcc, 0, v95, vcc
	global_store_dwordx4 v[94:95], v[90:93], off
	ds_read_b32 v90, v136 offset:576
	s_waitcnt lgkmcnt(0)
	v_pk_mul_f32 v[86:87], v[86:87], v[90:91] op_sel_hi:[1,0]
	v_pk_mul_f32 v[92:93], v[84:85], v[90:91] op_sel_hi:[1,0]
	v_pk_mul_f32 v[84:85], v[82:83], v[90:91] op_sel_hi:[1,0]
	v_cvt_pk_bf16_f32 v82, v86, v87
	v_mov_b64_e32 v[86:87], v[134:135]
	v_pk_mul_f32 v[88:89], v[88:89], v[90:91] op_sel_hi:[1,0]
	v_add_co_u32_e32 v86, vcc, s1, v86
	v_cvt_pk_bf16_f32 v83, v88, v89
	v_cvt_pk_bf16_f32 v84, v84, v85
	v_cvt_pk_bf16_f32 v85, v92, v93
	v_addc_co_u32_e32 v87, vcc, 0, v87, vcc
	global_store_dwordx4 v[86:87], v[82:85], off offset:3072
	ds_read_b32 v82, v136 offset:640
	s_waitcnt lgkmcnt(0)
	v_pk_mul_f32 v[78:79], v[78:79], v[82:83] op_sel_hi:[1,0]
	v_pk_mul_f32 v[84:85], v[76:77], v[82:83] op_sel_hi:[1,0]
	v_pk_mul_f32 v[76:77], v[74:75], v[82:83] op_sel_hi:[1,0]
	v_cvt_pk_bf16_f32 v74, v78, v79
	v_mov_b64_e32 v[78:79], v[134:135]
	v_pk_mul_f32 v[80:81], v[80:81], v[82:83] op_sel_hi:[1,0]
	v_add_co_u32_e32 v78, vcc, s17, v78
	v_cvt_pk_bf16_f32 v75, v80, v81
	v_cvt_pk_bf16_f32 v76, v76, v77
	v_cvt_pk_bf16_f32 v77, v84, v85
	v_addc_co_u32_e32 v79, vcc, 0, v79, vcc
	global_store_dwordx4 v[78:79], v[74:77], off offset:2048
	ds_read_b32 v74, v136 offset:704
	s_waitcnt lgkmcnt(0)
	v_pk_mul_f32 v[70:71], v[70:71], v[74:75] op_sel_hi:[1,0]
	v_pk_mul_f32 v[72:73], v[72:73], v[74:75] op_sel_hi:[1,0]
	v_pk_mul_f32 v[76:77], v[68:69], v[74:75] op_sel_hi:[1,0]
	v_pk_mul_f32 v[68:69], v[66:67], v[74:75] op_sel_hi:[1,0]
	v_cvt_pk_bf16_f32 v66, v70, v71
	v_add_co_u32_e32 v70, vcc, 0x8000, v134
	v_cvt_pk_bf16_f32 v67, v72, v73
	v_cvt_pk_bf16_f32 v68, v68, v69
	v_cvt_pk_bf16_f32 v69, v76, v77
	v_addc_co_u32_e32 v71, vcc, 0, v135, vcc
	global_store_dwordx4 v[70:71], v[66:69], off offset:1024
.LBB0_639:
	ds_read_b32 v66, v136
	s_add_i32 s18, s18, 1
	s_ashr_i32 s19, s18, 31
	s_andn2_b64 vcc, exec, s[6:7]
	s_mov_b64 s[6:7], -1
	s_waitcnt lgkmcnt(0)
	v_pk_mul_f32 v[64:65], v[64:65], v[66:67] op_sel_hi:[1,0]
	v_pk_mul_f32 v[62:63], v[62:63], v[66:67] op_sel_hi:[1,0]
	v_pk_mul_f32 v[60:61], v[60:61], v[66:67] op_sel_hi:[1,0]
	v_pk_mul_f32 v[58:59], v[58:59], v[66:67] op_sel_hi:[1,0]
	s_cbranch_vccnz .LBB0_641
	s_lshl_b64 s[6:7], s[18:19], 20
	s_add_u32 s6, s34, s6
	s_addc_u32 s7, s35, s7
	v_lshl_add_u64 v[66:67], s[6:7], 0, v[122:123]
	v_lshl_add_u64 v[66:67], v[66:67], 0, v[0:1]
	v_mov_b64_e32 v[68:69], v[66:67]
	v_cvt_pk_bf16_f32 v72, v63, s0
	v_add_co_u32_e32 v70, vcc, s86, v68
	v_cvt_pk_bf16_f32 v0, v62, s0
	s_nop 0
	v_addc_co_u32_e32 v71, vcc, 0, v69, vcc
	global_store_short v[70:71], v72, off
	v_add_co_u32_e32 v70, vcc, s67, v68
	global_store_short v[68:69], v0, off
	v_cvt_pk_bf16_f32 v0, v64, s0
	v_addc_co_u32_e32 v71, vcc, 0, v69, vcc
	global_store_short v[70:71], v0, off
	v_add_co_u32_e32 v70, vcc, s89, v68
	v_cvt_pk_bf16_f32 v0, v65, s0
	s_nop 0
	v_addc_co_u32_e32 v71, vcc, 0, v69, vcc
	global_store_short v[70:71], v0, off
	v_add_co_u32_e32 v70, vcc, s63, v68
	v_cvt_pk_bf16_f32 v0, v58, s0
	s_nop 0
	v_addc_co_u32_e32 v71, vcc, 0, v69, vcc
	global_store_short v[70:71], v0, off
	v_add_co_u32_e32 v70, vcc, s85, v68
	v_cvt_pk_bf16_f32 v0, v59, s0
	s_nop 0
	v_addc_co_u32_e32 v71, vcc, 0, v69, vcc
	global_store_short v[70:71], v0, off
	v_add_co_u32_e32 v70, vcc, s87, v68
	v_cvt_pk_bf16_f32 v0, v60, s0
	s_nop 0
	v_addc_co_u32_e32 v71, vcc, 0, v69, vcc
	global_store_short v[70:71], v0, off
	ds_read_b32 v0, v136 offset:64
	v_add_co_u32_e32 v68, vcc, s88, v68
	v_cvt_pk_bf16_f32 v70, v61, s0
	s_nop 0
	v_addc_co_u32_e32 v69, vcc, 0, v69, vcc
	global_store_short v[68:69], v70, off
	s_waitcnt lgkmcnt(0)
	v_pk_mul_f32 v[70:71], v[54:55], v[0:1] op_sel_hi:[1,0]
	v_lshl_add_u64 v[76:77], v[66:67], 0, 32
	v_pk_mul_f32 v[68:69], v[56:57], v[0:1] op_sel_hi:[1,0]
	v_pk_mul_f32 v[72:73], v[52:53], v[0:1] op_sel_hi:[1,0]
	v_pk_mul_f32 v[74:75], v[50:51], v[0:1] op_sel_hi:[1,0]
	v_cvt_pk_bf16_f32 v0, v70, s0
	v_add_co_u32_e32 v70, vcc, s86, v76
	global_store_short v[76:77], v0, off
	v_cvt_pk_bf16_f32 v0, v71, s0
	v_addc_co_u32_e32 v71, vcc, 0, v77, vcc
	global_store_short v[70:71], v0, off
	v_add_co_u32_e32 v70, vcc, s67, v76
	v_cvt_pk_bf16_f32 v0, v68, s0
	s_nop 0
	v_addc_co_u32_e32 v71, vcc, 0, v77, vcc
	v_add_co_u32_e32 v68, vcc, s89, v76
	global_store_short v[70:71], v0, off
	v_cvt_pk_bf16_f32 v0, v69, s0
	v_addc_co_u32_e32 v69, vcc, 0, v77, vcc
	global_store_short v[68:69], v0, off
	v_add_co_u32_e32 v68, vcc, s63, v76
	v_cvt_pk_bf16_f32 v0, v74, s0
	s_nop 0
	v_addc_co_u32_e32 v69, vcc, 0, v77, vcc
	global_store_short v[68:69], v0, off
	v_add_co_u32_e32 v68, vcc, s85, v76
	v_cvt_pk_bf16_f32 v0, v75, s0
	s_nop 0
	v_addc_co_u32_e32 v69, vcc, 0, v77, vcc
	global_store_short v[68:69], v0, off
	v_add_co_u32_e32 v68, vcc, s87, v76
	v_cvt_pk_bf16_f32 v0, v72, s0
	s_nop 0
	v_addc_co_u32_e32 v69, vcc, 0, v77, vcc
	global_store_short v[68:69], v0, off
	ds_read_b32 v0, v136 offset:128
	v_add_co_u32_e32 v68, vcc, s88, v76
	v_cvt_pk_bf16_f32 v70, v73, s0
	s_nop 0
	v_addc_co_u32_e32 v69, vcc, 0, v77, vcc
	global_store_short v[68:69], v70, off
	s_waitcnt lgkmcnt(0)
; DI bf16_t tobf(float a) { return (bf16_t)(pk2(a, 0.f) & 0xffffu); }
; template <typename T> DI T* opaque(T* p) { asm volatile("" : "+v"(p) : : "memory"); return p; }
;     DI void operator()(const pg8::f32x4 (&acc)[2][2][4][2], const pg8::Unit& u, int wr, int wc, int fr, int fq) const {
;     ...
;             } else {
;                 bf16_t* pb = (bf16_t*)(ws + O_MVT) + ((size_t)bh * 64 + (within - 64) + 8 * fq) * S_ + s0;
; #pragma unroll
;                 for (int ai = 0; ai < 2; ++ai)
; #pragma unroll
;                     for (int m = 0; m < 4; ++m) {
;                         const float sc = rs[ai * 128 + wr * 64 + m * 16 + fr];
;                         const f32x4 v0 = acc[ai][bj][m][0] * sc, v1 = acc[ai][bj][m][1] * sc;
;                         bf16_t* q = opaque(pb + ai * 128 + m * 16);
;                         q[0] = tobf(v0.x); q[(size_t)S_] = tobf(v0.y); q[(size_t)2 * S_] = tobf(v0.z); q[(size_t)3 * S_] = tobf(v0.w);
;                         q[(size_t)4 * S_] = tobf(v1.x); q[(size_t)5 * S_] = tobf(v1.y); q[(size_t)6 * S_] = tobf(v1.z); q[(size_t)7 * S_] = tobf(v1.w);
;                     }
	v_pk_mul_f32 v[70:71], v[46:47], v[0:1] op_sel_hi:[1,0]
	v_lshl_add_u64 v[76:77], v[66:67], 0, 64
	v_pk_mul_f32 v[68:69], v[48:49], v[0:1] op_sel_hi:[1,0]
	v_pk_mul_f32 v[72:73], v[44:45], v[0:1] op_sel_hi:[1,0]
	v_pk_mul_f32 v[74:75], v[42:43], v[0:1] op_sel_hi:[1,0]
	v_cvt_pk_bf16_f32 v0, v70, s0
	v_add_co_u32_e32 v70, vcc, s86, v76
	global_store_short v[76:77], v0, off
	v_cvt_pk_bf16_f32 v0, v71, s0
	v_addc_co_u32_e32 v71, vcc, 0, v77, vcc
	global_store_short v[70:71], v0, off
	v_add_co_u32_e32 v70, vcc, s67, v76
	v_cvt_pk_bf16_f32 v0, v68, s0
	s_nop 0
	v_addc_co_u32_e32 v71, vcc, 0, v77, vcc
	v_add_co_u32_e32 v68, vcc, s89, v76
	global_store_short v[70:71], v0, off
	v_cvt_pk_bf16_f32 v0, v69, s0
	v_addc_co_u32_e32 v69, vcc, 0, v77, vcc
	global_store_short v[68:69], v0, off
	v_add_co_u32_e32 v68, vcc, s63, v76
	v_cvt_pk_bf16_f32 v0, v74, s0
	s_nop 0
	v_addc_co_u32_e32 v69, vcc, 0, v77, vcc
	global_store_short v[68:69], v0, off
	v_add_co_u32_e32 v68, vcc, s85, v76
	v_cvt_pk_bf16_f32 v0, v75, s0
	s_nop 0
	v_addc_co_u32_e32 v69, vcc, 0, v77, vcc
	global_store_short v[68:69], v0, off
	v_add_co_u32_e32 v68, vcc, s87, v76
	v_cvt_pk_bf16_f32 v0, v72, s0
	s_nop 0
	v_addc_co_u32_e32 v69, vcc, 0, v77, vcc
	global_store_short v[68:69], v0, off
	ds_read_b32 v0, v136 offset:192
	v_add_co_u32_e32 v68, vcc, s88, v76
	v_cvt_pk_bf16_f32 v70, v73, s0
	s_nop 0
	v_addc_co_u32_e32 v69, vcc, 0, v77, vcc
	s_mov_b64 s[6:7], 0x60
	global_store_short v[68:69], v70, off
	s_waitcnt lgkmcnt(0)
	v_pk_mul_f32 v[70:71], v[38:39], v[0:1] op_sel_hi:[1,0]
	v_lshl_add_u64 v[76:77], v[66:67], 0, s[6:7]
	v_pk_mul_f32 v[68:69], v[40:41], v[0:1] op_sel_hi:[1,0]
	v_pk_mul_f32 v[72:73], v[36:37], v[0:1] op_sel_hi:[1,0]
	v_pk_mul_f32 v[74:75], v[34:35], v[0:1] op_sel_hi:[1,0]
	v_cvt_pk_bf16_f32 v0, v70, s0
	v_add_co_u32_e32 v70, vcc, s86, v76
	global_store_short v[76:77], v0, off
	v_cvt_pk_bf16_f32 v0, v71, s0
	v_addc_co_u32_e32 v71, vcc, 0, v77, vcc
	global_store_short v[70:71], v0, off
	v_add_co_u32_e32 v70, vcc, s67, v76
	v_cvt_pk_bf16_f32 v0, v68, s0
	s_nop 0
	v_addc_co_u32_e32 v71, vcc, 0, v77, vcc
	v_add_co_u32_e32 v68, vcc, s89, v76
	global_store_short v[70:71], v0, off
	v_cvt_pk_bf16_f32 v0, v69, s0
	v_addc_co_u32_e32 v69, vcc, 0, v77, vcc
	global_store_short v[68:69], v0, off
	v_add_co_u32_e32 v68, vcc, s63, v76
	v_cvt_pk_bf16_f32 v0, v74, s0
	s_nop 0
	v_addc_co_u32_e32 v69, vcc, 0, v77, vcc
	global_store_short v[68:69], v0, off
	v_add_co_u32_e32 v68, vcc, s85, v76
	v_cvt_pk_bf16_f32 v0, v75, s0
	s_nop 0
	v_addc_co_u32_e32 v69, vcc, 0, v77, vcc
	global_store_short v[68:69], v0, off
	v_add_co_u32_e32 v68, vcc, s87, v76
	v_cvt_pk_bf16_f32 v0, v72, s0
	s_nop 0
	v_addc_co_u32_e32 v69, vcc, 0, v77, vcc
	global_store_short v[68:69], v0, off
	ds_read_b32 v0, v136 offset:512
	v_add_co_u32_e32 v68, vcc, s88, v76
	v_cvt_pk_bf16_f32 v70, v73, s0
	s_nop 0
	v_addc_co_u32_e32 v69, vcc, 0, v77, vcc
	s_mov_b64 s[6:7], 0x100
	global_store_short v[68:69], v70, off
	v_lshl_add_u64 v[68:69], v[66:67], 0, s[6:7]
	s_waitcnt lgkmcnt(0)
	v_pk_mul_f32 v[72:73], v[30:31], v[0:1] op_sel_hi:[1,0]
	v_pk_mul_f32 v[70:71], v[32:33], v[0:1] op_sel_hi:[1,0]
	v_pk_mul_f32 v[74:75], v[28:29], v[0:1] op_sel_hi:[1,0]
	v_pk_mul_f32 v[76:77], v[26:27], v[0:1] op_sel_hi:[1,0]
	v_cvt_pk_bf16_f32 v0, v72, s0
	v_add_co_u32_e32 v72, vcc, s86, v68
	global_store_short v[68:69], v0, off
	v_cvt_pk_bf16_f32 v0, v73, s0
	v_addc_co_u32_e32 v73, vcc, 0, v69, vcc
	global_store_short v[72:73], v0, off
	v_add_co_u32_e32 v72, vcc, s67, v68
	v_cvt_pk_bf16_f32 v0, v70, s0
	s_nop 0
	v_addc_co_u32_e32 v73, vcc, 0, v69, vcc
	v_add_co_u32_e32 v70, vcc, s89, v68
	global_store_short v[72:73], v0, off
	v_cvt_pk_bf16_f32 v0, v71, s0
	v_addc_co_u32_e32 v71, vcc, 0, v69, vcc
	global_store_short v[70:71], v0, off
	v_add_co_u32_e32 v70, vcc, s63, v68
	v_cvt_pk_bf16_f32 v0, v76, s0
	s_nop 0
	v_addc_co_u32_e32 v71, vcc, 0, v69, vcc
	global_store_short v[70:71], v0, off
	v_add_co_u32_e32 v70, vcc, s85, v68
	v_cvt_pk_bf16_f32 v0, v77, s0
	s_nop 0
	v_addc_co_u32_e32 v71, vcc, 0, v69, vcc
	global_store_short v[70:71], v0, off
	v_add_co_u32_e32 v70, vcc, s87, v68
	v_cvt_pk_bf16_f32 v0, v74, s0
	s_nop 0
	v_addc_co_u32_e32 v71, vcc, 0, v69, vcc
	global_store_short v[70:71], v0, off
	ds_read_b32 v0, v136 offset:576
	v_add_co_u32_e32 v68, vcc, s88, v68
	v_cvt_pk_bf16_f32 v70, v75, s0
	s_nop 0
	v_addc_co_u32_e32 v69, vcc, 0, v69, vcc
	s_mov_b64 s[6:7], 0x120
	global_store_short v[68:69], v70, off
	s_waitcnt lgkmcnt(0)
	v_pk_mul_f32 v[70:71], v[22:23], v[0:1] op_sel_hi:[1,0]
	v_lshl_add_u64 v[76:77], v[66:67], 0, s[6:7]
	v_pk_mul_f32 v[68:69], v[24:25], v[0:1] op_sel_hi:[1,0]
	v_pk_mul_f32 v[72:73], v[20:21], v[0:1] op_sel_hi:[1,0]
	v_pk_mul_f32 v[74:75], v[18:19], v[0:1] op_sel_hi:[1,0]
	v_cvt_pk_bf16_f32 v0, v70, s0
	v_add_co_u32_e32 v70, vcc, s86, v76
	global_store_short v[76:77], v0, off
	v_cvt_pk_bf16_f32 v0, v71, s0
	v_addc_co_u32_e32 v71, vcc, 0, v77, vcc
	global_store_short v[70:71], v0, off
	v_add_co_u32_e32 v70, vcc, s67, v76
	v_cvt_pk_bf16_f32 v0, v68, s0
	s_nop 0
	v_addc_co_u32_e32 v71, vcc, 0, v77, vcc
	v_add_co_u32_e32 v68, vcc, s89, v76
	global_store_short v[70:71], v0, off
	v_cvt_pk_bf16_f32 v0, v69, s0
	v_addc_co_u32_e32 v69, vcc, 0, v77, vcc
	global_store_short v[68:69], v0, off
	v_add_co_u32_e32 v68, vcc, s63, v76
	v_cvt_pk_bf16_f32 v0, v74, s0
	s_nop 0
	v_addc_co_u32_e32 v69, vcc, 0, v77, vcc
	global_store_short v[68:69], v0, off
	v_add_co_u32_e32 v68, vcc, s85, v76
	v_cvt_pk_bf16_f32 v0, v75, s0
	s_nop 0
	v_addc_co_u32_e32 v69, vcc, 0, v77, vcc
	global_store_short v[68:69], v0, off
	v_add_co_u32_e32 v68, vcc, s87, v76
	v_cvt_pk_bf16_f32 v0, v72, s0
	s_nop 0
	v_addc_co_u32_e32 v69, vcc, 0, v77, vcc
	global_store_short v[68:69], v0, off
	ds_read_b32 v0, v136 offset:640
	v_add_co_u32_e32 v68, vcc, s88, v76
	v_cvt_pk_bf16_f32 v70, v73, s0
	s_nop 0
	v_addc_co_u32_e32 v69, vcc, 0, v77, vcc
	s_mov_b64 s[6:7], 0x140
	global_store_short v[68:69], v70, off
	s_waitcnt lgkmcnt(0)
; DI bf16_t tobf(float a) { return (bf16_t)(pk2(a, 0.f) & 0xffffu); }
; template <typename T> DI T* opaque(T* p) { asm volatile("" : "+v"(p) : : "memory"); return p; }
;     DI void operator()(const pg8::f32x4 (&acc)[2][2][4][2], const pg8::Unit& u, int wr, int wc, int fr, int fq) const {
;     ...
;             } else {
;                 bf16_t* pb = (bf16_t*)(ws + O_MVT) + ((size_t)bh * 64 + (within - 64) + 8 * fq) * S_ + s0;
; #pragma unroll
;                 for (int ai = 0; ai < 2; ++ai)
; #pragma unroll
;                     for (int m = 0; m < 4; ++m) {
;                         const float sc = rs[ai * 128 + wr * 64 + m * 16 + fr];
;                         const f32x4 v0 = acc[ai][bj][m][0] * sc, v1 = acc[ai][bj][m][1] * sc;
;                         bf16_t* q = opaque(pb + ai * 128 + m * 16);
;                         q[0] = tobf(v0.x); q[(size_t)S_] = tobf(v0.y); q[(size_t)2 * S_] = tobf(v0.z); q[(size_t)3 * S_] = tobf(v0.w);
;                         q[(size_t)4 * S_] = tobf(v1.x); q[(size_t)5 * S_] = tobf(v1.y); q[(size_t)6 * S_] = tobf(v1.z); q[(size_t)7 * S_] = tobf(v1.w);
;                     }
	v_pk_mul_f32 v[70:71], v[14:15], v[0:1] op_sel_hi:[1,0]
	v_lshl_add_u64 v[76:77], v[66:67], 0, s[6:7]
	v_pk_mul_f32 v[68:69], v[16:17], v[0:1] op_sel_hi:[1,0]
	v_pk_mul_f32 v[72:73], v[12:13], v[0:1] op_sel_hi:[1,0]
	v_pk_mul_f32 v[74:75], v[10:11], v[0:1] op_sel_hi:[1,0]
	v_cvt_pk_bf16_f32 v0, v70, s0
	v_add_co_u32_e32 v70, vcc, s86, v76
	global_store_short v[76:77], v0, off
	v_cvt_pk_bf16_f32 v0, v71, s0
	v_addc_co_u32_e32 v71, vcc, 0, v77, vcc
	global_store_short v[70:71], v0, off
	v_add_co_u32_e32 v70, vcc, s67, v76
	v_cvt_pk_bf16_f32 v0, v68, s0
	s_nop 0
	v_addc_co_u32_e32 v71, vcc, 0, v77, vcc
	v_add_co_u32_e32 v68, vcc, s89, v76
	global_store_short v[70:71], v0, off
	v_cvt_pk_bf16_f32 v0, v69, s0
	v_addc_co_u32_e32 v69, vcc, 0, v77, vcc
	global_store_short v[68:69], v0, off
	v_add_co_u32_e32 v68, vcc, s63, v76
	v_cvt_pk_bf16_f32 v0, v74, s0
	s_nop 0
	v_addc_co_u32_e32 v69, vcc, 0, v77, vcc
	global_store_short v[68:69], v0, off
	v_add_co_u32_e32 v68, vcc, s85, v76
	v_cvt_pk_bf16_f32 v0, v75, s0
	s_nop 0
	v_addc_co_u32_e32 v69, vcc, 0, v77, vcc
	global_store_short v[68:69], v0, off
	v_add_co_u32_e32 v68, vcc, s87, v76
	v_cvt_pk_bf16_f32 v0, v72, s0
	s_nop 0
	v_addc_co_u32_e32 v69, vcc, 0, v77, vcc
	global_store_short v[68:69], v0, off
	ds_read_b32 v0, v136 offset:704
	v_add_co_u32_e32 v68, vcc, s88, v76
	v_cvt_pk_bf16_f32 v70, v73, s0
	s_nop 0
	v_addc_co_u32_e32 v69, vcc, 0, v77, vcc
	s_mov_b64 s[6:7], 0x160
	global_store_short v[68:69], v70, off
	s_waitcnt lgkmcnt(0)
	v_pk_mul_f32 v[70:71], v[6:7], v[0:1] op_sel_hi:[1,0]
	v_lshl_add_u64 v[66:67], v[66:67], 0, s[6:7]
	v_pk_mul_f32 v[68:69], v[8:9], v[0:1] op_sel_hi:[1,0]
	v_pk_mul_f32 v[72:73], v[4:5], v[0:1] op_sel_hi:[1,0]
	v_pk_mul_f32 v[74:75], v[2:3], v[0:1] op_sel_hi:[1,0]
	v_cvt_pk_bf16_f32 v0, v70, s0
	v_add_co_u32_e32 v70, vcc, s86, v66
	global_store_short v[66:67], v0, off
	v_cvt_pk_bf16_f32 v0, v71, s0
	v_addc_co_u32_e32 v71, vcc, 0, v67, vcc
	global_store_short v[70:71], v0, off
	v_add_co_u32_e32 v70, vcc, s67, v66
	v_cvt_pk_bf16_f32 v0, v68, s0
	s_nop 0
	v_addc_co_u32_e32 v71, vcc, 0, v67, vcc
	v_add_co_u32_e32 v68, vcc, s89, v66
	global_store_short v[70:71], v0, off
	v_cvt_pk_bf16_f32 v0, v69, s0
	v_addc_co_u32_e32 v69, vcc, 0, v67, vcc
	global_store_short v[68:69], v0, off
	v_add_co_u32_e32 v68, vcc, s63, v66
	v_cvt_pk_bf16_f32 v0, v74, s0
	s_nop 0
	v_addc_co_u32_e32 v69, vcc, 0, v67, vcc
	global_store_short v[68:69], v0, off
	v_add_co_u32_e32 v68, vcc, s85, v66
	v_cvt_pk_bf16_f32 v0, v75, s0
	s_nop 0
	v_addc_co_u32_e32 v69, vcc, 0, v67, vcc
	global_store_short v[68:69], v0, off
	v_add_co_u32_e32 v68, vcc, 0x18000, v66
	v_cvt_pk_bf16_f32 v0, v72, s0
	s_nop 0
	v_addc_co_u32_e32 v69, vcc, 0, v67, vcc
	v_add_co_u32_e32 v66, vcc, 0x1c000, v66
	global_store_short v[68:69], v0, off
	v_cvt_pk_bf16_f32 v0, v73, s0
	v_addc_co_u32_e32 v67, vcc, 0, v67, vcc
	s_mov_b64 s[6:7], 0
	global_store_short v[66:67], v0, off
; DI unsigned pk2(float a, float b) { f32x2 v = {a, b}; return __builtin_bit_cast(unsigned, __builtin_convertvector(v, bf2_t)); }
; template <typename T> DI T* opaque(T* p) { asm volatile("" : "+v"(p) : : "memory"); return p; }
;     DI void operator()(const pg8::f32x4 (&acc)[2][2][4][2], const pg8::Unit& u, int wr, int wc, int fr, int fq) const {
;     ...
;             if (within < 64) {
;                 bf16_t* pb = (bf16_t*)(ws + O_MK) + ((size_t)bh * S_ + s0) * 96 + within + 8 * fq;
; #pragma unroll
;                 for (int ai = 0; ai < 2; ++ai)
; #pragma unroll
;                     for (int m = 0; m < 4; ++m) {
;                         const float sc = rs[ai * 128 + wr * 64 + m * 16 + fr];
;                         const f32x4 v0 = acc[ai][bj][m][0] * sc, v1 = acc[ai][bj][m][1] * sc;
;                         u32x4 wv; wv.x = pk2(v0.x, v0.y); wv.y = pk2(v0.z, v0.w); wv.z = pk2(v1.x, v1.y); wv.w = pk2(v1.z, v1.w);
;                         *(u32x4*)(opaque(pb) + (size_t)(ai * 128 + m * 16) * 96) = wv;
;                         asm volatile("" ::: "memory");
;                     }
.LBB0_641:
	s_andn2_b64 vcc, exec, s[6:7]
	s_cbranch_vccnz .LBB0_643
	s_lshl_b64 s[6:7], s[18:19], 13
	v_or_b32_e32 v0, s6, v137
	v_mov_b64_e32 v[66:67], s[4:5]
	v_mad_u64_u32 v[66:67], s[4:5], v0, s79, v[66:67]
	v_mad_i32_i24 v67, s7, v227, v67
	v_lshl_add_u64 v[66:67], v[130:131], 1, v[66:67]
	v_cvt_pk_bf16_f32 v62, v62, v63
	v_cvt_pk_bf16_f32 v63, v64, v65
	v_cvt_pk_bf16_f32 v64, v58, v59
	v_cvt_pk_bf16_f32 v65, v60, v61
	v_mov_b64_e32 v[58:59], v[66:67]
	global_store_dwordx4 v[58:59], v[62:65], off
	ds_read_b32 v0, v136 offset:64
	s_movk_i32 s4, 0x7000
	s_waitcnt lgkmcnt(0)
	v_pk_mul_f32 v[56:57], v[56:57], v[0:1] op_sel_hi:[1,0]
	v_pk_mul_f32 v[54:55], v[54:55], v[0:1] op_sel_hi:[1,0]
	v_pk_mul_f32 v[58:59], v[52:53], v[0:1] op_sel_hi:[1,0]
	v_pk_mul_f32 v[52:53], v[50:51], v[0:1] op_sel_hi:[1,0]
	v_cvt_pk_bf16_f32 v50, v54, v55
	v_cvt_pk_bf16_f32 v51, v56, v57
	v_cvt_pk_bf16_f32 v52, v52, v53
	v_cvt_pk_bf16_f32 v53, v58, v59
	v_mov_b64_e32 v[54:55], v[66:67]
	global_store_dwordx4 v[54:55], v[50:53], off offset:3072
	ds_read_b32 v0, v136 offset:128
	s_waitcnt lgkmcnt(0)
	v_pk_mul_f32 v[46:47], v[46:47], v[0:1] op_sel_hi:[1,0]
	v_pk_mul_f32 v[50:51], v[44:45], v[0:1] op_sel_hi:[1,0]
	v_pk_mul_f32 v[44:45], v[42:43], v[0:1] op_sel_hi:[1,0]
	v_cvt_pk_bf16_f32 v42, v46, v47
	v_mov_b64_e32 v[46:47], v[66:67]
	v_pk_mul_f32 v[48:49], v[48:49], v[0:1] op_sel_hi:[1,0]
	v_add_co_u32_e32 v46, vcc, s90, v46
	v_cvt_pk_bf16_f32 v43, v48, v49
	v_cvt_pk_bf16_f32 v44, v44, v45
	v_cvt_pk_bf16_f32 v45, v50, v51
	v_addc_co_u32_e32 v47, vcc, 0, v47, vcc
	global_store_dwordx4 v[46:47], v[42:45], off offset:2048
	ds_read_b32 v0, v136 offset:192
	s_waitcnt lgkmcnt(0)
	v_pk_mul_f32 v[38:39], v[38:39], v[0:1] op_sel_hi:[1,0]
	v_pk_mul_f32 v[42:43], v[36:37], v[0:1] op_sel_hi:[1,0]
	v_pk_mul_f32 v[36:37], v[34:35], v[0:1] op_sel_hi:[1,0]
	v_cvt_pk_bf16_f32 v34, v38, v39
	v_mov_b64_e32 v[38:39], v[66:67]
	v_pk_mul_f32 v[40:41], v[40:41], v[0:1] op_sel_hi:[1,0]
	v_add_co_u32_e32 v38, vcc, s0, v38
	v_cvt_pk_bf16_f32 v35, v40, v41
	v_cvt_pk_bf16_f32 v36, v36, v37
	v_cvt_pk_bf16_f32 v37, v42, v43
	v_addc_co_u32_e32 v39, vcc, 0, v39, vcc
	global_store_dwordx4 v[38:39], v[34:37], off offset:1024
	ds_read_b32 v0, v136 offset:512
	s_waitcnt lgkmcnt(0)
	v_pk_mul_f32 v[30:31], v[30:31], v[0:1] op_sel_hi:[1,0]
	v_pk_mul_f32 v[34:35], v[28:29], v[0:1] op_sel_hi:[1,0]
	v_pk_mul_f32 v[28:29], v[26:27], v[0:1] op_sel_hi:[1,0]
	v_cvt_pk_bf16_f32 v26, v30, v31
	v_mov_b64_e32 v[30:31], v[66:67]
	v_pk_mul_f32 v[32:33], v[32:33], v[0:1] op_sel_hi:[1,0]
	v_add_co_u32_e32 v30, vcc, s1, v30
	v_cvt_pk_bf16_f32 v27, v32, v33
	v_cvt_pk_bf16_f32 v28, v28, v29
	v_cvt_pk_bf16_f32 v29, v34, v35
	v_addc_co_u32_e32 v31, vcc, 0, v31, vcc
	global_store_dwordx4 v[30:31], v[26:29], off
	ds_read_b32 v0, v136 offset:576
	s_waitcnt lgkmcnt(0)
	v_pk_mul_f32 v[22:23], v[22:23], v[0:1] op_sel_hi:[1,0]
	v_pk_mul_f32 v[26:27], v[20:21], v[0:1] op_sel_hi:[1,0]
	v_pk_mul_f32 v[20:21], v[18:19], v[0:1] op_sel_hi:[1,0]
	v_cvt_pk_bf16_f32 v18, v22, v23
	v_mov_b64_e32 v[22:23], v[66:67]
	v_pk_mul_f32 v[24:25], v[24:25], v[0:1] op_sel_hi:[1,0]
	v_add_co_u32_e32 v22, vcc, s1, v22
	v_cvt_pk_bf16_f32 v19, v24, v25
	v_cvt_pk_bf16_f32 v20, v20, v21
	v_cvt_pk_bf16_f32 v21, v26, v27
	v_addc_co_u32_e32 v23, vcc, 0, v23, vcc
	global_store_dwordx4 v[22:23], v[18:21], off offset:3072
	ds_read_b32 v0, v136 offset:640
	s_waitcnt lgkmcnt(0)
	v_pk_mul_f32 v[14:15], v[14:15], v[0:1] op_sel_hi:[1,0]
	v_pk_mul_f32 v[18:19], v[12:13], v[0:1] op_sel_hi:[1,0]
	v_pk_mul_f32 v[12:13], v[10:11], v[0:1] op_sel_hi:[1,0]
	v_cvt_pk_bf16_f32 v10, v14, v15
	v_mov_b64_e32 v[14:15], v[66:67]
	v_pk_mul_f32 v[16:17], v[16:17], v[0:1] op_sel_hi:[1,0]
	v_add_co_u32_e32 v14, vcc, s4, v14
	v_cvt_pk_bf16_f32 v11, v16, v17
	v_cvt_pk_bf16_f32 v12, v12, v13
	v_cvt_pk_bf16_f32 v13, v18, v19
	v_addc_co_u32_e32 v15, vcc, 0, v15, vcc
	global_store_dwordx4 v[14:15], v[10:13], off offset:2048
	ds_read_b32 v0, v136 offset:704
	s_waitcnt lgkmcnt(0)
	v_pk_mul_f32 v[6:7], v[6:7], v[0:1] op_sel_hi:[1,0]
	v_pk_mul_f32 v[8:9], v[8:9], v[0:1] op_sel_hi:[1,0]
	v_pk_mul_f32 v[10:11], v[4:5], v[0:1] op_sel_hi:[1,0]
	v_pk_mul_f32 v[4:5], v[2:3], v[0:1] op_sel_hi:[1,0]
	v_cvt_pk_bf16_f32 v2, v6, v7
	v_add_co_u32_e32 v6, vcc, 0x8000, v66
	v_cvt_pk_bf16_f32 v3, v8, v9
	v_cvt_pk_bf16_f32 v4, v4, v5
	v_cvt_pk_bf16_f32 v5, v10, v11
	v_addc_co_u32_e32 v7, vcc, 0, v67, vcc
	global_store_dwordx4 v[6:7], v[2:5], off offset:1024

; DI void phase2(const Params& p, int l, unsigned char* smem) {
;     ...
;             const int tk = (it - 1840) * 256 + tid, b = tk >> 13, s = tk & (S_ - 1);
;             const float* tl = (const float*)(ws + O_TAIL) + (size_t)tk * 32;
;             float x1[16], x2[16], c[16], sn[16];
; #pragma unroll
;             for (int j = 0; j < 4; ++j) {
;                 const f32x4 a = *(const f32x4*)(tl + 4 * j), bb = *(const f32x4*)(tl + 16 + 4 * j);
;                 const f32x4 cc = *(const f32x4*)(COS + (size_t)tk * 16 + 4 * j), ss = *(const f32x4*)(SIN + (size_t)tk * 16 + 4 * j);
;                 x1[4 * j] = a.x; x1[4 * j + 1] = a.y; x1[4 * j + 2] = a.z; x1[4 * j + 3] = a.w;
;                 x2[4 * j] = bb.x; x2[4 * j + 1] = bb.y; x2[4 * j + 2] = bb.z; x2[4 * j + 3] = bb.w;
;                 c[4 * j] = cc.x; c[4 * j + 1] = cc.y; c[4 * j + 2] = cc.z; c[4 * j + 3] = cc.w;
;                 sn[4 * j] = ss.x; sn[4 * j + 1] = ss.y; sn[4 * j + 2] = ss.z; sn[4 * j + 3] = ss.w;
;             }
;             u32x4 o[4];
; #pragma unroll
;             for (int j = 0; j < 2; ++j) {
;                 u32x4 a, bb;
;                 a.x = pk2(x1[8 * j] * c[8 * j] - x2[8 * j] * sn[8 * j], x1[8 * j + 1] * c[8 * j + 1] - x2[8 * j + 1] * sn[8 * j + 1]);
;                 a.y = pk2(x1[8 * j + 2] * c[8 * j + 2] - x2[8 * j + 2] * sn[8 * j + 2], x1[8 * j + 3] * c[8 * j + 3] - x2[8 * j + 3] * sn[8 * j + 3]);
;                 a.z = pk2(x1[8 * j + 4] * c[8 * j + 4] - x2[8 * j + 4] * sn[8 * j + 4], x1[8 * j + 5] * c[8 * j + 5] - x2[8 * j + 5] * sn[8 * j + 5]);
;                 a.w = pk2(x1[8 * j + 6] * c[8 * j + 6] - x2[8 * j + 6] * sn[8 * j + 6], x1[8 * j + 7] * c[8 * j + 7] - x2[8 * j + 7] * sn[8 * j + 7]);
;                 bb.x = pk2(x1[8 * j] * sn[8 * j] + x2[8 * j] * c[8 * j], x1[8 * j + 1] * sn[8 * j + 1] + x2[8 * j + 1] * c[8 * j + 1]);
;                 bb.y = pk2(x1[8 * j + 2] * sn[8 * j + 2] + x2[8 * j + 2] * c[8 * j + 2], x1[8 * j + 3] * sn[8 * j + 3] + x2[8 * j + 3] * c[8 * j + 3]);
;                 bb.z = pk2(x1[8 * j + 4] * sn[8 * j + 4] + x2[8 * j + 4] * c[8 * j + 4], x1[8 * j + 5] * sn[8 * j + 5] + x2[8 * j + 5] * c[8 * j + 5]);
;                 bb.w = pk2(x1[8 * j + 6] * sn[8 * j + 6] + x2[8 * j + 6] * c[8 * j + 6], x1[8 * j + 7] * sn[8 * j + 7] + x2[8 * j + 7] * c[8 * j + 7]);
;                 o[j] = a; o[2 + j] = bb;
;             }
; #pragma unroll
.LBB0_651:
	s_cmp_gt_i32 s28, 15
	s_cbranch_scc0 .LBB0_653
	v_lshl_add_u32 v70, s28, 8, v121
	v_ashrrev_i32_e32 v71, 31, v70
	s_waitcnt lgkmcnt(0)
	v_lshlrev_b64 v[2:3], 7, v[70:71]
	v_lshlrev_b64 v[4:5], 6, v[70:71]
	v_lshl_add_u64 v[2:3], s[26:27], 0, v[2:3]
	v_lshl_add_u64 v[62:63], s[22:23], 0, v[4:5]
	v_lshl_add_u64 v[4:5], s[24:25], 0, v[4:5]
	global_load_dwordx4 v[6:9], v[2:3], off
	global_load_dwordx4 v[10:13], v[2:3], off offset:64
	global_load_dwordx4 v[14:17], v[62:63], off
	global_load_dwordx4 v[18:21], v[4:5], off
	global_load_dwordx4 v[22:25], v[2:3], off offset:16
	global_load_dwordx4 v[26:29], v[2:3], off offset:80
	global_load_dwordx4 v[30:33], v[62:63], off offset:16
	global_load_dwordx4 v[34:37], v[4:5], off offset:16
	global_load_dwordx4 v[38:41], v[2:3], off offset:32
	global_load_dwordx4 v[42:45], v[2:3], off offset:96
	global_load_dwordx4 v[46:49], v[62:63], off offset:32
	global_load_dwordx4 v[50:53], v[4:5], off offset:32
	global_load_dwordx4 v[54:57], v[2:3], off offset:48
	global_load_dwordx4 v[58:61], v[2:3], off offset:112
	s_nop 0
	global_load_dwordx4 v[62:65], v[62:63], off offset:48
	s_nop 0
	global_load_dwordx4 v[66:69], v[4:5], off offset:48
	v_and_b32_e32 v0, 0x1fff, v70
	s_waitcnt vmcnt(0) lgkmcnt(0)
	v_pk_mul_f32 v[2:3], v[10:11], v[18:19]
	v_pk_mul_f32 v[4:5], v[12:13], v[20:21]
	v_pk_fma_f32 v[2:3], v[6:7], v[14:15], v[2:3] neg_lo:[0,0,1] neg_hi:[0,0,1]
	v_pk_fma_f32 v[4:5], v[8:9], v[16:17], v[4:5] neg_lo:[0,0,1] neg_hi:[0,0,1]
	v_pk_mul_f32 v[6:7], v[6:7], v[18:19]
	v_pk_mul_f32 v[8:9], v[8:9], v[20:21]
	v_pk_fma_f32 v[6:7], v[10:11], v[14:15], v[6:7]
	v_pk_fma_f32 v[8:9], v[12:13], v[16:17], v[8:9]
	v_cvt_pk_bf16_f32 v6, v6, v7
	v_cvt_pk_bf16_f32 v7, v8, v9
	v_pk_mul_f32 v[8:9], v[22:23], v[34:35]
	v_pk_mul_f32 v[10:11], v[24:25], v[36:37]
	v_pk_fma_f32 v[8:9], v[26:27], v[30:31], v[8:9]
	v_pk_fma_f32 v[10:11], v[28:29], v[32:33], v[10:11]
	v_cvt_pk_bf16_f32 v8, v8, v9
	v_cvt_pk_bf16_f32 v9, v10, v11
	v_pk_mul_f32 v[10:11], v[42:43], v[50:51]
	v_pk_mul_f32 v[12:13], v[44:45], v[52:53]
	v_pk_fma_f32 v[10:11], v[38:39], v[46:47], v[10:11] neg_lo:[0,0,1] neg_hi:[0,0,1]
	v_pk_fma_f32 v[12:13], v[40:41], v[48:49], v[12:13] neg_lo:[0,0,1] neg_hi:[0,0,1]
	v_cvt_pk_bf16_f32 v10, v10, v11
	v_cvt_pk_bf16_f32 v11, v12, v13
	v_pk_mul_f32 v[12:13], v[58:59], v[66:67]
	v_pk_mul_f32 v[14:15], v[60:61], v[68:69]
	v_pk_fma_f32 v[12:13], v[54:55], v[62:63], v[12:13] neg_lo:[0,0,1] neg_hi:[0,0,1]
	v_pk_fma_f32 v[14:15], v[56:57], v[64:65], v[14:15] neg_lo:[0,0,1] neg_hi:[0,0,1]
	v_cvt_pk_bf16_f32 v12, v12, v13
	v_cvt_pk_bf16_f32 v13, v14, v15
	v_pk_mul_f32 v[14:15], v[38:39], v[50:51]
	v_pk_mul_f32 v[16:17], v[40:41], v[52:53]
	v_pk_fma_f32 v[14:15], v[42:43], v[46:47], v[14:15]
	v_pk_fma_f32 v[16:17], v[44:45], v[48:49], v[16:17]
	v_pk_mul_f32 v[72:73], v[28:29], v[36:37]
	v_cvt_pk_bf16_f32 v14, v14, v15
	v_cvt_pk_bf16_f32 v15, v16, v17
	v_pk_mul_f32 v[16:17], v[54:55], v[66:67]
	v_pk_mul_f32 v[18:19], v[56:57], v[68:69]
	v_pk_fma_f32 v[72:73], v[24:25], v[32:33], v[72:73] neg_lo:[0,0,1] neg_hi:[0,0,1]
	v_pk_fma_f32 v[16:17], v[58:59], v[62:63], v[16:17]
	v_pk_fma_f32 v[18:19], v[60:61], v[64:65], v[18:19]
	v_ashrrev_i32_e32 v24, 11, v70
	v_cvt_pk_bf16_f32 v16, v16, v17
	v_cvt_pk_bf16_f32 v17, v18, v19
	v_and_b32_e32 v18, -4, v24
	v_ashrrev_i32_e32 v19, 31, v18
	v_cvt_pk_bf16_f32 v2, v2, v3
	v_cvt_pk_bf16_f32 v3, v4, v5
	v_pk_mul_f32 v[4:5], v[26:27], v[34:35]
	v_lshlrev_b64 v[20:21], 13, v[18:19]
	v_pk_fma_f32 v[4:5], v[22:23], v[30:31], v[4:5] neg_lo:[0,0,1] neg_hi:[0,0,1]
	v_or_b32_e32 v19, v20, v0
	v_mov_b64_e32 v[22:23], s[20:21]
	v_mad_u64_u32 v[26:27], s[30:31], v19, s79, v[22:23]
	v_mad_i32_i24 v19, v21, s79, v27
	v_add_co_u32_e32 v20, vcc, s0, v26
	v_cvt_pk_bf16_f32 v4, v4, v5
	v_cvt_pk_bf16_f32 v5, v72, v73
	v_addc_co_u32_e32 v21, vcc, 0, v19, vcc
	global_store_dwordx4 v[20:21], v[2:5], off offset:128
	global_store_dwordx4 v[20:21], v[10:13], off offset:144
	global_store_dwordx4 v[20:21], v[6:9], off offset:160
	global_store_dwordx4 v[20:21], v[14:17], off offset:176
	v_or_b32_e32 v20, 1, v18
	v_ashrrev_i32_e32 v21, 31, v20
	v_lshlrev_b64 v[20:21], 13, v[20:21]
	v_or_b32_e32 v19, v20, v0
	v_mad_u64_u32 v[26:27], s[30:31], v19, s79, v[22:23]
	v_mad_i32_i24 v19, v21, s79, v27
	v_add_co_u32_e32 v20, vcc, s0, v26
	v_or_b32_e32 v18, 2, v18
	s_nop 0
	v_addc_co_u32_e32 v21, vcc, 0, v19, vcc
	v_ashrrev_i32_e32 v19, 31, v18
	v_lshlrev_b64 v[18:19], 13, v[18:19]
	v_or_b32_e32 v18, v18, v0
	global_store_dwordx4 v[20:21], v[2:5], off offset:128
	global_store_dwordx4 v[20:21], v[10:13], off offset:144
	global_store_dwordx4 v[20:21], v[6:9], off offset:160
	global_store_dwordx4 v[20:21], v[14:17], off offset:176
	v_mad_u64_u32 v[20:21], s[30:31], v18, s79, v[22:23]
	v_mad_i32_i24 v19, v19, s79, v21
	v_add_co_u32_e32 v18, vcc, s0, v20
	s_nop 1
	v_addc_co_u32_e32 v19, vcc, 0, v19, vcc
	global_store_dwordx4 v[18:19], v[2:5], off offset:128
	global_store_dwordx4 v[18:19], v[10:13], off offset:144
	global_store_dwordx4 v[18:19], v[6:9], off offset:160
	global_store_dwordx4 v[18:19], v[14:17], off offset:176
	v_or_b32_e32 v18, 3, v24
	v_ashrrev_i32_e32 v19, 31, v18
	v_lshlrev_b64 v[18:19], 13, v[18:19]
	v_or_b32_e32 v0, v18, v0
	v_mad_u64_u32 v[20:21], s[30:31], v0, s79, v[22:23]
	v_mad_i32_i24 v0, v19, s79, v21
	v_add_co_u32_e32 v18, vcc, 0x17500000, v20
	s_mov_b64 s[30:31], 0
	s_nop 0
	v_addc_co_u32_e32 v19, vcc, 0, v0, vcc
	global_store_dwordx4 v[18:19], v[2:5], off offset:128
	global_store_dwordx4 v[18:19], v[10:13], off offset:144
	global_store_dwordx4 v[18:19], v[6:9], off offset:160
	global_store_dwordx4 v[18:19], v[14:17], off offset:176
; DI void phase2(const Params& p, int l, unsigned char* smem) {
;     ...
;             const float* fl = (const float*)(ws + O_FL) + (size_t)it * S_ + tid * 32;
;             f32x4 v[8];
; #pragma unroll
;             for (int j = 0; j < 8; ++j) v[j] = *(const f32x4*)(fl + 4 * j);
;             float sum = 0.f;
; #pragma unroll
;             for (int j = 0; j < 8; ++j) { sum += v[j].x; v[j].x = sum; sum += v[j].y; v[j].y = sum; sum += v[j].z; v[j].z = sum; sum += v[j].w; v[j].w = sum; }
;             float inc = sum;
; #pragma unroll
;             for (int d = 1; d < 64; d <<= 1) { const float o = __shfl_up(inc, d); if (lane >= d) inc += o; }
;             float* wt = (float*)smem;
;             if (lane == 63) wt[w] = inc;
;             __syncthreads();
;             float pre = inc - sum;
;             for (int k = 0; k < w; ++k) pre += wt[k];
.LBB0_653:
	s_andn2_b64 vcc, exec, s[30:31]
	s_cbranch_vccnz .LBB0_661
	s_ashr_i32 s29, s28, 31
	s_lshl_b64 s[30:31], s[28:29], 15
	v_lshl_add_u64 v[18:19], v[114:115], 0, s[30:31]
	s_waitcnt lgkmcnt(0)
	global_load_dwordx4 v[2:5], v[18:19], off
	global_load_dwordx4 v[6:9], v[18:19], off offset:16
	global_load_dwordx4 v[10:13], v[18:19], off offset:32
	global_load_dwordx4 v[14:17], v[18:19], off offset:48
	global_load_dwordx4 v[34:37], v[18:19], off offset:64
	global_load_dwordx4 v[38:41], v[18:19], off offset:80
	global_load_dwordx4 v[42:45], v[18:19], off offset:96
	global_load_dwordx4 v[46:49], v[18:19], off offset:112
	v_add_u32_e32 v0, -1, v224
	s_waitcnt vmcnt(0) lgkmcnt(0)
	v_add_f32_e32 v32, 0, v2
	v_add_f32_e32 v33, v3, v32
	v_add_f32_e32 v30, v4, v33
	v_add_f32_e32 v31, v5, v30
	v_add_f32_e32 v28, v6, v31
	v_add_f32_e32 v29, v7, v28
	v_add_f32_e32 v26, v8, v29
	v_add_f32_e32 v27, v9, v26
	v_add_f32_e32 v24, v10, v27
	v_add_f32_e32 v25, v11, v24
	v_add_f32_e32 v22, v12, v25
	v_add_f32_e32 v23, v13, v22
	v_add_f32_e32 v20, v14, v23
	v_add_f32_e32 v21, v15, v20
	v_add_f32_e32 v18, v16, v21
	v_add_f32_e32 v19, v17, v18
	v_add_f32_e32 v16, v34, v19
	v_add_f32_e32 v17, v35, v16
	v_add_f32_e32 v14, v36, v17
	v_add_f32_e32 v15, v37, v14
	v_add_f32_e32 v12, v38, v15
	v_add_f32_e32 v13, v39, v12
	v_add_f32_e32 v10, v40, v13
	v_add_f32_e32 v11, v41, v10
	v_add_f32_e32 v8, v42, v11
	v_add_f32_e32 v9, v43, v8
	v_add_f32_e32 v6, v44, v9
	v_add_f32_e32 v7, v45, v6
	v_add_f32_e32 v4, v46, v7
	v_and_b32_e32 v34, 64, v224
	v_add_f32_e32 v5, v47, v4
	v_cmp_lt_i32_e32 vcc, v0, v34
	v_add_f32_e32 v2, v48, v5
	v_add_f32_e32 v3, v49, v2
	v_cndmask_b32_e32 v0, v0, v224, vcc
	v_lshlrev_b32_e32 v0, 2, v0
	ds_bpermute_b32 v0, v0, v3
	v_add_u32_e32 v35, -2, v224
	v_cmp_lt_i32_e32 vcc, v35, v34
	s_waitcnt lgkmcnt(0)
	v_add_f32_e32 v0, v3, v0
	v_cndmask_b32_e32 v35, v35, v224, vcc
	v_cndmask_b32_e64 v0, v0, v3, s[8:9]
	v_lshlrev_b32_e32 v35, 2, v35
	ds_bpermute_b32 v35, v35, v0
	s_waitcnt lgkmcnt(0)
	v_add_f32_e32 v35, v0, v35
	v_cndmask_b32_e64 v0, v35, v0, s[10:11]
	v_add_u32_e32 v35, -4, v224
	v_cmp_lt_i32_e32 vcc, v35, v34
	s_nop 1
	v_cndmask_b32_e32 v35, v35, v224, vcc
	v_lshlrev_b32_e32 v35, 2, v35
	ds_bpermute_b32 v35, v35, v0
	s_waitcnt lgkmcnt(0)
	v_add_f32_e32 v35, v0, v35
	v_cndmask_b32_e64 v0, v35, v0, s[12:13]
	v_add_u32_e32 v35, -8, v224
	v_cmp_lt_i32_e32 vcc, v35, v34
	s_nop 1
	v_cndmask_b32_e32 v35, v35, v224, vcc
	v_lshlrev_b32_e32 v35, 2, v35
	ds_bpermute_b32 v35, v35, v0
	s_waitcnt lgkmcnt(0)
	v_add_f32_e32 v35, v0, v35
	v_cndmask_b32_e64 v0, v35, v0, s[14:15]
	v_add_u32_e32 v35, -16, v224
	v_cmp_lt_i32_e32 vcc, v35, v34
	s_nop 1
	v_cndmask_b32_e32 v35, v35, v224, vcc
	v_lshlrev_b32_e32 v35, 2, v35
	ds_bpermute_b32 v35, v35, v0
	s_waitcnt lgkmcnt(0)
	v_add_f32_e32 v35, v0, v35
	v_cndmask_b32_e64 v0, v35, v0, s[16:17]
	v_subrev_u32_e32 v35, 32, v224
	v_cmp_lt_i32_e32 vcc, v35, v34
	s_nop 1
	v_cndmask_b32_e32 v34, v35, v224, vcc
	v_lshlrev_b32_e32 v34, 2, v34
	ds_bpermute_b32 v34, v34, v0
	s_waitcnt lgkmcnt(0)
	v_add_f32_e32 v34, v0, v34
	s_and_saveexec_b64 s[30:31], s[4:5]
	ds_write_b32 v122, v34
	s_or_b64 exec, exec, s[30:31]
	v_cndmask_b32_e64 v0, v34, v0, s[18:19]
	v_sub_f32_e32 v0, v0, v3
	s_waitcnt lgkmcnt(0)
	s_barrier
	s_and_saveexec_b64 s[30:31], s[6:7]
	s_cbranch_execz .LBB0_660
	s_mov_b64 s[34:35], 0
	v_mov_b32_e32 v34, v120
	s_mov_b32 s40, s33

; DI void phase2(const Params& p, int l, unsigned char* smem) {
;     ...
;             float pre = inc - sum;
;             for (int k = 0; k < w; ++k) pre += wt[k];
;             float* fc = (float*)(ws + O_FC) + (size_t)it * S_ + tid * 32;
; #pragma unroll
;             for (int j = 0; j < 8; ++j) *(f32x4*)(fc + 4 * j) = -(v[j] + pre);
.LBB0_660:
	s_or_b64 exec, exec, s[30:31]
	s_lshl_b64 s[30:31], s[28:29], 13
	v_pk_add_f32 v[36:37], v[32:33], v[0:1] op_sel_hi:[1,0]
	v_pk_add_f32 v[30:31], v[30:31], v[0:1] op_sel_hi:[1,0]
	v_lshl_add_u64 v[34:35], s[30:31], 2, v[116:117]
	v_xor_b32_e32 v33, 0x80000000, v31
	v_xor_b32_e32 v32, 0x80000000, v30
	v_xor_b32_e32 v31, 0x80000000, v37
	v_xor_b32_e32 v30, 0x80000000, v36
	global_store_dwordx4 v[34:35], v[30:33], off
	v_pk_add_f32 v[26:27], v[26:27], v[0:1] op_sel_hi:[1,0]
	v_pk_add_f32 v[22:23], v[22:23], v[0:1] op_sel_hi:[1,0]
	v_pk_add_f32 v[30:31], v[28:29], v[0:1] op_sel_hi:[1,0]
	v_xor_b32_e32 v29, 0x80000000, v27
	v_xor_b32_e32 v28, 0x80000000, v26
	v_xor_b32_e32 v27, 0x80000000, v31
	v_xor_b32_e32 v26, 0x80000000, v30
	global_store_dwordx4 v[34:35], v[26:29], off offset:16
	v_pk_add_f32 v[18:19], v[18:19], v[0:1] op_sel_hi:[1,0]
	v_pk_add_f32 v[14:15], v[14:15], v[0:1] op_sel_hi:[1,0]
	v_pk_add_f32 v[26:27], v[24:25], v[0:1] op_sel_hi:[1,0]
	v_xor_b32_e32 v25, 0x80000000, v23
	v_xor_b32_e32 v24, 0x80000000, v22
	v_xor_b32_e32 v23, 0x80000000, v27
	v_xor_b32_e32 v22, 0x80000000, v26
	global_store_dwordx4 v[34:35], v[22:25], off offset:32
	v_pk_add_f32 v[10:11], v[10:11], v[0:1] op_sel_hi:[1,0]
	v_pk_add_f32 v[6:7], v[6:7], v[0:1] op_sel_hi:[1,0]
	v_pk_add_f32 v[22:23], v[20:21], v[0:1] op_sel_hi:[1,0]
	v_xor_b32_e32 v21, 0x80000000, v19
	v_xor_b32_e32 v20, 0x80000000, v18
	v_xor_b32_e32 v19, 0x80000000, v23
	v_xor_b32_e32 v18, 0x80000000, v22
	global_store_dwordx4 v[34:35], v[18:21], off offset:48
	v_pk_add_f32 v[2:3], v[2:3], v[0:1] op_sel_hi:[1,0]
	s_nop 0
	v_pk_add_f32 v[18:19], v[16:17], v[0:1] op_sel_hi:[1,0]
	v_xor_b32_e32 v17, 0x80000000, v15
	v_xor_b32_e32 v16, 0x80000000, v14
	v_xor_b32_e32 v15, 0x80000000, v19
	v_xor_b32_e32 v14, 0x80000000, v18
	global_store_dwordx4 v[34:35], v[14:17], off offset:64
	s_nop 1
	v_pk_add_f32 v[14:15], v[12:13], v[0:1] op_sel_hi:[1,0]
	v_xor_b32_e32 v13, 0x80000000, v11
	v_xor_b32_e32 v12, 0x80000000, v10
	v_xor_b32_e32 v11, 0x80000000, v15
	v_xor_b32_e32 v10, 0x80000000, v14
	global_store_dwordx4 v[34:35], v[10:13], off offset:80
	s_nop 1
	v_pk_add_f32 v[10:11], v[8:9], v[0:1] op_sel_hi:[1,0]
	v_xor_b32_e32 v9, 0x80000000, v7
	v_xor_b32_e32 v8, 0x80000000, v6
	v_xor_b32_e32 v7, 0x80000000, v11
	v_xor_b32_e32 v6, 0x80000000, v10
	global_store_dwordx4 v[34:35], v[6:9], off offset:96
	s_nop 1
	v_pk_add_f32 v[6:7], v[4:5], v[0:1] op_sel_hi:[1,0]
	v_xor_b32_e32 v5, 0x80000000, v3
	v_xor_b32_e32 v4, 0x80000000, v2
	v_xor_b32_e32 v3, 0x80000000, v7
	v_xor_b32_e32 v2, 0x80000000, v6
	global_store_dwordx4 v[34:35], v[2:5], off offset:112

; DI float bflo(unsigned u) { return __uint_as_float(u << 16); }
; DI float bfhi(unsigned u) { return __uint_as_float(u & 0xffff0000u); }
; DI void phase2(const Params& p, int l, unsigned char* smem) {
;     ...
;             const int bh = (it - 1968) >> 3, ch = (it - 1968) & 7;
;             const bf16_t* kp = (const bf16_t*)(ws + O_FK) + ((size_t)bh * S_ + ch * 1024 + tid * 4) * 64;
;             u32x4 v[4][8];
; #pragma unroll
;             for (int j = 0; j < 4; ++j)
; #pragma unroll
;                 for (int c = 0; c < 8; ++c) v[j][c] = *(const u32x4*)(kp + j * 64 + 8 * c);
;             float mxn = 0.f;
; #pragma unroll
;             for (int j = 0; j < 4; ++j) {
;                 float q = 0.f;
; #pragma unroll
;                 for (int c = 0; c < 8; ++c) { float a; a = bflo(v[j][c].x); q += a * a; a = bfhi(v[j][c].x); q += a * a; a = bflo(v[j][c].y); q += a * a; a = bfhi(v[j][c].y); q += a * a;
;                     a = bflo(v[j][c].z); q += a * a; a = bfhi(v[j][c].z); q += a * a; a = bflo(v[j][c].w); q += a * a; a = bfhi(v[j][c].w); q += a * a; }
;                 mxn = fmaxf(mxn, q);
.LBB0_662:
	s_add_i32 s29, s28, 0xfffff850
	s_lshl_b32 s28, s28, 10
	s_lshr_b32 s48, s29, 3
	s_and_b32 s28, s28, 0x1c00
	s_mov_b32 s29, s49
	s_waitcnt lgkmcnt(0)
	v_lshl_add_u64 v[2:3], s[28:29], 0, v[118:119]
	s_lshl_b64 s[28:29], s[48:49], 20
	s_add_u32 s28, s36, s28
	v_lshlrev_b64 v[2:3], 7, v[2:3]
	s_addc_u32 s29, s37, s29
	v_lshl_add_u64 v[2:3], s[28:29], 0, v[2:3]
	global_load_dwordx4 v[124:127], v[2:3], off
	global_load_dwordx4 v[128:131], v[2:3], off offset:16
	global_load_dwordx4 v[132:135], v[2:3], off offset:32
	global_load_dwordx4 v[136:139], v[2:3], off offset:48
	global_load_dwordx4 v[110:113], v[2:3], off offset:64
	global_load_dwordx4 v[106:109], v[2:3], off offset:80
	global_load_dwordx4 v[102:105], v[2:3], off offset:96
	global_load_dwordx4 v[98:101], v[2:3], off offset:112
	global_load_dwordx4 v[94:97], v[2:3], off offset:128
	global_load_dwordx4 v[90:93], v[2:3], off offset:144
	global_load_dwordx4 v[86:89], v[2:3], off offset:160
	global_load_dwordx4 v[82:85], v[2:3], off offset:176
	global_load_dwordx4 v[78:81], v[2:3], off offset:192
	global_load_dwordx4 v[74:77], v[2:3], off offset:208
	global_load_dwordx4 v[70:73], v[2:3], off offset:224
	global_load_dwordx4 v[66:69], v[2:3], off offset:240
	global_load_dwordx4 v[62:65], v[2:3], off offset:256
	global_load_dwordx4 v[58:61], v[2:3], off offset:272
	global_load_dwordx4 v[54:57], v[2:3], off offset:288
	global_load_dwordx4 v[50:53], v[2:3], off offset:304
	global_load_dwordx4 v[46:49], v[2:3], off offset:320
	global_load_dwordx4 v[42:45], v[2:3], off offset:336
	global_load_dwordx4 v[38:41], v[2:3], off offset:352
	global_load_dwordx4 v[34:37], v[2:3], off offset:368
	global_load_dwordx4 v[30:33], v[2:3], off offset:384
	global_load_dwordx4 v[26:29], v[2:3], off offset:400
	global_load_dwordx4 v[22:25], v[2:3], off offset:416
	global_load_dwordx4 v[18:21], v[2:3], off offset:432
	global_load_dwordx4 v[14:17], v[2:3], off offset:448
	global_load_dwordx4 v[10:13], v[2:3], off offset:464
	global_load_dwordx4 v[6:9], v[2:3], off offset:480
	s_nop 0
	global_load_dwordx4 v[2:5], v[2:3], off offset:496
	s_waitcnt vmcnt(0) lgkmcnt(0)
	v_lshlrev_b32_e32 v0, 16, v124
	v_mul_f32_e32 v0, v0, v0
	v_and_b32_e32 v123, 0xffff0000, v124
	v_fmac_f32_e32 v0, v123, v123
	v_lshlrev_b32_e32 v123, 16, v125
	v_fmac_f32_e32 v0, v123, v123
	v_and_b32_e32 v123, 0xffff0000, v125
	v_fmac_f32_e32 v0, v123, v123
	v_lshlrev_b32_e32 v123, 16, v126
	v_fmac_f32_e32 v0, v123, v123
	v_and_b32_e32 v123, 0xffff0000, v126
	v_fmac_f32_e32 v0, v123, v123
	v_lshlrev_b32_e32 v123, 16, v127
	v_fmac_f32_e32 v0, v123, v123
	v_and_b32_e32 v123, 0xffff0000, v127
	v_fmac_f32_e32 v0, v123, v123
	v_lshlrev_b32_e32 v123, 16, v128
	v_fmac_f32_e32 v0, v123, v123
	v_and_b32_e32 v123, 0xffff0000, v128
	v_fmac_f32_e32 v0, v123, v123
	v_lshlrev_b32_e32 v123, 16, v129
	v_fmac_f32_e32 v0, v123, v123
	v_and_b32_e32 v123, 0xffff0000, v129
	v_fmac_f32_e32 v0, v123, v123
	v_lshlrev_b32_e32 v123, 16, v130
	v_fmac_f32_e32 v0, v123, v123
	v_and_b32_e32 v123, 0xffff0000, v130
	v_fmac_f32_e32 v0, v123, v123
	v_lshlrev_b32_e32 v123, 16, v131
	v_fmac_f32_e32 v0, v123, v123
	v_and_b32_e32 v123, 0xffff0000, v131
	v_fmac_f32_e32 v0, v123, v123
	v_lshlrev_b32_e32 v123, 16, v132
	v_fmac_f32_e32 v0, v123, v123
	v_and_b32_e32 v123, 0xffff0000, v132
	v_fmac_f32_e32 v0, v123, v123
	v_lshlrev_b32_e32 v123, 16, v133
	v_fmac_f32_e32 v0, v123, v123
	v_and_b32_e32 v123, 0xffff0000, v133
	v_fmac_f32_e32 v0, v123, v123
	v_lshlrev_b32_e32 v123, 16, v134
	v_fmac_f32_e32 v0, v123, v123
	v_and_b32_e32 v123, 0xffff0000, v134
	v_fmac_f32_e32 v0, v123, v123
	v_lshlrev_b32_e32 v123, 16, v135
	v_fmac_f32_e32 v0, v123, v123
	v_and_b32_e32 v123, 0xffff0000, v135
	v_fmac_f32_e32 v0, v123, v123
	v_lshlrev_b32_e32 v123, 16, v136
	v_fmac_f32_e32 v0, v123, v123
	v_and_b32_e32 v123, 0xffff0000, v136
	v_fmac_f32_e32 v0, v123, v123
	v_lshlrev_b32_e32 v123, 16, v137
	v_fmac_f32_e32 v0, v123, v123
	v_and_b32_e32 v123, 0xffff0000, v137
	v_fmac_f32_e32 v0, v123, v123
	v_lshlrev_b32_e32 v123, 16, v138
	v_fmac_f32_e32 v0, v123, v123
	v_and_b32_e32 v123, 0xffff0000, v138
	v_fmac_f32_e32 v0, v123, v123
	v_lshlrev_b32_e32 v123, 16, v139
	v_fmac_f32_e32 v0, v123, v123
	v_and_b32_e32 v123, 0xffff0000, v139
	v_fmac_f32_e32 v0, v123, v123
	v_lshlrev_b32_e32 v123, 16, v110
	v_fmac_f32_e32 v0, v123, v123
	v_and_b32_e32 v110, 0xffff0000, v110
	v_fmac_f32_e32 v0, v110, v110
	v_lshlrev_b32_e32 v110, 16, v111
	v_fmac_f32_e32 v0, v110, v110
	v_and_b32_e32 v110, 0xffff0000, v111
	v_fmac_f32_e32 v0, v110, v110
	v_lshlrev_b32_e32 v110, 16, v112
	v_fmac_f32_e32 v0, v110, v110
	v_and_b32_e32 v110, 0xffff0000, v112
	v_fmac_f32_e32 v0, v110, v110
	v_lshlrev_b32_e32 v110, 16, v113
	v_fmac_f32_e32 v0, v110, v110
	v_and_b32_e32 v110, 0xffff0000, v113
	v_fmac_f32_e32 v0, v110, v110
	v_lshlrev_b32_e32 v110, 16, v106
	v_fmac_f32_e32 v0, v110, v110
	v_and_b32_e32 v106, 0xffff0000, v106
	v_fmac_f32_e32 v0, v106, v106
	v_lshlrev_b32_e32 v106, 16, v107
	v_fmac_f32_e32 v0, v106, v106
	v_and_b32_e32 v106, 0xffff0000, v107
	v_fmac_f32_e32 v0, v106, v106
	v_lshlrev_b32_e32 v106, 16, v108
	v_fmac_f32_e32 v0, v106, v106
	v_and_b32_e32 v106, 0xffff0000, v108
	v_fmac_f32_e32 v0, v106, v106
	v_lshlrev_b32_e32 v106, 16, v109
	v_fmac_f32_e32 v0, v106, v106
	v_and_b32_e32 v106, 0xffff0000, v109
	v_fmac_f32_e32 v0, v106, v106
	v_lshlrev_b32_e32 v106, 16, v102
	v_fmac_f32_e32 v0, v106, v106
	v_and_b32_e32 v102, 0xffff0000, v102
	v_fmac_f32_e32 v0, v102, v102
	v_lshlrev_b32_e32 v102, 16, v103
	v_fmac_f32_e32 v0, v102, v102
	v_and_b32_e32 v102, 0xffff0000, v103
	v_fmac_f32_e32 v0, v102, v102
	v_lshlrev_b32_e32 v102, 16, v104
; DI float bflo(unsigned u) { return __uint_as_float(u << 16); }
; DI float bfhi(unsigned u) { return __uint_as_float(u & 0xffff0000u); }
; DI void phase2(const Params& p, int l, unsigned char* smem) {
;     ...
;             for (int j = 0; j < 4; ++j) {
;                 float q = 0.f;
; #pragma unroll
;                 for (int c = 0; c < 8; ++c) { float a; a = bflo(v[j][c].x); q += a * a; a = bfhi(v[j][c].x); q += a * a; a = bflo(v[j][c].y); q += a * a; a = bfhi(v[j][c].y); q += a * a;
;                     a = bflo(v[j][c].z); q += a * a; a = bfhi(v[j][c].z); q += a * a; a = bflo(v[j][c].w); q += a * a; a = bfhi(v[j][c].w); q += a * a; }
;                 mxn = fmaxf(mxn, q);
	v_fmac_f32_e32 v0, v102, v102
	v_and_b32_e32 v102, 0xffff0000, v104
	v_fmac_f32_e32 v0, v102, v102
	v_lshlrev_b32_e32 v102, 16, v105
	v_fmac_f32_e32 v0, v102, v102
	v_and_b32_e32 v102, 0xffff0000, v105
	v_fmac_f32_e32 v0, v102, v102
	v_lshlrev_b32_e32 v102, 16, v98
	v_fmac_f32_e32 v0, v102, v102
	v_and_b32_e32 v98, 0xffff0000, v98
	v_fmac_f32_e32 v0, v98, v98
	v_lshlrev_b32_e32 v98, 16, v99
	v_fmac_f32_e32 v0, v98, v98
	v_and_b32_e32 v98, 0xffff0000, v99
	v_fmac_f32_e32 v0, v98, v98
	v_lshlrev_b32_e32 v98, 16, v100
	v_fmac_f32_e32 v0, v98, v98
	v_and_b32_e32 v98, 0xffff0000, v100
	v_fmac_f32_e32 v0, v98, v98
	v_lshlrev_b32_e32 v98, 16, v101
	v_fmac_f32_e32 v0, v98, v98
	v_and_b32_e32 v98, 0xffff0000, v101
	v_fmac_f32_e32 v0, v98, v98
	v_lshlrev_b32_e32 v98, 16, v94
	v_mul_f32_e32 v98, v98, v98
	v_and_b32_e32 v94, 0xffff0000, v94
	v_fmac_f32_e32 v98, v94, v94
	v_lshlrev_b32_e32 v94, 16, v95
	v_fmac_f32_e32 v98, v94, v94
	v_and_b32_e32 v94, 0xffff0000, v95
	v_fmac_f32_e32 v98, v94, v94
	v_lshlrev_b32_e32 v94, 16, v96
	v_fmac_f32_e32 v98, v94, v94
	v_and_b32_e32 v94, 0xffff0000, v96
	v_fmac_f32_e32 v98, v94, v94
	v_lshlrev_b32_e32 v94, 16, v97
	v_fmac_f32_e32 v98, v94, v94
	v_and_b32_e32 v94, 0xffff0000, v97
	v_fmac_f32_e32 v98, v94, v94
	v_lshlrev_b32_e32 v94, 16, v90
	v_fmac_f32_e32 v98, v94, v94
	v_and_b32_e32 v90, 0xffff0000, v90
	v_fmac_f32_e32 v98, v90, v90
	v_lshlrev_b32_e32 v90, 16, v91
	v_fmac_f32_e32 v98, v90, v90
	v_and_b32_e32 v90, 0xffff0000, v91
	v_fmac_f32_e32 v98, v90, v90
	v_lshlrev_b32_e32 v90, 16, v92
	v_fmac_f32_e32 v98, v90, v90
	v_and_b32_e32 v90, 0xffff0000, v92
	v_fmac_f32_e32 v98, v90, v90
	v_lshlrev_b32_e32 v90, 16, v93
	v_fmac_f32_e32 v98, v90, v90
	v_and_b32_e32 v90, 0xffff0000, v93
	v_fmac_f32_e32 v98, v90, v90
	v_lshlrev_b32_e32 v90, 16, v86
	v_fmac_f32_e32 v98, v90, v90
	v_and_b32_e32 v86, 0xffff0000, v86
	v_fmac_f32_e32 v98, v86, v86
	v_lshlrev_b32_e32 v86, 16, v87
	v_fmac_f32_e32 v98, v86, v86
	v_and_b32_e32 v86, 0xffff0000, v87
	v_fmac_f32_e32 v98, v86, v86
	v_lshlrev_b32_e32 v86, 16, v88
	v_fmac_f32_e32 v98, v86, v86
	v_and_b32_e32 v86, 0xffff0000, v88
	v_fmac_f32_e32 v98, v86, v86
	v_lshlrev_b32_e32 v86, 16, v89
	v_fmac_f32_e32 v98, v86, v86
	v_and_b32_e32 v86, 0xffff0000, v89
	v_fmac_f32_e32 v98, v86, v86
	v_lshlrev_b32_e32 v86, 16, v82
	v_fmac_f32_e32 v98, v86, v86
	v_and_b32_e32 v82, 0xffff0000, v82
	v_fmac_f32_e32 v98, v82, v82
	v_lshlrev_b32_e32 v82, 16, v83
	v_fmac_f32_e32 v98, v82, v82
	v_and_b32_e32 v82, 0xffff0000, v83
	v_fmac_f32_e32 v98, v82, v82
	v_lshlrev_b32_e32 v82, 16, v84
	v_fmac_f32_e32 v98, v82, v82
	v_and_b32_e32 v82, 0xffff0000, v84
	v_fmac_f32_e32 v98, v82, v82
	v_lshlrev_b32_e32 v82, 16, v85
	v_fmac_f32_e32 v98, v82, v82
	v_and_b32_e32 v82, 0xffff0000, v85
	v_fmac_f32_e32 v98, v82, v82
	v_lshlrev_b32_e32 v82, 16, v78
	v_fmac_f32_e32 v98, v82, v82
	v_and_b32_e32 v78, 0xffff0000, v78
	v_fmac_f32_e32 v98, v78, v78
	v_lshlrev_b32_e32 v78, 16, v79
	v_fmac_f32_e32 v98, v78, v78
	v_and_b32_e32 v78, 0xffff0000, v79
	v_fmac_f32_e32 v98, v78, v78
	v_lshlrev_b32_e32 v78, 16, v80
	v_fmac_f32_e32 v98, v78, v78
	v_and_b32_e32 v78, 0xffff0000, v80
	v_fmac_f32_e32 v98, v78, v78
	v_lshlrev_b32_e32 v78, 16, v81
	v_fmac_f32_e32 v98, v78, v78
	v_and_b32_e32 v78, 0xffff0000, v81
	v_fmac_f32_e32 v98, v78, v78
	v_lshlrev_b32_e32 v78, 16, v74
	v_fmac_f32_e32 v98, v78, v78
	v_and_b32_e32 v74, 0xffff0000, v74
	v_fmac_f32_e32 v98, v74, v74
	v_lshlrev_b32_e32 v74, 16, v75
	v_fmac_f32_e32 v98, v74, v74
	v_and_b32_e32 v74, 0xffff0000, v75
	v_fmac_f32_e32 v98, v74, v74
	v_lshlrev_b32_e32 v74, 16, v76
	v_fmac_f32_e32 v98, v74, v74
	v_and_b32_e32 v74, 0xffff0000, v76
	v_fmac_f32_e32 v98, v74, v74
	v_lshlrev_b32_e32 v74, 16, v77
	v_fmac_f32_e32 v98, v74, v74
	v_and_b32_e32 v74, 0xffff0000, v77
	v_fmac_f32_e32 v98, v74, v74
	v_lshlrev_b32_e32 v74, 16, v70
	v_fmac_f32_e32 v98, v74, v74
	v_and_b32_e32 v70, 0xffff0000, v70
	v_fmac_f32_e32 v98, v70, v70
	v_lshlrev_b32_e32 v70, 16, v71
	v_fmac_f32_e32 v98, v70, v70
	v_and_b32_e32 v70, 0xffff0000, v71
	v_fmac_f32_e32 v98, v70, v70
	v_lshlrev_b32_e32 v70, 16, v72
	v_fmac_f32_e32 v98, v70, v70
	v_and_b32_e32 v70, 0xffff0000, v72
	v_fmac_f32_e32 v98, v70, v70
	v_lshlrev_b32_e32 v70, 16, v73
	v_fmac_f32_e32 v98, v70, v70
	v_and_b32_e32 v70, 0xffff0000, v73
	v_fmac_f32_e32 v98, v70, v70
	v_lshlrev_b32_e32 v70, 16, v66
	v_fmac_f32_e32 v98, v70, v70
	v_and_b32_e32 v66, 0xffff0000, v66
	v_fmac_f32_e32 v98, v66, v66
	v_lshlrev_b32_e32 v66, 16, v67
	v_fmac_f32_e32 v98, v66, v66
	v_and_b32_e32 v66, 0xffff0000, v67
	v_fmac_f32_e32 v98, v66, v66
	v_lshlrev_b32_e32 v66, 16, v68
	v_fmac_f32_e32 v98, v66, v66
	v_and_b32_e32 v66, 0xffff0000, v68
	v_fmac_f32_e32 v98, v66, v66
	v_lshlrev_b32_e32 v66, 16, v69
	v_fmac_f32_e32 v98, v66, v66
	v_and_b32_e32 v66, 0xffff0000, v69
	v_fmac_f32_e32 v98, v66, v66
	v_lshlrev_b32_e32 v66, 16, v62
	v_mul_f32_e32 v66, v66, v66
	v_and_b32_e32 v62, 0xffff0000, v62
	v_fmac_f32_e32 v66, v62, v62
	v_lshlrev_b32_e32 v62, 16, v63
	v_fmac_f32_e32 v66, v62, v62
	v_and_b32_e32 v62, 0xffff0000, v63
	v_fmac_f32_e32 v66, v62, v62
	v_lshlrev_b32_e32 v62, 16, v64
	v_fmac_f32_e32 v66, v62, v62
	v_and_b32_e32 v62, 0xffff0000, v64
	v_fmac_f32_e32 v66, v62, v62
	v_lshlrev_b32_e32 v62, 16, v65
	v_fmac_f32_e32 v66, v62, v62
	v_and_b32_e32 v62, 0xffff0000, v65
	v_fmac_f32_e32 v66, v62, v62
	v_lshlrev_b32_e32 v62, 16, v58
	v_fmac_f32_e32 v66, v62, v62
	v_and_b32_e32 v58, 0xffff0000, v58
	v_fmac_f32_e32 v66, v58, v58
	v_lshlrev_b32_e32 v58, 16, v59
	v_fmac_f32_e32 v66, v58, v58
	v_and_b32_e32 v58, 0xffff0000, v59
	v_fmac_f32_e32 v66, v58, v58
	v_lshlrev_b32_e32 v58, 16, v60
; DI float bflo(unsigned u) { return __uint_as_float(u << 16); }
; DI float bfhi(unsigned u) { return __uint_as_float(u & 0xffff0000u); }
; DI void phase2(const Params& p, int l, unsigned char* smem) {
;     ...
;             for (int j = 0; j < 4; ++j) {
;                 float q = 0.f;
; #pragma unroll
;                 for (int c = 0; c < 8; ++c) { float a; a = bflo(v[j][c].x); q += a * a; a = bfhi(v[j][c].x); q += a * a; a = bflo(v[j][c].y); q += a * a; a = bfhi(v[j][c].y); q += a * a;
;                     a = bflo(v[j][c].z); q += a * a; a = bfhi(v[j][c].z); q += a * a; a = bflo(v[j][c].w); q += a * a; a = bfhi(v[j][c].w); q += a * a; }
;                 mxn = fmaxf(mxn, q);
	v_fmac_f32_e32 v66, v58, v58
	v_and_b32_e32 v58, 0xffff0000, v60
	v_fmac_f32_e32 v66, v58, v58
	v_lshlrev_b32_e32 v58, 16, v61
	v_fmac_f32_e32 v66, v58, v58
	v_and_b32_e32 v58, 0xffff0000, v61
	v_fmac_f32_e32 v66, v58, v58
	v_lshlrev_b32_e32 v58, 16, v54
	v_fmac_f32_e32 v66, v58, v58
	v_and_b32_e32 v54, 0xffff0000, v54
	v_fmac_f32_e32 v66, v54, v54
	v_lshlrev_b32_e32 v54, 16, v55
	v_fmac_f32_e32 v66, v54, v54
	v_and_b32_e32 v54, 0xffff0000, v55
	v_fmac_f32_e32 v66, v54, v54
	v_lshlrev_b32_e32 v54, 16, v56
	v_fmac_f32_e32 v66, v54, v54
	v_and_b32_e32 v54, 0xffff0000, v56
	v_fmac_f32_e32 v66, v54, v54
	v_lshlrev_b32_e32 v54, 16, v57
	v_fmac_f32_e32 v66, v54, v54
	v_and_b32_e32 v54, 0xffff0000, v57
	v_fmac_f32_e32 v66, v54, v54
	v_lshlrev_b32_e32 v54, 16, v50
	v_fmac_f32_e32 v66, v54, v54
	v_and_b32_e32 v50, 0xffff0000, v50
	v_fmac_f32_e32 v66, v50, v50
	v_lshlrev_b32_e32 v50, 16, v51
	v_fmac_f32_e32 v66, v50, v50
	v_and_b32_e32 v50, 0xffff0000, v51
	v_fmac_f32_e32 v66, v50, v50
	v_lshlrev_b32_e32 v50, 16, v52
	v_fmac_f32_e32 v66, v50, v50
	v_and_b32_e32 v50, 0xffff0000, v52
	v_fmac_f32_e32 v66, v50, v50
	v_lshlrev_b32_e32 v50, 16, v53
	v_fmac_f32_e32 v66, v50, v50
	v_and_b32_e32 v50, 0xffff0000, v53
	v_fmac_f32_e32 v66, v50, v50
	v_lshlrev_b32_e32 v50, 16, v46
	v_fmac_f32_e32 v66, v50, v50
	v_and_b32_e32 v46, 0xffff0000, v46
	v_fmac_f32_e32 v66, v46, v46
	v_lshlrev_b32_e32 v46, 16, v47
	v_fmac_f32_e32 v66, v46, v46
	v_and_b32_e32 v46, 0xffff0000, v47
	v_fmac_f32_e32 v66, v46, v46
	v_lshlrev_b32_e32 v46, 16, v48
	v_fmac_f32_e32 v66, v46, v46
	v_and_b32_e32 v46, 0xffff0000, v48
	v_fmac_f32_e32 v66, v46, v46
	v_lshlrev_b32_e32 v46, 16, v49
	v_fmac_f32_e32 v66, v46, v46
	v_and_b32_e32 v46, 0xffff0000, v49
	v_fmac_f32_e32 v66, v46, v46
	v_lshlrev_b32_e32 v46, 16, v42
	v_fmac_f32_e32 v66, v46, v46
	v_and_b32_e32 v42, 0xffff0000, v42
	v_fmac_f32_e32 v66, v42, v42
	v_lshlrev_b32_e32 v42, 16, v43
	v_fmac_f32_e32 v66, v42, v42
	v_and_b32_e32 v42, 0xffff0000, v43
	v_fmac_f32_e32 v66, v42, v42
	v_lshlrev_b32_e32 v42, 16, v44
	v_fmac_f32_e32 v66, v42, v42
	v_and_b32_e32 v42, 0xffff0000, v44
	v_fmac_f32_e32 v66, v42, v42
	v_lshlrev_b32_e32 v42, 16, v45
	v_fmac_f32_e32 v66, v42, v42
	v_and_b32_e32 v42, 0xffff0000, v45
	v_fmac_f32_e32 v66, v42, v42
	v_lshlrev_b32_e32 v42, 16, v38
	v_fmac_f32_e32 v66, v42, v42
	v_and_b32_e32 v38, 0xffff0000, v38
	v_fmac_f32_e32 v66, v38, v38
	v_lshlrev_b32_e32 v38, 16, v39
	v_fmac_f32_e32 v66, v38, v38
	v_and_b32_e32 v38, 0xffff0000, v39
	v_fmac_f32_e32 v66, v38, v38
	v_lshlrev_b32_e32 v38, 16, v40
	v_fmac_f32_e32 v66, v38, v38
	v_and_b32_e32 v38, 0xffff0000, v40
	v_fmac_f32_e32 v66, v38, v38
	v_lshlrev_b32_e32 v38, 16, v41
	v_fmac_f32_e32 v66, v38, v38
	v_and_b32_e32 v38, 0xffff0000, v41
	v_fmac_f32_e32 v66, v38, v38
	v_lshlrev_b32_e32 v38, 16, v34
	v_fmac_f32_e32 v66, v38, v38
	v_and_b32_e32 v34, 0xffff0000, v34
	v_fmac_f32_e32 v66, v34, v34
	v_lshlrev_b32_e32 v34, 16, v35
	v_fmac_f32_e32 v66, v34, v34
	v_and_b32_e32 v34, 0xffff0000, v35
	v_fmac_f32_e32 v66, v34, v34
	v_lshlrev_b32_e32 v34, 16, v36
	v_fmac_f32_e32 v66, v34, v34
	v_and_b32_e32 v34, 0xffff0000, v36
	v_fmac_f32_e32 v66, v34, v34
	v_lshlrev_b32_e32 v34, 16, v37
	v_fmac_f32_e32 v66, v34, v34
	v_and_b32_e32 v34, 0xffff0000, v37
	v_fmac_f32_e32 v66, v34, v34
	v_lshlrev_b32_e32 v34, 16, v30
	v_mul_f32_e32 v34, v34, v34
	v_and_b32_e32 v30, 0xffff0000, v30
	v_fmac_f32_e32 v34, v30, v30
	v_lshlrev_b32_e32 v30, 16, v31
	v_fmac_f32_e32 v34, v30, v30
	v_and_b32_e32 v30, 0xffff0000, v31
	v_fmac_f32_e32 v34, v30, v30
	v_lshlrev_b32_e32 v30, 16, v32
	v_fmac_f32_e32 v34, v30, v30
	v_and_b32_e32 v30, 0xffff0000, v32
	v_fmac_f32_e32 v34, v30, v30
	v_lshlrev_b32_e32 v30, 16, v33
	v_fmac_f32_e32 v34, v30, v30
	v_and_b32_e32 v30, 0xffff0000, v33
	v_fmac_f32_e32 v34, v30, v30
	v_lshlrev_b32_e32 v30, 16, v26
	v_fmac_f32_e32 v34, v30, v30
	v_and_b32_e32 v26, 0xffff0000, v26
	v_fmac_f32_e32 v34, v26, v26
	v_lshlrev_b32_e32 v26, 16, v27
	v_fmac_f32_e32 v34, v26, v26
	v_and_b32_e32 v26, 0xffff0000, v27
	v_fmac_f32_e32 v34, v26, v26
	v_lshlrev_b32_e32 v26, 16, v28
	v_fmac_f32_e32 v34, v26, v26
	v_and_b32_e32 v26, 0xffff0000, v28
	v_fmac_f32_e32 v34, v26, v26
	v_lshlrev_b32_e32 v26, 16, v29
	v_fmac_f32_e32 v34, v26, v26
	v_and_b32_e32 v26, 0xffff0000, v29
	v_fmac_f32_e32 v34, v26, v26
	v_lshlrev_b32_e32 v26, 16, v22
	v_fmac_f32_e32 v34, v26, v26
	v_and_b32_e32 v22, 0xffff0000, v22
	v_fmac_f32_e32 v34, v22, v22
	v_lshlrev_b32_e32 v22, 16, v23
	v_fmac_f32_e32 v34, v22, v22
	v_and_b32_e32 v22, 0xffff0000, v23
; DI float bflo(unsigned u) { return __uint_as_float(u << 16); }
; DI float bfhi(unsigned u) { return __uint_as_float(u & 0xffff0000u); }
; DI void phase2(const Params& p, int l, unsigned char* smem) {
;     ...
;                 for (int c = 0; c < 8; ++c) { float a; a = bflo(v[j][c].x); q += a * a; a = bfhi(v[j][c].x); q += a * a; a = bflo(v[j][c].y); q += a * a; a = bfhi(v[j][c].y); q += a * a;
;                     a = bflo(v[j][c].z); q += a * a; a = bfhi(v[j][c].z); q += a * a; a = bflo(v[j][c].w); q += a * a; a = bfhi(v[j][c].w); q += a * a; }
;                 mxn = fmaxf(mxn, q);
;             }
; #pragma unroll
;             for (int d = 32; d >= 1; d >>= 1) mxn = fmaxf(mxn, __shfl_xor(mxn, d));
;             if (lane == 0) atomicMax((unsigned*)(ws + O_KMAX) + bh, __float_as_uint(mxn));
	v_fmac_f32_e32 v34, v22, v22
	v_lshlrev_b32_e32 v22, 16, v24
	v_fmac_f32_e32 v34, v22, v22
	v_and_b32_e32 v22, 0xffff0000, v24
	v_fmac_f32_e32 v34, v22, v22
	v_lshlrev_b32_e32 v22, 16, v25
	v_fmac_f32_e32 v34, v22, v22
	v_and_b32_e32 v22, 0xffff0000, v25
	v_fmac_f32_e32 v34, v22, v22
	v_lshlrev_b32_e32 v22, 16, v18
	v_fmac_f32_e32 v34, v22, v22
	v_and_b32_e32 v18, 0xffff0000, v18
	v_fmac_f32_e32 v34, v18, v18
	v_lshlrev_b32_e32 v18, 16, v19
	v_fmac_f32_e32 v34, v18, v18
	v_and_b32_e32 v18, 0xffff0000, v19
	v_fmac_f32_e32 v34, v18, v18
	v_lshlrev_b32_e32 v18, 16, v20
	v_fmac_f32_e32 v34, v18, v18
	v_and_b32_e32 v18, 0xffff0000, v20
	v_fmac_f32_e32 v34, v18, v18
	v_lshlrev_b32_e32 v18, 16, v21
	v_fmac_f32_e32 v34, v18, v18
	v_and_b32_e32 v18, 0xffff0000, v21
	v_fmac_f32_e32 v34, v18, v18
	v_lshlrev_b32_e32 v18, 16, v14
	v_fmac_f32_e32 v34, v18, v18
	v_and_b32_e32 v14, 0xffff0000, v14
	v_fmac_f32_e32 v34, v14, v14
	v_lshlrev_b32_e32 v14, 16, v15
	v_fmac_f32_e32 v34, v14, v14
	v_and_b32_e32 v14, 0xffff0000, v15
	v_fmac_f32_e32 v34, v14, v14
	v_lshlrev_b32_e32 v14, 16, v16
	v_fmac_f32_e32 v34, v14, v14
	v_and_b32_e32 v14, 0xffff0000, v16
	v_fmac_f32_e32 v34, v14, v14
	v_lshlrev_b32_e32 v14, 16, v17
	v_fmac_f32_e32 v34, v14, v14
	v_and_b32_e32 v14, 0xffff0000, v17
	v_fmac_f32_e32 v34, v14, v14
	v_lshlrev_b32_e32 v14, 16, v10
	v_fmac_f32_e32 v34, v14, v14
	v_and_b32_e32 v10, 0xffff0000, v10
	v_fmac_f32_e32 v34, v10, v10
	v_lshlrev_b32_e32 v10, 16, v11
	v_fmac_f32_e32 v34, v10, v10
	v_and_b32_e32 v10, 0xffff0000, v11
	v_fmac_f32_e32 v34, v10, v10
	v_lshlrev_b32_e32 v10, 16, v12
	v_fmac_f32_e32 v34, v10, v10
	v_and_b32_e32 v10, 0xffff0000, v12
	v_fmac_f32_e32 v34, v10, v10
	v_lshlrev_b32_e32 v10, 16, v13
	v_fmac_f32_e32 v34, v10, v10
	v_and_b32_e32 v10, 0xffff0000, v13
	v_fmac_f32_e32 v34, v10, v10
	v_lshlrev_b32_e32 v10, 16, v6
	v_fmac_f32_e32 v34, v10, v10
	v_and_b32_e32 v6, 0xffff0000, v6
	v_fmac_f32_e32 v34, v6, v6
	v_lshlrev_b32_e32 v6, 16, v7
	v_fmac_f32_e32 v34, v6, v6
	v_and_b32_e32 v6, 0xffff0000, v7
	v_fmac_f32_e32 v34, v6, v6
	v_lshlrev_b32_e32 v6, 16, v8
	v_fmac_f32_e32 v34, v6, v6
	v_and_b32_e32 v6, 0xffff0000, v8
	v_fmac_f32_e32 v34, v6, v6
	v_lshlrev_b32_e32 v6, 16, v9
	v_fmac_f32_e32 v34, v6, v6
	v_and_b32_e32 v6, 0xffff0000, v9
	v_fmac_f32_e32 v34, v6, v6
	v_lshlrev_b32_e32 v6, 16, v2
	v_fmac_f32_e32 v34, v6, v6
	v_and_b32_e32 v2, 0xffff0000, v2
	v_fmac_f32_e32 v34, v2, v2
	v_lshlrev_b32_e32 v2, 16, v3
	v_fmac_f32_e32 v34, v2, v2
	v_and_b32_e32 v2, 0xffff0000, v3
	v_fmac_f32_e32 v34, v2, v2
	v_lshlrev_b32_e32 v2, 16, v4
	v_fmac_f32_e32 v34, v2, v2
	v_and_b32_e32 v2, 0xffff0000, v4
	v_fmac_f32_e32 v34, v2, v2
	v_lshlrev_b32_e32 v2, 16, v5
	v_fmac_f32_e32 v34, v2, v2
	v_and_b32_e32 v2, 0xffff0000, v5
	v_fmac_f32_e32 v34, v2, v2
	v_and_b32_e32 v2, 64, v224
	v_add_u32_e32 v2, 64, v2
	v_xor_b32_e32 v3, 32, v224
	v_cmp_lt_i32_e32 vcc, v3, v2
	v_max3_f32 v0, v0, 0, v98
	v_max3_f32 v0, v0, v66, v34
	v_cndmask_b32_e32 v3, v224, v3, vcc
	v_lshlrev_b32_e32 v3, 2, v3
	ds_bpermute_b32 v3, v3, v0
	s_waitcnt lgkmcnt(0)
	v_max_f32_e32 v3, v3, v3
	v_max_f32_e32 v0, v0, v3
	v_xor_b32_e32 v3, 16, v224
	v_cmp_lt_i32_e32 vcc, v3, v2
	s_nop 1
	v_cndmask_b32_e32 v3, v224, v3, vcc
	v_lshlrev_b32_e32 v3, 2, v3
	ds_bpermute_b32 v3, v3, v0
	s_waitcnt lgkmcnt(0)
	v_max_f32_e32 v3, v3, v3
	v_max_f32_e32 v0, v0, v3
	v_xor_b32_e32 v3, 8, v224
	v_cmp_lt_i32_e32 vcc, v3, v2
	s_nop 1
	v_cndmask_b32_e32 v3, v224, v3, vcc
	v_lshlrev_b32_e32 v3, 2, v3
	ds_bpermute_b32 v3, v3, v0
	s_waitcnt lgkmcnt(0)
	v_max_f32_e32 v3, v3, v3
	v_max_f32_e32 v0, v0, v3
	v_xor_b32_e32 v3, 4, v224
	v_cmp_lt_i32_e32 vcc, v3, v2
	s_nop 1
	v_cndmask_b32_e32 v3, v224, v3, vcc
	v_lshlrev_b32_e32 v3, 2, v3
	ds_bpermute_b32 v3, v3, v0
	s_waitcnt lgkmcnt(0)
	v_max_f32_e32 v3, v3, v3
	v_max_f32_e32 v0, v0, v3
	v_xor_b32_e32 v3, 2, v224
	v_cmp_lt_i32_e32 vcc, v3, v2
	s_nop 1
	v_cndmask_b32_e32 v3, v224, v3, vcc
	v_lshlrev_b32_e32 v3, 2, v3
	ds_bpermute_b32 v3, v3, v0
	s_waitcnt lgkmcnt(0)
	v_max_f32_e32 v3, v3, v3
	v_max_f32_e32 v0, v0, v3
	v_xor_b32_e32 v3, 1, v224
	v_cmp_lt_i32_e32 vcc, v3, v2
	s_nop 1
	v_cndmask_b32_e32 v2, v224, v3, vcc
	v_lshlrev_b32_e32 v2, 2, v2
	ds_bpermute_b32 v2, v2, v0
	s_and_saveexec_b64 s[28:29], s[8:9]
	s_cbranch_execz .LBB0_647
	s_lshl_b32 s30, s48, 2
	s_add_u32 s30, s38, s30
	s_addc_u32 s31, s39, 0
	s_waitcnt lgkmcnt(0)
	v_max_f32_e32 v2, v2, v2
	v_max_f32_e32 v0, v0, v0
	v_max_f32_e32 v0, v0, v2
	v_mov_b64_e32 v[2:3], s[30:31]
	flat_atomic_umax v[2:3], v0
	s_branch .LBB0_647

; DI unsigned pk2(float a, float b) { f32x2 v = {a, b}; return __builtin_bit_cast(unsigned, __builtin_convertvector(v, bf2_t)); }
; DI float bflo(unsigned u) { return __uint_as_float(u << 16); }
; DI float bfhi(unsigned u) { return __uint_as_float(u & 0xffff0000u); }
;     ...
;     bf16_t* yrow = yb + (size_t)(32 * w + r) * 1024 + 4 * h;
;     const bf16_t* grow = gt + (size_t)(32 * w + r) * 1024 + 4 * h;
;     u32x2 gv[2][4];
; #pragma unroll
;     for (int nt = 0; nt < 2; ++nt)
; #pragma unroll
;         for (int qd = 0; qd < 4; ++qd) gv[nt][qd] = *(const u32x2*)(grow + 32 * nt + 8 * qd);
; #pragma unroll
;     for (int nt = 0; nt < 2; ++nt)
; #pragma unroll
;         for (int qd = 0; qd < 4; ++qd) {
;             const u32x2 g = gv[nt][qd];
;             const f32x16& o = nt ? o1 : o0;
;             u32x2 v;
;             v.x = pk2(o[4 * qd] * bflo(g.x), o[4 * qd + 1] * bfhi(g.x));
;             v.y = pk2(o[4 * qd + 2] * bflo(g.y), o[4 * qd + 3] * bfhi(g.y));
;             *(u32x2*)(yrow + 32 * nt + 8 * qd) = v;
;         }
.LBB0_709:
	s_mov_b32 s57, s49
	s_lshl_b64 s[4:5], s[94:95], 11
	s_lshl_b64 s[6:7], s[56:57], 24
	s_or_b64 s[4:5], s[4:5], s[6:7]
	s_add_u32 s6, s69, s4
	s_addc_u32 s7, s60, s5
	s_lshl_b32 s8, s79, 7
	s_add_u32 s6, s6, s8
	s_addc_u32 s7, s7, 0
	v_lshlrev_b64 v[42:43], 11, v[100:101]
	v_lshl_add_u64 v[34:35], s[6:7], 0, v[42:43]
	v_lshlrev_b32_e32 v0, 1, v106
	v_lshl_add_u64 v[34:35], v[34:35], 0, v[0:1]
	global_load_dwordx2 v[44:45], v[34:35], off offset:512
	global_load_dwordx2 v[46:47], v[34:35], off offset:528
	global_load_dwordx2 v[48:49], v[34:35], off offset:544
	global_load_dwordx2 v[50:51], v[34:35], off offset:560
	global_load_dwordx2 v[40:41], v[34:35], off offset:576
	global_load_dwordx2 v[38:39], v[34:35], off offset:592
	global_load_dwordx2 v[36:37], v[34:35], off offset:608
	s_nop 0
	global_load_dwordx2 v[34:35], v[34:35], off offset:624
	s_add_u32 s4, s61, s4
	s_addc_u32 s5, s70, s5
	s_add_u32 s4, s4, s8
	s_addc_u32 s5, s5, 0
	v_lshl_add_u64 v[42:43], s[4:5], 0, v[42:43]
	v_lshl_add_u64 v[52:53], v[42:43], 0, v[0:1]
	s_mov_b64 s[4:5], 0x200
	v_lshl_add_u64 v[42:43], v[52:53], 0, s[4:5]
	s_mov_b32 s97, s0
	s_movk_i32 s90, 0x1000
	s_mov_b32 s88, 0x30000
	s_movk_i32 s92, 0x90
	s_mov_b32 s95, 0x7fffffe0
	s_movk_i32 s41, 0xffe0
	s_waitcnt vmcnt(0) lgkmcnt(0)
	v_lshlrev_b32_e32 v54, 16, v44
	v_and_b32_e32 v55, 0xffff0000, v44
	v_lshlrev_b32_e32 v44, 16, v45
	v_and_b32_e32 v45, 0xffff0000, v45
	v_pk_mul_f32 v[18:19], v[18:19], v[54:55]
	v_pk_mul_f32 v[20:21], v[20:21], v[44:45]
	v_cvt_pk_bf16_f32 v18, v18, v19
	v_cvt_pk_bf16_f32 v19, v20, v21
	global_store_dwordx2 v[52:53], v[18:19], off offset:512
	v_lshlrev_b32_e32 v18, 16, v46
	v_and_b32_e32 v19, 0xffff0000, v46
	v_lshlrev_b32_e32 v20, 16, v47
	v_and_b32_e32 v21, 0xffff0000, v47
	v_pk_mul_f32 v[18:19], v[22:23], v[18:19]
	v_pk_mul_f32 v[20:21], v[24:25], v[20:21]
	v_cvt_pk_bf16_f32 v18, v18, v19
	v_cvt_pk_bf16_f32 v19, v20, v21
	global_store_dwordx2 v[52:53], v[18:19], off offset:528
	v_lshlrev_b32_e32 v18, 16, v48
	v_and_b32_e32 v19, 0xffff0000, v48
	v_lshlrev_b32_e32 v20, 16, v49
	v_and_b32_e32 v21, 0xffff0000, v49
	v_pk_mul_f32 v[18:19], v[26:27], v[18:19]
	v_pk_mul_f32 v[20:21], v[28:29], v[20:21]
	v_cvt_pk_bf16_f32 v18, v18, v19
	v_cvt_pk_bf16_f32 v19, v20, v21
	global_store_dwordx2 v[52:53], v[18:19], off offset:544
	v_lshlrev_b32_e32 v18, 16, v50
	v_and_b32_e32 v19, 0xffff0000, v50
	v_lshlrev_b32_e32 v20, 16, v51
	v_and_b32_e32 v21, 0xffff0000, v51
	v_pk_mul_f32 v[18:19], v[30:31], v[18:19]
	v_pk_mul_f32 v[20:21], v[32:33], v[20:21]
	v_cvt_pk_bf16_f32 v18, v18, v19
	v_cvt_pk_bf16_f32 v19, v20, v21
	global_store_dwordx2 v[52:53], v[18:19], off offset:560

; DI unsigned pk2(float a, float b) { f32x2 v = {a, b}; return __builtin_bit_cast(unsigned, __builtin_convertvector(v, bf2_t)); }
; DI float bflo(unsigned u) { return __uint_as_float(u << 16); }
; DI float bfhi(unsigned u) { return __uint_as_float(u & 0xffff0000u); }
;     ...
;     for (int nt = 0; nt < 2; ++nt)
; #pragma unroll
;         for (int qd = 0; qd < 4; ++qd) {
;             const u32x2 g = gv[nt][qd];
;             const f32x16& o = nt ? o1 : o0;
;             u32x2 v;
;             v.x = pk2(o[4 * qd] * bflo(g.x), o[4 * qd + 1] * bfhi(g.x));
;             v.y = pk2(o[4 * qd + 2] * bflo(g.y), o[4 * qd + 3] * bfhi(g.y));
;             *(u32x2*)(yrow + 32 * nt + 8 * qd) = v;
;         }
.LBB0_711:
	v_lshlrev_b32_e32 v18, 16, v40
	v_and_b32_e32 v19, 0xffff0000, v40
	v_pk_mul_f32 v[2:3], v[2:3], v[18:19]
	v_lshlrev_b32_e32 v18, 16, v41
	v_and_b32_e32 v19, 0xffff0000, v41
	v_pk_mul_f32 v[4:5], v[4:5], v[18:19]
	v_cvt_pk_bf16_f32 v2, v2, v3
	v_cvt_pk_bf16_f32 v3, v4, v5
	global_store_dwordx2 v[42:43], v[2:3], off offset:64
	v_lshlrev_b32_e32 v2, 16, v38
	v_and_b32_e32 v3, 0xffff0000, v38
	v_lshlrev_b32_e32 v4, 16, v39
	v_and_b32_e32 v5, 0xffff0000, v39
	v_pk_mul_f32 v[2:3], v[6:7], v[2:3]
	v_pk_mul_f32 v[4:5], v[8:9], v[4:5]
	v_cvt_pk_bf16_f32 v2, v2, v3
	v_cvt_pk_bf16_f32 v3, v4, v5
	global_store_dwordx2 v[42:43], v[2:3], off offset:80
	v_lshlrev_b32_e32 v2, 16, v36
	v_and_b32_e32 v3, 0xffff0000, v36
	v_lshlrev_b32_e32 v4, 16, v37
	v_and_b32_e32 v5, 0xffff0000, v37
	v_pk_mul_f32 v[2:3], v[10:11], v[2:3]
	v_pk_mul_f32 v[4:5], v[12:13], v[4:5]
	v_cvt_pk_bf16_f32 v2, v2, v3
	v_cvt_pk_bf16_f32 v3, v4, v5
	global_store_dwordx2 v[42:43], v[2:3], off offset:96
	v_lshlrev_b32_e32 v2, 16, v34
	v_and_b32_e32 v3, 0xffff0000, v34
	v_lshlrev_b32_e32 v4, 16, v35
	v_and_b32_e32 v5, 0xffff0000, v35
	v_pk_mul_f32 v[2:3], v[14:15], v[2:3]
	v_pk_mul_f32 v[4:5], v[16:17], v[4:5]
	v_cvt_pk_bf16_f32 v2, v2, v3
	v_cvt_pk_bf16_f32 v3, v4, v5
	global_store_dwordx2 v[42:43], v[2:3], off offset:112

;     ...
;     const int tid = tid_op(), lane = tid & 63, w = tid >> 6, r = lane & 31, h = lane >> 5;
; DI void phase3(const Params& p, int l, unsigned char* smem, unsigned char* smem0) {
;     ...
;         const int code = *s_item;
;         if (code < 0) break;
;         const int x = code >> 8, idx = code & 255, bh = x + 8 * hf, b = bh >> 2, head = bh & 3;
;         if (idx < 192) {
;             const int qb = 63 - idx / 3, r3 = idx % 3, br = (r3 == 0) ? 1 : (r3 == 1 ? 2 : 0), q0 = qb * 128, nt = 2 * qb + 2;
;             if (br == 0) {
;                 attn_item<64, 1, true>((const bf16_t*)(ws + O_SBQ) + ((size_t)bh * S_ + q0) * 64, (const bf16_t*)(ws + O_SBK) + (size_t)bh * S_ * 64,
;                                  (const bf16_t*)(ws + O_SBVT) + (size_t)bh * 64 * S_, S_, nullptr, q0, nt, GATE + ((size_t)b * S_ + q0) * 1024 + 256 + head * 64, YBo + ((size_t)b * S_ + q0) * 1024 + 256 + head * 64, smem, smem0, hf);
;             } else if (br == 1) {
;                 attn_item<96, 0, false>((const bf16_t*)(ws + O_MQ) + ((size_t)bh * S_ + q0) * 96, (const bf16_t*)(ws + O_MK) + (size_t)bh * S_ * 96,
;                                  (const bf16_t*)(ws + O_MVT) + (size_t)bh * 64 * S_, S_, nullptr, q0, nt, GATE + ((size_t)b * S_ + q0) * 1024 + head * 64, YBo + ((size_t)b * S_ + q0) * 1024 + head * 64, smem, smem0, hf);
;             } else {
;                 attn_item<64, 0, true>((const bf16_t*)(ws + O_FQ) + ((size_t)bh * S_ + q0) * 64, (const bf16_t*)(ws + O_FK) + (size_t)bh * S_ * 64,
;                                  (const bf16_t*)(ws + O_FVT) + (size_t)bh * 64 * S_, S_, (const float*)(ws + O_FC) + (size_t)bh * S_, q0, nt,
;                                  GATE + ((size_t)b * S_ + q0) * 1024 + 512 + head * 64, YBo + ((size_t)b * S_ + q0) * 1024 + 512 + head * 64, smem, smem0, hf,
;                                  sqrtf(((const float*)(ws + O_KMAX))[bh]) * 1.0002f);
;             }
;         } else {
;             const int qb = idx - 192, q0 = qb * 128;
;             attn_item<64, 2, false>((const bf16_t*)(ws + O_MEMQ) + ((size_t)bh * S_ + q0) * 64, (const bf16_t*)(ws + O_MEMK) + (size_t)bh * 256 * 64,
;                              (const bf16_t*)(ws + O_MEMVT) + (size_t)bh * 64 * 256, 256, nullptr, q0, 4, GATE + ((size_t)b * S_ + q0) * 1024 + 768 + head * 64, YBo + ((size_t)b * S_ + q0) * 1024 + 768 + head * 64, smem, smem0, hf);
.LBB0_720:
	s_or_b64 exec, exec, s[4:5]
	s_waitcnt lgkmcnt(0)
	s_barrier
	ds_read_b32 v0, v219
	s_waitcnt lgkmcnt(0)
	v_cmp_gt_i32_e32 vcc, 0, v0
	v_readfirstlane_b32 s8, v0
	s_cbranch_vccnz .LBB0_730
	s_lshr_b32 s4, s8, 8
	s_add_i32 s10, s4, s72
	s_and_b32 s9, s8, 0xff
	s_lshr_b32 s56, s10, 2
	s_bfe_u32 s79, s8, 0x20008
	s_cmpk_gt_u32 s9, 0xbf
	s_mov_b64 s[4:5], -1
	s_cbranch_scc0 .LBB0_732
	s_lshl_b32 s4, s9, 7
	s_mov_b32 s11, s49
	s_add_i32 s48, s4, 0xffffa000
	s_lshl_b64 s[4:5], s[10:11], 20
	s_add_u32 s6, s73, s4
	s_addc_u32 s7, s74, s5
	s_lshl_b64 s[4:5], s[48:49], 7
	s_add_u32 s6, s6, s4
	s_addc_u32 s7, s7, s5
	s_lshl_b64 s[4:5], s[10:11], 15
	v_mov_b32_e32 v14, v215
	s_add_u32 s12, s75, s4
	s_addc_u32 s13, s87, s5
	v_lshlrev_b32_e32 v2, 4, v14
	v_lshlrev_b32_e32 v0, 6, v14
	v_and_b32_e32 v3, 0x70, v2
	s_movk_i32 s11, 0xfe00
	s_add_u32 s14, s62, s4
	v_and_or_b32 v4, v0, s11, v3
	v_mov_b32_e32 v3, v1
	v_add_u32_e32 v8, 0x1000, v2
	v_mov_b32_e32 v9, v1
	v_ashrrev_i32_e32 v0, 1, v14
	s_addc_u32 s15, s3, s5
	v_lshl_add_u64 v[6:7], s[12:13], 0, v[2:3]
	v_lshl_add_u64 v[10:11], s[12:13], 0, v[8:9]
	v_mov_b32_e32 v5, v1
	v_bfi_b32 v98, s41, v0, v14
	global_load_dwordx4 v[66:69], v[6:7], off
	global_load_dwordx4 v[70:73], v[10:11], off
	v_lshl_add_u64 v[6:7], s[14:15], 0, v[4:5]
	v_add_u32_e32 v10, 0x4000, v4
	v_mov_b32_e32 v11, v1
	v_ashrrev_i32_e32 v99, 31, v98
	v_lshl_add_u64 v[12:13], s[14:15], 0, v[10:11]
	global_load_dwordx4 v[74:77], v[6:7], off
	global_load_dwordx4 v[78:81], v[12:13], off
	v_bfe_u32 v101, v14, 5, 1
	v_lshlrev_b64 v[6:7], 7, v[98:99]
	v_lshl_add_u64 v[6:7], s[6:7], 0, v[6:7]
	v_lshlrev_b32_e32 v0, 4, v101
	v_lshl_add_u64 v[6:7], v[6:7], 0, v[0:1]
	global_load_dwordx4 v[82:85], v[6:7], off
	global_load_dwordx4 v[86:89], v[6:7], off offset:32
	global_load_dwordx4 v[90:93], v[6:7], off offset:64
	global_load_dwordx4 v[94:97], v[6:7], off offset:96
	v_ashrrev_i32_e32 v7, 31, v14
	v_add_u32_e32 v12, 0x100, v14
	v_and_b32_e32 v6, 31, v14
	v_lshrrev_b32_e32 v13, 3, v14
	v_lshlrev_b32_e32 v15, 3, v14
	v_lshrrev_b32_e32 v7, 29, v7
	v_ashrrev_i32_e32 v16, 31, v12
	s_movk_i32 s0, 0x48
	v_and_b32_e32 v15, 56, v15
	v_mul_lo_u32 v13, v13, s0
	v_lshrrev_b32_e32 v17, 3, v12
	v_mul_u32_u24_e32 v6, 0x48, v6
	v_add_u32_e32 v7, v14, v7
	v_lshrrev_b32_e32 v16, 29, v16
	v_lshlrev_b32_e32 v111, 1, v13
	v_lshlrev_b32_e32 v112, 1, v15
	v_mul_lo_u32 v13, v17, s0
	v_lshlrev_b32_e32 v6, 1, v6
	v_lshrrev_b32_e32 v15, 3, v7
	v_and_b32_e32 v7, -8, v7
	v_add_u32_e32 v16, v12, v16
	v_lshlrev_b32_e32 v113, 1, v13
	v_add3_u32 v114, s33, v6, v0
	v_sub_u32_e32 v0, v14, v7
	v_mul_lo_u32 v6, v15, s0
	v_lshrrev_b32_e32 v7, 3, v16
	v_and_b32_e32 v13, -8, v16
	v_lshlrev_b32_e32 v16, 3, v0
	v_lshlrev_b32_e32 v115, 1, v6
	v_lshlrev_b32_e32 v0, 4, v0
	v_sub_u32_e32 v6, v12, v13
	v_mul_lo_u32 v7, v7, s0
	v_add3_u32 v14, s33, v113, v112
	v_add3_u32 v0, s33, v115, v0
	v_lshlrev_b32_e32 v18, 3, v6
	v_lshlrev_b32_e32 v116, 1, v7
	v_lshlrev_b32_e32 v6, 4, v6
	v_add3_u32 v17, s33, v111, v112
	v_add3_u32 v6, s33, v116, v6
	s_waitcnt lgkmcnt(0)
	s_barrier
	v_mov_b32_e32 v15, v1
	v_lshl_add_u64 v[102:103], s[52:53], 0, v[10:11]
	v_lshl_add_u64 v[104:105], s[52:53], 0, v[4:5]
	v_lshl_add_u64 v[106:107], s[54:55], 0, v[8:9]
	v_lshl_add_u64 v[108:109], s[54:55], 0, v[2:3]
	v_mov_b32_e32 v2, v1
	v_mov_b32_e32 v4, v1
	s_waitcnt vmcnt(0)
	ds_write_b128 v0, v[66:69]
	ds_write_b128 v6, v[70:73]
	ds_write_b128 v17, v[74:77] offset:13312
	ds_write_b128 v14, v[78:81] offset:13312
	v_mov_b32_e32 v14, v1
	v_mov_b32_e32 v0, v1
	v_mov_b32_e32 v6, v1
	v_mov_b32_e32 v7, v1
	v_mov_b32_e32 v8, v1
	v_mov_b32_e32 v10, v1
	v_mov_b32_e32 v12, v1
	v_mov_b32_e32 v13, v1
	v_lshlrev_b32_e32 v119, 1, v18
	v_mov_b64_e32 v[32:33], v[14:15]
	v_lshlrev_b32_e32 v100, 3, v101
	v_lshlrev_b32_e32 v118, 1, v16
	v_mov_b64_e32 v[30:31], v[12:13]
	v_mov_b64_e32 v[28:29], v[10:11]
	v_mov_b64_e32 v[26:27], v[8:9]
	v_mov_b64_e32 v[24:25], v[6:7]
	v_mov_b64_e32 v[22:23], v[4:5]
	v_mov_b64_e32 v[20:21], v[2:3]
	v_mov_b64_e32 v[18:19], v[0:1]
	v_mov_b64_e32 v[16:17], v[14:15]
	s_mov_b32 s11, 0
	v_sub_u32_e32 v117, 0, v100
	v_mov_b32_e32 v120, 0
	v_mov_b32_e32 v110, 0xff800000
	v_mov_b64_e32 v[14:15], v[12:13]
	v_mov_b64_e32 v[12:13], v[10:11]
	v_mov_b64_e32 v[10:11], v[8:9]
	v_mov_b64_e32 v[8:9], v[6:7]
	v_mov_b64_e32 v[6:7], v[4:5]
	v_mov_b64_e32 v[4:5], v[2:3]
	v_mov_b64_e32 v[2:3], v[0:1]
	s_cmp_lg_u32 s11, 3
	s_cselect_b64 s[6:7], -1, 0
	s_cmp_eq_u32 s11, 3
	s_cbranch_scc1 .LBB0_724
.LBB0_723:
	v_lshl_add_u64 v[34:35], v[108:109], 0, s[4:5]
	s_waitcnt vmcnt(0)
	global_load_dwordx4 v[66:69], v[34:35], off
	v_lshl_add_u64 v[34:35], v[106:107], 0, s[4:5]
	global_load_dwordx4 v[70:73], v[34:35], off
	v_lshl_add_u64 v[34:35], v[104:105], 0, s[4:5]
	global_load_dwordx4 v[74:77], v[34:35], off
	v_lshl_add_u64 v[34:35], v[102:103], 0, s[4:5]
	global_load_dwordx4 v[78:81], v[34:35], off

; DI unsigned pk2(float a, float b) { f32x2 v = {a, b}; return __builtin_bit_cast(unsigned, __builtin_convertvector(v, bf2_t)); }
; DI float bflo(unsigned u) { return __uint_as_float(u << 16); }
; DI float bfhi(unsigned u) { return __uint_as_float(u & 0xffff0000u); }
; DI float xhalf_other(float x, int h) { auto r = __builtin_amdgcn_permlane32_swap(__float_as_uint(x), __float_as_uint(x), false, false); return h ? __uint_as_float(r[0]) : __uint_as_float(r[1]); }
;     ...
;     if (MODE != 1) {
;         const float lt = lsum + xhalf_other(lsum, h), inv = __builtin_amdgcn_rcpf(lt);
;         o0 *= inv; o1 *= inv;
;     }
;     bf16_t* yrow = yb + (size_t)(32 * w + r) * 1024 + 4 * h;
;     const bf16_t* grow = gt + (size_t)(32 * w + r) * 1024 + 4 * h;
;     u32x2 gv[2][4];
; #pragma unroll
;     for (int nt = 0; nt < 2; ++nt)
; #pragma unroll
;         for (int qd = 0; qd < 4; ++qd) gv[nt][qd] = *(const u32x2*)(grow + 32 * nt + 8 * qd);
; #pragma unroll
;     for (int nt = 0; nt < 2; ++nt)
; #pragma unroll
;         for (int qd = 0; qd < 4; ++qd) {
;             const u32x2 g = gv[nt][qd];
;             const f32x16& o = nt ? o1 : o0;
;             u32x2 v;
;             v.x = pk2(o[4 * qd] * bflo(g.x), o[4 * qd + 1] * bfhi(g.x));
;             v.y = pk2(o[4 * qd + 2] * bflo(g.y), o[4 * qd + 3] * bfhi(g.y));
;             *(u32x2*)(yrow + 32 * nt + 8 * qd) = v;
;         }
.LBB0_731:
	s_mov_b32 s57, s49
	s_lshl_b64 s[4:5], s[56:57], 23
	s_lshl_b64 s[6:7], s[48:49], 10
	s_add_u32 s4, s4, s6
	s_addc_u32 s5, s5, s7
	s_lshl_b64 s[4:5], s[4:5], 1
	s_add_u32 s6, s61, s4
	s_addc_u32 s7, s70, s5
	s_add_u32 s4, s69, s4
	s_addc_u32 s5, s60, s5
	s_lshl_b32 s11, s79, 7
	v_mov_b32_e32 v0, v34
	v_mov_b32_e32 v35, v34
	s_add_u32 s4, s4, s11
	s_nop 0
	v_permlane32_swap_b32_e32 v0, v35
	v_cmp_eq_u32_e32 vcc, 0, v101
	s_addc_u32 s5, s5, 0
	v_lshlrev_b64 v[42:43], 11, v[98:99]
	v_cndmask_b32_e32 v0, v0, v35, vcc
	v_add_f32_e32 v0, v34, v0
	v_lshl_add_u64 v[34:35], s[4:5], 0, v[42:43]
	v_mov_b32_e32 v101, v1
	v_lshl_add_u64 v[34:35], v[34:35], 0, v[100:101]
	global_load_dwordx2 v[44:45], v[34:35], off offset:1536
	global_load_dwordx2 v[46:47], v[34:35], off offset:1552
	global_load_dwordx2 v[48:49], v[34:35], off offset:1568
	global_load_dwordx2 v[50:51], v[34:35], off offset:1584
	global_load_dwordx2 v[40:41], v[34:35], off offset:1600
	global_load_dwordx2 v[38:39], v[34:35], off offset:1616
	global_load_dwordx2 v[36:37], v[34:35], off offset:1632
	s_nop 0
	global_load_dwordx2 v[34:35], v[34:35], off offset:1648
	v_rcp_f32_e32 v0, v0
	s_add_u32 s6, s6, s11
	s_addc_u32 s7, s7, 0
	v_lshl_add_u64 v[42:43], s[6:7], 0, v[42:43]
	v_pk_mul_f32 v[20:21], v[20:21], v[0:1] op_sel_hi:[1,0]
	v_pk_mul_f32 v[18:19], v[18:19], v[0:1] op_sel_hi:[1,0]
	v_lshl_add_u64 v[52:53], v[42:43], 0, v[100:101]
	v_pk_mul_f32 v[24:25], v[24:25], v[0:1] op_sel_hi:[1,0]
	v_pk_mul_f32 v[22:23], v[22:23], v[0:1] op_sel_hi:[1,0]
	v_pk_mul_f32 v[28:29], v[28:29], v[0:1] op_sel_hi:[1,0]
	v_pk_mul_f32 v[26:27], v[26:27], v[0:1] op_sel_hi:[1,0]
	v_pk_mul_f32 v[32:33], v[32:33], v[0:1] op_sel_hi:[1,0]
	v_pk_mul_f32 v[30:31], v[30:31], v[0:1] op_sel_hi:[1,0]
	s_mov_b64 s[4:5], 0x600
	v_lshl_add_u64 v[42:43], v[52:53], 0, s[4:5]
	v_pk_mul_f32 v[16:17], v[16:17], v[0:1] op_sel_hi:[1,0]
	v_pk_mul_f32 v[14:15], v[14:15], v[0:1] op_sel_hi:[1,0]
	v_pk_mul_f32 v[12:13], v[12:13], v[0:1] op_sel_hi:[1,0]
	v_pk_mul_f32 v[10:11], v[10:11], v[0:1] op_sel_hi:[1,0]
	v_pk_mul_f32 v[8:9], v[8:9], v[0:1] op_sel_hi:[1,0]
	v_pk_mul_f32 v[6:7], v[6:7], v[0:1] op_sel_hi:[1,0]
	v_pk_mul_f32 v[4:5], v[4:5], v[0:1] op_sel_hi:[1,0]
	v_pk_mul_f32 v[2:3], v[2:3], v[0:1] op_sel_hi:[1,0]
	s_mov_b64 s[4:5], 0
	s_waitcnt vmcnt(0) lgkmcnt(0)
	v_lshlrev_b32_e32 v54, 16, v44
	v_and_b32_e32 v55, 0xffff0000, v44
	v_lshlrev_b32_e32 v44, 16, v45
	v_and_b32_e32 v45, 0xffff0000, v45
	v_pk_mul_f32 v[18:19], v[18:19], v[54:55]
	v_pk_mul_f32 v[20:21], v[20:21], v[44:45]
	v_cvt_pk_bf16_f32 v18, v18, v19
	v_cvt_pk_bf16_f32 v19, v20, v21
	global_store_dwordx2 v[52:53], v[18:19], off offset:1536
	v_lshlrev_b32_e32 v18, 16, v46
	v_and_b32_e32 v19, 0xffff0000, v46
	v_lshlrev_b32_e32 v20, 16, v47
	v_and_b32_e32 v21, 0xffff0000, v47
	v_pk_mul_f32 v[18:19], v[22:23], v[18:19]
	v_pk_mul_f32 v[20:21], v[24:25], v[20:21]
	v_cvt_pk_bf16_f32 v18, v18, v19
	v_cvt_pk_bf16_f32 v19, v20, v21
	global_store_dwordx2 v[52:53], v[18:19], off offset:1552
	v_lshlrev_b32_e32 v18, 16, v48
	v_and_b32_e32 v19, 0xffff0000, v48
	v_lshlrev_b32_e32 v20, 16, v49
	v_and_b32_e32 v21, 0xffff0000, v49
	v_pk_mul_f32 v[18:19], v[26:27], v[18:19]
	v_pk_mul_f32 v[20:21], v[28:29], v[20:21]
	v_cvt_pk_bf16_f32 v18, v18, v19
	v_cvt_pk_bf16_f32 v19, v20, v21
	global_store_dwordx2 v[52:53], v[18:19], off offset:1568
	v_lshlrev_b32_e32 v18, 16, v50
	v_and_b32_e32 v19, 0xffff0000, v50
	v_lshlrev_b32_e32 v20, 16, v51
	v_and_b32_e32 v21, 0xffff0000, v51
	v_pk_mul_f32 v[18:19], v[30:31], v[18:19]
	v_pk_mul_f32 v[20:21], v[32:33], v[20:21]
	v_cvt_pk_bf16_f32 v18, v18, v19
	v_cvt_pk_bf16_f32 v19, v20, v21
	global_store_dwordx2 v[52:53], v[18:19], off offset:1584
;     ...
;     const int qidx = q0 + 32 * w + r;
;     bf16x8 qf[NKS];
; #pragma unroll
;     for (int s = 0; s < NKS; ++s) qf[s] = *(const bf16x8*)(Q + (size_t)(32 * w + r) * DQK + 16 * s + 8 * h);
;     float qn = 0.f;
;     if (MODE == 0 && DESC) {
; #pragma unroll
;         for (int s = 0; s < NKS; ++s)
; #pragma unroll
;             for (int j = 0; j < 8; ++j) { const float a = __uint_as_float(((unsigned)(unsigned short)qf[s][j]) << 16); qn += a * a; }
;         qn += xhalf_other(qn, h);
;         qn = sqrtf(qn) * kmax;
;     }
;     f32x16 o0, o1;
; #pragma unroll
;     for (int i = 0; i < 16; ++i) { o0[i] = 0.f; o1[i] = 0.f; }
;     float m = -INFINITY, lsum = 0.f, R = 1.f;
;     u32x4 rk[NKL], rv[2]; f32x4 rc = {0.f, 0.f, 0.f, 0.f};
; DI void phase3(const Params& p, int l, unsigned char* smem, unsigned char* smem0) {
;     ...
;             const int qb = 63 - idx / 3, r3 = idx % 3, br = (r3 == 0) ? 1 : (r3 == 1 ? 2 : 0), q0 = qb * 128, nt = 2 * qb + 2;
;             if (br == 0) {
;                 attn_item<64, 1, true>((const bf16_t*)(ws + O_SBQ) + ((size_t)bh * S_ + q0) * 64, (const bf16_t*)(ws + O_SBK) + (size_t)bh * S_ * 64,
;                                  (const bf16_t*)(ws + O_SBVT) + (size_t)bh * 64 * S_, S_, nullptr, q0, nt, GATE + ((size_t)b * S_ + q0) * 1024 + 256 + head * 64, YBo + ((size_t)b * S_ + q0) * 1024 + 256 + head * 64, smem, smem0, hf);
;             } else if (br == 1) {
;                 attn_item<96, 0, false>((const bf16_t*)(ws + O_MQ) + ((size_t)bh * S_ + q0) * 96, (const bf16_t*)(ws + O_MK) + (size_t)bh * S_ * 96,
;                                  (const bf16_t*)(ws + O_MVT) + (size_t)bh * 64 * S_, S_, nullptr, q0, nt, GATE + ((size_t)b * S_ + q0) * 1024 + head * 64, YBo + ((size_t)b * S_ + q0) * 1024 + head * 64, smem, smem0, hf);
;             } else {
;                 attn_item<64, 0, true>((const bf16_t*)(ws + O_FQ) + ((size_t)bh * S_ + q0) * 64, (const bf16_t*)(ws + O_FK) + (size_t)bh * S_ * 64,
;                                  (const bf16_t*)(ws + O_FVT) + (size_t)bh * 64 * S_, S_, (const float*)(ws + O_FC) + (size_t)bh * S_, q0, nt,
;                                  GATE + ((size_t)b * S_ + q0) * 1024 + 512 + head * 64, YBo + ((size_t)b * S_ + q0) * 1024 + 512 + head * 64, smem, smem0, hf,
;                                  sqrtf(((const float*)(ws + O_KMAX))[bh]) * 1.0002f);
.LBB0_732:
	s_and_b64 vcc, exec, s[4:5]
	s_cbranch_vccz .LBB0_711
	s_mulk_i32 s9, 0xab
	s_lshr_b32 s4, s9, 9
	s_sub_i32 s5, 63, s4
	s_mul_i32 s4, s4, 3
	s_sub_i32 s4, s8, s4
	s_and_b32 s4, s4, 0xff
	s_cmp_eq_u32 s4, 1
	s_cselect_b32 s6, 2, 0
	s_cmp_lg_u32 s4, 0
	s_cselect_b32 s6, s6, 1
	s_lshl_b32 s22, s5, 1
	s_lshl_b32 s94, s5, 7
	s_add_i32 s66, s22, 2
	s_mov_b32 s11, s49
	s_cmp_lt_i32 s6, 1
	s_mov_b64 s[4:5], -1
	s_cbranch_scc1 .LBB0_787
	s_cmp_lg_u32 s6, 1
	s_cbranch_scc0 .LBB0_771
	s_mov_b32 s95, s49
	s_lshl_b64 s[4:5], s[94:95], 7
	s_lshl_b64 s[6:7], s[10:11], 20
	s_or_b64 s[4:5], s[6:7], s[4:5]
	v_readlane_b32 s0, v255, 7
	s_add_u32 s4, s0, s4
	v_readlane_b32 s0, v255, 8
	s_addc_u32 s5, s0, s5
	v_readlane_b32 s0, v255, 9
	s_add_u32 s23, s0, s6
	v_readlane_b32 s0, v255, 10
	s_addc_u32 s24, s0, s7
	v_readlane_b32 s0, v255, 11
	s_add_u32 s25, s0, s6
	v_readlane_b32 s0, v255, 12
	s_addc_u32 s26, s0, s7
	s_lshl_b64 s[6:7], s[10:11], 15
	v_readlane_b32 s0, v255, 13
	s_add_u32 s12, s0, s6
	v_readlane_b32 s0, v255, 14
	s_addc_u32 s13, s0, s7
	s_lshl_b32 s6, s10, 2
	v_readlane_b32 s0, v255, 15
	s_add_u32 s6, s0, s6
	v_readlane_b32 s0, v255, 16
	s_addc_u32 s7, s0, 0
	v_mov_b64_e32 v[2:3], s[6:7]
	v_mov_b32_e32 v8, v215
	global_load_dword v6, v[2:3], off
	s_or_b32 s27, s22, 1
	v_ashrrev_i32_e32 v2, 6, v8
	v_and_b32_e32 v3, 31, v8
	v_lshlrev_b32_e32 v5, 5, v2
	v_or_b32_e32 v102, v5, v3
	v_ashrrev_i32_e32 v103, 31, v102
	v_bfe_u32 v4, v8, 5, 1
	v_lshlrev_b64 v[10:11], 7, v[102:103]
	v_lshl_add_u64 v[10:11], s[4:5], 0, v[10:11]
	v_lshlrev_b32_e32 v0, 4, v4
	v_lshl_add_u64 v[10:11], v[10:11], 0, v[0:1]
	global_load_dwordx4 v[66:69], v[10:11], off
	global_load_dwordx4 v[70:73], v[10:11], off offset:32
	global_load_dwordx4 v[74:77], v[10:11], off offset:64
	global_load_dwordx4 v[78:81], v[10:11], off offset:96
	s_lshl_b32 s48, s27, 6
	s_lshl_b64 s[4:5], s[48:49], 7
	s_add_u32 s4, s23, s4
	v_lshlrev_b32_e32 v11, 11, v8
	s_movk_i32 s0, 0xc000
	s_addc_u32 s5, s24, s5
	v_mov_b32_e32 v107, v1
	v_mov_b32_e32 v105, v1
	v_mov_b32_e32 v109, v1
	v_cmp_lt_i32_e32 vcc, 15, v8
	v_lshlrev_b32_e32 v110, 2, v8
	s_waitcnt vmcnt(0) lgkmcnt(0)
	v_and_b32_e32 v7, 0xffff0000, v66
	v_lshlrev_b32_e32 v0, 16, v66
	v_mul_f32_e32 v7, v7, v7
	v_fmac_f32_e32 v7, v0, v0
	v_lshlrev_b32_e32 v0, 16, v67
	v_fmac_f32_e32 v7, v0, v0
	v_and_b32_e32 v0, 0xffff0000, v67
	v_fmac_f32_e32 v7, v0, v0
	v_lshlrev_b32_e32 v0, 16, v68
	v_fmac_f32_e32 v7, v0, v0
	v_and_b32_e32 v0, 0xffff0000, v68
	v_fmac_f32_e32 v7, v0, v0
	v_lshlrev_b32_e32 v0, 16, v69
	v_fmac_f32_e32 v7, v0, v0
	v_and_b32_e32 v0, 0xffff0000, v69
	v_fmac_f32_e32 v7, v0, v0
	v_lshlrev_b32_e32 v0, 16, v70
	v_fmac_f32_e32 v7, v0, v0
	v_and_b32_e32 v0, 0xffff0000, v70
	v_fmac_f32_e32 v7, v0, v0
	v_lshlrev_b32_e32 v0, 16, v71
	v_fmac_f32_e32 v7, v0, v0
	v_and_b32_e32 v0, 0xffff0000, v71
	v_fmac_f32_e32 v7, v0, v0
	v_lshlrev_b32_e32 v0, 16, v72
	v_fmac_f32_e32 v7, v0, v0
	v_and_b32_e32 v0, 0xffff0000, v72
	v_fmac_f32_e32 v7, v0, v0
	v_lshlrev_b32_e32 v0, 16, v73
	v_fmac_f32_e32 v7, v0, v0
	v_and_b32_e32 v0, 0xffff0000, v73
	v_fmac_f32_e32 v7, v0, v0
	v_lshlrev_b32_e32 v0, 16, v74
	v_fmac_f32_e32 v7, v0, v0
	v_and_b32_e32 v0, 0xffff0000, v74
	v_fmac_f32_e32 v7, v0, v0
	v_lshlrev_b32_e32 v0, 16, v75
	v_fmac_f32_e32 v7, v0, v0
	v_and_b32_e32 v0, 0xffff0000, v75
	v_fmac_f32_e32 v7, v0, v0
	v_lshlrev_b32_e32 v0, 16, v76
	v_fmac_f32_e32 v7, v0, v0
	v_and_b32_e32 v0, 0xffff0000, v76
	v_fmac_f32_e32 v7, v0, v0
	v_lshlrev_b32_e32 v0, 16, v77
	v_fmac_f32_e32 v7, v0, v0
	v_and_b32_e32 v0, 0xffff0000, v77
	v_fmac_f32_e32 v7, v0, v0
	v_lshlrev_b32_e32 v0, 16, v78
	v_fmac_f32_e32 v7, v0, v0
	v_and_b32_e32 v0, 0xffff0000, v78
	v_fmac_f32_e32 v7, v0, v0
	v_lshlrev_b32_e32 v0, 16, v79
	v_fmac_f32_e32 v7, v0, v0
	v_and_b32_e32 v0, 0xffff0000, v79
	v_fmac_f32_e32 v7, v0, v0
	v_lshlrev_b32_e32 v0, 16, v80
	v_fmac_f32_e32 v7, v0, v0
	v_and_b32_e32 v0, 0xffff0000, v80
	v_fmac_f32_e32 v7, v0, v0
	v_lshlrev_b32_e32 v0, 16, v81
	v_fmac_f32_e32 v7, v0, v0
	v_and_b32_e32 v0, 0xffff0000, v81
	v_fmac_f32_e32 v7, v0, v0
	v_lshlrev_b32_e32 v0, 4, v8
	v_and_b32_e32 v12, 0x70, v0
	v_and_or_b32 v104, v11, s0, v12
	v_lshl_add_u64 v[12:13], s[4:5], 0, v[0:1]
	v_add_u32_e32 v106, 0x1000, v0
	global_load_dwordx4 v[82:85], v[12:13], off
	v_lshl_add_u64 v[12:13], s[4:5], 0, v[106:107]
	s_lshl_b32 s4, s27, 7
	s_add_u32 s4, s25, s4
	s_addc_u32 s5, s26, 0
	global_load_dwordx4 v[86:89], v[12:13], off
	v_lshl_add_u64 v[12:13], s[4:5], 0, v[104:105]
	v_add_u32_e32 v108, 0x80000, v104
	global_load_dwordx4 v[90:93], v[12:13], off
	v_lshl_add_u64 v[12:13], s[4:5], 0, v[108:109]
	global_load_dwordx4 v[94:97], v[12:13], off
	v_mov_b32_e32 v9, v7
	v_mov_b32_e32 v10, v7
	s_nop 1
	v_permlane32_swap_b32_e32 v9, v10
	v_cmp_gt_i32_e64 s[4:5], 16, v8
	s_and_saveexec_b64 s[6:7], vcc
	s_xor_b64 s[6:7], exec, s[6:7]
	v_lshlrev_b32_e32 v110, 2, v8
	s_or_saveexec_b64 s[6:7], s[6:7]
	v_mov_b32_e32 v98, v1
	v_mov_b32_e32 v99, v1
	v_mov_b32_e32 v100, v1
	v_mov_b32_e32 v101, v1
	s_xor_b64 exec, exec, s[6:7]
	s_cbranch_execz .LBB0_739
	s_lshl_b64 s[8:9], s[48:49], 2
	s_add_u32 s8, s12, s8
	s_addc_u32 s9, s13, s9
	v_ashrrev_i32_e32 v111, 31, v110
	v_lshl_add_u64 v[12:13], v[110:111], 2, s[8:9]
	global_load_dwordx4 v[98:101], v[12:13], off

;     ...
;     auto ld_tile = [&](int kt) {
;         const unsigned char* Kt = (const unsigned char*)(K + (size_t)(64 * kt) * DQK);
;         const unsigned char* Vt = (const unsigned char*)(VT + 64 * kt);
; #pragma unroll
;         for (int j = 0; j < NKL; ++j) rk[j] = *(const u32x4*)(Kt + (okk + j * 4096));
; #pragma unroll
;         for (int j = 0; j < 2; ++j) rv[j] = *(const u32x4*)(Vt + (ovv + j * svv));
;         if (cdec && tid < 16) rc = *(const f32x4*)(cdec + 64 * kt + 4 * tid);
;     };
;     auto st_tile = [&](int buf) {
;         bf16_t* sK = (bf16_t*)(smem + buf * ATT_BUF); bf16_t* sV = (bf16_t*)(smem + buf * ATT_BUF + 13312); float* sC = (float*)(smem + buf * ATT_BUF + 22528);
; #pragma unroll
;         for (int j = 0; j < NKL; ++j) { const int c = tid + 256 * j, row = c / KCH, kc = (c % KCH) * 8; *(u32x4*)(sK + row * KS + kc) = rk[j]; }
; #pragma unroll
;         for (int j = 0; j < 2; ++j) { const int c = tid + 256 * j, row = c >> 3, kc = (c & 7) * 8; *(u32x4*)(sV + row * LS + kc) = rv[j]; }
;         if (cdec && tid < 16) *(f32x4*)(sC + 4 * tid) = rc;
;     };
;     ld_tile(DESC ? ntiles - 1 : 0);
;     __syncthreads();
;     st_tile(0);
; #pragma unroll 1
;     for (int it = 0; it < ntiles; ++it) {
;         const int kt = DESC ? ntiles - 1 - it : it, buf = it & 1;
;         if (it + 1 < ntiles) ld_tile(DESC ? kt - 1 : kt + 1);
.LBB0_744:
	s_add_i32 s29, s20, 1
	s_cmp_lt_u32 s29, s66
	s_cselect_b64 s[16:17], -1, 0
	s_cmp_ge_u32 s29, s66
	s_cbranch_scc1 .LBB0_748
	s_ashr_i32 s15, s14, 31
	s_lshl_b64 s[18:19], s[14:15], 7
	s_add_u32 s18, s23, s18
	s_addc_u32 s19, s24, s19
	v_lshl_add_u64 v[34:35], s[18:19], 0, v[0:1]
	v_lshl_add_u64 v[36:37], s[18:19], 0, v[106:107]
	s_lshl_b64 s[18:19], s[14:15], 1
	s_add_u32 s18, s25, s18
	s_addc_u32 s19, s26, s19
	s_waitcnt vmcnt(0)
	global_load_dwordx4 v[82:85], v[34:35], off
	global_load_dwordx4 v[86:89], v[36:37], off
	v_lshl_add_u64 v[34:35], s[18:19], 0, v[104:105]
	v_lshl_add_u64 v[36:37], s[18:19], 0, v[108:109]
	global_load_dwordx4 v[90:93], v[34:35], off
	global_load_dwordx4 v[94:97], v[36:37], off
	s_and_saveexec_b64 s[18:19], s[4:5]
	s_cbranch_execz .LBB0_747
	v_lshl_add_u64 v[34:35], s[14:15], 2, v[114:115]
	global_load_dwordx4 v[98:101], v[34:35], off

; DI unsigned pk2(float a, float b) { f32x2 v = {a, b}; return __builtin_bit_cast(unsigned, __builtin_convertvector(v, bf2_t)); }
; DI float bflo(unsigned u) { return __uint_as_float(u << 16); }
; DI float bfhi(unsigned u) { return __uint_as_float(u & 0xffff0000u); }
; DI float xhalf_other(float x, int h) { auto r = __builtin_amdgcn_permlane32_swap(__float_as_uint(x), __float_as_uint(x), false, false); return h ? __uint_as_float(r[0]) : __uint_as_float(r[1]); }
;     ...
;     if (MODE != 1) {
;         const float lt = lsum + xhalf_other(lsum, h), inv = __builtin_amdgcn_rcpf(lt);
;         o0 *= inv; o1 *= inv;
;     }
;     bf16_t* yrow = yb + (size_t)(32 * w + r) * 1024 + 4 * h;
;     const bf16_t* grow = gt + (size_t)(32 * w + r) * 1024 + 4 * h;
;     u32x2 gv[2][4];
; #pragma unroll
;     for (int nt = 0; nt < 2; ++nt)
; #pragma unroll
;         for (int qd = 0; qd < 4; ++qd) gv[nt][qd] = *(const u32x2*)(grow + 32 * nt + 8 * qd);
; #pragma unroll
;     for (int nt = 0; nt < 2; ++nt)
; #pragma unroll
;         for (int qd = 0; qd < 4; ++qd) {
;             const u32x2 g = gv[nt][qd];
;             const f32x16& o = nt ? o1 : o0;
;             u32x2 v;
;             v.x = pk2(o[4 * qd] * bflo(g.x), o[4 * qd + 1] * bfhi(g.x));
;             v.y = pk2(o[4 * qd + 2] * bflo(g.y), o[4 * qd + 3] * bfhi(g.y));
;             *(u32x2*)(yrow + 32 * nt + 8 * qd) = v;
;         }
.LBB0_770:
	s_mov_b32 s57, s49
	s_lshl_b64 s[4:5], s[94:95], 11
	s_lshl_b64 s[8:9], s[56:57], 24
	s_or_b64 s[4:5], s[4:5], s[8:9]
	s_add_u32 s8, s69, s4
	s_addc_u32 s9, s60, s5
	s_lshl_b32 s12, s79, 7
	s_add_u32 s8, s8, s12
	s_addc_u32 s9, s9, 0
	v_lshlrev_b64 v[42:43], 11, v[102:103]
	v_lshl_add_u64 v[34:35], s[8:9], 0, v[42:43]
	v_lshlrev_b32_e32 v0, 1, v112
	v_lshl_add_u64 v[34:35], v[34:35], 0, v[0:1]
	global_load_dwordx2 v[44:45], v[34:35], off offset:1024
	global_load_dwordx2 v[46:47], v[34:35], off offset:1040
	global_load_dwordx2 v[48:49], v[34:35], off offset:1056
	global_load_dwordx2 v[50:51], v[34:35], off offset:1072
	global_load_dwordx2 v[40:41], v[34:35], off offset:1088
	global_load_dwordx2 v[38:39], v[34:35], off offset:1104
	global_load_dwordx2 v[36:37], v[34:35], off offset:1120
	s_nop 0
	global_load_dwordx2 v[34:35], v[34:35], off offset:1136
	v_mov_b32_e32 v52, v111
	v_mov_b32_e32 v53, v111
	s_nop 1
	v_permlane32_swap_b32_e32 v52, v53
	v_cndmask_b32_e64 v52, v52, v53, s[6:7]
	v_add_f32_e32 v52, v111, v52
	v_rcp_f32_e32 v52, v52
	s_add_u32 s4, s61, s4
	s_addc_u32 s5, s70, s5
	s_add_u32 s4, s4, s12
	s_addc_u32 s5, s5, 0
	v_pk_mul_f32 v[20:21], v[20:21], v[52:53] op_sel_hi:[1,0]
	v_pk_mul_f32 v[18:19], v[18:19], v[52:53] op_sel_hi:[1,0]
	v_lshl_add_u64 v[42:43], s[4:5], 0, v[42:43]
	v_pk_mul_f32 v[32:33], v[32:33], v[52:53] op_sel_hi:[1,0]
	v_pk_mul_f32 v[30:31], v[30:31], v[52:53] op_sel_hi:[1,0]
	v_pk_mul_f32 v[28:29], v[28:29], v[52:53] op_sel_hi:[1,0]
	v_pk_mul_f32 v[26:27], v[26:27], v[52:53] op_sel_hi:[1,0]
	v_pk_mul_f32 v[24:25], v[24:25], v[52:53] op_sel_hi:[1,0]
	v_pk_mul_f32 v[22:23], v[22:23], v[52:53] op_sel_hi:[1,0]
	v_pk_mul_f32 v[16:17], v[16:17], v[52:53] op_sel_hi:[1,0]
	v_pk_mul_f32 v[14:15], v[14:15], v[52:53] op_sel_hi:[1,0]
	v_pk_mul_f32 v[12:13], v[12:13], v[52:53] op_sel_hi:[1,0]
	v_pk_mul_f32 v[10:11], v[10:11], v[52:53] op_sel_hi:[1,0]
	v_pk_mul_f32 v[8:9], v[8:9], v[52:53] op_sel_hi:[1,0]
	v_pk_mul_f32 v[6:7], v[6:7], v[52:53] op_sel_hi:[1,0]
	v_pk_mul_f32 v[4:5], v[4:5], v[52:53] op_sel_hi:[1,0]
	v_pk_mul_f32 v[2:3], v[2:3], v[52:53] op_sel_hi:[1,0]
	v_lshl_add_u64 v[52:53], v[42:43], 0, v[0:1]
	s_mov_b64 s[0:1], 0x400
	v_lshl_add_u64 v[42:43], v[52:53], 0, s[0:1]
	s_mov_b64 s[4:5], 0
	s_mov_b32 s95, 0x7fffffe0
	s_waitcnt vmcnt(0) lgkmcnt(0)
	v_lshlrev_b32_e32 v54, 16, v44
	v_and_b32_e32 v55, 0xffff0000, v44
	v_lshlrev_b32_e32 v44, 16, v45
	v_and_b32_e32 v45, 0xffff0000, v45
	v_lshlrev_b32_e32 v56, 16, v46
	v_and_b32_e32 v57, 0xffff0000, v46
	v_lshlrev_b32_e32 v46, 16, v47
	v_and_b32_e32 v47, 0xffff0000, v47
	v_lshlrev_b32_e32 v58, 16, v48
	v_and_b32_e32 v59, 0xffff0000, v48
	v_lshlrev_b32_e32 v48, 16, v49
	v_and_b32_e32 v49, 0xffff0000, v49
	v_lshlrev_b32_e32 v60, 16, v50
	v_and_b32_e32 v61, 0xffff0000, v50
	v_lshlrev_b32_e32 v50, 16, v51
	v_and_b32_e32 v51, 0xffff0000, v51
	v_pk_mul_f32 v[18:19], v[18:19], v[54:55]
	v_pk_mul_f32 v[20:21], v[20:21], v[44:45]
	v_pk_mul_f32 v[22:23], v[22:23], v[56:57]
	v_pk_mul_f32 v[24:25], v[24:25], v[46:47]
	v_pk_mul_f32 v[26:27], v[26:27], v[58:59]
	v_pk_mul_f32 v[28:29], v[28:29], v[48:49]
	v_pk_mul_f32 v[30:31], v[30:31], v[60:61]
	v_pk_mul_f32 v[32:33], v[32:33], v[50:51]
	v_cvt_pk_bf16_f32 v18, v18, v19
	v_cvt_pk_bf16_f32 v19, v20, v21
	v_cvt_pk_bf16_f32 v20, v22, v23
	v_cvt_pk_bf16_f32 v21, v24, v25
	v_cvt_pk_bf16_f32 v22, v26, v27
	v_cvt_pk_bf16_f32 v23, v28, v29
	v_cvt_pk_bf16_f32 v24, v30, v31
	v_cvt_pk_bf16_f32 v25, v32, v33
	global_store_dwordx2 v[52:53], v[18:19], off offset:1024
	global_store_dwordx2 v[52:53], v[20:21], off offset:1040
	global_store_dwordx2 v[52:53], v[22:23], off offset:1056
	global_store_dwordx2 v[52:53], v[24:25], off offset:1072
;     constexpr int KS = DQK + 8, NKS = DQK / 16, KCH = DQK / 8, NKL = 64 * KCH / 256;
;     const int tid = tid_op(), lane = tid & 63, w = tid >> 6, r = lane & 31, h = lane >> 5;
;     const int qidx = q0 + 32 * w + r;
;     bf16x8 qf[NKS];
; #pragma unroll
;     for (int s = 0; s < NKS; ++s) qf[s] = *(const bf16x8*)(Q + (size_t)(32 * w + r) * DQK + 16 * s + 8 * h);
;     float qn = 0.f;
;     if (MODE == 0 && DESC) {
; #pragma unroll
;         for (int s = 0; s < NKS; ++s)
; #pragma unroll
;             for (int j = 0; j < 8; ++j) { const float a = __uint_as_float(((unsigned)(unsigned short)qf[s][j]) << 16); qn += a * a; }
;         qn += xhalf_other(qn, h);
;         qn = sqrtf(qn) * kmax;
;     }
;     f32x16 o0, o1;
; #pragma unroll
;     for (int i = 0; i < 16; ++i) { o0[i] = 0.f; o1[i] = 0.f; }
;     float m = -INFINITY, lsum = 0.f, R = 1.f;
;     u32x4 rk[NKL], rv[2]; f32x4 rc = {0.f, 0.f, 0.f, 0.f};
;     const unsigned okk = (unsigned)(((tid / KCH) * DQK + (tid % KCH) * 8) * 2);
;     const unsigned ovv = (unsigned)(((tid >> 3) * ldv + (tid & 7) * 8) * 2), svv = (unsigned)(ldv * 64);
;     auto ld_tile = [&](int kt) {
;         const unsigned char* Kt = (const unsigned char*)(K + (size_t)(64 * kt) * DQK);
;         const unsigned char* Vt = (const unsigned char*)(VT + 64 * kt);
; #pragma unroll
;         for (int j = 0; j < NKL; ++j) rk[j] = *(const u32x4*)(Kt + (okk + j * 4096));
; #pragma unroll
;         for (int j = 0; j < 2; ++j) rv[j] = *(const u32x4*)(Vt + (ovv + j * svv));
;         if (cdec && tid < 16) rc = *(const f32x4*)(cdec + 64 * kt + 4 * tid);
;     };
;     auto st_tile = [&](int buf) {
;         bf16_t* sK = (bf16_t*)(smem + buf * ATT_BUF); bf16_t* sV = (bf16_t*)(smem + buf * ATT_BUF + 13312); float* sC = (float*)(smem + buf * ATT_BUF + 22528);
; #pragma unroll
;         for (int j = 0; j < NKL; ++j) { const int c = tid + 256 * j, row = c / KCH, kc = (c % KCH) * 8; *(u32x4*)(sK + row * KS + kc) = rk[j]; }
; #pragma unroll
;         for (int j = 0; j < 2; ++j) { const int c = tid + 256 * j, row = c >> 3, kc = (c & 7) * 8; *(u32x4*)(sV + row * LS + kc) = rv[j]; }
;         if (cdec && tid < 16) *(f32x4*)(sC + 4 * tid) = rc;
;     };
;     ld_tile(DESC ? ntiles - 1 : 0);
;     __syncthreads();
;     st_tile(0);
; #pragma unroll 1
;     for (int it = 0; it < ntiles; ++it) {
.LBB0_771:
	s_and_b64 vcc, exec, s[4:5]
	s_cbranch_vccz .LBB0_786
	s_lshl_b64 s[4:5], s[10:11], 13
	s_or_b32 s4, s4, s94
	s_mulk_i32 s5, 0xc0
	s_mul_hi_u32 s6, s4, 0xc0
	s_add_i32 s5, s6, s5
	s_mulk_i32 s4, 0xc0
	v_readlane_b32 s0, v254, 58
	s_add_u32 s6, s0, s4
	v_readlane_b32 s0, v254, 59
	v_mov_b32_e32 v8, v215
	s_addc_u32 s7, s0, s5
	s_mul_i32 s4, s10, 0x180000
	v_ashrrev_i32_e32 v9, 1, v8
	v_readlane_b32 s0, v254, 60
	v_bfe_u32 v121, v8, 5, 1
	v_bfi_b32 v110, s41, v9, v8
	v_mov_b64_e32 v[2:3], s[6:7]
	s_mul_hi_u32 s5, s10, 0x180000
	s_add_u32 s4, s0, s4
	v_readlane_b32 s0, v254, 61
	v_mad_i64_i32 v[2:3], s[6:7], v110, s85, v[2:3]
	v_lshlrev_b32_e32 v0, 4, v121
	s_addc_u32 s5, s0, s5
	v_lshl_add_u64 v[2:3], v[2:3], 0, v[0:1]
	v_lshlrev_b32_e32 v0, 4, v8
	v_lshl_add_u64 v[4:5], s[4:5], 0, v[0:1]
	v_add_u32_e32 v112, 0x1000, v0
	v_mov_b32_e32 v113, v1
	v_lshl_add_u64 v[6:7], s[4:5], 0, v[112:113]
	global_load_dwordx4 v[66:69], v[4:5], off
	global_load_dwordx4 v[70:73], v[6:7], off
	v_add_u32_e32 v114, 0x2000, v0
	v_mov_b32_e32 v115, v1
	s_lshl_b64 s[6:7], s[10:11], 20
	v_lshl_add_u64 v[4:5], s[4:5], 0, v[114:115]
	v_readlane_b32 s0, v254, 62
	global_load_dwordx4 v[74:77], v[4:5], off
	s_add_u32 s6, s0, s6
	v_readlane_b32 s0, v254, 63
	s_addc_u32 s7, s0, s7
	v_lshlrev_b32_e32 v4, 11, v8
	v_and_b32_e32 v5, 0x70, v0
	s_movk_i32 s0, 0xc000
	v_and_or_b32 v116, v4, s0, v5
	v_mov_b32_e32 v117, v1
	v_lshl_add_u64 v[4:5], s[6:7], 0, v[116:117]
	global_load_dwordx4 v[78:81], v[4:5], off
	v_add_u32_e32 v118, 0x80000, v116
	v_mov_b32_e32 v119, v1
	v_lshl_add_u64 v[4:5], s[6:7], 0, v[118:119]
	global_load_dwordx4 v[82:85], v[4:5], off
	global_load_dwordx4 v[86:89], v[2:3], off
	global_load_dwordx4 v[90:93], v[2:3], off offset:32
	global_load_dwordx4 v[94:97], v[2:3], off offset:64
	global_load_dwordx4 v[98:101], v[2:3], off offset:96
	global_load_dwordx4 v[102:105], v[2:3], off offset:128
	global_load_dwordx4 v[106:109], v[2:3], off offset:160
	s_add_u32 s14, s4, 0x3000
	s_addc_u32 s15, s5, 0
	global_load_dwordx4 v[176:179], v0, s[14:15]
	global_load_dwordx4 v[180:183], v112, s[14:15]
	global_load_dwordx4 v[184:187], v114, s[14:15]
	s_mov_b32 s0, 0x2aaaaaab
	v_mul_hi_i32 v5, v8, s0
	v_add_u32_e32 v6, 0x100, v8
	v_add_u32_e32 v7, 0x200, v8
	v_lshrrev_b32_e32 v11, 31, v5
	v_ashrrev_i32_e32 v5, 1, v5
	v_mul_hi_i32 v12, v6, s0
	v_and_b32_e32 v9, 0xffffffe0, v9
	v_mul_hi_i32 v13, v7, s0
	v_add_u32_e32 v2, v5, v11
	v_lshrrev_b32_e32 v3, 31, v12
	v_ashrrev_i32_e32 v5, 1, v12
	s_movk_i32 s0, 0x68
	v_add_u32_e32 v125, s94, v9
	v_lshrrev_b32_e32 v9, 31, v13
	v_ashrrev_i32_e32 v11, 1, v13
	v_mul_lo_u32 v12, v2, 12
	v_mul_lo_u32 v2, v2, s0
	v_add_u32_e32 v3, v5, v3
	v_add_u32_e32 v5, v11, v9
	v_sub_u32_e32 v9, v8, v12
	v_lshlrev_b32_e32 v127, 1, v2
	v_mul_lo_u32 v2, v3, 12
	v_mul_lo_u32 v3, v3, s0
	v_lshlrev_b32_e32 v11, 3, v9
	v_lshlrev_b32_e32 v9, 4, v9
	v_sub_u32_e32 v2, v6, v2
	v_lshlrev_b32_e32 v128, 1, v3
	v_add3_u32 v3, s33, v127, v9
	v_lshlrev_b32_e32 v9, 3, v2
	v_lshlrev_b32_e32 v2, 4, v2
	v_add3_u32 v2, s33, v128, v2
	s_waitcnt lgkmcnt(0)
	s_barrier
	v_and_b32_e32 v4, 31, v8
	v_lshlrev_b32_e32 v10, 3, v121
	s_waitcnt vmcnt(0)
	ds_write_b128 v3, v[66:69]
	ds_write_b128 v2, v[70:73]
	v_mul_lo_u32 v2, v5, 12
	v_sub_u32_e32 v2, v7, v2
	v_mul_lo_u32 v5, v5, s0
	v_lshlrev_b32_e32 v3, 3, v2
	v_lshlrev_b32_e32 v129, 1, v5
	v_lshlrev_b32_e32 v2, 4, v2
	v_add3_u32 v2, s33, v129, v2
	ds_write_b128 v2, v[74:77]
	v_lshrrev_b32_e32 v2, 3, v8
	v_lshlrev_b32_e32 v5, 3, v8
	s_movk_i32 s0, 0x48
	v_and_b32_e32 v5, 56, v5
	v_mul_lo_u32 v2, v2, s0
	v_lshlrev_b32_e32 v130, 1, v2
	v_lshlrev_b32_e32 v131, 1, v5
	v_and_b32_e32 v217, 1, v215
	v_lshlrev_b32_e32 v217, 3, v217
	v_sub_u32_e32 v217, v131, v217
	v_add_u32_e32 v217, 0x3400, v217
	v_add3_u32 v2, s33, v130, v217
	ds_write2_b64 v2, v[78:79], v[80:81] offset1:2
	v_lshrrev_b32_e32 v2, 3, v6
	v_mul_lo_u32 v2, v2, s0
	v_lshlrev_b32_e32 v132, 1, v2
	v_add3_u32 v2, s33, v132, v217
	v_mov_b32_e32 v18, v1
	v_mov_b32_e32 v19, v1
	v_or_b32_e32 v126, v125, v4
	ds_write2_b64 v2, v[82:83], v[84:85] offset1:2
	v_mul_u32_u24_e32 v134, 0xd0, v4
	v_mul_u32_u24_e32 v136, 0x90, v4
	v_mov_b32_e32 v20, v1
	v_mov_b32_e32 v21, v1
	v_mov_b32_e32 v22, v1
	v_mov_b32_e32 v23, v1
	v_mov_b32_e32 v24, v1
	v_mov_b32_e32 v25, v1
	v_mov_b32_e32 v26, v1
	v_mov_b32_e32 v27, v1
	v_mov_b32_e32 v28, v1
	v_mov_b32_e32 v29, v1
	v_mov_b32_e32 v30, v1
	v_mov_b32_e32 v31, v1
	v_mov_b32_e32 v32, v1
	v_mov_b32_e32 v33, v1
	v_lshlrev_b32_e32 v137, 1, v10
	v_lshlrev_b32_e32 v138, 1, v11
	v_lshlrev_b32_e32 v139, 1, v9
	v_lshlrev_b32_e32 v140, 1, v3
	v_mov_b64_e32 v[2:3], v[18:19]
	s_mov_b32 s95, s49
	v_ashrrev_i32_e32 v111, 31, v110
	v_or_b32_e32 v133, 31, v125
	v_lshlrev_b32_e32 v123, 2, v121
	s_mov_b32 s16, 0
	v_mov_b32_e32 v135, 0
	v_mov_b32_e32 v122, 0xff800000
	s_mov_b32 s12, 0
	v_mov_b64_e32 v[4:5], v[20:21]
	v_mov_b64_e32 v[6:7], v[22:23]
	v_mov_b64_e32 v[8:9], v[24:25]
	v_mov_b64_e32 v[10:11], v[26:27]
	v_mov_b64_e32 v[12:13], v[28:29]
	v_mov_b64_e32 v[14:15], v[30:31]
	v_mov_b64_e32 v[16:17], v[32:33]
	v_add3_u32 v127, s33, v127, v138
	v_add3_u32 v128, s33, v128, v139
	v_add3_u32 v129, s33, v129, v140
	v_add3_u32 v130, s33, v130, v217
	v_add3_u32 v132, s33, v132, v217
	v_add_u32_e32 v138, 0x5900, v130
	v_add_u32_e32 v139, 0x5900, v132
	v_add3_u32 v216, s33, v134, v137
	v_lshlrev_b32_e32 v231, 2, v123
	v_add3_u32 v231, s33, v136, v231
	ds_write_b128 v127, v[176:179] offset:22784
	ds_write_b128 v128, v[180:183] offset:22784
	ds_write_b128 v129, v[184:187] offset:22784
	s_waitcnt lgkmcnt(0)
	s_barrier
	ds_read_b128 v[208:211], v216 offset:0
	ds_read_b128 v[232:235], v216 offset:6656
	ds_read_b128 v[236:239], v216 offset:32
	ds_read_b128 v[240:243], v216 offset:6688
	ds_read_b128 v[244:247], v216 offset:64
	ds_read_b128 v[248:251], v216 offset:6720
	s_waitcnt lgkmcnt(4)
	v_mfma_f32_32x32x16_bf16 v[50:65], v[208:211], v[86:89], 0
	v_mfma_f32_32x32x16_bf16 v[34:49], v[232:235], v[86:89], 0
	ds_read_b128 v[208:211], v216 offset:96
	ds_read_b128 v[232:235], v216 offset:6752
	s_waitcnt lgkmcnt(4)
	v_mfma_f32_32x32x16_bf16 v[50:65], v[236:239], v[90:93], v[50:65]
	v_mfma_f32_32x32x16_bf16 v[34:49], v[240:243], v[90:93], v[34:49]
	ds_read_b128 v[236:239], v216 offset:128
	ds_read_b128 v[240:243], v216 offset:6784
	s_waitcnt lgkmcnt(4)
	v_mfma_f32_32x32x16_bf16 v[50:65], v[244:247], v[94:97], v[50:65]
	v_mfma_f32_32x32x16_bf16 v[34:49], v[248:251], v[94:97], v[34:49]
	ds_read_b128 v[244:247], v216 offset:160
	ds_read_b128 v[248:251], v216 offset:6816
	s_waitcnt lgkmcnt(4)
	v_mfma_f32_32x32x16_bf16 v[50:65], v[208:211], v[98:101], v[50:65]
	v_mfma_f32_32x32x16_bf16 v[34:49], v[232:235], v[98:101], v[34:49]
	s_waitcnt lgkmcnt(2)
	v_mfma_f32_32x32x16_bf16 v[50:65], v[236:239], v[102:105], v[50:65]
	v_mfma_f32_32x32x16_bf16 v[34:49], v[240:243], v[102:105], v[34:49]
	s_waitcnt lgkmcnt(0)
	v_mfma_f32_32x32x16_bf16 v[50:65], v[244:247], v[106:109], v[50:65]
	v_mfma_f32_32x32x16_bf16 v[34:49], v[248:251], v[106:109], v[34:49]
	s_nop 7
	s_nop 3

; DI unsigned pk2(float a, float b) { f32x2 v = {a, b}; return __builtin_bit_cast(unsigned, __builtin_convertvector(v, bf2_t)); }
; DI float bflo(unsigned u) { return __uint_as_float(u << 16); }
; DI float bfhi(unsigned u) { return __uint_as_float(u & 0xffff0000u); }
; DI float xhalf_other(float x, int h) { auto r = __builtin_amdgcn_permlane32_swap(__float_as_uint(x), __float_as_uint(x), false, false); return h ? __uint_as_float(r[0]) : __uint_as_float(r[1]); }
;     ...
;     if (MODE != 1) {
;         const float lt = lsum + xhalf_other(lsum, h), inv = __builtin_amdgcn_rcpf(lt);
;         o0 *= inv; o1 *= inv;
;     }
;     bf16_t* yrow = yb + (size_t)(32 * w + r) * 1024 + 4 * h;
;     const bf16_t* grow = gt + (size_t)(32 * w + r) * 1024 + 4 * h;
;     u32x2 gv[2][4];
; #pragma unroll
;     for (int nt = 0; nt < 2; ++nt)
; #pragma unroll
;         for (int qd = 0; qd < 4; ++qd) gv[nt][qd] = *(const u32x2*)(grow + 32 * nt + 8 * qd);
; #pragma unroll
;     for (int nt = 0; nt < 2; ++nt)
; #pragma unroll
;         for (int qd = 0; qd < 4; ++qd) {
;             const u32x2 g = gv[nt][qd];
;             const f32x16& o = nt ? o1 : o0;
;             u32x2 v;
;             v.x = pk2(o[4 * qd] * bflo(g.x), o[4 * qd + 1] * bfhi(g.x));
;             v.y = pk2(o[4 * qd + 2] * bflo(g.y), o[4 * qd + 3] * bfhi(g.y));
;             *(u32x2*)(yrow + 32 * nt + 8 * qd) = v;
;         }
.LBB0_785:
	s_mov_b32 s57, s49
	s_lshl_b64 s[4:5], s[94:95], 11
	s_lshl_b64 s[6:7], s[56:57], 24
	s_or_b64 s[4:5], s[4:5], s[6:7]
	s_add_u32 s6, s61, s4
	s_addc_u32 s7, s70, s5
	s_add_u32 s4, s69, s4
	v_mov_b32_e32 v0, v135
	v_mov_b32_e32 v34, v135
	s_addc_u32 s5, s60, s5
	s_lshl_b32 s8, s79, 7
	v_permlane32_swap_b32_e32 v0, v34
	v_cmp_eq_u32_e32 vcc, 0, v121
	s_add_u32 s4, s4, s8
	s_addc_u32 s5, s5, 0
	v_cndmask_b32_e32 v0, v0, v34, vcc
	v_add_f32_e32 v0, v135, v0
	v_lshlrev_b64 v[42:43], 11, v[110:111]
	v_rcp_f32_e32 v44, v0
	v_lshl_add_u64 v[34:35], s[4:5], 0, v[42:43]
	v_lshlrev_b32_e32 v0, 1, v123
	v_lshl_add_u64 v[34:35], v[34:35], 0, v[0:1]
	global_load_dwordx2 v[46:47], v[34:35], off
	global_load_dwordx2 v[48:49], v[34:35], off offset:16
	global_load_dwordx2 v[50:51], v[34:35], off offset:32
	global_load_dwordx2 v[52:53], v[34:35], off offset:48
	global_load_dwordx2 v[40:41], v[34:35], off offset:64
	global_load_dwordx2 v[38:39], v[34:35], off offset:80
	global_load_dwordx2 v[36:37], v[34:35], off offset:96
	s_nop 0
	global_load_dwordx2 v[34:35], v[34:35], off offset:112
	s_add_u32 s6, s6, s8
	s_addc_u32 s7, s7, 0
	v_pk_mul_f32 v[20:21], v[20:21], v[44:45] op_sel_hi:[1,0]
	v_pk_mul_f32 v[18:19], v[18:19], v[44:45] op_sel_hi:[1,0]
	v_lshl_add_u64 v[42:43], s[6:7], 0, v[42:43]
	v_lshl_add_u64 v[42:43], v[42:43], 0, v[0:1]
	v_pk_mul_f32 v[24:25], v[24:25], v[44:45] op_sel_hi:[1,0]
	v_pk_mul_f32 v[22:23], v[22:23], v[44:45] op_sel_hi:[1,0]
	v_pk_mul_f32 v[28:29], v[28:29], v[44:45] op_sel_hi:[1,0]
	v_pk_mul_f32 v[26:27], v[26:27], v[44:45] op_sel_hi:[1,0]
	v_pk_mul_f32 v[32:33], v[32:33], v[44:45] op_sel_hi:[1,0]
	v_pk_mul_f32 v[30:31], v[30:31], v[44:45] op_sel_hi:[1,0]
	v_pk_mul_f32 v[16:17], v[16:17], v[44:45] op_sel_hi:[1,0]
	v_pk_mul_f32 v[14:15], v[14:15], v[44:45] op_sel_hi:[1,0]
	v_pk_mul_f32 v[12:13], v[12:13], v[44:45] op_sel_hi:[1,0]
	v_pk_mul_f32 v[10:11], v[10:11], v[44:45] op_sel_hi:[1,0]
	v_pk_mul_f32 v[8:9], v[8:9], v[44:45] op_sel_hi:[1,0]
	v_pk_mul_f32 v[6:7], v[6:7], v[44:45] op_sel_hi:[1,0]
	v_pk_mul_f32 v[4:5], v[4:5], v[44:45] op_sel_hi:[1,0]
	v_pk_mul_f32 v[2:3], v[2:3], v[44:45] op_sel_hi:[1,0]
	s_mov_b32 s95, 0x7fffffe0
	s_waitcnt vmcnt(0) lgkmcnt(0)
	v_lshlrev_b32_e32 v54, 16, v46
	v_and_b32_e32 v55, 0xffff0000, v46
	v_lshlrev_b32_e32 v46, 16, v47
	v_and_b32_e32 v47, 0xffff0000, v47
	v_pk_mul_f32 v[18:19], v[18:19], v[54:55]
	v_pk_mul_f32 v[20:21], v[20:21], v[46:47]
	v_cvt_pk_bf16_f32 v18, v18, v19
	v_cvt_pk_bf16_f32 v19, v20, v21
	global_store_dwordx2 v[42:43], v[18:19], off
	v_lshlrev_b32_e32 v18, 16, v48
	v_and_b32_e32 v19, 0xffff0000, v48
	v_lshlrev_b32_e32 v20, 16, v49
	v_and_b32_e32 v21, 0xffff0000, v49
	v_pk_mul_f32 v[18:19], v[22:23], v[18:19]
	v_pk_mul_f32 v[20:21], v[24:25], v[20:21]
	v_cvt_pk_bf16_f32 v18, v18, v19
	v_cvt_pk_bf16_f32 v19, v20, v21
	global_store_dwordx2 v[42:43], v[18:19], off offset:16
	v_lshlrev_b32_e32 v18, 16, v50
	v_and_b32_e32 v19, 0xffff0000, v50
	v_lshlrev_b32_e32 v20, 16, v51
	v_and_b32_e32 v21, 0xffff0000, v51
	v_pk_mul_f32 v[18:19], v[26:27], v[18:19]
	v_pk_mul_f32 v[20:21], v[28:29], v[20:21]
	v_cvt_pk_bf16_f32 v18, v18, v19
	v_cvt_pk_bf16_f32 v19, v20, v21
	global_store_dwordx2 v[42:43], v[18:19], off offset:32
	v_lshlrev_b32_e32 v18, 16, v52
	v_and_b32_e32 v19, 0xffff0000, v52
	v_lshlrev_b32_e32 v20, 16, v53
	v_and_b32_e32 v21, 0xffff0000, v53
	v_pk_mul_f32 v[18:19], v[30:31], v[18:19]
	v_pk_mul_f32 v[20:21], v[32:33], v[20:21]
	v_cvt_pk_bf16_f32 v18, v18, v19
	v_cvt_pk_bf16_f32 v19, v20, v21
	global_store_dwordx2 v[42:43], v[18:19], off offset:48

;     constexpr int KS = DQK + 8, NKS = DQK / 16, KCH = DQK / 8, NKL = 64 * KCH / 256;
;     const int tid = tid_op(), lane = tid & 63, w = tid >> 6, r = lane & 31, h = lane >> 5;
;     const int qidx = q0 + 32 * w + r;
;     bf16x8 qf[NKS];
; #pragma unroll
;     for (int s = 0; s < NKS; ++s) qf[s] = *(const bf16x8*)(Q + (size_t)(32 * w + r) * DQK + 16 * s + 8 * h);
;     float qn = 0.f;
;     if (MODE == 0 && DESC) {
; #pragma unroll
;         for (int s = 0; s < NKS; ++s)
; #pragma unroll
;             for (int j = 0; j < 8; ++j) { const float a = __uint_as_float(((unsigned)(unsigned short)qf[s][j]) << 16); qn += a * a; }
;         qn += xhalf_other(qn, h);
;         qn = sqrtf(qn) * kmax;
;     }
;     f32x16 o0, o1;
; #pragma unroll
;     for (int i = 0; i < 16; ++i) { o0[i] = 0.f; o1[i] = 0.f; }
;     float m = -INFINITY, lsum = 0.f, R = 1.f;
;     u32x4 rk[NKL], rv[2]; f32x4 rc = {0.f, 0.f, 0.f, 0.f};
;     const unsigned okk = (unsigned)(((tid / KCH) * DQK + (tid % KCH) * 8) * 2);
;     const unsigned ovv = (unsigned)(((tid >> 3) * ldv + (tid & 7) * 8) * 2), svv = (unsigned)(ldv * 64);
;     auto ld_tile = [&](int kt) {
;         const unsigned char* Kt = (const unsigned char*)(K + (size_t)(64 * kt) * DQK);
;         const unsigned char* Vt = (const unsigned char*)(VT + 64 * kt);
; #pragma unroll
;         for (int j = 0; j < NKL; ++j) rk[j] = *(const u32x4*)(Kt + (okk + j * 4096));
; #pragma unroll
;         for (int j = 0; j < 2; ++j) rv[j] = *(const u32x4*)(Vt + (ovv + j * svv));
;         if (cdec && tid < 16) rc = *(const f32x4*)(cdec + 64 * kt + 4 * tid);
;     };
;     auto st_tile = [&](int buf) {
;         bf16_t* sK = (bf16_t*)(smem + buf * ATT_BUF); bf16_t* sV = (bf16_t*)(smem + buf * ATT_BUF + 13312); float* sC = (float*)(smem + buf * ATT_BUF + 22528);
; #pragma unroll
;         for (int j = 0; j < NKL; ++j) { const int c = tid + 256 * j, row = c / KCH, kc = (c % KCH) * 8; *(u32x4*)(sK + row * KS + kc) = rk[j]; }
; #pragma unroll
;         for (int j = 0; j < 2; ++j) { const int c = tid + 256 * j, row = c >> 3, kc = (c & 7) * 8; *(u32x4*)(sV + row * LS + kc) = rv[j]; }
;         if (cdec && tid < 16) *(f32x4*)(sC + 4 * tid) = rc;
;     };
;     ld_tile(DESC ? ntiles - 1 : 0);
;     __syncthreads();
;     st_tile(0);
; #pragma unroll 1
;     for (int it = 0; it < ntiles; ++it) {
.LBB0_787:
	s_andn2_b64 vcc, exec, s[4:5]
	s_cbranch_vccnz .LBB0_710
	s_mov_b32 s95, s49
	s_lshl_b64 s[4:5], s[10:11], 20
	s_lshl_b64 s[6:7], s[94:95], 7
	v_readlane_b32 s1, v255, 0
	s_add_u32 s8, s1, s4
	v_readlane_b32 s1, v255, 1
	s_addc_u32 s9, s1, s5
	s_add_u32 s6, s8, s6
	s_addc_u32 s7, s9, s7
	v_readlane_b32 s1, v255, 2
	s_add_u32 s57, s1, s4
	v_readlane_b32 s1, v255, 3
	s_addc_u32 s86, s1, s5
	v_readlane_b32 s1, v255, 4
	s_add_u32 s88, s1, s4
	v_readlane_b32 s1, v255, 5
	s_mov_b32 s0, s97
	s_addc_u32 s97, s1, s5
	s_lshl_b32 s4, s22, 6
	s_or_b32 s48, s4, 64
	v_mov_b32_e32 v6, v215
	s_lshl_b64 s[4:5], s[48:49], 7
	s_add_u32 s4, s57, s4
	v_lshlrev_b32_e32 v0, 4, v6
	v_lshlrev_b32_e32 v2, 11, v6
	v_and_b32_e32 v3, 0x70, v0
	s_movk_i32 s1, 0xc000
	s_addc_u32 s5, s86, s5
	v_add_u32_e32 v102, 0x1000, v0
	v_mov_b32_e32 v103, v1
	v_and_or_b32 v98, v2, s1, v3
	v_lshl_add_u64 v[2:3], s[4:5], 0, v[0:1]
	v_lshl_add_u64 v[4:5], s[4:5], 0, v[102:103]
	s_lshl_b64 s[4:5], s[48:49], 1
	v_ashrrev_i32_e32 v7, 6, v6
	s_add_u32 s4, s88, s4
	v_and_b32_e32 v8, 31, v6
	v_lshlrev_b32_e32 v10, 5, v7
	s_addc_u32 s5, s97, s5
	v_mov_b32_e32 v99, v1
	v_or_b32_e32 v100, v10, v8
	global_load_dwordx4 v[66:69], v[2:3], off
	global_load_dwordx4 v[70:73], v[4:5], off
	v_lshl_add_u64 v[2:3], s[4:5], 0, v[98:99]
	v_add_u32_e32 v104, 0x80000, v98
	v_mov_b32_e32 v105, v1
	v_ashrrev_i32_e32 v101, 31, v100
	v_lshl_add_u64 v[4:5], s[4:5], 0, v[104:105]
	global_load_dwordx4 v[90:93], v[2:3], off
	global_load_dwordx4 v[94:97], v[4:5], off
	v_bfe_u32 v9, v6, 5, 1
	v_lshlrev_b64 v[2:3], 7, v[100:101]
	v_lshl_add_u64 v[2:3], s[6:7], 0, v[2:3]
	v_lshlrev_b32_e32 v4, 4, v9
	v_mov_b32_e32 v5, v1
	v_lshl_add_u64 v[2:3], v[2:3], 0, v[4:5]
	global_load_dwordx4 v[74:77], v[2:3], off
	global_load_dwordx4 v[78:81], v[2:3], off offset:32
	global_load_dwordx4 v[82:85], v[2:3], off offset:64
	global_load_dwordx4 v[86:89], v[2:3], off offset:96
	v_ashrrev_i32_e32 v3, 31, v6
	v_add_u32_e32 v5, 0x100, v6
	v_lshrrev_b32_e32 v11, 3, v6
	v_lshlrev_b32_e32 v12, 3, v6
	v_lshrrev_b32_e32 v3, 29, v3
	v_ashrrev_i32_e32 v14, 31, v5
	s_movk_i32 s1, 0x48
	v_and_b32_e32 v12, 56, v12
	v_mul_lo_u32 v11, v11, s1
	v_lshrrev_b32_e32 v15, 3, v5
	v_add_u32_e32 v107, s94, v10
	v_add_u32_e32 v3, v6, v3
	v_lshrrev_b32_e32 v10, 29, v14
	v_lshlrev_b32_e32 v125, 1, v11
	v_lshlrev_b32_e32 v126, 1, v12
	v_mul_lo_u32 v11, v15, s1
	v_lshrrev_b32_e32 v12, 3, v3
	v_and_b32_e32 v3, -8, v3
	v_add_u32_e32 v10, v5, v10
	v_and_b32_e32 v2, 63, v6
	v_lshlrev_b32_e32 v128, 1, v11
	v_sub_u32_e32 v3, v6, v3
	v_mul_lo_u32 v6, v12, s1
	v_lshrrev_b32_e32 v11, 3, v10
	v_and_b32_e32 v10, -8, v10
	v_lshlrev_b32_e32 v18, 3, v3
	v_lshlrev_b32_e32 v129, 1, v6
	v_lshlrev_b32_e32 v3, 4, v3
	v_sub_u32_e32 v5, v5, v10
	v_mul_lo_u32 v6, v11, s1
	v_add3_u32 v3, s33, v129, v3
	v_lshlrev_b32_e32 v19, 3, v5
	v_lshlrev_b32_e32 v130, 1, v6
	v_lshlrev_b32_e32 v5, 4, v5
	v_add3_u32 v14, s33, v125, v126
	v_add3_u32 v12, s33, v128, v126
	v_add3_u32 v5, s33, v130, v5
	s_waitcnt lgkmcnt(0)
	s_barrier
	v_lshlrev_b32_e32 v13, 3, v9
	v_cmp_gt_u32_e64 s[4:5], 32, v2
	s_waitcnt vmcnt(0)
	ds_write_b128 v3, v[66:69]
	ds_write_b128 v5, v[70:73]
	ds_write_b128 v14, v[90:93] offset:13312
	ds_write_b128 v12, v[94:97] offset:13312
	v_mul_u32_u24_e32 v3, 0x48, v8
	v_cmp_eq_u32_e64 s[6:7], 0, v2
	v_readlane_b32 s1, v255, 6
	v_lshlrev_b32_e32 v2, 1, v3
	v_mov_b32_e32 v16, v1
	v_mov_b32_e32 v17, v1
	v_or_b32_e32 v127, v107, v8
	v_lshlrev_b32_e32 v106, 2, v9
	v_lshl_add_u32 v132, v7, 2, s1
	v_add3_u32 v133, s33, v2, v4
	v_sub_u32_e32 v134, 0, v13
	v_mov_b32_e32 v2, v1
	v_mov_b32_e32 v3, v1
	v_mov_b32_e32 v4, v1
	v_mov_b32_e32 v5, v1
	v_mov_b32_e32 v6, v1
	v_mov_b32_e32 v7, v1
	v_mov_b32_e32 v8, v1
	v_mov_b32_e32 v9, v1
	v_mov_b32_e32 v10, v1
	v_mov_b32_e32 v11, v1
	v_mov_b32_e32 v12, v1
	v_mov_b32_e32 v13, v1
	v_mov_b32_e32 v14, v1
	v_mov_b32_e32 v15, v1
	v_lshlrev_b32_e32 v135, 1, v18
	v_lshlrev_b32_e32 v136, 1, v19
	v_mov_b64_e32 v[32:33], v[16:17]
	v_or_b32_e32 v131, 31, v107
	s_mov_b32 s48, 0
	v_mov_b32_e32 v109, 1.0
	s_mov_b32 s92, s94
	v_mov_b64_e32 v[30:31], v[14:15]
	v_mov_b64_e32 v[28:29], v[12:13]
	v_mov_b64_e32 v[26:27], v[10:11]
	v_mov_b64_e32 v[24:25], v[8:9]
	v_mov_b64_e32 v[22:23], v[6:7]
	v_mov_b64_e32 v[20:21], v[4:5]
	v_mov_b64_e32 v[18:19], v[2:3]
	s_mov_b32 s10, 0
	s_cmp_eq_u32 s66, s10
	s_mov_b64 s[8:9], -1
	s_cbranch_scc1 .LBB0_800
.LBB0_789:
	s_add_i32 s90, s10, 1
	s_cmp_lt_u32 s90, s66
	s_cselect_b64 s[44:45], -1, 0
	s_cmp_ge_u32 s90, s66
	s_cbranch_scc1 .LBB0_791
	s_ashr_i32 s93, s92, 31
	s_lshl_b64 s[8:9], s[92:93], 7
	s_add_u32 s8, s57, s8
	s_addc_u32 s9, s86, s9
	v_lshl_add_u64 v[34:35], s[8:9], 0, v[0:1]
	v_lshl_add_u64 v[36:37], s[8:9], 0, v[102:103]
	s_lshl_b64 s[8:9], s[92:93], 1
	s_add_u32 s8, s88, s8
	s_addc_u32 s9, s97, s9
	s_waitcnt vmcnt(0)
	global_load_dwordx4 v[66:69], v[34:35], off
	global_load_dwordx4 v[70:73], v[36:37], off
	v_lshl_add_u64 v[34:35], s[8:9], 0, v[98:99]
	v_lshl_add_u64 v[36:37], s[8:9], 0, v[104:105]
	global_load_dwordx4 v[90:93], v[34:35], off
	global_load_dwordx4 v[94:97], v[36:37], off

; DI void phase4(const Params& p, int l, unsigned char* smem) {
;     ...
;     auto ISS = [&](Stg4& R, int g) {
;         g = g < gmax ? g : gmax;
;         const int i = g / 24, v = g - i * 24, n = v / 6, jj = v - n * 6;
;         const int t = vb + i * G, xcd = t & 7, j = t >> 3, m0 = (32 * xcd + (j >> 3)) * 128, c0 = (j & 7) * 128;
;         if (jj < 2) stg4_issue(R, MR + (size_t)m0 * 128 + jj * 64, o128, s128, WMU + (size_t)(n * 1024 + c0) * 128 + jj * 64, o128, s128);
;         else stg4_issue(R, YB + (size_t)m0 * 1024 + n * 256 + (jj - 2) * 64, o1024, s1024, WBR + (size_t)c0 * 1024 + n * 256 + (jj - 2) * 64, o1024, s1024);
;     };
;     Stg4 R0, R1;
;     ISS(R0, 0); ISS(R1, 1);
;     stg4_commit(R0, sA, sB, srow, skc);
;     ISS(R0, 2);
.LBB0_855:
	v_lshl_add_u64 v[10:11], s[6:7], 0, v[0:1]
	v_lshl_add_u64 v[14:15], s[8:9], 0, v[0:1]
	global_load_dwordx4 v[2:5], v[2:3], off
	s_nop 0
	global_load_dwordx4 v[6:9], v[6:7], off
	v_readlane_b32 s0, v254, 1
	global_load_dwordx4 v[10:13], v[10:11], off
	v_readlane_b32 s1, v254, 2
	global_load_dwordx4 v[14:17], v[14:15], off
	s_and_b64 vcc, exec, s[0:1]
	s_cbranch_vccz .LBB0_857
	v_readlane_b32 s0, v254, 3
	v_readlane_b32 s1, v254, 4
	s_add_u32 s6, s3, s0
	s_addc_u32 s7, s16, s1
	v_readlane_b32 s0, v254, 30
	v_readlane_b32 s1, v254, 31
	s_add_u32 s6, s6, s0
	s_addc_u32 s7, s7, s1
	v_readlane_b32 s10, v254, 32
	v_readlane_b32 s11, v254, 33
	s_add_u32 s6, s6, s10
	s_addc_u32 s7, s7, s11
	v_readlane_b32 s8, v254, 34
	s_add_u32 s8, s21, s8
	s_addc_u32 s9, s22, 0
	s_add_u32 s8, s8, s0
	s_addc_u32 s9, s9, s1
	s_add_u32 s8, s8, s10
	s_addc_u32 s9, s9, s11
	v_mov_b32_e32 v99, v1
	v_lshl_add_u64 v[18:19], s[6:7], 0, v[98:99]
	v_lshl_add_u64 v[20:21], s[8:9], 0, v[98:99]
	v_add_u32_e32 v0, 0x20000, v98
	s_cbranch_execz .LBB0_858
	s_branch .LBB0_859

; DI void phase4(const Params& p, int l, unsigned char* smem) {
;     ...
;     auto ISS = [&](Stg4& R, int g) {
;         g = g < gmax ? g : gmax;
;         const int i = g / 24, v = g - i * 24, n = v / 6, jj = v - n * 6;
;         const int t = vb + i * G, xcd = t & 7, j = t >> 3, m0 = (32 * xcd + (j >> 3)) * 128, c0 = (j & 7) * 128;
;         if (jj < 2) stg4_issue(R, MR + (size_t)m0 * 128 + jj * 64, o128, s128, WMU + (size_t)(n * 1024 + c0) * 128 + jj * 64, o128, s128);
;         else stg4_issue(R, YB + (size_t)m0 * 1024 + n * 256 + (jj - 2) * 64, o1024, s1024, WBR + (size_t)c0 * 1024 + n * 256 + (jj - 2) * 64, o1024, s1024);
;     };
;     Stg4 R0, R1;
;     ISS(R0, 0); ISS(R1, 1);
;     stg4_commit(R0, sA, sB, srow, skc);
;     ISS(R0, 2);
.LBB0_859:
	global_load_dwordx4 v[66:69], v[18:19], off
	global_load_dwordx4 v[70:73], v[20:21], off
	v_lshl_add_u64 v[18:19], s[6:7], 0, v[0:1]
	global_load_dwordx4 v[74:77], v[18:19], off
	v_lshl_add_u64 v[18:19], s[8:9], 0, v[0:1]
	global_load_dwordx4 v[78:81], v[18:19], off
	v_readlane_b32 s0, v254, 9
	v_mul_lo_u32 v0, v23, s92
	v_readlane_b32 s1, v254, 10
	v_lshl_add_u32 v140, v24, 1, v0
	s_and_b64 vcc, exec, s[0:1]
	s_waitcnt vmcnt(0) lgkmcnt(0)
	ds_write_b128 v140, v[2:5]
	ds_write_b128 v140, v[6:9] offset:36864
	ds_write_b128 v140, v[10:13] offset:9216
	ds_write_b128 v140, v[14:17] offset:46080
	s_cbranch_vccz .LBB0_861
	v_readlane_b32 s0, v254, 11
	v_readlane_b32 s1, v254, 12
	s_add_u32 s6, s3, s0
	s_addc_u32 s7, s16, s1
	v_readlane_b32 s0, v254, 37
	v_readlane_b32 s1, v254, 38
	s_add_u32 s6, s6, s0
	s_addc_u32 s7, s7, s1
	v_readlane_b32 s10, v254, 39
	v_readlane_b32 s11, v254, 40
	s_add_u32 s6, s6, s10
	s_addc_u32 s7, s7, s11
	v_readlane_b32 s8, v254, 41
	s_add_u32 s8, s21, s8
	s_addc_u32 s9, s22, 0
	s_add_u32 s8, s8, s0
	s_addc_u32 s9, s9, s1
	s_add_u32 s8, s8, s10
	s_addc_u32 s9, s9, s11
	v_mov_b32_e32 v99, v1
	v_lshl_add_u64 v[2:3], s[6:7], 0, v[98:99]
	v_lshl_add_u64 v[4:5], s[8:9], 0, v[98:99]
	v_add_u32_e32 v0, 0x20000, v98
	s_cbranch_execz .LBB0_862
	s_branch .LBB0_863

; DI bf16_t tobf(float a) { return (bf16_t)(pk2(a, 0.f) & 0xffffu); }
; template <typename T> DI T* opaque(T* p) { asm volatile("" : "+v"(p) : : "memory"); return p; }
; DI void phase4(const Params& p, int l, unsigned char* smem) {
;     ...
;     auto ISS = [&](Stg4& R, int g) {
;         g = g < gmax ? g : gmax;
;         const int i = g / 24, v = g - i * 24, n = v / 6, jj = v - n * 6;
;         const int t = vb + i * G, xcd = t & 7, j = t >> 3, m0 = (32 * xcd + (j >> 3)) * 128, c0 = (j & 7) * 128;
;         if (jj < 2) stg4_issue(R, MR + (size_t)m0 * 128 + jj * 64, o128, s128, WMU + (size_t)(n * 1024 + c0) * 128 + jj * 64, o128, s128);
;         else stg4_issue(R, YB + (size_t)m0 * 1024 + n * 256 + (jj - 2) * 64, o1024, s1024, WBR + (size_t)c0 * 1024 + n * 256 + (jj - 2) * 64, o1024, s1024);
;     };
;     Stg4 R0, R1;
;     ISS(R0, 0); ISS(R1, 1);
;     ...
;         bf16_t* pb = (bf16_t*)(ws + O_XB) + (size_t)(m0 + 64 * wr + 4 * h) * 1024 + c0 + 32 * wc + r;
; #pragma unroll
;         for (int mi = 0; mi < 2; ++mi)
; #pragma unroll
;             for (int qd = 0; qd < 4; ++qd) {
;                 bf16_t* q = opaque(pb + (size_t)(32 * mi + 8 * qd) * 1024);
; #pragma unroll
;                 for (int e = 0; e < 4; ++e) q[e * 1024] = tobf(mg[mi][4 * qd + e]);
;             }
;         __builtin_amdgcn_s_waitcnt(0x0F70);
;     }
.LBB0_863:
	v_readlane_b32 s0, v254, 18
	v_readlane_b32 s1, v254, 19
	s_andn2_b64 vcc, exec, s[0:1]
	s_cbranch_vccnz .LBB0_892
	v_lshl_add_u64 v[6:7], s[8:9], 0, v[0:1]
	global_load_dwordx4 v[82:85], v[6:7], off
	v_lshl_add_u64 v[6:7], s[6:7], 0, v[0:1]
	global_load_dwordx4 v[94:97], v[6:7], off
	global_load_dwordx4 v[86:89], v[4:5], off
	global_load_dwordx4 v[90:93], v[2:3], off
	s_ashr_i32 s6, s12, 2
	v_and_b32_e32 v0, 31, v22
	v_bfe_u32 v3, v22, 5, 1
	s_and_b32 s8, s6, 0xffffffc0
	v_or_b32_e32 v4, s8, v0
	v_lshlrev_b32_e32 v2, 4, v3
	v_mad_u64_u32 v[102:103], s[6:7], v4, s92, v[2:3]
	s_lshr_b32 s6, s12, 1
	s_and_b32 s6, s6, 0x60
	v_or_b32_e32 v4, s6, v0
	v_mul_u32_u24_e32 v4, 0x48, v4
	s_add_u32 s4, s4, 0x3880000
	s_mov_b32 s23, 4
	v_lshl_add_u32 v103, v4, 1, v2
	v_mov_b32_e32 v99, v1
	v_mov_b32_e32 v101, v1
	s_addc_u32 s5, s5, 0
	v_lshl_or_b32 v141, v3, 2, s8
	s_mov_b32 s24, 0
	s_mov_b32 s25, 5
	s_mov_b32 s26, 3
	s_lshl_b32 s6, s6, 1
	v_lshlrev_b32_e32 v104, 1, v0
	s_mov_b32 s27, 0
	v_readlane_b32 s0, v254, 17
	s_branch .LBB0_866
.LBB0_865:
	s_mul_i32 s7, s27, s78
	s_add_i32 s7, s7, s2
	s_lshl_b32 s8, s7, 5
	s_lshr_b32 s7, s7, 6
	s_and_b32 s9, s8, 0xe0
	s_add_i32 s9, s9, s7
	v_lshl_add_u32 v2, s9, 7, v141
	v_ashrrev_i32_e32 v3, 31, v2
	v_lshlrev_b64 v[2:3], 11, v[2:3]
	v_lshl_add_u64 v[2:3], s[4:5], 0, v[2:3]
	s_and_b32 s48, s8, 0x700
	v_lshl_add_u64 v[2:3], v[2:3], 0, s[48:49]
	s_mov_b32 s7, s49
	v_lshl_add_u64 v[2:3], v[2:3], 0, s[6:7]
	v_mov_b32_e32 v105, v1
	v_lshl_add_u64 v[2:3], v[2:3], 0, v[104:105]
	v_mov_b64_e32 v[4:5], v[2:3]
	v_cvt_pk_bf16_f32 v0, v136, s0
	global_store_short v[4:5], v0, off
	v_cvt_pk_bf16_f32 v0, v137, s0
	global_store_short v[4:5], v0, off offset:2048
	v_add_co_u32_e32 v4, vcc, s90, v4
	v_cvt_pk_bf16_f32 v0, v134, s0
	s_nop 0
	v_addc_co_u32_e32 v5, vcc, 0, v5, vcc
	global_store_short v[4:5], v0, off
	v_cvt_pk_bf16_f32 v0, v135, s0
	s_mov_b64 s[8:9], 0x4000
	global_store_short v[4:5], v0, off offset:2048
	v_lshl_add_u64 v[4:5], v[2:3], 0, s[8:9]
	v_cvt_pk_bf16_f32 v0, v132, s0
	global_store_short v[4:5], v0, off
	v_cvt_pk_bf16_f32 v0, v133, s0
	global_store_short v[4:5], v0, off offset:2048
	v_add_co_u32_e32 v4, vcc, s90, v4
	v_cvt_pk_bf16_f32 v0, v130, s0
	s_nop 0
	v_addc_co_u32_e32 v5, vcc, 0, v5, vcc
	global_store_short v[4:5], v0, off
	v_cvt_pk_bf16_f32 v0, v131, s0
	s_mov_b64 s[8:9], 0x8000
	global_store_short v[4:5], v0, off offset:2048
	v_lshl_add_u64 v[4:5], v[2:3], 0, s[8:9]
	v_cvt_pk_bf16_f32 v0, v128, s0
	global_store_short v[4:5], v0, off
	v_cvt_pk_bf16_f32 v0, v129, s0
	global_store_short v[4:5], v0, off offset:2048
	v_add_co_u32_e32 v4, vcc, s90, v4
	v_cvt_pk_bf16_f32 v0, v126, s0
	s_nop 0
	v_addc_co_u32_e32 v5, vcc, 0, v5, vcc
	global_store_short v[4:5], v0, off
	v_cvt_pk_bf16_f32 v0, v127, s0
	s_mov_b64 s[8:9], 0xc000
	global_store_short v[4:5], v0, off offset:2048
	v_lshl_add_u64 v[4:5], v[2:3], 0, s[8:9]
	v_cvt_pk_bf16_f32 v0, v124, s0
	global_store_short v[4:5], v0, off
	v_cvt_pk_bf16_f32 v0, v125, s0
	global_store_short v[4:5], v0, off offset:2048
	v_add_co_u32_e32 v4, vcc, s90, v4
	v_cvt_pk_bf16_f32 v0, v122, s0
	s_nop 0
	v_addc_co_u32_e32 v5, vcc, 0, v5, vcc
	global_store_short v[4:5], v0, off
	v_cvt_pk_bf16_f32 v0, v123, s0
	s_mov_b64 s[8:9], 0x10000
	global_store_short v[4:5], v0, off offset:2048
	v_lshl_add_u64 v[4:5], v[2:3], 0, s[8:9]
	v_cvt_pk_bf16_f32 v0, v120, s0
	global_store_short v[4:5], v0, off
	v_cvt_pk_bf16_f32 v0, v121, s0
	global_store_short v[4:5], v0, off offset:2048
	v_add_co_u32_e32 v4, vcc, s90, v4
	v_cvt_pk_bf16_f32 v0, v118, s0
	s_nop 0
	v_addc_co_u32_e32 v5, vcc, 0, v5, vcc
	global_store_short v[4:5], v0, off
	v_cvt_pk_bf16_f32 v0, v119, s0
	s_mov_b64 s[8:9], 0x14000
	global_store_short v[4:5], v0, off offset:2048
	v_lshl_add_u64 v[4:5], v[2:3], 0, s[8:9]
	v_cvt_pk_bf16_f32 v0, v116, s0
	global_store_short v[4:5], v0, off
	v_cvt_pk_bf16_f32 v0, v117, s0
	global_store_short v[4:5], v0, off offset:2048
	v_add_co_u32_e32 v4, vcc, s90, v4
	v_cvt_pk_bf16_f32 v0, v114, s0
	s_nop 0
	v_addc_co_u32_e32 v5, vcc, 0, v5, vcc
	global_store_short v[4:5], v0, off
	v_cvt_pk_bf16_f32 v0, v115, s0
	s_mov_b64 s[8:9], 0x18000
	global_store_short v[4:5], v0, off offset:2048
	v_lshl_add_u64 v[4:5], v[2:3], 0, s[8:9]
	v_cvt_pk_bf16_f32 v0, v112, s0
	global_store_short v[4:5], v0, off
	v_cvt_pk_bf16_f32 v0, v113, s0
	global_store_short v[4:5], v0, off offset:2048
	v_add_co_u32_e32 v4, vcc, s90, v4
	v_cvt_pk_bf16_f32 v0, v110, s0
	s_nop 0
	v_addc_co_u32_e32 v5, vcc, 0, v5, vcc
	global_store_short v[4:5], v0, off
	v_cvt_pk_bf16_f32 v0, v111, s0
	s_mov_b64 s[8:9], 0x1c000
	global_store_short v[4:5], v0, off offset:2048
	v_lshl_add_u64 v[2:3], v[2:3], 0, s[8:9]
	v_cvt_pk_bf16_f32 v0, v108, s0
	global_store_short v[2:3], v0, off
	v_cvt_pk_bf16_f32 v0, v109, s0
	global_store_short v[2:3], v0, off offset:2048
	v_add_co_u32_e32 v2, vcc, 0x1000, v2
	v_cvt_pk_bf16_f32 v0, v106, s0
	s_nop 0
	v_addc_co_u32_e32 v3, vcc, 0, v3, vcc
	s_add_i32 s27, s27, 1
	s_add_i32 s24, s24, 24
	s_add_i32 s25, s25, 24
	s_add_i32 s23, s23, 24
	s_add_i32 s26, s26, 24
	global_store_short v[2:3], v0, off
	v_cvt_pk_bf16_f32 v0, v107, s0
	s_cmp_eq_u32 s27, s0
	global_store_short v[2:3], v0, off offset:2048
	s_waitcnt vmcnt(0)
	s_cbranch_scc1 .LBB0_892

; DI float fexp2(float x) { return __builtin_amdgcn_exp2f(x); }
; DI void phase4(const Params& p, int l, unsigned char* smem) {
;     ...
;             __syncthreads(); mma21(g, sA, sB, wr, wc, r, h); stg4_commit(R1, sA + TILE_E, sB + TILE_E, srow, skc); ISS(R1, g0 + 3);
;             __syncthreads(); mma21(g, sA + TILE_E, sB + TILE_E, wr, wc, r, h); stg4_commit(R0, sA, sB, srow, skc); ISS(R0, g0 + 4);
; #pragma unroll
;             for (int mi = 0; mi < 2; ++mi)
; #pragma unroll
;                 for (int i = 0; i < 16; ++i) g[mi][i] = __builtin_amdgcn_rcpf(1.f + fexp2(-g[mi][i] * LOG2E));
;             __syncthreads(); mma21(y, sA, sB, wr, wc, r, h); stg4_commit(R1, sA + TILE_E, sB + TILE_E, srow, skc); ISS(R1, g0 + 5);
;             __syncthreads(); mma21(y, sA + TILE_E, sB + TILE_E, wr, wc, r, h); stg4_commit(R0, sA, sB, srow, skc); ISS(R0, g0 + 6);
;             __syncthreads(); mma21(y, sA, sB, wr, wc, r, h); stg4_commit(R1, sA + TILE_E, sB + TILE_E, srow, skc); ISS(R1, g0 + 7);
;             __syncthreads(); mma21(y, sA + TILE_E, sB + TILE_E, wr, wc, r, h); stg4_commit(R0, sA, sB, srow, skc); ISS(R0, g0 + 8);
; #pragma unroll
;             for (int mi = 0; mi < 2; ++mi)
; #pragma unroll
;                 for (int i = 0; i < 16; ++i) mg[mi][i] += g[mi][i] * y[mi][i];
.LBB0_867:
	global_load_dwordx4 v[90:93], v[82:83], off
	global_load_dwordx4 v[86:89], v[84:85], off
	v_lshl_add_u64 v[82:83], s[8:9], 0, v[0:1]
	global_load_dwordx4 v[94:97], v[82:83], off
	v_lshl_add_u64 v[82:83], s[10:11], 0, v[0:1]
	global_load_dwordx4 v[82:85], v[82:83], off
	v_mul_f32_e32 v50, 0xbfb8aa3b, v50
	v_mul_f32_e32 v51, 0xbfb8aa3b, v51
	v_mul_f32_e32 v52, 0xbfb8aa3b, v52
	v_mul_f32_e32 v53, 0xbfb8aa3b, v53
	v_mul_f32_e32 v54, 0xbfb8aa3b, v54
	v_mul_f32_e32 v55, 0xbfb8aa3b, v55
	v_mul_f32_e32 v56, 0xbfb8aa3b, v56
	v_mul_f32_e32 v57, 0xbfb8aa3b, v57
	v_mul_f32_e32 v58, 0xbfb8aa3b, v58
	v_mul_f32_e32 v59, 0xbfb8aa3b, v59
	v_mul_f32_e32 v60, 0xbfb8aa3b, v60
	v_mul_f32_e32 v61, 0xbfb8aa3b, v61
	v_mul_f32_e32 v62, 0xbfb8aa3b, v62
	v_mul_f32_e32 v63, 0xbfb8aa3b, v63
	v_mul_f32_e32 v64, 0xbfb8aa3b, v64
	v_mul_f32_e32 v65, 0xbfb8aa3b, v65
	v_mul_f32_e32 v18, 0xbfb8aa3b, v18
	v_mul_f32_e32 v19, 0xbfb8aa3b, v19
	v_mul_f32_e32 v20, 0xbfb8aa3b, v20
	v_mul_f32_e32 v21, 0xbfb8aa3b, v21
	v_mul_f32_e32 v22, 0xbfb8aa3b, v22
	v_mul_f32_e32 v23, 0xbfb8aa3b, v23
	v_mul_f32_e32 v24, 0xbfb8aa3b, v24
	v_mul_f32_e32 v25, 0xbfb8aa3b, v25
	v_mul_f32_e32 v26, 0xbfb8aa3b, v26
	v_mul_f32_e32 v27, 0xbfb8aa3b, v27
	v_mul_f32_e32 v28, 0xbfb8aa3b, v28
	v_mul_f32_e32 v29, 0xbfb8aa3b, v29
	v_mul_f32_e32 v30, 0xbfb8aa3b, v30
	v_mul_f32_e32 v31, 0xbfb8aa3b, v31
	v_mul_f32_e32 v32, 0xbfb8aa3b, v32
	v_mul_f32_e32 v33, 0xbfb8aa3b, v33
	v_exp_f32_e32 v50, v50
	v_exp_f32_e32 v51, v51
	v_exp_f32_e32 v52, v52
	v_exp_f32_e32 v53, v53
	v_exp_f32_e32 v54, v54
	v_exp_f32_e32 v55, v55
	v_exp_f32_e32 v56, v56
	v_exp_f32_e32 v57, v57
	v_exp_f32_e32 v58, v58
	v_exp_f32_e32 v59, v59
	v_exp_f32_e32 v60, v60
	v_exp_f32_e32 v61, v61
	v_exp_f32_e32 v62, v62
	v_exp_f32_e32 v63, v63
	v_exp_f32_e32 v64, v64
	v_exp_f32_e32 v65, v65
	v_exp_f32_e32 v18, v18
	v_exp_f32_e32 v19, v19
	v_exp_f32_e32 v20, v20
	v_exp_f32_e32 v21, v21
	v_exp_f32_e32 v22, v22
	v_exp_f32_e32 v23, v23
	v_exp_f32_e32 v24, v24
	v_exp_f32_e32 v25, v25
	v_exp_f32_e32 v26, v26
	v_exp_f32_e32 v27, v27
	v_exp_f32_e32 v28, v28
	v_exp_f32_e32 v29, v29
	v_exp_f32_e32 v30, v30
	v_exp_f32_e32 v31, v31
	v_exp_f32_e32 v32, v32
	v_exp_f32_e32 v33, v33
	v_add_f32_e32 v50, 1.0, v50
	v_add_f32_e32 v51, 1.0, v51
	v_add_f32_e32 v52, 1.0, v52
	v_add_f32_e32 v53, 1.0, v53
	v_add_f32_e32 v54, 1.0, v54
	v_add_f32_e32 v55, 1.0, v55
	v_add_f32_e32 v56, 1.0, v56
	v_add_f32_e32 v57, 1.0, v57
	v_add_f32_e32 v58, 1.0, v58
	v_add_f32_e32 v59, 1.0, v59
	v_add_f32_e32 v60, 1.0, v60
	v_add_f32_e32 v61, 1.0, v61
	v_add_f32_e32 v62, 1.0, v62
	v_add_f32_e32 v63, 1.0, v63
	v_add_f32_e32 v64, 1.0, v64
	v_add_f32_e32 v65, 1.0, v65
	v_add_f32_e32 v18, 1.0, v18
	v_add_f32_e32 v19, 1.0, v19
	v_add_f32_e32 v20, 1.0, v20
	v_add_f32_e32 v21, 1.0, v21
	v_add_f32_e32 v22, 1.0, v22
	v_add_f32_e32 v23, 1.0, v23
	v_add_f32_e32 v24, 1.0, v24
	v_add_f32_e32 v25, 1.0, v25
	v_add_f32_e32 v26, 1.0, v26
	v_add_f32_e32 v27, 1.0, v27
	v_add_f32_e32 v28, 1.0, v28
	v_add_f32_e32 v29, 1.0, v29
	v_add_f32_e32 v30, 1.0, v30
	v_add_f32_e32 v31, 1.0, v31
	v_add_f32_e32 v32, 1.0, v32
	v_add_f32_e32 v33, 1.0, v33
	v_rcp_f32_e32 v50, v50
	v_rcp_f32_e32 v51, v51
	v_rcp_f32_e32 v52, v52
	v_rcp_f32_e32 v53, v53
	v_rcp_f32_e32 v54, v54
	v_rcp_f32_e32 v55, v55
	v_rcp_f32_e32 v56, v56
	v_rcp_f32_e32 v57, v57
	v_rcp_f32_e32 v58, v58
	v_rcp_f32_e32 v59, v59
	v_rcp_f32_e32 v60, v60
	v_rcp_f32_e32 v61, v61
	v_rcp_f32_e32 v62, v62
	v_rcp_f32_e32 v63, v63
	v_rcp_f32_e32 v64, v64
	v_rcp_f32_e32 v65, v65
	v_rcp_f32_e32 v18, v18
	v_rcp_f32_e32 v19, v19
	v_rcp_f32_e32 v20, v20
	v_rcp_f32_e32 v21, v21
	v_rcp_f32_e32 v22, v22
	v_rcp_f32_e32 v23, v23
	v_rcp_f32_e32 v24, v24
	v_rcp_f32_e32 v25, v25
	v_rcp_f32_e32 v26, v26
	v_rcp_f32_e32 v27, v27
	v_rcp_f32_e32 v28, v28
	v_rcp_f32_e32 v29, v29
	v_rcp_f32_e32 v30, v30
	v_rcp_f32_e32 v31, v31
	v_rcp_f32_e32 v32, v32
	v_rcp_f32_e32 v33, v33
	s_add_i32 s30, s30, 6
	s_add_i32 s29, s29, 6
	s_add_i32 s28, s28, 6
	s_add_i32 s7, s7, 6
	v_pk_fma_f32 v[136:137], v[50:51], v[34:35], v[136:137]
	v_pk_fma_f32 v[134:135], v[52:53], v[36:37], v[134:135]
	v_pk_fma_f32 v[132:133], v[54:55], v[38:39], v[132:133]
	v_pk_fma_f32 v[130:131], v[56:57], v[40:41], v[130:131]
	v_pk_fma_f32 v[128:129], v[58:59], v[42:43], v[128:129]
	v_pk_fma_f32 v[126:127], v[60:61], v[44:45], v[126:127]
	v_pk_fma_f32 v[124:125], v[62:63], v[46:47], v[124:125]
	v_pk_fma_f32 v[122:123], v[64:65], v[48:49], v[122:123]
	v_pk_fma_f32 v[120:121], v[18:19], v[2:3], v[120:121]
	v_pk_fma_f32 v[118:119], v[20:21], v[4:5], v[118:119]
	v_pk_fma_f32 v[116:117], v[22:23], v[6:7], v[116:117]
	v_pk_fma_f32 v[114:115], v[24:25], v[8:9], v[114:115]
	v_pk_fma_f32 v[112:113], v[26:27], v[10:11], v[112:113]
	v_pk_fma_f32 v[110:111], v[28:29], v[12:13], v[110:111]
	v_pk_fma_f32 v[108:109], v[30:31], v[14:15], v[108:109]
	v_pk_fma_f32 v[106:107], v[32:33], v[16:17], v[106:107]
	s_cmp_eq_u32 s30, 24
	s_cbranch_scc1 .LBB0_865

; #define MFMA32(a, b, c) __builtin_amdgcn_mfma_f32_32x32x16_bf16((a), (b), (c), 0, 0, 0)
; DI float fexp2(float x) { return __builtin_amdgcn_exp2f(x); }
; DI void mma21(f32x16 (&acc)[2], const bf16_t* sA, const bf16_t* sB, int wr, int wc, int r, int h) {
;     const bf16_t* a = sA + (wr * 64 + r) * LS + h * 8;
;     const bf16_t* b = sB + (wc * 32 + r) * LS + h * 8;
; #pragma unroll
;     for (int s = 0; s < 4; ++s) {
;         const bf16x8 a0 = *(const bf16x8*)(a + s * 16), a1 = *(const bf16x8*)(a + 32 * LS + s * 16);
;         const bf16x8 b0 = *(const bf16x8*)(b + s * 16);
;         acc[0] = MFMA32(a0, b0, acc[0]);
;         acc[1] = MFMA32(a1, b0, acc[1]);
;     }
; DI void phase4(const Params& p, int l, unsigned char* smem) {
;     ...
;             __syncthreads(); mma21(g, sA, sB, wr, wc, r, h); stg4_commit(R1, sA + TILE_E, sB + TILE_E, srow, skc); ISS(R1, g0 + 3);
;             __syncthreads(); mma21(g, sA + TILE_E, sB + TILE_E, wr, wc, r, h); stg4_commit(R0, sA, sB, srow, skc); ISS(R0, g0 + 4);
; #pragma unroll
;             for (int mi = 0; mi < 2; ++mi)
; #pragma unroll
;                 for (int i = 0; i < 16; ++i) g[mi][i] = __builtin_amdgcn_rcpf(1.f + fexp2(-g[mi][i] * LOG2E));
;             __syncthreads(); mma21(y, sA, sB, wr, wc, r, h); stg4_commit(R1, sA + TILE_E, sB + TILE_E, srow, skc); ISS(R1, g0 + 5);
;             __syncthreads(); mma21(y, sA + TILE_E, sB + TILE_E, wr, wc, r, h); stg4_commit(R0, sA, sB, srow, skc); ISS(R0, g0 + 6);
;             __syncthreads(); mma21(y, sA, sB, wr, wc, r, h); stg4_commit(R1, sA + TILE_E, sB + TILE_E, srow, skc); ISS(R1, g0 + 7);
;             __syncthreads(); mma21(y, sA + TILE_E, sB + TILE_E, wr, wc, r, h); stg4_commit(R0, sA, sB, srow, skc); ISS(R0, g0 + 8);
.LBB0_872:
	global_load_dwordx4 v[66:69], v[2:3], off
	global_load_dwordx4 v[70:73], v[4:5], off
	v_lshl_add_u64 v[2:3], s[8:9], 0, v[0:1]
	global_load_dwordx4 v[74:77], v[2:3], off
	v_lshl_add_u64 v[2:3], s[12:13], 0, v[0:1]
	global_load_dwordx4 v[78:81], v[2:3], off
	s_waitcnt lgkmcnt(0)
	s_barrier
	ds_read_b128 v[2:5], v102 offset:23040
	ds_read_b128 v[6:9], v102 offset:18432
	ds_read_b128 v[10:13], v102 offset:18464
	ds_read_b128 v[14:17], v103 offset:55296
	ds_read_b128 v[34:37], v103 offset:55328
	s_waitcnt lgkmcnt(0)
	v_mfma_f32_32x32x16_bf16 v[18:33], v[2:5], v[14:17], v[18:33]
	ds_read_b128 v[2:5], v102 offset:23072
	s_mul_hi_u32 s10, s28, 0xaaaaaaab
	s_lshr_b32 s10, s10, 4
	s_mul_i32 s10, s10, 24
	s_sub_i32 s9, s31, s10
	s_add_i32 s8, s31, 4
	s_add_i32 s35, s9, 4
	v_mfma_f32_32x32x16_bf16 v[50:65], v[6:9], v[14:17], v[50:65]
	s_mul_hi_u32 s8, s8, 0xaaaaaaab
	s_mul_hi_i32 s34, s35, 0x2aaaaaab
	s_lshr_b32 s8, s8, 4
	s_lshr_b32 s9, s34, 31
	s_add_i32 s34, s34, s9
	s_mul_i32 s8, s8, s78
	s_mul_i32 s9, s34, -6
	v_mfma_f32_32x32x16_bf16 v[50:65], v[10:13], v[34:37], v[50:65]
	s_add_i32 s8, s8, s2
	s_add_i32 s35, s35, s9
	s_lshl_b32 s9, s8, 5
	s_and_b32 s9, s9, 0xe0
	s_lshr_b32 s10, s8, 6
	s_add_i32 s9, s9, s10
	s_lshl_b32 s12, s9, 7
	s_waitcnt lgkmcnt(0)
	v_mfma_f32_32x32x16_bf16 v[18:33], v[2:5], v[34:37], v[18:33]
	ds_read_b128 v[2:5], v102 offset:18496
	ds_read_b128 v[6:9], v102 offset:23104
	ds_read_b128 v[10:13], v103 offset:55360
	s_lshl_b32 s8, s8, 4
	s_and_b32 s36, s8, 0x380
	s_ashr_i32 s13, s12, 31
	s_cmp_gt_i32 s35, 1
	s_waitcnt lgkmcnt(0)
	v_mfma_f32_32x32x16_bf16 v[50:65], v[2:5], v[10:13], v[50:65]
	v_mfma_f32_32x32x16_bf16 v[18:33], v[6:9], v[10:13], v[18:33]
	ds_read_b128 v[2:5], v102 offset:18528
	ds_read_b128 v[6:9], v102 offset:23136
	ds_read_b128 v[10:13], v103 offset:55392
	s_waitcnt vmcnt(0)
	ds_write_b128 v140, v[90:93]
	ds_write_b128 v140, v[86:89] offset:36864
	ds_write_b128 v140, v[94:97] offset:9216
	ds_write_b128 v140, v[82:85] offset:46080
	s_waitcnt lgkmcnt(4)
	v_mfma_f32_32x32x16_bf16 v[50:65], v[2:5], v[10:13], v[50:65]
	v_mfma_f32_32x32x16_bf16 v[18:33], v[6:9], v[10:13], v[18:33]
	s_cbranch_scc0 .LBB0_874
	s_lshl_b64 s[8:9], s[12:13], 11
	s_add_u32 s14, s3, s8
	s_addc_u32 s15, s16, s9
	s_lshl_b32 s8, s34, 8
	s_ashr_i32 s9, s8, 31
	s_lshl_b64 s[10:11], s[8:9], 1
	s_add_u32 s8, s14, s10
	s_addc_u32 s9, s15, s11
	s_lshl_b32 s14, s35, 6
	s_add_i32 s48, s14, 0xffffff80
	s_lshl_b64 s[14:15], s[48:49], 1
	s_add_u32 s8, s8, s14
	s_addc_u32 s9, s9, s15
	s_lshl_b32 s37, s36, 11
	s_add_u32 s37, s21, s37
	s_addc_u32 s38, s22, 0
	s_add_u32 s10, s37, s10
	s_addc_u32 s11, s38, s11
	s_add_u32 s10, s10, s14
	s_addc_u32 s11, s11, s15
	v_lshl_add_u64 v[2:3], s[8:9], 0, v[98:99]
	v_lshl_add_u64 v[4:5], s[10:11], 0, v[98:99]
	v_mov_b32_e32 v0, v138
	s_cbranch_execz .LBB0_875
	s_branch .LBB0_876

; #define MFMA32(a, b, c) __builtin_amdgcn_mfma_f32_32x32x16_bf16((a), (b), (c), 0, 0, 0)
; DI float fexp2(float x) { return __builtin_amdgcn_exp2f(x); }
; DI void mma21(f32x16 (&acc)[2], const bf16_t* sA, const bf16_t* sB, int wr, int wc, int r, int h) {
;     const bf16_t* a = sA + (wr * 64 + r) * LS + h * 8;
;     const bf16_t* b = sB + (wc * 32 + r) * LS + h * 8;
; #pragma unroll
;     for (int s = 0; s < 4; ++s) {
;         const bf16x8 a0 = *(const bf16x8*)(a + s * 16), a1 = *(const bf16x8*)(a + 32 * LS + s * 16);
;         const bf16x8 b0 = *(const bf16x8*)(b + s * 16);
;         acc[0] = MFMA32(a0, b0, acc[0]);
;         acc[1] = MFMA32(a1, b0, acc[1]);
;     }
; DI void phase4(const Params& p, int l, unsigned char* smem) {
;     ...
;             __syncthreads(); mma21(g, sA, sB, wr, wc, r, h); stg4_commit(R1, sA + TILE_E, sB + TILE_E, srow, skc); ISS(R1, g0 + 3);
;             __syncthreads(); mma21(g, sA + TILE_E, sB + TILE_E, wr, wc, r, h); stg4_commit(R0, sA, sB, srow, skc); ISS(R0, g0 + 4);
; #pragma unroll
;             for (int mi = 0; mi < 2; ++mi)
; #pragma unroll
;                 for (int i = 0; i < 16; ++i) g[mi][i] = __builtin_amdgcn_rcpf(1.f + fexp2(-g[mi][i] * LOG2E));
;             __syncthreads(); mma21(y, sA, sB, wr, wc, r, h); stg4_commit(R1, sA + TILE_E, sB + TILE_E, srow, skc); ISS(R1, g0 + 5);
;             __syncthreads(); mma21(y, sA + TILE_E, sB + TILE_E, wr, wc, r, h); stg4_commit(R0, sA, sB, srow, skc); ISS(R0, g0 + 6);
;             __syncthreads(); mma21(y, sA, sB, wr, wc, r, h); stg4_commit(R1, sA + TILE_E, sB + TILE_E, srow, skc); ISS(R1, g0 + 7);
;             __syncthreads(); mma21(y, sA + TILE_E, sB + TILE_E, wr, wc, r, h); stg4_commit(R0, sA, sB, srow, skc); ISS(R0, g0 + 8);
.LBB0_876:
	global_load_dwordx4 v[82:85], v[2:3], off
	global_load_dwordx4 v[86:89], v[4:5], off
	v_lshl_add_u64 v[2:3], s[8:9], 0, v[0:1]
	global_load_dwordx4 v[90:93], v[2:3], off
	v_lshl_add_u64 v[2:3], s[10:11], 0, v[0:1]
	global_load_dwordx4 v[94:97], v[2:3], off
	s_waitcnt lgkmcnt(0)
	s_barrier
	ds_read_b128 v[2:5], v102 offset:4608
	ds_read_b128 v[6:9], v102
	ds_read_b128 v[142:145], v102 offset:32
	ds_read_b128 v[10:13], v103 offset:36864
	ds_read_b128 v[146:149], v103 offset:36896
	ds_read_b128 v[150:153], v102 offset:4640
	s_waitcnt lgkmcnt(0)
	v_mfma_f32_32x32x16_bf16 v[34:49], v[6:9], v[10:13], 0
	s_mul_hi_u32 s12, s29, 0xaaaaaaab
	s_lshr_b32 s12, s12, 4
	s_mul_i32 s12, s12, 24
	s_sub_i32 s13, s25, s12
	s_add_i32 s9, s30, s13
	s_add_i32 s8, s31, 5
	s_mul_hi_i32 s34, s9, 0x2aaaaaab
	v_mfma_f32_32x32x16_bf16 v[2:17], v[2:5], v[10:13], 0
	s_mul_hi_u32 s8, s8, 0xaaaaaaab
	s_lshr_b32 s9, s34, 31
	s_lshr_b32 s8, s8, 4
	s_add_i32 s34, s34, s9
	s_mul_i32 s9, s34, -6
	s_mul_i32 s8, s8, s78
	s_add_i32 s9, s31, s9
	v_mfma_f32_32x32x16_bf16 v[34:49], v[142:145], v[146:149], v[34:49]
	s_add_i32 s8, s8, s2
	s_sub_i32 s35, s9, s12
	s_lshl_b32 s9, s8, 5
	s_and_b32 s9, s9, 0xe0
	s_lshr_b32 s10, s8, 6
	s_add_i32 s9, s9, s10
	s_lshl_b32 s10, s9, 7
	v_mfma_f32_32x32x16_bf16 v[2:17], v[150:153], v[146:149], v[2:17]
	ds_read_b128 v[142:145], v102 offset:64
	ds_read_b128 v[146:149], v102 offset:4672
	ds_read_b128 v[150:153], v103 offset:36928
	s_lshl_b32 s8, s8, 4
	s_add_i32 s35, s35, 5
	s_and_b32 s36, s8, 0x380
	s_ashr_i32 s11, s10, 31
	s_cmp_gt_i32 s35, 1
	s_waitcnt lgkmcnt(0)
	v_mfma_f32_32x32x16_bf16 v[34:49], v[142:145], v[150:153], v[34:49]
	v_mfma_f32_32x32x16_bf16 v[2:17], v[146:149], v[150:153], v[2:17]
	ds_read_b128 v[142:145], v102 offset:96
	ds_read_b128 v[146:149], v102 offset:4704
	ds_read_b128 v[150:153], v103 offset:36960
	ds_write_b128 v140, v[66:69] offset:18432
	ds_write_b128 v140, v[70:73] offset:55296
	ds_write_b128 v140, v[74:77] offset:27648
	ds_write_b128 v140, v[78:81] offset:64512
	s_waitcnt lgkmcnt(0)
	v_mfma_f32_32x32x16_bf16 v[34:49], v[142:145], v[150:153], v[34:49]
	v_mfma_f32_32x32x16_bf16 v[2:17], v[146:149], v[150:153], v[2:17]
	s_cbranch_scc0 .LBB0_878
	s_lshl_b64 s[8:9], s[10:11], 11
	s_add_u32 s14, s3, s8
	s_addc_u32 s15, s16, s9
	s_lshl_b32 s8, s34, 8
	s_ashr_i32 s9, s8, 31
	s_lshl_b64 s[12:13], s[8:9], 1
	s_add_u32 s8, s14, s12
	s_addc_u32 s9, s15, s13
	s_lshl_b32 s14, s35, 6
	s_add_i32 s48, s14, 0xffffff80
	s_lshl_b64 s[14:15], s[48:49], 1
	s_add_u32 s8, s8, s14
	s_addc_u32 s9, s9, s15
	s_lshl_b32 s37, s36, 11
	s_add_u32 s37, s21, s37
	s_addc_u32 s38, s22, 0
	s_add_u32 s12, s37, s12
	s_addc_u32 s13, s38, s13
	s_add_u32 s12, s12, s14
	s_addc_u32 s13, s13, s15
	v_lshl_add_u64 v[66:67], s[8:9], 0, v[98:99]
	v_lshl_add_u64 v[70:71], s[12:13], 0, v[98:99]
	v_mov_b32_e32 v0, v138
	s_cbranch_execz .LBB0_879
	s_branch .LBB0_880

; #define MFMA32(a, b, c) __builtin_amdgcn_mfma_f32_32x32x16_bf16((a), (b), (c), 0, 0, 0)
; DI float fexp2(float x) { return __builtin_amdgcn_exp2f(x); }
; DI void mma21(f32x16 (&acc)[2], const bf16_t* sA, const bf16_t* sB, int wr, int wc, int r, int h) {
;     const bf16_t* a = sA + (wr * 64 + r) * LS + h * 8;
;     const bf16_t* b = sB + (wc * 32 + r) * LS + h * 8;
; #pragma unroll
;     for (int s = 0; s < 4; ++s) {
;         const bf16x8 a0 = *(const bf16x8*)(a + s * 16), a1 = *(const bf16x8*)(a + 32 * LS + s * 16);
;         const bf16x8 b0 = *(const bf16x8*)(b + s * 16);
;         acc[0] = MFMA32(a0, b0, acc[0]);
;         acc[1] = MFMA32(a1, b0, acc[1]);
;     }
; DI void phase4(const Params& p, int l, unsigned char* smem) {
;     ...
;             __syncthreads(); mma21(g, sA, sB, wr, wc, r, h); stg4_commit(R1, sA + TILE_E, sB + TILE_E, srow, skc); ISS(R1, g0 + 3);
;             __syncthreads(); mma21(g, sA + TILE_E, sB + TILE_E, wr, wc, r, h); stg4_commit(R0, sA, sB, srow, skc); ISS(R0, g0 + 4);
; #pragma unroll
;             for (int mi = 0; mi < 2; ++mi)
; #pragma unroll
;                 for (int i = 0; i < 16; ++i) g[mi][i] = __builtin_amdgcn_rcpf(1.f + fexp2(-g[mi][i] * LOG2E));
;             __syncthreads(); mma21(y, sA, sB, wr, wc, r, h); stg4_commit(R1, sA + TILE_E, sB + TILE_E, srow, skc); ISS(R1, g0 + 5);
;             __syncthreads(); mma21(y, sA + TILE_E, sB + TILE_E, wr, wc, r, h); stg4_commit(R0, sA, sB, srow, skc); ISS(R0, g0 + 6);
;             __syncthreads(); mma21(y, sA, sB, wr, wc, r, h); stg4_commit(R1, sA + TILE_E, sB + TILE_E, srow, skc); ISS(R1, g0 + 7);
;             __syncthreads(); mma21(y, sA + TILE_E, sB + TILE_E, wr, wc, r, h); stg4_commit(R0, sA, sB, srow, skc); ISS(R0, g0 + 8);
.LBB0_880:
	v_lshl_add_u64 v[74:75], s[8:9], 0, v[0:1]
	v_lshl_add_u64 v[78:79], s[12:13], 0, v[0:1]
	global_load_dwordx4 v[66:69], v[66:67], off
	s_nop 0
	global_load_dwordx4 v[70:73], v[70:71], off
	s_add_i32 s8, s31, 6
	global_load_dwordx4 v[74:77], v[74:75], off
	s_min_i32 s8, s8, s65
	global_load_dwordx4 v[78:81], v[78:79], off
	s_waitcnt lgkmcnt(0)
	s_barrier
	ds_read_b128 v[142:145], v102 offset:23040
	ds_read_b128 v[146:149], v102 offset:18432
	ds_read_b128 v[150:153], v102 offset:18464
	ds_read_b128 v[154:157], v103 offset:55296
	ds_read_b128 v[158:161], v103 offset:55328
	s_waitcnt lgkmcnt(0)
	v_mfma_f32_32x32x16_bf16 v[2:17], v[142:145], v[154:157], v[2:17]
	ds_read_b128 v[142:145], v102 offset:23072
	s_mul_hi_i32 s9, s8, 0x2aaaaaab
	s_lshr_b32 s10, s9, 31
	s_ashr_i32 s9, s9, 2
	s_add_i32 s9, s9, s10
	s_mul_i32 s10, s9, 0xffffffe8
	s_add_i32 s10, s10, s8
	v_mfma_f32_32x32x16_bf16 v[34:49], v[146:149], v[154:157], v[34:49]
	s_mul_hi_i32 s34, s10, 0x2aaaaaab
	s_lshr_b32 s8, s34, 31
	s_add_i32 s34, s34, s8
	s_mul_i32 s8, s9, s78
	s_add_i32 s8, s8, s2
	s_mul_i32 s35, s34, -6
	s_lshl_b32 s9, s8, 5
	v_mfma_f32_32x32x16_bf16 v[34:49], v[150:153], v[158:161], v[34:49]
	s_add_i32 s35, s35, s10
	s_and_b32 s9, s9, 0xe0
	s_lshr_b32 s10, s8, 6
	s_add_i32 s9, s9, s10
	s_lshl_b32 s10, s9, 7
	s_lshl_b32 s8, s8, 4
	s_and_b32 s36, s8, 0x380
	s_waitcnt lgkmcnt(0)
	v_mfma_f32_32x32x16_bf16 v[2:17], v[142:145], v[158:161], v[2:17]
	ds_read_b128 v[142:145], v102 offset:18496
	ds_read_b128 v[146:149], v102 offset:23104
	ds_read_b128 v[150:153], v103 offset:55360
	s_ashr_i32 s11, s10, 31
	s_cmp_gt_i32 s35, 1
	s_waitcnt lgkmcnt(0)
	v_mfma_f32_32x32x16_bf16 v[34:49], v[142:145], v[150:153], v[34:49]
	v_mfma_f32_32x32x16_bf16 v[2:17], v[146:149], v[150:153], v[2:17]
	ds_read_b128 v[142:145], v102 offset:18528
	ds_read_b128 v[146:149], v102 offset:23136
	ds_read_b128 v[150:153], v103 offset:55392
	s_waitcnt vmcnt(0)
	ds_write_b128 v140, v[82:85]
	ds_write_b128 v140, v[86:89] offset:36864
	ds_write_b128 v140, v[90:93] offset:9216
	ds_write_b128 v140, v[94:97] offset:46080
	s_waitcnt lgkmcnt(4)
	v_mfma_f32_32x32x16_bf16 v[34:49], v[142:145], v[150:153], v[34:49]
	v_mfma_f32_32x32x16_bf16 v[2:17], v[146:149], v[150:153], v[2:17]
	s_cbranch_scc0 .LBB0_882
	s_lshl_b64 s[8:9], s[10:11], 11
	s_add_u32 s14, s3, s8
	s_addc_u32 s15, s16, s9
	s_lshl_b32 s8, s34, 8
	s_ashr_i32 s9, s8, 31
	s_lshl_b64 s[12:13], s[8:9], 1
	s_add_u32 s8, s14, s12
	s_addc_u32 s9, s15, s13
	s_lshl_b32 s14, s35, 6
	s_add_i32 s48, s14, 0xffffff80
	s_lshl_b64 s[14:15], s[48:49], 1
	s_add_u32 s8, s8, s14
	s_addc_u32 s9, s9, s15
	s_lshl_b32 s37, s36, 11
	s_add_u32 s37, s21, s37
	s_addc_u32 s38, s22, 0
	s_add_u32 s12, s37, s12
	s_addc_u32 s13, s38, s13
	s_add_u32 s12, s12, s14
	s_addc_u32 s13, s13, s15
	v_lshl_add_u64 v[82:83], s[8:9], 0, v[98:99]
	v_lshl_add_u64 v[86:87], s[12:13], 0, v[98:99]
	v_mov_b32_e32 v0, v138
	s_cbranch_execz .LBB0_883
	s_branch .LBB0_884

; #define MFMA32(a, b, c) __builtin_amdgcn_mfma_f32_32x32x16_bf16((a), (b), (c), 0, 0, 0)
; DI float fexp2(float x) { return __builtin_amdgcn_exp2f(x); }
; DI void mma21(f32x16 (&acc)[2], const bf16_t* sA, const bf16_t* sB, int wr, int wc, int r, int h) {
;     const bf16_t* a = sA + (wr * 64 + r) * LS + h * 8;
;     const bf16_t* b = sB + (wc * 32 + r) * LS + h * 8;
; #pragma unroll
;     for (int s = 0; s < 4; ++s) {
;         const bf16x8 a0 = *(const bf16x8*)(a + s * 16), a1 = *(const bf16x8*)(a + 32 * LS + s * 16);
;         const bf16x8 b0 = *(const bf16x8*)(b + s * 16);
;         acc[0] = MFMA32(a0, b0, acc[0]);
;         acc[1] = MFMA32(a1, b0, acc[1]);
;     }
; DI void phase4(const Params& p, int l, unsigned char* smem) {
;     ...
;             __syncthreads(); mma21(g, sA, sB, wr, wc, r, h); stg4_commit(R1, sA + TILE_E, sB + TILE_E, srow, skc); ISS(R1, g0 + 3);
;             __syncthreads(); mma21(g, sA + TILE_E, sB + TILE_E, wr, wc, r, h); stg4_commit(R0, sA, sB, srow, skc); ISS(R0, g0 + 4);
; #pragma unroll
;             for (int mi = 0; mi < 2; ++mi)
; #pragma unroll
;                 for (int i = 0; i < 16; ++i) g[mi][i] = __builtin_amdgcn_rcpf(1.f + fexp2(-g[mi][i] * LOG2E));
;             __syncthreads(); mma21(y, sA, sB, wr, wc, r, h); stg4_commit(R1, sA + TILE_E, sB + TILE_E, srow, skc); ISS(R1, g0 + 5);
;             __syncthreads(); mma21(y, sA + TILE_E, sB + TILE_E, wr, wc, r, h); stg4_commit(R0, sA, sB, srow, skc); ISS(R0, g0 + 6);
;             __syncthreads(); mma21(y, sA, sB, wr, wc, r, h); stg4_commit(R1, sA + TILE_E, sB + TILE_E, srow, skc); ISS(R1, g0 + 7);
;             __syncthreads(); mma21(y, sA + TILE_E, sB + TILE_E, wr, wc, r, h); stg4_commit(R0, sA, sB, srow, skc); ISS(R0, g0 + 8);
.LBB0_884:
	v_lshl_add_u64 v[90:91], s[8:9], 0, v[0:1]
	v_lshl_add_u64 v[94:95], s[12:13], 0, v[0:1]
	global_load_dwordx4 v[82:85], v[82:83], off
	s_nop 0
	global_load_dwordx4 v[86:89], v[86:87], off
	s_add_i32 s8, s31, 7
	global_load_dwordx4 v[90:93], v[90:91], off
	s_min_i32 s8, s8, s65
	global_load_dwordx4 v[94:97], v[94:95], off
	s_waitcnt lgkmcnt(0)
	s_barrier
	ds_read_b128 v[142:145], v102 offset:4608
	ds_read_b128 v[146:149], v102
	ds_read_b128 v[150:153], v102 offset:32
	ds_read_b128 v[154:157], v103 offset:36864
	ds_read_b128 v[158:161], v103 offset:36896
	s_waitcnt lgkmcnt(0)
	v_mfma_f32_32x32x16_bf16 v[2:17], v[142:145], v[154:157], v[2:17]
	ds_read_b128 v[142:145], v102 offset:4640
	s_mul_hi_i32 s9, s8, 0x2aaaaaab
	s_lshr_b32 s10, s9, 31
	s_ashr_i32 s9, s9, 2
	s_add_i32 s9, s9, s10
	s_mul_i32 s10, s9, 0xffffffe8
	s_add_i32 s10, s10, s8
	v_mfma_f32_32x32x16_bf16 v[34:49], v[146:149], v[154:157], v[34:49]
	s_mul_hi_i32 s34, s10, 0x2aaaaaab
	s_lshr_b32 s8, s34, 31
	s_add_i32 s34, s34, s8
	s_mul_i32 s8, s9, s78
	s_add_i32 s8, s8, s2
	s_mul_i32 s35, s34, -6
	s_lshl_b32 s9, s8, 5
	v_mfma_f32_32x32x16_bf16 v[34:49], v[150:153], v[158:161], v[34:49]
	s_add_i32 s35, s35, s10
	s_and_b32 s9, s9, 0xe0
	s_lshr_b32 s10, s8, 6
	s_add_i32 s9, s9, s10
	s_lshl_b32 s10, s9, 7
	s_lshl_b32 s8, s8, 4
	s_and_b32 s36, s8, 0x380
	s_waitcnt lgkmcnt(0)
	v_mfma_f32_32x32x16_bf16 v[2:17], v[142:145], v[158:161], v[2:17]
	ds_read_b128 v[142:145], v102 offset:64
	ds_read_b128 v[146:149], v102 offset:4672
	ds_read_b128 v[150:153], v103 offset:36928
	s_ashr_i32 s11, s10, 31
	s_cmp_gt_i32 s35, 1
	s_waitcnt lgkmcnt(0)
	v_mfma_f32_32x32x16_bf16 v[34:49], v[142:145], v[150:153], v[34:49]
	v_mfma_f32_32x32x16_bf16 v[2:17], v[146:149], v[150:153], v[2:17]
	ds_read_b128 v[142:145], v102 offset:96
	ds_read_b128 v[146:149], v102 offset:4704
	ds_read_b128 v[150:153], v103 offset:36960
	ds_write_b128 v140, v[66:69] offset:18432
	ds_write_b128 v140, v[70:73] offset:55296
	ds_write_b128 v140, v[74:77] offset:27648
	ds_write_b128 v140, v[78:81] offset:64512
	s_waitcnt lgkmcnt(0)
	v_mfma_f32_32x32x16_bf16 v[34:49], v[142:145], v[150:153], v[34:49]
	v_mfma_f32_32x32x16_bf16 v[2:17], v[146:149], v[150:153], v[2:17]
	s_cbranch_scc0 .LBB0_886
	s_lshl_b64 s[8:9], s[10:11], 11
	s_add_u32 s14, s3, s8
	s_addc_u32 s15, s16, s9
	s_lshl_b32 s8, s34, 8
	s_ashr_i32 s9, s8, 31
	s_lshl_b64 s[12:13], s[8:9], 1
	s_add_u32 s8, s14, s12
	s_addc_u32 s9, s15, s13
	s_lshl_b32 s14, s35, 6
	s_add_i32 s48, s14, 0xffffff80
	s_lshl_b64 s[14:15], s[48:49], 1
	s_add_u32 s8, s8, s14
	s_addc_u32 s9, s9, s15
	s_lshl_b32 s37, s36, 11
	s_add_u32 s37, s21, s37
	s_addc_u32 s38, s22, 0
	s_add_u32 s12, s37, s12
	s_addc_u32 s13, s38, s13
	s_add_u32 s12, s12, s14
	s_addc_u32 s13, s13, s15
	v_lshl_add_u64 v[66:67], s[8:9], 0, v[98:99]
	v_lshl_add_u64 v[70:71], s[12:13], 0, v[98:99]
	v_mov_b32_e32 v0, v138
	s_cbranch_execz .LBB0_887
	s_branch .LBB0_888

; #define MFMA32(a, b, c) __builtin_amdgcn_mfma_f32_32x32x16_bf16((a), (b), (c), 0, 0, 0)
; DI float fexp2(float x) { return __builtin_amdgcn_exp2f(x); }
; DI void mma21(f32x16 (&acc)[2], const bf16_t* sA, const bf16_t* sB, int wr, int wc, int r, int h) {
;     const bf16_t* a = sA + (wr * 64 + r) * LS + h * 8;
;     const bf16_t* b = sB + (wc * 32 + r) * LS + h * 8;
; #pragma unroll
;     for (int s = 0; s < 4; ++s) {
;         const bf16x8 a0 = *(const bf16x8*)(a + s * 16), a1 = *(const bf16x8*)(a + 32 * LS + s * 16);
;         const bf16x8 b0 = *(const bf16x8*)(b + s * 16);
;         acc[0] = MFMA32(a0, b0, acc[0]);
;         acc[1] = MFMA32(a1, b0, acc[1]);
;     }
; DI void phase4(const Params& p, int l, unsigned char* smem) {
;     ...
;             __syncthreads(); mma21(g, sA, sB, wr, wc, r, h); stg4_commit(R1, sA + TILE_E, sB + TILE_E, srow, skc); ISS(R1, g0 + 3);
;             __syncthreads(); mma21(g, sA + TILE_E, sB + TILE_E, wr, wc, r, h); stg4_commit(R0, sA, sB, srow, skc); ISS(R0, g0 + 4);
; #pragma unroll
;             for (int mi = 0; mi < 2; ++mi)
; #pragma unroll
;                 for (int i = 0; i < 16; ++i) g[mi][i] = __builtin_amdgcn_rcpf(1.f + fexp2(-g[mi][i] * LOG2E));
;             __syncthreads(); mma21(y, sA, sB, wr, wc, r, h); stg4_commit(R1, sA + TILE_E, sB + TILE_E, srow, skc); ISS(R1, g0 + 5);
;             __syncthreads(); mma21(y, sA + TILE_E, sB + TILE_E, wr, wc, r, h); stg4_commit(R0, sA, sB, srow, skc); ISS(R0, g0 + 6);
;             __syncthreads(); mma21(y, sA, sB, wr, wc, r, h); stg4_commit(R1, sA + TILE_E, sB + TILE_E, srow, skc); ISS(R1, g0 + 7);
;             __syncthreads(); mma21(y, sA + TILE_E, sB + TILE_E, wr, wc, r, h); stg4_commit(R0, sA, sB, srow, skc); ISS(R0, g0 + 8);
.LBB0_888:
	v_lshl_add_u64 v[74:75], s[8:9], 0, v[0:1]
	v_lshl_add_u64 v[78:79], s[12:13], 0, v[0:1]
	global_load_dwordx4 v[66:69], v[66:67], off
	s_nop 0
	global_load_dwordx4 v[70:73], v[70:71], off
	s_add_i32 s31, s31, 8
	global_load_dwordx4 v[74:77], v[74:75], off
	s_min_i32 s8, s31, s65
	global_load_dwordx4 v[78:81], v[78:79], off
	s_waitcnt lgkmcnt(0)
	s_barrier
	ds_read_b128 v[142:145], v102 offset:23040
	ds_read_b128 v[146:149], v102 offset:18432
	ds_read_b128 v[150:153], v102 offset:18464
	ds_read_b128 v[154:157], v103 offset:55296
	ds_read_b128 v[158:161], v103 offset:55328
	s_waitcnt lgkmcnt(0)
	v_mfma_f32_32x32x16_bf16 v[2:17], v[142:145], v[154:157], v[2:17]
	ds_read_b128 v[142:145], v102 offset:23072
	s_mul_hi_i32 s9, s8, 0x2aaaaaab
	s_lshr_b32 s10, s9, 31
	s_ashr_i32 s9, s9, 2
	s_add_i32 s9, s9, s10
	s_mul_i32 s10, s9, 0xffffffe8
	s_add_i32 s10, s10, s8
	v_mfma_f32_32x32x16_bf16 v[34:49], v[146:149], v[154:157], v[34:49]
	s_mul_hi_i32 s31, s10, 0x2aaaaaab
	s_lshr_b32 s8, s31, 31
	s_add_i32 s31, s31, s8
	s_mul_i32 s8, s9, s78
	s_add_i32 s8, s8, s2
	s_mul_i32 s34, s31, -6
	s_lshl_b32 s9, s8, 5
	v_mfma_f32_32x32x16_bf16 v[34:49], v[150:153], v[158:161], v[34:49]
	s_add_i32 s34, s34, s10
	s_and_b32 s9, s9, 0xe0
	s_lshr_b32 s10, s8, 6
	s_add_i32 s9, s9, s10
	s_lshl_b32 s12, s9, 7
	s_lshl_b32 s8, s8, 4
	s_and_b32 s35, s8, 0x380
	s_waitcnt lgkmcnt(0)
	v_mfma_f32_32x32x16_bf16 v[2:17], v[142:145], v[158:161], v[2:17]
	ds_read_b128 v[142:145], v102 offset:18496
	ds_read_b128 v[146:149], v102 offset:23104
	ds_read_b128 v[150:153], v103 offset:55360
	s_ashr_i32 s13, s12, 31
	s_cmp_gt_i32 s34, 1
	s_waitcnt lgkmcnt(0)
	v_mfma_f32_32x32x16_bf16 v[34:49], v[142:145], v[150:153], v[34:49]
	v_mfma_f32_32x32x16_bf16 v[2:17], v[146:149], v[150:153], v[2:17]
	ds_read_b128 v[142:145], v102 offset:18528
	ds_read_b128 v[146:149], v102 offset:23136
	ds_read_b128 v[150:153], v103 offset:55392
	s_waitcnt vmcnt(0)
	ds_write_b128 v140, v[82:85]
	ds_write_b128 v140, v[86:89] offset:36864
	ds_write_b128 v140, v[90:93] offset:9216
	ds_write_b128 v140, v[94:97] offset:46080
	s_waitcnt lgkmcnt(4)
	v_mfma_f32_32x32x16_bf16 v[34:49], v[142:145], v[150:153], v[34:49]
	v_mfma_f32_32x32x16_bf16 v[2:17], v[146:149], v[150:153], v[2:17]
	s_cbranch_scc0 .LBB0_890
	s_lshl_b64 s[8:9], s[12:13], 11
	s_add_u32 s14, s3, s8
	s_addc_u32 s15, s16, s9
	s_lshl_b32 s8, s31, 8
	s_ashr_i32 s9, s8, 31
	s_lshl_b64 s[10:11], s[8:9], 1
	s_add_u32 s8, s14, s10
	s_addc_u32 s9, s15, s11
	s_lshl_b32 s14, s34, 6
	s_add_i32 s48, s14, 0xffffff80
	s_lshl_b64 s[14:15], s[48:49], 1
	s_add_u32 s8, s8, s14
	s_addc_u32 s9, s9, s15
	s_lshl_b32 s36, s35, 11
	s_add_u32 s36, s21, s36
	s_addc_u32 s37, s22, 0
	s_add_u32 s10, s36, s10
	s_addc_u32 s11, s37, s11
	s_add_u32 s10, s10, s14
	s_addc_u32 s11, s11, s15
	v_lshl_add_u64 v[82:83], s[8:9], 0, v[98:99]
	v_lshl_add_u64 v[84:85], s[10:11], 0, v[98:99]
	v_mov_b32_e32 v0, v138
	s_cbranch_execnz .LBB0_867
	s_branch .LBB0_891

; template <typename T> DI T* opaque(T* p) { asm volatile("" : "+v"(p) : : "memory"); return p; }
;     DI void operator()(const pg8::f32x4 (&acc)[2][2][4][2], const pg8::Unit& u, int wr, int wc, int fr, int fq) const {
;     ...
;             const int col0 = u.pn * 256 + bj * 128 + wc * 32 + 8 * fq;
;             f32x4 g0 = {1.f, 1.f, 1.f, 1.f}, g1 = g0, b0 = {0.f, 0.f, 0.f, 0.f}, b1 = b0;
;             if (l > 0) { g0 = *(const f32x4*)(lg + col0); g1 = *(const f32x4*)(lg + col0 + 4); b0 = *(const f32x4*)(lb + col0); b1 = *(const f32x4*)(lb + col0 + 4); }
;             const float* src = (l == 0) ? x : (const float*)out;
; #pragma unroll
;             for (int ai = 0; ai < 2; ++ai) {
;                 const size_t i0 = (size_t)(rowb + ai * 128) * 1024 + col0;
;                 const float* ps = opaque(src + i0);
;                 f32x4 xa[4], xb_[4]; f32x2 sv[4];
; #pragma unroll
;                 for (int m = 0; m < 4; ++m) {
;                     xa[m] = *(const f32x4*)(ps + (size_t)(m * 16) * 1024); xb_[m] = *(const f32x4*)(ps + (size_t)(m * 16) * 1024 + 4);
;                     if (l > 0) sv[m] = *(const f32x2*)(st + 2 * (rowb + ai * 128 + m * 16));
;                 }
.LBB0_955:
	v_lshl_add_u32 v210, s60, 8, v229
	v_ashrrev_i32_e32 v211, 31, v210
	v_lshlrev_b64 v[146:147], 10, v[210:211]
	v_lshl_add_u64 v[206:207], v[146:147], 0, v[208:209]
	v_lshl_add_u64 v[204:205], v[206:207], 2, s[82:83]
	v_mov_b64_e32 v[146:147], v[204:205]
	v_lshlrev_b32_e32 v198, 1, v210
	s_and_b64 vcc, exec, s[6:7]
	v_ashrrev_i32_e32 v199, 31, v198
	s_waitcnt vmcnt(0)
	global_load_dwordx4 v[166:169], v[146:147], off
	global_load_dwordx4 v[174:177], v[146:147], off offset:16
	s_mov_b64 s[30:31], 0x200
	s_cbranch_vccnz .LBB0_957
	v_lshl_add_u64 v[148:149], v[198:199], 2, s[80:81]
	global_load_dwordx2 v[196:197], v[148:149], off
.LBB0_957:
	v_add_co_u32_e32 v148, vcc, 0x10000, v146
	s_nop 1
	v_addc_co_u32_e32 v149, vcc, 0, v147, vcc
	global_load_dwordx4 v[170:173], v[148:149], off
	global_load_dwordx4 v[162:165], v[148:149], off offset:16
	s_and_b64 vcc, exec, s[6:7]
	s_cbranch_vccnz .LBB0_959
	v_lshl_add_u64 v[148:149], v[198:199], 2, s[80:81]
	global_load_dwordx2 v[194:195], v[148:149], off offset:128
.LBB0_959:
	v_add_co_u32_e32 v148, vcc, 0x20000, v146
	s_nop 1
	v_addc_co_u32_e32 v149, vcc, 0, v147, vcc
	global_load_dwordx4 v[154:157], v[148:149], off
	global_load_dwordx4 v[158:161], v[148:149], off offset:16
	s_and_b64 vcc, exec, s[6:7]
	s_cbranch_vccnz .LBB0_961
	v_lshl_add_u64 v[148:149], v[198:199], 2, s[80:81]
	global_load_dwordx2 v[192:193], v[148:149], off offset:256
.LBB0_961:
	v_add_co_u32_e32 v146, vcc, 0x30000, v146
	s_nop 1
	v_addc_co_u32_e32 v147, vcc, 0, v147, vcc
	global_load_dwordx4 v[150:153], v[146:147], off
	s_nop 0
	global_load_dwordx4 v[146:149], v[146:147], off offset:16
	s_and_b64 vcc, exec, s[6:7]
	s_cbranch_vccnz .LBB0_963
	v_lshl_add_u64 v[178:179], v[198:199], 2, s[80:81]
	global_load_dwordx2 v[190:191], v[178:179], off offset:384

; template <typename T> DI T* opaque(T* p) { asm volatile("" : "+v"(p) : : "memory"); return p; }
;     DI void operator()(const pg8::f32x4 (&acc)[2][2][4][2], const pg8::Unit& u, int wr, int wc, int fr, int fq) const {
;     ...
; #pragma unroll
;                 for (int m = 0; m < 4; ++m) {
;                     xa[m] = *(const f32x4*)(ps + (size_t)(m * 16) * 1024); xb_[m] = *(const f32x4*)(ps + (size_t)(m * 16) * 1024 + 4);
;                     if (l > 0) sv[m] = *(const f32x2*)(st + 2 * (rowb + ai * 128 + m * 16));
;                 }
;                 float* po = opaque(out + i0);
; #pragma unroll
;                 for (int m = 0; m < 4; ++m) {
;                     f32x4 x0 = xa[m], x1 = xb_[m];
;                     if (l > 0) { x0 = (x0 - sv[m].x) * sv[m].y * g0 + b0; x1 = (x1 - sv[m].x) * sv[m].y * g1 + b1; }
;                     *(f32x4*)(po + (size_t)(m * 16) * 1024) = x0 * DN_ALPHA + acc[ai][bj][m][0];
;                     *(f32x4*)(po + (size_t)(m * 16) * 1024 + 4) = x1 * DN_ALPHA + acc[ai][bj][m][1];
.LBB0_965:
	s_waitcnt vmcnt(0) lgkmcnt(0)
	v_pk_fma_f32 v[124:125], v[168:169], s[96:97], v[124:125] op_sel_hi:[1,0,1]
	v_pk_fma_f32 v[122:123], v[166:167], s[96:97], v[122:123] op_sel_hi:[1,0,1]
	v_pk_fma_f32 v[128:129], v[176:177], s[96:97], v[128:129] op_sel_hi:[1,0,1]
	v_pk_fma_f32 v[126:127], v[174:175], s[96:97], v[126:127] op_sel_hi:[1,0,1]
	global_store_dwordx4 v[212:213], v[122:125], off
	global_store_dwordx4 v[212:213], v[126:129], off offset:16
	v_pk_fma_f32 v[120:121], v[172:173], s[96:97], v[120:121] op_sel_hi:[1,0,1]
	v_add_co_u32_e32 v122, vcc, s63, v212
	v_pk_fma_f32 v[118:119], v[170:171], s[96:97], v[118:119] op_sel_hi:[1,0,1]
	s_nop 0
	v_addc_co_u32_e32 v123, vcc, 0, v213, vcc
	v_pk_fma_f32 v[116:117], v[164:165], s[96:97], v[116:117] op_sel_hi:[1,0,1]
	v_pk_fma_f32 v[114:115], v[162:163], s[96:97], v[114:115] op_sel_hi:[1,0,1]
	s_and_b64 vcc, exec, s[6:7]
	global_store_dwordx4 v[122:123], v[118:121], off
	global_store_dwordx4 v[122:123], v[114:117], off offset:16
	s_cbranch_vccnz .LBB0_967
	s_nop 0
	v_sub_f32_e32 v115, v157, v192
	v_sub_f32_e32 v114, v156, v192
	v_sub_f32_e32 v117, v155, v192
	v_sub_f32_e32 v116, v154, v192
	v_pk_mul_f32 v[116:117], v[192:193], v[116:117] op_sel:[1,0]
	v_pk_mul_f32 v[114:115], v[192:193], v[114:115] op_sel:[1,0]
	v_pk_fma_f32 v[154:155], v[142:143], v[116:117], v[138:139]
	v_pk_fma_f32 v[156:157], v[144:145], v[114:115], v[140:141]
	v_sub_f32_e32 v115, v161, v192
	v_sub_f32_e32 v114, v160, v192
	v_sub_f32_e32 v117, v159, v192
	v_sub_f32_e32 v116, v158, v192
	v_pk_mul_f32 v[116:117], v[192:193], v[116:117] op_sel:[1,0]
	v_pk_mul_f32 v[114:115], v[192:193], v[114:115] op_sel:[1,0]
	v_pk_fma_f32 v[158:159], v[130:131], v[116:117], v[134:135]
	v_pk_fma_f32 v[160:161], v[132:133], v[114:115], v[136:137]
	v_sub_f32_e32 v115, v153, v190
	v_sub_f32_e32 v114, v152, v190
	v_sub_f32_e32 v117, v151, v190
	v_sub_f32_e32 v116, v150, v190
	v_pk_mul_f32 v[116:117], v[190:191], v[116:117] op_sel:[1,0]
	v_pk_mul_f32 v[114:115], v[190:191], v[114:115] op_sel:[1,0]
	v_pk_fma_f32 v[150:151], v[142:143], v[116:117], v[138:139]
	v_pk_fma_f32 v[152:153], v[144:145], v[114:115], v[140:141]
	v_sub_f32_e32 v115, v149, v190
	v_sub_f32_e32 v114, v148, v190
	v_sub_f32_e32 v117, v147, v190
	v_sub_f32_e32 v116, v146, v190
	v_pk_mul_f32 v[116:117], v[190:191], v[116:117] op_sel:[1,0]
	v_pk_mul_f32 v[114:115], v[190:191], v[114:115] op_sel:[1,0]
	v_pk_fma_f32 v[146:147], v[130:131], v[116:117], v[134:135]
	v_pk_fma_f32 v[148:149], v[132:133], v[114:115], v[136:137]
.LBB0_967:
	s_nop 0
	v_add_co_u32_e32 v114, vcc, s79, v212
	v_pk_fma_f32 v[108:109], v[156:157], s[96:97], v[108:109] op_sel_hi:[1,0,1]
	v_pk_fma_f32 v[106:107], v[154:155], s[96:97], v[106:107] op_sel_hi:[1,0,1]
	v_addc_co_u32_e32 v115, vcc, 0, v213, vcc
	v_pk_fma_f32 v[112:113], v[160:161], s[96:97], v[112:113] op_sel_hi:[1,0,1]
	v_pk_fma_f32 v[110:111], v[158:159], s[96:97], v[110:111] op_sel_hi:[1,0,1]
	global_store_dwordx4 v[114:115], v[106:109], off
	global_store_dwordx4 v[114:115], v[110:113], off offset:16
	v_pk_fma_f32 v[100:101], v[148:149], s[96:97], v[100:101] op_sel_hi:[1,0,1]
	v_add_co_u32_e32 v106, vcc, s88, v212
	v_pk_fma_f32 v[98:99], v[146:147], s[96:97], v[98:99] op_sel_hi:[1,0,1]
	s_nop 0
	v_addc_co_u32_e32 v107, vcc, 0, v213, vcc
	global_store_dwordx4 v[106:107], v[98:101], off offset:16
	v_pk_fma_f32 v[102:103], v[150:151], s[96:97], v[102:103] op_sel_hi:[1,0,1]
	v_pk_fma_f32 v[104:105], v[152:153], s[96:97], v[104:105] op_sel_hi:[1,0,1]
	v_add_u32_e32 v100, 0x80, v210
	v_ashrrev_i32_e32 v101, 31, v100
	v_lshlrev_b64 v[98:99], 10, v[100:101]
	v_lshl_add_u64 v[150:151], v[98:99], 0, v[208:209]
	v_lshl_add_u64 v[148:149], v[150:151], 2, s[82:83]
	global_store_dwordx4 v[106:107], v[102:105], off
	v_mov_b64_e32 v[98:99], v[148:149]
	global_load_dwordx4 v[118:121], v[98:99], off
	global_load_dwordx4 v[126:129], v[98:99], off offset:16
	v_lshlrev_b32_e32 v146, 1, v100
	s_and_b64 vcc, exec, s[6:7]
	v_ashrrev_i32_e32 v147, 31, v146
	s_cbranch_vccnz .LBB0_969
	v_lshl_add_u64 v[100:101], v[146:147], 2, s[80:81]
	global_load_dwordx2 v[196:197], v[100:101], off
.LBB0_969:
	v_add_co_u32_e32 v100, vcc, 0x10000, v98
	s_nop 1
	v_addc_co_u32_e32 v101, vcc, 0, v99, vcc
	global_load_dwordx4 v[122:125], v[100:101], off
	global_load_dwordx4 v[114:117], v[100:101], off offset:16
	s_and_b64 vcc, exec, s[6:7]
	s_cbranch_vccnz .LBB0_971
	v_lshl_add_u64 v[100:101], v[146:147], 2, s[80:81]
	global_load_dwordx2 v[194:195], v[100:101], off offset:128
.LBB0_971:
	v_add_co_u32_e32 v100, vcc, 0x20000, v98
	s_nop 1
	v_addc_co_u32_e32 v101, vcc, 0, v99, vcc
	global_load_dwordx4 v[106:109], v[100:101], off
	global_load_dwordx4 v[110:113], v[100:101], off offset:16
	s_and_b64 vcc, exec, s[6:7]
	s_cbranch_vccnz .LBB0_973
	v_lshl_add_u64 v[100:101], v[146:147], 2, s[80:81]
	global_load_dwordx2 v[192:193], v[100:101], off offset:256
.LBB0_973:
	v_add_co_u32_e32 v98, vcc, 0x30000, v98
	s_nop 1
	v_addc_co_u32_e32 v99, vcc, 0, v99, vcc
	global_load_dwordx4 v[102:105], v[98:99], off
	s_nop 0
	global_load_dwordx4 v[98:101], v[98:99], off offset:16
	s_and_b64 vcc, exec, s[6:7]
	s_cbranch_vccnz .LBB0_975
	v_lshl_add_u64 v[152:153], v[146:147], 2, s[80:81]
	global_load_dwordx2 v[190:191], v[152:153], off offset:384

; template <typename T> DI T* opaque(T* p) { asm volatile("" : "+v"(p) : : "memory"); return p; }
;     DI void operator()(const pg8::f32x4 (&acc)[2][2][4][2], const pg8::Unit& u, int wr, int wc, int fr, int fq) const {
;     ...
;         for (int bj = 0; bj < 2; ++bj) {
;             const int col0 = u.pn * 256 + bj * 128 + wc * 32 + 8 * fq;
;             f32x4 g0 = {1.f, 1.f, 1.f, 1.f}, g1 = g0, b0 = {0.f, 0.f, 0.f, 0.f}, b1 = b0;
;             if (l > 0) { g0 = *(const f32x4*)(lg + col0); g1 = *(const f32x4*)(lg + col0 + 4); b0 = *(const f32x4*)(lb + col0); b1 = *(const f32x4*)(lb + col0 + 4); }
;             const float* src = (l == 0) ? x : (const float*)out;
; #pragma unroll
;             for (int ai = 0; ai < 2; ++ai) {
;                 const size_t i0 = (size_t)(rowb + ai * 128) * 1024 + col0;
;                 const float* ps = opaque(src + i0);
;                 f32x4 xa[4], xb_[4]; f32x2 sv[4];
; #pragma unroll
;                 for (int m = 0; m < 4; ++m) {
;                     xa[m] = *(const f32x4*)(ps + (size_t)(m * 16) * 1024); xb_[m] = *(const f32x4*)(ps + (size_t)(m * 16) * 1024 + 4);
;                     if (l > 0) sv[m] = *(const f32x2*)(st + 2 * (rowb + ai * 128 + m * 16));
;                 }
;                 float* po = opaque(out + i0);
; #pragma unroll
;                 for (int m = 0; m < 4; ++m) {
;                     f32x4 x0 = xa[m], x1 = xb_[m];
;                     if (l > 0) { x0 = (x0 - sv[m].x) * sv[m].y * g0 + b0; x1 = (x1 - sv[m].x) * sv[m].y * g1 + b1; }
;                     *(f32x4*)(po + (size_t)(m * 16) * 1024) = x0 * DN_ALPHA + acc[ai][bj][m][0];
;                     *(f32x4*)(po + (size_t)(m * 16) * 1024 + 4) = x1 * DN_ALPHA + acc[ai][bj][m][1];
.LBB0_977:
	s_waitcnt vmcnt(0) lgkmcnt(0)
	v_pk_fma_f32 v[92:93], v[120:121], s[96:97], v[92:93] op_sel_hi:[1,0,1]
	v_pk_fma_f32 v[90:91], v[118:119], s[96:97], v[90:91] op_sel_hi:[1,0,1]
	v_pk_fma_f32 v[96:97], v[128:129], s[96:97], v[96:97] op_sel_hi:[1,0,1]
	v_pk_fma_f32 v[94:95], v[126:127], s[96:97], v[94:95] op_sel_hi:[1,0,1]
	global_store_dwordx4 v[152:153], v[90:93], off
	global_store_dwordx4 v[152:153], v[94:97], off offset:16
	v_pk_fma_f32 v[88:89], v[124:125], s[96:97], v[88:89] op_sel_hi:[1,0,1]
	v_add_co_u32_e32 v90, vcc, s63, v152
	v_pk_fma_f32 v[86:87], v[122:123], s[96:97], v[86:87] op_sel_hi:[1,0,1]
	s_nop 0
	v_addc_co_u32_e32 v91, vcc, 0, v153, vcc
	v_pk_fma_f32 v[84:85], v[116:117], s[96:97], v[84:85] op_sel_hi:[1,0,1]
	v_pk_fma_f32 v[82:83], v[114:115], s[96:97], v[82:83] op_sel_hi:[1,0,1]
	s_and_b64 vcc, exec, s[6:7]
	global_store_dwordx4 v[90:91], v[86:89], off
	global_store_dwordx4 v[90:91], v[82:85], off offset:16
	s_cbranch_vccnz .LBB0_979
	s_nop 0
	v_sub_f32_e32 v83, v109, v192
	v_sub_f32_e32 v82, v108, v192
	v_sub_f32_e32 v85, v107, v192
	v_sub_f32_e32 v84, v106, v192
	v_pk_mul_f32 v[84:85], v[192:193], v[84:85] op_sel:[1,0]
	v_pk_mul_f32 v[82:83], v[192:193], v[82:83] op_sel:[1,0]
	v_pk_fma_f32 v[106:107], v[142:143], v[84:85], v[138:139]
	v_pk_fma_f32 v[108:109], v[144:145], v[82:83], v[140:141]
	v_sub_f32_e32 v83, v113, v192
	v_sub_f32_e32 v82, v112, v192
	v_sub_f32_e32 v85, v111, v192
	v_sub_f32_e32 v84, v110, v192
	v_pk_mul_f32 v[84:85], v[192:193], v[84:85] op_sel:[1,0]
	v_pk_mul_f32 v[82:83], v[192:193], v[82:83] op_sel:[1,0]
	v_pk_fma_f32 v[110:111], v[130:131], v[84:85], v[134:135]
	v_pk_fma_f32 v[112:113], v[132:133], v[82:83], v[136:137]
	v_sub_f32_e32 v83, v105, v190
	v_sub_f32_e32 v82, v104, v190
	v_sub_f32_e32 v85, v103, v190
	v_sub_f32_e32 v84, v102, v190
	v_pk_mul_f32 v[84:85], v[190:191], v[84:85] op_sel:[1,0]
	v_pk_mul_f32 v[82:83], v[190:191], v[82:83] op_sel:[1,0]
	v_pk_fma_f32 v[102:103], v[142:143], v[84:85], v[138:139]
	v_pk_fma_f32 v[104:105], v[144:145], v[82:83], v[140:141]
	v_sub_f32_e32 v83, v101, v190
	v_sub_f32_e32 v82, v100, v190
	v_sub_f32_e32 v85, v99, v190
	v_sub_f32_e32 v84, v98, v190
	v_pk_mul_f32 v[84:85], v[190:191], v[84:85] op_sel:[1,0]
	v_pk_mul_f32 v[82:83], v[190:191], v[82:83] op_sel:[1,0]
	v_pk_fma_f32 v[98:99], v[130:131], v[84:85], v[134:135]
	v_pk_fma_f32 v[100:101], v[132:133], v[82:83], v[136:137]
.LBB0_979:
	s_nop 0
	v_add_co_u32_e32 v82, vcc, s79, v152
	v_pk_fma_f32 v[76:77], v[108:109], s[96:97], v[76:77] op_sel_hi:[1,0,1]
	v_pk_fma_f32 v[74:75], v[106:107], s[96:97], v[74:75] op_sel_hi:[1,0,1]
	v_addc_co_u32_e32 v83, vcc, 0, v153, vcc
	v_pk_fma_f32 v[80:81], v[112:113], s[96:97], v[80:81] op_sel_hi:[1,0,1]
	v_pk_fma_f32 v[78:79], v[110:111], s[96:97], v[78:79] op_sel_hi:[1,0,1]
	global_store_dwordx4 v[82:83], v[74:77], off
	global_store_dwordx4 v[82:83], v[78:81], off offset:16
	v_pk_fma_f32 v[72:73], v[104:105], s[96:97], v[72:73] op_sel_hi:[1,0,1]
	v_add_co_u32_e32 v74, vcc, 0x30000, v152
	v_pk_fma_f32 v[70:71], v[102:103], s[96:97], v[70:71] op_sel_hi:[1,0,1]
	s_nop 0
	v_addc_co_u32_e32 v75, vcc, 0, v153, vcc
	v_pk_fma_f32 v[68:69], v[100:101], s[96:97], v[68:69] op_sel_hi:[1,0,1]
	v_pk_fma_f32 v[66:67], v[98:99], s[96:97], v[66:67] op_sel_hi:[1,0,1]
	s_and_b64 vcc, exec, s[6:7]
	global_store_dwordx4 v[74:75], v[70:73], off
	global_store_dwordx4 v[74:75], v[66:69], off offset:16
	s_cbranch_vccnz .LBB0_981
	global_load_dwordx4 v[66:69], v[202:203], off offset:528
	global_load_dwordx4 v[78:81], v[202:203], off offset:512
	global_load_dwordx4 v[74:77], v[200:201], off offset:512
	global_load_dwordx4 v[70:73], v[200:201], off offset:528
	s_branch .LBB0_982

; template <typename T> DI T* opaque(T* p) { asm volatile("" : "+v"(p) : : "memory"); return p; }
;     DI void operator()(const pg8::f32x4 (&acc)[2][2][4][2], const pg8::Unit& u, int wr, int wc, int fr, int fq) const {
;     ...
;             const int col0 = u.pn * 256 + bj * 128 + wc * 32 + 8 * fq;
;             f32x4 g0 = {1.f, 1.f, 1.f, 1.f}, g1 = g0, b0 = {0.f, 0.f, 0.f, 0.f}, b1 = b0;
;             if (l > 0) { g0 = *(const f32x4*)(lg + col0); g1 = *(const f32x4*)(lg + col0 + 4); b0 = *(const f32x4*)(lb + col0); b1 = *(const f32x4*)(lb + col0 + 4); }
;             const float* src = (l == 0) ? x : (const float*)out;
; #pragma unroll
;             for (int ai = 0; ai < 2; ++ai) {
;                 const size_t i0 = (size_t)(rowb + ai * 128) * 1024 + col0;
;                 const float* ps = opaque(src + i0);
;                 f32x4 xa[4], xb_[4]; f32x2 sv[4];
; #pragma unroll
;                 for (int m = 0; m < 4; ++m) {
;                     xa[m] = *(const f32x4*)(ps + (size_t)(m * 16) * 1024); xb_[m] = *(const f32x4*)(ps + (size_t)(m * 16) * 1024 + 4);
;                     if (l > 0) sv[m] = *(const f32x2*)(st + 2 * (rowb + ai * 128 + m * 16));
;                 }
.LBB0_982:
	v_lshl_add_u64 v[82:83], v[204:205], 0, s[30:31]
	s_and_b64 vcc, exec, s[6:7]
	global_load_dwordx4 v[106:109], v[82:83], off
	global_load_dwordx4 v[110:113], v[82:83], off offset:16
	s_cbranch_vccnz .LBB0_984
	v_lshl_add_u64 v[84:85], v[198:199], 2, s[80:81]
	global_load_dwordx2 v[196:197], v[84:85], off
.LBB0_984:
	v_add_co_u32_e32 v84, vcc, 0x10000, v82
	s_nop 1
	v_addc_co_u32_e32 v85, vcc, 0, v83, vcc
	global_load_dwordx4 v[102:105], v[84:85], off
	global_load_dwordx4 v[98:101], v[84:85], off offset:16
	s_and_b64 vcc, exec, s[6:7]
	s_cbranch_vccnz .LBB0_986
	v_lshl_add_u64 v[84:85], v[198:199], 2, s[80:81]
	global_load_dwordx2 v[194:195], v[84:85], off offset:128
.LBB0_986:
	v_add_co_u32_e32 v84, vcc, 0x20000, v82
	s_nop 1
	v_addc_co_u32_e32 v85, vcc, 0, v83, vcc
	global_load_dwordx4 v[90:93], v[84:85], off
	global_load_dwordx4 v[94:97], v[84:85], off offset:16
	s_and_b64 vcc, exec, s[6:7]
	s_cbranch_vccnz .LBB0_988
	v_lshl_add_u64 v[84:85], v[198:199], 2, s[80:81]
	global_load_dwordx2 v[192:193], v[84:85], off offset:256
.LBB0_988:
	v_add_co_u32_e32 v82, vcc, 0x30000, v82
	s_nop 1
	v_addc_co_u32_e32 v83, vcc, 0, v83, vcc
	global_load_dwordx4 v[86:89], v[82:83], off
	s_nop 0
	global_load_dwordx4 v[82:85], v[82:83], off offset:16
	s_and_b64 vcc, exec, s[6:7]
	s_cbranch_vccnz .LBB0_990
	v_lshl_add_u64 v[114:115], v[198:199], 2, s[80:81]
	global_load_dwordx2 v[190:191], v[114:115], off offset:384

; template <typename T> DI T* opaque(T* p) { asm volatile("" : "+v"(p) : : "memory"); return p; }
;     DI void operator()(const pg8::f32x4 (&acc)[2][2][4][2], const pg8::Unit& u, int wr, int wc, int fr, int fq) const {
;     ...
;             for (int ai = 0; ai < 2; ++ai) {
;                 const size_t i0 = (size_t)(rowb + ai * 128) * 1024 + col0;
;                 const float* ps = opaque(src + i0);
;                 f32x4 xa[4], xb_[4]; f32x2 sv[4];
; #pragma unroll
;                 for (int m = 0; m < 4; ++m) {
;                     xa[m] = *(const f32x4*)(ps + (size_t)(m * 16) * 1024); xb_[m] = *(const f32x4*)(ps + (size_t)(m * 16) * 1024 + 4);
;                     if (l > 0) sv[m] = *(const f32x2*)(st + 2 * (rowb + ai * 128 + m * 16));
;                 }
;                 float* po = opaque(out + i0);
; #pragma unroll
;                 for (int m = 0; m < 4; ++m) {
;                     f32x4 x0 = xa[m], x1 = xb_[m];
;                     if (l > 0) { x0 = (x0 - sv[m].x) * sv[m].y * g0 + b0; x1 = (x1 - sv[m].x) * sv[m].y * g1 + b1; }
;                     *(f32x4*)(po + (size_t)(m * 16) * 1024) = x0 * DN_ALPHA + acc[ai][bj][m][0];
;                     *(f32x4*)(po + (size_t)(m * 16) * 1024 + 4) = x1 * DN_ALPHA + acc[ai][bj][m][1];
.LBB0_992:
	s_waitcnt vmcnt(0) lgkmcnt(0)
	v_pk_fma_f32 v[60:61], v[108:109], s[96:97], v[60:61] op_sel_hi:[1,0,1]
	v_pk_fma_f32 v[58:59], v[106:107], s[96:97], v[58:59] op_sel_hi:[1,0,1]
	v_pk_fma_f32 v[64:65], v[112:113], s[96:97], v[64:65] op_sel_hi:[1,0,1]
	v_pk_fma_f32 v[62:63], v[110:111], s[96:97], v[62:63] op_sel_hi:[1,0,1]
	global_store_dwordx4 v[114:115], v[58:61], off
	global_store_dwordx4 v[114:115], v[62:65], off offset:16
	v_pk_fma_f32 v[56:57], v[104:105], s[96:97], v[56:57] op_sel_hi:[1,0,1]
	v_add_co_u32_e32 v58, vcc, s63, v114
	v_pk_fma_f32 v[54:55], v[102:103], s[96:97], v[54:55] op_sel_hi:[1,0,1]
	s_nop 0
	v_addc_co_u32_e32 v59, vcc, 0, v115, vcc
	v_pk_fma_f32 v[52:53], v[100:101], s[96:97], v[52:53] op_sel_hi:[1,0,1]
	v_pk_fma_f32 v[50:51], v[98:99], s[96:97], v[50:51] op_sel_hi:[1,0,1]
	s_and_b64 vcc, exec, s[6:7]
	global_store_dwordx4 v[58:59], v[54:57], off
	global_store_dwordx4 v[58:59], v[50:53], off offset:16
	s_cbranch_vccnz .LBB0_994
	s_nop 0
	v_sub_f32_e32 v51, v93, v192
	v_sub_f32_e32 v50, v92, v192
	v_sub_f32_e32 v53, v91, v192
	v_sub_f32_e32 v52, v90, v192
	v_pk_mul_f32 v[52:53], v[192:193], v[52:53] op_sel:[1,0]
	v_pk_mul_f32 v[50:51], v[192:193], v[50:51] op_sel:[1,0]
	v_pk_fma_f32 v[90:91], v[78:79], v[52:53], v[74:75]
	v_pk_fma_f32 v[92:93], v[80:81], v[50:51], v[76:77]
	v_sub_f32_e32 v51, v97, v192
	v_sub_f32_e32 v50, v96, v192
	v_sub_f32_e32 v53, v95, v192
	v_sub_f32_e32 v52, v94, v192
	v_pk_mul_f32 v[52:53], v[192:193], v[52:53] op_sel:[1,0]
	v_pk_mul_f32 v[50:51], v[192:193], v[50:51] op_sel:[1,0]
	v_pk_fma_f32 v[94:95], v[66:67], v[52:53], v[70:71]
	v_pk_fma_f32 v[96:97], v[68:69], v[50:51], v[72:73]
	v_sub_f32_e32 v51, v89, v190
	v_sub_f32_e32 v50, v88, v190
	v_sub_f32_e32 v53, v87, v190
	v_sub_f32_e32 v52, v86, v190
	v_pk_mul_f32 v[52:53], v[190:191], v[52:53] op_sel:[1,0]
	v_pk_mul_f32 v[50:51], v[190:191], v[50:51] op_sel:[1,0]
	v_pk_fma_f32 v[86:87], v[78:79], v[52:53], v[74:75]
	v_pk_fma_f32 v[88:89], v[80:81], v[50:51], v[76:77]
	v_sub_f32_e32 v51, v85, v190
	v_sub_f32_e32 v50, v84, v190
	v_sub_f32_e32 v53, v83, v190
	v_sub_f32_e32 v52, v82, v190
	v_pk_mul_f32 v[52:53], v[190:191], v[52:53] op_sel:[1,0]
	v_pk_mul_f32 v[50:51], v[190:191], v[50:51] op_sel:[1,0]
	v_pk_fma_f32 v[82:83], v[66:67], v[52:53], v[70:71]
	v_pk_fma_f32 v[84:85], v[68:69], v[50:51], v[72:73]
.LBB0_994:
	s_nop 0
	v_add_co_u32_e32 v50, vcc, s79, v114
	v_pk_fma_f32 v[44:45], v[92:93], s[96:97], v[44:45] op_sel_hi:[1,0,1]
	v_pk_fma_f32 v[42:43], v[90:91], s[96:97], v[42:43] op_sel_hi:[1,0,1]
	v_addc_co_u32_e32 v51, vcc, 0, v115, vcc
	v_pk_fma_f32 v[48:49], v[96:97], s[96:97], v[48:49] op_sel_hi:[1,0,1]
	v_pk_fma_f32 v[46:47], v[94:95], s[96:97], v[46:47] op_sel_hi:[1,0,1]
	global_store_dwordx4 v[50:51], v[42:45], off
	global_store_dwordx4 v[50:51], v[46:49], off offset:16
	v_pk_fma_f32 v[40:41], v[88:89], s[96:97], v[40:41] op_sel_hi:[1,0,1]
	v_add_co_u32_e32 v42, vcc, s88, v114
	v_pk_fma_f32 v[38:39], v[86:87], s[96:97], v[38:39] op_sel_hi:[1,0,1]
	s_nop 0
	v_addc_co_u32_e32 v43, vcc, 0, v115, vcc
	v_pk_fma_f32 v[36:37], v[84:85], s[96:97], v[36:37] op_sel_hi:[1,0,1]
	v_pk_fma_f32 v[34:35], v[82:83], s[96:97], v[34:35] op_sel_hi:[1,0,1]
	global_store_dwordx4 v[42:43], v[38:41], off
	global_store_dwordx4 v[42:43], v[34:37], off offset:16
	s_and_b64 vcc, exec, s[6:7]
	s_nop 0
	v_lshl_add_u64 v[34:35], v[148:149], 0, s[30:31]
	global_load_dwordx4 v[58:61], v[34:35], off
	global_load_dwordx4 v[62:65], v[34:35], off offset:16
	s_cbranch_vccnz .LBB0_996
	v_lshl_add_u64 v[36:37], v[146:147], 2, s[80:81]
	global_load_dwordx2 v[196:197], v[36:37], off
.LBB0_996:
	v_add_co_u32_e32 v36, vcc, 0x10000, v34
	s_nop 1
	v_addc_co_u32_e32 v37, vcc, 0, v35, vcc
	global_load_dwordx4 v[54:57], v[36:37], off
	global_load_dwordx4 v[50:53], v[36:37], off offset:16
	s_and_b64 vcc, exec, s[6:7]
	s_cbranch_vccnz .LBB0_998
	v_lshl_add_u64 v[36:37], v[146:147], 2, s[80:81]
	global_load_dwordx2 v[194:195], v[36:37], off offset:128
.LBB0_998:
	v_add_co_u32_e32 v36, vcc, 0x20000, v34
	s_nop 1
	v_addc_co_u32_e32 v37, vcc, 0, v35, vcc
	global_load_dwordx4 v[42:45], v[36:37], off
	global_load_dwordx4 v[46:49], v[36:37], off offset:16
	s_and_b64 vcc, exec, s[6:7]
	s_cbranch_vccnz .LBB0_1000
	v_lshl_add_u64 v[36:37], v[146:147], 2, s[80:81]
	global_load_dwordx2 v[192:193], v[36:37], off offset:256
.LBB0_1000:
	v_add_co_u32_e32 v34, vcc, 0x30000, v34
	s_nop 1
	v_addc_co_u32_e32 v35, vcc, 0, v35, vcc
	global_load_dwordx4 v[38:41], v[34:35], off
	s_nop 0
	global_load_dwordx4 v[34:37], v[34:35], off offset:16
	s_and_b64 vcc, exec, s[6:7]
	s_cbranch_vccnz .LBB0_1002
	v_lshl_add_u64 v[82:83], v[146:147], 2, s[80:81]
	global_load_dwordx2 v[190:191], v[82:83], off offset:384

; template <typename T> DI T* opaque(T* p) { asm volatile("" : "+v"(p) : : "memory"); return p; }
;     DI void operator()(const pg8::f32x4 (&acc)[2][2][4][2], const pg8::Unit& u, int wr, int wc, int fr, int fq) const {
;     ...
;                 float* po = opaque(out + i0);
; #pragma unroll
;                 for (int m = 0; m < 4; ++m) {
;                     f32x4 x0 = xa[m], x1 = xb_[m];
;                     if (l > 0) { x0 = (x0 - sv[m].x) * sv[m].y * g0 + b0; x1 = (x1 - sv[m].x) * sv[m].y * g1 + b1; }
;                     *(f32x4*)(po + (size_t)(m * 16) * 1024) = x0 * DN_ALPHA + acc[ai][bj][m][0];
;                     *(f32x4*)(po + (size_t)(m * 16) * 1024 + 4) = x1 * DN_ALPHA + acc[ai][bj][m][1];
.LBB0_1004:
	s_waitcnt vmcnt(0) lgkmcnt(0)
	v_pk_fma_f32 v[28:29], v[60:61], s[96:97], v[28:29] op_sel_hi:[1,0,1]
	v_pk_fma_f32 v[26:27], v[58:59], s[96:97], v[26:27] op_sel_hi:[1,0,1]
	v_pk_fma_f32 v[32:33], v[64:65], s[96:97], v[32:33] op_sel_hi:[1,0,1]
	v_pk_fma_f32 v[30:31], v[62:63], s[96:97], v[30:31] op_sel_hi:[1,0,1]
	global_store_dwordx4 v[82:83], v[26:29], off
	global_store_dwordx4 v[82:83], v[30:33], off offset:16
	v_pk_fma_f32 v[24:25], v[56:57], s[96:97], v[24:25] op_sel_hi:[1,0,1]
	v_add_co_u32_e32 v26, vcc, s63, v82
	v_pk_fma_f32 v[22:23], v[54:55], s[96:97], v[22:23] op_sel_hi:[1,0,1]
	s_nop 0
	v_addc_co_u32_e32 v27, vcc, 0, v83, vcc
	v_pk_fma_f32 v[20:21], v[52:53], s[96:97], v[20:21] op_sel_hi:[1,0,1]
	v_pk_fma_f32 v[18:19], v[50:51], s[96:97], v[18:19] op_sel_hi:[1,0,1]
	s_and_b64 vcc, exec, s[6:7]
	global_store_dwordx4 v[26:27], v[22:25], off
	global_store_dwordx4 v[26:27], v[18:21], off offset:16
	s_cbranch_vccnz .LBB0_1006
	s_nop 0
	v_sub_f32_e32 v19, v45, v192
	v_sub_f32_e32 v18, v44, v192
	v_sub_f32_e32 v21, v43, v192
	v_sub_f32_e32 v20, v42, v192
	v_pk_mul_f32 v[20:21], v[192:193], v[20:21] op_sel:[1,0]
	v_pk_mul_f32 v[18:19], v[192:193], v[18:19] op_sel:[1,0]
	v_pk_fma_f32 v[42:43], v[78:79], v[20:21], v[74:75]
	v_pk_fma_f32 v[44:45], v[80:81], v[18:19], v[76:77]
	v_sub_f32_e32 v19, v49, v192
	v_sub_f32_e32 v18, v48, v192
	v_sub_f32_e32 v21, v47, v192
	v_sub_f32_e32 v20, v46, v192
	v_pk_mul_f32 v[20:21], v[192:193], v[20:21] op_sel:[1,0]
	v_pk_mul_f32 v[18:19], v[192:193], v[18:19] op_sel:[1,0]
	v_pk_fma_f32 v[46:47], v[66:67], v[20:21], v[70:71]
	v_pk_fma_f32 v[48:49], v[68:69], v[18:19], v[72:73]
	v_sub_f32_e32 v19, v41, v190
	v_sub_f32_e32 v18, v40, v190
	v_sub_f32_e32 v21, v39, v190
	v_sub_f32_e32 v20, v38, v190
	v_pk_mul_f32 v[20:21], v[190:191], v[20:21] op_sel:[1,0]
	v_pk_mul_f32 v[18:19], v[190:191], v[18:19] op_sel:[1,0]
	v_pk_fma_f32 v[38:39], v[78:79], v[20:21], v[74:75]
	v_pk_fma_f32 v[40:41], v[80:81], v[18:19], v[76:77]
	v_sub_f32_e32 v19, v37, v190
	v_sub_f32_e32 v18, v36, v190
	v_sub_f32_e32 v21, v35, v190
	v_sub_f32_e32 v20, v34, v190
	v_pk_mul_f32 v[20:21], v[190:191], v[20:21] op_sel:[1,0]
	v_pk_mul_f32 v[18:19], v[190:191], v[18:19] op_sel:[1,0]
	v_pk_fma_f32 v[34:35], v[66:67], v[20:21], v[70:71]
	v_pk_fma_f32 v[36:37], v[68:69], v[18:19], v[72:73]
.LBB0_1006:
	s_nop 0
	v_add_co_u32_e32 v18, vcc, s79, v82
	v_pk_fma_f32 v[12:13], v[44:45], s[96:97], v[12:13] op_sel_hi:[1,0,1]
	v_pk_fma_f32 v[10:11], v[42:43], s[96:97], v[10:11] op_sel_hi:[1,0,1]
	v_addc_co_u32_e32 v19, vcc, 0, v83, vcc
	v_pk_fma_f32 v[16:17], v[48:49], s[96:97], v[16:17] op_sel_hi:[1,0,1]
	v_pk_fma_f32 v[14:15], v[46:47], s[96:97], v[14:15] op_sel_hi:[1,0,1]
	global_store_dwordx4 v[18:19], v[10:13], off
	global_store_dwordx4 v[18:19], v[14:17], off offset:16
	v_pk_fma_f32 v[8:9], v[40:41], s[96:97], v[8:9] op_sel_hi:[1,0,1]
	v_add_co_u32_e32 v10, vcc, s88, v82
	v_pk_fma_f32 v[6:7], v[38:39], s[96:97], v[6:7] op_sel_hi:[1,0,1]
	s_nop 0
	v_addc_co_u32_e32 v11, vcc, 0, v83, vcc
	v_pk_fma_f32 v[4:5], v[36:37], s[96:97], v[4:5] op_sel_hi:[1,0,1]
	v_pk_fma_f32 v[2:3], v[34:35], s[96:97], v[2:3] op_sel_hi:[1,0,1]
	s_andn2_b64 vcc, exec, s[4:5]
	s_mov_b64 s[4:5], -1
	global_store_dwordx4 v[10:11], v[6:9], off
	global_store_dwordx4 v[10:11], v[2:5], off offset:16
	s_cbranch_vccnz .LBB0_941
	s_andn2_b64 vcc, exec, s[74:75]
	s_cbranch_vccnz .LBB0_940
	s_barrier
	s_branch .LBB0_940

; DI unsigned xb_ld(unsigned* p)              { return __hip_atomic_load(p, __ATOMIC_RELAXED, __HIP_MEMORY_SCOPE_AGENT); }
; DI void xcd_barrier_complete(unsigned* bar, unsigned x, unsigned& nloc, unsigned& nx) {
;     const unsigned G = gridDim.x * gridDim.y * gridDim.z;
;     unsigned sum, cnt, mine, sp = 0u;
;     for (;;) {
;         sum = 0u; cnt = 0u; mine = 0u;
; #pragma unroll
;         for (unsigned j = 0; j < 16; ++j) { const unsigned c = xb_ld(&bar[XB_XCNT(j)]); sum += c; cnt += (c > 0u) ? 1u : 0u; mine = (j == x) ? c : mine; }
;         if (sum == G) break;
;         __builtin_amdgcn_s_sleep(1);
;         if ((++sp & 255u) == 0u) { if (xb_ld(&bar[XB_TMO])) break; if (sp > XB_SPIN_CAP) { atomicAdd(&bar[XB_TMO], 1u); break; } }
;     }
;     nloc = mine > 0u ? mine : 1u; nx = cnt > 0u ? cnt : 1u;
; }
.LBB0_1015:
	v_mov_b64_e32 v[12:13], s[40:41]
	global_load_dword v2, v[12:13], off offset:1024 sc1
	s_waitcnt lgkmcnt(0)
	global_load_dword v0, v[12:13], off offset:1280 sc1
	global_load_dword v3, v[12:13], off offset:1536 sc1
	s_or_b64 s[18:19], s[18:19], exec
	s_or_b64 s[16:17], s[16:17], exec
	s_waitcnt vmcnt(0) lgkmcnt(0)
	v_add_u32_e32 v4, v0, v2
	v_add_u32_e32 v5, v4, v3
	global_load_dword v4, v[12:13], off offset:1792 sc1
	s_waitcnt vmcnt(0) lgkmcnt(0)
	v_add_u32_e32 v6, v5, v4
	global_load_dword v5, v[12:13], off offset:2048 sc1
	s_waitcnt vmcnt(0) lgkmcnt(0)
	v_add_u32_e32 v7, v6, v5
	global_load_dword v6, v[12:13], off offset:2304 sc1
	s_waitcnt vmcnt(0) lgkmcnt(0)
	v_add_u32_e32 v8, v7, v6
	global_load_dword v7, v[12:13], off offset:2560 sc1
	s_waitcnt vmcnt(0) lgkmcnt(0)
	v_add_u32_e32 v9, v8, v7
	global_load_dword v8, v[12:13], off offset:2816 sc1
	s_waitcnt vmcnt(0) lgkmcnt(0)
	v_add_u32_e32 v10, v9, v8
	global_load_dword v9, v[12:13], off offset:3072 sc1
	s_waitcnt vmcnt(0) lgkmcnt(0)
	v_add_u32_e32 v11, v10, v9
	global_load_dword v10, v[12:13], off offset:3328 sc1
	s_waitcnt vmcnt(0) lgkmcnt(0)
	v_add_u32_e32 v14, v11, v10
	global_load_dword v11, v[12:13], off offset:3584 sc1
	s_waitcnt vmcnt(0) lgkmcnt(0)
	v_add_u32_e32 v14, v14, v11
	global_load_dword v12, v[12:13], off offset:3840 sc1
	s_waitcnt vmcnt(0) lgkmcnt(0)
	v_add_u32_e32 v16, v14, v12
	v_mov_b64_e32 v[14:15], s[4:5]
	global_load_dword v13, v[14:15], off sc1
	v_mov_b64_e32 v[14:15], s[6:7]
	global_load_dword v14, v[14:15], off sc1
	s_waitcnt vmcnt(0) lgkmcnt(0)
	v_add_u32_e32 v16, v16, v13
	v_add_u32_e32 v18, v16, v14
	v_mov_b64_e32 v[16:17], s[8:9]
	global_load_dword v15, v[16:17], off sc1
	v_mov_b64_e32 v[16:17], s[10:11]
	global_load_dword v16, v[16:17], off sc1
	s_waitcnt vmcnt(0) lgkmcnt(0)
	v_add_u32_e32 v18, v18, v15
	v_add_u32_e32 v17, v18, v16
	v_cmp_ne_u32_e32 vcc, s84, v17
	s_and_saveexec_b64 s[20:21], vcc
	s_cbranch_execz .LBB0_1014
	s_and_b32 s24, s30, 0xff
	s_mov_b64 s[22:23], -1
	s_cmp_eq_u32 s24, 0
	s_mov_b64 s[26:27], -1
	s_mov_b64 s[24:25], -1
	s_sleep 1
	s_cbranch_scc1 .LBB0_1018
	s_and_saveexec_b64 s[28:29], s[26:27]
	s_cbranch_execz .LBB0_1013
	s_branch .LBB0_1021
.LBB0_1018:
	v_mov_b64_e32 v[18:19], s[40:41]
	global_load_dword v17, v[18:19], off offset:512 sc1
	s_mov_b64 s[26:27], 0
	s_waitcnt vmcnt(0) lgkmcnt(0)
	v_cmp_eq_u32_e32 vcc, 0, v17
	s_and_saveexec_b64 s[28:29], vcc
	s_cmp_lt_u32 s30, 0x40001
	s_cselect_b64 s[26:27], -1, 0
	s_xor_b64 s[24:25], exec, -1
	s_and_b64 s[26:27], s[26:27], exec
	s_or_b64 exec, exec, s[28:29]
	s_and_saveexec_b64 s[28:29], s[26:27]
	s_cbranch_execz .LBB0_1013

; DI unsigned xb_xcc_id() { return (unsigned)__builtin_amdgcn_readfirstlane((int)(__builtin_amdgcn_s_getreg((3 << 11) | 20) & 0xFu)); }
; DI unsigned xb_ld(unsigned* p)              { return __hip_atomic_load(p, __ATOMIC_RELAXED, __HIP_MEMORY_SCOPE_AGENT); }
; DI unsigned xb_add(unsigned* p, unsigned v) { return __hip_atomic_fetch_add(p, v, __ATOMIC_RELAXED, __HIP_MEMORY_SCOPE_AGENT); }
; #define XB_SPIN(cond, bar) do { unsigned _sp = 0; while (cond) { __builtin_amdgcn_s_sleep(1); \
;     if ((++_sp & 255u) == 0u) { if (xb_ld(&(bar)[XB_TMO])) break; if (_sp > XB_SPIN_CAP) { atomicAdd(&(bar)[XB_TMO], 1u); break; } } } } while (0)
; DI void xcd_barrier(const XcdBarrier& b) {
;     ...
;         const unsigned bx = xb_xcc_id();
;         __builtin_amdgcn_s_waitcnt(0);
;         unsigned nloc = b.st[0], nx = b.st[1];
;         if (nloc == 0u) { xcd_barrier_complete(bar, bx, nloc, nx); b.st[0] = nloc; b.st[1] = nx; }
;         const unsigned old = xb_add(&bar[XB_XSUB(bx)], 1u);
;         const unsigned gen = old / nloc;
;         if (old + 1u == (gen + 1u) * nloc) {
;             __builtin_amdgcn_fence(__ATOMIC_RELEASE, "agent");
;             asm volatile("s_waitcnt vmcnt(0)" ::: "memory");
;             const unsigned og = xb_add(&bar[XB_TOP], 1u);
;             const unsigned tg = og / nx;
;             if (og + 1u == (tg + 1u) * nx) xb_add(&bar[XB_TOPGEN], 1u);
;             else XB_SPIN(xb_ld(&bar[XB_TOPGEN]) == tg, bar);
;             __builtin_amdgcn_fence(__ATOMIC_ACQUIRE, "agent");
;             xb_add(&bar[XB_XGEN(bx)], 1u);
;             asm volatile("s_waitcnt vmcnt(0)" ::: "memory");
;         } else {
;             XB_SPIN(xb_ld(&bar[XB_XGEN(bx)]) == gen, bar);
.LBB0_1025:
	s_lshl_b32 s3, s3, 8
	s_add_u32 s24, s40, s3
	s_addc_u32 s3, s41, 0
	v_mov_b32_e32 v3, s24
	v_add_co_u32_e32 v4, vcc, 0x1000, v3
	v_mov_b32_e32 v3, s3
	s_nop 0
	v_addc_co_u32_e32 v5, vcc, 0, v3, vcc
	flat_atomic_add v4, v[4:5], v218 offset:1024 sc0
	v_cvt_f32_u32_e32 v3, v2
	v_sub_u32_e32 v5, 0, v2
	v_rcp_iflag_f32_e32 v3, v3
	s_nop 0
	v_mul_f32_e32 v3, 0x4f7ffffe, v3
	v_cvt_u32_f32_e32 v3, v3
	v_mul_lo_u32 v5, v5, v3
	v_mul_hi_u32 v5, v3, v5
	v_add_u32_e32 v3, v3, v5
	s_waitcnt vmcnt(0) lgkmcnt(0)
	v_mul_hi_u32 v3, v4, v3
	v_mul_lo_u32 v5, v3, v2
	v_sub_u32_e32 v5, v4, v5
	v_cmp_ge_u32_e32 vcc, v5, v2
	v_add_u32_e32 v6, 1, v3
	s_nop 0
	v_cndmask_b32_e32 v3, v3, v6, vcc
	v_sub_u32_e32 v6, v5, v2
	v_cndmask_b32_e32 v5, v5, v6, vcc
	v_cmp_ge_u32_e32 vcc, v5, v2
	v_add_u32_e32 v5, 1, v3
	v_add_u32_e32 v6, 1, v4
	v_cndmask_b32_e32 v3, v3, v5, vcc
	v_mad_u64_u32 v[4:5], s[4:5], v2, v3, v[2:3]
	v_cmp_ne_u32_e32 vcc, v6, v4
	s_and_saveexec_b64 s[4:5], vcc
	s_xor_b64 s[4:5], exec, s[4:5]
	s_cbranch_execz .LBB0_1038
	v_mov_b32_e32 v0, s24
	v_add_co_u32_e32 v4, vcc, 0x2000, v0
	v_mov_b32_e32 v0, s3
	s_nop 0
	v_addc_co_u32_e32 v5, vcc, 0, v0, vcc
	global_load_dword v0, v[4:5], off offset:1024 sc1
	s_add_u32 s8, s24, 0x2400
	s_addc_u32 s9, s3, 0
	s_waitcnt vmcnt(0) lgkmcnt(0)
	v_cmp_eq_u32_e32 vcc, v0, v3
	s_and_saveexec_b64 s[6:7], vcc
	s_cbranch_execz .LBB0_1037
	s_mov_b32 s25, 1
	s_mov_b64 s[10:11], 0
	s_branch .LBB0_1029

.LBB0_1029:
	s_and_b32 s18, s25, 0xff
	s_mov_b64 s[16:17], -1
	s_cmp_lg_u32 s18, 0
	s_mov_b64 s[18:19], -1
	s_sleep 1
	s_cbranch_scc1 .LBB0_1033
	v_mov_b64_e32 v[4:5], s[40:41]
	global_load_dword v0, v[4:5], off offset:512 sc1
	s_mov_b64 s[18:19], 0
	s_mov_b64 s[20:21], -1
	s_waitcnt vmcnt(0) lgkmcnt(0)
	v_cmp_eq_u32_e32 vcc, 0, v0
	s_and_saveexec_b64 s[22:23], vcc
	s_cmp_lt_u32 s25, 0x40001
	s_cselect_b64 s[18:19], -1, 0
	s_xor_b64 s[20:21], exec, -1
	s_and_b64 s[18:19], s[18:19], exec
	s_or_b64 exec, exec, s[22:23]

; DI unsigned xb_ld(unsigned* p)              { return __hip_atomic_load(p, __ATOMIC_RELAXED, __HIP_MEMORY_SCOPE_AGENT); }
; DI unsigned xb_add(unsigned* p, unsigned v) { return __hip_atomic_fetch_add(p, v, __ATOMIC_RELAXED, __HIP_MEMORY_SCOPE_AGENT); }
; #define XB_SPIN(cond, bar) do { unsigned _sp = 0; while (cond) { __builtin_amdgcn_s_sleep(1); \
;     if ((++_sp & 255u) == 0u) { if (xb_ld(&(bar)[XB_TMO])) break; if (_sp > XB_SPIN_CAP) { atomicAdd(&(bar)[XB_TMO], 1u); break; } } } } while (0)
; DI void xcd_barrier(const XcdBarrier& b) {
;     ...
;         if (old + 1u == (gen + 1u) * nloc) {
;             __builtin_amdgcn_fence(__ATOMIC_RELEASE, "agent");
;             asm volatile("s_waitcnt vmcnt(0)" ::: "memory");
;             const unsigned og = xb_add(&bar[XB_TOP], 1u);
;             const unsigned tg = og / nx;
;             if (og + 1u == (tg + 1u) * nx) xb_add(&bar[XB_TOPGEN], 1u);
;             else XB_SPIN(xb_ld(&bar[XB_TOPGEN]) == tg, bar);
.LBB0_1038:
	s_andn2_saveexec_b64 s[4:5], s[4:5]
	s_cbranch_execz .LBB0_1054
	v_mov_b32_e32 v2, s40
	v_add_co_u32_e32 v2, vcc, 0x3000, v2
	v_mov_b32_e32 v3, s41
	buffer_wbl2 sc1
	s_waitcnt vmcnt(0)
	v_addc_co_u32_e32 v3, vcc, 0, v3, vcc
	flat_atomic_add v2, v[2:3], v218 offset:1024 sc0
	v_cvt_f32_u32_e32 v3, v0
	v_sub_u32_e32 v4, 0, v0
	s_mov_b64 s[8:9], -1
	v_rcp_iflag_f32_e32 v3, v3
	s_nop 0
	v_mul_f32_e32 v3, 0x4f7ffffe, v3
	v_cvt_u32_f32_e32 v3, v3
	v_mul_lo_u32 v4, v4, v3
	v_mul_hi_u32 v4, v3, v4
	v_add_u32_e32 v3, v3, v4
	s_waitcnt vmcnt(0) lgkmcnt(0)
	v_mul_hi_u32 v3, v2, v3
	v_mul_lo_u32 v4, v3, v0
	v_sub_u32_e32 v4, v2, v4
	v_cmp_ge_u32_e32 vcc, v4, v0
	v_add_u32_e32 v5, 1, v3
	s_nop 0
	v_cndmask_b32_e32 v3, v3, v5, vcc
	v_sub_u32_e32 v5, v4, v0
	v_cndmask_b32_e32 v4, v4, v5, vcc
	v_cmp_ge_u32_e32 vcc, v4, v0
	v_add_u32_e32 v4, 1, v3
	v_add_u32_e32 v5, 1, v2
	v_cndmask_b32_e32 v4, v3, v4, vcc
	v_mad_u64_u32 v[2:3], s[4:5], v0, v4, v[0:1]
	s_add_u32 s4, s40, 0x3500
	s_addc_u32 s5, s41, 0
	v_cmp_ne_u32_e32 vcc, v5, v2
	v_mov_b64_e32 v[2:3], s[4:5]
	s_and_saveexec_b64 s[6:7], vcc
	s_cbranch_execz .LBB0_1051
	v_mov_b64_e32 v[2:3], s[4:5]
	global_load_dword v0, v[2:3], off sc1
	s_mov_b64 s[12:13], 0
	s_waitcnt vmcnt(0) lgkmcnt(0)
	v_cmp_eq_u32_e32 vcc, v0, v4
	s_and_saveexec_b64 s[10:11], vcc
	s_cbranch_execz .LBB0_1050
	s_add_u32 s8, s40, 0x200
	s_addc_u32 s9, s41, 0
	s_mov_b32 s25, 1
	s_branch .LBB0_1043

; DI unsigned pk2(float a, float b) { f32x2 v = {a, b}; return __builtin_bit_cast(unsigned, __builtin_convertvector(v, bf2_t)); }
; DI void phase6(const Params& p, int l) {
;     ...
;             const float rstd = rsqrtf(q * (1.f / 1024.f) + 1e-5f);
;             if (l == 3) {
; #pragma unroll
;                 for (int j = 0; j < 4; ++j) *(f32x4*)(pr + 256 * j + 4 * lane) = (v[u][j] - mu) * rstd * g[j] + bb[j];
;             } else {
;                 if (lane == 0) { f32x2 st = {mu, rstd}; *(f32x2*)((float*)(ws + O_STATS) + 2 * row) = st; }
;                 bf16_t* xb = (bf16_t*)(ws + O_XB) + (size_t)row * 1024;
; #pragma unroll
;                 for (int j = 0; j < 4; ++j) {
;                     const f32x4 y = (v[u][j] - mu) * rstd * g[j] + bb[j];
;                     u32x2 o; o.x = pk2(y.x, y.y); o.y = pk2(y.z, y.w);
;                     *(u32x2*)(xb + 256 * j + 4 * lane) = o;
;                 }
;             }
.LBB0_1062:
	s_and_saveexec_b64 s[14:15], s[4:5]
	s_cbranch_execz .LBB0_1064
	v_mul_f32_e32 v86, 0x3a800000, v71
	v_ashrrev_i32_e32 v71, 31, v70
	v_lshl_add_u64 v[88:89], v[70:71], 2, s[10:11]
	v_mov_b32_e32 v87, v0
	global_store_dwordx2 v[88:89], v[86:87], off
.LBB0_1064:
	s_or_b64 exec, exec, s[14:15]
	v_pk_mul_f32 v[86:87], v[64:65], v[0:1] op_sel_hi:[1,0]
	v_pk_mul_f32 v[88:89], v[62:63], v[0:1] op_sel_hi:[1,0]
	v_lshlrev_b64 v[76:77], 11, v[76:77]
	v_pk_fma_f32 v[86:87], v[4:5], v[86:87], v[12:13]
	v_pk_fma_f32 v[88:89], v[2:3], v[88:89], v[10:11]
	v_lshl_add_u64 v[76:77], v[66:67], 0, v[76:77]
	v_cvt_pk_bf16_f32 v88, v88, v89
	v_cvt_pk_bf16_f32 v89, v86, v87
	global_store_dwordx2 v[76:77], v[88:89], off
	v_pk_mul_f32 v[86:87], v[60:61], v[0:1] op_sel_hi:[1,0]
	v_pk_mul_f32 v[88:89], v[58:59], v[0:1] op_sel_hi:[1,0]
	v_pk_fma_f32 v[86:87], v[8:9], v[86:87], v[16:17]
	v_pk_fma_f32 v[88:89], v[6:7], v[88:89], v[14:15]
	s_nop 0
	v_cvt_pk_bf16_f32 v88, v88, v89
	v_cvt_pk_bf16_f32 v89, v86, v87
	global_store_dwordx2 v[76:77], v[88:89], off offset:512
	v_pk_mul_f32 v[86:87], v[56:57], v[0:1] op_sel_hi:[1,0]
	v_pk_mul_f32 v[88:89], v[54:55], v[0:1] op_sel_hi:[1,0]
	v_pk_fma_f32 v[86:87], v[20:21], v[86:87], v[28:29]
	v_pk_fma_f32 v[88:89], v[18:19], v[88:89], v[26:27]
	s_nop 0
	v_cvt_pk_bf16_f32 v88, v88, v89
	v_cvt_pk_bf16_f32 v89, v86, v87
	global_store_dwordx2 v[76:77], v[88:89], off offset:1024
	v_pk_mul_f32 v[86:87], v[52:53], v[0:1] op_sel_hi:[1,0]
	v_pk_mul_f32 v[88:89], v[50:51], v[0:1] op_sel_hi:[1,0]
	v_pk_fma_f32 v[86:87], v[24:25], v[86:87], v[32:33]
	v_pk_fma_f32 v[88:89], v[22:23], v[88:89], v[30:31]
	s_nop 0
	v_cvt_pk_bf16_f32 v88, v88, v89
	v_cvt_pk_bf16_f32 v89, v86, v87
	global_store_dwordx2 v[76:77], v[88:89], off offset:1536
	s_branch .LBB0_1061

; DI unsigned pk2(float a, float b) { f32x2 v = {a, b}; return __builtin_bit_cast(unsigned, __builtin_convertvector(v, bf2_t)); }
; DI void phase6(const Params& p, int l) {
;     ...
;         for (int u = 0; u < 2; ++u) {
;             const int row = row0 + u * nw;
;             if (row >= T_) continue;
;             float* pr = p.out + (size_t)row * 1024;
;             float s = 0.f;
; #pragma unroll
;             for (int j = 0; j < 4; ++j) s += (v[u][j].x + v[u][j].y) + (v[u][j].z + v[u][j].w);
; #pragma unroll
;             for (int d = 32; d >= 1; d >>= 1) s += __shfl_xor(s, d);
;             const float mu = s * (1.f / 1024.f);
;             float q = 0.f;
; #pragma unroll
;             for (int j = 0; j < 4; ++j) { const f32x4 d = v[u][j] - mu; q += (d.x * d.x + d.y * d.y) + (d.z * d.z + d.w * d.w); }
; #pragma unroll
;             for (int d = 32; d >= 1; d >>= 1) q += __shfl_xor(q, d);
;             const float rstd = rsqrtf(q * (1.f / 1024.f) + 1e-5f);
;             if (l == 3) {
; #pragma unroll
;                 for (int j = 0; j < 4; ++j) *(f32x4*)(pr + 256 * j + 4 * lane) = (v[u][j] - mu) * rstd * g[j] + bb[j];
;             } else {
;                 if (lane == 0) { f32x2 st = {mu, rstd}; *(f32x2*)((float*)(ws + O_STATS) + 2 * row) = st; }
;                 bf16_t* xb = (bf16_t*)(ws + O_XB) + (size_t)row * 1024;
; #pragma unroll
;                 for (int j = 0; j < 4; ++j) {
;                     const f32x4 y = (v[u][j] - mu) * rstd * g[j] + bb[j];
;                     u32x2 o; o.x = pk2(y.x, y.y); o.y = pk2(y.z, y.w);
;                     *(u32x2*)(xb + 256 * j + 4 * lane) = o;
;                 }
;             }
.LBB0_1066:
	v_mov_b32_e32 v50, v47
	v_mov_b32_e32 v51, v48
	v_mov_b32_e32 v52, v46
	v_mov_b32_e32 v53, v49
	v_pk_add_f32 v[50:51], v[50:51], v[52:53]
	v_mov_b32_e32 v52, v43
	v_mov_b32_e32 v53, v44
	v_mov_b32_e32 v54, v42
	v_mov_b32_e32 v55, v45
	v_pk_add_f32 v[52:53], v[52:53], v[54:55]
	v_add_f32_e32 v0, v50, v51
	v_pk_add_f32 v[52:53], v[52:53], v[52:53] op_sel_hi:[0,1]
	v_add_f32_e32 v51, 0, v0
	v_add_f32_e32 v55, v38, v39
	v_add_f32_e32 v57, v40, v41
	v_mov_b32_e32 v54, v34
	v_mov_b32_e32 v56, v35
	v_mov_b32_e32 v52, v36
	v_mov_b32_e32 v50, v37
	v_pk_add_f32 v[54:55], v[54:55], v[56:57]
	v_pk_add_f32 v[50:51], v[52:53], v[50:51]
	s_mov_b64 s[16:17], -1
	v_pk_add_f32 v[50:51], v[54:55], v[50:51]
	s_nop 0
	v_add_f32_e32 v0, v50, v51
	ds_bpermute_b32 v50, v80, v0
	s_waitcnt lgkmcnt(0)
	v_add_f32_e32 v0, v0, v50
	ds_bpermute_b32 v50, v81, v0
	s_waitcnt lgkmcnt(0)
	v_add_f32_e32 v0, v0, v50
	ds_bpermute_b32 v50, v82, v0
	s_waitcnt lgkmcnt(0)
	v_add_f32_e32 v0, v0, v50
	ds_bpermute_b32 v50, v83, v0
	s_waitcnt lgkmcnt(0)
	v_add_f32_e32 v0, v0, v50
	ds_bpermute_b32 v50, v84, v0
	s_waitcnt lgkmcnt(0)
	v_add_f32_e32 v0, v0, v50
	ds_bpermute_b32 v50, v85, v0
	s_waitcnt lgkmcnt(0)
	v_add_f32_e32 v71, v0, v50
	v_fmamk_f32 v51, v71, 0xba800000, v49
	v_fmamk_f32 v50, v71, 0xba800000, v48
	v_fmamk_f32 v53, v71, 0xba800000, v47
	v_fmamk_f32 v52, v71, 0xba800000, v46
	v_pk_mul_f32 v[58:59], v[50:51], v[50:51]
	v_pk_mul_f32 v[60:61], v[52:53], v[52:53]
	v_fmamk_f32 v55, v71, 0xba800000, v45
	v_pk_mov_b32 v[62:63], v[60:61], v[58:59] op_sel:[1,0]
	v_mov_b32_e32 v61, v59
	v_fmamk_f32 v54, v71, 0xba800000, v44
	v_fmamk_f32 v57, v71, 0xba800000, v43
	v_pk_add_f32 v[58:59], v[62:63], v[60:61]
	v_fmamk_f32 v56, v71, 0xba800000, v42
	v_pk_add_f32 v[76:77], v[58:59], v[58:59] op_sel_hi:[0,1]
	v_pk_mul_f32 v[58:59], v[54:55], v[54:55]
	v_pk_mul_f32 v[60:61], v[56:57], v[56:57]
	v_fmamk_f32 v65, v71, 0xba800000, v35
	v_pk_mov_b32 v[62:63], v[60:61], v[58:59] op_sel:[1,0]
	v_mov_b32_e32 v61, v59
	v_pk_add_f32 v[58:59], v[62:63], v[60:61]
	v_fmamk_f32 v62, v71, 0xba800000, v38
	v_pk_add_f32 v[78:79], v[58:59], v[58:59] op_sel_hi:[0,1]
	v_fmamk_f32 v58, v71, 0xba800000, v40
	v_fmamk_f32 v63, v71, 0xba800000, v39
	v_mul_f32_e32 v0, v62, v62
	v_fmamk_f32 v59, v71, 0xba800000, v41
	v_pk_fma_f32 v[86:87], v[62:63], v[62:63], v[0:1] op_sel_hi:[1,1,0]
	v_mul_f32_e32 v0, v58, v58
	v_pk_fma_f32 v[88:89], v[58:59], v[58:59], v[0:1] op_sel_hi:[1,1,0]
	v_fmamk_f32 v61, v71, 0xba800000, v37
	v_fmamk_f32 v60, v71, 0xba800000, v36
	v_fmamk_f32 v64, v71, 0xba800000, v34
	v_mul_f32_e32 v86, v64, v64
	v_mul_f32_e32 v88, v65, v65
	v_mul_f32_e32 v76, v60, v60
	v_mul_f32_e32 v78, v61, v61
	v_pk_add_f32 v[86:87], v[86:87], v[88:89]
	v_pk_add_f32 v[76:77], v[76:77], v[78:79]
	s_nop 0
	v_pk_add_f32 v[76:77], v[86:87], v[76:77]
	s_nop 0
	v_add_f32_e32 v0, v76, v77
	ds_bpermute_b32 v73, v80, v0
	v_lshlrev_b64 v[76:77], 10, v[74:75]
	s_waitcnt lgkmcnt(0)
	v_add_f32_e32 v0, v0, v73
	ds_bpermute_b32 v73, v81, v0
	s_waitcnt lgkmcnt(0)
	v_add_f32_e32 v0, v0, v73
	ds_bpermute_b32 v73, v82, v0
	s_waitcnt lgkmcnt(0)
	v_add_f32_e32 v0, v0, v73
	ds_bpermute_b32 v73, v83, v0
	s_waitcnt lgkmcnt(0)
	v_add_f32_e32 v0, v0, v73
	ds_bpermute_b32 v73, v84, v0
	s_waitcnt lgkmcnt(0)
	v_add_f32_e32 v0, v0, v73
	ds_bpermute_b32 v73, v85, v0
	s_waitcnt lgkmcnt(0)
	v_add_f32_e32 v0, v0, v73
	v_fmamk_f32 v0, v0, 0x3a800000, v221
	v_mul_f32_e32 v73, 0x4b800000, v0
	v_cmp_gt_f32_e32 vcc, s94, v0
	s_nop 1
	v_cndmask_b32_e32 v0, v0, v73, vcc
	v_rsq_f32_e32 v0, v0
	s_nop 0
	v_mul_f32_e32 v73, 0x45800000, v0
	v_cndmask_b32_e32 v0, v0, v73, vcc
	s_andn2_b64 vcc, exec, s[8:9]
	s_cbranch_vccnz .LBB0_1070
	s_and_saveexec_b64 s[16:17], s[4:5]
	s_cbranch_execz .LBB0_1069
	v_ashrrev_i32_e32 v73, 31, v72
	v_mul_f32_e32 v78, 0x3a800000, v71
	v_lshl_add_u64 v[86:87], v[72:73], 2, s[10:11]
	v_mov_b32_e32 v79, v0
	global_store_dwordx2 v[86:87], v[78:79], off
.LBB0_1069:
	s_or_b64 exec, exec, s[16:17]
	v_pk_mul_f32 v[86:87], v[50:51], v[0:1] op_sel_hi:[1,0]
	v_pk_mul_f32 v[88:89], v[52:53], v[0:1] op_sel_hi:[1,0]
	v_pk_fma_f32 v[86:87], v[4:5], v[86:87], v[12:13]
	v_pk_fma_f32 v[88:89], v[2:3], v[88:89], v[10:11]
	v_lshl_add_u64 v[78:79], v[76:77], 1, v[66:67]
	v_cvt_pk_bf16_f32 v88, v88, v89
	v_cvt_pk_bf16_f32 v89, v86, v87
	global_store_dwordx2 v[78:79], v[88:89], off
	v_pk_mul_f32 v[86:87], v[54:55], v[0:1] op_sel_hi:[1,0]
	v_pk_mul_f32 v[88:89], v[56:57], v[0:1] op_sel_hi:[1,0]
	v_pk_fma_f32 v[86:87], v[8:9], v[86:87], v[16:17]
	v_pk_fma_f32 v[88:89], v[6:7], v[88:89], v[14:15]
	s_mov_b64 s[16:17], 0
	v_cvt_pk_bf16_f32 v88, v88, v89
	v_cvt_pk_bf16_f32 v89, v86, v87
	global_store_dwordx2 v[78:79], v[88:89], off offset:512
	v_pk_mul_f32 v[86:87], v[58:59], v[0:1] op_sel_hi:[1,0]
	v_pk_mul_f32 v[88:89], v[62:63], v[0:1] op_sel_hi:[1,0]
	v_pk_fma_f32 v[86:87], v[20:21], v[86:87], v[28:29]
	v_pk_fma_f32 v[88:89], v[18:19], v[88:89], v[26:27]
	s_nop 0
	v_cvt_pk_bf16_f32 v88, v88, v89
	v_cvt_pk_bf16_f32 v89, v86, v87
	global_store_dwordx2 v[78:79], v[88:89], off offset:1024
	v_pk_mul_f32 v[86:87], v[60:61], v[0:1] op_sel_hi:[1,0]
	v_pk_mul_f32 v[88:89], v[64:65], v[0:1] op_sel_hi:[1,0]
	v_pk_fma_f32 v[86:87], v[24:25], v[86:87], v[32:33]
	v_pk_fma_f32 v[88:89], v[22:23], v[88:89], v[30:31]
	s_nop 0
	v_cvt_pk_bf16_f32 v88, v88, v89
	v_cvt_pk_bf16_f32 v89, v86, v87
	global_store_dwordx2 v[78:79], v[88:89], off offset:1536
